# v61 + barrier-approach priority in the remaining LDS-staged segments (prep transposes, mixA staging), diff loop left alone
# speedup vs baseline: 1.0033x; 1.0022x over previous
.LBB0_64:
	s_mul_hi_i32 s0, s71, 0x2aaaaaab
	s_lshr_b32 s1, s0, 31
	s_ashr_i32 s0, s0, 5
	s_add_i32 s4, s0, s1
	s_ashr_i32 s5, s4, 31
	s_lshl_b64 s[44:45], s[4:5], 10
	s_mul_i32 s0, s4, 0xfffff400
	v_lshl_add_u64 v[10:11], s[44:45], 0, v[4:5]
	s_add_i32 s0, s6, s0
	v_mad_u64_u32 v[16:17], s[44:45], v10, s8, v[6:7]
	v_mad_i32_i24 v17, v11, s8, v17
	s_ashr_i32 s1, s0, 31
	v_lshl_add_u64 v[10:11], s[0:1], 2, v[16:17]
	v_lshl_add_u64 v[10:11], v[10:11], 0, v[8:9]
	v_add_co_u32_e64 v16, s[0:1], s8, v10
	global_load_dword v42, v[10:11], off
	s_nop 0
	v_addc_co_u32_e64 v17, s[0:1], 0, v11, s[0:1]
	s_movk_i32 s0, 0x6000
	global_load_dword v43, v[16:17], off
	v_add_co_u32_e64 v16, s[0:1], s0, v10
	s_nop 1
	v_addc_co_u32_e64 v17, s[0:1], 0, v11, s[0:1]
	s_mov_b32 s0, 0x9000
	global_load_dword v44, v[16:17], off
	v_add_co_u32_e64 v16, s[0:1], s0, v10
	s_nop 1
	v_addc_co_u32_e64 v17, s[0:1], 0, v11, s[0:1]
	s_mov_b32 s0, 0xc000
	global_load_dword v45, v[16:17], off
	v_add_co_u32_e64 v16, s[0:1], s0, v10
	s_nop 1
	v_addc_co_u32_e64 v17, s[0:1], 0, v11, s[0:1]
	s_mov_b32 s0, 0xf000
	global_load_dword v46, v[16:17], off
	v_add_co_u32_e64 v16, s[0:1], s0, v10
	s_nop 1
	v_addc_co_u32_e64 v17, s[0:1], 0, v11, s[0:1]
	s_mov_b32 s0, 0x12000
	global_load_dword v47, v[16:17], off
	v_add_co_u32_e64 v16, s[0:1], s0, v10
	s_nop 1
	v_addc_co_u32_e64 v17, s[0:1], 0, v11, s[0:1]
	s_mov_b32 s0, 0x15000
	global_load_dword v48, v[16:17], off
	v_add_co_u32_e64 v16, s[0:1], s0, v10
	s_nop 1
	v_addc_co_u32_e64 v17, s[0:1], 0, v11, s[0:1]
	s_mov_b32 s0, 0x18000
	global_load_dword v49, v[16:17], off
	v_add_co_u32_e64 v16, s[0:1], s0, v10
	s_nop 1
	v_addc_co_u32_e64 v17, s[0:1], 0, v11, s[0:1]
	s_mov_b32 s0, 0x1b000
	global_load_dword v50, v[16:17], off
	v_add_co_u32_e64 v16, s[0:1], s0, v10
	s_nop 1
	v_addc_co_u32_e64 v17, s[0:1], 0, v11, s[0:1]
	s_mov_b32 s0, 0x1e000
	global_load_dword v51, v[16:17], off
	v_add_co_u32_e64 v16, s[0:1], s0, v10
	s_nop 1
	v_addc_co_u32_e64 v17, s[0:1], 0, v11, s[0:1]
	s_mov_b32 s0, 0x21000
	global_load_dword v52, v[16:17], off
	v_add_co_u32_e64 v16, s[0:1], s0, v10
	s_nop 1
	v_addc_co_u32_e64 v17, s[0:1], 0, v11, s[0:1]
	global_load_dword v53, v[16:17], off
	s_mov_b32 s0, 0x24000
	v_add_co_u32_e64 v16, s[0:1], s0, v10
	s_nop 1
	v_addc_co_u32_e64 v17, s[0:1], 0, v11, s[0:1]
	s_mov_b32 s0, 0x27000
	global_load_dword v54, v[16:17], off
	v_add_co_u32_e64 v16, s[0:1], s0, v10
	s_nop 1
	v_addc_co_u32_e64 v17, s[0:1], 0, v11, s[0:1]
	global_load_dword v55, v[16:17], off
	s_mov_b32 s0, 0x2a000
	v_add_co_u32_e64 v16, s[0:1], s0, v10
	s_nop 1
	v_addc_co_u32_e64 v17, s[0:1], 0, v11, s[0:1]
	global_load_dword v56, v[16:17], off
	v_add_co_u32_e64 v16, s[0:1], s9, v10
	s_nop 1
	v_addc_co_u32_e64 v17, s[0:1], 0, v11, s[0:1]
	global_load_dword v57, v[16:17], off
	ds_read_b128 v[18:21], v3
	ds_read_b128 v[22:25], v3 offset:16
	ds_read_b128 v[26:29], v3 offset:32
	ds_read_b128 v[30:33], v3 offset:48
	ds_read_b128 v[34:37], v3 offset:4096
	s_waitcnt vmcnt(15) lgkmcnt(4)
	v_fma_f32 v16, v42, v18, 0
	s_waitcnt vmcnt(14)
	v_fmac_f32_e32 v16, v43, v19
	s_waitcnt vmcnt(13)
	v_fmac_f32_e32 v16, v44, v20
	s_waitcnt vmcnt(12)
	v_fmac_f32_e32 v16, v45, v21
	s_waitcnt vmcnt(11) lgkmcnt(3)
	v_fmac_f32_e32 v16, v46, v22
	ds_read_b128 v[38:41], v3 offset:8192
	s_waitcnt vmcnt(10)
	v_fmac_f32_e32 v16, v47, v23
	ds_read_b128 v[20:23], v3 offset:4128
	s_waitcnt lgkmcnt(2)
	v_fma_f32 v17, v42, v34, 0
	v_fmac_f32_e32 v17, v43, v35
	v_fmac_f32_e32 v17, v44, v36
	v_fmac_f32_e32 v17, v45, v37
	ds_read_b128 v[34:37], v3 offset:4112
	s_waitcnt lgkmcnt(2)
	v_fma_f32 v18, v42, v38, 0
	v_fmac_f32_e32 v18, v43, v39
	v_fmac_f32_e32 v18, v44, v40
	v_fmac_f32_e32 v18, v45, v41
	s_waitcnt lgkmcnt(0)
	v_fmac_f32_e32 v17, v46, v34
	v_fmac_f32_e32 v17, v47, v35
	s_waitcnt vmcnt(9)
	v_fmac_f32_e32 v17, v48, v36
	s_waitcnt vmcnt(8)
	v_fmac_f32_e32 v17, v49, v37
	ds_read_b128 v[38:41], v3 offset:8208
	v_fmac_f32_e32 v16, v48, v24
	v_fmac_f32_e32 v16, v49, v25
	ds_read_b128 v[34:37], v3 offset:8224
	s_waitcnt vmcnt(7)
	v_fmac_f32_e32 v17, v50, v20
	v_fmac_f32_e32 v16, v50, v26
	s_waitcnt vmcnt(6)
	v_fmac_f32_e32 v17, v51, v21
	v_fmac_f32_e32 v16, v51, v27
	ds_read_b128 v[24:27], v3 offset:8240
	s_waitcnt vmcnt(5)
	v_fmac_f32_e32 v17, v52, v22
	v_fmac_f32_e32 v16, v52, v28
	s_waitcnt vmcnt(4)
	v_fmac_f32_e32 v17, v53, v23
	ds_read_b128 v[20:23], v3 offset:4144
	v_fmac_f32_e32 v16, v53, v29
	s_waitcnt lgkmcnt(3)
	v_fmac_f32_e32 v18, v46, v38
	v_fmac_f32_e32 v18, v47, v39
	v_fmac_f32_e32 v18, v48, v40
	v_fmac_f32_e32 v18, v49, v41
	s_waitcnt lgkmcnt(2)
	v_fmac_f32_e32 v18, v50, v34
	s_waitcnt vmcnt(3) lgkmcnt(0)
	v_fmac_f32_e32 v17, v54, v20
	v_add_co_u32_e64 v20, s[0:1], s10, v10
	v_fmac_f32_e32 v16, v54, v30
	v_fmac_f32_e32 v18, v51, v35
	v_fmac_f32_e32 v18, v52, v36
	s_waitcnt vmcnt(2)
	v_fmac_f32_e32 v17, v55, v21
	v_addc_co_u32_e64 v21, s[0:1], 0, v11, s[0:1]
	global_load_dword v19, v[20:21], off
	v_add_co_u32_e64 v20, s[0:1], s11, v10
	v_fmac_f32_e32 v16, v55, v31
	s_nop 0
	v_addc_co_u32_e64 v21, s[0:1], 0, v11, s[0:1]
	s_waitcnt vmcnt(2)
	v_fmac_f32_e32 v16, v56, v32
	global_load_dword v32, v[20:21], off
	v_add_co_u32_e64 v20, s[0:1], s46, v10
	s_waitcnt vmcnt(2)
	v_fmac_f32_e32 v16, v57, v33
	v_addc_co_u32_e64 v21, s[0:1], 0, v11, s[0:1]
	global_load_dword v33, v[20:21], off
	v_add_co_u32_e64 v20, s[0:1], s47, v10
	v_fmac_f32_e32 v18, v53, v37
	s_nop 0
	v_addc_co_u32_e64 v21, s[0:1], 0, v11, s[0:1]
	global_load_dword v34, v[20:21], off
	v_add_co_u32_e64 v20, s[0:1], s48, v10
	v_fmac_f32_e32 v17, v56, v22
	s_nop 0
	v_addc_co_u32_e64 v21, s[0:1], 0, v11, s[0:1]
	global_load_dword v35, v[20:21], off
	v_add_co_u32_e64 v20, s[0:1], s49, v10
	v_fmac_f32_e32 v17, v57, v23
	s_nop 0
	v_addc_co_u32_e64 v21, s[0:1], 0, v11, s[0:1]
	global_load_dword v36, v[20:21], off
	v_add_co_u32_e64 v20, s[0:1], s55, v10
	v_fmac_f32_e32 v18, v54, v24
	s_nop 0
	v_addc_co_u32_e64 v21, s[0:1], 0, v11, s[0:1]
	global_load_dword v37, v[20:21], off
	v_add_co_u32_e64 v20, s[0:1], s84, v10
	v_fmac_f32_e32 v18, v55, v25
	s_nop 0
	v_addc_co_u32_e64 v21, s[0:1], 0, v11, s[0:1]
	global_load_dword v38, v[20:21], off
	v_add_co_u32_e64 v20, s[0:1], s85, v10
	v_fmac_f32_e32 v18, v56, v26
	s_nop 0
	v_addc_co_u32_e64 v21, s[0:1], 0, v11, s[0:1]
	global_load_dword v39, v[20:21], off
	v_add_co_u32_e64 v20, s[0:1], s86, v10
	v_fmac_f32_e32 v18, v57, v27
	s_nop 0
	v_addc_co_u32_e64 v21, s[0:1], 0, v11, s[0:1]
	global_load_dword v40, v[20:21], off
	v_add_co_u32_e64 v20, s[0:1], s87, v10
	ds_read_b128 v[24:27], v3 offset:4160
	s_nop 0
	v_addc_co_u32_e64 v21, s[0:1], 0, v11, s[0:1]
	global_load_dword v41, v[20:21], off
	v_add_co_u32_e64 v20, s[0:1], s88, v10
	ds_read_b128 v[28:31], v3 offset:8256
	s_nop 0
	v_addc_co_u32_e64 v21, s[0:1], 0, v11, s[0:1]
	global_load_dword v42, v[20:21], off
	v_add_co_u32_e64 v20, s[0:1], s89, v10
	s_waitcnt vmcnt(11) lgkmcnt(1)
	v_fmac_f32_e32 v17, v19, v24
	v_addc_co_u32_e64 v21, s[0:1], 0, v11, s[0:1]
	global_load_dword v43, v[20:21], off
	v_add_co_u32_e64 v20, s[0:1], s90, v10
	s_waitcnt lgkmcnt(0)
	v_fmac_f32_e32 v18, v19, v28
	v_addc_co_u32_e64 v21, s[0:1], 0, v11, s[0:1]
	global_load_dword v44, v[20:21], off
	v_add_co_u32_e64 v20, s[0:1], s91, v10
	s_waitcnt vmcnt(12)
	v_fmac_f32_e32 v17, v32, v25
	v_addc_co_u32_e64 v21, s[0:1], 0, v11, s[0:1]
	global_load_dword v45, v[20:21], off
	v_add_co_u32_e64 v20, s[0:1], s92, v10
	s_waitcnt vmcnt(12)
	v_fmac_f32_e32 v17, v33, v26
	v_addc_co_u32_e64 v21, s[0:1], 0, v11, s[0:1]
	global_load_dword v46, v[20:21], off
	ds_read_b128 v[20:23], v3 offset:64
	s_waitcnt vmcnt(12)
	v_fmac_f32_e32 v17, v34, v27
	ds_read_b128 v[24:27], v3 offset:4176
	v_fmac_f32_e32 v18, v32, v29
	v_fmac_f32_e32 v18, v33, v30
	s_waitcnt lgkmcnt(1)
	v_fmac_f32_e32 v16, v19, v20
	v_fmac_f32_e32 v16, v32, v21
	v_fmac_f32_e32 v16, v33, v22
	v_fmac_f32_e32 v16, v34, v23
	ds_read_b128 v[20:23], v3 offset:80
	s_waitcnt vmcnt(11) lgkmcnt(1)
	v_fmac_f32_e32 v17, v35, v24
	s_waitcnt vmcnt(10)
	v_fmac_f32_e32 v17, v36, v25
	v_fmac_f32_e32 v18, v34, v31
	ds_read_b128 v[28:31], v3 offset:8272
	s_waitcnt lgkmcnt(1)
	v_fmac_f32_e32 v16, v35, v20
	v_fmac_f32_e32 v16, v36, v21
	s_waitcnt vmcnt(9)
	v_fmac_f32_e32 v16, v37, v22
	v_fmac_f32_e32 v17, v37, v26
	s_waitcnt lgkmcnt(0)
	v_fmac_f32_e32 v18, v35, v28
	v_fmac_f32_e32 v18, v36, v29
	v_fmac_f32_e32 v18, v37, v30
	s_waitcnt vmcnt(8)
	v_fmac_f32_e32 v16, v38, v23
	ds_read_b128 v[20:23], v3 offset:96
	v_fmac_f32_e32 v17, v38, v27
	ds_read_b128 v[24:27], v3 offset:4192
	v_fmac_f32_e32 v18, v38, v31
	ds_read_b128 v[28:31], v3 offset:8288
	s_waitcnt vmcnt(7) lgkmcnt(2)
	v_fmac_f32_e32 v16, v39, v20
	s_waitcnt lgkmcnt(1)
	v_fmac_f32_e32 v17, v39, v24
	s_waitcnt lgkmcnt(0)
	v_fmac_f32_e32 v18, v39, v28
	s_waitcnt vmcnt(6)
	v_fmac_f32_e32 v16, v40, v21
	v_fmac_f32_e32 v17, v40, v25
	v_fmac_f32_e32 v18, v40, v29
	s_waitcnt vmcnt(5)
	v_fmac_f32_e32 v16, v41, v22
	v_fmac_f32_e32 v17, v41, v26
	v_fmac_f32_e32 v18, v41, v30
	s_waitcnt vmcnt(4)
	v_fmac_f32_e32 v16, v42, v23
	ds_read_b128 v[20:23], v3 offset:112
	v_fmac_f32_e32 v17, v42, v27
	ds_read_b128 v[24:27], v3 offset:4208
	v_fmac_f32_e32 v18, v42, v31
	ds_read_b128 v[28:31], v3 offset:8304
	s_waitcnt vmcnt(3) lgkmcnt(2)
	v_fmac_f32_e32 v16, v43, v20
	v_add_co_u32_e64 v20, s[0:1], s93, v10
	s_waitcnt lgkmcnt(1)
	v_fmac_f32_e32 v17, v43, v24
	s_waitcnt lgkmcnt(0)
	v_fmac_f32_e32 v18, v43, v28
	s_waitcnt vmcnt(2)
	v_fmac_f32_e32 v16, v44, v21
	v_addc_co_u32_e64 v21, s[0:1], 0, v11, s[0:1]
	global_load_dword v19, v[20:21], off
	v_add_co_u32_e64 v20, s[0:1], s94, v10
	v_fmac_f32_e32 v17, v44, v25
	s_nop 0
	v_addc_co_u32_e64 v21, s[0:1], 0, v11, s[0:1]
	global_load_dword v32, v[20:21], off
	v_add_co_u32_e64 v20, s[0:1], s28, v10
	v_fmac_f32_e32 v18, v44, v29
	s_nop 0
	v_addc_co_u32_e64 v21, s[0:1], 0, v11, s[0:1]
	global_load_dword v33, v[20:21], off
	v_add_co_u32_e64 v20, s[0:1], s29, v10
	s_waitcnt vmcnt(4)
	v_fmac_f32_e32 v16, v45, v22
	v_addc_co_u32_e64 v21, s[0:1], 0, v11, s[0:1]
	global_load_dword v34, v[20:21], off
	v_add_co_u32_e64 v20, s[0:1], s30, v10
	v_fmac_f32_e32 v17, v45, v26
	s_nop 0
	v_addc_co_u32_e64 v21, s[0:1], 0, v11, s[0:1]
	global_load_dword v35, v[20:21], off
	v_add_co_u32_e64 v20, s[0:1], s31, v10
	v_fmac_f32_e32 v18, v45, v30
	s_nop 0
	v_addc_co_u32_e64 v21, s[0:1], 0, v11, s[0:1]
	global_load_dword v36, v[20:21], off
	v_add_co_u32_e64 v20, s[0:1], s33, v10
	s_waitcnt vmcnt(6)
	v_fmac_f32_e32 v16, v46, v23
	v_addc_co_u32_e64 v21, s[0:1], 0, v11, s[0:1]
	global_load_dword v37, v[20:21], off
	v_add_co_u32_e64 v20, s[0:1], s34, v10
	v_fmac_f32_e32 v17, v46, v27
	s_nop 0
	v_addc_co_u32_e64 v21, s[0:1], 0, v11, s[0:1]
	global_load_dword v38, v[20:21], off
	v_add_co_u32_e64 v20, s[0:1], s35, v10
	v_fmac_f32_e32 v18, v46, v31
	s_nop 0
	v_addc_co_u32_e64 v21, s[0:1], 0, v11, s[0:1]
	global_load_dword v39, v[20:21], off
	v_add_co_u32_e64 v20, s[0:1], s36, v10
	ds_read_b128 v[24:27], v3 offset:4224
	s_nop 0
	v_addc_co_u32_e64 v21, s[0:1], 0, v11, s[0:1]
	global_load_dword v40, v[20:21], off
	v_add_co_u32_e64 v20, s[0:1], s37, v10
	ds_read_b128 v[28:31], v3 offset:8320
	s_nop 0
	v_addc_co_u32_e64 v21, s[0:1], 0, v11, s[0:1]
	global_load_dword v41, v[20:21], off
	v_add_co_u32_e64 v20, s[0:1], s38, v10
	s_waitcnt vmcnt(10) lgkmcnt(1)
	v_fmac_f32_e32 v17, v19, v24
	v_addc_co_u32_e64 v21, s[0:1], 0, v11, s[0:1]
	global_load_dword v42, v[20:21], off
	v_add_co_u32_e64 v20, s[0:1], s39, v10
	s_waitcnt vmcnt(10)
	v_fmac_f32_e32 v17, v32, v25
	v_addc_co_u32_e64 v21, s[0:1], 0, v11, s[0:1]
	global_load_dword v43, v[20:21], off
	v_add_co_u32_e64 v20, s[0:1], s40, v10
	s_waitcnt vmcnt(10)
	v_fmac_f32_e32 v17, v33, v26
	v_addc_co_u32_e64 v21, s[0:1], 0, v11, s[0:1]
	global_load_dword v44, v[20:21], off
	v_add_co_u32_e64 v20, s[0:1], s41, v10
	s_waitcnt vmcnt(10)
	v_fmac_f32_e32 v17, v34, v27
	v_addc_co_u32_e64 v21, s[0:1], 0, v11, s[0:1]
	global_load_dword v45, v[20:21], off
	v_add_co_u32_e64 v20, s[0:1], s42, v10
	ds_read_b128 v[24:27], v3 offset:4240
	s_nop 0
	v_addc_co_u32_e64 v21, s[0:1], 0, v11, s[0:1]
	global_load_dword v46, v[20:21], off
	ds_read_b128 v[20:23], v3 offset:128
	s_waitcnt vmcnt(11) lgkmcnt(1)
	v_fmac_f32_e32 v17, v35, v24
	s_waitcnt vmcnt(10)
	v_fmac_f32_e32 v17, v36, v25
	v_fmac_f32_e32 v18, v19, v28
	v_fmac_f32_e32 v18, v32, v29
	s_waitcnt lgkmcnt(0)
	v_fmac_f32_e32 v16, v19, v20
	v_fmac_f32_e32 v16, v32, v21
	v_fmac_f32_e32 v16, v33, v22
	v_fmac_f32_e32 v16, v34, v23
	ds_read_b128 v[20:23], v3 offset:144
	s_waitcnt vmcnt(9)
	v_fmac_f32_e32 v17, v37, v26
	v_fmac_f32_e32 v18, v33, v30
	v_fmac_f32_e32 v18, v34, v31
	ds_read_b128 v[28:31], v3 offset:8336
	s_waitcnt lgkmcnt(1)
	v_fmac_f32_e32 v16, v35, v20
	v_fmac_f32_e32 v16, v36, v21
	v_fmac_f32_e32 v16, v37, v22
	s_waitcnt vmcnt(8)
	v_fmac_f32_e32 v16, v38, v23
	ds_read_b128 v[20:23], v3 offset:160
	v_fmac_f32_e32 v17, v38, v27
	ds_read_b128 v[24:27], v3 offset:4256
	s_waitcnt lgkmcnt(2)
	v_fmac_f32_e32 v18, v35, v28
	v_fmac_f32_e32 v18, v36, v29
	s_waitcnt vmcnt(7) lgkmcnt(1)
	v_fmac_f32_e32 v16, v39, v20
	v_fmac_f32_e32 v18, v37, v30
	s_waitcnt lgkmcnt(0)
	v_fmac_f32_e32 v17, v39, v24
	s_waitcnt vmcnt(6)
	v_fmac_f32_e32 v16, v40, v21
	v_fmac_f32_e32 v17, v40, v25
	v_fmac_f32_e32 v18, v38, v31
	ds_read_b128 v[28:31], v3 offset:8352
	s_waitcnt vmcnt(5)
	v_fmac_f32_e32 v16, v41, v22
	v_fmac_f32_e32 v17, v41, v26
	s_waitcnt lgkmcnt(0)
	v_fmac_f32_e32 v18, v39, v28
	v_fmac_f32_e32 v18, v40, v29
	v_fmac_f32_e32 v18, v41, v30
	s_waitcnt vmcnt(4)
	v_fmac_f32_e32 v16, v42, v23
	ds_read_b128 v[20:23], v3 offset:176
	v_fmac_f32_e32 v17, v42, v27
	ds_read_b128 v[24:27], v3 offset:4272
	v_fmac_f32_e32 v18, v42, v31
	ds_read_b128 v[28:31], v3 offset:8368
	s_waitcnt vmcnt(3) lgkmcnt(2)
	v_fmac_f32_e32 v16, v43, v20
	v_add_co_u32_e64 v20, s[0:1], s43, v10
	s_waitcnt lgkmcnt(1)
	v_fmac_f32_e32 v17, v43, v24
	s_waitcnt lgkmcnt(0)
	v_fmac_f32_e32 v18, v43, v28
	s_waitcnt vmcnt(2)
	v_fmac_f32_e32 v16, v44, v21
	v_addc_co_u32_e64 v21, s[0:1], 0, v11, s[0:1]
	global_load_dword v19, v[20:21], off
	v_add_co_u32_e64 v20, s[0:1], s56, v10
	v_fmac_f32_e32 v17, v44, v25
	s_nop 0
	v_addc_co_u32_e64 v21, s[0:1], 0, v11, s[0:1]
	global_load_dword v32, v[20:21], off
	v_add_co_u32_e64 v20, s[0:1], s57, v10
	v_fmac_f32_e32 v18, v44, v29
	s_nop 0
	v_addc_co_u32_e64 v21, s[0:1], 0, v11, s[0:1]
	global_load_dword v33, v[20:21], off
	v_add_co_u32_e64 v20, s[0:1], s58, v10
	s_waitcnt vmcnt(4)
	v_fmac_f32_e32 v16, v45, v22
	v_addc_co_u32_e64 v21, s[0:1], 0, v11, s[0:1]
	global_load_dword v34, v[20:21], off
	v_add_co_u32_e64 v20, s[0:1], s59, v10
	v_fmac_f32_e32 v17, v45, v26
	s_nop 0
	v_addc_co_u32_e64 v21, s[0:1], 0, v11, s[0:1]
	global_load_dword v35, v[20:21], off
	v_add_co_u32_e64 v20, s[0:1], s60, v10
	v_fmac_f32_e32 v18, v45, v30
	s_nop 0
	v_addc_co_u32_e64 v21, s[0:1], 0, v11, s[0:1]
	global_load_dword v36, v[20:21], off
	v_add_co_u32_e64 v20, s[0:1], s61, v10
	s_waitcnt vmcnt(6)
	v_fmac_f32_e32 v16, v46, v23
	v_addc_co_u32_e64 v21, s[0:1], 0, v11, s[0:1]
	global_load_dword v37, v[20:21], off
	v_add_co_u32_e64 v20, s[0:1], s62, v10
	v_fmac_f32_e32 v17, v46, v27
	s_nop 0
	v_addc_co_u32_e64 v21, s[0:1], 0, v11, s[0:1]
	global_load_dword v38, v[20:21], off
	v_add_co_u32_e64 v20, s[0:1], s63, v10
	ds_read_b128 v[24:27], v3 offset:4288
	s_nop 0
	v_addc_co_u32_e64 v21, s[0:1], 0, v11, s[0:1]
	global_load_dword v39, v[20:21], off
	v_add_co_u32_e64 v20, s[0:1], s64, v10
	v_fmac_f32_e32 v18, v46, v31
	s_nop 0
	v_addc_co_u32_e64 v21, s[0:1], 0, v11, s[0:1]
	global_load_dword v40, v[20:21], off
	v_add_co_u32_e64 v20, s[0:1], s65, v10
	ds_read_b128 v[28:31], v3 offset:8384
	s_nop 0
	v_addc_co_u32_e64 v21, s[0:1], 0, v11, s[0:1]
	global_load_dword v41, v[20:21], off
	v_add_co_u32_e64 v20, s[0:1], s66, v10
	s_waitcnt vmcnt(10) lgkmcnt(1)
	v_fmac_f32_e32 v17, v19, v24
	v_addc_co_u32_e64 v21, s[0:1], 0, v11, s[0:1]
	global_load_dword v42, v[20:21], off
	v_add_co_u32_e64 v20, s[0:1], s67, v10
	s_waitcnt lgkmcnt(0)
	v_fmac_f32_e32 v18, v19, v28
	v_addc_co_u32_e64 v21, s[0:1], 0, v11, s[0:1]
	global_load_dword v43, v[20:21], off
	v_add_co_u32_e64 v20, s[0:1], s68, v10
	s_waitcnt vmcnt(11)
	v_fmac_f32_e32 v17, v32, v25
	v_addc_co_u32_e64 v21, s[0:1], 0, v11, s[0:1]
	global_load_dword v44, v[20:21], off
	v_add_co_u32_e64 v20, s[0:1], s69, v10
	v_fmac_f32_e32 v18, v32, v29
	s_nop 0
	v_addc_co_u32_e64 v21, s[0:1], 0, v11, s[0:1]
	v_add_co_u32_e64 v10, s[0:1], s70, v10
	global_load_dword v45, v[20:21], off
	s_nop 0
	v_addc_co_u32_e64 v11, s[0:1], 0, v11, s[0:1]
	global_load_dword v10, v[10:11], off
	ds_read_b128 v[20:23], v3 offset:192
	s_waitcnt vmcnt(13)
	v_fmac_f32_e32 v17, v33, v26
	v_fmac_f32_e32 v18, v33, v30
	s_waitcnt vmcnt(12)
	v_fmac_f32_e32 v17, v34, v27
	ds_read_b128 v[24:27], v3 offset:4304
	s_waitcnt lgkmcnt(1)
	v_fmac_f32_e32 v16, v19, v20
	v_fmac_f32_e32 v16, v32, v21
	v_fmac_f32_e32 v16, v33, v22
	v_fmac_f32_e32 v16, v34, v23
	ds_read_b128 v[20:23], v3 offset:208
	v_fmac_f32_e32 v18, v34, v31
	ds_read_b128 v[28:31], v3 offset:8400
	s_waitcnt vmcnt(11) lgkmcnt(2)
	v_fmac_f32_e32 v17, v35, v24
	s_waitcnt vmcnt(10)
	v_fmac_f32_e32 v17, v36, v25
	s_waitcnt lgkmcnt(1)
	v_fmac_f32_e32 v16, v35, v20
	v_fmac_f32_e32 v16, v36, v21
	s_waitcnt lgkmcnt(0)
	v_fmac_f32_e32 v18, v35, v28
	v_fmac_f32_e32 v18, v36, v29
	s_waitcnt vmcnt(9)
	v_fmac_f32_e32 v16, v37, v22
	v_fmac_f32_e32 v17, v37, v26
	v_fmac_f32_e32 v18, v37, v30
	s_waitcnt vmcnt(8)
	v_fmac_f32_e32 v16, v38, v23
	v_fmac_f32_e32 v17, v38, v27
	ds_read_b128 v[20:23], v3 offset:224
	ds_read_b128 v[24:27], v3 offset:4320
	v_fmac_f32_e32 v18, v38, v31
	ds_read_b128 v[28:31], v3 offset:8416
	s_waitcnt vmcnt(7) lgkmcnt(2)
	v_fmac_f32_e32 v16, v39, v20
	s_waitcnt lgkmcnt(1)
	v_fmac_f32_e32 v17, v39, v24
	s_waitcnt vmcnt(6)
	v_fmac_f32_e32 v16, v40, v21
	s_waitcnt lgkmcnt(0)
	v_fmac_f32_e32 v18, v39, v28
	v_fmac_f32_e32 v17, v40, v25
	v_fmac_f32_e32 v18, v40, v29
	s_waitcnt vmcnt(5)
	v_fmac_f32_e32 v16, v41, v22
	v_fmac_f32_e32 v17, v41, v26
	v_fmac_f32_e32 v18, v41, v30
	s_waitcnt vmcnt(4)
	v_fmac_f32_e32 v16, v42, v23
	v_fmac_f32_e32 v17, v42, v27
	ds_read_b128 v[20:23], v3 offset:240
	ds_read_b128 v[24:27], v3 offset:4336
	v_fmac_f32_e32 v18, v42, v31
	ds_read_b128 v[28:31], v3 offset:8432
	s_waitcnt vmcnt(3) lgkmcnt(2)
	v_fmac_f32_e32 v16, v43, v20
	s_waitcnt lgkmcnt(1)
	v_fmac_f32_e32 v17, v43, v24
	s_waitcnt lgkmcnt(0)
	v_fmac_f32_e32 v18, v43, v28
	s_waitcnt vmcnt(2)
	v_fmac_f32_e32 v16, v44, v21
	v_fmac_f32_e32 v17, v44, v25
	v_fmac_f32_e32 v18, v44, v29
	s_waitcnt vmcnt(1)
	v_fmac_f32_e32 v16, v45, v22
	v_fmac_f32_e32 v17, v45, v26
	v_fmac_f32_e32 v18, v45, v30
	s_waitcnt vmcnt(0)
	v_fmac_f32_e32 v16, v10, v23
	v_fmac_f32_e32 v17, v10, v27
	v_fmac_f32_e32 v18, v10, v31
	s_setprio 1
	ds_write2_b32 v15, v16, v17 offset1:16
	ds_write_b32 v13, v18 offset:12416
	s_waitcnt lgkmcnt(0)
	s_barrier
	s_setprio 0
	s_and_saveexec_b64 s[0:1], vcc
	s_cbranch_execz .LBB0_63
	v_add_u32_e32 v10, s6, v2
	v_readlane_b32 s12, v248, 25
	v_ashrrev_i32_e32 v11, 31, v10
	v_readlane_b32 s16, v248, 29
	v_readlane_b32 s17, v248, 30
	v_add_u32_e32 v17, v12, v4
	v_add_u32_e32 v18, 0x3000, v17
	v_lshl_add_u64 v[10:11], v[10:11], 2, s[16:17]
	global_load_dword v16, v[10:11], off
	ds_read2_b32 v[10:11], v18 offset1:48
	s_mulk_i32 s4, 0x1800
	s_add_i32 s4, s4, s6
	v_readlane_b32 s13, v248, 26
	v_readlane_b32 s14, v248, 27
	v_readlane_b32 s15, v248, 28
	v_readlane_b32 s18, v248, 31
	v_readlane_b32 s19, v248, 32
	v_readlane_b32 s20, v248, 33
	v_readlane_b32 s21, v248, 34
	v_readlane_b32 s22, v248, 35
	v_readlane_b32 s23, v248, 36
	v_readlane_b32 s24, v248, 37
	v_readlane_b32 s25, v248, 38
	v_readlane_b32 s26, v248, 39
	v_readlane_b32 s27, v248, 40
	s_waitcnt vmcnt(0) lgkmcnt(0)
	v_add_f32_e32 v10, v16, v10
	v_add_f32_e32 v16, v10, v11
	ds_read2_b32 v[10:11], v18 offset0:96 offset1:144
	s_waitcnt lgkmcnt(0)
	v_add_f32_e32 v10, v16, v10
	v_add_f32_e32 v16, v10, v11
	ds_read2_b32 v[10:11], v18 offset0:192 offset1:240
	v_add_u32_e32 v18, 0x3400, v17
	s_waitcnt lgkmcnt(0)
	v_add_f32_e32 v10, v16, v10
	v_add_f32_e32 v16, v10, v11
	ds_read2_b32 v[10:11], v18 offset0:32 offset1:80
	s_waitcnt lgkmcnt(0)
	v_add_f32_e32 v10, v16, v10
	v_add_f32_e32 v16, v10, v11
	ds_read2_b32 v[10:11], v18 offset0:128 offset1:176
	s_waitcnt lgkmcnt(0)
	v_add_f32_e32 v10, v16, v10
	v_add_f32_e32 v16, v10, v11
	v_add_u32_e32 v10, 0x3600, v17
	ds_read2_b32 v[10:11], v10 offset0:96 offset1:144
	v_add_u32_e32 v17, 0x3800, v17
	s_waitcnt lgkmcnt(0)
	v_add_f32_e32 v10, v16, v10
	v_add_f32_e32 v16, v10, v11
	ds_read2_b32 v[10:11], v17 offset0:64 offset1:112
	s_waitcnt lgkmcnt(0)
	v_add_f32_e32 v10, v16, v10
	v_add_f32_e32 v16, v10, v11
	ds_read2_b32 v[10:11], v17 offset0:160 offset1:208
	s_waitcnt lgkmcnt(0)
	v_add_f32_e32 v10, v16, v10
	v_add_f32_e32 v16, v10, v11
	v_add_u32_e32 v10, s4, v14
	v_ashrrev_i32_e32 v11, 31, v10
	v_lshl_add_u64 v[10:11], v[10:11], 2, s[2:3]
	global_store_dword v[10:11], v16, off
	s_branch .LBB0_63

.LBB0_140:
	s_ashr_i32 s11, s10, 31
	s_lshl_b64 s[10:11], s[10:11], 2
	s_add_u32 s4, s4, s10
	s_addc_u32 s5, s5, s11
	v_or_b32_e32 v20, s0, v6
	v_add_u32_e32 v22, s0, v9
	v_lshl_add_u64 v[32:33], s[4:5], 0, v[2:3]
	v_mul_hi_u32_u24_e32 v21, s8, v20
	v_mul_u32_u24_e32 v20, s8, v20
	v_mul_hi_u32_u24_e32 v23, s8, v22
	v_mul_u32_u24_e32 v22, s8, v22
	v_lshl_add_u64 v[20:21], v[20:21], 2, v[32:33]
	v_lshl_add_u64 v[24:25], v[22:23], 2, v[32:33]
	global_load_dwordx4 v[20:23], v[20:21], off
	s_nop 0
	global_load_dwordx4 v[24:27], v[24:25], off
	v_add_u32_e32 v28, s0, v10
	v_mul_hi_u32_u24_e32 v29, s8, v28
	v_mul_u32_u24_e32 v28, s8, v28
	v_lshl_add_u64 v[28:29], v[28:29], 2, v[32:33]
	v_add_u32_e32 v34, s0, v11
	global_load_dwordx4 v[28:31], v[28:29], off
	v_mul_hi_u32_u24_e32 v35, s8, v34
	v_mul_u32_u24_e32 v34, s8, v34
	v_lshl_add_u64 v[32:33], v[34:35], 2, v[32:33]
	global_load_dwordx4 v[32:35], v[32:33], off
	v_add_u32_e32 v38, s27, v7
	v_ashrrev_i32_e32 v39, 31, v38
	v_mul_lo_u32 v40, s7, v38
	v_mad_u64_u32 v[36:37], s[4:5], s6, v38, 0
	v_add_u32_e32 v38, 32, v38
	v_mul_lo_u32 v41, s6, v39
	v_ashrrev_i32_e32 v42, 31, v38
	v_mul_lo_u32 v43, s7, v38
	v_mad_u64_u32 v[38:39], s[4:5], s6, v38, 0
	v_add3_u32 v37, v37, v41, v40
	v_mul_lo_u32 v40, s6, v42
	v_add3_u32 v39, v39, v40, v43
	s_lshl_b64 s[4:5], s[0:1], 1
	s_add_u32 s2, s2, s4
	s_addc_u32 s3, s3, s5
	s_add_i32 s26, s26, s50
	s_add_i32 s21, s21, s22
	s_add_i32 s13, s13, s23
	s_add_i32 s24, s24, s25
	v_lshl_add_u64 v[40:41], s[2:3], 0, v[4:5]
	s_cmpk_gt_i32 s26, 0x147f
	v_lshl_add_u64 v[36:37], v[36:37], 1, v[40:41]
	v_lshl_add_u64 v[38:39], v[38:39], 1, v[40:41]
	s_setprio 1
	s_waitcnt vmcnt(3)
	ds_write2_b32 v12, v20, v21 offset1:1
	ds_write2_b32 v12, v22, v23 offset0:2 offset1:3
	s_waitcnt vmcnt(2)
	ds_write2_b32 v13, v24, v25 offset1:1
	ds_write2_b32 v14, v26, v27 offset1:1
	s_waitcnt vmcnt(1)
	ds_write2_b32 v15, v28, v29 offset1:1
	ds_write2_b32 v16, v30, v31 offset1:1
	s_waitcnt vmcnt(0)
	ds_write2_b32 v17, v32, v33 offset1:1
	ds_write2_b32 v18, v34, v35 offset1:1
	s_waitcnt lgkmcnt(0)
	s_barrier
	s_setprio 0
	ds_read2_b32 v[24:25], v8 offset1:32
	ds_read2_b32 v[26:27], v8 offset0:65 offset1:97
	ds_read2_b32 v[28:29], v8 offset0:130 offset1:162
	ds_read2_b32 v[30:31], v8 offset0:195 offset1:227
	ds_read2_b32 v[32:33], v19 offset0:4 offset1:36
	ds_read2_b32 v[34:35], v19 offset0:69 offset1:101
	ds_read2_b32 v[42:43], v19 offset0:134 offset1:166
	ds_read2_b32 v[44:45], v19 offset0:199 offset1:231
	s_waitcnt lgkmcnt(6)
	v_cvt_pk_bf16_f32 v20, v24, v26
	s_waitcnt lgkmcnt(4)
	v_cvt_pk_bf16_f32 v21, v28, v30
	s_waitcnt lgkmcnt(2)
	v_cvt_pk_bf16_f32 v22, v32, v34
	v_cvt_pk_bf16_f32 v24, v25, v27
	s_waitcnt lgkmcnt(0)
	v_cvt_pk_bf16_f32 v23, v42, v44
	v_cvt_pk_bf16_f32 v25, v29, v31
	v_cvt_pk_bf16_f32 v26, v33, v35
	v_cvt_pk_bf16_f32 v27, v43, v45
	global_store_dwordx4 v[36:37], v[20:23], off
	global_store_dwordx4 v[38:39], v[24:27], off
	s_barrier
	s_cbranch_scc1 .LBB0_153

.LBB0_155:
	s_and_saveexec_b64 s[4:5], s[2:3]
	ds_write_b32 v45, v44 offset:16384
	s_or_b64 exec, exec, s[4:5]
	s_ashr_i32 s4, s9, 7
	s_lshl_b32 s0, s9, 5
	s_ashr_i32 s5, s4, 31
	s_and_b32 s10, s0, 0x3e0
	s_lshl_b64 s[12:13], s[4:5], 10
	s_or_b32 s12, s12, s10
	v_mov_b32_e32 v13, s13
	v_or_b32_e32 v12, s12, v130
	v_readlane_b32 s16, v248, 25
	s_bfe_u32 s11, s9, 0x20005
	v_lshlrev_b64 v[12:13], 15, v[12:13]
	v_readlane_b32 s22, v248, 31
	v_readlane_b32 s23, v248, 32
	s_lshl_b32 s0, s11, 9
	v_lshl_add_u64 v[14:15], s[12:13], 0, v[4:5]
	v_lshl_add_u64 v[12:13], s[22:23], 0, v[12:13]
	v_lshl_add_u64 v[12:13], v[12:13], 0, s[0:1]
	v_lshlrev_b64 v[14:15], 15, v[14:15]
	v_lshl_add_u64 v[12:13], v[12:13], 0, v[10:11]
	v_lshl_add_u64 v[14:15], s[22:23], 0, v[14:15]
	v_add_co_u32_e32 v12, vcc, s8, v12
	v_lshl_add_u64 v[14:15], v[14:15], 0, s[0:1]
	s_nop 0
	v_addc_co_u32_e32 v13, vcc, 0, v13, vcc
	v_lshl_add_u64 v[14:15], v[14:15], 0, v[10:11]
	v_add_co_u32_e32 v14, vcc, s8, v14
	v_mov_b32_e32 v2, v50
	s_nop 0
	v_addc_co_u32_e32 v15, vcc, 0, v15, vcc
	global_load_dwordx4 v[54:57], v[12:13], off
	global_load_dwordx4 v[58:61], v[14:15], off
	v_lshl_add_u64 v[12:13], s[12:13], 0, v[6:7]
	v_lshlrev_b64 v[12:13], 15, v[12:13]
	v_lshl_add_u64 v[12:13], s[22:23], 0, v[12:13]
	v_lshl_add_u64 v[12:13], v[12:13], 0, s[0:1]
	v_lshl_add_u64 v[12:13], v[12:13], 0, v[10:11]
	v_add_co_u32_e32 v12, vcc, s8, v12
	v_readlane_b32 s17, v248, 26
	s_nop 0
	v_addc_co_u32_e32 v13, vcc, 0, v13, vcc
	global_load_dwordx4 v[62:65], v[12:13], off
	v_lshl_add_u64 v[12:13], s[12:13], 0, v[8:9]
	v_lshlrev_b64 v[12:13], 15, v[12:13]
	v_lshl_add_u64 v[12:13], s[22:23], 0, v[12:13]
	v_lshl_add_u64 v[12:13], v[12:13], 0, s[0:1]
	v_lshl_add_u64 v[12:13], v[12:13], 0, v[10:11]
	v_add_co_u32_e32 v12, vcc, s8, v12
	s_mov_b32 s0, 0
	s_nop 0
	v_addc_co_u32_e32 v13, vcc, 0, v13, vcc
	global_load_dwordx4 v[66:69], v[12:13], off
	v_mov_b32_e32 v12, 0
	v_mov_b32_e32 v13, v12
	v_mov_b32_e32 v28, v12
	v_mov_b32_e32 v29, v12
	v_mov_b32_e32 v34, v12
	v_mov_b32_e32 v35, v12
	v_mov_b32_e32 v38, v12
	v_mov_b32_e32 v39, v12
	v_mov_b32_e32 v40, v12
	v_mov_b32_e32 v41, v12
	v_mov_b32_e32 v22, v12
	v_mov_b32_e32 v23, v12
	v_mov_b32_e32 v26, v12
	v_mov_b32_e32 v27, v12
	v_mov_b32_e32 v32, v12
	v_mov_b32_e32 v33, v12
	v_mov_b32_e32 v36, v12
	v_mov_b32_e32 v37, v12
	v_mov_b32_e32 v18, v12
	v_mov_b32_e32 v19, v12
	v_mov_b32_e32 v20, v12
	v_mov_b32_e32 v21, v12
	v_mov_b32_e32 v24, v12
	v_mov_b32_e32 v25, v12
	v_mov_b32_e32 v30, v12
	v_mov_b32_e32 v31, v12
	v_mov_b32_e32 v14, v12
	v_mov_b32_e32 v15, v12
	v_mov_b32_e32 v16, v12
	v_mov_b32_e32 v17, v12
	v_mov_b32_e32 v42, v12
	v_mov_b32_e32 v43, v12
	v_readlane_b32 s18, v248, 27
	v_readlane_b32 s19, v248, 28
	v_readlane_b32 s20, v248, 29
	v_readlane_b32 s21, v248, 30
	v_readlane_b32 s24, v248, 33
	v_readlane_b32 s25, v248, 34
	v_readlane_b32 s26, v248, 35
	v_readlane_b32 s27, v248, 36
	v_readlane_b32 s28, v248, 37
	v_readlane_b32 s29, v248, 38
	v_readlane_b32 s30, v248, 39
	v_readlane_b32 s31, v248, 40
	s_setprio 1
	s_waitcnt vmcnt(3)
	ds_write2_b32 v46, v54, v55 offset1:32
	ds_write2_b32 v46, v56, v57 offset0:64 offset1:96
	s_waitcnt vmcnt(2)
	ds_write2_b32 v47, v58, v59 offset1:32
	ds_write2_b32 v47, v60, v61 offset0:64 offset1:96
	s_waitcnt vmcnt(1)
	ds_write2_b32 v48, v62, v63 offset1:32
	ds_write2_b32 v48, v64, v65 offset0:64 offset1:96
	s_waitcnt vmcnt(0)
	ds_write2_b32 v49, v66, v67 offset1:32
	ds_write2_b32 v49, v68, v69 offset0:64 offset1:96
	s_waitcnt lgkmcnt(0)
	s_barrier
	s_setprio 0

.LBB0_257:
	v_ashrrev_i32_e32 v3, 31, v2
	v_lshlrev_b64 v[2:3], 11, v[2:3]
	v_lshl_add_u64 v[70:71], v[86:87], 0, v[2:3]
	v_or_b32_e32 v2, s56, v154
	v_ashrrev_i32_e32 v3, 31, v2
	v_lshlrev_b64 v[2:3], 11, v[2:3]
	v_lshl_add_u64 v[72:73], v[84:85], 0, v[2:3]
	v_add_u32_e32 v2, s56, v155
	v_ashrrev_i32_e32 v3, 31, v2
	v_lshlrev_b64 v[2:3], 11, v[2:3]
	v_lshl_add_u64 v[74:75], v[84:85], 0, v[2:3]
	v_add_u32_e32 v2, s56, v156
	v_ashrrev_i32_e32 v3, 31, v2
	v_lshlrev_b64 v[2:3], 11, v[2:3]
	v_lshl_add_u64 v[76:77], v[84:85], 0, v[2:3]
	v_add_u32_e32 v2, s56, v157
	v_ashrrev_i32_e32 v3, 31, v2
	v_ashrrev_i32_e32 v9, 31, v8
	v_ashrrev_i32_e32 v5, 31, v4
	v_lshlrev_b64 v[2:3], 11, v[2:3]
	v_ashrrev_i32_e32 v7, 31, v6
	v_lshlrev_b64 v[8:9], 11, v[8:9]
	v_lshlrev_b64 v[4:5], 11, v[4:5]
	v_lshl_add_u64 v[78:79], v[84:85], 0, v[2:3]
	v_lshlrev_b64 v[2:3], 11, v[6:7]
	v_lshl_add_u64 v[66:67], v[86:87], 0, v[8:9]
	v_lshl_add_u64 v[68:69], v[86:87], 0, v[4:5]
	v_lshl_add_u64 v[80:81], v[86:87], 0, v[2:3]
	global_load_dwordx4 v[2:5], v[70:71], off
	global_load_dwordx4 v[6:9], v[68:69], off
	global_load_dwordx4 v[10:13], v[66:67], off
	global_load_dwordx4 v[14:17], v[80:81], off
	global_load_dwordx4 v[18:21], v[72:73], off
	global_load_dwordx4 v[22:25], v[74:75], off
	global_load_dwordx4 v[26:29], v[76:77], off
	global_load_dwordx4 v[30:33], v[78:79], off
	global_load_dwordx4 v[122:125], v[70:71], off offset:128
	global_load_dwordx4 v[126:129], v[68:69], off offset:128
	global_load_dwordx4 v[136:139], v[66:67], off offset:128
	global_load_dwordx4 v[140:143], v[80:81], off offset:128
	global_load_dwordx4 v[144:147], v[72:73], off offset:128
	global_load_dwordx4 v[148:151], v[74:75], off offset:128
	global_load_dwordx4 v[172:175], v[76:77], off offset:128
	global_load_dwordx4 v[176:179], v[78:79], off offset:128
	s_setprio 1
	s_waitcnt vmcnt(15)
	ds_write_b128 v165, v[2:5] offset:36864
	s_waitcnt vmcnt(14)
	ds_write_b128 v165, v[6:9] offset:41472
	s_waitcnt vmcnt(13)
	ds_write_b128 v165, v[10:13] offset:46080
	s_waitcnt vmcnt(12)
	ds_write_b128 v165, v[14:17] offset:50688
	s_waitcnt vmcnt(11)
	ds_write_b128 v165, v[18:21]
	s_waitcnt vmcnt(10)
	ds_write_b128 v165, v[22:25] offset:4608
	s_waitcnt vmcnt(9)
	ds_write_b128 v165, v[26:29] offset:9216
	s_waitcnt vmcnt(8)
	ds_write_b128 v165, v[30:33] offset:13824
	s_waitcnt lgkmcnt(0)
	s_barrier
	s_setprio 0
	global_load_dwordx4 v[180:183], v[74:75], off offset:256
	global_load_dwordx4 v[184:187], v[76:77], off offset:256
	global_load_dwordx4 v[188:191], v[72:73], off offset:256
	global_load_dwordx4 v[192:195], v[70:71], off offset:256
	global_load_dwordx4 v[196:199], v[68:69], off offset:256
	global_load_dwordx4 v[200:203], v[66:67], off offset:256
	global_load_dwordx4 v[204:207], v[78:79], off offset:256
	global_load_dwordx4 v[208:211], v[80:81], off offset:256
	v_and_b32_e32 v246, 15, v1
	v_add_u32_e32 v246, 4, v246
	v_bfe_u32 v246, v246, 3, 1
	v_bfe_u32 v249, v1, 4, 2
	v_xor_b32_e32 v246, v246, v249
	v_bfe_u32 v249, v1, 5, 1
	v_sub_u32_e32 v246, v246, v249
	v_lshlrev_b32_e32 v246, 4, v246
	v_bfe_u32 v249, v1, 4, 1
	v_mul_u32_u24_e32 v249, 0x900, v249
	v_sub_u32_e32 v246, v246, v249
	v_add_u32_e32 v244, v246, v162
	v_add_u32_e32 v245, v246, v164
	ds_read_b128 v[228:231], v245 offset:36864
	ds_read_b128 v[212:215], v244
	ds_read_b128 v[236:239], v245 offset:39168
	ds_read_b128 v[240:243], v245 offset:41472
	ds_read_b128 v[252:255], v245 offset:43776
	ds_read_b128 v[216:219], v244 offset:2304
	ds_read_b128 v[220:223], v244 offset:4608
	ds_read_b128 v[224:227], v244 offset:6912
	s_waitcnt lgkmcnt(6)
	v_mfma_f32_16x16x32_bf16 v[50:53], v[212:215], v[228:231], 0
	s_waitcnt lgkmcnt(5)
	v_mfma_f32_16x16x32_bf16 v[54:57], v[212:215], v[236:239], 0
	s_waitcnt lgkmcnt(4)
	v_mfma_f32_16x16x32_bf16 v[34:37], v[212:215], v[240:243], 0
	s_waitcnt lgkmcnt(3)
	v_mfma_f32_16x16x32_bf16 v[38:41], v[212:215], v[252:255], 0
	ds_read_b128 v[212:215], v244 offset:64
	s_waitcnt lgkmcnt(3)
	v_mfma_f32_16x16x32_bf16 v[58:61], v[216:219], v[228:231], 0
	v_mfma_f32_16x16x32_bf16 v[62:65], v[216:219], v[236:239], 0
	v_mfma_f32_16x16x32_bf16 v[42:45], v[216:219], v[240:243], 0
	v_mfma_f32_16x16x32_bf16 v[46:49], v[216:219], v[252:255], 0
	ds_read_b128 v[216:219], v244 offset:2368
	s_setprio 1
	s_waitcnt vmcnt(11)
	ds_write_b128 v165, v[144:147] offset:18432
	s_waitcnt vmcnt(10)
	ds_write_b128 v165, v[148:151] offset:23040
	s_waitcnt lgkmcnt(5)
	v_mfma_f32_16x16x32_bf16 v[18:21], v[220:223], v[228:231], 0
	v_mfma_f32_16x16x32_bf16 v[22:25], v[220:223], v[236:239], 0
	v_mfma_f32_16x16x32_bf16 v[2:5], v[220:223], v[240:243], 0
	v_mfma_f32_16x16x32_bf16 v[6:9], v[220:223], v[252:255], 0
	ds_read_b128 v[220:223], v244 offset:4672
	s_waitcnt vmcnt(9)
	ds_write_b128 v165, v[172:175] offset:27648
	s_waitcnt vmcnt(8)
	ds_write_b128 v165, v[176:179] offset:32256
	s_waitcnt lgkmcnt(7)
	v_mfma_f32_16x16x32_bf16 v[26:29], v[224:227], v[228:231], 0
	ds_read_b128 v[228:231], v245 offset:36928
	v_mfma_f32_16x16x32_bf16 v[30:33], v[224:227], v[236:239], 0
	ds_read_b128 v[236:239], v245 offset:39232
	v_mfma_f32_16x16x32_bf16 v[10:13], v[224:227], v[240:243], 0
	ds_read_b128 v[240:243], v245 offset:41536
	v_mfma_f32_16x16x32_bf16 v[14:17], v[224:227], v[252:255], 0
	ds_read_b128 v[252:255], v245 offset:43840
	ds_read_b128 v[224:227], v244 offset:6976
	s_waitcnt lgkmcnt(4)
	v_mfma_f32_16x16x32_bf16 v[50:53], v[212:215], v[228:231], v[50:53]
	s_waitcnt lgkmcnt(3)
	v_mfma_f32_16x16x32_bf16 v[54:57], v[212:215], v[236:239], v[54:57]
	s_waitcnt lgkmcnt(2)
	v_mfma_f32_16x16x32_bf16 v[34:37], v[212:215], v[240:243], v[34:37]
	s_waitcnt lgkmcnt(1)
	v_mfma_f32_16x16x32_bf16 v[38:41], v[212:215], v[252:255], v[38:41]
	ds_write_b128 v165, v[122:125] offset:55296
	ds_write_b128 v165, v[126:129] offset:59904
	v_mfma_f32_16x16x32_bf16 v[58:61], v[216:219], v[228:231], v[58:61]
	v_mfma_f32_16x16x32_bf16 v[62:65], v[216:219], v[236:239], v[62:65]
	v_mfma_f32_16x16x32_bf16 v[42:45], v[216:219], v[240:243], v[42:45]
	v_mfma_f32_16x16x32_bf16 v[46:49], v[216:219], v[252:255], v[46:49]
	ds_write_b128 v165, v[136:139] offset:64512
	ds_write_b128 v166, v[140:143] offset:32256
	v_mfma_f32_16x16x32_bf16 v[18:21], v[220:223], v[228:231], v[18:21]
	v_mfma_f32_16x16x32_bf16 v[22:25], v[220:223], v[236:239], v[22:25]
	v_mfma_f32_16x16x32_bf16 v[2:5], v[220:223], v[240:243], v[2:5]
	v_mfma_f32_16x16x32_bf16 v[6:9], v[220:223], v[252:255], v[6:9]
	s_waitcnt lgkmcnt(4)
	v_mfma_f32_16x16x32_bf16 v[26:29], v[224:227], v[228:231], v[26:29]
	v_mfma_f32_16x16x32_bf16 v[30:33], v[224:227], v[236:239], v[30:33]
	v_mfma_f32_16x16x32_bf16 v[10:13], v[224:227], v[240:243], v[10:13]
	v_mfma_f32_16x16x32_bf16 v[14:17], v[224:227], v[252:255], v[14:17]
	s_waitcnt lgkmcnt(0)
	s_barrier
	s_setprio 0
	global_load_dwordx4 v[122:125], v[72:73], off offset:384
	global_load_dwordx4 v[126:129], v[74:75], off offset:384
	global_load_dwordx4 v[136:139], v[76:77], off offset:384
	global_load_dwordx4 v[140:143], v[78:79], off offset:384
	global_load_dwordx4 v[144:147], v[70:71], off offset:384
	global_load_dwordx4 v[148:151], v[68:69], off offset:384
	global_load_dwordx4 v[172:175], v[66:67], off offset:384
	global_load_dwordx4 v[176:179], v[80:81], off offset:384
	ds_read_b128 v[228:231], v245 offset:55296
	ds_read_b128 v[212:215], v244 offset:18432
	ds_read_b128 v[236:239], v245 offset:57600
	ds_read_b128 v[240:243], v245 offset:59904
	ds_read_b128 v[252:255], v245 offset:62208
	ds_read_b128 v[216:219], v244 offset:20736
	ds_read_b128 v[220:223], v244 offset:23040
	ds_read_b128 v[224:227], v244 offset:25344
	s_waitcnt lgkmcnt(6)
	v_mfma_f32_16x16x32_bf16 v[50:53], v[212:215], v[228:231], v[50:53]
	s_waitcnt lgkmcnt(5)
	v_mfma_f32_16x16x32_bf16 v[54:57], v[212:215], v[236:239], v[54:57]
	s_waitcnt lgkmcnt(4)
	v_mfma_f32_16x16x32_bf16 v[34:37], v[212:215], v[240:243], v[34:37]
	s_waitcnt lgkmcnt(3)
	v_mfma_f32_16x16x32_bf16 v[38:41], v[212:215], v[252:255], v[38:41]
	ds_read_b128 v[212:215], v244 offset:18496
	s_waitcnt lgkmcnt(3)
	v_mfma_f32_16x16x32_bf16 v[58:61], v[216:219], v[228:231], v[58:61]
	v_mfma_f32_16x16x32_bf16 v[62:65], v[216:219], v[236:239], v[62:65]
	v_mfma_f32_16x16x32_bf16 v[42:45], v[216:219], v[240:243], v[42:45]
	v_mfma_f32_16x16x32_bf16 v[46:49], v[216:219], v[252:255], v[46:49]
	ds_read_b128 v[216:219], v244 offset:20800
	s_setprio 1
	s_waitcnt vmcnt(13)
	ds_write_b128 v165, v[188:191]
	ds_write_b128 v165, v[180:183] offset:4608
	s_waitcnt lgkmcnt(5)
	v_mfma_f32_16x16x32_bf16 v[18:21], v[220:223], v[228:231], v[18:21]
	v_mfma_f32_16x16x32_bf16 v[22:25], v[220:223], v[236:239], v[22:25]
	v_mfma_f32_16x16x32_bf16 v[2:5], v[220:223], v[240:243], v[2:5]
	v_mfma_f32_16x16x32_bf16 v[6:9], v[220:223], v[252:255], v[6:9]
	ds_read_b128 v[220:223], v244 offset:23104
	ds_write_b128 v165, v[184:187] offset:9216
	s_waitcnt vmcnt(9)
	ds_write_b128 v165, v[204:207] offset:13824
	s_waitcnt lgkmcnt(7)
	v_mfma_f32_16x16x32_bf16 v[26:29], v[224:227], v[228:231], v[26:29]
	ds_read_b128 v[228:231], v245 offset:55360
	v_mfma_f32_16x16x32_bf16 v[30:33], v[224:227], v[236:239], v[30:33]
	ds_read_b128 v[236:239], v245 offset:57664
	v_mfma_f32_16x16x32_bf16 v[10:13], v[224:227], v[240:243], v[10:13]
	ds_read_b128 v[240:243], v245 offset:59968
	v_mfma_f32_16x16x32_bf16 v[14:17], v[224:227], v[252:255], v[14:17]
	ds_read_b128 v[252:255], v245 offset:62272
	ds_read_b128 v[224:227], v244 offset:25408
	s_waitcnt lgkmcnt(4)
	v_mfma_f32_16x16x32_bf16 v[50:53], v[212:215], v[228:231], v[50:53]
	s_waitcnt lgkmcnt(3)
	v_mfma_f32_16x16x32_bf16 v[54:57], v[212:215], v[236:239], v[54:57]
	s_waitcnt lgkmcnt(2)
	v_mfma_f32_16x16x32_bf16 v[34:37], v[212:215], v[240:243], v[34:37]
	s_waitcnt lgkmcnt(1)
	v_mfma_f32_16x16x32_bf16 v[38:41], v[212:215], v[252:255], v[38:41]
	ds_write_b128 v165, v[192:195] offset:36864
	ds_write_b128 v165, v[196:199] offset:41472
	v_mfma_f32_16x16x32_bf16 v[58:61], v[216:219], v[228:231], v[58:61]
	v_mfma_f32_16x16x32_bf16 v[62:65], v[216:219], v[236:239], v[62:65]
	v_mfma_f32_16x16x32_bf16 v[42:45], v[216:219], v[240:243], v[42:45]
	v_mfma_f32_16x16x32_bf16 v[46:49], v[216:219], v[252:255], v[46:49]
	ds_write_b128 v165, v[200:203] offset:46080
	s_waitcnt vmcnt(8)
	ds_write_b128 v165, v[208:211] offset:50688
	v_mfma_f32_16x16x32_bf16 v[18:21], v[220:223], v[228:231], v[18:21]
	v_mfma_f32_16x16x32_bf16 v[22:25], v[220:223], v[236:239], v[22:25]
	v_mfma_f32_16x16x32_bf16 v[2:5], v[220:223], v[240:243], v[2:5]
	v_mfma_f32_16x16x32_bf16 v[6:9], v[220:223], v[252:255], v[6:9]
	s_waitcnt lgkmcnt(4)
	v_mfma_f32_16x16x32_bf16 v[26:29], v[224:227], v[228:231], v[26:29]
	v_mfma_f32_16x16x32_bf16 v[30:33], v[224:227], v[236:239], v[30:33]
	v_mfma_f32_16x16x32_bf16 v[10:13], v[224:227], v[240:243], v[10:13]
	v_mfma_f32_16x16x32_bf16 v[14:17], v[224:227], v[252:255], v[14:17]
	s_waitcnt lgkmcnt(0)
	s_barrier
	s_setprio 0
	global_load_dwordx4 v[180:183], v[72:73], off offset:512
	global_load_dwordx4 v[184:187], v[74:75], off offset:512
	global_load_dwordx4 v[188:191], v[76:77], off offset:512
	global_load_dwordx4 v[192:195], v[78:79], off offset:512
	global_load_dwordx4 v[196:199], v[70:71], off offset:512
	global_load_dwordx4 v[200:203], v[68:69], off offset:512
	global_load_dwordx4 v[204:207], v[66:67], off offset:512
	global_load_dwordx4 v[208:211], v[80:81], off offset:512
	ds_read_b128 v[228:231], v245 offset:36864
	ds_read_b128 v[212:215], v244
	ds_read_b128 v[236:239], v245 offset:39168
	ds_read_b128 v[240:243], v245 offset:41472
	ds_read_b128 v[252:255], v245 offset:43776
	ds_read_b128 v[216:219], v244 offset:2304
	ds_read_b128 v[220:223], v244 offset:4608
	ds_read_b128 v[224:227], v244 offset:6912
	s_waitcnt lgkmcnt(6)
	v_mfma_f32_16x16x32_bf16 v[50:53], v[212:215], v[228:231], v[50:53]
	s_waitcnt lgkmcnt(5)
	v_mfma_f32_16x16x32_bf16 v[54:57], v[212:215], v[236:239], v[54:57]
	s_waitcnt lgkmcnt(4)
	v_mfma_f32_16x16x32_bf16 v[34:37], v[212:215], v[240:243], v[34:37]
	s_waitcnt lgkmcnt(3)
	v_mfma_f32_16x16x32_bf16 v[38:41], v[212:215], v[252:255], v[38:41]
	ds_read_b128 v[212:215], v244 offset:64
	s_waitcnt lgkmcnt(3)
	v_mfma_f32_16x16x32_bf16 v[58:61], v[216:219], v[228:231], v[58:61]
	v_mfma_f32_16x16x32_bf16 v[62:65], v[216:219], v[236:239], v[62:65]
	v_mfma_f32_16x16x32_bf16 v[42:45], v[216:219], v[240:243], v[42:45]
	v_mfma_f32_16x16x32_bf16 v[46:49], v[216:219], v[252:255], v[46:49]
	ds_read_b128 v[216:219], v244 offset:2368
	s_setprio 1
	s_waitcnt vmcnt(15)
	ds_write_b128 v165, v[122:125] offset:18432
	s_waitcnt vmcnt(14)
	ds_write_b128 v165, v[126:129] offset:23040
	s_waitcnt lgkmcnt(5)
	v_mfma_f32_16x16x32_bf16 v[18:21], v[220:223], v[228:231], v[18:21]
	v_mfma_f32_16x16x32_bf16 v[22:25], v[220:223], v[236:239], v[22:25]
	v_mfma_f32_16x16x32_bf16 v[2:5], v[220:223], v[240:243], v[2:5]
	v_mfma_f32_16x16x32_bf16 v[6:9], v[220:223], v[252:255], v[6:9]
	ds_read_b128 v[220:223], v244 offset:4672
	s_waitcnt vmcnt(13)
	ds_write_b128 v165, v[136:139] offset:27648
	s_waitcnt vmcnt(12)
	ds_write_b128 v165, v[140:143] offset:32256
	s_waitcnt lgkmcnt(7)
	v_mfma_f32_16x16x32_bf16 v[26:29], v[224:227], v[228:231], v[26:29]
	ds_read_b128 v[228:231], v245 offset:36928
	v_mfma_f32_16x16x32_bf16 v[30:33], v[224:227], v[236:239], v[30:33]
	ds_read_b128 v[236:239], v245 offset:39232
	v_mfma_f32_16x16x32_bf16 v[10:13], v[224:227], v[240:243], v[10:13]
	ds_read_b128 v[240:243], v245 offset:41536
	v_mfma_f32_16x16x32_bf16 v[14:17], v[224:227], v[252:255], v[14:17]
	ds_read_b128 v[252:255], v245 offset:43840
	ds_read_b128 v[224:227], v244 offset:6976
	s_waitcnt lgkmcnt(4)
	v_mfma_f32_16x16x32_bf16 v[50:53], v[212:215], v[228:231], v[50:53]
	s_waitcnt lgkmcnt(3)
	v_mfma_f32_16x16x32_bf16 v[54:57], v[212:215], v[236:239], v[54:57]
	s_waitcnt lgkmcnt(2)
	v_mfma_f32_16x16x32_bf16 v[34:37], v[212:215], v[240:243], v[34:37]
	s_waitcnt lgkmcnt(1)
	v_mfma_f32_16x16x32_bf16 v[38:41], v[212:215], v[252:255], v[38:41]
	s_waitcnt vmcnt(11)
	ds_write_b128 v165, v[144:147] offset:55296
	s_waitcnt vmcnt(10)
	ds_write_b128 v165, v[148:151] offset:59904
	v_mfma_f32_16x16x32_bf16 v[58:61], v[216:219], v[228:231], v[58:61]
	v_mfma_f32_16x16x32_bf16 v[62:65], v[216:219], v[236:239], v[62:65]
	v_mfma_f32_16x16x32_bf16 v[42:45], v[216:219], v[240:243], v[42:45]
	v_mfma_f32_16x16x32_bf16 v[46:49], v[216:219], v[252:255], v[46:49]
	s_waitcnt vmcnt(9)
	ds_write_b128 v165, v[172:175] offset:64512
	s_waitcnt vmcnt(8)
	ds_write_b128 v166, v[176:179] offset:32256
	v_mfma_f32_16x16x32_bf16 v[18:21], v[220:223], v[228:231], v[18:21]
	v_mfma_f32_16x16x32_bf16 v[22:25], v[220:223], v[236:239], v[22:25]
	v_mfma_f32_16x16x32_bf16 v[2:5], v[220:223], v[240:243], v[2:5]
	v_mfma_f32_16x16x32_bf16 v[6:9], v[220:223], v[252:255], v[6:9]
	s_waitcnt lgkmcnt(4)
	v_mfma_f32_16x16x32_bf16 v[26:29], v[224:227], v[228:231], v[26:29]
	v_mfma_f32_16x16x32_bf16 v[30:33], v[224:227], v[236:239], v[30:33]
	v_mfma_f32_16x16x32_bf16 v[10:13], v[224:227], v[240:243], v[10:13]
	v_mfma_f32_16x16x32_bf16 v[14:17], v[224:227], v[252:255], v[14:17]
	s_waitcnt lgkmcnt(0)
	s_barrier
	s_setprio 0
	global_load_dwordx4 v[122:125], v[72:73], off offset:640
	global_load_dwordx4 v[126:129], v[74:75], off offset:640
	global_load_dwordx4 v[136:139], v[76:77], off offset:640
	global_load_dwordx4 v[140:143], v[78:79], off offset:640
	global_load_dwordx4 v[144:147], v[70:71], off offset:640
	global_load_dwordx4 v[148:151], v[68:69], off offset:640
	global_load_dwordx4 v[172:175], v[66:67], off offset:640
	global_load_dwordx4 v[176:179], v[80:81], off offset:640
	ds_read_b128 v[228:231], v245 offset:55296
	ds_read_b128 v[212:215], v244 offset:18432
	ds_read_b128 v[236:239], v245 offset:57600
	ds_read_b128 v[240:243], v245 offset:59904
	ds_read_b128 v[252:255], v245 offset:62208
	ds_read_b128 v[216:219], v244 offset:20736
	ds_read_b128 v[220:223], v244 offset:23040
	ds_read_b128 v[224:227], v244 offset:25344
	s_waitcnt lgkmcnt(6)
	v_mfma_f32_16x16x32_bf16 v[50:53], v[212:215], v[228:231], v[50:53]
	s_waitcnt lgkmcnt(5)
	v_mfma_f32_16x16x32_bf16 v[54:57], v[212:215], v[236:239], v[54:57]
	s_waitcnt lgkmcnt(4)
	v_mfma_f32_16x16x32_bf16 v[34:37], v[212:215], v[240:243], v[34:37]
	s_waitcnt lgkmcnt(3)
	v_mfma_f32_16x16x32_bf16 v[38:41], v[212:215], v[252:255], v[38:41]
	ds_read_b128 v[212:215], v244 offset:18496
	s_waitcnt lgkmcnt(3)
	v_mfma_f32_16x16x32_bf16 v[58:61], v[216:219], v[228:231], v[58:61]
	v_mfma_f32_16x16x32_bf16 v[62:65], v[216:219], v[236:239], v[62:65]
	v_mfma_f32_16x16x32_bf16 v[42:45], v[216:219], v[240:243], v[42:45]
	v_mfma_f32_16x16x32_bf16 v[46:49], v[216:219], v[252:255], v[46:49]
	ds_read_b128 v[216:219], v244 offset:20800
	s_setprio 1
	s_waitcnt vmcnt(15)
	ds_write_b128 v165, v[180:183]
	s_waitcnt vmcnt(14)
	ds_write_b128 v165, v[184:187] offset:4608
	s_waitcnt lgkmcnt(5)
	v_mfma_f32_16x16x32_bf16 v[18:21], v[220:223], v[228:231], v[18:21]
	v_mfma_f32_16x16x32_bf16 v[22:25], v[220:223], v[236:239], v[22:25]
	v_mfma_f32_16x16x32_bf16 v[2:5], v[220:223], v[240:243], v[2:5]
	v_mfma_f32_16x16x32_bf16 v[6:9], v[220:223], v[252:255], v[6:9]
	ds_read_b128 v[220:223], v244 offset:23104
	s_waitcnt vmcnt(13)
	ds_write_b128 v165, v[188:191] offset:9216
	s_waitcnt vmcnt(12)
	ds_write_b128 v165, v[192:195] offset:13824
	s_waitcnt lgkmcnt(7)
	v_mfma_f32_16x16x32_bf16 v[26:29], v[224:227], v[228:231], v[26:29]
	ds_read_b128 v[228:231], v245 offset:55360
	v_mfma_f32_16x16x32_bf16 v[30:33], v[224:227], v[236:239], v[30:33]
	ds_read_b128 v[236:239], v245 offset:57664
	v_mfma_f32_16x16x32_bf16 v[10:13], v[224:227], v[240:243], v[10:13]
	ds_read_b128 v[240:243], v245 offset:59968
	v_mfma_f32_16x16x32_bf16 v[14:17], v[224:227], v[252:255], v[14:17]
	ds_read_b128 v[252:255], v245 offset:62272
	ds_read_b128 v[224:227], v244 offset:25408
	s_waitcnt lgkmcnt(4)
	v_mfma_f32_16x16x32_bf16 v[50:53], v[212:215], v[228:231], v[50:53]
	s_waitcnt lgkmcnt(3)
	v_mfma_f32_16x16x32_bf16 v[54:57], v[212:215], v[236:239], v[54:57]
	s_waitcnt lgkmcnt(2)
	v_mfma_f32_16x16x32_bf16 v[34:37], v[212:215], v[240:243], v[34:37]
	s_waitcnt lgkmcnt(1)
	v_mfma_f32_16x16x32_bf16 v[38:41], v[212:215], v[252:255], v[38:41]
	s_waitcnt vmcnt(11)
	ds_write_b128 v165, v[196:199] offset:36864
	s_waitcnt vmcnt(10)
	ds_write_b128 v165, v[200:203] offset:41472
	v_mfma_f32_16x16x32_bf16 v[58:61], v[216:219], v[228:231], v[58:61]
	v_mfma_f32_16x16x32_bf16 v[62:65], v[216:219], v[236:239], v[62:65]
	v_mfma_f32_16x16x32_bf16 v[42:45], v[216:219], v[240:243], v[42:45]
	v_mfma_f32_16x16x32_bf16 v[46:49], v[216:219], v[252:255], v[46:49]
	s_waitcnt vmcnt(9)
	ds_write_b128 v165, v[204:207] offset:46080
	s_waitcnt vmcnt(8)
	ds_write_b128 v165, v[208:211] offset:50688
	v_mfma_f32_16x16x32_bf16 v[18:21], v[220:223], v[228:231], v[18:21]
	v_mfma_f32_16x16x32_bf16 v[22:25], v[220:223], v[236:239], v[22:25]
	v_mfma_f32_16x16x32_bf16 v[2:5], v[220:223], v[240:243], v[2:5]
	v_mfma_f32_16x16x32_bf16 v[6:9], v[220:223], v[252:255], v[6:9]
	s_waitcnt lgkmcnt(4)
	v_mfma_f32_16x16x32_bf16 v[26:29], v[224:227], v[228:231], v[26:29]
	v_mfma_f32_16x16x32_bf16 v[30:33], v[224:227], v[236:239], v[30:33]
	v_mfma_f32_16x16x32_bf16 v[10:13], v[224:227], v[240:243], v[10:13]
	v_mfma_f32_16x16x32_bf16 v[14:17], v[224:227], v[252:255], v[14:17]
	s_waitcnt lgkmcnt(0)
	s_barrier
	s_setprio 0
	global_load_dwordx4 v[180:183], v[72:73], off offset:768
	global_load_dwordx4 v[184:187], v[74:75], off offset:768
	global_load_dwordx4 v[188:191], v[76:77], off offset:768
	global_load_dwordx4 v[192:195], v[78:79], off offset:768
	global_load_dwordx4 v[196:199], v[70:71], off offset:768
	global_load_dwordx4 v[200:203], v[68:69], off offset:768
	global_load_dwordx4 v[204:207], v[66:67], off offset:768
	global_load_dwordx4 v[208:211], v[80:81], off offset:768
	ds_read_b128 v[228:231], v245 offset:36864
	ds_read_b128 v[212:215], v244
	ds_read_b128 v[236:239], v245 offset:39168
	ds_read_b128 v[240:243], v245 offset:41472
	ds_read_b128 v[252:255], v245 offset:43776
	ds_read_b128 v[216:219], v244 offset:2304
	ds_read_b128 v[220:223], v244 offset:4608
	ds_read_b128 v[224:227], v244 offset:6912
	s_waitcnt lgkmcnt(6)
	v_mfma_f32_16x16x32_bf16 v[50:53], v[212:215], v[228:231], v[50:53]
	s_waitcnt lgkmcnt(5)
	v_mfma_f32_16x16x32_bf16 v[54:57], v[212:215], v[236:239], v[54:57]
	s_waitcnt lgkmcnt(4)
	v_mfma_f32_16x16x32_bf16 v[34:37], v[212:215], v[240:243], v[34:37]
	s_waitcnt lgkmcnt(3)
	v_mfma_f32_16x16x32_bf16 v[38:41], v[212:215], v[252:255], v[38:41]
	ds_read_b128 v[212:215], v244 offset:64
	s_waitcnt lgkmcnt(3)
	v_mfma_f32_16x16x32_bf16 v[58:61], v[216:219], v[228:231], v[58:61]
	v_mfma_f32_16x16x32_bf16 v[62:65], v[216:219], v[236:239], v[62:65]
	v_mfma_f32_16x16x32_bf16 v[42:45], v[216:219], v[240:243], v[42:45]
	v_mfma_f32_16x16x32_bf16 v[46:49], v[216:219], v[252:255], v[46:49]
	ds_read_b128 v[216:219], v244 offset:2368
	s_setprio 1
	s_waitcnt vmcnt(15)
	ds_write_b128 v165, v[122:125] offset:18432
	s_waitcnt vmcnt(14)
	ds_write_b128 v165, v[126:129] offset:23040
	s_waitcnt lgkmcnt(5)
	v_mfma_f32_16x16x32_bf16 v[18:21], v[220:223], v[228:231], v[18:21]
	v_mfma_f32_16x16x32_bf16 v[22:25], v[220:223], v[236:239], v[22:25]
	v_mfma_f32_16x16x32_bf16 v[2:5], v[220:223], v[240:243], v[2:5]
	v_mfma_f32_16x16x32_bf16 v[6:9], v[220:223], v[252:255], v[6:9]
	ds_read_b128 v[220:223], v244 offset:4672
	s_waitcnt vmcnt(13)
	ds_write_b128 v165, v[136:139] offset:27648
	s_waitcnt vmcnt(12)
	ds_write_b128 v165, v[140:143] offset:32256
	s_waitcnt lgkmcnt(7)
	v_mfma_f32_16x16x32_bf16 v[26:29], v[224:227], v[228:231], v[26:29]
	ds_read_b128 v[228:231], v245 offset:36928
	v_mfma_f32_16x16x32_bf16 v[30:33], v[224:227], v[236:239], v[30:33]
	ds_read_b128 v[236:239], v245 offset:39232
	v_mfma_f32_16x16x32_bf16 v[10:13], v[224:227], v[240:243], v[10:13]
	ds_read_b128 v[240:243], v245 offset:41536
	v_mfma_f32_16x16x32_bf16 v[14:17], v[224:227], v[252:255], v[14:17]
	ds_read_b128 v[252:255], v245 offset:43840
	ds_read_b128 v[224:227], v244 offset:6976
	s_waitcnt lgkmcnt(4)
	v_mfma_f32_16x16x32_bf16 v[50:53], v[212:215], v[228:231], v[50:53]
	s_waitcnt lgkmcnt(3)
	v_mfma_f32_16x16x32_bf16 v[54:57], v[212:215], v[236:239], v[54:57]
	s_waitcnt lgkmcnt(2)
	v_mfma_f32_16x16x32_bf16 v[34:37], v[212:215], v[240:243], v[34:37]
	s_waitcnt lgkmcnt(1)
	v_mfma_f32_16x16x32_bf16 v[38:41], v[212:215], v[252:255], v[38:41]
	s_waitcnt vmcnt(11)
	ds_write_b128 v165, v[144:147] offset:55296
	s_waitcnt vmcnt(10)
	ds_write_b128 v165, v[148:151] offset:59904
	v_mfma_f32_16x16x32_bf16 v[58:61], v[216:219], v[228:231], v[58:61]
	v_mfma_f32_16x16x32_bf16 v[62:65], v[216:219], v[236:239], v[62:65]
	v_mfma_f32_16x16x32_bf16 v[42:45], v[216:219], v[240:243], v[42:45]
	v_mfma_f32_16x16x32_bf16 v[46:49], v[216:219], v[252:255], v[46:49]
	s_waitcnt vmcnt(9)
	ds_write_b128 v165, v[172:175] offset:64512
	s_waitcnt vmcnt(8)
	ds_write_b128 v166, v[176:179] offset:32256
	v_mfma_f32_16x16x32_bf16 v[18:21], v[220:223], v[228:231], v[18:21]
	v_mfma_f32_16x16x32_bf16 v[22:25], v[220:223], v[236:239], v[22:25]
	v_mfma_f32_16x16x32_bf16 v[2:5], v[220:223], v[240:243], v[2:5]
	v_mfma_f32_16x16x32_bf16 v[6:9], v[220:223], v[252:255], v[6:9]
	s_waitcnt lgkmcnt(4)
	v_mfma_f32_16x16x32_bf16 v[26:29], v[224:227], v[228:231], v[26:29]
	v_mfma_f32_16x16x32_bf16 v[30:33], v[224:227], v[236:239], v[30:33]
	v_mfma_f32_16x16x32_bf16 v[10:13], v[224:227], v[240:243], v[10:13]
	v_mfma_f32_16x16x32_bf16 v[14:17], v[224:227], v[252:255], v[14:17]
	s_waitcnt lgkmcnt(0)
	s_barrier
	s_setprio 0
	global_load_dwordx4 v[122:125], v[72:73], off offset:896
	global_load_dwordx4 v[126:129], v[74:75], off offset:896
	global_load_dwordx4 v[136:139], v[76:77], off offset:896
	global_load_dwordx4 v[140:143], v[78:79], off offset:896
	global_load_dwordx4 v[144:147], v[70:71], off offset:896
	global_load_dwordx4 v[148:151], v[68:69], off offset:896
	global_load_dwordx4 v[172:175], v[66:67], off offset:896
	global_load_dwordx4 v[176:179], v[80:81], off offset:896
	ds_read_b128 v[228:231], v245 offset:55296
	ds_read_b128 v[212:215], v244 offset:18432
	ds_read_b128 v[236:239], v245 offset:57600
	ds_read_b128 v[240:243], v245 offset:59904
	ds_read_b128 v[252:255], v245 offset:62208
	ds_read_b128 v[216:219], v244 offset:20736
	ds_read_b128 v[220:223], v244 offset:23040
	ds_read_b128 v[224:227], v244 offset:25344
	s_waitcnt lgkmcnt(6)
	v_mfma_f32_16x16x32_bf16 v[50:53], v[212:215], v[228:231], v[50:53]
	s_waitcnt lgkmcnt(5)
	v_mfma_f32_16x16x32_bf16 v[54:57], v[212:215], v[236:239], v[54:57]
	s_waitcnt lgkmcnt(4)
	v_mfma_f32_16x16x32_bf16 v[34:37], v[212:215], v[240:243], v[34:37]
	s_waitcnt lgkmcnt(3)
	v_mfma_f32_16x16x32_bf16 v[38:41], v[212:215], v[252:255], v[38:41]
	ds_read_b128 v[212:215], v244 offset:18496
	s_waitcnt lgkmcnt(3)
	v_mfma_f32_16x16x32_bf16 v[58:61], v[216:219], v[228:231], v[58:61]
	v_mfma_f32_16x16x32_bf16 v[62:65], v[216:219], v[236:239], v[62:65]
	v_mfma_f32_16x16x32_bf16 v[42:45], v[216:219], v[240:243], v[42:45]
	v_mfma_f32_16x16x32_bf16 v[46:49], v[216:219], v[252:255], v[46:49]
	ds_read_b128 v[216:219], v244 offset:20800
	s_setprio 1
	s_waitcnt vmcnt(15)
	ds_write_b128 v165, v[180:183]
	s_waitcnt vmcnt(14)
	ds_write_b128 v165, v[184:187] offset:4608
	s_waitcnt lgkmcnt(5)
	v_mfma_f32_16x16x32_bf16 v[18:21], v[220:223], v[228:231], v[18:21]
	v_mfma_f32_16x16x32_bf16 v[22:25], v[220:223], v[236:239], v[22:25]
	v_mfma_f32_16x16x32_bf16 v[2:5], v[220:223], v[240:243], v[2:5]
	v_mfma_f32_16x16x32_bf16 v[6:9], v[220:223], v[252:255], v[6:9]
	ds_read_b128 v[220:223], v244 offset:23104
	s_waitcnt vmcnt(13)
	ds_write_b128 v165, v[188:191] offset:9216
	s_waitcnt vmcnt(12)
	ds_write_b128 v165, v[192:195] offset:13824
	s_waitcnt lgkmcnt(7)
	v_mfma_f32_16x16x32_bf16 v[26:29], v[224:227], v[228:231], v[26:29]
	ds_read_b128 v[228:231], v245 offset:55360
	v_mfma_f32_16x16x32_bf16 v[30:33], v[224:227], v[236:239], v[30:33]
	ds_read_b128 v[236:239], v245 offset:57664
	v_mfma_f32_16x16x32_bf16 v[10:13], v[224:227], v[240:243], v[10:13]
	ds_read_b128 v[240:243], v245 offset:59968
	v_mfma_f32_16x16x32_bf16 v[14:17], v[224:227], v[252:255], v[14:17]
	ds_read_b128 v[252:255], v245 offset:62272
	ds_read_b128 v[224:227], v244 offset:25408
	s_waitcnt lgkmcnt(4)
	v_mfma_f32_16x16x32_bf16 v[50:53], v[212:215], v[228:231], v[50:53]
	s_waitcnt lgkmcnt(3)
	v_mfma_f32_16x16x32_bf16 v[54:57], v[212:215], v[236:239], v[54:57]
	s_waitcnt lgkmcnt(2)
	v_mfma_f32_16x16x32_bf16 v[34:37], v[212:215], v[240:243], v[34:37]
	s_waitcnt lgkmcnt(1)
	v_mfma_f32_16x16x32_bf16 v[38:41], v[212:215], v[252:255], v[38:41]
	s_waitcnt vmcnt(11)
	ds_write_b128 v165, v[196:199] offset:36864
	s_waitcnt vmcnt(10)
	ds_write_b128 v165, v[200:203] offset:41472
	v_mfma_f32_16x16x32_bf16 v[58:61], v[216:219], v[228:231], v[58:61]
	v_mfma_f32_16x16x32_bf16 v[62:65], v[216:219], v[236:239], v[62:65]
	v_mfma_f32_16x16x32_bf16 v[42:45], v[216:219], v[240:243], v[42:45]
	v_mfma_f32_16x16x32_bf16 v[46:49], v[216:219], v[252:255], v[46:49]
	s_waitcnt vmcnt(9)
	ds_write_b128 v165, v[204:207] offset:46080
	s_waitcnt vmcnt(8)
	ds_write_b128 v165, v[208:211] offset:50688
	v_mfma_f32_16x16x32_bf16 v[18:21], v[220:223], v[228:231], v[18:21]
	v_mfma_f32_16x16x32_bf16 v[22:25], v[220:223], v[236:239], v[22:25]
	v_mfma_f32_16x16x32_bf16 v[2:5], v[220:223], v[240:243], v[2:5]
	v_mfma_f32_16x16x32_bf16 v[6:9], v[220:223], v[252:255], v[6:9]
	s_waitcnt lgkmcnt(4)
	v_mfma_f32_16x16x32_bf16 v[26:29], v[224:227], v[228:231], v[26:29]
	v_mfma_f32_16x16x32_bf16 v[30:33], v[224:227], v[236:239], v[30:33]
	v_mfma_f32_16x16x32_bf16 v[10:13], v[224:227], v[240:243], v[10:13]
	v_mfma_f32_16x16x32_bf16 v[14:17], v[224:227], v[252:255], v[14:17]
	s_waitcnt lgkmcnt(0)
	s_barrier
	s_setprio 0
	global_load_dwordx4 v[180:183], v[72:73], off offset:1024
	global_load_dwordx4 v[184:187], v[74:75], off offset:1024
	global_load_dwordx4 v[188:191], v[76:77], off offset:1024
	global_load_dwordx4 v[192:195], v[78:79], off offset:1024
	global_load_dwordx4 v[196:199], v[70:71], off offset:1024
	global_load_dwordx4 v[200:203], v[68:69], off offset:1024
	global_load_dwordx4 v[204:207], v[66:67], off offset:1024
	global_load_dwordx4 v[208:211], v[80:81], off offset:1024
	ds_read_b128 v[228:231], v245 offset:36864
	ds_read_b128 v[212:215], v244
	ds_read_b128 v[236:239], v245 offset:39168
	ds_read_b128 v[240:243], v245 offset:41472
	ds_read_b128 v[252:255], v245 offset:43776
	ds_read_b128 v[216:219], v244 offset:2304
	ds_read_b128 v[220:223], v244 offset:4608
	ds_read_b128 v[224:227], v244 offset:6912
	s_waitcnt lgkmcnt(6)
	v_mfma_f32_16x16x32_bf16 v[50:53], v[212:215], v[228:231], v[50:53]
	s_waitcnt lgkmcnt(5)
	v_mfma_f32_16x16x32_bf16 v[54:57], v[212:215], v[236:239], v[54:57]
	s_waitcnt lgkmcnt(4)
	v_mfma_f32_16x16x32_bf16 v[34:37], v[212:215], v[240:243], v[34:37]
	s_waitcnt lgkmcnt(3)
	v_mfma_f32_16x16x32_bf16 v[38:41], v[212:215], v[252:255], v[38:41]
	ds_read_b128 v[212:215], v244 offset:64
	s_waitcnt lgkmcnt(3)
	v_mfma_f32_16x16x32_bf16 v[58:61], v[216:219], v[228:231], v[58:61]
	v_mfma_f32_16x16x32_bf16 v[62:65], v[216:219], v[236:239], v[62:65]
	v_mfma_f32_16x16x32_bf16 v[42:45], v[216:219], v[240:243], v[42:45]
	v_mfma_f32_16x16x32_bf16 v[46:49], v[216:219], v[252:255], v[46:49]
	ds_read_b128 v[216:219], v244 offset:2368
	s_setprio 1
	s_waitcnt vmcnt(15)
	ds_write_b128 v165, v[122:125] offset:18432
	s_waitcnt vmcnt(14)
	ds_write_b128 v165, v[126:129] offset:23040
	s_waitcnt lgkmcnt(5)
	v_mfma_f32_16x16x32_bf16 v[18:21], v[220:223], v[228:231], v[18:21]
	v_mfma_f32_16x16x32_bf16 v[22:25], v[220:223], v[236:239], v[22:25]
	v_mfma_f32_16x16x32_bf16 v[2:5], v[220:223], v[240:243], v[2:5]
	v_mfma_f32_16x16x32_bf16 v[6:9], v[220:223], v[252:255], v[6:9]
	ds_read_b128 v[220:223], v244 offset:4672
	s_waitcnt vmcnt(13)
	ds_write_b128 v165, v[136:139] offset:27648
	s_waitcnt vmcnt(12)
	ds_write_b128 v165, v[140:143] offset:32256
	s_waitcnt lgkmcnt(7)
	v_mfma_f32_16x16x32_bf16 v[26:29], v[224:227], v[228:231], v[26:29]
	ds_read_b128 v[228:231], v245 offset:36928
	v_mfma_f32_16x16x32_bf16 v[30:33], v[224:227], v[236:239], v[30:33]
	ds_read_b128 v[236:239], v245 offset:39232
	v_mfma_f32_16x16x32_bf16 v[10:13], v[224:227], v[240:243], v[10:13]
	ds_read_b128 v[240:243], v245 offset:41536
	v_mfma_f32_16x16x32_bf16 v[14:17], v[224:227], v[252:255], v[14:17]
	ds_read_b128 v[252:255], v245 offset:43840
	ds_read_b128 v[224:227], v244 offset:6976
	s_waitcnt lgkmcnt(4)
	v_mfma_f32_16x16x32_bf16 v[50:53], v[212:215], v[228:231], v[50:53]
	s_waitcnt lgkmcnt(3)
	v_mfma_f32_16x16x32_bf16 v[54:57], v[212:215], v[236:239], v[54:57]
	s_waitcnt lgkmcnt(2)
	v_mfma_f32_16x16x32_bf16 v[34:37], v[212:215], v[240:243], v[34:37]
	s_waitcnt lgkmcnt(1)
	v_mfma_f32_16x16x32_bf16 v[38:41], v[212:215], v[252:255], v[38:41]
	s_waitcnt vmcnt(11)
	ds_write_b128 v165, v[144:147] offset:55296
	s_waitcnt vmcnt(10)
	ds_write_b128 v165, v[148:151] offset:59904
	v_mfma_f32_16x16x32_bf16 v[58:61], v[216:219], v[228:231], v[58:61]
	v_mfma_f32_16x16x32_bf16 v[62:65], v[216:219], v[236:239], v[62:65]
	v_mfma_f32_16x16x32_bf16 v[42:45], v[216:219], v[240:243], v[42:45]
	v_mfma_f32_16x16x32_bf16 v[46:49], v[216:219], v[252:255], v[46:49]
	s_waitcnt vmcnt(9)
	ds_write_b128 v165, v[172:175] offset:64512
	s_waitcnt vmcnt(8)
	ds_write_b128 v166, v[176:179] offset:32256
	v_mfma_f32_16x16x32_bf16 v[18:21], v[220:223], v[228:231], v[18:21]
	v_mfma_f32_16x16x32_bf16 v[22:25], v[220:223], v[236:239], v[22:25]
	v_mfma_f32_16x16x32_bf16 v[2:5], v[220:223], v[240:243], v[2:5]
	v_mfma_f32_16x16x32_bf16 v[6:9], v[220:223], v[252:255], v[6:9]
	s_waitcnt lgkmcnt(4)
	v_mfma_f32_16x16x32_bf16 v[26:29], v[224:227], v[228:231], v[26:29]
	v_mfma_f32_16x16x32_bf16 v[30:33], v[224:227], v[236:239], v[30:33]
	v_mfma_f32_16x16x32_bf16 v[10:13], v[224:227], v[240:243], v[10:13]
	v_mfma_f32_16x16x32_bf16 v[14:17], v[224:227], v[252:255], v[14:17]
	s_waitcnt lgkmcnt(0)
	s_barrier
	s_setprio 0
	global_load_dwordx4 v[122:125], v[72:73], off offset:1152
	global_load_dwordx4 v[126:129], v[74:75], off offset:1152
	global_load_dwordx4 v[136:139], v[76:77], off offset:1152
	global_load_dwordx4 v[140:143], v[78:79], off offset:1152
	global_load_dwordx4 v[144:147], v[70:71], off offset:1152
	global_load_dwordx4 v[148:151], v[68:69], off offset:1152
	global_load_dwordx4 v[172:175], v[66:67], off offset:1152
	global_load_dwordx4 v[176:179], v[80:81], off offset:1152
	ds_read_b128 v[228:231], v245 offset:55296
	ds_read_b128 v[212:215], v244 offset:18432
	ds_read_b128 v[236:239], v245 offset:57600
	ds_read_b128 v[240:243], v245 offset:59904
	ds_read_b128 v[252:255], v245 offset:62208
	ds_read_b128 v[216:219], v244 offset:20736
	ds_read_b128 v[220:223], v244 offset:23040
	ds_read_b128 v[224:227], v244 offset:25344
	s_waitcnt lgkmcnt(6)
	v_mfma_f32_16x16x32_bf16 v[50:53], v[212:215], v[228:231], v[50:53]
	s_waitcnt lgkmcnt(5)
	v_mfma_f32_16x16x32_bf16 v[54:57], v[212:215], v[236:239], v[54:57]
	s_waitcnt lgkmcnt(4)
	v_mfma_f32_16x16x32_bf16 v[34:37], v[212:215], v[240:243], v[34:37]
	s_waitcnt lgkmcnt(3)
	v_mfma_f32_16x16x32_bf16 v[38:41], v[212:215], v[252:255], v[38:41]
	ds_read_b128 v[212:215], v244 offset:18496
	s_waitcnt lgkmcnt(3)
	v_mfma_f32_16x16x32_bf16 v[58:61], v[216:219], v[228:231], v[58:61]
	v_mfma_f32_16x16x32_bf16 v[62:65], v[216:219], v[236:239], v[62:65]
	v_mfma_f32_16x16x32_bf16 v[42:45], v[216:219], v[240:243], v[42:45]
	v_mfma_f32_16x16x32_bf16 v[46:49], v[216:219], v[252:255], v[46:49]
	ds_read_b128 v[216:219], v244 offset:20800
	s_setprio 1
	s_waitcnt vmcnt(15)
	ds_write_b128 v165, v[180:183]
	s_waitcnt vmcnt(14)
	ds_write_b128 v165, v[184:187] offset:4608
	s_waitcnt lgkmcnt(5)
	v_mfma_f32_16x16x32_bf16 v[18:21], v[220:223], v[228:231], v[18:21]
	v_mfma_f32_16x16x32_bf16 v[22:25], v[220:223], v[236:239], v[22:25]
	v_mfma_f32_16x16x32_bf16 v[2:5], v[220:223], v[240:243], v[2:5]
	v_mfma_f32_16x16x32_bf16 v[6:9], v[220:223], v[252:255], v[6:9]
	ds_read_b128 v[220:223], v244 offset:23104
	s_waitcnt vmcnt(13)
	ds_write_b128 v165, v[188:191] offset:9216
	s_waitcnt vmcnt(12)
	ds_write_b128 v165, v[192:195] offset:13824
	s_waitcnt lgkmcnt(7)
	v_mfma_f32_16x16x32_bf16 v[26:29], v[224:227], v[228:231], v[26:29]
	ds_read_b128 v[228:231], v245 offset:55360
	v_mfma_f32_16x16x32_bf16 v[30:33], v[224:227], v[236:239], v[30:33]
	ds_read_b128 v[236:239], v245 offset:57664
	v_mfma_f32_16x16x32_bf16 v[10:13], v[224:227], v[240:243], v[10:13]
	ds_read_b128 v[240:243], v245 offset:59968
	v_mfma_f32_16x16x32_bf16 v[14:17], v[224:227], v[252:255], v[14:17]
	ds_read_b128 v[252:255], v245 offset:62272
	ds_read_b128 v[224:227], v244 offset:25408
	s_waitcnt lgkmcnt(4)
	v_mfma_f32_16x16x32_bf16 v[50:53], v[212:215], v[228:231], v[50:53]
	s_waitcnt lgkmcnt(3)
	v_mfma_f32_16x16x32_bf16 v[54:57], v[212:215], v[236:239], v[54:57]
	s_waitcnt lgkmcnt(2)
	v_mfma_f32_16x16x32_bf16 v[34:37], v[212:215], v[240:243], v[34:37]
	s_waitcnt lgkmcnt(1)
	v_mfma_f32_16x16x32_bf16 v[38:41], v[212:215], v[252:255], v[38:41]
	s_waitcnt vmcnt(11)
	ds_write_b128 v165, v[196:199] offset:36864
	s_waitcnt vmcnt(10)
	ds_write_b128 v165, v[200:203] offset:41472
	v_mfma_f32_16x16x32_bf16 v[58:61], v[216:219], v[228:231], v[58:61]
	v_mfma_f32_16x16x32_bf16 v[62:65], v[216:219], v[236:239], v[62:65]
	v_mfma_f32_16x16x32_bf16 v[42:45], v[216:219], v[240:243], v[42:45]
	v_mfma_f32_16x16x32_bf16 v[46:49], v[216:219], v[252:255], v[46:49]
	s_waitcnt vmcnt(9)
	ds_write_b128 v165, v[204:207] offset:46080
	s_waitcnt vmcnt(8)
	ds_write_b128 v165, v[208:211] offset:50688
	v_mfma_f32_16x16x32_bf16 v[18:21], v[220:223], v[228:231], v[18:21]
	v_mfma_f32_16x16x32_bf16 v[22:25], v[220:223], v[236:239], v[22:25]
	v_mfma_f32_16x16x32_bf16 v[2:5], v[220:223], v[240:243], v[2:5]
	v_mfma_f32_16x16x32_bf16 v[6:9], v[220:223], v[252:255], v[6:9]
	s_waitcnt lgkmcnt(4)
	v_mfma_f32_16x16x32_bf16 v[26:29], v[224:227], v[228:231], v[26:29]
	v_mfma_f32_16x16x32_bf16 v[30:33], v[224:227], v[236:239], v[30:33]
	v_mfma_f32_16x16x32_bf16 v[10:13], v[224:227], v[240:243], v[10:13]
	v_mfma_f32_16x16x32_bf16 v[14:17], v[224:227], v[252:255], v[14:17]
	s_waitcnt lgkmcnt(0)
	s_barrier
	s_setprio 0
	global_load_dwordx4 v[180:183], v[72:73], off offset:1280
	global_load_dwordx4 v[184:187], v[74:75], off offset:1280
	global_load_dwordx4 v[188:191], v[76:77], off offset:1280
	global_load_dwordx4 v[192:195], v[78:79], off offset:1280
	global_load_dwordx4 v[196:199], v[70:71], off offset:1280
	global_load_dwordx4 v[200:203], v[68:69], off offset:1280
	global_load_dwordx4 v[204:207], v[66:67], off offset:1280
	global_load_dwordx4 v[208:211], v[80:81], off offset:1280
	ds_read_b128 v[228:231], v245 offset:36864
	ds_read_b128 v[212:215], v244
	ds_read_b128 v[236:239], v245 offset:39168
	ds_read_b128 v[240:243], v245 offset:41472
	ds_read_b128 v[252:255], v245 offset:43776
	ds_read_b128 v[216:219], v244 offset:2304
	ds_read_b128 v[220:223], v244 offset:4608
	ds_read_b128 v[224:227], v244 offset:6912
	s_waitcnt lgkmcnt(6)
	v_mfma_f32_16x16x32_bf16 v[50:53], v[212:215], v[228:231], v[50:53]
	s_waitcnt lgkmcnt(5)
	v_mfma_f32_16x16x32_bf16 v[54:57], v[212:215], v[236:239], v[54:57]
	s_waitcnt lgkmcnt(4)
	v_mfma_f32_16x16x32_bf16 v[34:37], v[212:215], v[240:243], v[34:37]
	s_waitcnt lgkmcnt(3)
	v_mfma_f32_16x16x32_bf16 v[38:41], v[212:215], v[252:255], v[38:41]
	ds_read_b128 v[212:215], v244 offset:64
	s_waitcnt lgkmcnt(3)
	v_mfma_f32_16x16x32_bf16 v[58:61], v[216:219], v[228:231], v[58:61]
	v_mfma_f32_16x16x32_bf16 v[62:65], v[216:219], v[236:239], v[62:65]
	v_mfma_f32_16x16x32_bf16 v[42:45], v[216:219], v[240:243], v[42:45]
	v_mfma_f32_16x16x32_bf16 v[46:49], v[216:219], v[252:255], v[46:49]
	ds_read_b128 v[216:219], v244 offset:2368
	s_setprio 1
	s_waitcnt vmcnt(15)
	ds_write_b128 v165, v[122:125] offset:18432
	s_waitcnt vmcnt(14)
	ds_write_b128 v165, v[126:129] offset:23040
	s_waitcnt lgkmcnt(5)
	v_mfma_f32_16x16x32_bf16 v[18:21], v[220:223], v[228:231], v[18:21]
	v_mfma_f32_16x16x32_bf16 v[22:25], v[220:223], v[236:239], v[22:25]
	v_mfma_f32_16x16x32_bf16 v[2:5], v[220:223], v[240:243], v[2:5]
	v_mfma_f32_16x16x32_bf16 v[6:9], v[220:223], v[252:255], v[6:9]
	ds_read_b128 v[220:223], v244 offset:4672
	s_waitcnt vmcnt(13)
	ds_write_b128 v165, v[136:139] offset:27648
	s_waitcnt vmcnt(12)
	ds_write_b128 v165, v[140:143] offset:32256
	s_waitcnt lgkmcnt(7)
	v_mfma_f32_16x16x32_bf16 v[26:29], v[224:227], v[228:231], v[26:29]
	ds_read_b128 v[228:231], v245 offset:36928
	v_mfma_f32_16x16x32_bf16 v[30:33], v[224:227], v[236:239], v[30:33]
	ds_read_b128 v[236:239], v245 offset:39232
	v_mfma_f32_16x16x32_bf16 v[10:13], v[224:227], v[240:243], v[10:13]
	ds_read_b128 v[240:243], v245 offset:41536
	v_mfma_f32_16x16x32_bf16 v[14:17], v[224:227], v[252:255], v[14:17]
	ds_read_b128 v[252:255], v245 offset:43840
	ds_read_b128 v[224:227], v244 offset:6976
	s_waitcnt lgkmcnt(4)
	v_mfma_f32_16x16x32_bf16 v[50:53], v[212:215], v[228:231], v[50:53]
	s_waitcnt lgkmcnt(3)
	v_mfma_f32_16x16x32_bf16 v[54:57], v[212:215], v[236:239], v[54:57]
	s_waitcnt lgkmcnt(2)
	v_mfma_f32_16x16x32_bf16 v[34:37], v[212:215], v[240:243], v[34:37]
	s_waitcnt lgkmcnt(1)
	v_mfma_f32_16x16x32_bf16 v[38:41], v[212:215], v[252:255], v[38:41]
	s_waitcnt vmcnt(11)
	ds_write_b128 v165, v[144:147] offset:55296
	s_waitcnt vmcnt(10)
	ds_write_b128 v165, v[148:151] offset:59904
	v_mfma_f32_16x16x32_bf16 v[58:61], v[216:219], v[228:231], v[58:61]
	v_mfma_f32_16x16x32_bf16 v[62:65], v[216:219], v[236:239], v[62:65]
	v_mfma_f32_16x16x32_bf16 v[42:45], v[216:219], v[240:243], v[42:45]
	v_mfma_f32_16x16x32_bf16 v[46:49], v[216:219], v[252:255], v[46:49]
	s_waitcnt vmcnt(9)
	ds_write_b128 v165, v[172:175] offset:64512
	s_waitcnt vmcnt(8)
	ds_write_b128 v166, v[176:179] offset:32256
	v_mfma_f32_16x16x32_bf16 v[18:21], v[220:223], v[228:231], v[18:21]
	v_mfma_f32_16x16x32_bf16 v[22:25], v[220:223], v[236:239], v[22:25]
	v_mfma_f32_16x16x32_bf16 v[2:5], v[220:223], v[240:243], v[2:5]
	v_mfma_f32_16x16x32_bf16 v[6:9], v[220:223], v[252:255], v[6:9]
	s_waitcnt lgkmcnt(4)
	v_mfma_f32_16x16x32_bf16 v[26:29], v[224:227], v[228:231], v[26:29]
	v_mfma_f32_16x16x32_bf16 v[30:33], v[224:227], v[236:239], v[30:33]
	v_mfma_f32_16x16x32_bf16 v[10:13], v[224:227], v[240:243], v[10:13]
	v_mfma_f32_16x16x32_bf16 v[14:17], v[224:227], v[252:255], v[14:17]
	s_waitcnt lgkmcnt(0)
	s_barrier
	s_setprio 0
	global_load_dwordx4 v[122:125], v[72:73], off offset:1408
	global_load_dwordx4 v[126:129], v[74:75], off offset:1408
	global_load_dwordx4 v[136:139], v[76:77], off offset:1408
	global_load_dwordx4 v[140:143], v[78:79], off offset:1408
	global_load_dwordx4 v[144:147], v[70:71], off offset:1408
	global_load_dwordx4 v[148:151], v[68:69], off offset:1408
	global_load_dwordx4 v[172:175], v[66:67], off offset:1408
	global_load_dwordx4 v[176:179], v[80:81], off offset:1408
	ds_read_b128 v[228:231], v245 offset:55296
	ds_read_b128 v[212:215], v244 offset:18432
	ds_read_b128 v[236:239], v245 offset:57600
	ds_read_b128 v[240:243], v245 offset:59904
	ds_read_b128 v[252:255], v245 offset:62208
	ds_read_b128 v[216:219], v244 offset:20736
	ds_read_b128 v[220:223], v244 offset:23040
	ds_read_b128 v[224:227], v244 offset:25344
	s_waitcnt lgkmcnt(6)
	v_mfma_f32_16x16x32_bf16 v[50:53], v[212:215], v[228:231], v[50:53]
	s_waitcnt lgkmcnt(5)
	v_mfma_f32_16x16x32_bf16 v[54:57], v[212:215], v[236:239], v[54:57]
	s_waitcnt lgkmcnt(4)
	v_mfma_f32_16x16x32_bf16 v[34:37], v[212:215], v[240:243], v[34:37]
	s_waitcnt lgkmcnt(3)
	v_mfma_f32_16x16x32_bf16 v[38:41], v[212:215], v[252:255], v[38:41]
	ds_read_b128 v[212:215], v244 offset:18496
	s_waitcnt lgkmcnt(3)
	v_mfma_f32_16x16x32_bf16 v[58:61], v[216:219], v[228:231], v[58:61]
	v_mfma_f32_16x16x32_bf16 v[62:65], v[216:219], v[236:239], v[62:65]
	v_mfma_f32_16x16x32_bf16 v[42:45], v[216:219], v[240:243], v[42:45]
	v_mfma_f32_16x16x32_bf16 v[46:49], v[216:219], v[252:255], v[46:49]
	ds_read_b128 v[216:219], v244 offset:20800
	s_setprio 1
	s_waitcnt vmcnt(15)
	ds_write_b128 v165, v[180:183]
	s_waitcnt vmcnt(14)
	ds_write_b128 v165, v[184:187] offset:4608
	s_waitcnt lgkmcnt(5)
	v_mfma_f32_16x16x32_bf16 v[18:21], v[220:223], v[228:231], v[18:21]
	v_mfma_f32_16x16x32_bf16 v[22:25], v[220:223], v[236:239], v[22:25]
	v_mfma_f32_16x16x32_bf16 v[2:5], v[220:223], v[240:243], v[2:5]
	v_mfma_f32_16x16x32_bf16 v[6:9], v[220:223], v[252:255], v[6:9]
	ds_read_b128 v[220:223], v244 offset:23104
	s_waitcnt vmcnt(13)
	ds_write_b128 v165, v[188:191] offset:9216
	s_waitcnt vmcnt(12)
	ds_write_b128 v165, v[192:195] offset:13824
	s_waitcnt lgkmcnt(7)
	v_mfma_f32_16x16x32_bf16 v[26:29], v[224:227], v[228:231], v[26:29]
	ds_read_b128 v[228:231], v245 offset:55360
	v_mfma_f32_16x16x32_bf16 v[30:33], v[224:227], v[236:239], v[30:33]
	ds_read_b128 v[236:239], v245 offset:57664
	v_mfma_f32_16x16x32_bf16 v[10:13], v[224:227], v[240:243], v[10:13]
	ds_read_b128 v[240:243], v245 offset:59968
	v_mfma_f32_16x16x32_bf16 v[14:17], v[224:227], v[252:255], v[14:17]
	ds_read_b128 v[252:255], v245 offset:62272
	ds_read_b128 v[224:227], v244 offset:25408
	s_waitcnt lgkmcnt(4)
	v_mfma_f32_16x16x32_bf16 v[50:53], v[212:215], v[228:231], v[50:53]
	s_waitcnt lgkmcnt(3)
	v_mfma_f32_16x16x32_bf16 v[54:57], v[212:215], v[236:239], v[54:57]
	s_waitcnt lgkmcnt(2)
	v_mfma_f32_16x16x32_bf16 v[34:37], v[212:215], v[240:243], v[34:37]
	s_waitcnt lgkmcnt(1)
	v_mfma_f32_16x16x32_bf16 v[38:41], v[212:215], v[252:255], v[38:41]
	s_waitcnt vmcnt(11)
	ds_write_b128 v165, v[196:199] offset:36864
	s_waitcnt vmcnt(10)
	ds_write_b128 v165, v[200:203] offset:41472
	v_mfma_f32_16x16x32_bf16 v[58:61], v[216:219], v[228:231], v[58:61]
	v_mfma_f32_16x16x32_bf16 v[62:65], v[216:219], v[236:239], v[62:65]
	v_mfma_f32_16x16x32_bf16 v[42:45], v[216:219], v[240:243], v[42:45]
	v_mfma_f32_16x16x32_bf16 v[46:49], v[216:219], v[252:255], v[46:49]
	s_waitcnt vmcnt(9)
	ds_write_b128 v165, v[204:207] offset:46080
	s_waitcnt vmcnt(8)
	ds_write_b128 v165, v[208:211] offset:50688
	v_mfma_f32_16x16x32_bf16 v[18:21], v[220:223], v[228:231], v[18:21]
	v_mfma_f32_16x16x32_bf16 v[22:25], v[220:223], v[236:239], v[22:25]
	v_mfma_f32_16x16x32_bf16 v[2:5], v[220:223], v[240:243], v[2:5]
	v_mfma_f32_16x16x32_bf16 v[6:9], v[220:223], v[252:255], v[6:9]
	s_waitcnt lgkmcnt(4)
	v_mfma_f32_16x16x32_bf16 v[26:29], v[224:227], v[228:231], v[26:29]
	v_mfma_f32_16x16x32_bf16 v[30:33], v[224:227], v[236:239], v[30:33]
	v_mfma_f32_16x16x32_bf16 v[10:13], v[224:227], v[240:243], v[10:13]
	v_mfma_f32_16x16x32_bf16 v[14:17], v[224:227], v[252:255], v[14:17]
	s_waitcnt lgkmcnt(0)
	s_barrier
	s_setprio 0
	global_load_dwordx4 v[180:183], v[72:73], off offset:1536
	global_load_dwordx4 v[184:187], v[74:75], off offset:1536
	global_load_dwordx4 v[188:191], v[76:77], off offset:1536
	global_load_dwordx4 v[192:195], v[78:79], off offset:1536
	global_load_dwordx4 v[196:199], v[70:71], off offset:1536
	global_load_dwordx4 v[200:203], v[68:69], off offset:1536
	global_load_dwordx4 v[204:207], v[66:67], off offset:1536
	global_load_dwordx4 v[208:211], v[80:81], off offset:1536
	ds_read_b128 v[228:231], v245 offset:36864
	ds_read_b128 v[212:215], v244
	ds_read_b128 v[236:239], v245 offset:39168
	ds_read_b128 v[240:243], v245 offset:41472
	ds_read_b128 v[252:255], v245 offset:43776
	ds_read_b128 v[216:219], v244 offset:2304
	ds_read_b128 v[220:223], v244 offset:4608
	ds_read_b128 v[224:227], v244 offset:6912
	s_waitcnt lgkmcnt(6)
	v_mfma_f32_16x16x32_bf16 v[50:53], v[212:215], v[228:231], v[50:53]
	s_waitcnt lgkmcnt(5)
	v_mfma_f32_16x16x32_bf16 v[54:57], v[212:215], v[236:239], v[54:57]
	s_waitcnt lgkmcnt(4)
	v_mfma_f32_16x16x32_bf16 v[34:37], v[212:215], v[240:243], v[34:37]
	s_waitcnt lgkmcnt(3)
	v_mfma_f32_16x16x32_bf16 v[38:41], v[212:215], v[252:255], v[38:41]
	ds_read_b128 v[212:215], v244 offset:64
	s_waitcnt lgkmcnt(3)
	v_mfma_f32_16x16x32_bf16 v[58:61], v[216:219], v[228:231], v[58:61]
	v_mfma_f32_16x16x32_bf16 v[62:65], v[216:219], v[236:239], v[62:65]
	v_mfma_f32_16x16x32_bf16 v[42:45], v[216:219], v[240:243], v[42:45]
	v_mfma_f32_16x16x32_bf16 v[46:49], v[216:219], v[252:255], v[46:49]
	ds_read_b128 v[216:219], v244 offset:2368
	s_setprio 1
	s_waitcnt vmcnt(15)
	ds_write_b128 v165, v[122:125] offset:18432
	s_waitcnt vmcnt(14)
	ds_write_b128 v165, v[126:129] offset:23040
	s_waitcnt lgkmcnt(5)
	v_mfma_f32_16x16x32_bf16 v[18:21], v[220:223], v[228:231], v[18:21]
	v_mfma_f32_16x16x32_bf16 v[22:25], v[220:223], v[236:239], v[22:25]
	v_mfma_f32_16x16x32_bf16 v[2:5], v[220:223], v[240:243], v[2:5]
	v_mfma_f32_16x16x32_bf16 v[6:9], v[220:223], v[252:255], v[6:9]
	ds_read_b128 v[220:223], v244 offset:4672
	s_waitcnt vmcnt(13)
	ds_write_b128 v165, v[136:139] offset:27648
	s_waitcnt vmcnt(12)
	ds_write_b128 v165, v[140:143] offset:32256
	s_waitcnt lgkmcnt(7)
	v_mfma_f32_16x16x32_bf16 v[26:29], v[224:227], v[228:231], v[26:29]
	ds_read_b128 v[228:231], v245 offset:36928
	v_mfma_f32_16x16x32_bf16 v[30:33], v[224:227], v[236:239], v[30:33]
	ds_read_b128 v[236:239], v245 offset:39232
	v_mfma_f32_16x16x32_bf16 v[10:13], v[224:227], v[240:243], v[10:13]
	ds_read_b128 v[240:243], v245 offset:41536
	v_mfma_f32_16x16x32_bf16 v[14:17], v[224:227], v[252:255], v[14:17]
	ds_read_b128 v[252:255], v245 offset:43840
	ds_read_b128 v[224:227], v244 offset:6976
	s_waitcnt lgkmcnt(4)
	v_mfma_f32_16x16x32_bf16 v[50:53], v[212:215], v[228:231], v[50:53]
	s_waitcnt lgkmcnt(3)
	v_mfma_f32_16x16x32_bf16 v[54:57], v[212:215], v[236:239], v[54:57]
	s_waitcnt lgkmcnt(2)
	v_mfma_f32_16x16x32_bf16 v[34:37], v[212:215], v[240:243], v[34:37]
	s_waitcnt lgkmcnt(1)
	v_mfma_f32_16x16x32_bf16 v[38:41], v[212:215], v[252:255], v[38:41]
	s_waitcnt vmcnt(11)
	ds_write_b128 v165, v[144:147] offset:55296
	s_waitcnt vmcnt(10)
	ds_write_b128 v165, v[148:151] offset:59904
	v_mfma_f32_16x16x32_bf16 v[58:61], v[216:219], v[228:231], v[58:61]
	v_mfma_f32_16x16x32_bf16 v[62:65], v[216:219], v[236:239], v[62:65]
	v_mfma_f32_16x16x32_bf16 v[42:45], v[216:219], v[240:243], v[42:45]
	v_mfma_f32_16x16x32_bf16 v[46:49], v[216:219], v[252:255], v[46:49]
	s_waitcnt vmcnt(9)
	ds_write_b128 v165, v[172:175] offset:64512
	s_waitcnt vmcnt(8)
	ds_write_b128 v166, v[176:179] offset:32256
	v_mfma_f32_16x16x32_bf16 v[18:21], v[220:223], v[228:231], v[18:21]
	v_mfma_f32_16x16x32_bf16 v[22:25], v[220:223], v[236:239], v[22:25]
	v_mfma_f32_16x16x32_bf16 v[2:5], v[220:223], v[240:243], v[2:5]
	v_mfma_f32_16x16x32_bf16 v[6:9], v[220:223], v[252:255], v[6:9]
	s_waitcnt lgkmcnt(4)
	v_mfma_f32_16x16x32_bf16 v[26:29], v[224:227], v[228:231], v[26:29]
	v_mfma_f32_16x16x32_bf16 v[30:33], v[224:227], v[236:239], v[30:33]
	v_mfma_f32_16x16x32_bf16 v[10:13], v[224:227], v[240:243], v[10:13]
	v_mfma_f32_16x16x32_bf16 v[14:17], v[224:227], v[252:255], v[14:17]
	s_waitcnt lgkmcnt(0)
	s_barrier
	s_setprio 0
	global_load_dwordx4 v[122:125], v[72:73], off offset:1664
	global_load_dwordx4 v[126:129], v[74:75], off offset:1664
	global_load_dwordx4 v[136:139], v[76:77], off offset:1664
	global_load_dwordx4 v[140:143], v[78:79], off offset:1664
	global_load_dwordx4 v[144:147], v[70:71], off offset:1664
	global_load_dwordx4 v[148:151], v[68:69], off offset:1664
	global_load_dwordx4 v[172:175], v[66:67], off offset:1664
	global_load_dwordx4 v[176:179], v[80:81], off offset:1664
	ds_read_b128 v[228:231], v245 offset:55296
	ds_read_b128 v[212:215], v244 offset:18432
	ds_read_b128 v[236:239], v245 offset:57600
	ds_read_b128 v[240:243], v245 offset:59904
	ds_read_b128 v[252:255], v245 offset:62208
	ds_read_b128 v[216:219], v244 offset:20736
	ds_read_b128 v[220:223], v244 offset:23040
	ds_read_b128 v[224:227], v244 offset:25344
	s_waitcnt lgkmcnt(6)
	v_mfma_f32_16x16x32_bf16 v[50:53], v[212:215], v[228:231], v[50:53]
	s_waitcnt lgkmcnt(5)
	v_mfma_f32_16x16x32_bf16 v[54:57], v[212:215], v[236:239], v[54:57]
	s_waitcnt lgkmcnt(4)
	v_mfma_f32_16x16x32_bf16 v[34:37], v[212:215], v[240:243], v[34:37]
	s_waitcnt lgkmcnt(3)
	v_mfma_f32_16x16x32_bf16 v[38:41], v[212:215], v[252:255], v[38:41]
	ds_read_b128 v[212:215], v244 offset:18496
	s_waitcnt lgkmcnt(3)
	v_mfma_f32_16x16x32_bf16 v[58:61], v[216:219], v[228:231], v[58:61]
	v_mfma_f32_16x16x32_bf16 v[62:65], v[216:219], v[236:239], v[62:65]
	v_mfma_f32_16x16x32_bf16 v[42:45], v[216:219], v[240:243], v[42:45]
	v_mfma_f32_16x16x32_bf16 v[46:49], v[216:219], v[252:255], v[46:49]
	ds_read_b128 v[216:219], v244 offset:20800
	s_setprio 1
	s_waitcnt vmcnt(15)
	ds_write_b128 v165, v[180:183]
	s_waitcnt vmcnt(14)
	ds_write_b128 v165, v[184:187] offset:4608
	s_waitcnt lgkmcnt(5)
	v_mfma_f32_16x16x32_bf16 v[18:21], v[220:223], v[228:231], v[18:21]
	v_mfma_f32_16x16x32_bf16 v[22:25], v[220:223], v[236:239], v[22:25]
	v_mfma_f32_16x16x32_bf16 v[2:5], v[220:223], v[240:243], v[2:5]
	v_mfma_f32_16x16x32_bf16 v[6:9], v[220:223], v[252:255], v[6:9]
	ds_read_b128 v[220:223], v244 offset:23104
	s_waitcnt vmcnt(13)
	ds_write_b128 v165, v[188:191] offset:9216
	s_waitcnt vmcnt(12)
	ds_write_b128 v165, v[192:195] offset:13824
	s_waitcnt lgkmcnt(7)
	v_mfma_f32_16x16x32_bf16 v[26:29], v[224:227], v[228:231], v[26:29]
	ds_read_b128 v[228:231], v245 offset:55360
	v_mfma_f32_16x16x32_bf16 v[30:33], v[224:227], v[236:239], v[30:33]
	ds_read_b128 v[236:239], v245 offset:57664
	v_mfma_f32_16x16x32_bf16 v[10:13], v[224:227], v[240:243], v[10:13]
	ds_read_b128 v[240:243], v245 offset:59968
	v_mfma_f32_16x16x32_bf16 v[14:17], v[224:227], v[252:255], v[14:17]
	ds_read_b128 v[252:255], v245 offset:62272
	ds_read_b128 v[224:227], v244 offset:25408
	s_waitcnt lgkmcnt(4)
	v_mfma_f32_16x16x32_bf16 v[50:53], v[212:215], v[228:231], v[50:53]
	s_waitcnt lgkmcnt(3)
	v_mfma_f32_16x16x32_bf16 v[54:57], v[212:215], v[236:239], v[54:57]
	s_waitcnt lgkmcnt(2)
	v_mfma_f32_16x16x32_bf16 v[34:37], v[212:215], v[240:243], v[34:37]
	s_waitcnt lgkmcnt(1)
	v_mfma_f32_16x16x32_bf16 v[38:41], v[212:215], v[252:255], v[38:41]
	s_waitcnt vmcnt(11)
	ds_write_b128 v165, v[196:199] offset:36864
	s_waitcnt vmcnt(10)
	ds_write_b128 v165, v[200:203] offset:41472
	v_mfma_f32_16x16x32_bf16 v[58:61], v[216:219], v[228:231], v[58:61]
	v_mfma_f32_16x16x32_bf16 v[62:65], v[216:219], v[236:239], v[62:65]
	v_mfma_f32_16x16x32_bf16 v[42:45], v[216:219], v[240:243], v[42:45]
	v_mfma_f32_16x16x32_bf16 v[46:49], v[216:219], v[252:255], v[46:49]
	s_waitcnt vmcnt(9)
	ds_write_b128 v165, v[204:207] offset:46080
	s_waitcnt vmcnt(8)
	ds_write_b128 v165, v[208:211] offset:50688
	v_mfma_f32_16x16x32_bf16 v[18:21], v[220:223], v[228:231], v[18:21]
	v_mfma_f32_16x16x32_bf16 v[22:25], v[220:223], v[236:239], v[22:25]
	v_mfma_f32_16x16x32_bf16 v[2:5], v[220:223], v[240:243], v[2:5]
	v_mfma_f32_16x16x32_bf16 v[6:9], v[220:223], v[252:255], v[6:9]
	s_waitcnt lgkmcnt(4)
	v_mfma_f32_16x16x32_bf16 v[26:29], v[224:227], v[228:231], v[26:29]
	v_mfma_f32_16x16x32_bf16 v[30:33], v[224:227], v[236:239], v[30:33]
	v_mfma_f32_16x16x32_bf16 v[10:13], v[224:227], v[240:243], v[10:13]
	v_mfma_f32_16x16x32_bf16 v[14:17], v[224:227], v[252:255], v[14:17]
	s_waitcnt lgkmcnt(0)
	s_barrier
	s_setprio 0
	global_load_dwordx4 v[180:183], v[72:73], off offset:1792
	global_load_dwordx4 v[184:187], v[74:75], off offset:1792
	global_load_dwordx4 v[188:191], v[76:77], off offset:1792
	global_load_dwordx4 v[192:195], v[78:79], off offset:1792
	global_load_dwordx4 v[196:199], v[70:71], off offset:1792
	global_load_dwordx4 v[200:203], v[68:69], off offset:1792
	global_load_dwordx4 v[204:207], v[66:67], off offset:1792
	global_load_dwordx4 v[208:211], v[80:81], off offset:1792
	ds_read_b128 v[228:231], v245 offset:36864
	ds_read_b128 v[212:215], v244
	ds_read_b128 v[236:239], v245 offset:39168
	ds_read_b128 v[240:243], v245 offset:41472
	ds_read_b128 v[252:255], v245 offset:43776
	ds_read_b128 v[216:219], v244 offset:2304
	ds_read_b128 v[220:223], v244 offset:4608
	ds_read_b128 v[224:227], v244 offset:6912
	s_waitcnt lgkmcnt(6)
	v_mfma_f32_16x16x32_bf16 v[50:53], v[212:215], v[228:231], v[50:53]
	s_waitcnt lgkmcnt(5)
	v_mfma_f32_16x16x32_bf16 v[54:57], v[212:215], v[236:239], v[54:57]
	s_waitcnt lgkmcnt(4)
	v_mfma_f32_16x16x32_bf16 v[34:37], v[212:215], v[240:243], v[34:37]
	s_waitcnt lgkmcnt(3)
	v_mfma_f32_16x16x32_bf16 v[38:41], v[212:215], v[252:255], v[38:41]
	ds_read_b128 v[212:215], v244 offset:64
	s_waitcnt lgkmcnt(3)
	v_mfma_f32_16x16x32_bf16 v[58:61], v[216:219], v[228:231], v[58:61]
	v_mfma_f32_16x16x32_bf16 v[62:65], v[216:219], v[236:239], v[62:65]
	v_mfma_f32_16x16x32_bf16 v[42:45], v[216:219], v[240:243], v[42:45]
	v_mfma_f32_16x16x32_bf16 v[46:49], v[216:219], v[252:255], v[46:49]
	ds_read_b128 v[216:219], v244 offset:2368
	s_setprio 1
	s_waitcnt vmcnt(15)
	ds_write_b128 v165, v[122:125] offset:18432
	s_waitcnt vmcnt(14)
	ds_write_b128 v165, v[126:129] offset:23040
	s_waitcnt lgkmcnt(5)
	v_mfma_f32_16x16x32_bf16 v[18:21], v[220:223], v[228:231], v[18:21]
	v_mfma_f32_16x16x32_bf16 v[22:25], v[220:223], v[236:239], v[22:25]
	v_mfma_f32_16x16x32_bf16 v[2:5], v[220:223], v[240:243], v[2:5]
	v_mfma_f32_16x16x32_bf16 v[6:9], v[220:223], v[252:255], v[6:9]
	ds_read_b128 v[220:223], v244 offset:4672
	s_waitcnt vmcnt(13)
	ds_write_b128 v165, v[136:139] offset:27648
	s_waitcnt vmcnt(12)
	ds_write_b128 v165, v[140:143] offset:32256
	s_waitcnt lgkmcnt(7)
	v_mfma_f32_16x16x32_bf16 v[26:29], v[224:227], v[228:231], v[26:29]
	ds_read_b128 v[228:231], v245 offset:36928
	v_mfma_f32_16x16x32_bf16 v[30:33], v[224:227], v[236:239], v[30:33]
	ds_read_b128 v[236:239], v245 offset:39232
	v_mfma_f32_16x16x32_bf16 v[10:13], v[224:227], v[240:243], v[10:13]
	ds_read_b128 v[240:243], v245 offset:41536
	v_mfma_f32_16x16x32_bf16 v[14:17], v[224:227], v[252:255], v[14:17]
	ds_read_b128 v[252:255], v245 offset:43840
	ds_read_b128 v[224:227], v244 offset:6976
	s_waitcnt lgkmcnt(4)
	v_mfma_f32_16x16x32_bf16 v[50:53], v[212:215], v[228:231], v[50:53]
	s_waitcnt lgkmcnt(3)
	v_mfma_f32_16x16x32_bf16 v[54:57], v[212:215], v[236:239], v[54:57]
	s_waitcnt lgkmcnt(2)
	v_mfma_f32_16x16x32_bf16 v[34:37], v[212:215], v[240:243], v[34:37]
	s_waitcnt lgkmcnt(1)
	v_mfma_f32_16x16x32_bf16 v[38:41], v[212:215], v[252:255], v[38:41]
	s_waitcnt vmcnt(11)
	ds_write_b128 v165, v[144:147] offset:55296
	s_waitcnt vmcnt(10)
	ds_write_b128 v165, v[148:151] offset:59904
	v_mfma_f32_16x16x32_bf16 v[58:61], v[216:219], v[228:231], v[58:61]
	v_mfma_f32_16x16x32_bf16 v[62:65], v[216:219], v[236:239], v[62:65]
	v_mfma_f32_16x16x32_bf16 v[42:45], v[216:219], v[240:243], v[42:45]
	v_mfma_f32_16x16x32_bf16 v[46:49], v[216:219], v[252:255], v[46:49]
	s_waitcnt vmcnt(9)
	ds_write_b128 v165, v[172:175] offset:64512
	s_waitcnt vmcnt(8)
	ds_write_b128 v166, v[176:179] offset:32256
	v_mfma_f32_16x16x32_bf16 v[18:21], v[220:223], v[228:231], v[18:21]
	v_mfma_f32_16x16x32_bf16 v[22:25], v[220:223], v[236:239], v[22:25]
	v_mfma_f32_16x16x32_bf16 v[2:5], v[220:223], v[240:243], v[2:5]
	v_mfma_f32_16x16x32_bf16 v[6:9], v[220:223], v[252:255], v[6:9]
	s_waitcnt lgkmcnt(4)
	v_mfma_f32_16x16x32_bf16 v[26:29], v[224:227], v[228:231], v[26:29]
	v_mfma_f32_16x16x32_bf16 v[30:33], v[224:227], v[236:239], v[30:33]
	v_mfma_f32_16x16x32_bf16 v[10:13], v[224:227], v[240:243], v[10:13]
	v_mfma_f32_16x16x32_bf16 v[14:17], v[224:227], v[252:255], v[14:17]
	s_waitcnt lgkmcnt(0)
	s_barrier
	s_setprio 0
	global_load_dwordx4 v[122:125], v[72:73], off offset:1920
	s_nop 0
	global_load_dwordx4 v[72:75], v[74:75], off offset:1920
	s_nop 0
	global_load_dwordx4 v[126:129], v[76:77], off offset:1920
	s_nop 0
	global_load_dwordx4 v[76:79], v[78:79], off offset:1920
	s_nop 0
	global_load_dwordx4 v[136:139], v[70:71], off offset:1920
	s_nop 0
	global_load_dwordx4 v[68:71], v[68:69], off offset:1920
	s_nop 0
	global_load_dwordx4 v[140:143], v[66:67], off offset:1920
	global_load_dwordx4 v[144:147], v[80:81], off offset:1920
	ds_read_b128 v[228:231], v245 offset:55296
	ds_read_b128 v[212:215], v244 offset:18432
	ds_read_b128 v[236:239], v245 offset:57600
	ds_read_b128 v[240:243], v245 offset:59904
	ds_read_b128 v[252:255], v245 offset:62208
	ds_read_b128 v[216:219], v244 offset:20736
	ds_read_b128 v[220:223], v244 offset:23040
	ds_read_b128 v[224:227], v244 offset:25344
	s_waitcnt lgkmcnt(6)
	v_mfma_f32_16x16x32_bf16 v[50:53], v[212:215], v[228:231], v[50:53]
	s_waitcnt lgkmcnt(5)
	v_mfma_f32_16x16x32_bf16 v[54:57], v[212:215], v[236:239], v[54:57]
	s_waitcnt lgkmcnt(4)
	v_mfma_f32_16x16x32_bf16 v[34:37], v[212:215], v[240:243], v[34:37]
	s_waitcnt lgkmcnt(3)
	v_mfma_f32_16x16x32_bf16 v[38:41], v[212:215], v[252:255], v[38:41]
	ds_read_b128 v[212:215], v244 offset:18496
	s_waitcnt lgkmcnt(3)
	v_mfma_f32_16x16x32_bf16 v[58:61], v[216:219], v[228:231], v[58:61]
	v_mfma_f32_16x16x32_bf16 v[62:65], v[216:219], v[236:239], v[62:65]
	v_mfma_f32_16x16x32_bf16 v[42:45], v[216:219], v[240:243], v[42:45]
	v_mfma_f32_16x16x32_bf16 v[46:49], v[216:219], v[252:255], v[46:49]
	ds_read_b128 v[216:219], v244 offset:20800
	s_setprio 1
	s_waitcnt vmcnt(15)
	ds_write_b128 v165, v[180:183]
	s_waitcnt vmcnt(14)
	ds_write_b128 v165, v[184:187] offset:4608
	s_waitcnt lgkmcnt(5)
	v_mfma_f32_16x16x32_bf16 v[18:21], v[220:223], v[228:231], v[18:21]
	v_mfma_f32_16x16x32_bf16 v[22:25], v[220:223], v[236:239], v[22:25]
	v_mfma_f32_16x16x32_bf16 v[2:5], v[220:223], v[240:243], v[2:5]
	v_mfma_f32_16x16x32_bf16 v[6:9], v[220:223], v[252:255], v[6:9]
	ds_read_b128 v[220:223], v244 offset:23104
	s_waitcnt vmcnt(13)
	ds_write_b128 v165, v[188:191] offset:9216
	s_waitcnt vmcnt(12)
	ds_write_b128 v165, v[192:195] offset:13824
	s_waitcnt lgkmcnt(7)
	v_mfma_f32_16x16x32_bf16 v[26:29], v[224:227], v[228:231], v[26:29]
	ds_read_b128 v[228:231], v245 offset:55360
	v_mfma_f32_16x16x32_bf16 v[30:33], v[224:227], v[236:239], v[30:33]
	ds_read_b128 v[236:239], v245 offset:57664
	v_mfma_f32_16x16x32_bf16 v[10:13], v[224:227], v[240:243], v[10:13]
	ds_read_b128 v[240:243], v245 offset:59968
	v_mfma_f32_16x16x32_bf16 v[14:17], v[224:227], v[252:255], v[14:17]
	ds_read_b128 v[252:255], v245 offset:62272
	ds_read_b128 v[224:227], v244 offset:25408
	s_waitcnt lgkmcnt(4)
	v_mfma_f32_16x16x32_bf16 v[50:53], v[212:215], v[228:231], v[50:53]
	s_waitcnt lgkmcnt(3)
	v_mfma_f32_16x16x32_bf16 v[54:57], v[212:215], v[236:239], v[54:57]
	s_waitcnt lgkmcnt(2)
	v_mfma_f32_16x16x32_bf16 v[34:37], v[212:215], v[240:243], v[34:37]
	s_waitcnt lgkmcnt(1)
	v_mfma_f32_16x16x32_bf16 v[38:41], v[212:215], v[252:255], v[38:41]
	s_waitcnt vmcnt(11)
	ds_write_b128 v165, v[196:199] offset:36864
	s_waitcnt vmcnt(10)
	ds_write_b128 v165, v[200:203] offset:41472
	v_mfma_f32_16x16x32_bf16 v[58:61], v[216:219], v[228:231], v[58:61]
	v_mfma_f32_16x16x32_bf16 v[62:65], v[216:219], v[236:239], v[62:65]
	v_mfma_f32_16x16x32_bf16 v[42:45], v[216:219], v[240:243], v[42:45]
	v_mfma_f32_16x16x32_bf16 v[46:49], v[216:219], v[252:255], v[46:49]
	s_waitcnt vmcnt(9)
	ds_write_b128 v165, v[204:207] offset:46080
	s_waitcnt vmcnt(8)
	ds_write_b128 v165, v[208:211] offset:50688
	v_mfma_f32_16x16x32_bf16 v[18:21], v[220:223], v[228:231], v[18:21]
	v_mfma_f32_16x16x32_bf16 v[22:25], v[220:223], v[236:239], v[22:25]
	v_mfma_f32_16x16x32_bf16 v[2:5], v[220:223], v[240:243], v[2:5]
	v_mfma_f32_16x16x32_bf16 v[6:9], v[220:223], v[252:255], v[6:9]
	s_waitcnt lgkmcnt(4)
	v_mfma_f32_16x16x32_bf16 v[26:29], v[224:227], v[228:231], v[26:29]
	v_mfma_f32_16x16x32_bf16 v[30:33], v[224:227], v[236:239], v[30:33]
	v_mfma_f32_16x16x32_bf16 v[10:13], v[224:227], v[240:243], v[10:13]
	v_mfma_f32_16x16x32_bf16 v[14:17], v[224:227], v[252:255], v[14:17]
	s_waitcnt lgkmcnt(0)
	s_barrier
	s_setprio 0
	ds_read_b128 v[228:231], v245 offset:36864
	ds_read_b128 v[212:215], v244
	ds_read_b128 v[236:239], v245 offset:39168
	ds_read_b128 v[240:243], v245 offset:41472
	ds_read_b128 v[252:255], v245 offset:43776
	ds_read_b128 v[216:219], v244 offset:2304
	ds_read_b128 v[220:223], v244 offset:4608
	ds_read_b128 v[224:227], v244 offset:6912
	s_waitcnt lgkmcnt(6)
	v_mfma_f32_16x16x32_bf16 v[50:53], v[212:215], v[228:231], v[50:53]
	s_waitcnt lgkmcnt(5)
	v_mfma_f32_16x16x32_bf16 v[54:57], v[212:215], v[236:239], v[54:57]
	s_waitcnt lgkmcnt(4)
	v_mfma_f32_16x16x32_bf16 v[34:37], v[212:215], v[240:243], v[34:37]
	s_waitcnt lgkmcnt(3)
	v_mfma_f32_16x16x32_bf16 v[38:41], v[212:215], v[252:255], v[38:41]
	ds_read_b128 v[212:215], v244 offset:64
	s_waitcnt lgkmcnt(3)
	v_mfma_f32_16x16x32_bf16 v[58:61], v[216:219], v[228:231], v[58:61]
	v_mfma_f32_16x16x32_bf16 v[62:65], v[216:219], v[236:239], v[62:65]
	v_mfma_f32_16x16x32_bf16 v[42:45], v[216:219], v[240:243], v[42:45]
	v_mfma_f32_16x16x32_bf16 v[46:49], v[216:219], v[252:255], v[46:49]
	ds_read_b128 v[216:219], v244 offset:2368
	s_setprio 1
	s_waitcnt vmcnt(7)
	ds_write_b128 v165, v[122:125] offset:18432
	s_waitcnt vmcnt(6)
	ds_write_b128 v165, v[72:75] offset:23040
	s_waitcnt lgkmcnt(5)
	v_mfma_f32_16x16x32_bf16 v[18:21], v[220:223], v[228:231], v[18:21]
	v_mfma_f32_16x16x32_bf16 v[22:25], v[220:223], v[236:239], v[22:25]
	v_mfma_f32_16x16x32_bf16 v[2:5], v[220:223], v[240:243], v[2:5]
	v_mfma_f32_16x16x32_bf16 v[6:9], v[220:223], v[252:255], v[6:9]
	ds_read_b128 v[220:223], v244 offset:4672
	s_waitcnt vmcnt(5)
	ds_write_b128 v165, v[126:129] offset:27648
	s_waitcnt vmcnt(4)
	ds_write_b128 v165, v[76:79] offset:32256
	s_waitcnt lgkmcnt(7)
	v_mfma_f32_16x16x32_bf16 v[26:29], v[224:227], v[228:231], v[26:29]
	ds_read_b128 v[228:231], v245 offset:36928
	v_mfma_f32_16x16x32_bf16 v[30:33], v[224:227], v[236:239], v[30:33]
	ds_read_b128 v[236:239], v245 offset:39232
	v_mfma_f32_16x16x32_bf16 v[10:13], v[224:227], v[240:243], v[10:13]
	ds_read_b128 v[240:243], v245 offset:41536
	v_mfma_f32_16x16x32_bf16 v[14:17], v[224:227], v[252:255], v[14:17]
	ds_read_b128 v[252:255], v245 offset:43840
	ds_read_b128 v[224:227], v244 offset:6976
	s_waitcnt lgkmcnt(4)
	v_mfma_f32_16x16x32_bf16 v[50:53], v[212:215], v[228:231], v[50:53]
	s_waitcnt lgkmcnt(3)
	v_mfma_f32_16x16x32_bf16 v[54:57], v[212:215], v[236:239], v[54:57]
	s_waitcnt lgkmcnt(2)
	v_mfma_f32_16x16x32_bf16 v[34:37], v[212:215], v[240:243], v[34:37]
	s_waitcnt lgkmcnt(1)
	v_mfma_f32_16x16x32_bf16 v[38:41], v[212:215], v[252:255], v[38:41]
	s_waitcnt vmcnt(3)
	ds_write_b128 v165, v[136:139] offset:55296
	s_waitcnt vmcnt(2)
	ds_write_b128 v165, v[68:71] offset:59904
	v_mfma_f32_16x16x32_bf16 v[58:61], v[216:219], v[228:231], v[58:61]
	v_mfma_f32_16x16x32_bf16 v[62:65], v[216:219], v[236:239], v[62:65]
	v_mfma_f32_16x16x32_bf16 v[42:45], v[216:219], v[240:243], v[42:45]
	v_mfma_f32_16x16x32_bf16 v[46:49], v[216:219], v[252:255], v[46:49]
	s_waitcnt vmcnt(1)
	ds_write_b128 v165, v[140:143] offset:64512
	s_waitcnt vmcnt(0)
	ds_write_b128 v166, v[144:147] offset:32256
	v_mfma_f32_16x16x32_bf16 v[18:21], v[220:223], v[228:231], v[18:21]
	v_mfma_f32_16x16x32_bf16 v[22:25], v[220:223], v[236:239], v[22:25]
	v_mfma_f32_16x16x32_bf16 v[2:5], v[220:223], v[240:243], v[2:5]
	v_mfma_f32_16x16x32_bf16 v[6:9], v[220:223], v[252:255], v[6:9]
	s_waitcnt lgkmcnt(4)
	v_mfma_f32_16x16x32_bf16 v[26:29], v[224:227], v[228:231], v[26:29]
	v_mfma_f32_16x16x32_bf16 v[30:33], v[224:227], v[236:239], v[30:33]
	v_mfma_f32_16x16x32_bf16 v[10:13], v[224:227], v[240:243], v[10:13]
	v_mfma_f32_16x16x32_bf16 v[14:17], v[224:227], v[252:255], v[14:17]
	s_waitcnt lgkmcnt(0)
	s_barrier
	s_setprio 0
	ds_read_b128 v[228:231], v245 offset:55296
	ds_read_b128 v[212:215], v244 offset:18432
	ds_read_b128 v[236:239], v245 offset:57600
	ds_read_b128 v[240:243], v245 offset:59904
	ds_read_b128 v[252:255], v245 offset:62208
	ds_read_b128 v[216:219], v244 offset:20736
	ds_read_b128 v[220:223], v244 offset:23040
	ds_read_b128 v[224:227], v244 offset:25344
	s_waitcnt lgkmcnt(6)
	v_mfma_f32_16x16x32_bf16 v[50:53], v[212:215], v[228:231], v[50:53]
	s_waitcnt lgkmcnt(5)
	v_mfma_f32_16x16x32_bf16 v[54:57], v[212:215], v[236:239], v[54:57]
	s_waitcnt lgkmcnt(4)
	v_mfma_f32_16x16x32_bf16 v[34:37], v[212:215], v[240:243], v[34:37]
	s_waitcnt lgkmcnt(3)
	v_mfma_f32_16x16x32_bf16 v[38:41], v[212:215], v[252:255], v[38:41]
	ds_read_b128 v[212:215], v244 offset:18496
	s_waitcnt lgkmcnt(3)
	v_mfma_f32_16x16x32_bf16 v[58:61], v[216:219], v[228:231], v[58:61]
	v_mfma_f32_16x16x32_bf16 v[62:65], v[216:219], v[236:239], v[62:65]
	v_mfma_f32_16x16x32_bf16 v[42:45], v[216:219], v[240:243], v[42:45]
	v_mfma_f32_16x16x32_bf16 v[46:49], v[216:219], v[252:255], v[46:49]
	ds_read_b128 v[216:219], v244 offset:20800
	s_waitcnt lgkmcnt(3)
	v_mfma_f32_16x16x32_bf16 v[18:21], v[220:223], v[228:231], v[18:21]
	v_mfma_f32_16x16x32_bf16 v[22:25], v[220:223], v[236:239], v[22:25]
	v_mfma_f32_16x16x32_bf16 v[2:5], v[220:223], v[240:243], v[2:5]
	v_mfma_f32_16x16x32_bf16 v[6:9], v[220:223], v[252:255], v[6:9]
	ds_read_b128 v[220:223], v244 offset:23104
	s_waitcnt lgkmcnt(3)
	v_mfma_f32_16x16x32_bf16 v[26:29], v[224:227], v[228:231], v[26:29]
	ds_read_b128 v[228:231], v245 offset:55360
	v_mfma_f32_16x16x32_bf16 v[30:33], v[224:227], v[236:239], v[30:33]
	ds_read_b128 v[236:239], v245 offset:57664
	v_mfma_f32_16x16x32_bf16 v[10:13], v[224:227], v[240:243], v[10:13]
	ds_read_b128 v[240:243], v245 offset:59968
	v_mfma_f32_16x16x32_bf16 v[14:17], v[224:227], v[252:255], v[14:17]
	ds_read_b128 v[252:255], v245 offset:62272
	ds_read_b128 v[224:227], v244 offset:25408
	s_waitcnt lgkmcnt(4)
	v_mfma_f32_16x16x32_bf16 v[50:53], v[212:215], v[228:231], v[50:53]
	s_waitcnt lgkmcnt(3)
	v_mfma_f32_16x16x32_bf16 v[54:57], v[212:215], v[236:239], v[54:57]
	s_waitcnt lgkmcnt(2)
	v_mfma_f32_16x16x32_bf16 v[34:37], v[212:215], v[240:243], v[34:37]
	s_waitcnt lgkmcnt(1)
	v_mfma_f32_16x16x32_bf16 v[38:41], v[212:215], v[252:255], v[38:41]
	v_mfma_f32_16x16x32_bf16 v[58:61], v[216:219], v[228:231], v[58:61]
	v_mfma_f32_16x16x32_bf16 v[62:65], v[216:219], v[236:239], v[62:65]
	v_mfma_f32_16x16x32_bf16 v[42:45], v[216:219], v[240:243], v[42:45]
	v_mfma_f32_16x16x32_bf16 v[46:49], v[216:219], v[252:255], v[46:49]
	v_mfma_f32_16x16x32_bf16 v[18:21], v[220:223], v[228:231], v[18:21]
	v_mfma_f32_16x16x32_bf16 v[22:25], v[220:223], v[236:239], v[22:25]
	v_mfma_f32_16x16x32_bf16 v[2:5], v[220:223], v[240:243], v[2:5]
	v_mfma_f32_16x16x32_bf16 v[6:9], v[220:223], v[252:255], v[6:9]
	s_waitcnt lgkmcnt(0)
	v_mfma_f32_16x16x32_bf16 v[26:29], v[224:227], v[228:231], v[26:29]
	v_mfma_f32_16x16x32_bf16 v[30:33], v[224:227], v[236:239], v[30:33]
	v_mfma_f32_16x16x32_bf16 v[10:13], v[224:227], v[240:243], v[10:13]
	v_mfma_f32_16x16x32_bf16 v[14:17], v[224:227], v[252:255], v[14:17]
	s_mov_b64 s[2:3], 0
	s_waitcnt lgkmcnt(0)
	s_barrier
	s_nop 7
	v_permlane16_swap_b32_e32 v50, v54
	v_permlane16_swap_b32_e32 v51, v55
	v_permlane16_swap_b32_e32 v52, v56
	v_permlane16_swap_b32_e32 v53, v57
	v_permlane16_swap_b32_e32 v58, v62
	v_permlane16_swap_b32_e32 v59, v63
	v_permlane16_swap_b32_e32 v60, v64
	v_permlane16_swap_b32_e32 v61, v65
	v_permlane16_swap_b32_e32 v34, v38
	v_permlane16_swap_b32_e32 v35, v39
	v_permlane16_swap_b32_e32 v36, v40
	v_permlane16_swap_b32_e32 v37, v41
	v_permlane16_swap_b32_e32 v42, v46
	v_permlane16_swap_b32_e32 v43, v47
	v_permlane16_swap_b32_e32 v44, v48
	v_permlane16_swap_b32_e32 v45, v49
	v_permlane16_swap_b32_e32 v18, v22
	v_permlane16_swap_b32_e32 v19, v23
	v_permlane16_swap_b32_e32 v20, v24
	v_permlane16_swap_b32_e32 v21, v25
	v_permlane16_swap_b32_e32 v26, v30
	v_permlane16_swap_b32_e32 v27, v31
	v_permlane16_swap_b32_e32 v28, v32
	v_permlane16_swap_b32_e32 v29, v33
	v_permlane16_swap_b32_e32 v2, v6
	v_permlane16_swap_b32_e32 v3, v7
	v_permlane16_swap_b32_e32 v4, v8
	v_permlane16_swap_b32_e32 v5, v9
	v_permlane16_swap_b32_e32 v10, v14
	v_permlane16_swap_b32_e32 v11, v15
	v_permlane16_swap_b32_e32 v12, v16
	v_permlane16_swap_b32_e32 v13, v17
	v_permlane32_swap_b32_e32 v50, v54
	v_permlane32_swap_b32_e32 v51, v55
	v_permlane32_swap_b32_e32 v52, v56
	v_permlane32_swap_b32_e32 v53, v57
	v_permlane32_swap_b32_e32 v58, v62
	v_permlane32_swap_b32_e32 v59, v63
	v_permlane32_swap_b32_e32 v60, v64
	v_permlane32_swap_b32_e32 v61, v65
	v_permlane32_swap_b32_e32 v34, v38
	v_permlane32_swap_b32_e32 v35, v39
	v_permlane32_swap_b32_e32 v36, v40
	v_permlane32_swap_b32_e32 v37, v41
	v_permlane32_swap_b32_e32 v42, v46
	v_permlane32_swap_b32_e32 v43, v47
	v_permlane32_swap_b32_e32 v44, v48
	v_permlane32_swap_b32_e32 v45, v49
	v_permlane32_swap_b32_e32 v18, v22
	v_permlane32_swap_b32_e32 v19, v23
	v_permlane32_swap_b32_e32 v20, v24
	v_permlane32_swap_b32_e32 v21, v25
	v_permlane32_swap_b32_e32 v26, v30
	v_permlane32_swap_b32_e32 v27, v31
	v_permlane32_swap_b32_e32 v28, v32
	v_permlane32_swap_b32_e32 v29, v33
	v_permlane32_swap_b32_e32 v2, v6
	v_permlane32_swap_b32_e32 v3, v7
	v_permlane32_swap_b32_e32 v4, v8
	v_permlane32_swap_b32_e32 v5, v9
	v_permlane32_swap_b32_e32 v10, v14
	v_permlane32_swap_b32_e32 v11, v15
	v_permlane32_swap_b32_e32 v12, v16
	v_permlane32_swap_b32_e32 v13, v17

.LBB0_275:
	v_ashrrev_i32_e32 v3, 31, v2
	v_lshlrev_b64 v[2:3], 11, v[2:3]
	v_ashrrev_i32_e32 v9, 31, v8
	v_lshl_add_u64 v[70:71], v[86:87], 0, v[2:3]
	v_lshlrev_b64 v[2:3], 11, v[8:9]
	v_lshl_add_u64 v[72:73], v[86:87], 0, v[2:3]
	v_or_b32_e32 v2, s56, v154
	v_ashrrev_i32_e32 v3, 31, v2
	v_lshlrev_b64 v[2:3], 11, v[2:3]
	v_lshl_add_u64 v[74:75], v[84:85], 0, v[2:3]
	v_add_u32_e32 v2, s56, v155
	v_ashrrev_i32_e32 v3, 31, v2
	v_lshlrev_b64 v[2:3], 11, v[2:3]
	v_lshl_add_u64 v[76:77], v[84:85], 0, v[2:3]
	v_add_u32_e32 v2, s56, v156
	v_ashrrev_i32_e32 v3, 31, v2
	v_lshlrev_b64 v[2:3], 11, v[2:3]
	v_lshl_add_u64 v[78:79], v[84:85], 0, v[2:3]
	v_add_u32_e32 v2, s56, v157
	v_ashrrev_i32_e32 v7, 31, v6
	v_ashrrev_i32_e32 v5, 31, v4
	v_ashrrev_i32_e32 v3, 31, v2
	v_lshlrev_b64 v[6:7], 11, v[6:7]
	v_lshlrev_b64 v[4:5], 11, v[4:5]
	v_lshlrev_b64 v[2:3], 11, v[2:3]
	v_lshl_add_u64 v[66:67], v[86:87], 0, v[6:7]
	v_lshl_add_u64 v[68:69], v[86:87], 0, v[4:5]
	v_lshl_add_u64 v[80:81], v[84:85], 0, v[2:3]
	global_load_dwordx4 v[2:5], v[70:71], off
	global_load_dwordx4 v[6:9], v[68:69], off
	global_load_dwordx4 v[10:13], v[66:67], off
	global_load_dwordx4 v[14:17], v[72:73], off
	global_load_dwordx4 v[18:21], v[74:75], off
	global_load_dwordx4 v[22:25], v[76:77], off
	global_load_dwordx4 v[26:29], v[78:79], off
	global_load_dwordx4 v[30:33], v[80:81], off
	global_load_dwordx4 v[122:125], v[70:71], off offset:128
	global_load_dwordx4 v[126:129], v[68:69], off offset:128
	global_load_dwordx4 v[136:139], v[66:67], off offset:128
	global_load_dwordx4 v[140:143], v[72:73], off offset:128
	global_load_dwordx4 v[144:147], v[74:75], off offset:128
	global_load_dwordx4 v[148:151], v[76:77], off offset:128
	global_load_dwordx4 v[172:175], v[78:79], off offset:128
	global_load_dwordx4 v[176:179], v[80:81], off offset:128
	s_setprio 1
	s_waitcnt vmcnt(15)
	ds_write_b128 v165, v[2:5]
	s_waitcnt vmcnt(14)
	ds_write_b128 v165, v[6:9] offset:4608
	s_waitcnt vmcnt(13)
	ds_write_b128 v165, v[10:13] offset:9216
	s_waitcnt vmcnt(12)
	ds_write_b128 v165, v[14:17] offset:13824
	s_waitcnt vmcnt(11)
	ds_write_b128 v165, v[18:21] offset:36864
	s_waitcnt vmcnt(10)
	ds_write_b128 v165, v[22:25] offset:41472
	s_waitcnt vmcnt(9)
	ds_write_b128 v165, v[26:29] offset:46080
	s_waitcnt vmcnt(8)
	ds_write_b128 v165, v[30:33] offset:50688
	s_waitcnt lgkmcnt(0)
	s_barrier
	s_setprio 0
	global_load_dwordx4 v[180:183], v[68:69], off offset:256
	global_load_dwordx4 v[184:187], v[66:67], off offset:256
	global_load_dwordx4 v[188:191], v[70:71], off offset:256
	global_load_dwordx4 v[192:195], v[72:73], off offset:256
	global_load_dwordx4 v[196:199], v[74:75], off offset:256
	global_load_dwordx4 v[200:203], v[76:77], off offset:256
	global_load_dwordx4 v[204:207], v[78:79], off offset:256
	global_load_dwordx4 v[208:211], v[80:81], off offset:256
	v_and_b32_e32 v246, 15, v1
	v_add_u32_e32 v246, 4, v246
	v_bfe_u32 v246, v246, 3, 1
	v_bfe_u32 v249, v1, 4, 2
	v_xor_b32_e32 v246, v246, v249
	v_bfe_u32 v249, v1, 5, 1
	v_sub_u32_e32 v246, v246, v249
	v_lshlrev_b32_e32 v246, 4, v246
	v_bfe_u32 v249, v1, 4, 1
	v_mul_u32_u24_e32 v249, 0x900, v249
	v_sub_u32_e32 v246, v246, v249
	v_add_u32_e32 v244, v246, v162
	v_add_u32_e32 v245, v246, v164
	ds_read_b128 v[228:231], v245 offset:36864
	ds_read_b128 v[212:215], v244
	ds_read_b128 v[236:239], v245 offset:39168
	ds_read_b128 v[240:243], v245 offset:41472
	ds_read_b128 v[252:255], v245 offset:43776
	ds_read_b128 v[216:219], v244 offset:2304
	ds_read_b128 v[220:223], v244 offset:4608
	ds_read_b128 v[224:227], v244 offset:6912
	s_waitcnt lgkmcnt(6)
	v_mfma_f32_16x16x32_bf16 v[50:53], v[212:215], v[228:231], 0
	s_waitcnt lgkmcnt(5)
	v_mfma_f32_16x16x32_bf16 v[54:57], v[212:215], v[236:239], 0
	s_waitcnt lgkmcnt(4)
	v_mfma_f32_16x16x32_bf16 v[34:37], v[212:215], v[240:243], 0
	s_waitcnt lgkmcnt(3)
	v_mfma_f32_16x16x32_bf16 v[38:41], v[212:215], v[252:255], 0
	ds_read_b128 v[212:215], v244 offset:64
	s_waitcnt lgkmcnt(3)
	v_mfma_f32_16x16x32_bf16 v[58:61], v[216:219], v[228:231], 0
	v_mfma_f32_16x16x32_bf16 v[62:65], v[216:219], v[236:239], 0
	v_mfma_f32_16x16x32_bf16 v[42:45], v[216:219], v[240:243], 0
	v_mfma_f32_16x16x32_bf16 v[46:49], v[216:219], v[252:255], 0
	ds_read_b128 v[216:219], v244 offset:2368
	s_setprio 1
	s_waitcnt vmcnt(15)
	ds_write_b128 v165, v[122:125] offset:18432
	s_waitcnt vmcnt(14)
	ds_write_b128 v165, v[126:129] offset:23040
	s_waitcnt lgkmcnt(5)
	v_mfma_f32_16x16x32_bf16 v[18:21], v[220:223], v[228:231], 0
	v_mfma_f32_16x16x32_bf16 v[22:25], v[220:223], v[236:239], 0
	v_mfma_f32_16x16x32_bf16 v[2:5], v[220:223], v[240:243], 0
	v_mfma_f32_16x16x32_bf16 v[6:9], v[220:223], v[252:255], 0
	ds_read_b128 v[220:223], v244 offset:4672
	s_waitcnt vmcnt(13)
	ds_write_b128 v165, v[136:139] offset:27648
	s_waitcnt vmcnt(12)
	ds_write_b128 v165, v[140:143] offset:32256
	s_waitcnt lgkmcnt(7)
	v_mfma_f32_16x16x32_bf16 v[26:29], v[224:227], v[228:231], 0
	ds_read_b128 v[228:231], v245 offset:36928
	v_mfma_f32_16x16x32_bf16 v[30:33], v[224:227], v[236:239], 0
	ds_read_b128 v[236:239], v245 offset:39232
	v_mfma_f32_16x16x32_bf16 v[10:13], v[224:227], v[240:243], 0
	ds_read_b128 v[240:243], v245 offset:41536
	v_mfma_f32_16x16x32_bf16 v[14:17], v[224:227], v[252:255], 0
	ds_read_b128 v[252:255], v245 offset:43840
	ds_read_b128 v[224:227], v244 offset:6976
	s_waitcnt lgkmcnt(4)
	v_mfma_f32_16x16x32_bf16 v[50:53], v[212:215], v[228:231], v[50:53]
	s_waitcnt lgkmcnt(3)
	v_mfma_f32_16x16x32_bf16 v[54:57], v[212:215], v[236:239], v[54:57]
	s_waitcnt lgkmcnt(2)
	v_mfma_f32_16x16x32_bf16 v[34:37], v[212:215], v[240:243], v[34:37]
	s_waitcnt lgkmcnt(1)
	v_mfma_f32_16x16x32_bf16 v[38:41], v[212:215], v[252:255], v[38:41]
	s_waitcnt vmcnt(11)
	ds_write_b128 v165, v[144:147] offset:55296
	s_waitcnt vmcnt(10)
	ds_write_b128 v165, v[148:151] offset:59904
	v_mfma_f32_16x16x32_bf16 v[58:61], v[216:219], v[228:231], v[58:61]
	v_mfma_f32_16x16x32_bf16 v[62:65], v[216:219], v[236:239], v[62:65]
	v_mfma_f32_16x16x32_bf16 v[42:45], v[216:219], v[240:243], v[42:45]
	v_mfma_f32_16x16x32_bf16 v[46:49], v[216:219], v[252:255], v[46:49]
	s_waitcnt vmcnt(9)
	ds_write_b128 v165, v[172:175] offset:64512
	s_waitcnt vmcnt(8)
	ds_write_b128 v166, v[176:179] offset:32256
	v_mfma_f32_16x16x32_bf16 v[18:21], v[220:223], v[228:231], v[18:21]
	v_mfma_f32_16x16x32_bf16 v[22:25], v[220:223], v[236:239], v[22:25]
	v_mfma_f32_16x16x32_bf16 v[2:5], v[220:223], v[240:243], v[2:5]
	v_mfma_f32_16x16x32_bf16 v[6:9], v[220:223], v[252:255], v[6:9]
	s_waitcnt lgkmcnt(4)
	v_mfma_f32_16x16x32_bf16 v[26:29], v[224:227], v[228:231], v[26:29]
	v_mfma_f32_16x16x32_bf16 v[30:33], v[224:227], v[236:239], v[30:33]
	v_mfma_f32_16x16x32_bf16 v[10:13], v[224:227], v[240:243], v[10:13]
	v_mfma_f32_16x16x32_bf16 v[14:17], v[224:227], v[252:255], v[14:17]
	s_waitcnt lgkmcnt(0)
	s_barrier
	s_setprio 0
	global_load_dwordx4 v[122:125], v[70:71], off offset:384
	global_load_dwordx4 v[126:129], v[68:69], off offset:384
	global_load_dwordx4 v[136:139], v[66:67], off offset:384
	global_load_dwordx4 v[140:143], v[72:73], off offset:384
	global_load_dwordx4 v[144:147], v[74:75], off offset:384
	global_load_dwordx4 v[148:151], v[76:77], off offset:384
	global_load_dwordx4 v[172:175], v[78:79], off offset:384
	global_load_dwordx4 v[176:179], v[80:81], off offset:384
	ds_read_b128 v[228:231], v245 offset:55296
	ds_read_b128 v[212:215], v244 offset:18432
	ds_read_b128 v[236:239], v245 offset:57600
	ds_read_b128 v[240:243], v245 offset:59904
	ds_read_b128 v[252:255], v245 offset:62208
	ds_read_b128 v[216:219], v244 offset:20736
	ds_read_b128 v[220:223], v244 offset:23040
	ds_read_b128 v[224:227], v244 offset:25344
	s_waitcnt lgkmcnt(6)
	v_mfma_f32_16x16x32_bf16 v[50:53], v[212:215], v[228:231], v[50:53]
	s_waitcnt lgkmcnt(5)
	v_mfma_f32_16x16x32_bf16 v[54:57], v[212:215], v[236:239], v[54:57]
	s_waitcnt lgkmcnt(4)
	v_mfma_f32_16x16x32_bf16 v[34:37], v[212:215], v[240:243], v[34:37]
	s_waitcnt lgkmcnt(3)
	v_mfma_f32_16x16x32_bf16 v[38:41], v[212:215], v[252:255], v[38:41]
	ds_read_b128 v[212:215], v244 offset:18496
	s_waitcnt lgkmcnt(3)
	v_mfma_f32_16x16x32_bf16 v[58:61], v[216:219], v[228:231], v[58:61]
	v_mfma_f32_16x16x32_bf16 v[62:65], v[216:219], v[236:239], v[62:65]
	v_mfma_f32_16x16x32_bf16 v[42:45], v[216:219], v[240:243], v[42:45]
	v_mfma_f32_16x16x32_bf16 v[46:49], v[216:219], v[252:255], v[46:49]
	ds_read_b128 v[216:219], v244 offset:20800
	s_setprio 1
	s_waitcnt vmcnt(13)
	ds_write_b128 v165, v[188:191]
	ds_write_b128 v165, v[180:183] offset:4608
	s_waitcnt lgkmcnt(5)
	v_mfma_f32_16x16x32_bf16 v[18:21], v[220:223], v[228:231], v[18:21]
	v_mfma_f32_16x16x32_bf16 v[22:25], v[220:223], v[236:239], v[22:25]
	v_mfma_f32_16x16x32_bf16 v[2:5], v[220:223], v[240:243], v[2:5]
	v_mfma_f32_16x16x32_bf16 v[6:9], v[220:223], v[252:255], v[6:9]
	ds_read_b128 v[220:223], v244 offset:23104
	ds_write_b128 v165, v[184:187] offset:9216
	s_waitcnt vmcnt(12)
	ds_write_b128 v165, v[192:195] offset:13824
	s_waitcnt lgkmcnt(7)
	v_mfma_f32_16x16x32_bf16 v[26:29], v[224:227], v[228:231], v[26:29]
	ds_read_b128 v[228:231], v245 offset:55360
	v_mfma_f32_16x16x32_bf16 v[30:33], v[224:227], v[236:239], v[30:33]
	ds_read_b128 v[236:239], v245 offset:57664
	v_mfma_f32_16x16x32_bf16 v[10:13], v[224:227], v[240:243], v[10:13]
	ds_read_b128 v[240:243], v245 offset:59968
	v_mfma_f32_16x16x32_bf16 v[14:17], v[224:227], v[252:255], v[14:17]
	ds_read_b128 v[252:255], v245 offset:62272
	ds_read_b128 v[224:227], v244 offset:25408
	s_waitcnt lgkmcnt(4)
	v_mfma_f32_16x16x32_bf16 v[50:53], v[212:215], v[228:231], v[50:53]
	s_waitcnt lgkmcnt(3)
	v_mfma_f32_16x16x32_bf16 v[54:57], v[212:215], v[236:239], v[54:57]
	s_waitcnt lgkmcnt(2)
	v_mfma_f32_16x16x32_bf16 v[34:37], v[212:215], v[240:243], v[34:37]
	s_waitcnt lgkmcnt(1)
	v_mfma_f32_16x16x32_bf16 v[38:41], v[212:215], v[252:255], v[38:41]
	s_waitcnt vmcnt(11)
	ds_write_b128 v165, v[196:199] offset:36864
	s_waitcnt vmcnt(10)
	ds_write_b128 v165, v[200:203] offset:41472
	v_mfma_f32_16x16x32_bf16 v[58:61], v[216:219], v[228:231], v[58:61]
	v_mfma_f32_16x16x32_bf16 v[62:65], v[216:219], v[236:239], v[62:65]
	v_mfma_f32_16x16x32_bf16 v[42:45], v[216:219], v[240:243], v[42:45]
	v_mfma_f32_16x16x32_bf16 v[46:49], v[216:219], v[252:255], v[46:49]
	s_waitcnt vmcnt(9)
	ds_write_b128 v165, v[204:207] offset:46080
	s_waitcnt vmcnt(8)
	ds_write_b128 v165, v[208:211] offset:50688
	v_mfma_f32_16x16x32_bf16 v[18:21], v[220:223], v[228:231], v[18:21]
	v_mfma_f32_16x16x32_bf16 v[22:25], v[220:223], v[236:239], v[22:25]
	v_mfma_f32_16x16x32_bf16 v[2:5], v[220:223], v[240:243], v[2:5]
	v_mfma_f32_16x16x32_bf16 v[6:9], v[220:223], v[252:255], v[6:9]
	s_waitcnt lgkmcnt(4)
	v_mfma_f32_16x16x32_bf16 v[26:29], v[224:227], v[228:231], v[26:29]
	v_mfma_f32_16x16x32_bf16 v[30:33], v[224:227], v[236:239], v[30:33]
	v_mfma_f32_16x16x32_bf16 v[10:13], v[224:227], v[240:243], v[10:13]
	v_mfma_f32_16x16x32_bf16 v[14:17], v[224:227], v[252:255], v[14:17]
	s_waitcnt lgkmcnt(0)
	s_barrier
	s_setprio 0
	global_load_dwordx4 v[180:183], v[70:71], off offset:512
	global_load_dwordx4 v[184:187], v[68:69], off offset:512
	global_load_dwordx4 v[188:191], v[66:67], off offset:512
	global_load_dwordx4 v[192:195], v[72:73], off offset:512
	global_load_dwordx4 v[196:199], v[74:75], off offset:512
	global_load_dwordx4 v[200:203], v[76:77], off offset:512
	global_load_dwordx4 v[204:207], v[78:79], off offset:512
	global_load_dwordx4 v[208:211], v[80:81], off offset:512
	ds_read_b128 v[228:231], v245 offset:36864
	ds_read_b128 v[212:215], v244
	ds_read_b128 v[236:239], v245 offset:39168
	ds_read_b128 v[240:243], v245 offset:41472
	ds_read_b128 v[252:255], v245 offset:43776
	ds_read_b128 v[216:219], v244 offset:2304
	ds_read_b128 v[220:223], v244 offset:4608
	ds_read_b128 v[224:227], v244 offset:6912
	s_waitcnt lgkmcnt(6)
	v_mfma_f32_16x16x32_bf16 v[50:53], v[212:215], v[228:231], v[50:53]
	s_waitcnt lgkmcnt(5)
	v_mfma_f32_16x16x32_bf16 v[54:57], v[212:215], v[236:239], v[54:57]
	s_waitcnt lgkmcnt(4)
	v_mfma_f32_16x16x32_bf16 v[34:37], v[212:215], v[240:243], v[34:37]
	s_waitcnt lgkmcnt(3)
	v_mfma_f32_16x16x32_bf16 v[38:41], v[212:215], v[252:255], v[38:41]
	ds_read_b128 v[212:215], v244 offset:64
	s_waitcnt lgkmcnt(3)
	v_mfma_f32_16x16x32_bf16 v[58:61], v[216:219], v[228:231], v[58:61]
	v_mfma_f32_16x16x32_bf16 v[62:65], v[216:219], v[236:239], v[62:65]
	v_mfma_f32_16x16x32_bf16 v[42:45], v[216:219], v[240:243], v[42:45]
	v_mfma_f32_16x16x32_bf16 v[46:49], v[216:219], v[252:255], v[46:49]
	ds_read_b128 v[216:219], v244 offset:2368
	s_setprio 1
	s_waitcnt vmcnt(15)
	ds_write_b128 v165, v[122:125] offset:18432
	s_waitcnt vmcnt(14)
	ds_write_b128 v165, v[126:129] offset:23040
	s_waitcnt lgkmcnt(5)
	v_mfma_f32_16x16x32_bf16 v[18:21], v[220:223], v[228:231], v[18:21]
	v_mfma_f32_16x16x32_bf16 v[22:25], v[220:223], v[236:239], v[22:25]
	v_mfma_f32_16x16x32_bf16 v[2:5], v[220:223], v[240:243], v[2:5]
	v_mfma_f32_16x16x32_bf16 v[6:9], v[220:223], v[252:255], v[6:9]
	ds_read_b128 v[220:223], v244 offset:4672
	s_waitcnt vmcnt(13)
	ds_write_b128 v165, v[136:139] offset:27648
	s_waitcnt vmcnt(12)
	ds_write_b128 v165, v[140:143] offset:32256
	s_waitcnt lgkmcnt(7)
	v_mfma_f32_16x16x32_bf16 v[26:29], v[224:227], v[228:231], v[26:29]
	ds_read_b128 v[228:231], v245 offset:36928
	v_mfma_f32_16x16x32_bf16 v[30:33], v[224:227], v[236:239], v[30:33]
	ds_read_b128 v[236:239], v245 offset:39232
	v_mfma_f32_16x16x32_bf16 v[10:13], v[224:227], v[240:243], v[10:13]
	ds_read_b128 v[240:243], v245 offset:41536
	v_mfma_f32_16x16x32_bf16 v[14:17], v[224:227], v[252:255], v[14:17]
	ds_read_b128 v[252:255], v245 offset:43840
	ds_read_b128 v[224:227], v244 offset:6976
	s_waitcnt lgkmcnt(4)
	v_mfma_f32_16x16x32_bf16 v[50:53], v[212:215], v[228:231], v[50:53]
	s_waitcnt lgkmcnt(3)
	v_mfma_f32_16x16x32_bf16 v[54:57], v[212:215], v[236:239], v[54:57]
	s_waitcnt lgkmcnt(2)
	v_mfma_f32_16x16x32_bf16 v[34:37], v[212:215], v[240:243], v[34:37]
	s_waitcnt lgkmcnt(1)
	v_mfma_f32_16x16x32_bf16 v[38:41], v[212:215], v[252:255], v[38:41]
	s_waitcnt vmcnt(11)
	ds_write_b128 v165, v[144:147] offset:55296
	s_waitcnt vmcnt(10)
	ds_write_b128 v165, v[148:151] offset:59904
	v_mfma_f32_16x16x32_bf16 v[58:61], v[216:219], v[228:231], v[58:61]
	v_mfma_f32_16x16x32_bf16 v[62:65], v[216:219], v[236:239], v[62:65]
	v_mfma_f32_16x16x32_bf16 v[42:45], v[216:219], v[240:243], v[42:45]
	v_mfma_f32_16x16x32_bf16 v[46:49], v[216:219], v[252:255], v[46:49]
	s_waitcnt vmcnt(9)
	ds_write_b128 v165, v[172:175] offset:64512
	s_waitcnt vmcnt(8)
	ds_write_b128 v166, v[176:179] offset:32256
	v_mfma_f32_16x16x32_bf16 v[18:21], v[220:223], v[228:231], v[18:21]
	v_mfma_f32_16x16x32_bf16 v[22:25], v[220:223], v[236:239], v[22:25]
	v_mfma_f32_16x16x32_bf16 v[2:5], v[220:223], v[240:243], v[2:5]
	v_mfma_f32_16x16x32_bf16 v[6:9], v[220:223], v[252:255], v[6:9]
	s_waitcnt lgkmcnt(4)
	v_mfma_f32_16x16x32_bf16 v[26:29], v[224:227], v[228:231], v[26:29]
	v_mfma_f32_16x16x32_bf16 v[30:33], v[224:227], v[236:239], v[30:33]
	v_mfma_f32_16x16x32_bf16 v[10:13], v[224:227], v[240:243], v[10:13]
	v_mfma_f32_16x16x32_bf16 v[14:17], v[224:227], v[252:255], v[14:17]
	s_waitcnt lgkmcnt(0)
	s_barrier
	s_setprio 0
	global_load_dwordx4 v[122:125], v[70:71], off offset:640
	global_load_dwordx4 v[126:129], v[68:69], off offset:640
	global_load_dwordx4 v[136:139], v[66:67], off offset:640
	global_load_dwordx4 v[140:143], v[72:73], off offset:640
	global_load_dwordx4 v[144:147], v[74:75], off offset:640
	global_load_dwordx4 v[148:151], v[76:77], off offset:640
	global_load_dwordx4 v[172:175], v[78:79], off offset:640
	global_load_dwordx4 v[176:179], v[80:81], off offset:640
	ds_read_b128 v[228:231], v245 offset:55296
	ds_read_b128 v[212:215], v244 offset:18432
	ds_read_b128 v[236:239], v245 offset:57600
	ds_read_b128 v[240:243], v245 offset:59904
	ds_read_b128 v[252:255], v245 offset:62208
	ds_read_b128 v[216:219], v244 offset:20736
	ds_read_b128 v[220:223], v244 offset:23040
	ds_read_b128 v[224:227], v244 offset:25344
	s_waitcnt lgkmcnt(6)
	v_mfma_f32_16x16x32_bf16 v[50:53], v[212:215], v[228:231], v[50:53]
	s_waitcnt lgkmcnt(5)
	v_mfma_f32_16x16x32_bf16 v[54:57], v[212:215], v[236:239], v[54:57]
	s_waitcnt lgkmcnt(4)
	v_mfma_f32_16x16x32_bf16 v[34:37], v[212:215], v[240:243], v[34:37]
	s_waitcnt lgkmcnt(3)
	v_mfma_f32_16x16x32_bf16 v[38:41], v[212:215], v[252:255], v[38:41]
	ds_read_b128 v[212:215], v244 offset:18496
	s_waitcnt lgkmcnt(3)
	v_mfma_f32_16x16x32_bf16 v[58:61], v[216:219], v[228:231], v[58:61]
	v_mfma_f32_16x16x32_bf16 v[62:65], v[216:219], v[236:239], v[62:65]
	v_mfma_f32_16x16x32_bf16 v[42:45], v[216:219], v[240:243], v[42:45]
	v_mfma_f32_16x16x32_bf16 v[46:49], v[216:219], v[252:255], v[46:49]
	ds_read_b128 v[216:219], v244 offset:20800
	s_setprio 1
	s_waitcnt vmcnt(15)
	ds_write_b128 v165, v[180:183]
	s_waitcnt vmcnt(14)
	ds_write_b128 v165, v[184:187] offset:4608
	s_waitcnt lgkmcnt(5)
	v_mfma_f32_16x16x32_bf16 v[18:21], v[220:223], v[228:231], v[18:21]
	v_mfma_f32_16x16x32_bf16 v[22:25], v[220:223], v[236:239], v[22:25]
	v_mfma_f32_16x16x32_bf16 v[2:5], v[220:223], v[240:243], v[2:5]
	v_mfma_f32_16x16x32_bf16 v[6:9], v[220:223], v[252:255], v[6:9]
	ds_read_b128 v[220:223], v244 offset:23104
	s_waitcnt vmcnt(13)
	ds_write_b128 v165, v[188:191] offset:9216
	s_waitcnt vmcnt(12)
	ds_write_b128 v165, v[192:195] offset:13824
	s_waitcnt lgkmcnt(7)
	v_mfma_f32_16x16x32_bf16 v[26:29], v[224:227], v[228:231], v[26:29]
	ds_read_b128 v[228:231], v245 offset:55360
	v_mfma_f32_16x16x32_bf16 v[30:33], v[224:227], v[236:239], v[30:33]
	ds_read_b128 v[236:239], v245 offset:57664
	v_mfma_f32_16x16x32_bf16 v[10:13], v[224:227], v[240:243], v[10:13]
	ds_read_b128 v[240:243], v245 offset:59968
	v_mfma_f32_16x16x32_bf16 v[14:17], v[224:227], v[252:255], v[14:17]
	ds_read_b128 v[252:255], v245 offset:62272
	ds_read_b128 v[224:227], v244 offset:25408
	s_waitcnt lgkmcnt(4)
	v_mfma_f32_16x16x32_bf16 v[50:53], v[212:215], v[228:231], v[50:53]
	s_waitcnt lgkmcnt(3)
	v_mfma_f32_16x16x32_bf16 v[54:57], v[212:215], v[236:239], v[54:57]
	s_waitcnt lgkmcnt(2)
	v_mfma_f32_16x16x32_bf16 v[34:37], v[212:215], v[240:243], v[34:37]
	s_waitcnt lgkmcnt(1)
	v_mfma_f32_16x16x32_bf16 v[38:41], v[212:215], v[252:255], v[38:41]
	s_waitcnt vmcnt(11)
	ds_write_b128 v165, v[196:199] offset:36864
	s_waitcnt vmcnt(10)
	ds_write_b128 v165, v[200:203] offset:41472
	v_mfma_f32_16x16x32_bf16 v[58:61], v[216:219], v[228:231], v[58:61]
	v_mfma_f32_16x16x32_bf16 v[62:65], v[216:219], v[236:239], v[62:65]
	v_mfma_f32_16x16x32_bf16 v[42:45], v[216:219], v[240:243], v[42:45]
	v_mfma_f32_16x16x32_bf16 v[46:49], v[216:219], v[252:255], v[46:49]
	s_waitcnt vmcnt(9)
	ds_write_b128 v165, v[204:207] offset:46080
	s_waitcnt vmcnt(8)
	ds_write_b128 v165, v[208:211] offset:50688
	v_mfma_f32_16x16x32_bf16 v[18:21], v[220:223], v[228:231], v[18:21]
	v_mfma_f32_16x16x32_bf16 v[22:25], v[220:223], v[236:239], v[22:25]
	v_mfma_f32_16x16x32_bf16 v[2:5], v[220:223], v[240:243], v[2:5]
	v_mfma_f32_16x16x32_bf16 v[6:9], v[220:223], v[252:255], v[6:9]
	s_waitcnt lgkmcnt(4)
	v_mfma_f32_16x16x32_bf16 v[26:29], v[224:227], v[228:231], v[26:29]
	v_mfma_f32_16x16x32_bf16 v[30:33], v[224:227], v[236:239], v[30:33]
	v_mfma_f32_16x16x32_bf16 v[10:13], v[224:227], v[240:243], v[10:13]
	v_mfma_f32_16x16x32_bf16 v[14:17], v[224:227], v[252:255], v[14:17]
	s_waitcnt lgkmcnt(0)
	s_barrier
	s_setprio 0
	global_load_dwordx4 v[180:183], v[70:71], off offset:768
	global_load_dwordx4 v[184:187], v[68:69], off offset:768
	global_load_dwordx4 v[188:191], v[66:67], off offset:768
	global_load_dwordx4 v[192:195], v[72:73], off offset:768
	global_load_dwordx4 v[196:199], v[74:75], off offset:768
	global_load_dwordx4 v[200:203], v[76:77], off offset:768
	global_load_dwordx4 v[204:207], v[78:79], off offset:768
	global_load_dwordx4 v[208:211], v[80:81], off offset:768
	ds_read_b128 v[228:231], v245 offset:36864
	ds_read_b128 v[212:215], v244
	ds_read_b128 v[236:239], v245 offset:39168
	ds_read_b128 v[240:243], v245 offset:41472
	ds_read_b128 v[252:255], v245 offset:43776
	ds_read_b128 v[216:219], v244 offset:2304
	ds_read_b128 v[220:223], v244 offset:4608
	ds_read_b128 v[224:227], v244 offset:6912
	s_waitcnt lgkmcnt(6)
	v_mfma_f32_16x16x32_bf16 v[50:53], v[212:215], v[228:231], v[50:53]
	s_waitcnt lgkmcnt(5)
	v_mfma_f32_16x16x32_bf16 v[54:57], v[212:215], v[236:239], v[54:57]
	s_waitcnt lgkmcnt(4)
	v_mfma_f32_16x16x32_bf16 v[34:37], v[212:215], v[240:243], v[34:37]
	s_waitcnt lgkmcnt(3)
	v_mfma_f32_16x16x32_bf16 v[38:41], v[212:215], v[252:255], v[38:41]
	ds_read_b128 v[212:215], v244 offset:64
	s_waitcnt lgkmcnt(3)
	v_mfma_f32_16x16x32_bf16 v[58:61], v[216:219], v[228:231], v[58:61]
	v_mfma_f32_16x16x32_bf16 v[62:65], v[216:219], v[236:239], v[62:65]
	v_mfma_f32_16x16x32_bf16 v[42:45], v[216:219], v[240:243], v[42:45]
	v_mfma_f32_16x16x32_bf16 v[46:49], v[216:219], v[252:255], v[46:49]
	ds_read_b128 v[216:219], v244 offset:2368
	s_setprio 1
	s_waitcnt vmcnt(15)
	ds_write_b128 v165, v[122:125] offset:18432
	s_waitcnt vmcnt(14)
	ds_write_b128 v165, v[126:129] offset:23040
	s_waitcnt lgkmcnt(5)
	v_mfma_f32_16x16x32_bf16 v[18:21], v[220:223], v[228:231], v[18:21]
	v_mfma_f32_16x16x32_bf16 v[22:25], v[220:223], v[236:239], v[22:25]
	v_mfma_f32_16x16x32_bf16 v[2:5], v[220:223], v[240:243], v[2:5]
	v_mfma_f32_16x16x32_bf16 v[6:9], v[220:223], v[252:255], v[6:9]
	ds_read_b128 v[220:223], v244 offset:4672
	s_waitcnt vmcnt(13)
	ds_write_b128 v165, v[136:139] offset:27648
	s_waitcnt vmcnt(12)
	ds_write_b128 v165, v[140:143] offset:32256
	s_waitcnt lgkmcnt(7)
	v_mfma_f32_16x16x32_bf16 v[26:29], v[224:227], v[228:231], v[26:29]
	ds_read_b128 v[228:231], v245 offset:36928
	v_mfma_f32_16x16x32_bf16 v[30:33], v[224:227], v[236:239], v[30:33]
	ds_read_b128 v[236:239], v245 offset:39232
	v_mfma_f32_16x16x32_bf16 v[10:13], v[224:227], v[240:243], v[10:13]
	ds_read_b128 v[240:243], v245 offset:41536
	v_mfma_f32_16x16x32_bf16 v[14:17], v[224:227], v[252:255], v[14:17]
	ds_read_b128 v[252:255], v245 offset:43840
	ds_read_b128 v[224:227], v244 offset:6976
	s_waitcnt lgkmcnt(4)
	v_mfma_f32_16x16x32_bf16 v[50:53], v[212:215], v[228:231], v[50:53]
	s_waitcnt lgkmcnt(3)
	v_mfma_f32_16x16x32_bf16 v[54:57], v[212:215], v[236:239], v[54:57]
	s_waitcnt lgkmcnt(2)
	v_mfma_f32_16x16x32_bf16 v[34:37], v[212:215], v[240:243], v[34:37]
	s_waitcnt lgkmcnt(1)
	v_mfma_f32_16x16x32_bf16 v[38:41], v[212:215], v[252:255], v[38:41]
	s_waitcnt vmcnt(11)
	ds_write_b128 v165, v[144:147] offset:55296
	s_waitcnt vmcnt(10)
	ds_write_b128 v165, v[148:151] offset:59904
	v_mfma_f32_16x16x32_bf16 v[58:61], v[216:219], v[228:231], v[58:61]
	v_mfma_f32_16x16x32_bf16 v[62:65], v[216:219], v[236:239], v[62:65]
	v_mfma_f32_16x16x32_bf16 v[42:45], v[216:219], v[240:243], v[42:45]
	v_mfma_f32_16x16x32_bf16 v[46:49], v[216:219], v[252:255], v[46:49]
	s_waitcnt vmcnt(9)
	ds_write_b128 v165, v[172:175] offset:64512
	s_waitcnt vmcnt(8)
	ds_write_b128 v166, v[176:179] offset:32256
	v_mfma_f32_16x16x32_bf16 v[18:21], v[220:223], v[228:231], v[18:21]
	v_mfma_f32_16x16x32_bf16 v[22:25], v[220:223], v[236:239], v[22:25]
	v_mfma_f32_16x16x32_bf16 v[2:5], v[220:223], v[240:243], v[2:5]
	v_mfma_f32_16x16x32_bf16 v[6:9], v[220:223], v[252:255], v[6:9]
	s_waitcnt lgkmcnt(4)
	v_mfma_f32_16x16x32_bf16 v[26:29], v[224:227], v[228:231], v[26:29]
	v_mfma_f32_16x16x32_bf16 v[30:33], v[224:227], v[236:239], v[30:33]
	v_mfma_f32_16x16x32_bf16 v[10:13], v[224:227], v[240:243], v[10:13]
	v_mfma_f32_16x16x32_bf16 v[14:17], v[224:227], v[252:255], v[14:17]
	s_waitcnt lgkmcnt(0)
	s_barrier
	s_setprio 0
	global_load_dwordx4 v[122:125], v[70:71], off offset:896
	global_load_dwordx4 v[126:129], v[68:69], off offset:896
	global_load_dwordx4 v[136:139], v[66:67], off offset:896
	global_load_dwordx4 v[140:143], v[72:73], off offset:896
	global_load_dwordx4 v[144:147], v[74:75], off offset:896
	global_load_dwordx4 v[148:151], v[76:77], off offset:896
	global_load_dwordx4 v[172:175], v[78:79], off offset:896
	global_load_dwordx4 v[176:179], v[80:81], off offset:896
	ds_read_b128 v[228:231], v245 offset:55296
	ds_read_b128 v[212:215], v244 offset:18432
	ds_read_b128 v[236:239], v245 offset:57600
	ds_read_b128 v[240:243], v245 offset:59904
	ds_read_b128 v[252:255], v245 offset:62208
	ds_read_b128 v[216:219], v244 offset:20736
	ds_read_b128 v[220:223], v244 offset:23040
	ds_read_b128 v[224:227], v244 offset:25344
	s_waitcnt lgkmcnt(6)
	v_mfma_f32_16x16x32_bf16 v[50:53], v[212:215], v[228:231], v[50:53]
	s_waitcnt lgkmcnt(5)
	v_mfma_f32_16x16x32_bf16 v[54:57], v[212:215], v[236:239], v[54:57]
	s_waitcnt lgkmcnt(4)
	v_mfma_f32_16x16x32_bf16 v[34:37], v[212:215], v[240:243], v[34:37]
	s_waitcnt lgkmcnt(3)
	v_mfma_f32_16x16x32_bf16 v[38:41], v[212:215], v[252:255], v[38:41]
	ds_read_b128 v[212:215], v244 offset:18496
	s_waitcnt lgkmcnt(3)
	v_mfma_f32_16x16x32_bf16 v[58:61], v[216:219], v[228:231], v[58:61]
	v_mfma_f32_16x16x32_bf16 v[62:65], v[216:219], v[236:239], v[62:65]
	v_mfma_f32_16x16x32_bf16 v[42:45], v[216:219], v[240:243], v[42:45]
	v_mfma_f32_16x16x32_bf16 v[46:49], v[216:219], v[252:255], v[46:49]
	ds_read_b128 v[216:219], v244 offset:20800
	s_setprio 1
	s_waitcnt vmcnt(15)
	ds_write_b128 v165, v[180:183]
	s_waitcnt vmcnt(14)
	ds_write_b128 v165, v[184:187] offset:4608
	s_waitcnt lgkmcnt(5)
	v_mfma_f32_16x16x32_bf16 v[18:21], v[220:223], v[228:231], v[18:21]
	v_mfma_f32_16x16x32_bf16 v[22:25], v[220:223], v[236:239], v[22:25]
	v_mfma_f32_16x16x32_bf16 v[2:5], v[220:223], v[240:243], v[2:5]
	v_mfma_f32_16x16x32_bf16 v[6:9], v[220:223], v[252:255], v[6:9]
	ds_read_b128 v[220:223], v244 offset:23104
	s_waitcnt vmcnt(13)
	ds_write_b128 v165, v[188:191] offset:9216
	s_waitcnt vmcnt(12)
	ds_write_b128 v165, v[192:195] offset:13824
	s_waitcnt lgkmcnt(7)
	v_mfma_f32_16x16x32_bf16 v[26:29], v[224:227], v[228:231], v[26:29]
	ds_read_b128 v[228:231], v245 offset:55360
	v_mfma_f32_16x16x32_bf16 v[30:33], v[224:227], v[236:239], v[30:33]
	ds_read_b128 v[236:239], v245 offset:57664
	v_mfma_f32_16x16x32_bf16 v[10:13], v[224:227], v[240:243], v[10:13]
	ds_read_b128 v[240:243], v245 offset:59968
	v_mfma_f32_16x16x32_bf16 v[14:17], v[224:227], v[252:255], v[14:17]
	ds_read_b128 v[252:255], v245 offset:62272
	ds_read_b128 v[224:227], v244 offset:25408
	s_waitcnt lgkmcnt(4)
	v_mfma_f32_16x16x32_bf16 v[50:53], v[212:215], v[228:231], v[50:53]
	s_waitcnt lgkmcnt(3)
	v_mfma_f32_16x16x32_bf16 v[54:57], v[212:215], v[236:239], v[54:57]
	s_waitcnt lgkmcnt(2)
	v_mfma_f32_16x16x32_bf16 v[34:37], v[212:215], v[240:243], v[34:37]
	s_waitcnt lgkmcnt(1)
	v_mfma_f32_16x16x32_bf16 v[38:41], v[212:215], v[252:255], v[38:41]
	s_waitcnt vmcnt(11)
	ds_write_b128 v165, v[196:199] offset:36864
	s_waitcnt vmcnt(10)
	ds_write_b128 v165, v[200:203] offset:41472
	v_mfma_f32_16x16x32_bf16 v[58:61], v[216:219], v[228:231], v[58:61]
	v_mfma_f32_16x16x32_bf16 v[62:65], v[216:219], v[236:239], v[62:65]
	v_mfma_f32_16x16x32_bf16 v[42:45], v[216:219], v[240:243], v[42:45]
	v_mfma_f32_16x16x32_bf16 v[46:49], v[216:219], v[252:255], v[46:49]
	s_waitcnt vmcnt(9)
	ds_write_b128 v165, v[204:207] offset:46080
	s_waitcnt vmcnt(8)
	ds_write_b128 v165, v[208:211] offset:50688
	v_mfma_f32_16x16x32_bf16 v[18:21], v[220:223], v[228:231], v[18:21]
	v_mfma_f32_16x16x32_bf16 v[22:25], v[220:223], v[236:239], v[22:25]
	v_mfma_f32_16x16x32_bf16 v[2:5], v[220:223], v[240:243], v[2:5]
	v_mfma_f32_16x16x32_bf16 v[6:9], v[220:223], v[252:255], v[6:9]
	s_waitcnt lgkmcnt(4)
	v_mfma_f32_16x16x32_bf16 v[26:29], v[224:227], v[228:231], v[26:29]
	v_mfma_f32_16x16x32_bf16 v[30:33], v[224:227], v[236:239], v[30:33]
	v_mfma_f32_16x16x32_bf16 v[10:13], v[224:227], v[240:243], v[10:13]
	v_mfma_f32_16x16x32_bf16 v[14:17], v[224:227], v[252:255], v[14:17]
	s_waitcnt lgkmcnt(0)
	s_barrier
	s_setprio 0
	global_load_dwordx4 v[180:183], v[70:71], off offset:1024
	global_load_dwordx4 v[184:187], v[68:69], off offset:1024
	global_load_dwordx4 v[188:191], v[66:67], off offset:1024
	global_load_dwordx4 v[192:195], v[72:73], off offset:1024
	global_load_dwordx4 v[196:199], v[74:75], off offset:1024
	global_load_dwordx4 v[200:203], v[76:77], off offset:1024
	global_load_dwordx4 v[204:207], v[78:79], off offset:1024
	global_load_dwordx4 v[208:211], v[80:81], off offset:1024
	ds_read_b128 v[228:231], v245 offset:36864
	ds_read_b128 v[212:215], v244
	ds_read_b128 v[236:239], v245 offset:39168
	ds_read_b128 v[240:243], v245 offset:41472
	ds_read_b128 v[252:255], v245 offset:43776
	ds_read_b128 v[216:219], v244 offset:2304
	ds_read_b128 v[220:223], v244 offset:4608
	ds_read_b128 v[224:227], v244 offset:6912
	s_waitcnt lgkmcnt(6)
	v_mfma_f32_16x16x32_bf16 v[50:53], v[212:215], v[228:231], v[50:53]
	s_waitcnt lgkmcnt(5)
	v_mfma_f32_16x16x32_bf16 v[54:57], v[212:215], v[236:239], v[54:57]
	s_waitcnt lgkmcnt(4)
	v_mfma_f32_16x16x32_bf16 v[34:37], v[212:215], v[240:243], v[34:37]
	s_waitcnt lgkmcnt(3)
	v_mfma_f32_16x16x32_bf16 v[38:41], v[212:215], v[252:255], v[38:41]
	ds_read_b128 v[212:215], v244 offset:64
	s_waitcnt lgkmcnt(3)
	v_mfma_f32_16x16x32_bf16 v[58:61], v[216:219], v[228:231], v[58:61]
	v_mfma_f32_16x16x32_bf16 v[62:65], v[216:219], v[236:239], v[62:65]
	v_mfma_f32_16x16x32_bf16 v[42:45], v[216:219], v[240:243], v[42:45]
	v_mfma_f32_16x16x32_bf16 v[46:49], v[216:219], v[252:255], v[46:49]
	ds_read_b128 v[216:219], v244 offset:2368
	s_setprio 1
	s_waitcnt vmcnt(15)
	ds_write_b128 v165, v[122:125] offset:18432
	s_waitcnt vmcnt(14)
	ds_write_b128 v165, v[126:129] offset:23040
	s_waitcnt lgkmcnt(5)
	v_mfma_f32_16x16x32_bf16 v[18:21], v[220:223], v[228:231], v[18:21]
	v_mfma_f32_16x16x32_bf16 v[22:25], v[220:223], v[236:239], v[22:25]
	v_mfma_f32_16x16x32_bf16 v[2:5], v[220:223], v[240:243], v[2:5]
	v_mfma_f32_16x16x32_bf16 v[6:9], v[220:223], v[252:255], v[6:9]
	ds_read_b128 v[220:223], v244 offset:4672
	s_waitcnt vmcnt(13)
	ds_write_b128 v165, v[136:139] offset:27648
	s_waitcnt vmcnt(12)
	ds_write_b128 v165, v[140:143] offset:32256
	s_waitcnt lgkmcnt(7)
	v_mfma_f32_16x16x32_bf16 v[26:29], v[224:227], v[228:231], v[26:29]
	ds_read_b128 v[228:231], v245 offset:36928
	v_mfma_f32_16x16x32_bf16 v[30:33], v[224:227], v[236:239], v[30:33]
	ds_read_b128 v[236:239], v245 offset:39232
	v_mfma_f32_16x16x32_bf16 v[10:13], v[224:227], v[240:243], v[10:13]
	ds_read_b128 v[240:243], v245 offset:41536
	v_mfma_f32_16x16x32_bf16 v[14:17], v[224:227], v[252:255], v[14:17]
	ds_read_b128 v[252:255], v245 offset:43840
	ds_read_b128 v[224:227], v244 offset:6976
	s_waitcnt lgkmcnt(4)
	v_mfma_f32_16x16x32_bf16 v[50:53], v[212:215], v[228:231], v[50:53]
	s_waitcnt lgkmcnt(3)
	v_mfma_f32_16x16x32_bf16 v[54:57], v[212:215], v[236:239], v[54:57]
	s_waitcnt lgkmcnt(2)
	v_mfma_f32_16x16x32_bf16 v[34:37], v[212:215], v[240:243], v[34:37]
	s_waitcnt lgkmcnt(1)
	v_mfma_f32_16x16x32_bf16 v[38:41], v[212:215], v[252:255], v[38:41]
	s_waitcnt vmcnt(11)
	ds_write_b128 v165, v[144:147] offset:55296
	s_waitcnt vmcnt(10)
	ds_write_b128 v165, v[148:151] offset:59904
	v_mfma_f32_16x16x32_bf16 v[58:61], v[216:219], v[228:231], v[58:61]
	v_mfma_f32_16x16x32_bf16 v[62:65], v[216:219], v[236:239], v[62:65]
	v_mfma_f32_16x16x32_bf16 v[42:45], v[216:219], v[240:243], v[42:45]
	v_mfma_f32_16x16x32_bf16 v[46:49], v[216:219], v[252:255], v[46:49]
	s_waitcnt vmcnt(9)
	ds_write_b128 v165, v[172:175] offset:64512
	s_waitcnt vmcnt(8)
	ds_write_b128 v166, v[176:179] offset:32256
	v_mfma_f32_16x16x32_bf16 v[18:21], v[220:223], v[228:231], v[18:21]
	v_mfma_f32_16x16x32_bf16 v[22:25], v[220:223], v[236:239], v[22:25]
	v_mfma_f32_16x16x32_bf16 v[2:5], v[220:223], v[240:243], v[2:5]
	v_mfma_f32_16x16x32_bf16 v[6:9], v[220:223], v[252:255], v[6:9]
	s_waitcnt lgkmcnt(4)
	v_mfma_f32_16x16x32_bf16 v[26:29], v[224:227], v[228:231], v[26:29]
	v_mfma_f32_16x16x32_bf16 v[30:33], v[224:227], v[236:239], v[30:33]
	v_mfma_f32_16x16x32_bf16 v[10:13], v[224:227], v[240:243], v[10:13]
	v_mfma_f32_16x16x32_bf16 v[14:17], v[224:227], v[252:255], v[14:17]
	s_waitcnt lgkmcnt(0)
	s_barrier
	s_setprio 0
	global_load_dwordx4 v[122:125], v[70:71], off offset:1152
	global_load_dwordx4 v[126:129], v[68:69], off offset:1152
	global_load_dwordx4 v[136:139], v[66:67], off offset:1152
	global_load_dwordx4 v[140:143], v[72:73], off offset:1152
	global_load_dwordx4 v[144:147], v[74:75], off offset:1152
	global_load_dwordx4 v[148:151], v[76:77], off offset:1152
	global_load_dwordx4 v[172:175], v[78:79], off offset:1152
	global_load_dwordx4 v[176:179], v[80:81], off offset:1152
	ds_read_b128 v[228:231], v245 offset:55296
	ds_read_b128 v[212:215], v244 offset:18432
	ds_read_b128 v[236:239], v245 offset:57600
	ds_read_b128 v[240:243], v245 offset:59904
	ds_read_b128 v[252:255], v245 offset:62208
	ds_read_b128 v[216:219], v244 offset:20736
	ds_read_b128 v[220:223], v244 offset:23040
	ds_read_b128 v[224:227], v244 offset:25344
	s_waitcnt lgkmcnt(6)
	v_mfma_f32_16x16x32_bf16 v[50:53], v[212:215], v[228:231], v[50:53]
	s_waitcnt lgkmcnt(5)
	v_mfma_f32_16x16x32_bf16 v[54:57], v[212:215], v[236:239], v[54:57]
	s_waitcnt lgkmcnt(4)
	v_mfma_f32_16x16x32_bf16 v[34:37], v[212:215], v[240:243], v[34:37]
	s_waitcnt lgkmcnt(3)
	v_mfma_f32_16x16x32_bf16 v[38:41], v[212:215], v[252:255], v[38:41]
	ds_read_b128 v[212:215], v244 offset:18496
	s_waitcnt lgkmcnt(3)
	v_mfma_f32_16x16x32_bf16 v[58:61], v[216:219], v[228:231], v[58:61]
	v_mfma_f32_16x16x32_bf16 v[62:65], v[216:219], v[236:239], v[62:65]
	v_mfma_f32_16x16x32_bf16 v[42:45], v[216:219], v[240:243], v[42:45]
	v_mfma_f32_16x16x32_bf16 v[46:49], v[216:219], v[252:255], v[46:49]
	ds_read_b128 v[216:219], v244 offset:20800
	s_setprio 1
	s_waitcnt vmcnt(15)
	ds_write_b128 v165, v[180:183]
	s_waitcnt vmcnt(14)
	ds_write_b128 v165, v[184:187] offset:4608
	s_waitcnt lgkmcnt(5)
	v_mfma_f32_16x16x32_bf16 v[18:21], v[220:223], v[228:231], v[18:21]
	v_mfma_f32_16x16x32_bf16 v[22:25], v[220:223], v[236:239], v[22:25]
	v_mfma_f32_16x16x32_bf16 v[2:5], v[220:223], v[240:243], v[2:5]
	v_mfma_f32_16x16x32_bf16 v[6:9], v[220:223], v[252:255], v[6:9]
	ds_read_b128 v[220:223], v244 offset:23104
	s_waitcnt vmcnt(13)
	ds_write_b128 v165, v[188:191] offset:9216
	s_waitcnt vmcnt(12)
	ds_write_b128 v165, v[192:195] offset:13824
	s_waitcnt lgkmcnt(7)
	v_mfma_f32_16x16x32_bf16 v[26:29], v[224:227], v[228:231], v[26:29]
	ds_read_b128 v[228:231], v245 offset:55360
	v_mfma_f32_16x16x32_bf16 v[30:33], v[224:227], v[236:239], v[30:33]
	ds_read_b128 v[236:239], v245 offset:57664
	v_mfma_f32_16x16x32_bf16 v[10:13], v[224:227], v[240:243], v[10:13]
	ds_read_b128 v[240:243], v245 offset:59968
	v_mfma_f32_16x16x32_bf16 v[14:17], v[224:227], v[252:255], v[14:17]
	ds_read_b128 v[252:255], v245 offset:62272
	ds_read_b128 v[224:227], v244 offset:25408
	s_waitcnt lgkmcnt(4)
	v_mfma_f32_16x16x32_bf16 v[50:53], v[212:215], v[228:231], v[50:53]
	s_waitcnt lgkmcnt(3)
	v_mfma_f32_16x16x32_bf16 v[54:57], v[212:215], v[236:239], v[54:57]
	s_waitcnt lgkmcnt(2)
	v_mfma_f32_16x16x32_bf16 v[34:37], v[212:215], v[240:243], v[34:37]
	s_waitcnt lgkmcnt(1)
	v_mfma_f32_16x16x32_bf16 v[38:41], v[212:215], v[252:255], v[38:41]
	s_waitcnt vmcnt(11)
	ds_write_b128 v165, v[196:199] offset:36864
	s_waitcnt vmcnt(10)
	ds_write_b128 v165, v[200:203] offset:41472
	v_mfma_f32_16x16x32_bf16 v[58:61], v[216:219], v[228:231], v[58:61]
	v_mfma_f32_16x16x32_bf16 v[62:65], v[216:219], v[236:239], v[62:65]
	v_mfma_f32_16x16x32_bf16 v[42:45], v[216:219], v[240:243], v[42:45]
	v_mfma_f32_16x16x32_bf16 v[46:49], v[216:219], v[252:255], v[46:49]
	s_waitcnt vmcnt(9)
	ds_write_b128 v165, v[204:207] offset:46080
	s_waitcnt vmcnt(8)
	ds_write_b128 v165, v[208:211] offset:50688
	v_mfma_f32_16x16x32_bf16 v[18:21], v[220:223], v[228:231], v[18:21]
	v_mfma_f32_16x16x32_bf16 v[22:25], v[220:223], v[236:239], v[22:25]
	v_mfma_f32_16x16x32_bf16 v[2:5], v[220:223], v[240:243], v[2:5]
	v_mfma_f32_16x16x32_bf16 v[6:9], v[220:223], v[252:255], v[6:9]
	s_waitcnt lgkmcnt(4)
	v_mfma_f32_16x16x32_bf16 v[26:29], v[224:227], v[228:231], v[26:29]
	v_mfma_f32_16x16x32_bf16 v[30:33], v[224:227], v[236:239], v[30:33]
	v_mfma_f32_16x16x32_bf16 v[10:13], v[224:227], v[240:243], v[10:13]
	v_mfma_f32_16x16x32_bf16 v[14:17], v[224:227], v[252:255], v[14:17]
	s_waitcnt lgkmcnt(0)
	s_barrier
	s_setprio 0
	global_load_dwordx4 v[180:183], v[70:71], off offset:1280
	global_load_dwordx4 v[184:187], v[68:69], off offset:1280
	global_load_dwordx4 v[188:191], v[66:67], off offset:1280
	global_load_dwordx4 v[192:195], v[72:73], off offset:1280
	global_load_dwordx4 v[196:199], v[74:75], off offset:1280
	global_load_dwordx4 v[200:203], v[76:77], off offset:1280
	global_load_dwordx4 v[204:207], v[78:79], off offset:1280
	global_load_dwordx4 v[208:211], v[80:81], off offset:1280
	ds_read_b128 v[228:231], v245 offset:36864
	ds_read_b128 v[212:215], v244
	ds_read_b128 v[236:239], v245 offset:39168
	ds_read_b128 v[240:243], v245 offset:41472
	ds_read_b128 v[252:255], v245 offset:43776
	ds_read_b128 v[216:219], v244 offset:2304
	ds_read_b128 v[220:223], v244 offset:4608
	ds_read_b128 v[224:227], v244 offset:6912
	s_waitcnt lgkmcnt(6)
	v_mfma_f32_16x16x32_bf16 v[50:53], v[212:215], v[228:231], v[50:53]
	s_waitcnt lgkmcnt(5)
	v_mfma_f32_16x16x32_bf16 v[54:57], v[212:215], v[236:239], v[54:57]
	s_waitcnt lgkmcnt(4)
	v_mfma_f32_16x16x32_bf16 v[34:37], v[212:215], v[240:243], v[34:37]
	s_waitcnt lgkmcnt(3)
	v_mfma_f32_16x16x32_bf16 v[38:41], v[212:215], v[252:255], v[38:41]
	ds_read_b128 v[212:215], v244 offset:64
	s_waitcnt lgkmcnt(3)
	v_mfma_f32_16x16x32_bf16 v[58:61], v[216:219], v[228:231], v[58:61]
	v_mfma_f32_16x16x32_bf16 v[62:65], v[216:219], v[236:239], v[62:65]
	v_mfma_f32_16x16x32_bf16 v[42:45], v[216:219], v[240:243], v[42:45]
	v_mfma_f32_16x16x32_bf16 v[46:49], v[216:219], v[252:255], v[46:49]
	ds_read_b128 v[216:219], v244 offset:2368
	s_setprio 1
	s_waitcnt vmcnt(15)
	ds_write_b128 v165, v[122:125] offset:18432
	s_waitcnt vmcnt(14)
	ds_write_b128 v165, v[126:129] offset:23040
	s_waitcnt lgkmcnt(5)
	v_mfma_f32_16x16x32_bf16 v[18:21], v[220:223], v[228:231], v[18:21]
	v_mfma_f32_16x16x32_bf16 v[22:25], v[220:223], v[236:239], v[22:25]
	v_mfma_f32_16x16x32_bf16 v[2:5], v[220:223], v[240:243], v[2:5]
	v_mfma_f32_16x16x32_bf16 v[6:9], v[220:223], v[252:255], v[6:9]
	ds_read_b128 v[220:223], v244 offset:4672
	s_waitcnt vmcnt(13)
	ds_write_b128 v165, v[136:139] offset:27648
	s_waitcnt vmcnt(12)
	ds_write_b128 v165, v[140:143] offset:32256
	s_waitcnt lgkmcnt(7)
	v_mfma_f32_16x16x32_bf16 v[26:29], v[224:227], v[228:231], v[26:29]
	ds_read_b128 v[228:231], v245 offset:36928
	v_mfma_f32_16x16x32_bf16 v[30:33], v[224:227], v[236:239], v[30:33]
	ds_read_b128 v[236:239], v245 offset:39232
	v_mfma_f32_16x16x32_bf16 v[10:13], v[224:227], v[240:243], v[10:13]
	ds_read_b128 v[240:243], v245 offset:41536
	v_mfma_f32_16x16x32_bf16 v[14:17], v[224:227], v[252:255], v[14:17]
	ds_read_b128 v[252:255], v245 offset:43840
	ds_read_b128 v[224:227], v244 offset:6976
	s_waitcnt lgkmcnt(4)
	v_mfma_f32_16x16x32_bf16 v[50:53], v[212:215], v[228:231], v[50:53]
	s_waitcnt lgkmcnt(3)
	v_mfma_f32_16x16x32_bf16 v[54:57], v[212:215], v[236:239], v[54:57]
	s_waitcnt lgkmcnt(2)
	v_mfma_f32_16x16x32_bf16 v[34:37], v[212:215], v[240:243], v[34:37]
	s_waitcnt lgkmcnt(1)
	v_mfma_f32_16x16x32_bf16 v[38:41], v[212:215], v[252:255], v[38:41]
	s_waitcnt vmcnt(11)
	ds_write_b128 v165, v[144:147] offset:55296
	s_waitcnt vmcnt(10)
	ds_write_b128 v165, v[148:151] offset:59904
	v_mfma_f32_16x16x32_bf16 v[58:61], v[216:219], v[228:231], v[58:61]
	v_mfma_f32_16x16x32_bf16 v[62:65], v[216:219], v[236:239], v[62:65]
	v_mfma_f32_16x16x32_bf16 v[42:45], v[216:219], v[240:243], v[42:45]
	v_mfma_f32_16x16x32_bf16 v[46:49], v[216:219], v[252:255], v[46:49]
	s_waitcnt vmcnt(9)
	ds_write_b128 v165, v[172:175] offset:64512
	s_waitcnt vmcnt(8)
	ds_write_b128 v166, v[176:179] offset:32256
	v_mfma_f32_16x16x32_bf16 v[18:21], v[220:223], v[228:231], v[18:21]
	v_mfma_f32_16x16x32_bf16 v[22:25], v[220:223], v[236:239], v[22:25]
	v_mfma_f32_16x16x32_bf16 v[2:5], v[220:223], v[240:243], v[2:5]
	v_mfma_f32_16x16x32_bf16 v[6:9], v[220:223], v[252:255], v[6:9]
	s_waitcnt lgkmcnt(4)
	v_mfma_f32_16x16x32_bf16 v[26:29], v[224:227], v[228:231], v[26:29]
	v_mfma_f32_16x16x32_bf16 v[30:33], v[224:227], v[236:239], v[30:33]
	v_mfma_f32_16x16x32_bf16 v[10:13], v[224:227], v[240:243], v[10:13]
	v_mfma_f32_16x16x32_bf16 v[14:17], v[224:227], v[252:255], v[14:17]
	s_waitcnt lgkmcnt(0)
	s_barrier
	s_setprio 0
	global_load_dwordx4 v[122:125], v[70:71], off offset:1408
	global_load_dwordx4 v[126:129], v[68:69], off offset:1408
	global_load_dwordx4 v[136:139], v[66:67], off offset:1408
	global_load_dwordx4 v[140:143], v[72:73], off offset:1408
	global_load_dwordx4 v[144:147], v[74:75], off offset:1408
	global_load_dwordx4 v[148:151], v[76:77], off offset:1408
	global_load_dwordx4 v[172:175], v[78:79], off offset:1408
	global_load_dwordx4 v[176:179], v[80:81], off offset:1408
	ds_read_b128 v[228:231], v245 offset:55296
	ds_read_b128 v[212:215], v244 offset:18432
	ds_read_b128 v[236:239], v245 offset:57600
	ds_read_b128 v[240:243], v245 offset:59904
	ds_read_b128 v[252:255], v245 offset:62208
	ds_read_b128 v[216:219], v244 offset:20736
	ds_read_b128 v[220:223], v244 offset:23040
	ds_read_b128 v[224:227], v244 offset:25344
	s_waitcnt lgkmcnt(6)
	v_mfma_f32_16x16x32_bf16 v[50:53], v[212:215], v[228:231], v[50:53]
	s_waitcnt lgkmcnt(5)
	v_mfma_f32_16x16x32_bf16 v[54:57], v[212:215], v[236:239], v[54:57]
	s_waitcnt lgkmcnt(4)
	v_mfma_f32_16x16x32_bf16 v[34:37], v[212:215], v[240:243], v[34:37]
	s_waitcnt lgkmcnt(3)
	v_mfma_f32_16x16x32_bf16 v[38:41], v[212:215], v[252:255], v[38:41]
	ds_read_b128 v[212:215], v244 offset:18496
	s_waitcnt lgkmcnt(3)
	v_mfma_f32_16x16x32_bf16 v[58:61], v[216:219], v[228:231], v[58:61]
	v_mfma_f32_16x16x32_bf16 v[62:65], v[216:219], v[236:239], v[62:65]
	v_mfma_f32_16x16x32_bf16 v[42:45], v[216:219], v[240:243], v[42:45]
	v_mfma_f32_16x16x32_bf16 v[46:49], v[216:219], v[252:255], v[46:49]
	ds_read_b128 v[216:219], v244 offset:20800
	s_setprio 1
	s_waitcnt vmcnt(15)
	ds_write_b128 v165, v[180:183]
	s_waitcnt vmcnt(14)
	ds_write_b128 v165, v[184:187] offset:4608
	s_waitcnt lgkmcnt(5)
	v_mfma_f32_16x16x32_bf16 v[18:21], v[220:223], v[228:231], v[18:21]
	v_mfma_f32_16x16x32_bf16 v[22:25], v[220:223], v[236:239], v[22:25]
	v_mfma_f32_16x16x32_bf16 v[2:5], v[220:223], v[240:243], v[2:5]
	v_mfma_f32_16x16x32_bf16 v[6:9], v[220:223], v[252:255], v[6:9]
	ds_read_b128 v[220:223], v244 offset:23104
	s_waitcnt vmcnt(13)
	ds_write_b128 v165, v[188:191] offset:9216
	s_waitcnt vmcnt(12)
	ds_write_b128 v165, v[192:195] offset:13824
	s_waitcnt lgkmcnt(7)
	v_mfma_f32_16x16x32_bf16 v[26:29], v[224:227], v[228:231], v[26:29]
	ds_read_b128 v[228:231], v245 offset:55360
	v_mfma_f32_16x16x32_bf16 v[30:33], v[224:227], v[236:239], v[30:33]
	ds_read_b128 v[236:239], v245 offset:57664
	v_mfma_f32_16x16x32_bf16 v[10:13], v[224:227], v[240:243], v[10:13]
	ds_read_b128 v[240:243], v245 offset:59968
	v_mfma_f32_16x16x32_bf16 v[14:17], v[224:227], v[252:255], v[14:17]
	ds_read_b128 v[252:255], v245 offset:62272
	ds_read_b128 v[224:227], v244 offset:25408
	s_waitcnt lgkmcnt(4)
	v_mfma_f32_16x16x32_bf16 v[50:53], v[212:215], v[228:231], v[50:53]
	s_waitcnt lgkmcnt(3)
	v_mfma_f32_16x16x32_bf16 v[54:57], v[212:215], v[236:239], v[54:57]
	s_waitcnt lgkmcnt(2)
	v_mfma_f32_16x16x32_bf16 v[34:37], v[212:215], v[240:243], v[34:37]
	s_waitcnt lgkmcnt(1)
	v_mfma_f32_16x16x32_bf16 v[38:41], v[212:215], v[252:255], v[38:41]
	s_waitcnt vmcnt(11)
	ds_write_b128 v165, v[196:199] offset:36864
	s_waitcnt vmcnt(10)
	ds_write_b128 v165, v[200:203] offset:41472
	v_mfma_f32_16x16x32_bf16 v[58:61], v[216:219], v[228:231], v[58:61]
	v_mfma_f32_16x16x32_bf16 v[62:65], v[216:219], v[236:239], v[62:65]
	v_mfma_f32_16x16x32_bf16 v[42:45], v[216:219], v[240:243], v[42:45]
	v_mfma_f32_16x16x32_bf16 v[46:49], v[216:219], v[252:255], v[46:49]
	s_waitcnt vmcnt(9)
	ds_write_b128 v165, v[204:207] offset:46080
	s_waitcnt vmcnt(8)
	ds_write_b128 v165, v[208:211] offset:50688
	v_mfma_f32_16x16x32_bf16 v[18:21], v[220:223], v[228:231], v[18:21]
	v_mfma_f32_16x16x32_bf16 v[22:25], v[220:223], v[236:239], v[22:25]
	v_mfma_f32_16x16x32_bf16 v[2:5], v[220:223], v[240:243], v[2:5]
	v_mfma_f32_16x16x32_bf16 v[6:9], v[220:223], v[252:255], v[6:9]
	s_waitcnt lgkmcnt(4)
	v_mfma_f32_16x16x32_bf16 v[26:29], v[224:227], v[228:231], v[26:29]
	v_mfma_f32_16x16x32_bf16 v[30:33], v[224:227], v[236:239], v[30:33]
	v_mfma_f32_16x16x32_bf16 v[10:13], v[224:227], v[240:243], v[10:13]
	v_mfma_f32_16x16x32_bf16 v[14:17], v[224:227], v[252:255], v[14:17]
	s_waitcnt lgkmcnt(0)
	s_barrier
	s_setprio 0
	global_load_dwordx4 v[180:183], v[70:71], off offset:1536
	global_load_dwordx4 v[184:187], v[68:69], off offset:1536
	global_load_dwordx4 v[188:191], v[66:67], off offset:1536
	global_load_dwordx4 v[192:195], v[72:73], off offset:1536
	global_load_dwordx4 v[196:199], v[74:75], off offset:1536
	global_load_dwordx4 v[200:203], v[76:77], off offset:1536
	global_load_dwordx4 v[204:207], v[78:79], off offset:1536
	global_load_dwordx4 v[208:211], v[80:81], off offset:1536
	ds_read_b128 v[228:231], v245 offset:36864
	ds_read_b128 v[212:215], v244
	ds_read_b128 v[236:239], v245 offset:39168
	ds_read_b128 v[240:243], v245 offset:41472
	ds_read_b128 v[252:255], v245 offset:43776
	ds_read_b128 v[216:219], v244 offset:2304
	ds_read_b128 v[220:223], v244 offset:4608
	ds_read_b128 v[224:227], v244 offset:6912
	s_waitcnt lgkmcnt(6)
	v_mfma_f32_16x16x32_bf16 v[50:53], v[212:215], v[228:231], v[50:53]
	s_waitcnt lgkmcnt(5)
	v_mfma_f32_16x16x32_bf16 v[54:57], v[212:215], v[236:239], v[54:57]
	s_waitcnt lgkmcnt(4)
	v_mfma_f32_16x16x32_bf16 v[34:37], v[212:215], v[240:243], v[34:37]
	s_waitcnt lgkmcnt(3)
	v_mfma_f32_16x16x32_bf16 v[38:41], v[212:215], v[252:255], v[38:41]
	ds_read_b128 v[212:215], v244 offset:64
	s_waitcnt lgkmcnt(3)
	v_mfma_f32_16x16x32_bf16 v[58:61], v[216:219], v[228:231], v[58:61]
	v_mfma_f32_16x16x32_bf16 v[62:65], v[216:219], v[236:239], v[62:65]
	v_mfma_f32_16x16x32_bf16 v[42:45], v[216:219], v[240:243], v[42:45]
	v_mfma_f32_16x16x32_bf16 v[46:49], v[216:219], v[252:255], v[46:49]
	ds_read_b128 v[216:219], v244 offset:2368
	s_setprio 1
	s_waitcnt vmcnt(15)
	ds_write_b128 v165, v[122:125] offset:18432
	s_waitcnt vmcnt(14)
	ds_write_b128 v165, v[126:129] offset:23040
	s_waitcnt lgkmcnt(5)
	v_mfma_f32_16x16x32_bf16 v[18:21], v[220:223], v[228:231], v[18:21]
	v_mfma_f32_16x16x32_bf16 v[22:25], v[220:223], v[236:239], v[22:25]
	v_mfma_f32_16x16x32_bf16 v[2:5], v[220:223], v[240:243], v[2:5]
	v_mfma_f32_16x16x32_bf16 v[6:9], v[220:223], v[252:255], v[6:9]
	ds_read_b128 v[220:223], v244 offset:4672
	s_waitcnt vmcnt(13)
	ds_write_b128 v165, v[136:139] offset:27648
	s_waitcnt vmcnt(12)
	ds_write_b128 v165, v[140:143] offset:32256
	s_waitcnt lgkmcnt(7)
	v_mfma_f32_16x16x32_bf16 v[26:29], v[224:227], v[228:231], v[26:29]
	ds_read_b128 v[228:231], v245 offset:36928
	v_mfma_f32_16x16x32_bf16 v[30:33], v[224:227], v[236:239], v[30:33]
	ds_read_b128 v[236:239], v245 offset:39232
	v_mfma_f32_16x16x32_bf16 v[10:13], v[224:227], v[240:243], v[10:13]
	ds_read_b128 v[240:243], v245 offset:41536
	v_mfma_f32_16x16x32_bf16 v[14:17], v[224:227], v[252:255], v[14:17]
	ds_read_b128 v[252:255], v245 offset:43840
	ds_read_b128 v[224:227], v244 offset:6976
	s_waitcnt lgkmcnt(4)
	v_mfma_f32_16x16x32_bf16 v[50:53], v[212:215], v[228:231], v[50:53]
	s_waitcnt lgkmcnt(3)
	v_mfma_f32_16x16x32_bf16 v[54:57], v[212:215], v[236:239], v[54:57]
	s_waitcnt lgkmcnt(2)
	v_mfma_f32_16x16x32_bf16 v[34:37], v[212:215], v[240:243], v[34:37]
	s_waitcnt lgkmcnt(1)
	v_mfma_f32_16x16x32_bf16 v[38:41], v[212:215], v[252:255], v[38:41]
	s_waitcnt vmcnt(11)
	ds_write_b128 v165, v[144:147] offset:55296
	s_waitcnt vmcnt(10)
	ds_write_b128 v165, v[148:151] offset:59904
	v_mfma_f32_16x16x32_bf16 v[58:61], v[216:219], v[228:231], v[58:61]
	v_mfma_f32_16x16x32_bf16 v[62:65], v[216:219], v[236:239], v[62:65]
	v_mfma_f32_16x16x32_bf16 v[42:45], v[216:219], v[240:243], v[42:45]
	v_mfma_f32_16x16x32_bf16 v[46:49], v[216:219], v[252:255], v[46:49]
	s_waitcnt vmcnt(9)
	ds_write_b128 v165, v[172:175] offset:64512
	s_waitcnt vmcnt(8)
	ds_write_b128 v166, v[176:179] offset:32256
	v_mfma_f32_16x16x32_bf16 v[18:21], v[220:223], v[228:231], v[18:21]
	v_mfma_f32_16x16x32_bf16 v[22:25], v[220:223], v[236:239], v[22:25]
	v_mfma_f32_16x16x32_bf16 v[2:5], v[220:223], v[240:243], v[2:5]
	v_mfma_f32_16x16x32_bf16 v[6:9], v[220:223], v[252:255], v[6:9]
	s_waitcnt lgkmcnt(4)
	v_mfma_f32_16x16x32_bf16 v[26:29], v[224:227], v[228:231], v[26:29]
	v_mfma_f32_16x16x32_bf16 v[30:33], v[224:227], v[236:239], v[30:33]
	v_mfma_f32_16x16x32_bf16 v[10:13], v[224:227], v[240:243], v[10:13]
	v_mfma_f32_16x16x32_bf16 v[14:17], v[224:227], v[252:255], v[14:17]
	s_waitcnt lgkmcnt(0)
	s_barrier
	s_setprio 0
	global_load_dwordx4 v[122:125], v[70:71], off offset:1664
	global_load_dwordx4 v[126:129], v[68:69], off offset:1664
	global_load_dwordx4 v[136:139], v[66:67], off offset:1664
	global_load_dwordx4 v[140:143], v[72:73], off offset:1664
	global_load_dwordx4 v[144:147], v[74:75], off offset:1664
	global_load_dwordx4 v[148:151], v[76:77], off offset:1664
	global_load_dwordx4 v[172:175], v[78:79], off offset:1664
	global_load_dwordx4 v[176:179], v[80:81], off offset:1664
	ds_read_b128 v[228:231], v245 offset:55296
	ds_read_b128 v[212:215], v244 offset:18432
	ds_read_b128 v[236:239], v245 offset:57600
	ds_read_b128 v[240:243], v245 offset:59904
	ds_read_b128 v[252:255], v245 offset:62208
	ds_read_b128 v[216:219], v244 offset:20736
	ds_read_b128 v[220:223], v244 offset:23040
	ds_read_b128 v[224:227], v244 offset:25344
	s_waitcnt lgkmcnt(6)
	v_mfma_f32_16x16x32_bf16 v[50:53], v[212:215], v[228:231], v[50:53]
	s_waitcnt lgkmcnt(5)
	v_mfma_f32_16x16x32_bf16 v[54:57], v[212:215], v[236:239], v[54:57]
	s_waitcnt lgkmcnt(4)
	v_mfma_f32_16x16x32_bf16 v[34:37], v[212:215], v[240:243], v[34:37]
	s_waitcnt lgkmcnt(3)
	v_mfma_f32_16x16x32_bf16 v[38:41], v[212:215], v[252:255], v[38:41]
	ds_read_b128 v[212:215], v244 offset:18496
	s_waitcnt lgkmcnt(3)
	v_mfma_f32_16x16x32_bf16 v[58:61], v[216:219], v[228:231], v[58:61]
	v_mfma_f32_16x16x32_bf16 v[62:65], v[216:219], v[236:239], v[62:65]
	v_mfma_f32_16x16x32_bf16 v[42:45], v[216:219], v[240:243], v[42:45]
	v_mfma_f32_16x16x32_bf16 v[46:49], v[216:219], v[252:255], v[46:49]
	ds_read_b128 v[216:219], v244 offset:20800
	s_setprio 1
	s_waitcnt vmcnt(15)
	ds_write_b128 v165, v[180:183]
	s_waitcnt vmcnt(14)
	ds_write_b128 v165, v[184:187] offset:4608
	s_waitcnt lgkmcnt(5)
	v_mfma_f32_16x16x32_bf16 v[18:21], v[220:223], v[228:231], v[18:21]
	v_mfma_f32_16x16x32_bf16 v[22:25], v[220:223], v[236:239], v[22:25]
	v_mfma_f32_16x16x32_bf16 v[2:5], v[220:223], v[240:243], v[2:5]
	v_mfma_f32_16x16x32_bf16 v[6:9], v[220:223], v[252:255], v[6:9]
	ds_read_b128 v[220:223], v244 offset:23104
	s_waitcnt vmcnt(13)
	ds_write_b128 v165, v[188:191] offset:9216
	s_waitcnt vmcnt(12)
	ds_write_b128 v165, v[192:195] offset:13824
	s_waitcnt lgkmcnt(7)
	v_mfma_f32_16x16x32_bf16 v[26:29], v[224:227], v[228:231], v[26:29]
	ds_read_b128 v[228:231], v245 offset:55360
	v_mfma_f32_16x16x32_bf16 v[30:33], v[224:227], v[236:239], v[30:33]
	ds_read_b128 v[236:239], v245 offset:57664
	v_mfma_f32_16x16x32_bf16 v[10:13], v[224:227], v[240:243], v[10:13]
	ds_read_b128 v[240:243], v245 offset:59968
	v_mfma_f32_16x16x32_bf16 v[14:17], v[224:227], v[252:255], v[14:17]
	ds_read_b128 v[252:255], v245 offset:62272
	ds_read_b128 v[224:227], v244 offset:25408
	s_waitcnt lgkmcnt(4)
	v_mfma_f32_16x16x32_bf16 v[50:53], v[212:215], v[228:231], v[50:53]
	s_waitcnt lgkmcnt(3)
	v_mfma_f32_16x16x32_bf16 v[54:57], v[212:215], v[236:239], v[54:57]
	s_waitcnt lgkmcnt(2)
	v_mfma_f32_16x16x32_bf16 v[34:37], v[212:215], v[240:243], v[34:37]
	s_waitcnt lgkmcnt(1)
	v_mfma_f32_16x16x32_bf16 v[38:41], v[212:215], v[252:255], v[38:41]
	s_waitcnt vmcnt(11)
	ds_write_b128 v165, v[196:199] offset:36864
	s_waitcnt vmcnt(10)
	ds_write_b128 v165, v[200:203] offset:41472
	v_mfma_f32_16x16x32_bf16 v[58:61], v[216:219], v[228:231], v[58:61]
	v_mfma_f32_16x16x32_bf16 v[62:65], v[216:219], v[236:239], v[62:65]
	v_mfma_f32_16x16x32_bf16 v[42:45], v[216:219], v[240:243], v[42:45]
	v_mfma_f32_16x16x32_bf16 v[46:49], v[216:219], v[252:255], v[46:49]
	s_waitcnt vmcnt(9)
	ds_write_b128 v165, v[204:207] offset:46080
	s_waitcnt vmcnt(8)
	ds_write_b128 v165, v[208:211] offset:50688
	v_mfma_f32_16x16x32_bf16 v[18:21], v[220:223], v[228:231], v[18:21]
	v_mfma_f32_16x16x32_bf16 v[22:25], v[220:223], v[236:239], v[22:25]
	v_mfma_f32_16x16x32_bf16 v[2:5], v[220:223], v[240:243], v[2:5]
	v_mfma_f32_16x16x32_bf16 v[6:9], v[220:223], v[252:255], v[6:9]
	s_waitcnt lgkmcnt(4)
	v_mfma_f32_16x16x32_bf16 v[26:29], v[224:227], v[228:231], v[26:29]
	v_mfma_f32_16x16x32_bf16 v[30:33], v[224:227], v[236:239], v[30:33]
	v_mfma_f32_16x16x32_bf16 v[10:13], v[224:227], v[240:243], v[10:13]
	v_mfma_f32_16x16x32_bf16 v[14:17], v[224:227], v[252:255], v[14:17]
	s_waitcnt lgkmcnt(0)
	s_barrier
	s_setprio 0
	global_load_dwordx4 v[180:183], v[70:71], off offset:1792
	global_load_dwordx4 v[184:187], v[68:69], off offset:1792
	global_load_dwordx4 v[188:191], v[66:67], off offset:1792
	global_load_dwordx4 v[192:195], v[72:73], off offset:1792
	global_load_dwordx4 v[196:199], v[74:75], off offset:1792
	global_load_dwordx4 v[200:203], v[76:77], off offset:1792
	global_load_dwordx4 v[204:207], v[78:79], off offset:1792
	global_load_dwordx4 v[208:211], v[80:81], off offset:1792
	ds_read_b128 v[228:231], v245 offset:36864
	ds_read_b128 v[212:215], v244
	ds_read_b128 v[236:239], v245 offset:39168
	ds_read_b128 v[240:243], v245 offset:41472
	ds_read_b128 v[252:255], v245 offset:43776
	ds_read_b128 v[216:219], v244 offset:2304
	ds_read_b128 v[220:223], v244 offset:4608
	ds_read_b128 v[224:227], v244 offset:6912
	s_waitcnt lgkmcnt(6)
	v_mfma_f32_16x16x32_bf16 v[50:53], v[212:215], v[228:231], v[50:53]
	s_waitcnt lgkmcnt(5)
	v_mfma_f32_16x16x32_bf16 v[54:57], v[212:215], v[236:239], v[54:57]
	s_waitcnt lgkmcnt(4)
	v_mfma_f32_16x16x32_bf16 v[34:37], v[212:215], v[240:243], v[34:37]
	s_waitcnt lgkmcnt(3)
	v_mfma_f32_16x16x32_bf16 v[38:41], v[212:215], v[252:255], v[38:41]
	ds_read_b128 v[212:215], v244 offset:64
	s_waitcnt lgkmcnt(3)
	v_mfma_f32_16x16x32_bf16 v[58:61], v[216:219], v[228:231], v[58:61]
	v_mfma_f32_16x16x32_bf16 v[62:65], v[216:219], v[236:239], v[62:65]
	v_mfma_f32_16x16x32_bf16 v[42:45], v[216:219], v[240:243], v[42:45]
	v_mfma_f32_16x16x32_bf16 v[46:49], v[216:219], v[252:255], v[46:49]
	ds_read_b128 v[216:219], v244 offset:2368
	s_setprio 1
	s_waitcnt vmcnt(15)
	ds_write_b128 v165, v[122:125] offset:18432
	s_waitcnt vmcnt(14)
	ds_write_b128 v165, v[126:129] offset:23040
	s_waitcnt lgkmcnt(5)
	v_mfma_f32_16x16x32_bf16 v[18:21], v[220:223], v[228:231], v[18:21]
	v_mfma_f32_16x16x32_bf16 v[22:25], v[220:223], v[236:239], v[22:25]
	v_mfma_f32_16x16x32_bf16 v[2:5], v[220:223], v[240:243], v[2:5]
	v_mfma_f32_16x16x32_bf16 v[6:9], v[220:223], v[252:255], v[6:9]
	ds_read_b128 v[220:223], v244 offset:4672
	s_waitcnt vmcnt(13)
	ds_write_b128 v165, v[136:139] offset:27648
	s_waitcnt vmcnt(12)
	ds_write_b128 v165, v[140:143] offset:32256
	s_waitcnt lgkmcnt(7)
	v_mfma_f32_16x16x32_bf16 v[26:29], v[224:227], v[228:231], v[26:29]
	ds_read_b128 v[228:231], v245 offset:36928
	v_mfma_f32_16x16x32_bf16 v[30:33], v[224:227], v[236:239], v[30:33]
	ds_read_b128 v[236:239], v245 offset:39232
	v_mfma_f32_16x16x32_bf16 v[10:13], v[224:227], v[240:243], v[10:13]
	ds_read_b128 v[240:243], v245 offset:41536
	v_mfma_f32_16x16x32_bf16 v[14:17], v[224:227], v[252:255], v[14:17]
	ds_read_b128 v[252:255], v245 offset:43840
	ds_read_b128 v[224:227], v244 offset:6976
	s_waitcnt lgkmcnt(4)
	v_mfma_f32_16x16x32_bf16 v[50:53], v[212:215], v[228:231], v[50:53]
	s_waitcnt lgkmcnt(3)
	v_mfma_f32_16x16x32_bf16 v[54:57], v[212:215], v[236:239], v[54:57]
	s_waitcnt lgkmcnt(2)
	v_mfma_f32_16x16x32_bf16 v[34:37], v[212:215], v[240:243], v[34:37]
	s_waitcnt lgkmcnt(1)
	v_mfma_f32_16x16x32_bf16 v[38:41], v[212:215], v[252:255], v[38:41]
	s_waitcnt vmcnt(11)
	ds_write_b128 v165, v[144:147] offset:55296
	s_waitcnt vmcnt(10)
	ds_write_b128 v165, v[148:151] offset:59904
	v_mfma_f32_16x16x32_bf16 v[58:61], v[216:219], v[228:231], v[58:61]
	v_mfma_f32_16x16x32_bf16 v[62:65], v[216:219], v[236:239], v[62:65]
	v_mfma_f32_16x16x32_bf16 v[42:45], v[216:219], v[240:243], v[42:45]
	v_mfma_f32_16x16x32_bf16 v[46:49], v[216:219], v[252:255], v[46:49]
	s_waitcnt vmcnt(9)
	ds_write_b128 v165, v[172:175] offset:64512
	s_waitcnt vmcnt(8)
	ds_write_b128 v166, v[176:179] offset:32256
	v_mfma_f32_16x16x32_bf16 v[18:21], v[220:223], v[228:231], v[18:21]
	v_mfma_f32_16x16x32_bf16 v[22:25], v[220:223], v[236:239], v[22:25]
	v_mfma_f32_16x16x32_bf16 v[2:5], v[220:223], v[240:243], v[2:5]
	v_mfma_f32_16x16x32_bf16 v[6:9], v[220:223], v[252:255], v[6:9]
	s_waitcnt lgkmcnt(4)
	v_mfma_f32_16x16x32_bf16 v[26:29], v[224:227], v[228:231], v[26:29]
	v_mfma_f32_16x16x32_bf16 v[30:33], v[224:227], v[236:239], v[30:33]
	v_mfma_f32_16x16x32_bf16 v[10:13], v[224:227], v[240:243], v[10:13]
	v_mfma_f32_16x16x32_bf16 v[14:17], v[224:227], v[252:255], v[14:17]
	s_waitcnt lgkmcnt(0)
	s_barrier
	s_setprio 0
	global_load_dwordx4 v[122:125], v[70:71], off offset:1920
	s_nop 0
	global_load_dwordx4 v[68:71], v[68:69], off offset:1920
	s_nop 0
	global_load_dwordx4 v[126:129], v[66:67], off offset:1920
	global_load_dwordx4 v[136:139], v[72:73], off offset:1920
	s_nop 0
	global_load_dwordx4 v[72:75], v[74:75], off offset:1920
	s_nop 0
	global_load_dwordx4 v[140:143], v[76:77], off offset:1920
	s_nop 0
	global_load_dwordx4 v[76:79], v[78:79], off offset:1920
	s_nop 0
	global_load_dwordx4 v[144:147], v[80:81], off offset:1920
	ds_read_b128 v[228:231], v245 offset:55296
	ds_read_b128 v[212:215], v244 offset:18432
	ds_read_b128 v[236:239], v245 offset:57600
	ds_read_b128 v[240:243], v245 offset:59904
	ds_read_b128 v[252:255], v245 offset:62208
	ds_read_b128 v[216:219], v244 offset:20736
	ds_read_b128 v[220:223], v244 offset:23040
	ds_read_b128 v[224:227], v244 offset:25344
	s_waitcnt lgkmcnt(6)
	v_mfma_f32_16x16x32_bf16 v[50:53], v[212:215], v[228:231], v[50:53]
	s_waitcnt lgkmcnt(5)
	v_mfma_f32_16x16x32_bf16 v[54:57], v[212:215], v[236:239], v[54:57]
	s_waitcnt lgkmcnt(4)
	v_mfma_f32_16x16x32_bf16 v[34:37], v[212:215], v[240:243], v[34:37]
	s_waitcnt lgkmcnt(3)
	v_mfma_f32_16x16x32_bf16 v[38:41], v[212:215], v[252:255], v[38:41]
	ds_read_b128 v[212:215], v244 offset:18496
	s_waitcnt lgkmcnt(3)
	v_mfma_f32_16x16x32_bf16 v[58:61], v[216:219], v[228:231], v[58:61]
	v_mfma_f32_16x16x32_bf16 v[62:65], v[216:219], v[236:239], v[62:65]
	v_mfma_f32_16x16x32_bf16 v[42:45], v[216:219], v[240:243], v[42:45]
	v_mfma_f32_16x16x32_bf16 v[46:49], v[216:219], v[252:255], v[46:49]
	ds_read_b128 v[216:219], v244 offset:20800
	s_setprio 1
	s_waitcnt vmcnt(15)
	ds_write_b128 v165, v[180:183]
	s_waitcnt vmcnt(14)
	ds_write_b128 v165, v[184:187] offset:4608
	s_waitcnt lgkmcnt(5)
	v_mfma_f32_16x16x32_bf16 v[18:21], v[220:223], v[228:231], v[18:21]
	v_mfma_f32_16x16x32_bf16 v[22:25], v[220:223], v[236:239], v[22:25]
	v_mfma_f32_16x16x32_bf16 v[2:5], v[220:223], v[240:243], v[2:5]
	v_mfma_f32_16x16x32_bf16 v[6:9], v[220:223], v[252:255], v[6:9]
	ds_read_b128 v[220:223], v244 offset:23104
	s_waitcnt vmcnt(13)
	ds_write_b128 v165, v[188:191] offset:9216
	s_waitcnt vmcnt(12)
	ds_write_b128 v165, v[192:195] offset:13824
	s_waitcnt lgkmcnt(7)
	v_mfma_f32_16x16x32_bf16 v[26:29], v[224:227], v[228:231], v[26:29]
	ds_read_b128 v[228:231], v245 offset:55360
	v_mfma_f32_16x16x32_bf16 v[30:33], v[224:227], v[236:239], v[30:33]
	ds_read_b128 v[236:239], v245 offset:57664
	v_mfma_f32_16x16x32_bf16 v[10:13], v[224:227], v[240:243], v[10:13]
	ds_read_b128 v[240:243], v245 offset:59968
	v_mfma_f32_16x16x32_bf16 v[14:17], v[224:227], v[252:255], v[14:17]
	ds_read_b128 v[252:255], v245 offset:62272
	ds_read_b128 v[224:227], v244 offset:25408
	s_waitcnt lgkmcnt(4)
	v_mfma_f32_16x16x32_bf16 v[50:53], v[212:215], v[228:231], v[50:53]
	s_waitcnt lgkmcnt(3)
	v_mfma_f32_16x16x32_bf16 v[54:57], v[212:215], v[236:239], v[54:57]
	s_waitcnt lgkmcnt(2)
	v_mfma_f32_16x16x32_bf16 v[34:37], v[212:215], v[240:243], v[34:37]
	s_waitcnt lgkmcnt(1)
	v_mfma_f32_16x16x32_bf16 v[38:41], v[212:215], v[252:255], v[38:41]
	s_waitcnt vmcnt(11)
	ds_write_b128 v165, v[196:199] offset:36864
	s_waitcnt vmcnt(10)
	ds_write_b128 v165, v[200:203] offset:41472
	v_mfma_f32_16x16x32_bf16 v[58:61], v[216:219], v[228:231], v[58:61]
	v_mfma_f32_16x16x32_bf16 v[62:65], v[216:219], v[236:239], v[62:65]
	v_mfma_f32_16x16x32_bf16 v[42:45], v[216:219], v[240:243], v[42:45]
	v_mfma_f32_16x16x32_bf16 v[46:49], v[216:219], v[252:255], v[46:49]
	s_waitcnt vmcnt(9)
	ds_write_b128 v165, v[204:207] offset:46080
	s_waitcnt vmcnt(8)
	ds_write_b128 v165, v[208:211] offset:50688
	v_mfma_f32_16x16x32_bf16 v[18:21], v[220:223], v[228:231], v[18:21]
	v_mfma_f32_16x16x32_bf16 v[22:25], v[220:223], v[236:239], v[22:25]
	v_mfma_f32_16x16x32_bf16 v[2:5], v[220:223], v[240:243], v[2:5]
	v_mfma_f32_16x16x32_bf16 v[6:9], v[220:223], v[252:255], v[6:9]
	s_waitcnt lgkmcnt(4)
	v_mfma_f32_16x16x32_bf16 v[26:29], v[224:227], v[228:231], v[26:29]
	v_mfma_f32_16x16x32_bf16 v[30:33], v[224:227], v[236:239], v[30:33]
	v_mfma_f32_16x16x32_bf16 v[10:13], v[224:227], v[240:243], v[10:13]
	v_mfma_f32_16x16x32_bf16 v[14:17], v[224:227], v[252:255], v[14:17]
	s_waitcnt lgkmcnt(0)
	s_barrier
	s_setprio 0
	ds_read_b128 v[228:231], v245 offset:36864
	ds_read_b128 v[212:215], v244
	ds_read_b128 v[236:239], v245 offset:39168
	ds_read_b128 v[240:243], v245 offset:41472
	ds_read_b128 v[252:255], v245 offset:43776
	ds_read_b128 v[216:219], v244 offset:2304
	ds_read_b128 v[220:223], v244 offset:4608
	ds_read_b128 v[224:227], v244 offset:6912
	s_waitcnt lgkmcnt(6)
	v_mfma_f32_16x16x32_bf16 v[50:53], v[212:215], v[228:231], v[50:53]
	s_waitcnt lgkmcnt(5)
	v_mfma_f32_16x16x32_bf16 v[54:57], v[212:215], v[236:239], v[54:57]
	s_waitcnt lgkmcnt(4)
	v_mfma_f32_16x16x32_bf16 v[34:37], v[212:215], v[240:243], v[34:37]
	s_waitcnt lgkmcnt(3)
	v_mfma_f32_16x16x32_bf16 v[38:41], v[212:215], v[252:255], v[38:41]
	ds_read_b128 v[212:215], v244 offset:64
	s_waitcnt lgkmcnt(3)
	v_mfma_f32_16x16x32_bf16 v[58:61], v[216:219], v[228:231], v[58:61]
	v_mfma_f32_16x16x32_bf16 v[62:65], v[216:219], v[236:239], v[62:65]
	v_mfma_f32_16x16x32_bf16 v[42:45], v[216:219], v[240:243], v[42:45]
	v_mfma_f32_16x16x32_bf16 v[46:49], v[216:219], v[252:255], v[46:49]
	ds_read_b128 v[216:219], v244 offset:2368
	s_setprio 1
	s_waitcnt vmcnt(7)
	ds_write_b128 v165, v[122:125] offset:18432
	s_waitcnt vmcnt(6)
	ds_write_b128 v165, v[68:71] offset:23040
	s_waitcnt lgkmcnt(5)
	v_mfma_f32_16x16x32_bf16 v[18:21], v[220:223], v[228:231], v[18:21]
	v_mfma_f32_16x16x32_bf16 v[22:25], v[220:223], v[236:239], v[22:25]
	v_mfma_f32_16x16x32_bf16 v[2:5], v[220:223], v[240:243], v[2:5]
	v_mfma_f32_16x16x32_bf16 v[6:9], v[220:223], v[252:255], v[6:9]
	ds_read_b128 v[220:223], v244 offset:4672
	s_waitcnt vmcnt(5)
	ds_write_b128 v165, v[126:129] offset:27648
	s_waitcnt vmcnt(4)
	ds_write_b128 v165, v[136:139] offset:32256
	s_waitcnt lgkmcnt(7)
	v_mfma_f32_16x16x32_bf16 v[26:29], v[224:227], v[228:231], v[26:29]
	ds_read_b128 v[228:231], v245 offset:36928
	v_mfma_f32_16x16x32_bf16 v[30:33], v[224:227], v[236:239], v[30:33]
	ds_read_b128 v[236:239], v245 offset:39232
	v_mfma_f32_16x16x32_bf16 v[10:13], v[224:227], v[240:243], v[10:13]
	ds_read_b128 v[240:243], v245 offset:41536
	v_mfma_f32_16x16x32_bf16 v[14:17], v[224:227], v[252:255], v[14:17]
	ds_read_b128 v[252:255], v245 offset:43840
	ds_read_b128 v[224:227], v244 offset:6976
	s_waitcnt lgkmcnt(4)
	v_mfma_f32_16x16x32_bf16 v[50:53], v[212:215], v[228:231], v[50:53]
	s_waitcnt lgkmcnt(3)
	v_mfma_f32_16x16x32_bf16 v[54:57], v[212:215], v[236:239], v[54:57]
	s_waitcnt lgkmcnt(2)
	v_mfma_f32_16x16x32_bf16 v[34:37], v[212:215], v[240:243], v[34:37]
	s_waitcnt lgkmcnt(1)
	v_mfma_f32_16x16x32_bf16 v[38:41], v[212:215], v[252:255], v[38:41]
	s_waitcnt vmcnt(3)
	ds_write_b128 v165, v[72:75] offset:55296
	s_waitcnt vmcnt(2)
	ds_write_b128 v165, v[140:143] offset:59904
	v_mfma_f32_16x16x32_bf16 v[58:61], v[216:219], v[228:231], v[58:61]
	v_mfma_f32_16x16x32_bf16 v[62:65], v[216:219], v[236:239], v[62:65]
	v_mfma_f32_16x16x32_bf16 v[42:45], v[216:219], v[240:243], v[42:45]
	v_mfma_f32_16x16x32_bf16 v[46:49], v[216:219], v[252:255], v[46:49]
	s_waitcnt vmcnt(1)
	ds_write_b128 v165, v[76:79] offset:64512
	s_waitcnt vmcnt(0)
	ds_write_b128 v166, v[144:147] offset:32256
	v_mfma_f32_16x16x32_bf16 v[18:21], v[220:223], v[228:231], v[18:21]
	v_mfma_f32_16x16x32_bf16 v[22:25], v[220:223], v[236:239], v[22:25]
	v_mfma_f32_16x16x32_bf16 v[2:5], v[220:223], v[240:243], v[2:5]
	v_mfma_f32_16x16x32_bf16 v[6:9], v[220:223], v[252:255], v[6:9]
	s_waitcnt lgkmcnt(4)
	v_mfma_f32_16x16x32_bf16 v[26:29], v[224:227], v[228:231], v[26:29]
	v_mfma_f32_16x16x32_bf16 v[30:33], v[224:227], v[236:239], v[30:33]
	v_mfma_f32_16x16x32_bf16 v[10:13], v[224:227], v[240:243], v[10:13]
	v_mfma_f32_16x16x32_bf16 v[14:17], v[224:227], v[252:255], v[14:17]
	s_waitcnt lgkmcnt(0)
	s_barrier
	s_setprio 0
	ds_read_b128 v[228:231], v245 offset:55296
	ds_read_b128 v[212:215], v244 offset:18432
	ds_read_b128 v[236:239], v245 offset:57600
	ds_read_b128 v[240:243], v245 offset:59904
	ds_read_b128 v[252:255], v245 offset:62208
	ds_read_b128 v[216:219], v244 offset:20736
	ds_read_b128 v[220:223], v244 offset:23040
	ds_read_b128 v[224:227], v244 offset:25344
	s_waitcnt lgkmcnt(6)
	v_mfma_f32_16x16x32_bf16 v[50:53], v[212:215], v[228:231], v[50:53]
	s_waitcnt lgkmcnt(5)
	v_mfma_f32_16x16x32_bf16 v[54:57], v[212:215], v[236:239], v[54:57]
	s_waitcnt lgkmcnt(4)
	v_mfma_f32_16x16x32_bf16 v[34:37], v[212:215], v[240:243], v[34:37]
	s_waitcnt lgkmcnt(3)
	v_mfma_f32_16x16x32_bf16 v[38:41], v[212:215], v[252:255], v[38:41]
	ds_read_b128 v[212:215], v244 offset:18496
	s_waitcnt lgkmcnt(3)
	v_mfma_f32_16x16x32_bf16 v[58:61], v[216:219], v[228:231], v[58:61]
	v_mfma_f32_16x16x32_bf16 v[62:65], v[216:219], v[236:239], v[62:65]
	v_mfma_f32_16x16x32_bf16 v[42:45], v[216:219], v[240:243], v[42:45]
	v_mfma_f32_16x16x32_bf16 v[46:49], v[216:219], v[252:255], v[46:49]
	ds_read_b128 v[216:219], v244 offset:20800
	s_waitcnt lgkmcnt(3)
	v_mfma_f32_16x16x32_bf16 v[18:21], v[220:223], v[228:231], v[18:21]
	v_mfma_f32_16x16x32_bf16 v[22:25], v[220:223], v[236:239], v[22:25]
	v_mfma_f32_16x16x32_bf16 v[2:5], v[220:223], v[240:243], v[2:5]
	v_mfma_f32_16x16x32_bf16 v[6:9], v[220:223], v[252:255], v[6:9]
	ds_read_b128 v[220:223], v244 offset:23104
	s_waitcnt lgkmcnt(3)
	v_mfma_f32_16x16x32_bf16 v[26:29], v[224:227], v[228:231], v[26:29]
	ds_read_b128 v[228:231], v245 offset:55360
	v_mfma_f32_16x16x32_bf16 v[30:33], v[224:227], v[236:239], v[30:33]
	ds_read_b128 v[236:239], v245 offset:57664
	v_mfma_f32_16x16x32_bf16 v[10:13], v[224:227], v[240:243], v[10:13]
	ds_read_b128 v[240:243], v245 offset:59968
	v_mfma_f32_16x16x32_bf16 v[14:17], v[224:227], v[252:255], v[14:17]
	ds_read_b128 v[252:255], v245 offset:62272
	ds_read_b128 v[224:227], v244 offset:25408
	s_waitcnt lgkmcnt(4)
	v_mfma_f32_16x16x32_bf16 v[50:53], v[212:215], v[228:231], v[50:53]
	s_waitcnt lgkmcnt(3)
	v_mfma_f32_16x16x32_bf16 v[54:57], v[212:215], v[236:239], v[54:57]
	s_waitcnt lgkmcnt(2)
	v_mfma_f32_16x16x32_bf16 v[34:37], v[212:215], v[240:243], v[34:37]
	s_waitcnt lgkmcnt(1)
	v_mfma_f32_16x16x32_bf16 v[38:41], v[212:215], v[252:255], v[38:41]
	v_mfma_f32_16x16x32_bf16 v[58:61], v[216:219], v[228:231], v[58:61]
	v_mfma_f32_16x16x32_bf16 v[62:65], v[216:219], v[236:239], v[62:65]
	v_mfma_f32_16x16x32_bf16 v[42:45], v[216:219], v[240:243], v[42:45]
	v_mfma_f32_16x16x32_bf16 v[46:49], v[216:219], v[252:255], v[46:49]
	v_mfma_f32_16x16x32_bf16 v[18:21], v[220:223], v[228:231], v[18:21]
	v_mfma_f32_16x16x32_bf16 v[22:25], v[220:223], v[236:239], v[22:25]
	v_mfma_f32_16x16x32_bf16 v[2:5], v[220:223], v[240:243], v[2:5]
	v_mfma_f32_16x16x32_bf16 v[6:9], v[220:223], v[252:255], v[6:9]
	s_waitcnt lgkmcnt(0)
	v_mfma_f32_16x16x32_bf16 v[26:29], v[224:227], v[228:231], v[26:29]
	v_mfma_f32_16x16x32_bf16 v[30:33], v[224:227], v[236:239], v[30:33]
	v_mfma_f32_16x16x32_bf16 v[10:13], v[224:227], v[240:243], v[10:13]
	v_mfma_f32_16x16x32_bf16 v[14:17], v[224:227], v[252:255], v[14:17]
	s_waitcnt lgkmcnt(0)
	s_barrier
	s_nop 7
	v_permlane16_swap_b32_e32 v50, v54
	v_permlane16_swap_b32_e32 v51, v55
	v_permlane16_swap_b32_e32 v52, v56
	v_permlane16_swap_b32_e32 v53, v57
	v_permlane16_swap_b32_e32 v58, v62
	v_permlane16_swap_b32_e32 v59, v63
	v_permlane16_swap_b32_e32 v60, v64
	v_permlane16_swap_b32_e32 v61, v65
	v_permlane16_swap_b32_e32 v34, v38
	v_permlane16_swap_b32_e32 v35, v39
	v_permlane16_swap_b32_e32 v36, v40
	v_permlane16_swap_b32_e32 v37, v41
	v_permlane16_swap_b32_e32 v42, v46
	v_permlane16_swap_b32_e32 v43, v47
	v_permlane16_swap_b32_e32 v44, v48
	v_permlane16_swap_b32_e32 v45, v49
	v_permlane16_swap_b32_e32 v18, v22
	v_permlane16_swap_b32_e32 v19, v23
	v_permlane16_swap_b32_e32 v20, v24
	v_permlane16_swap_b32_e32 v21, v25
	v_permlane16_swap_b32_e32 v26, v30
	v_permlane16_swap_b32_e32 v27, v31
	v_permlane16_swap_b32_e32 v28, v32
	v_permlane16_swap_b32_e32 v29, v33
	v_permlane16_swap_b32_e32 v2, v6
	v_permlane16_swap_b32_e32 v3, v7
	v_permlane16_swap_b32_e32 v4, v8
	v_permlane16_swap_b32_e32 v5, v9
	v_permlane16_swap_b32_e32 v10, v14
	v_permlane16_swap_b32_e32 v11, v15
	v_permlane16_swap_b32_e32 v12, v16
	v_permlane16_swap_b32_e32 v13, v17
	v_permlane32_swap_b32_e32 v50, v54
	v_permlane32_swap_b32_e32 v51, v55
	v_permlane32_swap_b32_e32 v52, v56
	v_permlane32_swap_b32_e32 v53, v57
	v_permlane32_swap_b32_e32 v58, v62
	v_permlane32_swap_b32_e32 v59, v63
	v_permlane32_swap_b32_e32 v60, v64
	v_permlane32_swap_b32_e32 v61, v65
	v_permlane32_swap_b32_e32 v34, v38
	v_permlane32_swap_b32_e32 v35, v39
	v_permlane32_swap_b32_e32 v36, v40
	v_permlane32_swap_b32_e32 v37, v41
	v_permlane32_swap_b32_e32 v42, v46
	v_permlane32_swap_b32_e32 v43, v47
	v_permlane32_swap_b32_e32 v44, v48
	v_permlane32_swap_b32_e32 v45, v49
	v_permlane32_swap_b32_e32 v18, v22
	v_permlane32_swap_b32_e32 v19, v23
	v_permlane32_swap_b32_e32 v20, v24
	v_permlane32_swap_b32_e32 v21, v25
	v_permlane32_swap_b32_e32 v26, v30
	v_permlane32_swap_b32_e32 v27, v31
	v_permlane32_swap_b32_e32 v28, v32
	v_permlane32_swap_b32_e32 v29, v33
	v_permlane32_swap_b32_e32 v2, v6
	v_permlane32_swap_b32_e32 v3, v7
	v_permlane32_swap_b32_e32 v4, v8
	v_permlane32_swap_b32_e32 v5, v9
	v_permlane32_swap_b32_e32 v10, v14
	v_permlane32_swap_b32_e32 v11, v15
	v_permlane32_swap_b32_e32 v12, v16
	v_permlane32_swap_b32_e32 v13, v17

.LBB0_554:
	s_add_i32 s0, s37, 0xfffffe00
	s_cmpk_lt_i32 s37, 0x200
	s_cselect_b64 s[12:13], -1, 0
	s_and_b64 s[12:13], s[12:13], exec
	s_cselect_b32 s14, s37, s0
	s_cselect_b32 s38, 0x43, 3
	s_lshr_b32 s15, s14, 2
	s_cmpk_lt_i32 s37, 0x200
	s_cselect_b64 s[12:13], -1, 0
	s_and_b64 s[12:13], s[12:13], exec
	s_cselect_b32 s15, s37, s15
	s_bfe_u32 s14, s14, 0x10002
	s_ashr_i32 s18, s0, 4
	s_cmpk_lt_i32 s37, 0x200
	s_cselect_b64 s[12:13], -1, 0
	s_and_b64 s[12:13], s[12:13], exec
	s_cselect_b32 s19, s14, s18
	s_and_b32 s21, s15, 3
	s_lshl_b32 s33, s21, 7
	s_lshl_b32 s0, s19, 9
	s_or_b32 s12, s33, s0
	s_ashr_i32 s13, s12, 31
	s_lshl_b64 s[14:15], s[12:13], 12
	s_add_u32 s0, s14, 0x200000
	s_addc_u32 s16, s15, 0
	s_lshl_b64 s[12:13], s[12:13], 8
	s_cmpk_lt_i32 s37, 0x200
	s_cselect_b64 s[14:15], -1, 0
	s_and_b64 s[14:15], s[14:15], exec
	s_cselect_b32 s20, -4, 0
	s_cselect_b32 s14, s0, s12
	s_cselect_b32 s15, s16, s13
	s_lshl_b32 s0, s19, 3
	s_or_b32 s25, s0, s21
	s_lshl_b32 s12, s25, 7
	s_ashr_i32 s13, s12, 31
	s_lshl_b64 s[12:13], s[12:13], 9
	s_add_u32 s12, s28, s12
	s_addc_u32 s13, s29, s13
	s_lshl_b64 s[14:15], s[14:15], 1
	s_add_u32 s14, s34, s14
	s_addc_u32 s15, s35, s15
	s_lshl_b32 s0, s20, 6
	s_lshl_b64 s[16:17], s[0:1], 1
	s_add_u32 s0, s14, s16
	s_addc_u32 s23, s15, s17
	s_cmpk_lt_i32 s37, 0x200
	s_cselect_b64 s[16:17], -1, 0
	s_and_b64 s[16:17], s[16:17], exec
	s_cselect_b32 s22, s12, s0
	s_cselect_b32 s23, s13, s23
	s_lshl_b32 s0, s19, 12
	s_addk_i32 s0, 0x1000
	s_lshl_b32 s18, s18, 8
	s_cmpk_lt_i32 s37, 0x200
	s_cselect_b64 s[16:17], -1, 0
	s_and_b64 s[16:17], s[16:17], exec
	s_cselect_b32 s24, s0, s18
	s_lshl_b32 s16, s25, 8
	s_ashr_i32 s17, s16, 31
	s_lshl_b32 s0, s21, 8
	s_lshl_b64 s[16:17], s[16:17], 8
	s_add_u32 s16, s26, s16
	s_addc_u32 s17, s27, s17
	s_ashr_i32 s25, s24, 31
	s_lshl_b64 s[18:19], s[24:25], 10
	s_add_u32 s18, s30, s18
	s_addc_u32 s19, s31, s19
	s_mov_b32 s21, s1
	s_add_u32 s18, s18, s0
	s_addc_u32 s19, s19, 0
	s_lshl_b64 s[20:21], s[20:21], 16
	s_add_u32 s25, s18, s20
	s_addc_u32 s40, s19, s21
	s_cmpk_lt_i32 s37, 0x200
	s_cselect_b64 s[20:21], -1, 0
	s_and_b64 s[20:21], s[20:21], exec
	s_cselect_b32 s39, 4, 0
	s_cselect_b32 s41, 12, 8
	s_cselect_b32 s21, s17, s40
	s_cselect_b32 s20, s16, s25
	s_lshr_b32 s25, s37, 3
	s_and_b32 s40, s37, 3
	s_cmpk_lt_i32 s37, 0x200
	s_cselect_b64 vcc, -1, 0
	v_cndmask_b32_e32 v82, v139, v137, vcc
	v_cndmask_b32_e32 v156, v163, v166, vcc
	v_cndmask_b32_e32 v158, v162, v165, vcc
	v_cndmask_b32_e32 v160, v143, v164, vcc
	v_lshlrev_b32_e32 v2, 1, v82
	v_lshlrev_b32_e32 v4, 1, v160
	v_lshlrev_b32_e32 v5, 1, v158
	v_lshlrev_b32_e32 v6, 1, v156
	global_load_dwordx4 v[14:17], v2, s[20:21]
	global_load_dwordx4 v[18:21], v195, s[22:23]
	global_load_dwordx4 v[22:25], v4, s[20:21]
	global_load_dwordx4 v[26:29], v196, s[22:23]
	global_load_dwordx4 v[30:33], v5, s[20:21]
	global_load_dwordx4 v[34:37], v197, s[22:23]
	global_load_dwordx4 v[38:41], v6, s[20:21]
	global_load_dwordx4 v[42:45], v198, s[22:23]
	s_and_b64 s[20:21], vcc, exec
	s_cselect_b32 s20, s25, s40
	s_lshl_b32 s20, s20, 6
	s_add_i32 s20, s24, s20
	v_or_b32_e32 v46, s20, v194
	v_ashrrev_i32_e32 v47, 31, v46
	v_lshlrev_b64 v[4:5], 10, v[46:47]
	v_lshl_add_u64 v[4:5], s[6:7], 0, v[4:5]
	v_lshl_add_u64 v[152:153], v[4:5], 0, s[0:1]
	v_lshl_add_u64 v[4:5], v[152:153], 0, v[146:147]
	v_lshl_add_u64 v[4:5], v[4:5], 0, v[150:151]
	global_load_dwordx4 v[126:129], v[4:5], off
	global_load_dwordx4 v[122:125], v[4:5], off offset:32
	global_load_dwordx4 v[118:121], v[4:5], off offset:64
	global_load_dwordx4 v[114:117], v[4:5], off offset:96
	v_mov_b32_e32 v2, v3
	v_mov_b32_e32 v4, v3
	v_mov_b32_e32 v5, v3
	v_mov_b32_e32 v6, v3
	v_mov_b32_e32 v7, v3
	v_mov_b32_e32 v8, v3
	v_mov_b32_e32 v9, v3
	v_mov_b32_e32 v10, v3
	v_mov_b32_e32 v11, v3
	v_mov_b32_e32 v12, v3
	v_mov_b32_e32 v13, v3
	v_lshlrev_b64 v[154:155], 9, v[46:47]
	v_lshl_or_b32 v201, v168, s41, v141
	v_lshl_or_b32 v202, v184, s41, v141
	v_lshl_or_b32 v203, v189, s41, v141
	v_lshl_or_b32 v204, v171, s41, v141
	s_sub_i32 s40, 1, s39
	v_mov_b32_e32 v149, 0xff800000
	s_mov_b32 s42, s1
	s_setprio 1
	s_waitcnt vmcnt(11)
	ds_write_b128 v179, v[14:17]
	s_waitcnt vmcnt(10)
	ds_write_b128 v181, v[18:21]
	s_waitcnt vmcnt(9)
	ds_write_b128 v183, v[22:25]
	s_waitcnt vmcnt(8)
	ds_write_b128 v186, v[26:29]
	s_waitcnt vmcnt(7)
	ds_write_b128 v188, v[30:33]
	s_waitcnt vmcnt(6)
	ds_write_b128 v191, v[34:37]
	s_waitcnt vmcnt(5)
	ds_write_b128 v192, v[38:41]
	s_waitcnt vmcnt(4)
	ds_write_b128 v193, v[42:45]
	v_mov_b32_e32 v16, v3
	v_mov_b32_e32 v17, v3
	v_mov_b32_e32 v14, v3
	v_mov_b32_e32 v15, v3
	v_mov_b64_e32 v[32:33], v[16:17]
	v_mov_b64_e32 v[48:49], v[16:17]
	v_mov_b64_e32 v[64:65], v[16:17]
	v_mov_b64_e32 v[80:81], v[16:17]
	v_mov_b64_e32 v[30:31], v[14:15]
	v_mov_b64_e32 v[28:29], v[12:13]
	v_mov_b64_e32 v[26:27], v[10:11]
	v_mov_b64_e32 v[24:25], v[8:9]
	v_mov_b64_e32 v[22:23], v[6:7]
	v_mov_b64_e32 v[20:21], v[4:5]
	v_mov_b64_e32 v[18:19], v[2:3]
	v_mov_b64_e32 v[46:47], v[14:15]
	v_mov_b64_e32 v[44:45], v[12:13]
	v_mov_b64_e32 v[42:43], v[10:11]
	v_mov_b64_e32 v[40:41], v[8:9]
	v_mov_b64_e32 v[38:39], v[6:7]
	v_mov_b64_e32 v[36:37], v[4:5]
	v_mov_b64_e32 v[34:35], v[2:3]
	v_mov_b64_e32 v[62:63], v[14:15]
	v_mov_b64_e32 v[60:61], v[12:13]
	v_mov_b64_e32 v[58:59], v[10:11]
	v_mov_b64_e32 v[56:57], v[8:9]
	v_mov_b64_e32 v[54:55], v[6:7]
	v_mov_b64_e32 v[52:53], v[4:5]
	v_mov_b64_e32 v[50:51], v[2:3]
	v_mov_b64_e32 v[78:79], v[14:15]
	v_mov_b64_e32 v[76:77], v[12:13]
	v_mov_b64_e32 v[74:75], v[10:11]
	v_mov_b64_e32 v[72:73], v[8:9]
	v_mov_b64_e32 v[70:71], v[6:7]
	v_mov_b64_e32 v[68:69], v[4:5]
	v_mov_b64_e32 v[66:67], v[2:3]
	v_mov_b32_e32 v10, v136
	v_mov_b32_e32 v8, v138
	v_mov_b32_e32 v6, v140
	v_mov_b32_e32 v4, v142
	v_mov_b32_e32 v2, v82
	s_waitcnt lgkmcnt(0)
	s_barrier
	s_setprio 0

.LBB0_584:
	v_lshlrev_b64 v[152:153], 9, v[2:3]
	v_mul_u32_u24_e32 v2, s58, v157
	v_lshlrev_b32_e32 v136, 1, v2
	v_lshl_add_u64 v[2:3], s[2:3], 0, v[136:137]
	v_lshl_add_u64 v[2:3], v[2:3], 0, v[148:149]
	v_lshl_add_u64 v[4:5], s[48:49], 0, v[138:139]
	global_load_dwordx4 v[114:117], v[2:3], off
	v_mul_u32_u24_e32 v2, s58, v158
	v_lshl_add_u64 v[4:5], v[4:5], 0, v[148:149]
	v_lshlrev_b32_e32 v136, 1, v2
	global_load_dwordx4 v[122:125], v[4:5], off
	v_lshl_add_u64 v[4:5], s[48:49], 0, v[140:141]
	v_lshl_add_u64 v[2:3], s[2:3], 0, v[136:137]
	v_lshl_add_u64 v[4:5], v[4:5], 0, v[148:149]
	v_lshl_add_u64 v[2:3], v[2:3], 0, v[148:149]
	global_load_dwordx4 v[126:129], v[4:5], off
	global_load_dwordx4 v[118:121], v[2:3], off
	v_sub_u32_e64 v2, s10, 4 clamp
	v_sub_u32_e64 v3, s10, 3 clamp
	v_readfirstlane_b32 s6, v2
	v_readfirstlane_b32 s7, v3
	s_min_u32 s40, s6, 56
	s_min_u32 s6, s7, 56
	s_sub_i32 s6, s6, s40
	s_add_i32 s10, s6, 12
	s_and_b64 s[6:7], s[4:5], exec
	s_cselect_b32 s43, s10, 4
	s_cmp_lt_i32 s43, 1
	s_setprio 1
	s_waitcnt vmcnt(2)
	ds_write_b128 v160, v[122:125] offset:18432
	ds_write_b128 v160, v[114:117]
	s_waitcnt vmcnt(1)
	ds_write_b128 v162, v[126:129] offset:18432
	s_waitcnt vmcnt(0)
	ds_write_b128 v162, v[118:121]
	s_waitcnt lgkmcnt(0)
	s_barrier
	s_setprio 0
	s_cbranch_scc1 .LBB0_666
	s_and_b64 s[6:7], s[4:5], exec
	s_cselect_b32 s6, s9, s8
	s_lshl_b32 s6, s6, 12
	s_ashr_i32 s7, s6, 31
	s_lshl_b64 s[6:7], s[6:7], 10
	v_readlane_b32 s8, v247, 1
	v_cndmask_b32_e64 v2, 0, v6, s[4:5]
	s_add_u32 s6, s8, s6
	v_readlane_b32 s8, v247, 2
	v_sub_u32_e64 v3, v2, 4 clamp
	s_addc_u32 s7, s8, s7
	s_lshl_b32 s8, s13, 1
	v_min_u32_e32 v145, 56, v3
	s_add_u32 s6, s6, s8
	v_cndmask_b32_e64 v3, 0, v154, s[4:5]
	s_addc_u32 s7, s7, 0
	v_or_b32_e32 v4, v3, v132
	s_add_u32 s60, s6, 0x400000
	v_sub_u32_e64 v4, v4, 8 clamp
	s_addc_u32 s61, s7, 0
	s_lshl_b64 s[0:1], s[0:1], 13
	v_readlane_b32 s6, v247, 4
	v_min_u32_e32 v4, 48, v4
	s_add_u32 s62, s6, s0
	v_readlane_b32 s0, v247, 5
	v_add_u32_e32 v5, 16, v4
	s_addc_u32 s63, s0, s1
	v_cmp_ge_u32_e64 s[0:1], v165, v4
	v_cmp_lt_u32_e64 s[6:7], v165, v5
	s_and_b64 s[66:67], s[0:1], s[6:7]
	v_cmp_ge_u32_e64 s[0:1], v167, v4
	v_cmp_lt_u32_e64 s[8:9], v167, v5
	s_and_b64 s[68:69], s[0:1], s[8:9]
	v_cmp_ge_u32_e64 s[0:1], v169, v4
	v_cmp_lt_u32_e64 s[10:11], v169, v5
	s_mov_b32 s51, s13
	s_and_b64 s[70:71], s[0:1], s[10:11]
	v_cmp_ge_u32_e64 s[0:1], v171, v4
	v_cmp_lt_u32_e64 s[12:13], v171, v5
	s_and_b64 s[76:77], s[0:1], s[12:13]
	v_cmp_ge_u32_e64 s[0:1], v173, v4
	v_cmp_lt_u32_e64 s[14:15], v173, v5
	s_and_b64 s[78:79], s[0:1], s[14:15]
	v_cmp_ge_u32_e64 s[0:1], v175, v4
	v_cmp_lt_u32_e64 s[16:17], v175, v5
	s_and_b64 s[80:81], s[0:1], s[16:17]
	v_cmp_ge_u32_e64 s[0:1], v177, v4
	v_cmp_lt_u32_e64 s[18:19], v177, v5
	s_and_b64 s[82:83], s[0:1], s[18:19]
	v_cmp_ge_u32_e64 s[0:1], v179, v4
	v_cmp_lt_u32_e64 s[20:21], v179, v5
	v_cmp_lt_u32_e32 vcc, v164, v4
	s_and_b64 s[84:85], s[0:1], s[20:21]
	v_cmp_ge_u32_e64 s[0:1], v180, v4
	s_and_b64 s[86:87], s[0:1], vcc
	v_cmp_ge_u32_e32 vcc, v182, v4
	v_cmp_lt_u32_e64 s[0:1], v182, v5
	s_and_b64 s[96:97], vcc, s[0:1]
	v_cmp_ge_u32_e32 vcc, v184, v4
	v_cmp_lt_u32_e64 s[0:1], v184, v5
	s_and_b64 s[38:39], vcc, s[0:1]
	v_cmp_ge_u32_e32 vcc, v186, v4
	v_cmp_lt_u32_e64 s[0:1], v186, v5
	s_and_b64 s[92:93], vcc, s[0:1]
	v_cmp_ge_u32_e32 vcc, v188, v4
	v_cmp_lt_u32_e64 s[0:1], v188, v5
	s_and_b64 s[88:89], vcc, s[0:1]
	v_cmp_ge_u32_e32 vcc, v190, v4
	v_cmp_lt_u32_e64 s[0:1], v190, v5
	s_and_b64 s[90:91], vcc, s[0:1]
	v_cmp_ge_u32_e32 vcc, v192, v4
	v_cmp_lt_u32_e64 s[0:1], v192, v5
	s_and_b64 s[56:57], vcc, s[0:1]
	v_cmp_ge_u32_e32 vcc, v194, v4
	v_cmp_lt_u32_e64 s[0:1], v194, v5
	s_and_b64 s[64:65], vcc, s[0:1]
	v_add_u32_e32 v3, v132, v3
	s_mul_i32 s0, s40, 0x7c
	v_mul_u32_u24_e32 v2, 0x7c, v2
	v_sub_u32_e32 v211, s0, v2
	v_sub_u32_e32 v2, v165, v3
	v_max_i32_e32 v2, -15, v2
	v_add_u32_e32 v2, 15, v2
	v_min_u32_e32 v2, 30, v2
	v_lshlrev_b32_e32 v212, 2, v2
	v_sub_u32_e32 v2, v166, v3
	v_max_i32_e32 v2, -15, v2
	v_lshlrev_b32_e32 v213, 2, v2
	v_sub_u32_e32 v2, v167, v3
	v_max_i32_e32 v2, -15, v2
	v_add_u32_e32 v2, 15, v2
	v_min_u32_e32 v2, 30, v2
	v_lshlrev_b32_e32 v214, 2, v2
	v_sub_u32_e32 v2, v168, v3
	v_max_i32_e32 v2, -15, v2
	v_lshlrev_b32_e32 v215, 2, v2
	v_sub_u32_e32 v2, v169, v3
	v_max_i32_e32 v2, -15, v2
	v_add_u32_e32 v2, 15, v2
	v_min_u32_e32 v2, 30, v2
	v_lshlrev_b32_e32 v216, 2, v2
	v_sub_u32_e32 v2, v170, v3
	v_max_i32_e32 v2, -15, v2
	v_lshlrev_b32_e32 v217, 2, v2
	v_sub_u32_e32 v2, v171, v3
	v_max_i32_e32 v2, -15, v2
	v_add_u32_e32 v2, 15, v2
	v_min_u32_e32 v2, 30, v2
	v_lshlrev_b32_e32 v218, 2, v2
	v_sub_u32_e32 v2, v172, v3
	v_max_i32_e32 v2, -15, v2
	v_lshlrev_b32_e32 v219, 2, v2
	v_sub_u32_e32 v2, v173, v3
	v_max_i32_e32 v2, -15, v2
	v_add_u32_e32 v2, 15, v2
	v_min_u32_e32 v2, 30, v2
	v_lshlrev_b32_e32 v220, 2, v2
	v_sub_u32_e32 v2, v174, v3
	v_max_i32_e32 v2, -15, v2
	v_lshlrev_b32_e32 v221, 2, v2
	v_sub_u32_e32 v2, v175, v3
	v_max_i32_e32 v2, -15, v2
	v_add_u32_e32 v2, 15, v2
	v_min_u32_e32 v2, 30, v2
	v_lshlrev_b32_e32 v222, 2, v2
	v_sub_u32_e32 v2, v176, v3
	v_max_i32_e32 v2, -15, v2
	v_lshlrev_b32_e32 v223, 2, v2
	v_sub_u32_e32 v2, v177, v3
	v_max_i32_e32 v2, -15, v2
	v_add_u32_e32 v2, 15, v2
	v_min_u32_e32 v2, 30, v2
	v_lshlrev_b32_e32 v224, 2, v2
	v_sub_u32_e32 v2, v178, v3
	v_max_i32_e32 v2, -15, v2
	v_lshlrev_b32_e32 v225, 2, v2
	v_sub_u32_e32 v2, v179, v3
	v_max_i32_e32 v2, -15, v2
	v_add_u32_e32 v2, 15, v2
	v_min_u32_e32 v2, 30, v2
	v_lshlrev_b32_e32 v226, 2, v2
	v_sub_u32_e32 v2, v180, v3
	v_max_i32_e32 v2, -15, v2
	v_add_u32_e32 v2, 15, v2
	v_min_u32_e32 v2, 30, v2
	v_lshlrev_b32_e32 v227, 2, v2
	v_sub_u32_e32 v2, v199, v3
	v_min_u32_e32 v2, 30, v2
	v_lshlrev_b32_e32 v228, 2, v2
	v_sub_u32_e32 v2, v182, v3
	v_max_i32_e32 v2, -15, v2
	v_add_u32_e32 v2, 15, v2
	v_min_u32_e32 v2, 30, v2
	v_lshlrev_b32_e32 v229, 2, v2
	v_sub_u32_e32 v2, v200, v3
	v_min_u32_e32 v2, 30, v2
	v_lshlrev_b32_e32 v230, 2, v2
	v_sub_u32_e32 v2, v184, v3
	v_max_i32_e32 v2, -15, v2
	v_add_u32_e32 v2, 15, v2
	v_min_u32_e32 v2, 30, v2
	v_lshlrev_b32_e32 v231, 2, v2
	v_sub_u32_e32 v2, v201, v3
	v_min_u32_e32 v2, 30, v2
	v_lshlrev_b32_e32 v232, 2, v2
	v_sub_u32_e32 v2, v186, v3
	v_max_i32_e32 v2, -15, v2
	v_add_u32_e32 v2, 15, v2
	v_min_u32_e32 v2, 30, v2
	v_lshlrev_b32_e32 v233, 2, v2
	v_sub_u32_e32 v2, v202, v3
	v_min_u32_e32 v2, 30, v2
	v_lshlrev_b32_e32 v234, 2, v2
	v_sub_u32_e32 v2, v188, v3
	v_max_i32_e32 v2, -15, v2
	v_add_u32_e32 v2, 15, v2
	v_min_u32_e32 v2, 30, v2
	v_lshlrev_b32_e32 v235, 2, v2
	v_sub_u32_e32 v2, v203, v3
	v_min_u32_e32 v2, 30, v2
	v_lshlrev_b32_e32 v236, 2, v2
	v_sub_u32_e32 v2, v190, v3
	v_max_i32_e32 v2, -15, v2
	v_add_u32_e32 v2, 15, v2
	v_min_u32_e32 v2, 30, v2
	v_lshlrev_b32_e32 v237, 2, v2
	v_sub_u32_e32 v2, v204, v3
	v_min_u32_e32 v2, 30, v2
	v_lshlrev_b32_e32 v238, 2, v2
	v_sub_u32_e32 v2, v192, v3
	v_max_i32_e32 v2, -15, v2
	v_add_u32_e32 v2, 15, v2
	v_min_u32_e32 v2, 30, v2
	v_lshlrev_b32_e32 v239, 2, v2
	v_sub_u32_e32 v2, v205, v3
	v_min_u32_e32 v2, 30, v2
	v_lshlrev_b32_e32 v240, 2, v2
	v_sub_u32_e32 v2, v194, v3
	v_max_i32_e32 v2, -15, v2
	v_add_u32_e32 v2, 15, v2
	v_min_u32_e32 v2, 30, v2
	v_cmp_ge_u32_e64 s[4:5], v164, v4
	v_cmp_ge_u32_e64 s[6:7], v166, v4
	v_cmp_ge_u32_e64 s[8:9], v168, v4
	v_cmp_ge_u32_e64 s[10:11], v170, v4
	v_cmp_ge_u32_e64 s[12:13], v172, v4
	v_cmp_ge_u32_e64 s[14:15], v174, v4
	v_cmp_ge_u32_e64 s[16:17], v176, v4
	v_cmp_ge_u32_e64 s[18:19], v178, v4
	v_sub_u32_e32 v4, v164, v3
	v_lshlrev_b32_e32 v241, 2, v2
	v_sub_u32_e32 v2, v206, v3
	v_max_i32_e32 v4, -15, v4
	v_min_u32_e32 v2, 30, v2
	v_mov_b32_e32 v209, 0
	s_mov_b32 s50, 0
	v_add_u32_e32 v208, 8, v145
	v_cmp_lt_u32_e64 s[20:21], v181, v5
	v_cmp_lt_u32_e64 s[22:23], v183, v5
	v_cmp_lt_u32_e64 s[24:25], v185, v5
	v_cmp_lt_u32_e64 s[26:27], v187, v5
	v_cmp_lt_u32_e64 s[28:29], v189, v5
	v_cmp_lt_u32_e64 s[30:31], v191, v5
	v_cmp_lt_u32_e64 s[34:35], v193, v5
	v_cmp_lt_u32_e64 s[36:37], v195, v5
	s_add_i32 s42, s40, -4
	v_lshlrev_b32_e32 v210, 2, v4
	v_lshlrev_b32_e32 v242, 2, v2
	v_mov_b32_e32 v243, 0xff800000
	s_mov_b32 s44, 64
	v_mov_b32_e32 v18, 0
	v_mov_b32_e32 v19, v209
	v_mov_b32_e32 v20, v209
	v_mov_b32_e32 v21, v209
	v_mov_b32_e32 v22, v209
	v_mov_b32_e32 v23, v209
	v_mov_b32_e32 v24, v209
	v_mov_b32_e32 v25, v209
	v_mov_b32_e32 v26, v209
	v_mov_b32_e32 v27, v209
	v_mov_b32_e32 v28, v209
	v_mov_b32_e32 v29, v209
	v_mov_b32_e32 v30, v209
	v_mov_b32_e32 v31, v209
	v_mov_b32_e32 v32, v209
	v_mov_b32_e32 v33, v209
	v_mov_b32_e32 v2, v209
	v_mov_b32_e32 v3, v209
	v_mov_b32_e32 v4, v209
	v_mov_b32_e32 v5, v209
	v_mov_b32_e32 v6, v209
	v_mov_b32_e32 v7, v209
	v_mov_b32_e32 v8, v209
	v_mov_b32_e32 v9, v209
	v_mov_b32_e32 v10, v209
	v_mov_b32_e32 v11, v209
	v_mov_b32_e32 v12, v209
	v_mov_b32_e32 v13, v209
	v_mov_b32_e32 v14, v209
	v_mov_b32_e32 v15, v209
	v_mov_b32_e32 v16, v209
	v_mov_b32_e32 v17, v209

.LBB0_749:
	s_and_b32 s3, s2, 0xffff
	s_mul_i32 s3, s3, 0xaaab
	s_lshr_b32 s3, s3, 18
	s_mul_i32 s10, s3, 6
	s_sub_i32 s2, s2, s10
	s_and_b32 s2, s2, 0xffff
	s_add_i32 s2, s6, s2
	s_lshl_b32 s10, s2, 7
	v_or_b32_e32 v2, s10, v91
	v_lshlrev_b32_e32 v66, 11, v2
	v_lshl_add_u64 v[74:75], v[68:69], 0, v[66:67]
	v_add_lshl_u32 v66, s10, v92, 11
	s_add_i32 s3, s8, s3
	v_lshl_add_u64 v[76:77], v[68:69], 0, v[66:67]
	v_add_lshl_u32 v66, s10, v93, 11
	s_lshl_b32 s11, s3, 7
	v_lshl_add_u64 v[78:79], v[68:69], 0, v[66:67]
	v_add_lshl_u32 v66, s10, v94, 11
	v_lshl_add_u64 v[80:81], v[68:69], 0, v[66:67]
	v_or_b32_e32 v66, s11, v91
	v_lshlrev_b64 v[2:3], 11, v[66:67]
	v_add_u32_e32 v66, s11, v92
	v_lshl_add_u64 v[82:83], v[70:71], 0, v[2:3]
	v_lshlrev_b64 v[2:3], 11, v[66:67]
	v_add_u32_e32 v66, s11, v93
	v_lshl_add_u64 v[84:85], v[70:71], 0, v[2:3]
	v_lshlrev_b64 v[2:3], 11, v[66:67]
	v_add_u32_e32 v66, s11, v94
	v_lshl_add_u64 v[86:87], v[70:71], 0, v[2:3]
	v_lshlrev_b64 v[2:3], 11, v[66:67]
	v_lshl_add_u64 v[88:89], v[70:71], 0, v[2:3]
	global_load_dwordx4 v[2:5], v[74:75], off
	global_load_dwordx4 v[6:9], v[76:77], off
	global_load_dwordx4 v[10:13], v[78:79], off
	global_load_dwordx4 v[14:17], v[80:81], off
	global_load_dwordx4 v[18:21], v[82:83], off
	global_load_dwordx4 v[22:25], v[84:85], off
	global_load_dwordx4 v[26:29], v[86:87], off
	global_load_dwordx4 v[30:33], v[88:89], off
	global_load_dwordx4 v[102:105], v[74:75], off offset:128
	global_load_dwordx4 v[106:109], v[76:77], off offset:128
	global_load_dwordx4 v[110:113], v[78:79], off offset:128
	global_load_dwordx4 v[114:117], v[80:81], off offset:128
	global_load_dwordx4 v[118:121], v[82:83], off offset:128
	global_load_dwordx4 v[122:125], v[84:85], off offset:128
	global_load_dwordx4 v[126:129], v[86:87], off offset:128
	global_load_dwordx4 v[136:139], v[88:89], off offset:128
	s_setprio 1
	s_waitcnt vmcnt(15)
	ds_write_b128 v98, v[2:5]
	s_waitcnt vmcnt(14)
	ds_write_b128 v98, v[6:9] offset:4608
	s_waitcnt vmcnt(13)
	ds_write_b128 v98, v[10:13] offset:9216
	s_waitcnt vmcnt(12)
	ds_write_b128 v98, v[14:17] offset:13824
	s_waitcnt vmcnt(11)
	ds_write_b128 v98, v[18:21] offset:36864
	s_waitcnt vmcnt(10)
	ds_write_b128 v98, v[22:25] offset:41472
	s_waitcnt vmcnt(9)
	ds_write_b128 v98, v[26:29] offset:46080
	s_waitcnt vmcnt(8)
	ds_write_b128 v98, v[30:33] offset:50688
	s_waitcnt lgkmcnt(0)
	s_barrier
	s_setprio 0
	global_load_dwordx4 v[140:143], v[74:75], off offset:256
	global_load_dwordx4 v[144:147], v[76:77], off offset:256
	global_load_dwordx4 v[148:151], v[78:79], off offset:256
	global_load_dwordx4 v[152:155], v[80:81], off offset:256
	global_load_dwordx4 v[156:159], v[82:83], off offset:256
	global_load_dwordx4 v[160:163], v[84:85], off offset:256
	global_load_dwordx4 v[164:167], v[86:87], off offset:256
	global_load_dwordx4 v[168:171], v[88:89], off offset:256
	v_and_b32_e32 v246, 15, v1
	v_add_u32_e32 v246, 4, v246
	v_bfe_u32 v246, v246, 3, 1
	v_bfe_u32 v249, v1, 4, 2
	v_xor_b32_e32 v246, v246, v249
	v_bfe_u32 v249, v1, 5, 1
	v_sub_u32_e32 v246, v246, v249
	v_lshlrev_b32_e32 v246, 4, v246
	v_bfe_u32 v249, v1, 4, 1
	v_mul_u32_u24_e32 v249, 0x900, v249
	v_sub_u32_e32 v246, v246, v249
	v_add_u32_e32 v244, v246, v96
	v_add_u32_e32 v245, v246, v97
	ds_read_b128 v[212:215], v245 offset:36864
	ds_read_b128 v[196:199], v244
	ds_read_b128 v[216:219], v245 offset:39168
	ds_read_b128 v[220:223], v245 offset:41472
	ds_read_b128 v[224:227], v245 offset:43776
	ds_read_b128 v[200:203], v244 offset:2304
	ds_read_b128 v[204:207], v244 offset:4608
	ds_read_b128 v[208:211], v244 offset:6912
	s_waitcnt lgkmcnt(6)
	v_mfma_f32_16x16x32_bf16 v[50:53], v[196:199], v[212:215], 0
	ds_read_b128 v[228:231], v245 offset:36928
	s_waitcnt lgkmcnt(6)
	v_mfma_f32_16x16x32_bf16 v[54:57], v[196:199], v[216:219], 0
	ds_read_b128 v[232:235], v245 offset:39232
	s_waitcnt lgkmcnt(6)
	v_mfma_f32_16x16x32_bf16 v[18:21], v[196:199], v[220:223], 0
	ds_read_b128 v[236:239], v245 offset:41536
	s_waitcnt lgkmcnt(6)
	v_mfma_f32_16x16x32_bf16 v[22:25], v[196:199], v[224:227], 0
	ds_read_b128 v[240:243], v245 offset:43840
	ds_read_b128 v[196:199], v244 offset:64
	s_waitcnt lgkmcnt(7)
	v_mfma_f32_16x16x32_bf16 v[58:61], v[200:203], v[212:215], 0
	v_mfma_f32_16x16x32_bf16 v[62:65], v[200:203], v[216:219], 0
	v_mfma_f32_16x16x32_bf16 v[26:29], v[200:203], v[220:223], 0
	v_mfma_f32_16x16x32_bf16 v[30:33], v[200:203], v[224:227], 0
	ds_read_b128 v[200:203], v244 offset:2368
	s_waitcnt lgkmcnt(7)
	v_mfma_f32_16x16x32_bf16 v[34:37], v[204:207], v[212:215], 0
	v_mfma_f32_16x16x32_bf16 v[38:41], v[204:207], v[216:219], 0
	v_mfma_f32_16x16x32_bf16 v[2:5], v[204:207], v[220:223], 0
	v_mfma_f32_16x16x32_bf16 v[6:9], v[204:207], v[224:227], 0
	ds_read_b128 v[204:207], v244 offset:4672
	s_setprio 1
	s_waitcnt vmcnt(15)
	ds_write_b128 v98, v[102:105] offset:18432
	s_waitcnt vmcnt(14)
	ds_write_b128 v98, v[106:109] offset:23040
	s_waitcnt lgkmcnt(9)
	v_mfma_f32_16x16x32_bf16 v[42:45], v[208:211], v[212:215], 0
	v_mfma_f32_16x16x32_bf16 v[46:49], v[208:211], v[216:219], 0
	v_mfma_f32_16x16x32_bf16 v[10:13], v[208:211], v[220:223], 0
	v_mfma_f32_16x16x32_bf16 v[14:17], v[208:211], v[224:227], 0
	ds_read_b128 v[208:211], v244 offset:6976
	s_waitcnt vmcnt(13)
	ds_write_b128 v98, v[110:113] offset:27648
	s_waitcnt vmcnt(12)
	ds_write_b128 v98, v[114:117] offset:32256
	s_waitcnt lgkmcnt(7)
	v_mfma_f32_16x16x32_bf16 v[50:53], v[196:199], v[228:231], v[50:53]
	v_mfma_f32_16x16x32_bf16 v[54:57], v[196:199], v[232:235], v[54:57]
	v_mfma_f32_16x16x32_bf16 v[18:21], v[196:199], v[236:239], v[18:21]
	v_mfma_f32_16x16x32_bf16 v[22:25], v[196:199], v[240:243], v[22:25]
	s_waitcnt vmcnt(11)
	ds_write_b128 v98, v[118:121] offset:55296
	s_waitcnt vmcnt(10)
	ds_write_b128 v98, v[122:125] offset:59904
	s_waitcnt lgkmcnt(8)
	v_mfma_f32_16x16x32_bf16 v[58:61], v[200:203], v[228:231], v[58:61]
	v_mfma_f32_16x16x32_bf16 v[62:65], v[200:203], v[232:235], v[62:65]
	v_mfma_f32_16x16x32_bf16 v[26:29], v[200:203], v[236:239], v[26:29]
	v_mfma_f32_16x16x32_bf16 v[30:33], v[200:203], v[240:243], v[30:33]
	s_waitcnt vmcnt(9)
	ds_write_b128 v98, v[126:129] offset:64512
	s_waitcnt vmcnt(8)
	ds_write_b128 v99, v[136:139] offset:32256
	s_waitcnt lgkmcnt(0)
	s_barrier
	s_setprio 0
	ds_read_b128 v[212:215], v245 offset:55296
	ds_read_b128 v[196:199], v244 offset:18432
	ds_read_b128 v[216:219], v245 offset:57600
	ds_read_b128 v[220:223], v245 offset:59904
	ds_read_b128 v[224:227], v245 offset:62208
	ds_read_b128 v[200:203], v244 offset:20736
	v_mfma_f32_16x16x32_bf16 v[34:37], v[204:207], v[228:231], v[34:37]
	v_mfma_f32_16x16x32_bf16 v[38:41], v[204:207], v[232:235], v[38:41]
	v_mfma_f32_16x16x32_bf16 v[2:5], v[204:207], v[236:239], v[2:5]
	v_mfma_f32_16x16x32_bf16 v[6:9], v[204:207], v[240:243], v[6:9]
	ds_read_b128 v[204:207], v244 offset:23040
	v_mfma_f32_16x16x32_bf16 v[42:45], v[208:211], v[228:231], v[42:45]
	v_mfma_f32_16x16x32_bf16 v[46:49], v[208:211], v[232:235], v[46:49]
	v_mfma_f32_16x16x32_bf16 v[10:13], v[208:211], v[236:239], v[10:13]
	v_mfma_f32_16x16x32_bf16 v[14:17], v[208:211], v[240:243], v[14:17]
	ds_read_b128 v[208:211], v244 offset:25344
	global_load_dwordx4 v[102:105], v[74:75], off offset:384
	global_load_dwordx4 v[106:109], v[76:77], off offset:384
	global_load_dwordx4 v[110:113], v[78:79], off offset:384
	global_load_dwordx4 v[114:117], v[80:81], off offset:384
	global_load_dwordx4 v[118:121], v[82:83], off offset:384
	global_load_dwordx4 v[122:125], v[84:85], off offset:384
	global_load_dwordx4 v[126:129], v[86:87], off offset:384
	global_load_dwordx4 v[136:139], v[88:89], off offset:384
	s_waitcnt lgkmcnt(6)
	v_mfma_f32_16x16x32_bf16 v[50:53], v[196:199], v[212:215], v[50:53]
	ds_read_b128 v[228:231], v245 offset:55360
	s_waitcnt lgkmcnt(6)
	v_mfma_f32_16x16x32_bf16 v[54:57], v[196:199], v[216:219], v[54:57]
	ds_read_b128 v[232:235], v245 offset:57664
	s_waitcnt lgkmcnt(6)
	v_mfma_f32_16x16x32_bf16 v[18:21], v[196:199], v[220:223], v[18:21]
	ds_read_b128 v[236:239], v245 offset:59968
	s_waitcnt lgkmcnt(6)
	v_mfma_f32_16x16x32_bf16 v[22:25], v[196:199], v[224:227], v[22:25]
	ds_read_b128 v[240:243], v245 offset:62272
	ds_read_b128 v[196:199], v244 offset:18496
	s_waitcnt lgkmcnt(7)
	v_mfma_f32_16x16x32_bf16 v[58:61], v[200:203], v[212:215], v[58:61]
	v_mfma_f32_16x16x32_bf16 v[62:65], v[200:203], v[216:219], v[62:65]
	v_mfma_f32_16x16x32_bf16 v[26:29], v[200:203], v[220:223], v[26:29]
	v_mfma_f32_16x16x32_bf16 v[30:33], v[200:203], v[224:227], v[30:33]
	ds_read_b128 v[200:203], v244 offset:20800
	s_waitcnt lgkmcnt(7)
	v_mfma_f32_16x16x32_bf16 v[34:37], v[204:207], v[212:215], v[34:37]
	v_mfma_f32_16x16x32_bf16 v[38:41], v[204:207], v[216:219], v[38:41]
	v_mfma_f32_16x16x32_bf16 v[2:5], v[204:207], v[220:223], v[2:5]
	v_mfma_f32_16x16x32_bf16 v[6:9], v[204:207], v[224:227], v[6:9]
	ds_read_b128 v[204:207], v244 offset:23104
	s_setprio 1
	s_waitcnt vmcnt(15)
	ds_write_b128 v98, v[140:143]
	s_waitcnt vmcnt(14)
	ds_write_b128 v98, v[144:147] offset:4608
	s_waitcnt lgkmcnt(9)
	v_mfma_f32_16x16x32_bf16 v[42:45], v[208:211], v[212:215], v[42:45]
	v_mfma_f32_16x16x32_bf16 v[46:49], v[208:211], v[216:219], v[46:49]
	v_mfma_f32_16x16x32_bf16 v[10:13], v[208:211], v[220:223], v[10:13]
	v_mfma_f32_16x16x32_bf16 v[14:17], v[208:211], v[224:227], v[14:17]
	ds_read_b128 v[208:211], v244 offset:25408
	s_waitcnt vmcnt(13)
	ds_write_b128 v98, v[148:151] offset:9216
	s_waitcnt vmcnt(12)
	ds_write_b128 v98, v[152:155] offset:13824
	s_waitcnt lgkmcnt(7)
	v_mfma_f32_16x16x32_bf16 v[50:53], v[196:199], v[228:231], v[50:53]
	v_mfma_f32_16x16x32_bf16 v[54:57], v[196:199], v[232:235], v[54:57]
	v_mfma_f32_16x16x32_bf16 v[18:21], v[196:199], v[236:239], v[18:21]
	v_mfma_f32_16x16x32_bf16 v[22:25], v[196:199], v[240:243], v[22:25]
	s_waitcnt vmcnt(11)
	ds_write_b128 v98, v[156:159] offset:36864
	s_waitcnt vmcnt(10)
	ds_write_b128 v98, v[160:163] offset:41472
	s_waitcnt lgkmcnt(8)
	v_mfma_f32_16x16x32_bf16 v[58:61], v[200:203], v[228:231], v[58:61]
	v_mfma_f32_16x16x32_bf16 v[62:65], v[200:203], v[232:235], v[62:65]
	v_mfma_f32_16x16x32_bf16 v[26:29], v[200:203], v[236:239], v[26:29]
	v_mfma_f32_16x16x32_bf16 v[30:33], v[200:203], v[240:243], v[30:33]
	s_waitcnt vmcnt(9)
	ds_write_b128 v98, v[164:167] offset:46080
	s_waitcnt vmcnt(8)
	ds_write_b128 v98, v[168:171] offset:50688
	s_waitcnt lgkmcnt(0)
	s_barrier
	s_setprio 0
	ds_read_b128 v[212:215], v245 offset:36864
	ds_read_b128 v[196:199], v244
	ds_read_b128 v[216:219], v245 offset:39168
	ds_read_b128 v[220:223], v245 offset:41472
	ds_read_b128 v[224:227], v245 offset:43776
	ds_read_b128 v[200:203], v244 offset:2304
	v_mfma_f32_16x16x32_bf16 v[34:37], v[204:207], v[228:231], v[34:37]
	v_mfma_f32_16x16x32_bf16 v[38:41], v[204:207], v[232:235], v[38:41]
	v_mfma_f32_16x16x32_bf16 v[2:5], v[204:207], v[236:239], v[2:5]
	v_mfma_f32_16x16x32_bf16 v[6:9], v[204:207], v[240:243], v[6:9]
	ds_read_b128 v[204:207], v244 offset:4608
	v_mfma_f32_16x16x32_bf16 v[42:45], v[208:211], v[228:231], v[42:45]
	v_mfma_f32_16x16x32_bf16 v[46:49], v[208:211], v[232:235], v[46:49]
	v_mfma_f32_16x16x32_bf16 v[10:13], v[208:211], v[236:239], v[10:13]
	v_mfma_f32_16x16x32_bf16 v[14:17], v[208:211], v[240:243], v[14:17]
	ds_read_b128 v[208:211], v244 offset:6912
	global_load_dwordx4 v[140:143], v[74:75], off offset:512
	global_load_dwordx4 v[144:147], v[76:77], off offset:512
	global_load_dwordx4 v[148:151], v[78:79], off offset:512
	global_load_dwordx4 v[152:155], v[80:81], off offset:512
	global_load_dwordx4 v[156:159], v[82:83], off offset:512
	global_load_dwordx4 v[160:163], v[84:85], off offset:512
	global_load_dwordx4 v[164:167], v[86:87], off offset:512
	global_load_dwordx4 v[168:171], v[88:89], off offset:512
	s_waitcnt lgkmcnt(6)
	v_mfma_f32_16x16x32_bf16 v[50:53], v[196:199], v[212:215], v[50:53]
	ds_read_b128 v[228:231], v245 offset:36928
	s_waitcnt lgkmcnt(6)
	v_mfma_f32_16x16x32_bf16 v[54:57], v[196:199], v[216:219], v[54:57]
	ds_read_b128 v[232:235], v245 offset:39232
	s_waitcnt lgkmcnt(6)
	v_mfma_f32_16x16x32_bf16 v[18:21], v[196:199], v[220:223], v[18:21]
	ds_read_b128 v[236:239], v245 offset:41536
	s_waitcnt lgkmcnt(6)
	v_mfma_f32_16x16x32_bf16 v[22:25], v[196:199], v[224:227], v[22:25]
	ds_read_b128 v[240:243], v245 offset:43840
	ds_read_b128 v[196:199], v244 offset:64
	s_waitcnt lgkmcnt(7)
	v_mfma_f32_16x16x32_bf16 v[58:61], v[200:203], v[212:215], v[58:61]
	v_mfma_f32_16x16x32_bf16 v[62:65], v[200:203], v[216:219], v[62:65]
	v_mfma_f32_16x16x32_bf16 v[26:29], v[200:203], v[220:223], v[26:29]
	v_mfma_f32_16x16x32_bf16 v[30:33], v[200:203], v[224:227], v[30:33]
	ds_read_b128 v[200:203], v244 offset:2368
	s_waitcnt lgkmcnt(7)
	v_mfma_f32_16x16x32_bf16 v[34:37], v[204:207], v[212:215], v[34:37]
	v_mfma_f32_16x16x32_bf16 v[38:41], v[204:207], v[216:219], v[38:41]
	v_mfma_f32_16x16x32_bf16 v[2:5], v[204:207], v[220:223], v[2:5]
	v_mfma_f32_16x16x32_bf16 v[6:9], v[204:207], v[224:227], v[6:9]
	ds_read_b128 v[204:207], v244 offset:4672
	s_setprio 1
	s_waitcnt vmcnt(15)
	ds_write_b128 v98, v[102:105] offset:18432
	s_waitcnt vmcnt(14)
	ds_write_b128 v98, v[106:109] offset:23040
	s_waitcnt lgkmcnt(9)
	v_mfma_f32_16x16x32_bf16 v[42:45], v[208:211], v[212:215], v[42:45]
	v_mfma_f32_16x16x32_bf16 v[46:49], v[208:211], v[216:219], v[46:49]
	v_mfma_f32_16x16x32_bf16 v[10:13], v[208:211], v[220:223], v[10:13]
	v_mfma_f32_16x16x32_bf16 v[14:17], v[208:211], v[224:227], v[14:17]
	ds_read_b128 v[208:211], v244 offset:6976
	s_waitcnt vmcnt(13)
	ds_write_b128 v98, v[110:113] offset:27648
	s_waitcnt vmcnt(12)
	ds_write_b128 v98, v[114:117] offset:32256
	s_waitcnt lgkmcnt(7)
	v_mfma_f32_16x16x32_bf16 v[50:53], v[196:199], v[228:231], v[50:53]
	v_mfma_f32_16x16x32_bf16 v[54:57], v[196:199], v[232:235], v[54:57]
	v_mfma_f32_16x16x32_bf16 v[18:21], v[196:199], v[236:239], v[18:21]
	v_mfma_f32_16x16x32_bf16 v[22:25], v[196:199], v[240:243], v[22:25]
	s_waitcnt vmcnt(11)
	ds_write_b128 v98, v[118:121] offset:55296
	s_waitcnt vmcnt(10)
	ds_write_b128 v98, v[122:125] offset:59904
	s_waitcnt lgkmcnt(8)
	v_mfma_f32_16x16x32_bf16 v[58:61], v[200:203], v[228:231], v[58:61]
	v_mfma_f32_16x16x32_bf16 v[62:65], v[200:203], v[232:235], v[62:65]
	v_mfma_f32_16x16x32_bf16 v[26:29], v[200:203], v[236:239], v[26:29]
	v_mfma_f32_16x16x32_bf16 v[30:33], v[200:203], v[240:243], v[30:33]
	s_waitcnt vmcnt(9)
	ds_write_b128 v98, v[126:129] offset:64512
	s_waitcnt vmcnt(8)
	ds_write_b128 v99, v[136:139] offset:32256
	s_waitcnt lgkmcnt(0)
	s_barrier
	s_setprio 0
	ds_read_b128 v[212:215], v245 offset:55296
	ds_read_b128 v[196:199], v244 offset:18432
	ds_read_b128 v[216:219], v245 offset:57600
	ds_read_b128 v[220:223], v245 offset:59904
	ds_read_b128 v[224:227], v245 offset:62208
	ds_read_b128 v[200:203], v244 offset:20736
	v_mfma_f32_16x16x32_bf16 v[34:37], v[204:207], v[228:231], v[34:37]
	v_mfma_f32_16x16x32_bf16 v[38:41], v[204:207], v[232:235], v[38:41]
	v_mfma_f32_16x16x32_bf16 v[2:5], v[204:207], v[236:239], v[2:5]
	v_mfma_f32_16x16x32_bf16 v[6:9], v[204:207], v[240:243], v[6:9]
	ds_read_b128 v[204:207], v244 offset:23040
	v_mfma_f32_16x16x32_bf16 v[42:45], v[208:211], v[228:231], v[42:45]
	v_mfma_f32_16x16x32_bf16 v[46:49], v[208:211], v[232:235], v[46:49]
	v_mfma_f32_16x16x32_bf16 v[10:13], v[208:211], v[236:239], v[10:13]
	v_mfma_f32_16x16x32_bf16 v[14:17], v[208:211], v[240:243], v[14:17]
	ds_read_b128 v[208:211], v244 offset:25344
	global_load_dwordx4 v[102:105], v[74:75], off offset:640
	global_load_dwordx4 v[106:109], v[76:77], off offset:640
	global_load_dwordx4 v[110:113], v[78:79], off offset:640
	global_load_dwordx4 v[114:117], v[80:81], off offset:640
	global_load_dwordx4 v[118:121], v[82:83], off offset:640
	global_load_dwordx4 v[122:125], v[84:85], off offset:640
	global_load_dwordx4 v[126:129], v[86:87], off offset:640
	global_load_dwordx4 v[136:139], v[88:89], off offset:640
	s_waitcnt lgkmcnt(6)
	v_mfma_f32_16x16x32_bf16 v[50:53], v[196:199], v[212:215], v[50:53]
	ds_read_b128 v[228:231], v245 offset:55360
	s_waitcnt lgkmcnt(6)
	v_mfma_f32_16x16x32_bf16 v[54:57], v[196:199], v[216:219], v[54:57]
	ds_read_b128 v[232:235], v245 offset:57664
	s_waitcnt lgkmcnt(6)
	v_mfma_f32_16x16x32_bf16 v[18:21], v[196:199], v[220:223], v[18:21]
	ds_read_b128 v[236:239], v245 offset:59968
	s_waitcnt lgkmcnt(6)
	v_mfma_f32_16x16x32_bf16 v[22:25], v[196:199], v[224:227], v[22:25]
	ds_read_b128 v[240:243], v245 offset:62272
	ds_read_b128 v[196:199], v244 offset:18496
	s_waitcnt lgkmcnt(7)
	v_mfma_f32_16x16x32_bf16 v[58:61], v[200:203], v[212:215], v[58:61]
	v_mfma_f32_16x16x32_bf16 v[62:65], v[200:203], v[216:219], v[62:65]
	v_mfma_f32_16x16x32_bf16 v[26:29], v[200:203], v[220:223], v[26:29]
	v_mfma_f32_16x16x32_bf16 v[30:33], v[200:203], v[224:227], v[30:33]
	ds_read_b128 v[200:203], v244 offset:20800
	s_waitcnt lgkmcnt(7)
	v_mfma_f32_16x16x32_bf16 v[34:37], v[204:207], v[212:215], v[34:37]
	v_mfma_f32_16x16x32_bf16 v[38:41], v[204:207], v[216:219], v[38:41]
	v_mfma_f32_16x16x32_bf16 v[2:5], v[204:207], v[220:223], v[2:5]
	v_mfma_f32_16x16x32_bf16 v[6:9], v[204:207], v[224:227], v[6:9]
	ds_read_b128 v[204:207], v244 offset:23104
	s_setprio 1
	s_waitcnt vmcnt(15)
	ds_write_b128 v98, v[140:143]
	s_waitcnt vmcnt(14)
	ds_write_b128 v98, v[144:147] offset:4608
	s_waitcnt lgkmcnt(9)
	v_mfma_f32_16x16x32_bf16 v[42:45], v[208:211], v[212:215], v[42:45]
	v_mfma_f32_16x16x32_bf16 v[46:49], v[208:211], v[216:219], v[46:49]
	v_mfma_f32_16x16x32_bf16 v[10:13], v[208:211], v[220:223], v[10:13]
	v_mfma_f32_16x16x32_bf16 v[14:17], v[208:211], v[224:227], v[14:17]
	ds_read_b128 v[208:211], v244 offset:25408
	s_waitcnt vmcnt(13)
	ds_write_b128 v98, v[148:151] offset:9216
	s_waitcnt vmcnt(12)
	ds_write_b128 v98, v[152:155] offset:13824
	s_waitcnt lgkmcnt(7)
	v_mfma_f32_16x16x32_bf16 v[50:53], v[196:199], v[228:231], v[50:53]
	v_mfma_f32_16x16x32_bf16 v[54:57], v[196:199], v[232:235], v[54:57]
	v_mfma_f32_16x16x32_bf16 v[18:21], v[196:199], v[236:239], v[18:21]
	v_mfma_f32_16x16x32_bf16 v[22:25], v[196:199], v[240:243], v[22:25]
	s_waitcnt vmcnt(11)
	ds_write_b128 v98, v[156:159] offset:36864
	s_waitcnt vmcnt(10)
	ds_write_b128 v98, v[160:163] offset:41472
	s_waitcnt lgkmcnt(8)
	v_mfma_f32_16x16x32_bf16 v[58:61], v[200:203], v[228:231], v[58:61]
	v_mfma_f32_16x16x32_bf16 v[62:65], v[200:203], v[232:235], v[62:65]
	v_mfma_f32_16x16x32_bf16 v[26:29], v[200:203], v[236:239], v[26:29]
	v_mfma_f32_16x16x32_bf16 v[30:33], v[200:203], v[240:243], v[30:33]
	s_waitcnt vmcnt(9)
	ds_write_b128 v98, v[164:167] offset:46080
	s_waitcnt vmcnt(8)
	ds_write_b128 v98, v[168:171] offset:50688
	s_waitcnt lgkmcnt(0)
	s_barrier
	s_setprio 0
	ds_read_b128 v[212:215], v245 offset:36864
	ds_read_b128 v[196:199], v244
	ds_read_b128 v[216:219], v245 offset:39168
	ds_read_b128 v[220:223], v245 offset:41472
	ds_read_b128 v[224:227], v245 offset:43776
	ds_read_b128 v[200:203], v244 offset:2304
	v_mfma_f32_16x16x32_bf16 v[34:37], v[204:207], v[228:231], v[34:37]
	v_mfma_f32_16x16x32_bf16 v[38:41], v[204:207], v[232:235], v[38:41]
	v_mfma_f32_16x16x32_bf16 v[2:5], v[204:207], v[236:239], v[2:5]
	v_mfma_f32_16x16x32_bf16 v[6:9], v[204:207], v[240:243], v[6:9]
	ds_read_b128 v[204:207], v244 offset:4608
	v_mfma_f32_16x16x32_bf16 v[42:45], v[208:211], v[228:231], v[42:45]
	v_mfma_f32_16x16x32_bf16 v[46:49], v[208:211], v[232:235], v[46:49]
	v_mfma_f32_16x16x32_bf16 v[10:13], v[208:211], v[236:239], v[10:13]
	v_mfma_f32_16x16x32_bf16 v[14:17], v[208:211], v[240:243], v[14:17]
	ds_read_b128 v[208:211], v244 offset:6912
	global_load_dwordx4 v[140:143], v[74:75], off offset:768
	global_load_dwordx4 v[144:147], v[76:77], off offset:768
	global_load_dwordx4 v[148:151], v[78:79], off offset:768
	global_load_dwordx4 v[152:155], v[80:81], off offset:768
	global_load_dwordx4 v[156:159], v[82:83], off offset:768
	global_load_dwordx4 v[160:163], v[84:85], off offset:768
	global_load_dwordx4 v[164:167], v[86:87], off offset:768
	global_load_dwordx4 v[168:171], v[88:89], off offset:768
	s_waitcnt lgkmcnt(6)
	v_mfma_f32_16x16x32_bf16 v[50:53], v[196:199], v[212:215], v[50:53]
	ds_read_b128 v[228:231], v245 offset:36928
	s_waitcnt lgkmcnt(6)
	v_mfma_f32_16x16x32_bf16 v[54:57], v[196:199], v[216:219], v[54:57]
	ds_read_b128 v[232:235], v245 offset:39232
	s_waitcnt lgkmcnt(6)
	v_mfma_f32_16x16x32_bf16 v[18:21], v[196:199], v[220:223], v[18:21]
	ds_read_b128 v[236:239], v245 offset:41536
	s_waitcnt lgkmcnt(6)
	v_mfma_f32_16x16x32_bf16 v[22:25], v[196:199], v[224:227], v[22:25]
	ds_read_b128 v[240:243], v245 offset:43840
	ds_read_b128 v[196:199], v244 offset:64
	s_waitcnt lgkmcnt(7)
	v_mfma_f32_16x16x32_bf16 v[58:61], v[200:203], v[212:215], v[58:61]
	v_mfma_f32_16x16x32_bf16 v[62:65], v[200:203], v[216:219], v[62:65]
	v_mfma_f32_16x16x32_bf16 v[26:29], v[200:203], v[220:223], v[26:29]
	v_mfma_f32_16x16x32_bf16 v[30:33], v[200:203], v[224:227], v[30:33]
	ds_read_b128 v[200:203], v244 offset:2368
	s_waitcnt lgkmcnt(7)
	v_mfma_f32_16x16x32_bf16 v[34:37], v[204:207], v[212:215], v[34:37]
	v_mfma_f32_16x16x32_bf16 v[38:41], v[204:207], v[216:219], v[38:41]
	v_mfma_f32_16x16x32_bf16 v[2:5], v[204:207], v[220:223], v[2:5]
	v_mfma_f32_16x16x32_bf16 v[6:9], v[204:207], v[224:227], v[6:9]
	ds_read_b128 v[204:207], v244 offset:4672
	s_setprio 1
	s_waitcnt vmcnt(15)
	ds_write_b128 v98, v[102:105] offset:18432
	s_waitcnt vmcnt(14)
	ds_write_b128 v98, v[106:109] offset:23040
	s_waitcnt lgkmcnt(9)
	v_mfma_f32_16x16x32_bf16 v[42:45], v[208:211], v[212:215], v[42:45]
	v_mfma_f32_16x16x32_bf16 v[46:49], v[208:211], v[216:219], v[46:49]
	v_mfma_f32_16x16x32_bf16 v[10:13], v[208:211], v[220:223], v[10:13]
	v_mfma_f32_16x16x32_bf16 v[14:17], v[208:211], v[224:227], v[14:17]
	ds_read_b128 v[208:211], v244 offset:6976
	s_waitcnt vmcnt(13)
	ds_write_b128 v98, v[110:113] offset:27648
	s_waitcnt vmcnt(12)
	ds_write_b128 v98, v[114:117] offset:32256
	s_waitcnt lgkmcnt(7)
	v_mfma_f32_16x16x32_bf16 v[50:53], v[196:199], v[228:231], v[50:53]
	v_mfma_f32_16x16x32_bf16 v[54:57], v[196:199], v[232:235], v[54:57]
	v_mfma_f32_16x16x32_bf16 v[18:21], v[196:199], v[236:239], v[18:21]
	v_mfma_f32_16x16x32_bf16 v[22:25], v[196:199], v[240:243], v[22:25]
	s_waitcnt vmcnt(11)
	ds_write_b128 v98, v[118:121] offset:55296
	s_waitcnt vmcnt(10)
	ds_write_b128 v98, v[122:125] offset:59904
	s_waitcnt lgkmcnt(8)
	v_mfma_f32_16x16x32_bf16 v[58:61], v[200:203], v[228:231], v[58:61]
	v_mfma_f32_16x16x32_bf16 v[62:65], v[200:203], v[232:235], v[62:65]
	v_mfma_f32_16x16x32_bf16 v[26:29], v[200:203], v[236:239], v[26:29]
	v_mfma_f32_16x16x32_bf16 v[30:33], v[200:203], v[240:243], v[30:33]
	s_waitcnt vmcnt(9)
	ds_write_b128 v98, v[126:129] offset:64512
	s_waitcnt vmcnt(8)
	ds_write_b128 v99, v[136:139] offset:32256
	s_waitcnt lgkmcnt(0)
	s_barrier
	s_setprio 0
	ds_read_b128 v[212:215], v245 offset:55296
	ds_read_b128 v[196:199], v244 offset:18432
	ds_read_b128 v[216:219], v245 offset:57600
	ds_read_b128 v[220:223], v245 offset:59904
	ds_read_b128 v[224:227], v245 offset:62208
	ds_read_b128 v[200:203], v244 offset:20736
	v_mfma_f32_16x16x32_bf16 v[34:37], v[204:207], v[228:231], v[34:37]
	v_mfma_f32_16x16x32_bf16 v[38:41], v[204:207], v[232:235], v[38:41]
	v_mfma_f32_16x16x32_bf16 v[2:5], v[204:207], v[236:239], v[2:5]
	v_mfma_f32_16x16x32_bf16 v[6:9], v[204:207], v[240:243], v[6:9]
	ds_read_b128 v[204:207], v244 offset:23040
	v_mfma_f32_16x16x32_bf16 v[42:45], v[208:211], v[228:231], v[42:45]
	v_mfma_f32_16x16x32_bf16 v[46:49], v[208:211], v[232:235], v[46:49]
	v_mfma_f32_16x16x32_bf16 v[10:13], v[208:211], v[236:239], v[10:13]
	v_mfma_f32_16x16x32_bf16 v[14:17], v[208:211], v[240:243], v[14:17]
	ds_read_b128 v[208:211], v244 offset:25344
	global_load_dwordx4 v[102:105], v[74:75], off offset:896
	global_load_dwordx4 v[106:109], v[76:77], off offset:896
	global_load_dwordx4 v[110:113], v[78:79], off offset:896
	global_load_dwordx4 v[114:117], v[80:81], off offset:896
	global_load_dwordx4 v[118:121], v[82:83], off offset:896
	global_load_dwordx4 v[122:125], v[84:85], off offset:896
	global_load_dwordx4 v[126:129], v[86:87], off offset:896
	global_load_dwordx4 v[136:139], v[88:89], off offset:896
	s_waitcnt lgkmcnt(6)
	v_mfma_f32_16x16x32_bf16 v[50:53], v[196:199], v[212:215], v[50:53]
	ds_read_b128 v[228:231], v245 offset:55360
	s_waitcnt lgkmcnt(6)
	v_mfma_f32_16x16x32_bf16 v[54:57], v[196:199], v[216:219], v[54:57]
	ds_read_b128 v[232:235], v245 offset:57664
	s_waitcnt lgkmcnt(6)
	v_mfma_f32_16x16x32_bf16 v[18:21], v[196:199], v[220:223], v[18:21]
	ds_read_b128 v[236:239], v245 offset:59968
	s_waitcnt lgkmcnt(6)
	v_mfma_f32_16x16x32_bf16 v[22:25], v[196:199], v[224:227], v[22:25]
	ds_read_b128 v[240:243], v245 offset:62272
	ds_read_b128 v[196:199], v244 offset:18496
	s_waitcnt lgkmcnt(7)
	v_mfma_f32_16x16x32_bf16 v[58:61], v[200:203], v[212:215], v[58:61]
	v_mfma_f32_16x16x32_bf16 v[62:65], v[200:203], v[216:219], v[62:65]
	v_mfma_f32_16x16x32_bf16 v[26:29], v[200:203], v[220:223], v[26:29]
	v_mfma_f32_16x16x32_bf16 v[30:33], v[200:203], v[224:227], v[30:33]
	ds_read_b128 v[200:203], v244 offset:20800
	s_waitcnt lgkmcnt(7)
	v_mfma_f32_16x16x32_bf16 v[34:37], v[204:207], v[212:215], v[34:37]
	v_mfma_f32_16x16x32_bf16 v[38:41], v[204:207], v[216:219], v[38:41]
	v_mfma_f32_16x16x32_bf16 v[2:5], v[204:207], v[220:223], v[2:5]
	v_mfma_f32_16x16x32_bf16 v[6:9], v[204:207], v[224:227], v[6:9]
	ds_read_b128 v[204:207], v244 offset:23104
	s_setprio 1
	s_waitcnt vmcnt(15)
	ds_write_b128 v98, v[140:143]
	s_waitcnt vmcnt(14)
	ds_write_b128 v98, v[144:147] offset:4608
	s_waitcnt lgkmcnt(9)
	v_mfma_f32_16x16x32_bf16 v[42:45], v[208:211], v[212:215], v[42:45]
	v_mfma_f32_16x16x32_bf16 v[46:49], v[208:211], v[216:219], v[46:49]
	v_mfma_f32_16x16x32_bf16 v[10:13], v[208:211], v[220:223], v[10:13]
	v_mfma_f32_16x16x32_bf16 v[14:17], v[208:211], v[224:227], v[14:17]
	ds_read_b128 v[208:211], v244 offset:25408
	s_waitcnt vmcnt(13)
	ds_write_b128 v98, v[148:151] offset:9216
	s_waitcnt vmcnt(12)
	ds_write_b128 v98, v[152:155] offset:13824
	s_waitcnt lgkmcnt(7)
	v_mfma_f32_16x16x32_bf16 v[50:53], v[196:199], v[228:231], v[50:53]
	v_mfma_f32_16x16x32_bf16 v[54:57], v[196:199], v[232:235], v[54:57]
	v_mfma_f32_16x16x32_bf16 v[18:21], v[196:199], v[236:239], v[18:21]
	v_mfma_f32_16x16x32_bf16 v[22:25], v[196:199], v[240:243], v[22:25]
	s_waitcnt vmcnt(11)
	ds_write_b128 v98, v[156:159] offset:36864
	s_waitcnt vmcnt(10)
	ds_write_b128 v98, v[160:163] offset:41472
	s_waitcnt lgkmcnt(8)
	v_mfma_f32_16x16x32_bf16 v[58:61], v[200:203], v[228:231], v[58:61]
	v_mfma_f32_16x16x32_bf16 v[62:65], v[200:203], v[232:235], v[62:65]
	v_mfma_f32_16x16x32_bf16 v[26:29], v[200:203], v[236:239], v[26:29]
	v_mfma_f32_16x16x32_bf16 v[30:33], v[200:203], v[240:243], v[30:33]
	s_waitcnt vmcnt(9)
	ds_write_b128 v98, v[164:167] offset:46080
	s_waitcnt vmcnt(8)
	ds_write_b128 v98, v[168:171] offset:50688
	s_waitcnt lgkmcnt(0)
	s_barrier
	s_setprio 0
	ds_read_b128 v[212:215], v245 offset:36864
	ds_read_b128 v[196:199], v244
	ds_read_b128 v[216:219], v245 offset:39168
	ds_read_b128 v[220:223], v245 offset:41472
	ds_read_b128 v[224:227], v245 offset:43776
	ds_read_b128 v[200:203], v244 offset:2304
	v_mfma_f32_16x16x32_bf16 v[34:37], v[204:207], v[228:231], v[34:37]
	v_mfma_f32_16x16x32_bf16 v[38:41], v[204:207], v[232:235], v[38:41]
	v_mfma_f32_16x16x32_bf16 v[2:5], v[204:207], v[236:239], v[2:5]
	v_mfma_f32_16x16x32_bf16 v[6:9], v[204:207], v[240:243], v[6:9]
	ds_read_b128 v[204:207], v244 offset:4608
	v_mfma_f32_16x16x32_bf16 v[42:45], v[208:211], v[228:231], v[42:45]
	v_mfma_f32_16x16x32_bf16 v[46:49], v[208:211], v[232:235], v[46:49]
	v_mfma_f32_16x16x32_bf16 v[10:13], v[208:211], v[236:239], v[10:13]
	v_mfma_f32_16x16x32_bf16 v[14:17], v[208:211], v[240:243], v[14:17]
	ds_read_b128 v[208:211], v244 offset:6912
	global_load_dwordx4 v[140:143], v[74:75], off offset:1024
	global_load_dwordx4 v[144:147], v[76:77], off offset:1024
	global_load_dwordx4 v[148:151], v[78:79], off offset:1024
	global_load_dwordx4 v[152:155], v[80:81], off offset:1024
	global_load_dwordx4 v[156:159], v[82:83], off offset:1024
	global_load_dwordx4 v[160:163], v[84:85], off offset:1024
	global_load_dwordx4 v[164:167], v[86:87], off offset:1024
	global_load_dwordx4 v[168:171], v[88:89], off offset:1024
	s_waitcnt lgkmcnt(6)
	v_mfma_f32_16x16x32_bf16 v[50:53], v[196:199], v[212:215], v[50:53]
	ds_read_b128 v[228:231], v245 offset:36928
	s_waitcnt lgkmcnt(6)
	v_mfma_f32_16x16x32_bf16 v[54:57], v[196:199], v[216:219], v[54:57]
	ds_read_b128 v[232:235], v245 offset:39232
	s_waitcnt lgkmcnt(6)
	v_mfma_f32_16x16x32_bf16 v[18:21], v[196:199], v[220:223], v[18:21]
	ds_read_b128 v[236:239], v245 offset:41536
	s_waitcnt lgkmcnt(6)
	v_mfma_f32_16x16x32_bf16 v[22:25], v[196:199], v[224:227], v[22:25]
	ds_read_b128 v[240:243], v245 offset:43840
	ds_read_b128 v[196:199], v244 offset:64
	s_waitcnt lgkmcnt(7)
	v_mfma_f32_16x16x32_bf16 v[58:61], v[200:203], v[212:215], v[58:61]
	v_mfma_f32_16x16x32_bf16 v[62:65], v[200:203], v[216:219], v[62:65]
	v_mfma_f32_16x16x32_bf16 v[26:29], v[200:203], v[220:223], v[26:29]
	v_mfma_f32_16x16x32_bf16 v[30:33], v[200:203], v[224:227], v[30:33]
	ds_read_b128 v[200:203], v244 offset:2368
	s_waitcnt lgkmcnt(7)
	v_mfma_f32_16x16x32_bf16 v[34:37], v[204:207], v[212:215], v[34:37]
	v_mfma_f32_16x16x32_bf16 v[38:41], v[204:207], v[216:219], v[38:41]
	v_mfma_f32_16x16x32_bf16 v[2:5], v[204:207], v[220:223], v[2:5]
	v_mfma_f32_16x16x32_bf16 v[6:9], v[204:207], v[224:227], v[6:9]
	ds_read_b128 v[204:207], v244 offset:4672
	s_setprio 1
	s_waitcnt vmcnt(15)
	ds_write_b128 v98, v[102:105] offset:18432
	s_waitcnt vmcnt(14)
	ds_write_b128 v98, v[106:109] offset:23040
	s_waitcnt lgkmcnt(9)
	v_mfma_f32_16x16x32_bf16 v[42:45], v[208:211], v[212:215], v[42:45]
	v_mfma_f32_16x16x32_bf16 v[46:49], v[208:211], v[216:219], v[46:49]
	v_mfma_f32_16x16x32_bf16 v[10:13], v[208:211], v[220:223], v[10:13]
	v_mfma_f32_16x16x32_bf16 v[14:17], v[208:211], v[224:227], v[14:17]
	ds_read_b128 v[208:211], v244 offset:6976
	s_waitcnt vmcnt(13)
	ds_write_b128 v98, v[110:113] offset:27648
	s_waitcnt vmcnt(12)
	ds_write_b128 v98, v[114:117] offset:32256
	s_waitcnt lgkmcnt(7)
	v_mfma_f32_16x16x32_bf16 v[50:53], v[196:199], v[228:231], v[50:53]
	v_mfma_f32_16x16x32_bf16 v[54:57], v[196:199], v[232:235], v[54:57]
	v_mfma_f32_16x16x32_bf16 v[18:21], v[196:199], v[236:239], v[18:21]
	v_mfma_f32_16x16x32_bf16 v[22:25], v[196:199], v[240:243], v[22:25]
	s_waitcnt vmcnt(11)
	ds_write_b128 v98, v[118:121] offset:55296
	s_waitcnt vmcnt(10)
	ds_write_b128 v98, v[122:125] offset:59904
	s_waitcnt lgkmcnt(8)
	v_mfma_f32_16x16x32_bf16 v[58:61], v[200:203], v[228:231], v[58:61]
	v_mfma_f32_16x16x32_bf16 v[62:65], v[200:203], v[232:235], v[62:65]
	v_mfma_f32_16x16x32_bf16 v[26:29], v[200:203], v[236:239], v[26:29]
	v_mfma_f32_16x16x32_bf16 v[30:33], v[200:203], v[240:243], v[30:33]
	s_waitcnt vmcnt(9)
	ds_write_b128 v98, v[126:129] offset:64512
	s_waitcnt vmcnt(8)
	ds_write_b128 v99, v[136:139] offset:32256
	s_waitcnt lgkmcnt(0)
	s_barrier
	s_setprio 0
	ds_read_b128 v[212:215], v245 offset:55296
	ds_read_b128 v[196:199], v244 offset:18432
	ds_read_b128 v[216:219], v245 offset:57600
	ds_read_b128 v[220:223], v245 offset:59904
	ds_read_b128 v[224:227], v245 offset:62208
	ds_read_b128 v[200:203], v244 offset:20736
	v_mfma_f32_16x16x32_bf16 v[34:37], v[204:207], v[228:231], v[34:37]
	v_mfma_f32_16x16x32_bf16 v[38:41], v[204:207], v[232:235], v[38:41]
	v_mfma_f32_16x16x32_bf16 v[2:5], v[204:207], v[236:239], v[2:5]
	v_mfma_f32_16x16x32_bf16 v[6:9], v[204:207], v[240:243], v[6:9]
	ds_read_b128 v[204:207], v244 offset:23040
	v_mfma_f32_16x16x32_bf16 v[42:45], v[208:211], v[228:231], v[42:45]
	v_mfma_f32_16x16x32_bf16 v[46:49], v[208:211], v[232:235], v[46:49]
	v_mfma_f32_16x16x32_bf16 v[10:13], v[208:211], v[236:239], v[10:13]
	v_mfma_f32_16x16x32_bf16 v[14:17], v[208:211], v[240:243], v[14:17]
	ds_read_b128 v[208:211], v244 offset:25344
	global_load_dwordx4 v[102:105], v[74:75], off offset:1152
	global_load_dwordx4 v[106:109], v[76:77], off offset:1152
	global_load_dwordx4 v[110:113], v[78:79], off offset:1152
	global_load_dwordx4 v[114:117], v[80:81], off offset:1152
	global_load_dwordx4 v[118:121], v[82:83], off offset:1152
	global_load_dwordx4 v[122:125], v[84:85], off offset:1152
	global_load_dwordx4 v[126:129], v[86:87], off offset:1152
	global_load_dwordx4 v[136:139], v[88:89], off offset:1152
	s_waitcnt lgkmcnt(6)
	v_mfma_f32_16x16x32_bf16 v[50:53], v[196:199], v[212:215], v[50:53]
	ds_read_b128 v[228:231], v245 offset:55360
	s_waitcnt lgkmcnt(6)
	v_mfma_f32_16x16x32_bf16 v[54:57], v[196:199], v[216:219], v[54:57]
	ds_read_b128 v[232:235], v245 offset:57664
	s_waitcnt lgkmcnt(6)
	v_mfma_f32_16x16x32_bf16 v[18:21], v[196:199], v[220:223], v[18:21]
	ds_read_b128 v[236:239], v245 offset:59968
	s_waitcnt lgkmcnt(6)
	v_mfma_f32_16x16x32_bf16 v[22:25], v[196:199], v[224:227], v[22:25]
	ds_read_b128 v[240:243], v245 offset:62272
	ds_read_b128 v[196:199], v244 offset:18496
	s_waitcnt lgkmcnt(7)
	v_mfma_f32_16x16x32_bf16 v[58:61], v[200:203], v[212:215], v[58:61]
	v_mfma_f32_16x16x32_bf16 v[62:65], v[200:203], v[216:219], v[62:65]
	v_mfma_f32_16x16x32_bf16 v[26:29], v[200:203], v[220:223], v[26:29]
	v_mfma_f32_16x16x32_bf16 v[30:33], v[200:203], v[224:227], v[30:33]
	ds_read_b128 v[200:203], v244 offset:20800
	s_waitcnt lgkmcnt(7)
	v_mfma_f32_16x16x32_bf16 v[34:37], v[204:207], v[212:215], v[34:37]
	v_mfma_f32_16x16x32_bf16 v[38:41], v[204:207], v[216:219], v[38:41]
	v_mfma_f32_16x16x32_bf16 v[2:5], v[204:207], v[220:223], v[2:5]
	v_mfma_f32_16x16x32_bf16 v[6:9], v[204:207], v[224:227], v[6:9]
	ds_read_b128 v[204:207], v244 offset:23104
	s_setprio 1
	s_waitcnt vmcnt(15)
	ds_write_b128 v98, v[140:143]
	s_waitcnt vmcnt(14)
	ds_write_b128 v98, v[144:147] offset:4608
	s_waitcnt lgkmcnt(9)
	v_mfma_f32_16x16x32_bf16 v[42:45], v[208:211], v[212:215], v[42:45]
	v_mfma_f32_16x16x32_bf16 v[46:49], v[208:211], v[216:219], v[46:49]
	v_mfma_f32_16x16x32_bf16 v[10:13], v[208:211], v[220:223], v[10:13]
	v_mfma_f32_16x16x32_bf16 v[14:17], v[208:211], v[224:227], v[14:17]
	ds_read_b128 v[208:211], v244 offset:25408
	s_waitcnt vmcnt(13)
	ds_write_b128 v98, v[148:151] offset:9216
	s_waitcnt vmcnt(12)
	ds_write_b128 v98, v[152:155] offset:13824
	s_waitcnt lgkmcnt(7)
	v_mfma_f32_16x16x32_bf16 v[50:53], v[196:199], v[228:231], v[50:53]
	v_mfma_f32_16x16x32_bf16 v[54:57], v[196:199], v[232:235], v[54:57]
	v_mfma_f32_16x16x32_bf16 v[18:21], v[196:199], v[236:239], v[18:21]
	v_mfma_f32_16x16x32_bf16 v[22:25], v[196:199], v[240:243], v[22:25]
	s_waitcnt vmcnt(11)
	ds_write_b128 v98, v[156:159] offset:36864
	s_waitcnt vmcnt(10)
	ds_write_b128 v98, v[160:163] offset:41472
	s_waitcnt lgkmcnt(8)
	v_mfma_f32_16x16x32_bf16 v[58:61], v[200:203], v[228:231], v[58:61]
	v_mfma_f32_16x16x32_bf16 v[62:65], v[200:203], v[232:235], v[62:65]
	v_mfma_f32_16x16x32_bf16 v[26:29], v[200:203], v[236:239], v[26:29]
	v_mfma_f32_16x16x32_bf16 v[30:33], v[200:203], v[240:243], v[30:33]
	s_waitcnt vmcnt(9)
	ds_write_b128 v98, v[164:167] offset:46080
	s_waitcnt vmcnt(8)
	ds_write_b128 v98, v[168:171] offset:50688
	s_waitcnt lgkmcnt(0)
	s_barrier
	s_setprio 0
	ds_read_b128 v[212:215], v245 offset:36864
	ds_read_b128 v[196:199], v244
	ds_read_b128 v[216:219], v245 offset:39168
	ds_read_b128 v[220:223], v245 offset:41472
	ds_read_b128 v[224:227], v245 offset:43776
	ds_read_b128 v[200:203], v244 offset:2304
	v_mfma_f32_16x16x32_bf16 v[34:37], v[204:207], v[228:231], v[34:37]
	v_mfma_f32_16x16x32_bf16 v[38:41], v[204:207], v[232:235], v[38:41]
	v_mfma_f32_16x16x32_bf16 v[2:5], v[204:207], v[236:239], v[2:5]
	v_mfma_f32_16x16x32_bf16 v[6:9], v[204:207], v[240:243], v[6:9]
	ds_read_b128 v[204:207], v244 offset:4608
	v_mfma_f32_16x16x32_bf16 v[42:45], v[208:211], v[228:231], v[42:45]
	v_mfma_f32_16x16x32_bf16 v[46:49], v[208:211], v[232:235], v[46:49]
	v_mfma_f32_16x16x32_bf16 v[10:13], v[208:211], v[236:239], v[10:13]
	v_mfma_f32_16x16x32_bf16 v[14:17], v[208:211], v[240:243], v[14:17]
	ds_read_b128 v[208:211], v244 offset:6912
	global_load_dwordx4 v[140:143], v[74:75], off offset:1280
	global_load_dwordx4 v[144:147], v[76:77], off offset:1280
	global_load_dwordx4 v[148:151], v[78:79], off offset:1280
	global_load_dwordx4 v[152:155], v[80:81], off offset:1280
	global_load_dwordx4 v[156:159], v[82:83], off offset:1280
	global_load_dwordx4 v[160:163], v[84:85], off offset:1280
	global_load_dwordx4 v[164:167], v[86:87], off offset:1280
	global_load_dwordx4 v[168:171], v[88:89], off offset:1280
	s_waitcnt lgkmcnt(6)
	v_mfma_f32_16x16x32_bf16 v[50:53], v[196:199], v[212:215], v[50:53]
	ds_read_b128 v[228:231], v245 offset:36928
	s_waitcnt lgkmcnt(6)
	v_mfma_f32_16x16x32_bf16 v[54:57], v[196:199], v[216:219], v[54:57]
	ds_read_b128 v[232:235], v245 offset:39232
	s_waitcnt lgkmcnt(6)
	v_mfma_f32_16x16x32_bf16 v[18:21], v[196:199], v[220:223], v[18:21]
	ds_read_b128 v[236:239], v245 offset:41536
	s_waitcnt lgkmcnt(6)
	v_mfma_f32_16x16x32_bf16 v[22:25], v[196:199], v[224:227], v[22:25]
	ds_read_b128 v[240:243], v245 offset:43840
	ds_read_b128 v[196:199], v244 offset:64
	s_waitcnt lgkmcnt(7)
	v_mfma_f32_16x16x32_bf16 v[58:61], v[200:203], v[212:215], v[58:61]
	v_mfma_f32_16x16x32_bf16 v[62:65], v[200:203], v[216:219], v[62:65]
	v_mfma_f32_16x16x32_bf16 v[26:29], v[200:203], v[220:223], v[26:29]
	v_mfma_f32_16x16x32_bf16 v[30:33], v[200:203], v[224:227], v[30:33]
	ds_read_b128 v[200:203], v244 offset:2368
	s_waitcnt lgkmcnt(7)
	v_mfma_f32_16x16x32_bf16 v[34:37], v[204:207], v[212:215], v[34:37]
	v_mfma_f32_16x16x32_bf16 v[38:41], v[204:207], v[216:219], v[38:41]
	v_mfma_f32_16x16x32_bf16 v[2:5], v[204:207], v[220:223], v[2:5]
	v_mfma_f32_16x16x32_bf16 v[6:9], v[204:207], v[224:227], v[6:9]
	ds_read_b128 v[204:207], v244 offset:4672
	s_setprio 1
	s_waitcnt vmcnt(15)
	ds_write_b128 v98, v[102:105] offset:18432
	s_waitcnt vmcnt(14)
	ds_write_b128 v98, v[106:109] offset:23040
	s_waitcnt lgkmcnt(9)
	v_mfma_f32_16x16x32_bf16 v[42:45], v[208:211], v[212:215], v[42:45]
	v_mfma_f32_16x16x32_bf16 v[46:49], v[208:211], v[216:219], v[46:49]
	v_mfma_f32_16x16x32_bf16 v[10:13], v[208:211], v[220:223], v[10:13]
	v_mfma_f32_16x16x32_bf16 v[14:17], v[208:211], v[224:227], v[14:17]
	ds_read_b128 v[208:211], v244 offset:6976
	s_waitcnt vmcnt(13)
	ds_write_b128 v98, v[110:113] offset:27648
	s_waitcnt vmcnt(12)
	ds_write_b128 v98, v[114:117] offset:32256
	s_waitcnt lgkmcnt(7)
	v_mfma_f32_16x16x32_bf16 v[50:53], v[196:199], v[228:231], v[50:53]
	v_mfma_f32_16x16x32_bf16 v[54:57], v[196:199], v[232:235], v[54:57]
	v_mfma_f32_16x16x32_bf16 v[18:21], v[196:199], v[236:239], v[18:21]
	v_mfma_f32_16x16x32_bf16 v[22:25], v[196:199], v[240:243], v[22:25]
	s_waitcnt vmcnt(11)
	ds_write_b128 v98, v[118:121] offset:55296
	s_waitcnt vmcnt(10)
	ds_write_b128 v98, v[122:125] offset:59904
	s_waitcnt lgkmcnt(8)
	v_mfma_f32_16x16x32_bf16 v[58:61], v[200:203], v[228:231], v[58:61]
	v_mfma_f32_16x16x32_bf16 v[62:65], v[200:203], v[232:235], v[62:65]
	v_mfma_f32_16x16x32_bf16 v[26:29], v[200:203], v[236:239], v[26:29]
	v_mfma_f32_16x16x32_bf16 v[30:33], v[200:203], v[240:243], v[30:33]
	s_waitcnt vmcnt(9)
	ds_write_b128 v98, v[126:129] offset:64512
	s_waitcnt vmcnt(8)
	ds_write_b128 v99, v[136:139] offset:32256
	s_waitcnt lgkmcnt(0)
	s_barrier
	s_setprio 0
	ds_read_b128 v[212:215], v245 offset:55296
	ds_read_b128 v[196:199], v244 offset:18432
	ds_read_b128 v[216:219], v245 offset:57600
	ds_read_b128 v[220:223], v245 offset:59904
	ds_read_b128 v[224:227], v245 offset:62208
	ds_read_b128 v[200:203], v244 offset:20736
	v_mfma_f32_16x16x32_bf16 v[34:37], v[204:207], v[228:231], v[34:37]
	v_mfma_f32_16x16x32_bf16 v[38:41], v[204:207], v[232:235], v[38:41]
	v_mfma_f32_16x16x32_bf16 v[2:5], v[204:207], v[236:239], v[2:5]
	v_mfma_f32_16x16x32_bf16 v[6:9], v[204:207], v[240:243], v[6:9]
	ds_read_b128 v[204:207], v244 offset:23040
	v_mfma_f32_16x16x32_bf16 v[42:45], v[208:211], v[228:231], v[42:45]
	v_mfma_f32_16x16x32_bf16 v[46:49], v[208:211], v[232:235], v[46:49]
	v_mfma_f32_16x16x32_bf16 v[10:13], v[208:211], v[236:239], v[10:13]
	v_mfma_f32_16x16x32_bf16 v[14:17], v[208:211], v[240:243], v[14:17]
	ds_read_b128 v[208:211], v244 offset:25344
	global_load_dwordx4 v[102:105], v[74:75], off offset:1408
	global_load_dwordx4 v[106:109], v[76:77], off offset:1408
	global_load_dwordx4 v[110:113], v[78:79], off offset:1408
	global_load_dwordx4 v[114:117], v[80:81], off offset:1408
	global_load_dwordx4 v[118:121], v[82:83], off offset:1408
	global_load_dwordx4 v[122:125], v[84:85], off offset:1408
	global_load_dwordx4 v[126:129], v[86:87], off offset:1408
	global_load_dwordx4 v[136:139], v[88:89], off offset:1408
	s_waitcnt lgkmcnt(6)
	v_mfma_f32_16x16x32_bf16 v[50:53], v[196:199], v[212:215], v[50:53]
	ds_read_b128 v[228:231], v245 offset:55360
	s_waitcnt lgkmcnt(6)
	v_mfma_f32_16x16x32_bf16 v[54:57], v[196:199], v[216:219], v[54:57]
	ds_read_b128 v[232:235], v245 offset:57664
	s_waitcnt lgkmcnt(6)
	v_mfma_f32_16x16x32_bf16 v[18:21], v[196:199], v[220:223], v[18:21]
	ds_read_b128 v[236:239], v245 offset:59968
	s_waitcnt lgkmcnt(6)
	v_mfma_f32_16x16x32_bf16 v[22:25], v[196:199], v[224:227], v[22:25]
	ds_read_b128 v[240:243], v245 offset:62272
	ds_read_b128 v[196:199], v244 offset:18496
	s_waitcnt lgkmcnt(7)
	v_mfma_f32_16x16x32_bf16 v[58:61], v[200:203], v[212:215], v[58:61]
	v_mfma_f32_16x16x32_bf16 v[62:65], v[200:203], v[216:219], v[62:65]
	v_mfma_f32_16x16x32_bf16 v[26:29], v[200:203], v[220:223], v[26:29]
	v_mfma_f32_16x16x32_bf16 v[30:33], v[200:203], v[224:227], v[30:33]
	ds_read_b128 v[200:203], v244 offset:20800
	s_waitcnt lgkmcnt(7)
	v_mfma_f32_16x16x32_bf16 v[34:37], v[204:207], v[212:215], v[34:37]
	v_mfma_f32_16x16x32_bf16 v[38:41], v[204:207], v[216:219], v[38:41]
	v_mfma_f32_16x16x32_bf16 v[2:5], v[204:207], v[220:223], v[2:5]
	v_mfma_f32_16x16x32_bf16 v[6:9], v[204:207], v[224:227], v[6:9]
	ds_read_b128 v[204:207], v244 offset:23104
	s_setprio 1
	s_waitcnt vmcnt(15)
	ds_write_b128 v98, v[140:143]
	s_waitcnt vmcnt(14)
	ds_write_b128 v98, v[144:147] offset:4608
	s_waitcnt lgkmcnt(9)
	v_mfma_f32_16x16x32_bf16 v[42:45], v[208:211], v[212:215], v[42:45]
	v_mfma_f32_16x16x32_bf16 v[46:49], v[208:211], v[216:219], v[46:49]
	v_mfma_f32_16x16x32_bf16 v[10:13], v[208:211], v[220:223], v[10:13]
	v_mfma_f32_16x16x32_bf16 v[14:17], v[208:211], v[224:227], v[14:17]
	ds_read_b128 v[208:211], v244 offset:25408
	s_waitcnt vmcnt(13)
	ds_write_b128 v98, v[148:151] offset:9216
	s_waitcnt vmcnt(12)
	ds_write_b128 v98, v[152:155] offset:13824
	s_waitcnt lgkmcnt(7)
	v_mfma_f32_16x16x32_bf16 v[50:53], v[196:199], v[228:231], v[50:53]
	v_mfma_f32_16x16x32_bf16 v[54:57], v[196:199], v[232:235], v[54:57]
	v_mfma_f32_16x16x32_bf16 v[18:21], v[196:199], v[236:239], v[18:21]
	v_mfma_f32_16x16x32_bf16 v[22:25], v[196:199], v[240:243], v[22:25]
	s_waitcnt vmcnt(11)
	ds_write_b128 v98, v[156:159] offset:36864
	s_waitcnt vmcnt(10)
	ds_write_b128 v98, v[160:163] offset:41472
	s_waitcnt lgkmcnt(8)
	v_mfma_f32_16x16x32_bf16 v[58:61], v[200:203], v[228:231], v[58:61]
	v_mfma_f32_16x16x32_bf16 v[62:65], v[200:203], v[232:235], v[62:65]
	v_mfma_f32_16x16x32_bf16 v[26:29], v[200:203], v[236:239], v[26:29]
	v_mfma_f32_16x16x32_bf16 v[30:33], v[200:203], v[240:243], v[30:33]
	s_waitcnt vmcnt(9)
	ds_write_b128 v98, v[164:167] offset:46080
	s_waitcnt vmcnt(8)
	ds_write_b128 v98, v[168:171] offset:50688
	s_waitcnt lgkmcnt(0)
	s_barrier
	s_setprio 0
	ds_read_b128 v[212:215], v245 offset:36864
	ds_read_b128 v[196:199], v244
	ds_read_b128 v[216:219], v245 offset:39168
	ds_read_b128 v[220:223], v245 offset:41472
	ds_read_b128 v[224:227], v245 offset:43776
	ds_read_b128 v[200:203], v244 offset:2304
	v_mfma_f32_16x16x32_bf16 v[34:37], v[204:207], v[228:231], v[34:37]
	v_mfma_f32_16x16x32_bf16 v[38:41], v[204:207], v[232:235], v[38:41]
	v_mfma_f32_16x16x32_bf16 v[2:5], v[204:207], v[236:239], v[2:5]
	v_mfma_f32_16x16x32_bf16 v[6:9], v[204:207], v[240:243], v[6:9]
	ds_read_b128 v[204:207], v244 offset:4608
	v_mfma_f32_16x16x32_bf16 v[42:45], v[208:211], v[228:231], v[42:45]
	v_mfma_f32_16x16x32_bf16 v[46:49], v[208:211], v[232:235], v[46:49]
	v_mfma_f32_16x16x32_bf16 v[10:13], v[208:211], v[236:239], v[10:13]
	v_mfma_f32_16x16x32_bf16 v[14:17], v[208:211], v[240:243], v[14:17]
	ds_read_b128 v[208:211], v244 offset:6912
	global_load_dwordx4 v[140:143], v[74:75], off offset:1536
	global_load_dwordx4 v[144:147], v[76:77], off offset:1536
	global_load_dwordx4 v[148:151], v[78:79], off offset:1536
	global_load_dwordx4 v[152:155], v[80:81], off offset:1536
	global_load_dwordx4 v[156:159], v[82:83], off offset:1536
	global_load_dwordx4 v[160:163], v[84:85], off offset:1536
	global_load_dwordx4 v[164:167], v[86:87], off offset:1536
	global_load_dwordx4 v[168:171], v[88:89], off offset:1536
	s_waitcnt lgkmcnt(6)
	v_mfma_f32_16x16x32_bf16 v[50:53], v[196:199], v[212:215], v[50:53]
	ds_read_b128 v[228:231], v245 offset:36928
	s_waitcnt lgkmcnt(6)
	v_mfma_f32_16x16x32_bf16 v[54:57], v[196:199], v[216:219], v[54:57]
	ds_read_b128 v[232:235], v245 offset:39232
	s_waitcnt lgkmcnt(6)
	v_mfma_f32_16x16x32_bf16 v[18:21], v[196:199], v[220:223], v[18:21]
	ds_read_b128 v[236:239], v245 offset:41536
	s_waitcnt lgkmcnt(6)
	v_mfma_f32_16x16x32_bf16 v[22:25], v[196:199], v[224:227], v[22:25]
	ds_read_b128 v[240:243], v245 offset:43840
	ds_read_b128 v[196:199], v244 offset:64
	s_waitcnt lgkmcnt(7)
	v_mfma_f32_16x16x32_bf16 v[58:61], v[200:203], v[212:215], v[58:61]
	v_mfma_f32_16x16x32_bf16 v[62:65], v[200:203], v[216:219], v[62:65]
	v_mfma_f32_16x16x32_bf16 v[26:29], v[200:203], v[220:223], v[26:29]
	v_mfma_f32_16x16x32_bf16 v[30:33], v[200:203], v[224:227], v[30:33]
	ds_read_b128 v[200:203], v244 offset:2368
	s_waitcnt lgkmcnt(7)
	v_mfma_f32_16x16x32_bf16 v[34:37], v[204:207], v[212:215], v[34:37]
	v_mfma_f32_16x16x32_bf16 v[38:41], v[204:207], v[216:219], v[38:41]
	v_mfma_f32_16x16x32_bf16 v[2:5], v[204:207], v[220:223], v[2:5]
	v_mfma_f32_16x16x32_bf16 v[6:9], v[204:207], v[224:227], v[6:9]
	ds_read_b128 v[204:207], v244 offset:4672
	s_setprio 1
	s_waitcnt vmcnt(15)
	ds_write_b128 v98, v[102:105] offset:18432
	s_waitcnt vmcnt(14)
	ds_write_b128 v98, v[106:109] offset:23040
	s_waitcnt lgkmcnt(9)
	v_mfma_f32_16x16x32_bf16 v[42:45], v[208:211], v[212:215], v[42:45]
	v_mfma_f32_16x16x32_bf16 v[46:49], v[208:211], v[216:219], v[46:49]
	v_mfma_f32_16x16x32_bf16 v[10:13], v[208:211], v[220:223], v[10:13]
	v_mfma_f32_16x16x32_bf16 v[14:17], v[208:211], v[224:227], v[14:17]
	ds_read_b128 v[208:211], v244 offset:6976
	s_waitcnt vmcnt(13)
	ds_write_b128 v98, v[110:113] offset:27648
	s_waitcnt vmcnt(12)
	ds_write_b128 v98, v[114:117] offset:32256
	s_waitcnt lgkmcnt(7)
	v_mfma_f32_16x16x32_bf16 v[50:53], v[196:199], v[228:231], v[50:53]
	v_mfma_f32_16x16x32_bf16 v[54:57], v[196:199], v[232:235], v[54:57]
	v_mfma_f32_16x16x32_bf16 v[18:21], v[196:199], v[236:239], v[18:21]
	v_mfma_f32_16x16x32_bf16 v[22:25], v[196:199], v[240:243], v[22:25]
	s_waitcnt vmcnt(11)
	ds_write_b128 v98, v[118:121] offset:55296
	s_waitcnt vmcnt(10)
	ds_write_b128 v98, v[122:125] offset:59904
	s_waitcnt lgkmcnt(8)
	v_mfma_f32_16x16x32_bf16 v[58:61], v[200:203], v[228:231], v[58:61]
	v_mfma_f32_16x16x32_bf16 v[62:65], v[200:203], v[232:235], v[62:65]
	v_mfma_f32_16x16x32_bf16 v[26:29], v[200:203], v[236:239], v[26:29]
	v_mfma_f32_16x16x32_bf16 v[30:33], v[200:203], v[240:243], v[30:33]
	s_waitcnt vmcnt(9)
	ds_write_b128 v98, v[126:129] offset:64512
	s_waitcnt vmcnt(8)
	ds_write_b128 v99, v[136:139] offset:32256
	s_waitcnt lgkmcnt(0)
	s_barrier
	s_setprio 0
	ds_read_b128 v[212:215], v245 offset:55296
	ds_read_b128 v[196:199], v244 offset:18432
	ds_read_b128 v[216:219], v245 offset:57600
	ds_read_b128 v[220:223], v245 offset:59904
	ds_read_b128 v[224:227], v245 offset:62208
	ds_read_b128 v[200:203], v244 offset:20736
	v_mfma_f32_16x16x32_bf16 v[34:37], v[204:207], v[228:231], v[34:37]
	v_mfma_f32_16x16x32_bf16 v[38:41], v[204:207], v[232:235], v[38:41]
	v_mfma_f32_16x16x32_bf16 v[2:5], v[204:207], v[236:239], v[2:5]
	v_mfma_f32_16x16x32_bf16 v[6:9], v[204:207], v[240:243], v[6:9]
	ds_read_b128 v[204:207], v244 offset:23040
	v_mfma_f32_16x16x32_bf16 v[42:45], v[208:211], v[228:231], v[42:45]
	v_mfma_f32_16x16x32_bf16 v[46:49], v[208:211], v[232:235], v[46:49]
	v_mfma_f32_16x16x32_bf16 v[10:13], v[208:211], v[236:239], v[10:13]
	v_mfma_f32_16x16x32_bf16 v[14:17], v[208:211], v[240:243], v[14:17]
	ds_read_b128 v[208:211], v244 offset:25344
	global_load_dwordx4 v[102:105], v[74:75], off offset:1664
	global_load_dwordx4 v[106:109], v[76:77], off offset:1664
	global_load_dwordx4 v[110:113], v[78:79], off offset:1664
	global_load_dwordx4 v[114:117], v[80:81], off offset:1664
	global_load_dwordx4 v[118:121], v[82:83], off offset:1664
	global_load_dwordx4 v[122:125], v[84:85], off offset:1664
	global_load_dwordx4 v[126:129], v[86:87], off offset:1664
	global_load_dwordx4 v[136:139], v[88:89], off offset:1664
	s_waitcnt lgkmcnt(6)
	v_mfma_f32_16x16x32_bf16 v[50:53], v[196:199], v[212:215], v[50:53]
	ds_read_b128 v[228:231], v245 offset:55360
	s_waitcnt lgkmcnt(6)
	v_mfma_f32_16x16x32_bf16 v[54:57], v[196:199], v[216:219], v[54:57]
	ds_read_b128 v[232:235], v245 offset:57664
	s_waitcnt lgkmcnt(6)
	v_mfma_f32_16x16x32_bf16 v[18:21], v[196:199], v[220:223], v[18:21]
	ds_read_b128 v[236:239], v245 offset:59968
	s_waitcnt lgkmcnt(6)
	v_mfma_f32_16x16x32_bf16 v[22:25], v[196:199], v[224:227], v[22:25]
	ds_read_b128 v[240:243], v245 offset:62272
	ds_read_b128 v[196:199], v244 offset:18496
	s_waitcnt lgkmcnt(7)
	v_mfma_f32_16x16x32_bf16 v[58:61], v[200:203], v[212:215], v[58:61]
	v_mfma_f32_16x16x32_bf16 v[62:65], v[200:203], v[216:219], v[62:65]
	v_mfma_f32_16x16x32_bf16 v[26:29], v[200:203], v[220:223], v[26:29]
	v_mfma_f32_16x16x32_bf16 v[30:33], v[200:203], v[224:227], v[30:33]
	ds_read_b128 v[200:203], v244 offset:20800
	s_waitcnt lgkmcnt(7)
	v_mfma_f32_16x16x32_bf16 v[34:37], v[204:207], v[212:215], v[34:37]
	v_mfma_f32_16x16x32_bf16 v[38:41], v[204:207], v[216:219], v[38:41]
	v_mfma_f32_16x16x32_bf16 v[2:5], v[204:207], v[220:223], v[2:5]
	v_mfma_f32_16x16x32_bf16 v[6:9], v[204:207], v[224:227], v[6:9]
	ds_read_b128 v[204:207], v244 offset:23104
	s_setprio 1
	s_waitcnt vmcnt(15)
	ds_write_b128 v98, v[140:143]
	s_waitcnt vmcnt(14)
	ds_write_b128 v98, v[144:147] offset:4608
	s_waitcnt lgkmcnt(9)
	v_mfma_f32_16x16x32_bf16 v[42:45], v[208:211], v[212:215], v[42:45]
	v_mfma_f32_16x16x32_bf16 v[46:49], v[208:211], v[216:219], v[46:49]
	v_mfma_f32_16x16x32_bf16 v[10:13], v[208:211], v[220:223], v[10:13]
	v_mfma_f32_16x16x32_bf16 v[14:17], v[208:211], v[224:227], v[14:17]
	ds_read_b128 v[208:211], v244 offset:25408
	s_waitcnt vmcnt(13)
	ds_write_b128 v98, v[148:151] offset:9216
	s_waitcnt vmcnt(12)
	ds_write_b128 v98, v[152:155] offset:13824
	s_waitcnt lgkmcnt(7)
	v_mfma_f32_16x16x32_bf16 v[50:53], v[196:199], v[228:231], v[50:53]
	v_mfma_f32_16x16x32_bf16 v[54:57], v[196:199], v[232:235], v[54:57]
	v_mfma_f32_16x16x32_bf16 v[18:21], v[196:199], v[236:239], v[18:21]
	v_mfma_f32_16x16x32_bf16 v[22:25], v[196:199], v[240:243], v[22:25]
	s_waitcnt vmcnt(11)
	ds_write_b128 v98, v[156:159] offset:36864
	s_waitcnt vmcnt(10)
	ds_write_b128 v98, v[160:163] offset:41472
	s_waitcnt lgkmcnt(8)
	v_mfma_f32_16x16x32_bf16 v[58:61], v[200:203], v[228:231], v[58:61]
	v_mfma_f32_16x16x32_bf16 v[62:65], v[200:203], v[232:235], v[62:65]
	v_mfma_f32_16x16x32_bf16 v[26:29], v[200:203], v[236:239], v[26:29]
	v_mfma_f32_16x16x32_bf16 v[30:33], v[200:203], v[240:243], v[30:33]
	s_waitcnt vmcnt(9)
	ds_write_b128 v98, v[164:167] offset:46080
	s_waitcnt vmcnt(8)
	ds_write_b128 v98, v[168:171] offset:50688
	s_waitcnt lgkmcnt(0)
	s_barrier
	s_setprio 0
	ds_read_b128 v[212:215], v245 offset:36864
	ds_read_b128 v[196:199], v244
	ds_read_b128 v[216:219], v245 offset:39168
	ds_read_b128 v[220:223], v245 offset:41472
	ds_read_b128 v[224:227], v245 offset:43776
	ds_read_b128 v[200:203], v244 offset:2304
	v_mfma_f32_16x16x32_bf16 v[34:37], v[204:207], v[228:231], v[34:37]
	v_mfma_f32_16x16x32_bf16 v[38:41], v[204:207], v[232:235], v[38:41]
	v_mfma_f32_16x16x32_bf16 v[2:5], v[204:207], v[236:239], v[2:5]
	v_mfma_f32_16x16x32_bf16 v[6:9], v[204:207], v[240:243], v[6:9]
	ds_read_b128 v[204:207], v244 offset:4608
	v_mfma_f32_16x16x32_bf16 v[42:45], v[208:211], v[228:231], v[42:45]
	v_mfma_f32_16x16x32_bf16 v[46:49], v[208:211], v[232:235], v[46:49]
	v_mfma_f32_16x16x32_bf16 v[10:13], v[208:211], v[236:239], v[10:13]
	v_mfma_f32_16x16x32_bf16 v[14:17], v[208:211], v[240:243], v[14:17]
	ds_read_b128 v[208:211], v244 offset:6912
	global_load_dwordx4 v[140:143], v[74:75], off offset:1792
	global_load_dwordx4 v[144:147], v[76:77], off offset:1792
	global_load_dwordx4 v[148:151], v[78:79], off offset:1792
	global_load_dwordx4 v[152:155], v[80:81], off offset:1792
	global_load_dwordx4 v[156:159], v[82:83], off offset:1792
	global_load_dwordx4 v[160:163], v[84:85], off offset:1792
	global_load_dwordx4 v[164:167], v[86:87], off offset:1792
	global_load_dwordx4 v[168:171], v[88:89], off offset:1792
	s_waitcnt lgkmcnt(6)
	v_mfma_f32_16x16x32_bf16 v[50:53], v[196:199], v[212:215], v[50:53]
	ds_read_b128 v[228:231], v245 offset:36928
	s_waitcnt lgkmcnt(6)
	v_mfma_f32_16x16x32_bf16 v[54:57], v[196:199], v[216:219], v[54:57]
	ds_read_b128 v[232:235], v245 offset:39232
	s_waitcnt lgkmcnt(6)
	v_mfma_f32_16x16x32_bf16 v[18:21], v[196:199], v[220:223], v[18:21]
	ds_read_b128 v[236:239], v245 offset:41536
	s_waitcnt lgkmcnt(6)
	v_mfma_f32_16x16x32_bf16 v[22:25], v[196:199], v[224:227], v[22:25]
	ds_read_b128 v[240:243], v245 offset:43840
	ds_read_b128 v[196:199], v244 offset:64
	s_waitcnt lgkmcnt(7)
	v_mfma_f32_16x16x32_bf16 v[58:61], v[200:203], v[212:215], v[58:61]
	v_mfma_f32_16x16x32_bf16 v[62:65], v[200:203], v[216:219], v[62:65]
	v_mfma_f32_16x16x32_bf16 v[26:29], v[200:203], v[220:223], v[26:29]
	v_mfma_f32_16x16x32_bf16 v[30:33], v[200:203], v[224:227], v[30:33]
	ds_read_b128 v[200:203], v244 offset:2368
	s_waitcnt lgkmcnt(7)
	v_mfma_f32_16x16x32_bf16 v[34:37], v[204:207], v[212:215], v[34:37]
	v_mfma_f32_16x16x32_bf16 v[38:41], v[204:207], v[216:219], v[38:41]
	v_mfma_f32_16x16x32_bf16 v[2:5], v[204:207], v[220:223], v[2:5]
	v_mfma_f32_16x16x32_bf16 v[6:9], v[204:207], v[224:227], v[6:9]
	ds_read_b128 v[204:207], v244 offset:4672
	s_setprio 1
	s_waitcnt vmcnt(15)
	ds_write_b128 v98, v[102:105] offset:18432
	s_waitcnt vmcnt(14)
	ds_write_b128 v98, v[106:109] offset:23040
	s_waitcnt lgkmcnt(9)
	v_mfma_f32_16x16x32_bf16 v[42:45], v[208:211], v[212:215], v[42:45]
	v_mfma_f32_16x16x32_bf16 v[46:49], v[208:211], v[216:219], v[46:49]
	v_mfma_f32_16x16x32_bf16 v[10:13], v[208:211], v[220:223], v[10:13]
	v_mfma_f32_16x16x32_bf16 v[14:17], v[208:211], v[224:227], v[14:17]
	ds_read_b128 v[208:211], v244 offset:6976
	s_waitcnt vmcnt(13)
	ds_write_b128 v98, v[110:113] offset:27648
	s_waitcnt vmcnt(12)
	ds_write_b128 v98, v[114:117] offset:32256
	s_waitcnt lgkmcnt(7)
	v_mfma_f32_16x16x32_bf16 v[50:53], v[196:199], v[228:231], v[50:53]
	v_mfma_f32_16x16x32_bf16 v[54:57], v[196:199], v[232:235], v[54:57]
	v_mfma_f32_16x16x32_bf16 v[18:21], v[196:199], v[236:239], v[18:21]
	v_mfma_f32_16x16x32_bf16 v[22:25], v[196:199], v[240:243], v[22:25]
	s_waitcnt vmcnt(11)
	ds_write_b128 v98, v[118:121] offset:55296
	s_waitcnt vmcnt(10)
	ds_write_b128 v98, v[122:125] offset:59904
	s_waitcnt lgkmcnt(8)
	v_mfma_f32_16x16x32_bf16 v[58:61], v[200:203], v[228:231], v[58:61]
	v_mfma_f32_16x16x32_bf16 v[62:65], v[200:203], v[232:235], v[62:65]
	v_mfma_f32_16x16x32_bf16 v[26:29], v[200:203], v[236:239], v[26:29]
	v_mfma_f32_16x16x32_bf16 v[30:33], v[200:203], v[240:243], v[30:33]
	s_waitcnt vmcnt(9)
	ds_write_b128 v98, v[126:129] offset:64512
	s_waitcnt vmcnt(8)
	ds_write_b128 v99, v[136:139] offset:32256
	s_waitcnt lgkmcnt(0)
	s_barrier
	s_setprio 0
	ds_read_b128 v[212:215], v245 offset:55296
	ds_read_b128 v[196:199], v244 offset:18432
	ds_read_b128 v[216:219], v245 offset:57600
	ds_read_b128 v[220:223], v245 offset:59904
	ds_read_b128 v[224:227], v245 offset:62208
	ds_read_b128 v[200:203], v244 offset:20736
	v_mfma_f32_16x16x32_bf16 v[34:37], v[204:207], v[228:231], v[34:37]
	v_mfma_f32_16x16x32_bf16 v[38:41], v[204:207], v[232:235], v[38:41]
	v_mfma_f32_16x16x32_bf16 v[2:5], v[204:207], v[236:239], v[2:5]
	v_mfma_f32_16x16x32_bf16 v[6:9], v[204:207], v[240:243], v[6:9]
	ds_read_b128 v[204:207], v244 offset:23040
	v_mfma_f32_16x16x32_bf16 v[42:45], v[208:211], v[228:231], v[42:45]
	v_mfma_f32_16x16x32_bf16 v[46:49], v[208:211], v[232:235], v[46:49]
	v_mfma_f32_16x16x32_bf16 v[10:13], v[208:211], v[236:239], v[10:13]
	v_mfma_f32_16x16x32_bf16 v[14:17], v[208:211], v[240:243], v[14:17]
	ds_read_b128 v[208:211], v244 offset:25344
	global_load_dwordx4 v[102:105], v[74:75], off offset:1920
	s_nop 0
	global_load_dwordx4 v[74:77], v[76:77], off offset:1920
	s_nop 0
	global_load_dwordx4 v[106:109], v[78:79], off offset:1920
	s_nop 0
	global_load_dwordx4 v[78:81], v[80:81], off offset:1920
	s_nop 0
	global_load_dwordx4 v[110:113], v[82:83], off offset:1920
	s_nop 0
	global_load_dwordx4 v[82:85], v[84:85], off offset:1920
	s_nop 0
	global_load_dwordx4 v[114:117], v[86:87], off offset:1920
	s_nop 0
	global_load_dwordx4 v[86:89], v[88:89], off offset:1920
	s_waitcnt lgkmcnt(6)
	v_mfma_f32_16x16x32_bf16 v[50:53], v[196:199], v[212:215], v[50:53]
	ds_read_b128 v[228:231], v245 offset:55360
	s_waitcnt lgkmcnt(6)
	v_mfma_f32_16x16x32_bf16 v[54:57], v[196:199], v[216:219], v[54:57]
	ds_read_b128 v[232:235], v245 offset:57664
	s_waitcnt lgkmcnt(6)
	v_mfma_f32_16x16x32_bf16 v[18:21], v[196:199], v[220:223], v[18:21]
	ds_read_b128 v[236:239], v245 offset:59968
	s_waitcnt lgkmcnt(6)
	v_mfma_f32_16x16x32_bf16 v[22:25], v[196:199], v[224:227], v[22:25]
	ds_read_b128 v[240:243], v245 offset:62272
	ds_read_b128 v[196:199], v244 offset:18496
	s_waitcnt lgkmcnt(7)
	v_mfma_f32_16x16x32_bf16 v[58:61], v[200:203], v[212:215], v[58:61]
	v_mfma_f32_16x16x32_bf16 v[62:65], v[200:203], v[216:219], v[62:65]
	v_mfma_f32_16x16x32_bf16 v[26:29], v[200:203], v[220:223], v[26:29]
	v_mfma_f32_16x16x32_bf16 v[30:33], v[200:203], v[224:227], v[30:33]
	ds_read_b128 v[200:203], v244 offset:20800
	s_waitcnt lgkmcnt(7)
	v_mfma_f32_16x16x32_bf16 v[34:37], v[204:207], v[212:215], v[34:37]
	v_mfma_f32_16x16x32_bf16 v[38:41], v[204:207], v[216:219], v[38:41]
	v_mfma_f32_16x16x32_bf16 v[2:5], v[204:207], v[220:223], v[2:5]
	v_mfma_f32_16x16x32_bf16 v[6:9], v[204:207], v[224:227], v[6:9]
	ds_read_b128 v[204:207], v244 offset:23104
	s_setprio 1
	s_waitcnt vmcnt(15)
	ds_write_b128 v98, v[140:143]
	s_waitcnt vmcnt(14)
	ds_write_b128 v98, v[144:147] offset:4608
	s_waitcnt lgkmcnt(9)
	v_mfma_f32_16x16x32_bf16 v[42:45], v[208:211], v[212:215], v[42:45]
	v_mfma_f32_16x16x32_bf16 v[46:49], v[208:211], v[216:219], v[46:49]
	v_mfma_f32_16x16x32_bf16 v[10:13], v[208:211], v[220:223], v[10:13]
	v_mfma_f32_16x16x32_bf16 v[14:17], v[208:211], v[224:227], v[14:17]
	ds_read_b128 v[208:211], v244 offset:25408
	s_waitcnt vmcnt(13)
	ds_write_b128 v98, v[148:151] offset:9216
	s_waitcnt vmcnt(12)
	ds_write_b128 v98, v[152:155] offset:13824
	s_waitcnt lgkmcnt(7)
	v_mfma_f32_16x16x32_bf16 v[50:53], v[196:199], v[228:231], v[50:53]
	v_mfma_f32_16x16x32_bf16 v[54:57], v[196:199], v[232:235], v[54:57]
	v_mfma_f32_16x16x32_bf16 v[18:21], v[196:199], v[236:239], v[18:21]
	v_mfma_f32_16x16x32_bf16 v[22:25], v[196:199], v[240:243], v[22:25]
	s_waitcnt vmcnt(11)
	ds_write_b128 v98, v[156:159] offset:36864
	s_waitcnt vmcnt(10)
	ds_write_b128 v98, v[160:163] offset:41472
	s_waitcnt lgkmcnt(8)
	v_mfma_f32_16x16x32_bf16 v[58:61], v[200:203], v[228:231], v[58:61]
	v_mfma_f32_16x16x32_bf16 v[62:65], v[200:203], v[232:235], v[62:65]
	v_mfma_f32_16x16x32_bf16 v[26:29], v[200:203], v[236:239], v[26:29]
	v_mfma_f32_16x16x32_bf16 v[30:33], v[200:203], v[240:243], v[30:33]
	s_waitcnt vmcnt(9)
	ds_write_b128 v98, v[164:167] offset:46080
	s_waitcnt vmcnt(8)
	ds_write_b128 v98, v[168:171] offset:50688
	s_waitcnt lgkmcnt(0)
	s_barrier
	s_setprio 0
	ds_read_b128 v[212:215], v245 offset:36864
	ds_read_b128 v[196:199], v244
	ds_read_b128 v[216:219], v245 offset:39168
	ds_read_b128 v[220:223], v245 offset:41472
	ds_read_b128 v[224:227], v245 offset:43776
	ds_read_b128 v[200:203], v244 offset:2304
	v_mfma_f32_16x16x32_bf16 v[34:37], v[204:207], v[228:231], v[34:37]
	v_mfma_f32_16x16x32_bf16 v[38:41], v[204:207], v[232:235], v[38:41]
	v_mfma_f32_16x16x32_bf16 v[2:5], v[204:207], v[236:239], v[2:5]
	v_mfma_f32_16x16x32_bf16 v[6:9], v[204:207], v[240:243], v[6:9]
	ds_read_b128 v[204:207], v244 offset:4608
	v_mfma_f32_16x16x32_bf16 v[42:45], v[208:211], v[228:231], v[42:45]
	v_mfma_f32_16x16x32_bf16 v[46:49], v[208:211], v[232:235], v[46:49]
	v_mfma_f32_16x16x32_bf16 v[10:13], v[208:211], v[236:239], v[10:13]
	v_mfma_f32_16x16x32_bf16 v[14:17], v[208:211], v[240:243], v[14:17]
	ds_read_b128 v[208:211], v244 offset:6912
	s_waitcnt lgkmcnt(6)
	v_mfma_f32_16x16x32_bf16 v[50:53], v[196:199], v[212:215], v[50:53]
	ds_read_b128 v[228:231], v245 offset:36928
	s_waitcnt lgkmcnt(6)
	v_mfma_f32_16x16x32_bf16 v[54:57], v[196:199], v[216:219], v[54:57]
	ds_read_b128 v[232:235], v245 offset:39232
	s_waitcnt lgkmcnt(6)
	v_mfma_f32_16x16x32_bf16 v[18:21], v[196:199], v[220:223], v[18:21]
	ds_read_b128 v[236:239], v245 offset:41536
	s_waitcnt lgkmcnt(6)
	v_mfma_f32_16x16x32_bf16 v[22:25], v[196:199], v[224:227], v[22:25]
	ds_read_b128 v[240:243], v245 offset:43840
	ds_read_b128 v[196:199], v244 offset:64
	s_waitcnt lgkmcnt(7)
	v_mfma_f32_16x16x32_bf16 v[58:61], v[200:203], v[212:215], v[58:61]
	v_mfma_f32_16x16x32_bf16 v[62:65], v[200:203], v[216:219], v[62:65]
	v_mfma_f32_16x16x32_bf16 v[26:29], v[200:203], v[220:223], v[26:29]
	v_mfma_f32_16x16x32_bf16 v[30:33], v[200:203], v[224:227], v[30:33]
	ds_read_b128 v[200:203], v244 offset:2368
	s_waitcnt lgkmcnt(7)
	v_mfma_f32_16x16x32_bf16 v[34:37], v[204:207], v[212:215], v[34:37]
	v_mfma_f32_16x16x32_bf16 v[38:41], v[204:207], v[216:219], v[38:41]
	v_mfma_f32_16x16x32_bf16 v[2:5], v[204:207], v[220:223], v[2:5]
	v_mfma_f32_16x16x32_bf16 v[6:9], v[204:207], v[224:227], v[6:9]
	ds_read_b128 v[204:207], v244 offset:4672
	s_setprio 1
	s_waitcnt vmcnt(7)
	ds_write_b128 v98, v[102:105] offset:18432
	s_waitcnt vmcnt(6)
	ds_write_b128 v98, v[74:77] offset:23040
	s_waitcnt lgkmcnt(9)
	v_mfma_f32_16x16x32_bf16 v[42:45], v[208:211], v[212:215], v[42:45]
	v_mfma_f32_16x16x32_bf16 v[46:49], v[208:211], v[216:219], v[46:49]
	v_mfma_f32_16x16x32_bf16 v[10:13], v[208:211], v[220:223], v[10:13]
	v_mfma_f32_16x16x32_bf16 v[14:17], v[208:211], v[224:227], v[14:17]
	ds_read_b128 v[208:211], v244 offset:6976
	s_waitcnt vmcnt(5)
	ds_write_b128 v98, v[106:109] offset:27648
	s_waitcnt vmcnt(4)
	ds_write_b128 v98, v[78:81] offset:32256
	s_waitcnt lgkmcnt(7)
	v_mfma_f32_16x16x32_bf16 v[50:53], v[196:199], v[228:231], v[50:53]
	v_mfma_f32_16x16x32_bf16 v[54:57], v[196:199], v[232:235], v[54:57]
	v_mfma_f32_16x16x32_bf16 v[18:21], v[196:199], v[236:239], v[18:21]
	v_mfma_f32_16x16x32_bf16 v[22:25], v[196:199], v[240:243], v[22:25]
	s_waitcnt vmcnt(3)
	ds_write_b128 v98, v[110:113] offset:55296
	s_waitcnt vmcnt(2)
	ds_write_b128 v98, v[82:85] offset:59904
	s_waitcnt lgkmcnt(8)
	v_mfma_f32_16x16x32_bf16 v[58:61], v[200:203], v[228:231], v[58:61]
	v_mfma_f32_16x16x32_bf16 v[62:65], v[200:203], v[232:235], v[62:65]
	v_mfma_f32_16x16x32_bf16 v[26:29], v[200:203], v[236:239], v[26:29]
	v_mfma_f32_16x16x32_bf16 v[30:33], v[200:203], v[240:243], v[30:33]
	s_waitcnt vmcnt(1)
	ds_write_b128 v98, v[114:117] offset:64512
	s_waitcnt vmcnt(0)
	ds_write_b128 v99, v[86:89] offset:32256
	s_waitcnt lgkmcnt(0)
	s_barrier
	s_setprio 0
	ds_read_b128 v[212:215], v245 offset:55296
	ds_read_b128 v[196:199], v244 offset:18432
	ds_read_b128 v[216:219], v245 offset:57600
	ds_read_b128 v[220:223], v245 offset:59904
	ds_read_b128 v[224:227], v245 offset:62208
	ds_read_b128 v[200:203], v244 offset:20736
	v_mfma_f32_16x16x32_bf16 v[34:37], v[204:207], v[228:231], v[34:37]
	v_mfma_f32_16x16x32_bf16 v[38:41], v[204:207], v[232:235], v[38:41]
	v_mfma_f32_16x16x32_bf16 v[2:5], v[204:207], v[236:239], v[2:5]
	v_mfma_f32_16x16x32_bf16 v[6:9], v[204:207], v[240:243], v[6:9]
	ds_read_b128 v[204:207], v244 offset:23040
	v_mfma_f32_16x16x32_bf16 v[42:45], v[208:211], v[228:231], v[42:45]
	v_mfma_f32_16x16x32_bf16 v[46:49], v[208:211], v[232:235], v[46:49]
	v_mfma_f32_16x16x32_bf16 v[10:13], v[208:211], v[236:239], v[10:13]
	v_mfma_f32_16x16x32_bf16 v[14:17], v[208:211], v[240:243], v[14:17]
	ds_read_b128 v[208:211], v244 offset:25344
	s_waitcnt lgkmcnt(6)
	v_mfma_f32_16x16x32_bf16 v[50:53], v[196:199], v[212:215], v[50:53]
	ds_read_b128 v[228:231], v245 offset:55360
	s_waitcnt lgkmcnt(6)
	v_mfma_f32_16x16x32_bf16 v[54:57], v[196:199], v[216:219], v[54:57]
	ds_read_b128 v[232:235], v245 offset:57664
	s_waitcnt lgkmcnt(6)
	v_mfma_f32_16x16x32_bf16 v[18:21], v[196:199], v[220:223], v[18:21]
	ds_read_b128 v[236:239], v245 offset:59968
	s_waitcnt lgkmcnt(6)
	v_mfma_f32_16x16x32_bf16 v[22:25], v[196:199], v[224:227], v[22:25]
	ds_read_b128 v[240:243], v245 offset:62272
	ds_read_b128 v[196:199], v244 offset:18496
	s_waitcnt lgkmcnt(7)
	v_mfma_f32_16x16x32_bf16 v[58:61], v[200:203], v[212:215], v[58:61]
	v_mfma_f32_16x16x32_bf16 v[62:65], v[200:203], v[216:219], v[62:65]
	v_mfma_f32_16x16x32_bf16 v[26:29], v[200:203], v[220:223], v[26:29]
	v_mfma_f32_16x16x32_bf16 v[30:33], v[200:203], v[224:227], v[30:33]
	ds_read_b128 v[200:203], v244 offset:20800
	s_waitcnt lgkmcnt(7)
	v_mfma_f32_16x16x32_bf16 v[34:37], v[204:207], v[212:215], v[34:37]
	v_mfma_f32_16x16x32_bf16 v[38:41], v[204:207], v[216:219], v[38:41]
	v_mfma_f32_16x16x32_bf16 v[2:5], v[204:207], v[220:223], v[2:5]
	v_mfma_f32_16x16x32_bf16 v[6:9], v[204:207], v[224:227], v[6:9]
	ds_read_b128 v[204:207], v244 offset:23104
	s_waitcnt lgkmcnt(7)
	v_mfma_f32_16x16x32_bf16 v[42:45], v[208:211], v[212:215], v[42:45]
	v_mfma_f32_16x16x32_bf16 v[46:49], v[208:211], v[216:219], v[46:49]
	v_mfma_f32_16x16x32_bf16 v[10:13], v[208:211], v[220:223], v[10:13]
	v_mfma_f32_16x16x32_bf16 v[14:17], v[208:211], v[224:227], v[14:17]
	ds_read_b128 v[208:211], v244 offset:25408
	s_waitcnt lgkmcnt(3)
	v_mfma_f32_16x16x32_bf16 v[50:53], v[196:199], v[228:231], v[50:53]
	v_mfma_f32_16x16x32_bf16 v[54:57], v[196:199], v[232:235], v[54:57]
	v_mfma_f32_16x16x32_bf16 v[18:21], v[196:199], v[236:239], v[18:21]
	v_mfma_f32_16x16x32_bf16 v[22:25], v[196:199], v[240:243], v[22:25]
	s_waitcnt lgkmcnt(2)
	v_mfma_f32_16x16x32_bf16 v[58:61], v[200:203], v[228:231], v[58:61]
	v_mfma_f32_16x16x32_bf16 v[62:65], v[200:203], v[232:235], v[62:65]
	v_mfma_f32_16x16x32_bf16 v[26:29], v[200:203], v[236:239], v[26:29]
	v_mfma_f32_16x16x32_bf16 v[30:33], v[200:203], v[240:243], v[30:33]
	s_lshr_b32 s14, s2, 3
	s_bfe_u32 s13, s2, 0x10002
	s_cmp_lt_i32 s14, 1
	s_mov_b64 s[2:3], -1
	s_waitcnt lgkmcnt(0)
	s_barrier
	v_mfma_f32_16x16x32_bf16 v[34:37], v[204:207], v[228:231], v[34:37]
	v_mfma_f32_16x16x32_bf16 v[38:41], v[204:207], v[232:235], v[38:41]
	v_mfma_f32_16x16x32_bf16 v[2:5], v[204:207], v[236:239], v[2:5]
	v_mfma_f32_16x16x32_bf16 v[6:9], v[204:207], v[240:243], v[6:9]
	v_mfma_f32_16x16x32_bf16 v[42:45], v[208:211], v[228:231], v[42:45]
	v_mfma_f32_16x16x32_bf16 v[46:49], v[208:211], v[232:235], v[46:49]
	v_mfma_f32_16x16x32_bf16 v[10:13], v[208:211], v[236:239], v[10:13]
	v_mfma_f32_16x16x32_bf16 v[14:17], v[208:211], v[240:243], v[14:17]
	s_nop 7
	v_permlane16_swap_b32_e32 v50, v54
	v_permlane16_swap_b32_e32 v51, v55
	v_permlane16_swap_b32_e32 v52, v56
	v_permlane16_swap_b32_e32 v53, v57
	v_permlane16_swap_b32_e32 v58, v62
	v_permlane16_swap_b32_e32 v59, v63
	v_permlane16_swap_b32_e32 v60, v64
	v_permlane16_swap_b32_e32 v61, v65
	v_permlane16_swap_b32_e32 v18, v22
	v_permlane16_swap_b32_e32 v19, v23
	v_permlane16_swap_b32_e32 v20, v24
	v_permlane16_swap_b32_e32 v21, v25
	v_permlane16_swap_b32_e32 v26, v30
	v_permlane16_swap_b32_e32 v27, v31
	v_permlane16_swap_b32_e32 v28, v32
	v_permlane16_swap_b32_e32 v29, v33
	v_permlane16_swap_b32_e32 v34, v38
	v_permlane16_swap_b32_e32 v35, v39
	v_permlane16_swap_b32_e32 v36, v40
	v_permlane16_swap_b32_e32 v37, v41
	v_permlane16_swap_b32_e32 v42, v46
	v_permlane16_swap_b32_e32 v43, v47
	v_permlane16_swap_b32_e32 v44, v48
	v_permlane16_swap_b32_e32 v45, v49
	v_permlane16_swap_b32_e32 v2, v6
	v_permlane16_swap_b32_e32 v3, v7
	v_permlane16_swap_b32_e32 v4, v8
	v_permlane16_swap_b32_e32 v5, v9
	v_permlane16_swap_b32_e32 v10, v14
	v_permlane16_swap_b32_e32 v11, v15
	v_permlane16_swap_b32_e32 v12, v16
	v_permlane16_swap_b32_e32 v13, v17
	v_permlane32_swap_b32_e32 v50, v54
	v_permlane32_swap_b32_e32 v51, v55
	v_permlane32_swap_b32_e32 v52, v56
	v_permlane32_swap_b32_e32 v53, v57
	v_permlane32_swap_b32_e32 v58, v62
	v_permlane32_swap_b32_e32 v59, v63
	v_permlane32_swap_b32_e32 v60, v64
	v_permlane32_swap_b32_e32 v61, v65
	v_permlane32_swap_b32_e32 v18, v22
	v_permlane32_swap_b32_e32 v19, v23
	v_permlane32_swap_b32_e32 v20, v24
	v_permlane32_swap_b32_e32 v21, v25
	v_permlane32_swap_b32_e32 v26, v30
	v_permlane32_swap_b32_e32 v27, v31
	v_permlane32_swap_b32_e32 v28, v32
	v_permlane32_swap_b32_e32 v29, v33
	v_permlane32_swap_b32_e32 v34, v38
	v_permlane32_swap_b32_e32 v35, v39
	v_permlane32_swap_b32_e32 v36, v40
	v_permlane32_swap_b32_e32 v37, v41
	v_permlane32_swap_b32_e32 v42, v46
	v_permlane32_swap_b32_e32 v43, v47
	v_permlane32_swap_b32_e32 v44, v48
	v_permlane32_swap_b32_e32 v45, v49
	v_permlane32_swap_b32_e32 v2, v6
	v_permlane32_swap_b32_e32 v3, v7
	v_permlane32_swap_b32_e32 v4, v8
	v_permlane32_swap_b32_e32 v5, v9
	v_permlane32_swap_b32_e32 v10, v14
	v_permlane32_swap_b32_e32 v11, v15
	v_permlane32_swap_b32_e32 v12, v16
	v_permlane32_swap_b32_e32 v13, v17
	s_cbranch_scc1 .LBB0_755
	s_and_b32 s2, 0xffff, s14
	s_cmp_lg_u32 s2, 1
	s_mov_b64 s[2:3], -1
	s_cbranch_scc0 .LBB0_752
	s_cmp_eq_u32 s13, 0
	s_cselect_b32 s12, 3, 10
	s_mov_b64 s[2:3], 0

.LBB0_828:
	s_lshr_b32 s8, s0, 2
	s_lshl_b32 s0, s0, 7
	s_and_b32 s7, s0, 0x180
	v_or_b32_e32 v2, s7, v93
	v_lshlrev_b32_e32 v74, 10, v2
	s_add_i32 s8, s8, s4
	v_lshl_add_u64 v[66:67], v[76:77], 0, v[74:75]
	v_add_lshl_u32 v74, s7, v94, 10
	s_lshl_b32 s0, s8, 7
	v_lshl_add_u64 v[68:69], v[76:77], 0, v[74:75]
	v_add_lshl_u32 v74, s7, v95, 10
	v_lshl_add_u64 v[70:71], v[76:77], 0, v[74:75]
	v_add_lshl_u32 v74, s7, v96, 10
	v_or_b32_e32 v2, s0, v93
	v_lshl_add_u64 v[72:73], v[76:77], 0, v[74:75]
	v_lshlrev_b32_e32 v74, 10, v2
	v_lshl_add_u64 v[84:85], v[78:79], 0, v[74:75]
	v_add_lshl_u32 v74, s0, v94, 10
	v_lshl_add_u64 v[86:87], v[78:79], 0, v[74:75]
	v_add_lshl_u32 v74, s0, v95, 10
	v_lshl_add_u64 v[88:89], v[78:79], 0, v[74:75]
	v_add_lshl_u32 v74, s0, v96, 10
	v_lshl_add_u64 v[90:91], v[78:79], 0, v[74:75]
	global_load_dwordx4 v[2:5], v[66:67], off
	global_load_dwordx4 v[6:9], v[68:69], off
	global_load_dwordx4 v[10:13], v[70:71], off
	global_load_dwordx4 v[14:17], v[72:73], off
	global_load_dwordx4 v[18:21], v[84:85], off
	global_load_dwordx4 v[22:25], v[86:87], off
	global_load_dwordx4 v[26:29], v[88:89], off
	global_load_dwordx4 v[30:33], v[90:91], off
	global_load_dwordx4 v[102:105], v[66:67], off offset:128
	global_load_dwordx4 v[106:109], v[68:69], off offset:128
	global_load_dwordx4 v[110:113], v[70:71], off offset:128
	global_load_dwordx4 v[114:117], v[72:73], off offset:128
	global_load_dwordx4 v[118:121], v[84:85], off offset:128
	global_load_dwordx4 v[122:125], v[86:87], off offset:128
	global_load_dwordx4 v[126:129], v[88:89], off offset:128
	global_load_dwordx4 v[136:139], v[90:91], off offset:128
	s_setprio 1
	s_waitcnt vmcnt(15)
	ds_write_b128 v100, v[2:5]
	s_waitcnt vmcnt(14)
	ds_write_b128 v100, v[6:9] offset:4608
	s_waitcnt vmcnt(13)
	ds_write_b128 v100, v[10:13] offset:9216
	s_waitcnt vmcnt(12)
	ds_write_b128 v100, v[14:17] offset:13824
	s_waitcnt vmcnt(11)
	ds_write_b128 v100, v[18:21] offset:36864
	s_waitcnt vmcnt(10)
	ds_write_b128 v100, v[22:25] offset:41472
	s_waitcnt vmcnt(9)
	ds_write_b128 v100, v[26:29] offset:46080
	s_waitcnt vmcnt(8)
	ds_write_b128 v100, v[30:33] offset:50688
	s_waitcnt lgkmcnt(0)
	s_barrier
	s_setprio 0
	global_load_dwordx4 v[140:143], v[66:67], off offset:256
	global_load_dwordx4 v[144:147], v[68:69], off offset:256
	global_load_dwordx4 v[148:151], v[70:71], off offset:256
	global_load_dwordx4 v[152:155], v[72:73], off offset:256
	global_load_dwordx4 v[156:159], v[84:85], off offset:256
	global_load_dwordx4 v[160:163], v[86:87], off offset:256
	global_load_dwordx4 v[164:167], v[88:89], off offset:256
	global_load_dwordx4 v[168:171], v[90:91], off offset:256
	v_and_b32_e32 v246, 15, v1
	v_add_u32_e32 v246, 4, v246
	v_bfe_u32 v246, v246, 3, 1
	v_bfe_u32 v249, v1, 4, 2
	v_xor_b32_e32 v246, v246, v249
	v_bfe_u32 v249, v1, 5, 1
	v_sub_u32_e32 v246, v246, v249
	v_lshlrev_b32_e32 v246, 4, v246
	v_bfe_u32 v249, v1, 4, 1
	v_mul_u32_u24_e32 v249, 0x900, v249
	v_sub_u32_e32 v246, v246, v249
	v_add_u32_e32 v244, v246, v98
	v_add_u32_e32 v245, v246, v99
	ds_read_b128 v[212:215], v245 offset:36864
	ds_read_b128 v[196:199], v244
	ds_read_b128 v[216:219], v245 offset:39168
	ds_read_b128 v[220:223], v245 offset:41472
	ds_read_b128 v[224:227], v245 offset:43776
	ds_read_b128 v[200:203], v244 offset:2304
	ds_read_b128 v[204:207], v244 offset:4608
	ds_read_b128 v[208:211], v244 offset:6912
	s_waitcnt lgkmcnt(6)
	v_mfma_f32_16x16x32_bf16 v[50:53], v[196:199], v[212:215], 0
	ds_read_b128 v[228:231], v245 offset:36928
	s_waitcnt lgkmcnt(6)
	v_mfma_f32_16x16x32_bf16 v[54:57], v[196:199], v[216:219], 0
	ds_read_b128 v[232:235], v245 offset:39232
	s_waitcnt lgkmcnt(6)
	v_mfma_f32_16x16x32_bf16 v[18:21], v[196:199], v[220:223], 0
	ds_read_b128 v[236:239], v245 offset:41536
	s_waitcnt lgkmcnt(6)
	v_mfma_f32_16x16x32_bf16 v[22:25], v[196:199], v[224:227], 0
	ds_read_b128 v[240:243], v245 offset:43840
	ds_read_b128 v[196:199], v244 offset:64
	s_waitcnt lgkmcnt(7)
	v_mfma_f32_16x16x32_bf16 v[58:61], v[200:203], v[212:215], 0
	v_mfma_f32_16x16x32_bf16 v[62:65], v[200:203], v[216:219], 0
	v_mfma_f32_16x16x32_bf16 v[26:29], v[200:203], v[220:223], 0
	v_mfma_f32_16x16x32_bf16 v[30:33], v[200:203], v[224:227], 0
	ds_read_b128 v[200:203], v244 offset:2368
	s_waitcnt lgkmcnt(7)
	v_mfma_f32_16x16x32_bf16 v[34:37], v[204:207], v[212:215], 0
	v_mfma_f32_16x16x32_bf16 v[38:41], v[204:207], v[216:219], 0
	v_mfma_f32_16x16x32_bf16 v[2:5], v[204:207], v[220:223], 0
	v_mfma_f32_16x16x32_bf16 v[6:9], v[204:207], v[224:227], 0
	ds_read_b128 v[204:207], v244 offset:4672
	s_setprio 1
	s_waitcnt vmcnt(15)
	ds_write_b128 v100, v[102:105] offset:18432
	s_waitcnt vmcnt(14)
	ds_write_b128 v100, v[106:109] offset:23040
	s_waitcnt lgkmcnt(9)
	v_mfma_f32_16x16x32_bf16 v[42:45], v[208:211], v[212:215], 0
	v_mfma_f32_16x16x32_bf16 v[46:49], v[208:211], v[216:219], 0
	v_mfma_f32_16x16x32_bf16 v[10:13], v[208:211], v[220:223], 0
	v_mfma_f32_16x16x32_bf16 v[14:17], v[208:211], v[224:227], 0
	ds_read_b128 v[208:211], v244 offset:6976
	s_waitcnt vmcnt(13)
	ds_write_b128 v100, v[110:113] offset:27648
	s_waitcnt vmcnt(12)
	ds_write_b128 v100, v[114:117] offset:32256
	s_waitcnt lgkmcnt(7)
	v_mfma_f32_16x16x32_bf16 v[50:53], v[196:199], v[228:231], v[50:53]
	v_mfma_f32_16x16x32_bf16 v[54:57], v[196:199], v[232:235], v[54:57]
	v_mfma_f32_16x16x32_bf16 v[18:21], v[196:199], v[236:239], v[18:21]
	v_mfma_f32_16x16x32_bf16 v[22:25], v[196:199], v[240:243], v[22:25]
	s_waitcnt vmcnt(11)
	ds_write_b128 v100, v[118:121] offset:55296
	s_waitcnt vmcnt(10)
	ds_write_b128 v100, v[122:125] offset:59904
	s_waitcnt lgkmcnt(8)
	v_mfma_f32_16x16x32_bf16 v[58:61], v[200:203], v[228:231], v[58:61]
	v_mfma_f32_16x16x32_bf16 v[62:65], v[200:203], v[232:235], v[62:65]
	v_mfma_f32_16x16x32_bf16 v[26:29], v[200:203], v[236:239], v[26:29]
	v_mfma_f32_16x16x32_bf16 v[30:33], v[200:203], v[240:243], v[30:33]
	s_waitcnt vmcnt(9)
	ds_write_b128 v100, v[126:129] offset:64512
	s_waitcnt vmcnt(8)
	ds_write_b128 v101, v[136:139] offset:32256
	s_waitcnt lgkmcnt(0)
	s_barrier
	s_setprio 0
	ds_read_b128 v[212:215], v245 offset:55296
	ds_read_b128 v[196:199], v244 offset:18432
	ds_read_b128 v[216:219], v245 offset:57600
	ds_read_b128 v[220:223], v245 offset:59904
	ds_read_b128 v[224:227], v245 offset:62208
	ds_read_b128 v[200:203], v244 offset:20736
	v_mfma_f32_16x16x32_bf16 v[34:37], v[204:207], v[228:231], v[34:37]
	v_mfma_f32_16x16x32_bf16 v[38:41], v[204:207], v[232:235], v[38:41]
	v_mfma_f32_16x16x32_bf16 v[2:5], v[204:207], v[236:239], v[2:5]
	v_mfma_f32_16x16x32_bf16 v[6:9], v[204:207], v[240:243], v[6:9]
	ds_read_b128 v[204:207], v244 offset:23040
	v_mfma_f32_16x16x32_bf16 v[42:45], v[208:211], v[228:231], v[42:45]
	v_mfma_f32_16x16x32_bf16 v[46:49], v[208:211], v[232:235], v[46:49]
	v_mfma_f32_16x16x32_bf16 v[10:13], v[208:211], v[236:239], v[10:13]
	v_mfma_f32_16x16x32_bf16 v[14:17], v[208:211], v[240:243], v[14:17]
	ds_read_b128 v[208:211], v244 offset:25344
	global_load_dwordx4 v[102:105], v[66:67], off offset:384
	global_load_dwordx4 v[106:109], v[68:69], off offset:384
	global_load_dwordx4 v[110:113], v[70:71], off offset:384
	global_load_dwordx4 v[114:117], v[72:73], off offset:384
	global_load_dwordx4 v[118:121], v[84:85], off offset:384
	global_load_dwordx4 v[122:125], v[86:87], off offset:384
	global_load_dwordx4 v[126:129], v[88:89], off offset:384
	global_load_dwordx4 v[136:139], v[90:91], off offset:384
	s_waitcnt lgkmcnt(6)
	v_mfma_f32_16x16x32_bf16 v[50:53], v[196:199], v[212:215], v[50:53]
	ds_read_b128 v[228:231], v245 offset:55360
	s_waitcnt lgkmcnt(6)
	v_mfma_f32_16x16x32_bf16 v[54:57], v[196:199], v[216:219], v[54:57]
	ds_read_b128 v[232:235], v245 offset:57664
	s_waitcnt lgkmcnt(6)
	v_mfma_f32_16x16x32_bf16 v[18:21], v[196:199], v[220:223], v[18:21]
	ds_read_b128 v[236:239], v245 offset:59968
	s_waitcnt lgkmcnt(6)
	v_mfma_f32_16x16x32_bf16 v[22:25], v[196:199], v[224:227], v[22:25]
	ds_read_b128 v[240:243], v245 offset:62272
	ds_read_b128 v[196:199], v244 offset:18496
	s_waitcnt lgkmcnt(7)
	v_mfma_f32_16x16x32_bf16 v[58:61], v[200:203], v[212:215], v[58:61]
	v_mfma_f32_16x16x32_bf16 v[62:65], v[200:203], v[216:219], v[62:65]
	v_mfma_f32_16x16x32_bf16 v[26:29], v[200:203], v[220:223], v[26:29]
	v_mfma_f32_16x16x32_bf16 v[30:33], v[200:203], v[224:227], v[30:33]
	ds_read_b128 v[200:203], v244 offset:20800
	s_waitcnt lgkmcnt(7)
	v_mfma_f32_16x16x32_bf16 v[34:37], v[204:207], v[212:215], v[34:37]
	v_mfma_f32_16x16x32_bf16 v[38:41], v[204:207], v[216:219], v[38:41]
	v_mfma_f32_16x16x32_bf16 v[2:5], v[204:207], v[220:223], v[2:5]
	v_mfma_f32_16x16x32_bf16 v[6:9], v[204:207], v[224:227], v[6:9]
	ds_read_b128 v[204:207], v244 offset:23104
	s_setprio 1
	s_waitcnt vmcnt(15)
	ds_write_b128 v100, v[140:143]
	s_waitcnt vmcnt(14)
	ds_write_b128 v100, v[144:147] offset:4608
	s_waitcnt lgkmcnt(9)
	v_mfma_f32_16x16x32_bf16 v[42:45], v[208:211], v[212:215], v[42:45]
	v_mfma_f32_16x16x32_bf16 v[46:49], v[208:211], v[216:219], v[46:49]
	v_mfma_f32_16x16x32_bf16 v[10:13], v[208:211], v[220:223], v[10:13]
	v_mfma_f32_16x16x32_bf16 v[14:17], v[208:211], v[224:227], v[14:17]
	ds_read_b128 v[208:211], v244 offset:25408
	s_waitcnt vmcnt(13)
	ds_write_b128 v100, v[148:151] offset:9216
	s_waitcnt vmcnt(12)
	ds_write_b128 v100, v[152:155] offset:13824
	s_waitcnt lgkmcnt(7)
	v_mfma_f32_16x16x32_bf16 v[50:53], v[196:199], v[228:231], v[50:53]
	v_mfma_f32_16x16x32_bf16 v[54:57], v[196:199], v[232:235], v[54:57]
	v_mfma_f32_16x16x32_bf16 v[18:21], v[196:199], v[236:239], v[18:21]
	v_mfma_f32_16x16x32_bf16 v[22:25], v[196:199], v[240:243], v[22:25]
	s_waitcnt vmcnt(11)
	ds_write_b128 v100, v[156:159] offset:36864
	s_waitcnt vmcnt(10)
	ds_write_b128 v100, v[160:163] offset:41472
	s_waitcnt lgkmcnt(8)
	v_mfma_f32_16x16x32_bf16 v[58:61], v[200:203], v[228:231], v[58:61]
	v_mfma_f32_16x16x32_bf16 v[62:65], v[200:203], v[232:235], v[62:65]
	v_mfma_f32_16x16x32_bf16 v[26:29], v[200:203], v[236:239], v[26:29]
	v_mfma_f32_16x16x32_bf16 v[30:33], v[200:203], v[240:243], v[30:33]
	s_waitcnt vmcnt(9)
	ds_write_b128 v100, v[164:167] offset:46080
	s_waitcnt vmcnt(8)
	ds_write_b128 v100, v[168:171] offset:50688
	s_waitcnt lgkmcnt(0)
	s_barrier
	s_setprio 0
	ds_read_b128 v[212:215], v245 offset:36864
	ds_read_b128 v[196:199], v244
	ds_read_b128 v[216:219], v245 offset:39168
	ds_read_b128 v[220:223], v245 offset:41472
	ds_read_b128 v[224:227], v245 offset:43776
	ds_read_b128 v[200:203], v244 offset:2304
	v_mfma_f32_16x16x32_bf16 v[34:37], v[204:207], v[228:231], v[34:37]
	v_mfma_f32_16x16x32_bf16 v[38:41], v[204:207], v[232:235], v[38:41]
	v_mfma_f32_16x16x32_bf16 v[2:5], v[204:207], v[236:239], v[2:5]
	v_mfma_f32_16x16x32_bf16 v[6:9], v[204:207], v[240:243], v[6:9]
	ds_read_b128 v[204:207], v244 offset:4608
	v_mfma_f32_16x16x32_bf16 v[42:45], v[208:211], v[228:231], v[42:45]
	v_mfma_f32_16x16x32_bf16 v[46:49], v[208:211], v[232:235], v[46:49]
	v_mfma_f32_16x16x32_bf16 v[10:13], v[208:211], v[236:239], v[10:13]
	v_mfma_f32_16x16x32_bf16 v[14:17], v[208:211], v[240:243], v[14:17]
	ds_read_b128 v[208:211], v244 offset:6912
	global_load_dwordx4 v[140:143], v[66:67], off offset:512
	global_load_dwordx4 v[144:147], v[68:69], off offset:512
	global_load_dwordx4 v[148:151], v[70:71], off offset:512
	global_load_dwordx4 v[152:155], v[72:73], off offset:512
	global_load_dwordx4 v[156:159], v[84:85], off offset:512
	global_load_dwordx4 v[160:163], v[86:87], off offset:512
	global_load_dwordx4 v[164:167], v[88:89], off offset:512
	global_load_dwordx4 v[168:171], v[90:91], off offset:512
	s_waitcnt lgkmcnt(6)
	v_mfma_f32_16x16x32_bf16 v[50:53], v[196:199], v[212:215], v[50:53]
	ds_read_b128 v[228:231], v245 offset:36928
	s_waitcnt lgkmcnt(6)
	v_mfma_f32_16x16x32_bf16 v[54:57], v[196:199], v[216:219], v[54:57]
	ds_read_b128 v[232:235], v245 offset:39232
	s_waitcnt lgkmcnt(6)
	v_mfma_f32_16x16x32_bf16 v[18:21], v[196:199], v[220:223], v[18:21]
	ds_read_b128 v[236:239], v245 offset:41536
	s_waitcnt lgkmcnt(6)
	v_mfma_f32_16x16x32_bf16 v[22:25], v[196:199], v[224:227], v[22:25]
	ds_read_b128 v[240:243], v245 offset:43840
	ds_read_b128 v[196:199], v244 offset:64
	s_waitcnt lgkmcnt(7)
	v_mfma_f32_16x16x32_bf16 v[58:61], v[200:203], v[212:215], v[58:61]
	v_mfma_f32_16x16x32_bf16 v[62:65], v[200:203], v[216:219], v[62:65]
	v_mfma_f32_16x16x32_bf16 v[26:29], v[200:203], v[220:223], v[26:29]
	v_mfma_f32_16x16x32_bf16 v[30:33], v[200:203], v[224:227], v[30:33]
	ds_read_b128 v[200:203], v244 offset:2368
	s_waitcnt lgkmcnt(7)
	v_mfma_f32_16x16x32_bf16 v[34:37], v[204:207], v[212:215], v[34:37]
	v_mfma_f32_16x16x32_bf16 v[38:41], v[204:207], v[216:219], v[38:41]
	v_mfma_f32_16x16x32_bf16 v[2:5], v[204:207], v[220:223], v[2:5]
	v_mfma_f32_16x16x32_bf16 v[6:9], v[204:207], v[224:227], v[6:9]
	ds_read_b128 v[204:207], v244 offset:4672
	s_setprio 1
	s_waitcnt vmcnt(15)
	ds_write_b128 v100, v[102:105] offset:18432
	s_waitcnt vmcnt(14)
	ds_write_b128 v100, v[106:109] offset:23040
	s_waitcnt lgkmcnt(9)
	v_mfma_f32_16x16x32_bf16 v[42:45], v[208:211], v[212:215], v[42:45]
	v_mfma_f32_16x16x32_bf16 v[46:49], v[208:211], v[216:219], v[46:49]
	v_mfma_f32_16x16x32_bf16 v[10:13], v[208:211], v[220:223], v[10:13]
	v_mfma_f32_16x16x32_bf16 v[14:17], v[208:211], v[224:227], v[14:17]
	ds_read_b128 v[208:211], v244 offset:6976
	s_waitcnt vmcnt(13)
	ds_write_b128 v100, v[110:113] offset:27648
	s_waitcnt vmcnt(12)
	ds_write_b128 v100, v[114:117] offset:32256
	s_waitcnt lgkmcnt(7)
	v_mfma_f32_16x16x32_bf16 v[50:53], v[196:199], v[228:231], v[50:53]
	v_mfma_f32_16x16x32_bf16 v[54:57], v[196:199], v[232:235], v[54:57]
	v_mfma_f32_16x16x32_bf16 v[18:21], v[196:199], v[236:239], v[18:21]
	v_mfma_f32_16x16x32_bf16 v[22:25], v[196:199], v[240:243], v[22:25]
	s_waitcnt vmcnt(11)
	ds_write_b128 v100, v[118:121] offset:55296
	s_waitcnt vmcnt(10)
	ds_write_b128 v100, v[122:125] offset:59904
	s_waitcnt lgkmcnt(8)
	v_mfma_f32_16x16x32_bf16 v[58:61], v[200:203], v[228:231], v[58:61]
	v_mfma_f32_16x16x32_bf16 v[62:65], v[200:203], v[232:235], v[62:65]
	v_mfma_f32_16x16x32_bf16 v[26:29], v[200:203], v[236:239], v[26:29]
	v_mfma_f32_16x16x32_bf16 v[30:33], v[200:203], v[240:243], v[30:33]
	s_waitcnt vmcnt(9)
	ds_write_b128 v100, v[126:129] offset:64512
	s_waitcnt vmcnt(8)
	ds_write_b128 v101, v[136:139] offset:32256
	s_waitcnt lgkmcnt(0)
	s_barrier
	s_setprio 0
	ds_read_b128 v[212:215], v245 offset:55296
	ds_read_b128 v[196:199], v244 offset:18432
	ds_read_b128 v[216:219], v245 offset:57600
	ds_read_b128 v[220:223], v245 offset:59904
	ds_read_b128 v[224:227], v245 offset:62208
	ds_read_b128 v[200:203], v244 offset:20736
	v_mfma_f32_16x16x32_bf16 v[34:37], v[204:207], v[228:231], v[34:37]
	v_mfma_f32_16x16x32_bf16 v[38:41], v[204:207], v[232:235], v[38:41]
	v_mfma_f32_16x16x32_bf16 v[2:5], v[204:207], v[236:239], v[2:5]
	v_mfma_f32_16x16x32_bf16 v[6:9], v[204:207], v[240:243], v[6:9]
	ds_read_b128 v[204:207], v244 offset:23040
	v_mfma_f32_16x16x32_bf16 v[42:45], v[208:211], v[228:231], v[42:45]
	v_mfma_f32_16x16x32_bf16 v[46:49], v[208:211], v[232:235], v[46:49]
	v_mfma_f32_16x16x32_bf16 v[10:13], v[208:211], v[236:239], v[10:13]
	v_mfma_f32_16x16x32_bf16 v[14:17], v[208:211], v[240:243], v[14:17]
	ds_read_b128 v[208:211], v244 offset:25344
	global_load_dwordx4 v[102:105], v[66:67], off offset:640
	global_load_dwordx4 v[106:109], v[68:69], off offset:640
	global_load_dwordx4 v[110:113], v[70:71], off offset:640
	global_load_dwordx4 v[114:117], v[72:73], off offset:640
	global_load_dwordx4 v[118:121], v[84:85], off offset:640
	global_load_dwordx4 v[122:125], v[86:87], off offset:640
	global_load_dwordx4 v[126:129], v[88:89], off offset:640
	global_load_dwordx4 v[136:139], v[90:91], off offset:640
	s_waitcnt lgkmcnt(6)
	v_mfma_f32_16x16x32_bf16 v[50:53], v[196:199], v[212:215], v[50:53]
	ds_read_b128 v[228:231], v245 offset:55360
	s_waitcnt lgkmcnt(6)
	v_mfma_f32_16x16x32_bf16 v[54:57], v[196:199], v[216:219], v[54:57]
	ds_read_b128 v[232:235], v245 offset:57664
	s_waitcnt lgkmcnt(6)
	v_mfma_f32_16x16x32_bf16 v[18:21], v[196:199], v[220:223], v[18:21]
	ds_read_b128 v[236:239], v245 offset:59968
	s_waitcnt lgkmcnt(6)
	v_mfma_f32_16x16x32_bf16 v[22:25], v[196:199], v[224:227], v[22:25]
	ds_read_b128 v[240:243], v245 offset:62272
	ds_read_b128 v[196:199], v244 offset:18496
	s_waitcnt lgkmcnt(7)
	v_mfma_f32_16x16x32_bf16 v[58:61], v[200:203], v[212:215], v[58:61]
	v_mfma_f32_16x16x32_bf16 v[62:65], v[200:203], v[216:219], v[62:65]
	v_mfma_f32_16x16x32_bf16 v[26:29], v[200:203], v[220:223], v[26:29]
	v_mfma_f32_16x16x32_bf16 v[30:33], v[200:203], v[224:227], v[30:33]
	ds_read_b128 v[200:203], v244 offset:20800
	s_waitcnt lgkmcnt(7)
	v_mfma_f32_16x16x32_bf16 v[34:37], v[204:207], v[212:215], v[34:37]
	v_mfma_f32_16x16x32_bf16 v[38:41], v[204:207], v[216:219], v[38:41]
	v_mfma_f32_16x16x32_bf16 v[2:5], v[204:207], v[220:223], v[2:5]
	v_mfma_f32_16x16x32_bf16 v[6:9], v[204:207], v[224:227], v[6:9]
	ds_read_b128 v[204:207], v244 offset:23104
	s_setprio 1
	s_waitcnt vmcnt(15)
	ds_write_b128 v100, v[140:143]
	s_waitcnt vmcnt(14)
	ds_write_b128 v100, v[144:147] offset:4608
	s_waitcnt lgkmcnt(9)
	v_mfma_f32_16x16x32_bf16 v[42:45], v[208:211], v[212:215], v[42:45]
	v_mfma_f32_16x16x32_bf16 v[46:49], v[208:211], v[216:219], v[46:49]
	v_mfma_f32_16x16x32_bf16 v[10:13], v[208:211], v[220:223], v[10:13]
	v_mfma_f32_16x16x32_bf16 v[14:17], v[208:211], v[224:227], v[14:17]
	ds_read_b128 v[208:211], v244 offset:25408
	s_waitcnt vmcnt(13)
	ds_write_b128 v100, v[148:151] offset:9216
	s_waitcnt vmcnt(12)
	ds_write_b128 v100, v[152:155] offset:13824
	s_waitcnt lgkmcnt(7)
	v_mfma_f32_16x16x32_bf16 v[50:53], v[196:199], v[228:231], v[50:53]
	v_mfma_f32_16x16x32_bf16 v[54:57], v[196:199], v[232:235], v[54:57]
	v_mfma_f32_16x16x32_bf16 v[18:21], v[196:199], v[236:239], v[18:21]
	v_mfma_f32_16x16x32_bf16 v[22:25], v[196:199], v[240:243], v[22:25]
	s_waitcnt vmcnt(11)
	ds_write_b128 v100, v[156:159] offset:36864
	s_waitcnt vmcnt(10)
	ds_write_b128 v100, v[160:163] offset:41472
	s_waitcnt lgkmcnt(8)
	v_mfma_f32_16x16x32_bf16 v[58:61], v[200:203], v[228:231], v[58:61]
	v_mfma_f32_16x16x32_bf16 v[62:65], v[200:203], v[232:235], v[62:65]
	v_mfma_f32_16x16x32_bf16 v[26:29], v[200:203], v[236:239], v[26:29]
	v_mfma_f32_16x16x32_bf16 v[30:33], v[200:203], v[240:243], v[30:33]
	s_waitcnt vmcnt(9)
	ds_write_b128 v100, v[164:167] offset:46080
	s_waitcnt vmcnt(8)
	ds_write_b128 v100, v[168:171] offset:50688
	s_waitcnt lgkmcnt(0)
	s_barrier
	s_setprio 0
	ds_read_b128 v[212:215], v245 offset:36864
	ds_read_b128 v[196:199], v244
	ds_read_b128 v[216:219], v245 offset:39168
	ds_read_b128 v[220:223], v245 offset:41472
	ds_read_b128 v[224:227], v245 offset:43776
	ds_read_b128 v[200:203], v244 offset:2304
	v_mfma_f32_16x16x32_bf16 v[34:37], v[204:207], v[228:231], v[34:37]
	v_mfma_f32_16x16x32_bf16 v[38:41], v[204:207], v[232:235], v[38:41]
	v_mfma_f32_16x16x32_bf16 v[2:5], v[204:207], v[236:239], v[2:5]
	v_mfma_f32_16x16x32_bf16 v[6:9], v[204:207], v[240:243], v[6:9]
	ds_read_b128 v[204:207], v244 offset:4608
	v_mfma_f32_16x16x32_bf16 v[42:45], v[208:211], v[228:231], v[42:45]
	v_mfma_f32_16x16x32_bf16 v[46:49], v[208:211], v[232:235], v[46:49]
	v_mfma_f32_16x16x32_bf16 v[10:13], v[208:211], v[236:239], v[10:13]
	v_mfma_f32_16x16x32_bf16 v[14:17], v[208:211], v[240:243], v[14:17]
	ds_read_b128 v[208:211], v244 offset:6912
	global_load_dwordx4 v[140:143], v[66:67], off offset:768
	global_load_dwordx4 v[144:147], v[68:69], off offset:768
	global_load_dwordx4 v[148:151], v[70:71], off offset:768
	global_load_dwordx4 v[152:155], v[72:73], off offset:768
	global_load_dwordx4 v[156:159], v[84:85], off offset:768
	global_load_dwordx4 v[160:163], v[86:87], off offset:768
	global_load_dwordx4 v[164:167], v[88:89], off offset:768
	global_load_dwordx4 v[168:171], v[90:91], off offset:768
	s_waitcnt lgkmcnt(6)
	v_mfma_f32_16x16x32_bf16 v[50:53], v[196:199], v[212:215], v[50:53]
	ds_read_b128 v[228:231], v245 offset:36928
	s_waitcnt lgkmcnt(6)
	v_mfma_f32_16x16x32_bf16 v[54:57], v[196:199], v[216:219], v[54:57]
	ds_read_b128 v[232:235], v245 offset:39232
	s_waitcnt lgkmcnt(6)
	v_mfma_f32_16x16x32_bf16 v[18:21], v[196:199], v[220:223], v[18:21]
	ds_read_b128 v[236:239], v245 offset:41536
	s_waitcnt lgkmcnt(6)
	v_mfma_f32_16x16x32_bf16 v[22:25], v[196:199], v[224:227], v[22:25]
	ds_read_b128 v[240:243], v245 offset:43840
	ds_read_b128 v[196:199], v244 offset:64
	s_waitcnt lgkmcnt(7)
	v_mfma_f32_16x16x32_bf16 v[58:61], v[200:203], v[212:215], v[58:61]
	v_mfma_f32_16x16x32_bf16 v[62:65], v[200:203], v[216:219], v[62:65]
	v_mfma_f32_16x16x32_bf16 v[26:29], v[200:203], v[220:223], v[26:29]
	v_mfma_f32_16x16x32_bf16 v[30:33], v[200:203], v[224:227], v[30:33]
	ds_read_b128 v[200:203], v244 offset:2368
	s_waitcnt lgkmcnt(7)
	v_mfma_f32_16x16x32_bf16 v[34:37], v[204:207], v[212:215], v[34:37]
	v_mfma_f32_16x16x32_bf16 v[38:41], v[204:207], v[216:219], v[38:41]
	v_mfma_f32_16x16x32_bf16 v[2:5], v[204:207], v[220:223], v[2:5]
	v_mfma_f32_16x16x32_bf16 v[6:9], v[204:207], v[224:227], v[6:9]
	ds_read_b128 v[204:207], v244 offset:4672
	s_setprio 1
	s_waitcnt vmcnt(15)
	ds_write_b128 v100, v[102:105] offset:18432
	s_waitcnt vmcnt(14)
	ds_write_b128 v100, v[106:109] offset:23040
	s_waitcnt lgkmcnt(9)
	v_mfma_f32_16x16x32_bf16 v[42:45], v[208:211], v[212:215], v[42:45]
	v_mfma_f32_16x16x32_bf16 v[46:49], v[208:211], v[216:219], v[46:49]
	v_mfma_f32_16x16x32_bf16 v[10:13], v[208:211], v[220:223], v[10:13]
	v_mfma_f32_16x16x32_bf16 v[14:17], v[208:211], v[224:227], v[14:17]
	ds_read_b128 v[208:211], v244 offset:6976
	s_waitcnt vmcnt(13)
	ds_write_b128 v100, v[110:113] offset:27648
	s_waitcnt vmcnt(12)
	ds_write_b128 v100, v[114:117] offset:32256
	s_waitcnt lgkmcnt(7)
	v_mfma_f32_16x16x32_bf16 v[50:53], v[196:199], v[228:231], v[50:53]
	v_mfma_f32_16x16x32_bf16 v[54:57], v[196:199], v[232:235], v[54:57]
	v_mfma_f32_16x16x32_bf16 v[18:21], v[196:199], v[236:239], v[18:21]
	v_mfma_f32_16x16x32_bf16 v[22:25], v[196:199], v[240:243], v[22:25]
	s_waitcnt vmcnt(11)
	ds_write_b128 v100, v[118:121] offset:55296
	s_waitcnt vmcnt(10)
	ds_write_b128 v100, v[122:125] offset:59904
	s_waitcnt lgkmcnt(8)
	v_mfma_f32_16x16x32_bf16 v[58:61], v[200:203], v[228:231], v[58:61]
	v_mfma_f32_16x16x32_bf16 v[62:65], v[200:203], v[232:235], v[62:65]
	v_mfma_f32_16x16x32_bf16 v[26:29], v[200:203], v[236:239], v[26:29]
	v_mfma_f32_16x16x32_bf16 v[30:33], v[200:203], v[240:243], v[30:33]
	s_waitcnt vmcnt(9)
	ds_write_b128 v100, v[126:129] offset:64512
	s_waitcnt vmcnt(8)
	ds_write_b128 v101, v[136:139] offset:32256
	s_waitcnt lgkmcnt(0)
	s_barrier
	s_setprio 0
	ds_read_b128 v[212:215], v245 offset:55296
	ds_read_b128 v[196:199], v244 offset:18432
	ds_read_b128 v[216:219], v245 offset:57600
	ds_read_b128 v[220:223], v245 offset:59904
	ds_read_b128 v[224:227], v245 offset:62208
	ds_read_b128 v[200:203], v244 offset:20736
	v_mfma_f32_16x16x32_bf16 v[34:37], v[204:207], v[228:231], v[34:37]
	v_mfma_f32_16x16x32_bf16 v[38:41], v[204:207], v[232:235], v[38:41]
	v_mfma_f32_16x16x32_bf16 v[2:5], v[204:207], v[236:239], v[2:5]
	v_mfma_f32_16x16x32_bf16 v[6:9], v[204:207], v[240:243], v[6:9]
	ds_read_b128 v[204:207], v244 offset:23040
	v_mfma_f32_16x16x32_bf16 v[42:45], v[208:211], v[228:231], v[42:45]
	v_mfma_f32_16x16x32_bf16 v[46:49], v[208:211], v[232:235], v[46:49]
	v_mfma_f32_16x16x32_bf16 v[10:13], v[208:211], v[236:239], v[10:13]
	v_mfma_f32_16x16x32_bf16 v[14:17], v[208:211], v[240:243], v[14:17]
	ds_read_b128 v[208:211], v244 offset:25344
	global_load_dwordx4 v[102:105], v[66:67], off offset:896
	s_nop 0
	global_load_dwordx4 v[66:69], v[68:69], off offset:896
	s_nop 0
	global_load_dwordx4 v[106:109], v[70:71], off offset:896
	s_nop 0
	global_load_dwordx4 v[70:73], v[72:73], off offset:896
	s_nop 0
	global_load_dwordx4 v[110:113], v[84:85], off offset:896
	s_nop 0
	global_load_dwordx4 v[84:87], v[86:87], off offset:896
	s_nop 0
	global_load_dwordx4 v[114:117], v[88:89], off offset:896
	s_nop 0
	global_load_dwordx4 v[88:91], v[90:91], off offset:896
	s_waitcnt lgkmcnt(6)
	v_mfma_f32_16x16x32_bf16 v[50:53], v[196:199], v[212:215], v[50:53]
	ds_read_b128 v[228:231], v245 offset:55360
	s_waitcnt lgkmcnt(6)
	v_mfma_f32_16x16x32_bf16 v[54:57], v[196:199], v[216:219], v[54:57]
	ds_read_b128 v[232:235], v245 offset:57664
	s_waitcnt lgkmcnt(6)
	v_mfma_f32_16x16x32_bf16 v[18:21], v[196:199], v[220:223], v[18:21]
	ds_read_b128 v[236:239], v245 offset:59968
	s_waitcnt lgkmcnt(6)
	v_mfma_f32_16x16x32_bf16 v[22:25], v[196:199], v[224:227], v[22:25]
	ds_read_b128 v[240:243], v245 offset:62272
	ds_read_b128 v[196:199], v244 offset:18496
	s_waitcnt lgkmcnt(7)
	v_mfma_f32_16x16x32_bf16 v[58:61], v[200:203], v[212:215], v[58:61]
	v_mfma_f32_16x16x32_bf16 v[62:65], v[200:203], v[216:219], v[62:65]
	v_mfma_f32_16x16x32_bf16 v[26:29], v[200:203], v[220:223], v[26:29]
	v_mfma_f32_16x16x32_bf16 v[30:33], v[200:203], v[224:227], v[30:33]
	ds_read_b128 v[200:203], v244 offset:20800
	s_waitcnt lgkmcnt(7)
	v_mfma_f32_16x16x32_bf16 v[34:37], v[204:207], v[212:215], v[34:37]
	v_mfma_f32_16x16x32_bf16 v[38:41], v[204:207], v[216:219], v[38:41]
	v_mfma_f32_16x16x32_bf16 v[2:5], v[204:207], v[220:223], v[2:5]
	v_mfma_f32_16x16x32_bf16 v[6:9], v[204:207], v[224:227], v[6:9]
	ds_read_b128 v[204:207], v244 offset:23104
	s_setprio 1
	s_waitcnt vmcnt(15)
	ds_write_b128 v100, v[140:143]
	s_waitcnt vmcnt(14)
	ds_write_b128 v100, v[144:147] offset:4608
	s_waitcnt lgkmcnt(9)
	v_mfma_f32_16x16x32_bf16 v[42:45], v[208:211], v[212:215], v[42:45]
	v_mfma_f32_16x16x32_bf16 v[46:49], v[208:211], v[216:219], v[46:49]
	v_mfma_f32_16x16x32_bf16 v[10:13], v[208:211], v[220:223], v[10:13]
	v_mfma_f32_16x16x32_bf16 v[14:17], v[208:211], v[224:227], v[14:17]
	ds_read_b128 v[208:211], v244 offset:25408
	s_waitcnt vmcnt(13)
	ds_write_b128 v100, v[148:151] offset:9216
	s_waitcnt vmcnt(12)
	ds_write_b128 v100, v[152:155] offset:13824
	s_waitcnt lgkmcnt(7)
	v_mfma_f32_16x16x32_bf16 v[50:53], v[196:199], v[228:231], v[50:53]
	v_mfma_f32_16x16x32_bf16 v[54:57], v[196:199], v[232:235], v[54:57]
	v_mfma_f32_16x16x32_bf16 v[18:21], v[196:199], v[236:239], v[18:21]
	v_mfma_f32_16x16x32_bf16 v[22:25], v[196:199], v[240:243], v[22:25]
	s_waitcnt vmcnt(11)
	ds_write_b128 v100, v[156:159] offset:36864
	s_waitcnt vmcnt(10)
	ds_write_b128 v100, v[160:163] offset:41472
	s_waitcnt lgkmcnt(8)
	v_mfma_f32_16x16x32_bf16 v[58:61], v[200:203], v[228:231], v[58:61]
	v_mfma_f32_16x16x32_bf16 v[62:65], v[200:203], v[232:235], v[62:65]
	v_mfma_f32_16x16x32_bf16 v[26:29], v[200:203], v[236:239], v[26:29]
	v_mfma_f32_16x16x32_bf16 v[30:33], v[200:203], v[240:243], v[30:33]
	s_waitcnt vmcnt(9)
	ds_write_b128 v100, v[164:167] offset:46080
	s_waitcnt vmcnt(8)
	ds_write_b128 v100, v[168:171] offset:50688
	s_waitcnt lgkmcnt(0)
	s_barrier
	s_setprio 0
	ds_read_b128 v[212:215], v245 offset:36864
	ds_read_b128 v[196:199], v244
	ds_read_b128 v[216:219], v245 offset:39168
	ds_read_b128 v[220:223], v245 offset:41472
	ds_read_b128 v[224:227], v245 offset:43776
	ds_read_b128 v[200:203], v244 offset:2304
	v_mfma_f32_16x16x32_bf16 v[34:37], v[204:207], v[228:231], v[34:37]
	v_mfma_f32_16x16x32_bf16 v[38:41], v[204:207], v[232:235], v[38:41]
	v_mfma_f32_16x16x32_bf16 v[2:5], v[204:207], v[236:239], v[2:5]
	v_mfma_f32_16x16x32_bf16 v[6:9], v[204:207], v[240:243], v[6:9]
	ds_read_b128 v[204:207], v244 offset:4608
	v_mfma_f32_16x16x32_bf16 v[42:45], v[208:211], v[228:231], v[42:45]
	v_mfma_f32_16x16x32_bf16 v[46:49], v[208:211], v[232:235], v[46:49]
	v_mfma_f32_16x16x32_bf16 v[10:13], v[208:211], v[236:239], v[10:13]
	v_mfma_f32_16x16x32_bf16 v[14:17], v[208:211], v[240:243], v[14:17]
	ds_read_b128 v[208:211], v244 offset:6912
	s_waitcnt lgkmcnt(6)
	v_mfma_f32_16x16x32_bf16 v[50:53], v[196:199], v[212:215], v[50:53]
	ds_read_b128 v[228:231], v245 offset:36928
	s_waitcnt lgkmcnt(6)
	v_mfma_f32_16x16x32_bf16 v[54:57], v[196:199], v[216:219], v[54:57]
	ds_read_b128 v[232:235], v245 offset:39232
	s_waitcnt lgkmcnt(6)
	v_mfma_f32_16x16x32_bf16 v[18:21], v[196:199], v[220:223], v[18:21]
	ds_read_b128 v[236:239], v245 offset:41536
	s_waitcnt lgkmcnt(6)
	v_mfma_f32_16x16x32_bf16 v[22:25], v[196:199], v[224:227], v[22:25]
	ds_read_b128 v[240:243], v245 offset:43840
	ds_read_b128 v[196:199], v244 offset:64
	s_waitcnt lgkmcnt(7)
	v_mfma_f32_16x16x32_bf16 v[58:61], v[200:203], v[212:215], v[58:61]
	v_mfma_f32_16x16x32_bf16 v[62:65], v[200:203], v[216:219], v[62:65]
	v_mfma_f32_16x16x32_bf16 v[26:29], v[200:203], v[220:223], v[26:29]
	v_mfma_f32_16x16x32_bf16 v[30:33], v[200:203], v[224:227], v[30:33]
	ds_read_b128 v[200:203], v244 offset:2368
	s_waitcnt lgkmcnt(7)
	v_mfma_f32_16x16x32_bf16 v[34:37], v[204:207], v[212:215], v[34:37]
	v_mfma_f32_16x16x32_bf16 v[38:41], v[204:207], v[216:219], v[38:41]
	v_mfma_f32_16x16x32_bf16 v[2:5], v[204:207], v[220:223], v[2:5]
	v_mfma_f32_16x16x32_bf16 v[6:9], v[204:207], v[224:227], v[6:9]
	ds_read_b128 v[204:207], v244 offset:4672
	s_setprio 1
	s_waitcnt vmcnt(7)
	ds_write_b128 v100, v[102:105] offset:18432
	s_waitcnt vmcnt(6)
	ds_write_b128 v100, v[66:69] offset:23040
	s_waitcnt lgkmcnt(9)
	v_mfma_f32_16x16x32_bf16 v[42:45], v[208:211], v[212:215], v[42:45]
	v_mfma_f32_16x16x32_bf16 v[46:49], v[208:211], v[216:219], v[46:49]
	v_mfma_f32_16x16x32_bf16 v[10:13], v[208:211], v[220:223], v[10:13]
	v_mfma_f32_16x16x32_bf16 v[14:17], v[208:211], v[224:227], v[14:17]
	ds_read_b128 v[208:211], v244 offset:6976
	s_waitcnt vmcnt(5)
	ds_write_b128 v100, v[106:109] offset:27648
	s_waitcnt vmcnt(4)
	ds_write_b128 v100, v[70:73] offset:32256
	s_waitcnt lgkmcnt(7)
	v_mfma_f32_16x16x32_bf16 v[50:53], v[196:199], v[228:231], v[50:53]
	v_mfma_f32_16x16x32_bf16 v[54:57], v[196:199], v[232:235], v[54:57]
	v_mfma_f32_16x16x32_bf16 v[18:21], v[196:199], v[236:239], v[18:21]
	v_mfma_f32_16x16x32_bf16 v[22:25], v[196:199], v[240:243], v[22:25]
	s_waitcnt vmcnt(3)
	ds_write_b128 v100, v[110:113] offset:55296
	s_waitcnt vmcnt(2)
	ds_write_b128 v100, v[84:87] offset:59904
	s_waitcnt lgkmcnt(8)
	v_mfma_f32_16x16x32_bf16 v[58:61], v[200:203], v[228:231], v[58:61]
	v_mfma_f32_16x16x32_bf16 v[62:65], v[200:203], v[232:235], v[62:65]
	v_mfma_f32_16x16x32_bf16 v[26:29], v[200:203], v[236:239], v[26:29]
	v_mfma_f32_16x16x32_bf16 v[30:33], v[200:203], v[240:243], v[30:33]
	s_waitcnt vmcnt(1)
	ds_write_b128 v100, v[114:117] offset:64512
	s_waitcnt vmcnt(0)
	ds_write_b128 v101, v[88:91] offset:32256
	s_waitcnt lgkmcnt(0)
	s_barrier
	s_setprio 0
	ds_read_b128 v[212:215], v245 offset:55296
	ds_read_b128 v[196:199], v244 offset:18432
	ds_read_b128 v[216:219], v245 offset:57600
	ds_read_b128 v[220:223], v245 offset:59904
	ds_read_b128 v[224:227], v245 offset:62208
	ds_read_b128 v[200:203], v244 offset:20736
	v_mfma_f32_16x16x32_bf16 v[34:37], v[204:207], v[228:231], v[34:37]
	v_mfma_f32_16x16x32_bf16 v[38:41], v[204:207], v[232:235], v[38:41]
	v_mfma_f32_16x16x32_bf16 v[2:5], v[204:207], v[236:239], v[2:5]
	v_mfma_f32_16x16x32_bf16 v[6:9], v[204:207], v[240:243], v[6:9]
	ds_read_b128 v[204:207], v244 offset:23040
	v_mfma_f32_16x16x32_bf16 v[42:45], v[208:211], v[228:231], v[42:45]
	v_mfma_f32_16x16x32_bf16 v[46:49], v[208:211], v[232:235], v[46:49]
	v_mfma_f32_16x16x32_bf16 v[10:13], v[208:211], v[236:239], v[10:13]
	v_mfma_f32_16x16x32_bf16 v[14:17], v[208:211], v[240:243], v[14:17]
	ds_read_b128 v[208:211], v244 offset:25344
	s_waitcnt lgkmcnt(6)
	v_mfma_f32_16x16x32_bf16 v[50:53], v[196:199], v[212:215], v[50:53]
	ds_read_b128 v[228:231], v245 offset:55360
	s_waitcnt lgkmcnt(6)
	v_mfma_f32_16x16x32_bf16 v[54:57], v[196:199], v[216:219], v[54:57]
	ds_read_b128 v[232:235], v245 offset:57664
	s_waitcnt lgkmcnt(6)
	v_mfma_f32_16x16x32_bf16 v[18:21], v[196:199], v[220:223], v[18:21]
	ds_read_b128 v[236:239], v245 offset:59968
	s_waitcnt lgkmcnt(6)
	v_mfma_f32_16x16x32_bf16 v[22:25], v[196:199], v[224:227], v[22:25]
	ds_read_b128 v[240:243], v245 offset:62272
	ds_read_b128 v[196:199], v244 offset:18496
	s_waitcnt lgkmcnt(7)
	v_mfma_f32_16x16x32_bf16 v[58:61], v[200:203], v[212:215], v[58:61]
	v_mfma_f32_16x16x32_bf16 v[62:65], v[200:203], v[216:219], v[62:65]
	v_mfma_f32_16x16x32_bf16 v[26:29], v[200:203], v[220:223], v[26:29]
	v_mfma_f32_16x16x32_bf16 v[30:33], v[200:203], v[224:227], v[30:33]
	ds_read_b128 v[200:203], v244 offset:20800
	s_waitcnt lgkmcnt(7)
	v_mfma_f32_16x16x32_bf16 v[34:37], v[204:207], v[212:215], v[34:37]
	v_mfma_f32_16x16x32_bf16 v[38:41], v[204:207], v[216:219], v[38:41]
	v_mfma_f32_16x16x32_bf16 v[2:5], v[204:207], v[220:223], v[2:5]
	v_mfma_f32_16x16x32_bf16 v[6:9], v[204:207], v[224:227], v[6:9]
	ds_read_b128 v[204:207], v244 offset:23104
	s_waitcnt lgkmcnt(7)
	v_mfma_f32_16x16x32_bf16 v[42:45], v[208:211], v[212:215], v[42:45]
	v_mfma_f32_16x16x32_bf16 v[46:49], v[208:211], v[216:219], v[46:49]
	v_mfma_f32_16x16x32_bf16 v[10:13], v[208:211], v[220:223], v[10:13]
	v_mfma_f32_16x16x32_bf16 v[14:17], v[208:211], v[224:227], v[14:17]
	ds_read_b128 v[208:211], v244 offset:25408
	s_waitcnt lgkmcnt(3)
	v_mfma_f32_16x16x32_bf16 v[50:53], v[196:199], v[228:231], v[50:53]
	v_mfma_f32_16x16x32_bf16 v[54:57], v[196:199], v[232:235], v[54:57]
	v_mfma_f32_16x16x32_bf16 v[18:21], v[196:199], v[236:239], v[18:21]
	v_mfma_f32_16x16x32_bf16 v[22:25], v[196:199], v[240:243], v[22:25]
	s_waitcnt lgkmcnt(2)
	v_mfma_f32_16x16x32_bf16 v[58:61], v[200:203], v[228:231], v[58:61]
	v_mfma_f32_16x16x32_bf16 v[62:65], v[200:203], v[232:235], v[62:65]
	v_mfma_f32_16x16x32_bf16 v[26:29], v[200:203], v[236:239], v[26:29]
	v_mfma_f32_16x16x32_bf16 v[30:33], v[200:203], v[240:243], v[30:33]
	s_add_i32 s6, s6, 1
	s_add_i32 s5, s5, s3
	v_or_b32_e32 v70, s0, v92
	s_lshl_b32 s0, s7, 1
	v_lshl_add_u64 v[110:111], v[80:81], 0, s[0:1]
	v_lshlrev_b32_e32 v74, 10, v70
	v_lshl_add_u64 v[112:113], v[110:111], 0, v[74:75]
	s_waitcnt lgkmcnt(0)
	s_barrier
	v_mfma_f32_16x16x32_bf16 v[34:37], v[204:207], v[228:231], v[34:37]
	v_mfma_f32_16x16x32_bf16 v[38:41], v[204:207], v[232:235], v[38:41]
	v_mfma_f32_16x16x32_bf16 v[2:5], v[204:207], v[236:239], v[2:5]
	v_mfma_f32_16x16x32_bf16 v[6:9], v[204:207], v[240:243], v[6:9]
	v_mfma_f32_16x16x32_bf16 v[42:45], v[208:211], v[228:231], v[42:45]
	v_mfma_f32_16x16x32_bf16 v[46:49], v[208:211], v[232:235], v[46:49]
	v_mfma_f32_16x16x32_bf16 v[10:13], v[208:211], v[236:239], v[10:13]
	v_mfma_f32_16x16x32_bf16 v[14:17], v[208:211], v[240:243], v[14:17]
	s_nop 7
	v_permlane16_swap_b32_e32 v50, v54
	v_permlane16_swap_b32_e32 v51, v55
	v_permlane16_swap_b32_e32 v52, v56
	v_permlane16_swap_b32_e32 v53, v57
	v_permlane16_swap_b32_e32 v58, v62
	v_permlane16_swap_b32_e32 v59, v63
	v_permlane16_swap_b32_e32 v60, v64
	v_permlane16_swap_b32_e32 v61, v65
	v_permlane16_swap_b32_e32 v18, v22
	v_permlane16_swap_b32_e32 v19, v23
	v_permlane16_swap_b32_e32 v20, v24
	v_permlane16_swap_b32_e32 v21, v25
	v_permlane16_swap_b32_e32 v26, v30
	v_permlane16_swap_b32_e32 v27, v31
	v_permlane16_swap_b32_e32 v28, v32
	v_permlane16_swap_b32_e32 v29, v33
	v_permlane16_swap_b32_e32 v34, v38
	v_permlane16_swap_b32_e32 v35, v39
	v_permlane16_swap_b32_e32 v36, v40
	v_permlane16_swap_b32_e32 v37, v41
	v_permlane16_swap_b32_e32 v42, v46
	v_permlane16_swap_b32_e32 v43, v47
	v_permlane16_swap_b32_e32 v44, v48
	v_permlane16_swap_b32_e32 v45, v49
	v_permlane16_swap_b32_e32 v2, v6
	v_permlane16_swap_b32_e32 v3, v7
	v_permlane16_swap_b32_e32 v4, v8
	v_permlane16_swap_b32_e32 v5, v9
	v_permlane16_swap_b32_e32 v10, v14
	v_permlane16_swap_b32_e32 v11, v15
	v_permlane16_swap_b32_e32 v12, v16
	v_permlane16_swap_b32_e32 v13, v17
	v_permlane32_swap_b32_e32 v50, v54
	v_permlane32_swap_b32_e32 v51, v55
	v_permlane32_swap_b32_e32 v52, v56
	v_permlane32_swap_b32_e32 v53, v57
	v_permlane32_swap_b32_e32 v58, v62
	v_permlane32_swap_b32_e32 v59, v63
	v_permlane32_swap_b32_e32 v60, v64
	v_permlane32_swap_b32_e32 v61, v65
	v_permlane32_swap_b32_e32 v18, v22
	v_permlane32_swap_b32_e32 v19, v23
	v_permlane32_swap_b32_e32 v20, v24
	v_permlane32_swap_b32_e32 v21, v25
	v_permlane32_swap_b32_e32 v26, v30
	v_permlane32_swap_b32_e32 v27, v31
	v_permlane32_swap_b32_e32 v28, v32
	v_permlane32_swap_b32_e32 v29, v33
	v_permlane32_swap_b32_e32 v34, v38
	v_permlane32_swap_b32_e32 v35, v39
	v_permlane32_swap_b32_e32 v36, v40
	v_permlane32_swap_b32_e32 v37, v41
	v_permlane32_swap_b32_e32 v42, v46
	v_permlane32_swap_b32_e32 v43, v47
	v_permlane32_swap_b32_e32 v44, v48
	v_permlane32_swap_b32_e32 v45, v49
	v_permlane32_swap_b32_e32 v2, v6
	v_permlane32_swap_b32_e32 v3, v7
	v_permlane32_swap_b32_e32 v4, v8
	v_permlane32_swap_b32_e32 v5, v9
	v_permlane32_swap_b32_e32 v10, v14
	v_permlane32_swap_b32_e32 v11, v15
	v_permlane32_swap_b32_e32 v12, v16
	v_permlane32_swap_b32_e32 v13, v17
	global_load_dwordx4 v[106:109], v[112:113], off
	s_mul_i32 s0, s6, s3
	s_add_i32 s0, s0, s2
	s_cmp_lt_u32 s5, 48
	global_load_dwordx4 v[88:91], v[112:113], off offset:32
	global_load_dwordx4 v[70:73], v[112:113], off offset:64
	s_waitcnt vmcnt(2)
	v_mov_b32_e32 v86, v108
	global_load_dwordx4 v[66:69], v[112:113], off offset:96
	v_permlane32_swap_b32_e32 v106, v86
	v_mov_b32_e32 v102, v109
	s_nop 1
	v_permlane32_swap_b32_e32 v107, v102
	s_waitcnt vmcnt(2)
	v_mov_b32_e32 v108, v90
	v_mov_b32_e32 v109, v91
	s_nop 0
	v_permlane32_swap_b32_e32 v88, v108
	v_permlane32_swap_b32_e32 v89, v109
	s_waitcnt vmcnt(1)
	v_mov_b32_e32 v112, v72
	v_mov_b32_e32 v113, v73
	v_lshlrev_b32_e32 v72, 16, v106
	v_and_b32_e32 v73, 0xffff0000, v106
	v_pk_mul_f32 v[72:73], v[50:51], v[72:73]
	v_lshlrev_b32_e32 v50, 16, v107
	v_and_b32_e32 v51, 0xffff0000, v107
	v_pk_mul_f32 v[84:85], v[52:53], v[50:51]
	v_lshlrev_b32_e32 v50, 16, v86
	v_and_b32_e32 v51, 0xffff0000, v86
	v_pk_mul_f32 v[86:87], v[54:55], v[50:51]
	v_lshlrev_b32_e32 v54, 16, v102
	v_and_b32_e32 v55, 0xffff0000, v102
	v_pk_mul_f32 v[102:103], v[56:57], v[54:55]
	v_cvt_pk_bf16_f32 v55, v84, v85
	v_cvt_pk_bf16_f32 v56, v86, v87
	v_cvt_pk_bf16_f32 v57, v102, v103
	v_cvt_pk_bf16_f32 v54, v72, v73
	v_add_lshl_u32 v72, s7, v97, 1
	v_mov_b32_e32 v73, v75
	v_permlane32_swap_b32_e32 v54, v56
	v_permlane32_swap_b32_e32 v55, v57
	v_lshlrev_b32_e32 v106, 16, v88
	v_and_b32_e32 v107, 0xffff0000, v88
	v_lshlrev_b32_e32 v88, 16, v89
	v_and_b32_e32 v89, 0xffff0000, v89
	v_pk_mul_f32 v[60:61], v[60:61], v[88:89]
	v_lshlrev_b32_e32 v88, 16, v108
	v_and_b32_e32 v89, 0xffff0000, v108
	v_pk_mul_f32 v[62:63], v[62:63], v[88:89]
	v_lshlrev_b32_e32 v88, 16, v109
	v_and_b32_e32 v89, 0xffff0000, v109
	v_pk_mul_f32 v[58:59], v[58:59], v[106:107]
	v_pk_mul_f32 v[64:65], v[64:65], v[88:89]
	v_cvt_pk_bf16_f32 v58, v58, v59
	v_cvt_pk_bf16_f32 v59, v60, v61
	v_cvt_pk_bf16_f32 v60, v62, v63
	v_cvt_pk_bf16_f32 v61, v64, v65
	v_permlane32_swap_b32_e32 v70, v112
	v_permlane32_swap_b32_e32 v58, v60
	v_permlane32_swap_b32_e32 v59, v61
	v_permlane32_swap_b32_e32 v71, v113
	s_waitcnt vmcnt(0)
	v_mov_b32_e32 v114, v68
	v_mov_b32_e32 v115, v69
	v_lshl_add_u64 v[68:69], v[82:83], 0, v[74:75]
	v_or_b32_e32 v74, 0x8000, v74
	v_lshl_add_u64 v[90:91], v[110:111], 0, v[74:75]
	global_load_dwordx4 v[50:53], v[90:91], off
	global_load_dwordx4 v[84:87], v[90:91], off offset:32
	global_load_dwordx4 v[102:105], v[90:91], off offset:64
	v_lshl_add_u64 v[68:69], v[68:69], 0, v[72:73]
	global_store_dwordx4 v[68:69], v[54:57], off
	global_load_dwordx4 v[54:57], v[90:91], off offset:96
	v_permlane32_swap_b32_e32 v66, v114
	global_store_dwordx4 v[68:69], v[58:61], off offset:32
	v_permlane32_swap_b32_e32 v67, v115
	s_nop 0
	v_lshlrev_b32_e32 v58, 16, v70
	v_and_b32_e32 v59, 0xffff0000, v70
	v_pk_mul_f32 v[34:35], v[34:35], v[58:59]
	v_lshlrev_b32_e32 v58, 16, v71
	v_and_b32_e32 v59, 0xffff0000, v71
	v_pk_mul_f32 v[36:37], v[36:37], v[58:59]
	v_lshlrev_b32_e32 v58, 16, v112
	v_and_b32_e32 v59, 0xffff0000, v112
	v_pk_mul_f32 v[38:39], v[38:39], v[58:59]
	v_lshlrev_b32_e32 v58, 16, v113
	v_and_b32_e32 v59, 0xffff0000, v113
	v_pk_mul_f32 v[40:41], v[40:41], v[58:59]
	v_cvt_pk_bf16_f32 v34, v34, v35
	v_cvt_pk_bf16_f32 v35, v36, v37
	v_cvt_pk_bf16_f32 v36, v38, v39
	v_cvt_pk_bf16_f32 v37, v40, v41
	s_nop 0
	v_permlane32_swap_b32_e32 v34, v36
	v_permlane32_swap_b32_e32 v35, v37
	global_store_dwordx4 v[68:69], v[34:37], off offset:64
	v_lshlrev_b32_e32 v38, 16, v114
	v_and_b32_e32 v39, 0xffff0000, v114
	v_lshlrev_b32_e32 v34, 16, v66
	v_and_b32_e32 v35, 0xffff0000, v66
	v_lshlrev_b32_e32 v36, 16, v67
	v_and_b32_e32 v37, 0xffff0000, v67
	v_lshlrev_b32_e32 v40, 16, v115
	v_and_b32_e32 v41, 0xffff0000, v115
	v_pk_mul_f32 v[34:35], v[42:43], v[34:35]
	v_pk_mul_f32 v[36:37], v[44:45], v[36:37]
	v_pk_mul_f32 v[38:39], v[46:47], v[38:39]
	v_pk_mul_f32 v[40:41], v[48:49], v[40:41]
	v_cvt_pk_bf16_f32 v34, v34, v35
	v_cvt_pk_bf16_f32 v35, v36, v37
	v_cvt_pk_bf16_f32 v36, v38, v39
	v_cvt_pk_bf16_f32 v37, v40, v41
	s_nop 0
	v_permlane32_swap_b32_e32 v34, v36
	v_permlane32_swap_b32_e32 v35, v37
	global_store_dwordx4 v[68:69], v[34:37], off offset:96
	s_waitcnt vmcnt(7)
	v_mov_b32_e32 v38, v52
	s_nop 1
	v_permlane32_swap_b32_e32 v50, v38
	v_mov_b32_e32 v39, v53
	s_nop 1
	v_permlane32_swap_b32_e32 v51, v39
	v_lshlrev_b32_e32 v36, 16, v50
	v_and_b32_e32 v37, 0xffff0000, v50
	v_pk_mul_f32 v[18:19], v[18:19], v[36:37]
	v_lshlrev_b32_e32 v36, 16, v51
	v_and_b32_e32 v37, 0xffff0000, v51
	v_pk_mul_f32 v[20:21], v[20:21], v[36:37]
	v_lshlrev_b32_e32 v36, 16, v38
	v_and_b32_e32 v37, 0xffff0000, v38
	v_pk_mul_f32 v[22:23], v[22:23], v[36:37]
	v_lshlrev_b32_e32 v36, 16, v39
	v_and_b32_e32 v37, 0xffff0000, v39
	v_pk_mul_f32 v[24:25], v[24:25], v[36:37]
	s_waitcnt vmcnt(6)
	v_mov_b32_e32 v40, v86
	v_lshl_add_u64 v[34:35], v[82:83], 0, v[74:75]
	v_cvt_pk_bf16_f32 v18, v18, v19
	v_cvt_pk_bf16_f32 v19, v20, v21
	v_cvt_pk_bf16_f32 v20, v22, v23
	v_cvt_pk_bf16_f32 v21, v24, v25
	v_permlane32_swap_b32_e32 v84, v40
	v_mov_b32_e32 v41, v87
	v_permlane32_swap_b32_e32 v18, v20
	v_permlane32_swap_b32_e32 v19, v21
	v_lshl_add_u64 v[22:23], v[34:35], 0, v[72:73]
	v_permlane32_swap_b32_e32 v85, v41
	global_store_dwordx4 v[22:23], v[18:21], off
	v_lshlrev_b32_e32 v24, 16, v40
	v_and_b32_e32 v25, 0xffff0000, v40
	v_lshlrev_b32_e32 v18, 16, v84
	v_and_b32_e32 v19, 0xffff0000, v84
	v_pk_mul_f32 v[18:19], v[26:27], v[18:19]
	v_lshlrev_b32_e32 v20, 16, v85
	v_and_b32_e32 v21, 0xffff0000, v85
	v_lshlrev_b32_e32 v26, 16, v41
	v_and_b32_e32 v27, 0xffff0000, v41
	v_pk_mul_f32 v[20:21], v[28:29], v[20:21]
	v_pk_mul_f32 v[24:25], v[30:31], v[24:25]
	v_pk_mul_f32 v[26:27], v[32:33], v[26:27]
	s_waitcnt vmcnt(6)
	v_mov_b32_e32 v42, v104
	v_cvt_pk_bf16_f32 v18, v18, v19
	v_cvt_pk_bf16_f32 v19, v20, v21
	v_cvt_pk_bf16_f32 v20, v24, v25
	v_cvt_pk_bf16_f32 v21, v26, v27
	v_permlane32_swap_b32_e32 v102, v42
	v_mov_b32_e32 v43, v105
	v_permlane32_swap_b32_e32 v18, v20
	v_permlane32_swap_b32_e32 v19, v21
	v_permlane32_swap_b32_e32 v103, v43
	global_store_dwordx4 v[22:23], v[18:21], off offset:32
	s_waitcnt vmcnt(5)
	v_mov_b32_e32 v44, v56
	v_mov_b32_e32 v45, v57
	v_lshlrev_b32_e32 v18, 16, v102
	v_and_b32_e32 v19, 0xffff0000, v102
	v_pk_mul_f32 v[2:3], v[2:3], v[18:19]
	v_lshlrev_b32_e32 v18, 16, v103
	v_and_b32_e32 v19, 0xffff0000, v103
	v_pk_mul_f32 v[4:5], v[4:5], v[18:19]
	v_lshlrev_b32_e32 v18, 16, v42
	v_and_b32_e32 v19, 0xffff0000, v42
	v_pk_mul_f32 v[6:7], v[6:7], v[18:19]
	v_lshlrev_b32_e32 v18, 16, v43
	v_and_b32_e32 v19, 0xffff0000, v43
	v_pk_mul_f32 v[8:9], v[8:9], v[18:19]
	v_cvt_pk_bf16_f32 v2, v2, v3
	v_cvt_pk_bf16_f32 v3, v4, v5
	v_cvt_pk_bf16_f32 v4, v6, v7
	v_cvt_pk_bf16_f32 v5, v8, v9
	v_permlane32_swap_b32_e32 v54, v44
	v_permlane32_swap_b32_e32 v55, v45
	v_permlane32_swap_b32_e32 v2, v4
	v_permlane32_swap_b32_e32 v3, v5
	global_store_dwordx4 v[22:23], v[2:5], off offset:64
	v_lshlrev_b32_e32 v6, 16, v44
	v_and_b32_e32 v7, 0xffff0000, v44
	v_lshlrev_b32_e32 v2, 16, v54
	v_and_b32_e32 v3, 0xffff0000, v54
	v_lshlrev_b32_e32 v4, 16, v55
	v_and_b32_e32 v5, 0xffff0000, v55
	v_lshlrev_b32_e32 v8, 16, v45
	v_and_b32_e32 v9, 0xffff0000, v45
	v_pk_mul_f32 v[2:3], v[10:11], v[2:3]
	v_pk_mul_f32 v[4:5], v[12:13], v[4:5]
	v_pk_mul_f32 v[6:7], v[14:15], v[6:7]
	v_pk_mul_f32 v[8:9], v[16:17], v[8:9]
	v_cvt_pk_bf16_f32 v2, v2, v3
	v_cvt_pk_bf16_f32 v3, v4, v5
	v_cvt_pk_bf16_f32 v4, v6, v7
	v_cvt_pk_bf16_f32 v5, v8, v9
	s_nop 0
	v_permlane32_swap_b32_e32 v2, v4
	v_permlane32_swap_b32_e32 v3, v5
	global_store_dwordx4 v[22:23], v[2:5], off offset:96
	s_cbranch_scc1 .LBB0_828

.LBB0_903:
	s_cmp_eq_u32 s2, 0x100000
	s_cselect_b32 s0, s13, 0x5400000
	s_cmp_lg_u32 s2, 0
	v_lshl_add_u64 v[2:3], v[152:153], 0, s[2:3]
	s_cselect_b32 s0, s0, 0
	v_add_co_u32_e32 v178, vcc, s14, v2
	s_add_u32 s4, s82, s0
	v_lshl_add_u64 v[4:5], v[156:157], 0, s[2:3]
	v_addc_co_u32_e32 v179, vcc, 0, v3, vcc
	s_addc_u32 s5, s83, 0
	v_add_co_u32_e32 v180, vcc, s14, v4
	v_lshl_add_u64 v[10:11], v[158:159], 0, s[2:3]
	v_lshl_add_u64 v[6:7], s[4:5], 0, v[104:105]
	v_addc_co_u32_e32 v181, vcc, 0, v5, vcc
	v_lshl_add_u64 v[66:67], v[6:7], 0, v[82:83]
	v_lshl_add_u64 v[6:7], s[4:5], 0, v[112:113]
	v_add_co_u32_e32 v182, vcc, s14, v10
	v_lshl_add_u64 v[12:13], v[160:161], 0, s[2:3]
	v_lshl_add_u64 v[70:71], v[6:7], 0, v[82:83]
	v_lshl_add_u64 v[6:7], s[4:5], 0, v[116:117]
	v_addc_co_u32_e32 v183, vcc, 0, v11, vcc
	v_lshl_add_u64 v[68:69], v[6:7], 0, v[82:83]
	v_lshl_add_u64 v[6:7], s[4:5], 0, v[120:121]
	v_add_co_u32_e32 v184, vcc, s14, v12
	v_lshl_add_u64 v[72:73], v[6:7], 0, v[82:83]
	global_load_dwordx4 v[2:5], v[178:179], off
	global_load_dwordx4 v[6:9], v[180:181], off
	v_addc_co_u32_e32 v185, vcc, 0, v13, vcc
	global_load_dwordx4 v[10:13], v[182:183], off
	global_load_dwordx4 v[14:17], v[184:185], off
	global_load_dwordx4 v[18:21], v[66:67], off
	global_load_dwordx4 v[22:25], v[70:71], off
	global_load_dwordx4 v[26:29], v[68:69], off
	global_load_dwordx4 v[30:33], v[72:73], off
	s_cmp_lt_i32 s17, 1
	s_mov_b32 s0, s11
	s_setprio 1
	s_waitcnt vmcnt(7)
	ds_write_b128 v196, v[2:5]
	s_waitcnt vmcnt(6)
	ds_write_b128 v196, v[6:9] offset:4608
	s_waitcnt vmcnt(5)
	ds_write_b128 v196, v[10:13] offset:9216
	s_waitcnt vmcnt(4)
	ds_write_b128 v196, v[14:17] offset:13824
	s_waitcnt vmcnt(3)
	ds_write_b128 v196, v[18:21] offset:36864
	s_waitcnt vmcnt(2)
	ds_write_b128 v196, v[22:25] offset:41472
	s_waitcnt vmcnt(1)
	ds_write_b128 v196, v[26:29] offset:46080
	s_waitcnt vmcnt(0)
	ds_write_b128 v196, v[30:33] offset:50688
	s_waitcnt lgkmcnt(0)
	s_barrier
	s_setprio 0
	ds_read_b128 v[2:5], v193
	ds_read_b128 v[6:9], v195 offset:36864
	ds_read_b128 v[202:205], v193 offset:32
	ds_read_b128 v[206:209], v195 offset:36896
	ds_read_b128 v[10:13], v193 offset:4608
	ds_read_b128 v[210:213], v193 offset:4640
	s_waitcnt lgkmcnt(4)
	v_mfma_f32_32x32x16_bf16 v[50:65], v[2:5], v[6:9], 0
	s_waitcnt lgkmcnt(1)
	v_mfma_f32_32x32x16_bf16 v[34:49], v[10:13], v[6:9], 0
	ds_read_b128 v[6:9], v195 offset:41472
	ds_read_b128 v[214:217], v195 offset:41504
	s_waitcnt lgkmcnt(1)
	v_mfma_f32_32x32x16_bf16 v[18:33], v[2:5], v[6:9], 0
	v_mfma_f32_32x32x16_bf16 v[2:17], v[10:13], v[6:9], 0
	v_mfma_f32_32x32x16_bf16 v[50:65], v[202:205], v[206:209], v[50:65]
	v_mfma_f32_32x32x16_bf16 v[34:49], v[210:213], v[206:209], v[34:49]
	s_waitcnt lgkmcnt(0)
	v_mfma_f32_32x32x16_bf16 v[18:33], v[202:205], v[214:217], v[18:33]
	v_mfma_f32_32x32x16_bf16 v[2:17], v[210:213], v[214:217], v[2:17]
	ds_read_b128 v[202:205], v193 offset:64
	ds_read_b128 v[206:209], v195 offset:36928
	ds_read_b128 v[210:213], v193 offset:96
	ds_read_b128 v[214:217], v195 offset:36960
	ds_read_b128 v[218:221], v193 offset:4672
	ds_read_b128 v[222:225], v193 offset:4704
	s_waitcnt lgkmcnt(4)
	v_mfma_f32_32x32x16_bf16 v[50:65], v[202:205], v[206:209], v[50:65]
	s_waitcnt lgkmcnt(1)
	v_mfma_f32_32x32x16_bf16 v[34:49], v[218:221], v[206:209], v[34:49]
	ds_read_b128 v[206:209], v195 offset:41536
	ds_read_b128 v[226:229], v195 offset:41568
	s_waitcnt lgkmcnt(1)
	v_mfma_f32_32x32x16_bf16 v[18:33], v[202:205], v[206:209], v[18:33]
	v_mfma_f32_32x32x16_bf16 v[2:17], v[218:221], v[206:209], v[2:17]
	v_mfma_f32_32x32x16_bf16 v[50:65], v[210:213], v[214:217], v[50:65]
	v_mfma_f32_32x32x16_bf16 v[34:49], v[222:225], v[214:217], v[34:49]
	global_load_dwordx4 v[202:205], v[178:179], off offset:128
	global_load_dwordx4 v[206:209], v[180:181], off offset:128
	global_load_dwordx4 v[214:217], v[182:183], off offset:128
	global_load_dwordx4 v[218:221], v[184:185], off offset:128
	global_load_dwordx4 v[230:233], v[66:67], off offset:128
	global_load_dwordx4 v[234:237], v[70:71], off offset:128
	s_waitcnt lgkmcnt(0)
	v_mfma_f32_32x32x16_bf16 v[18:33], v[210:213], v[226:229], v[18:33]
	global_load_dwordx4 v[210:213], v[68:69], off offset:128
	global_load_dwordx4 v[238:241], v[72:73], off offset:128
	s_setprio 1
	s_waitcnt vmcnt(7)
	ds_write_b128 v196, v[202:205] offset:18432
	s_waitcnt vmcnt(6)
	ds_write_b128 v196, v[206:209] offset:23040
	s_waitcnt vmcnt(5)
	ds_write_b128 v196, v[214:217] offset:27648
	s_waitcnt vmcnt(4)
	ds_write_b128 v196, v[218:221] offset:32256
	s_waitcnt vmcnt(3)
	ds_write_b128 v196, v[230:233] offset:55296
	s_waitcnt vmcnt(2)
	ds_write_b128 v196, v[234:237] offset:59904
	s_waitcnt vmcnt(1)
	ds_write_b128 v196, v[210:213] offset:64512
	s_waitcnt vmcnt(0)
	ds_write_b128 v197, v[238:241] offset:32256
	v_mfma_f32_32x32x16_bf16 v[2:17], v[222:225], v[226:229], v[2:17]
	s_waitcnt lgkmcnt(0)
	s_barrier
	s_setprio 0
	ds_read_b128 v[202:205], v193 offset:18432
	ds_read_b128 v[206:209], v195 offset:55296
	ds_read_b128 v[210:213], v193 offset:18464
	ds_read_b128 v[214:217], v195 offset:55328
	ds_read_b128 v[218:221], v193 offset:23040
	ds_read_b128 v[222:225], v193 offset:23072
	s_waitcnt lgkmcnt(4)
	v_mfma_f32_32x32x16_bf16 v[50:65], v[202:205], v[206:209], v[50:65]
	s_waitcnt lgkmcnt(1)
	v_mfma_f32_32x32x16_bf16 v[34:49], v[218:221], v[206:209], v[34:49]
	ds_read_b128 v[206:209], v195 offset:59904
	ds_read_b128 v[226:229], v195 offset:59936
	s_waitcnt lgkmcnt(1)
	v_mfma_f32_32x32x16_bf16 v[18:33], v[202:205], v[206:209], v[18:33]
	v_mfma_f32_32x32x16_bf16 v[2:17], v[218:221], v[206:209], v[2:17]
	v_mfma_f32_32x32x16_bf16 v[50:65], v[210:213], v[214:217], v[50:65]
	v_mfma_f32_32x32x16_bf16 v[34:49], v[222:225], v[214:217], v[34:49]
	s_waitcnt lgkmcnt(0)
	v_mfma_f32_32x32x16_bf16 v[18:33], v[210:213], v[226:229], v[18:33]
	ds_read_b128 v[202:205], v193 offset:18496
	ds_read_b128 v[206:209], v195 offset:55360
	ds_read_b128 v[210:213], v193 offset:18528
	ds_read_b128 v[214:217], v195 offset:55392
	v_mfma_f32_32x32x16_bf16 v[2:17], v[222:225], v[226:229], v[2:17]
	ds_read_b128 v[218:221], v193 offset:23104
	ds_read_b128 v[222:225], v193 offset:23136
	s_waitcnt lgkmcnt(4)
	v_mfma_f32_32x32x16_bf16 v[50:65], v[202:205], v[206:209], v[50:65]
	s_waitcnt lgkmcnt(1)
	v_mfma_f32_32x32x16_bf16 v[34:49], v[218:221], v[206:209], v[34:49]
	ds_read_b128 v[206:209], v195 offset:59968
	ds_read_b128 v[226:229], v195 offset:60000
	s_waitcnt lgkmcnt(1)
	v_mfma_f32_32x32x16_bf16 v[18:33], v[202:205], v[206:209], v[18:33]
	v_mfma_f32_32x32x16_bf16 v[2:17], v[218:221], v[206:209], v[2:17]
	v_mfma_f32_32x32x16_bf16 v[50:65], v[210:213], v[214:217], v[50:65]
	v_mfma_f32_32x32x16_bf16 v[34:49], v[222:225], v[214:217], v[34:49]
	global_load_dwordx4 v[202:205], v[178:179], off offset:256
	global_load_dwordx4 v[206:209], v[180:181], off offset:256
	global_load_dwordx4 v[214:217], v[182:183], off offset:256
	global_load_dwordx4 v[218:221], v[184:185], off offset:256
	global_load_dwordx4 v[230:233], v[66:67], off offset:256
	global_load_dwordx4 v[234:237], v[70:71], off offset:256
	s_waitcnt lgkmcnt(0)
	v_mfma_f32_32x32x16_bf16 v[18:33], v[210:213], v[226:229], v[18:33]
	global_load_dwordx4 v[210:213], v[68:69], off offset:256
	global_load_dwordx4 v[238:241], v[72:73], off offset:256
	s_setprio 1
	s_waitcnt vmcnt(7)
	ds_write_b128 v196, v[202:205]
	s_waitcnt vmcnt(6)
	ds_write_b128 v196, v[206:209] offset:4608
	s_waitcnt vmcnt(5)
	ds_write_b128 v196, v[214:217] offset:9216
	s_waitcnt vmcnt(4)
	ds_write_b128 v196, v[218:221] offset:13824
	s_waitcnt vmcnt(3)
	ds_write_b128 v196, v[230:233] offset:36864
	s_waitcnt vmcnt(2)
	ds_write_b128 v196, v[234:237] offset:41472
	s_waitcnt vmcnt(1)
	ds_write_b128 v196, v[210:213] offset:46080
	s_waitcnt vmcnt(0)
	ds_write_b128 v196, v[238:241] offset:50688
	v_mfma_f32_32x32x16_bf16 v[2:17], v[222:225], v[226:229], v[2:17]
	s_waitcnt lgkmcnt(0)
	s_barrier
	s_setprio 0
	ds_read_b128 v[202:205], v193
	ds_read_b128 v[206:209], v195 offset:36864
	ds_read_b128 v[210:213], v193 offset:32
	ds_read_b128 v[214:217], v195 offset:36896
	ds_read_b128 v[218:221], v193 offset:4608
	ds_read_b128 v[222:225], v193 offset:4640
	s_waitcnt lgkmcnt(4)
	v_mfma_f32_32x32x16_bf16 v[50:65], v[202:205], v[206:209], v[50:65]
	s_waitcnt lgkmcnt(1)
	v_mfma_f32_32x32x16_bf16 v[34:49], v[218:221], v[206:209], v[34:49]
	ds_read_b128 v[206:209], v195 offset:41472
	ds_read_b128 v[226:229], v195 offset:41504
	s_waitcnt lgkmcnt(1)
	v_mfma_f32_32x32x16_bf16 v[18:33], v[202:205], v[206:209], v[18:33]
	v_mfma_f32_32x32x16_bf16 v[2:17], v[218:221], v[206:209], v[2:17]
	v_mfma_f32_32x32x16_bf16 v[50:65], v[210:213], v[214:217], v[50:65]
	v_mfma_f32_32x32x16_bf16 v[34:49], v[222:225], v[214:217], v[34:49]
	s_waitcnt lgkmcnt(0)
	v_mfma_f32_32x32x16_bf16 v[18:33], v[210:213], v[226:229], v[18:33]
	ds_read_b128 v[202:205], v193 offset:64
	ds_read_b128 v[206:209], v195 offset:36928
	ds_read_b128 v[210:213], v193 offset:96
	ds_read_b128 v[214:217], v195 offset:36960
	v_mfma_f32_32x32x16_bf16 v[2:17], v[222:225], v[226:229], v[2:17]
	ds_read_b128 v[218:221], v193 offset:4672
	ds_read_b128 v[222:225], v193 offset:4704
	s_waitcnt lgkmcnt(4)
	v_mfma_f32_32x32x16_bf16 v[50:65], v[202:205], v[206:209], v[50:65]
	s_waitcnt lgkmcnt(1)
	v_mfma_f32_32x32x16_bf16 v[34:49], v[218:221], v[206:209], v[34:49]
	ds_read_b128 v[206:209], v195 offset:41536
	ds_read_b128 v[226:229], v195 offset:41568
	s_waitcnt lgkmcnt(1)
	v_mfma_f32_32x32x16_bf16 v[18:33], v[202:205], v[206:209], v[18:33]
	v_mfma_f32_32x32x16_bf16 v[2:17], v[218:221], v[206:209], v[2:17]
	v_mfma_f32_32x32x16_bf16 v[50:65], v[210:213], v[214:217], v[50:65]
	v_mfma_f32_32x32x16_bf16 v[34:49], v[222:225], v[214:217], v[34:49]
	global_load_dwordx4 v[202:205], v[178:179], off offset:384
	global_load_dwordx4 v[206:209], v[180:181], off offset:384
	global_load_dwordx4 v[214:217], v[182:183], off offset:384
	global_load_dwordx4 v[218:221], v[184:185], off offset:384
	global_load_dwordx4 v[230:233], v[66:67], off offset:384
	global_load_dwordx4 v[234:237], v[70:71], off offset:384
	s_waitcnt lgkmcnt(0)
	v_mfma_f32_32x32x16_bf16 v[18:33], v[210:213], v[226:229], v[18:33]
	global_load_dwordx4 v[210:213], v[68:69], off offset:384
	global_load_dwordx4 v[238:241], v[72:73], off offset:384
	s_setprio 1
	s_waitcnt vmcnt(7)
	ds_write_b128 v196, v[202:205] offset:18432
	s_waitcnt vmcnt(6)
	ds_write_b128 v196, v[206:209] offset:23040
	s_waitcnt vmcnt(5)
	ds_write_b128 v196, v[214:217] offset:27648
	s_waitcnt vmcnt(4)
	ds_write_b128 v196, v[218:221] offset:32256
	s_waitcnt vmcnt(3)
	ds_write_b128 v196, v[230:233] offset:55296
	s_waitcnt vmcnt(2)
	ds_write_b128 v196, v[234:237] offset:59904
	s_waitcnt vmcnt(1)
	ds_write_b128 v196, v[210:213] offset:64512
	s_waitcnt vmcnt(0)
	ds_write_b128 v197, v[238:241] offset:32256
	v_mfma_f32_32x32x16_bf16 v[2:17], v[222:225], v[226:229], v[2:17]
	s_waitcnt lgkmcnt(0)
	s_barrier
	s_setprio 0
	ds_read_b128 v[202:205], v193 offset:18432
	ds_read_b128 v[206:209], v195 offset:55296
	ds_read_b128 v[210:213], v193 offset:18464
	ds_read_b128 v[214:217], v195 offset:55328
	ds_read_b128 v[218:221], v193 offset:23040
	ds_read_b128 v[222:225], v193 offset:23072
	s_waitcnt lgkmcnt(4)
	v_mfma_f32_32x32x16_bf16 v[50:65], v[202:205], v[206:209], v[50:65]
	s_waitcnt lgkmcnt(1)
	v_mfma_f32_32x32x16_bf16 v[34:49], v[218:221], v[206:209], v[34:49]
	ds_read_b128 v[206:209], v195 offset:59904
	ds_read_b128 v[226:229], v195 offset:59936
	s_waitcnt lgkmcnt(1)
	v_mfma_f32_32x32x16_bf16 v[18:33], v[202:205], v[206:209], v[18:33]
	v_mfma_f32_32x32x16_bf16 v[2:17], v[218:221], v[206:209], v[2:17]
	v_mfma_f32_32x32x16_bf16 v[50:65], v[210:213], v[214:217], v[50:65]
	v_mfma_f32_32x32x16_bf16 v[34:49], v[222:225], v[214:217], v[34:49]
	s_waitcnt lgkmcnt(0)
	v_mfma_f32_32x32x16_bf16 v[18:33], v[210:213], v[226:229], v[18:33]
	ds_read_b128 v[202:205], v193 offset:18496
	ds_read_b128 v[206:209], v195 offset:55360
	ds_read_b128 v[210:213], v193 offset:18528
	ds_read_b128 v[214:217], v195 offset:55392
	v_mfma_f32_32x32x16_bf16 v[2:17], v[222:225], v[226:229], v[2:17]
	ds_read_b128 v[218:221], v193 offset:23104
	ds_read_b128 v[222:225], v193 offset:23136
	s_waitcnt lgkmcnt(4)
	v_mfma_f32_32x32x16_bf16 v[50:65], v[202:205], v[206:209], v[50:65]
	s_waitcnt lgkmcnt(1)
	v_mfma_f32_32x32x16_bf16 v[34:49], v[218:221], v[206:209], v[34:49]
	ds_read_b128 v[206:209], v195 offset:59968
	ds_read_b128 v[226:229], v195 offset:60000
	s_waitcnt lgkmcnt(1)
	v_mfma_f32_32x32x16_bf16 v[18:33], v[202:205], v[206:209], v[18:33]
	v_mfma_f32_32x32x16_bf16 v[2:17], v[218:221], v[206:209], v[2:17]
	v_mfma_f32_32x32x16_bf16 v[50:65], v[210:213], v[214:217], v[50:65]
	v_mfma_f32_32x32x16_bf16 v[34:49], v[222:225], v[214:217], v[34:49]
	global_load_dwordx4 v[202:205], v[178:179], off offset:512
	global_load_dwordx4 v[206:209], v[180:181], off offset:512
	global_load_dwordx4 v[214:217], v[182:183], off offset:512
	global_load_dwordx4 v[218:221], v[184:185], off offset:512
	global_load_dwordx4 v[230:233], v[66:67], off offset:512
	global_load_dwordx4 v[234:237], v[70:71], off offset:512
	s_waitcnt lgkmcnt(0)
	v_mfma_f32_32x32x16_bf16 v[18:33], v[210:213], v[226:229], v[18:33]
	global_load_dwordx4 v[210:213], v[68:69], off offset:512
	global_load_dwordx4 v[238:241], v[72:73], off offset:512
	s_setprio 1
	s_waitcnt vmcnt(7)
	ds_write_b128 v196, v[202:205]
	s_waitcnt vmcnt(6)
	ds_write_b128 v196, v[206:209] offset:4608
	s_waitcnt vmcnt(5)
	ds_write_b128 v196, v[214:217] offset:9216
	s_waitcnt vmcnt(4)
	ds_write_b128 v196, v[218:221] offset:13824
	s_waitcnt vmcnt(3)
	ds_write_b128 v196, v[230:233] offset:36864
	s_waitcnt vmcnt(2)
	ds_write_b128 v196, v[234:237] offset:41472
	s_waitcnt vmcnt(1)
	ds_write_b128 v196, v[210:213] offset:46080
	s_waitcnt vmcnt(0)
	ds_write_b128 v196, v[238:241] offset:50688
	v_mfma_f32_32x32x16_bf16 v[2:17], v[222:225], v[226:229], v[2:17]
	s_waitcnt lgkmcnt(0)
	s_barrier
	s_setprio 0
	ds_read_b128 v[202:205], v193
	ds_read_b128 v[206:209], v195 offset:36864
	ds_read_b128 v[210:213], v193 offset:32
	ds_read_b128 v[214:217], v195 offset:36896
	ds_read_b128 v[218:221], v193 offset:4608
	ds_read_b128 v[222:225], v193 offset:4640
	s_waitcnt lgkmcnt(4)
	v_mfma_f32_32x32x16_bf16 v[50:65], v[202:205], v[206:209], v[50:65]
	s_waitcnt lgkmcnt(1)
	v_mfma_f32_32x32x16_bf16 v[34:49], v[218:221], v[206:209], v[34:49]
	ds_read_b128 v[206:209], v195 offset:41472
	ds_read_b128 v[226:229], v195 offset:41504
	s_waitcnt lgkmcnt(1)
	v_mfma_f32_32x32x16_bf16 v[18:33], v[202:205], v[206:209], v[18:33]
	v_mfma_f32_32x32x16_bf16 v[2:17], v[218:221], v[206:209], v[2:17]
	v_mfma_f32_32x32x16_bf16 v[50:65], v[210:213], v[214:217], v[50:65]
	v_mfma_f32_32x32x16_bf16 v[34:49], v[222:225], v[214:217], v[34:49]
	s_waitcnt lgkmcnt(0)
	v_mfma_f32_32x32x16_bf16 v[18:33], v[210:213], v[226:229], v[18:33]
	ds_read_b128 v[202:205], v193 offset:64
	ds_read_b128 v[206:209], v195 offset:36928
	ds_read_b128 v[210:213], v193 offset:96
	ds_read_b128 v[214:217], v195 offset:36960
	v_mfma_f32_32x32x16_bf16 v[2:17], v[222:225], v[226:229], v[2:17]
	ds_read_b128 v[218:221], v193 offset:4672
	ds_read_b128 v[222:225], v193 offset:4704
	s_waitcnt lgkmcnt(4)
	v_mfma_f32_32x32x16_bf16 v[50:65], v[202:205], v[206:209], v[50:65]
	s_waitcnt lgkmcnt(1)
	v_mfma_f32_32x32x16_bf16 v[34:49], v[218:221], v[206:209], v[34:49]
	ds_read_b128 v[206:209], v195 offset:41536
	ds_read_b128 v[226:229], v195 offset:41568
	s_waitcnt lgkmcnt(1)
	v_mfma_f32_32x32x16_bf16 v[18:33], v[202:205], v[206:209], v[18:33]
	v_mfma_f32_32x32x16_bf16 v[2:17], v[218:221], v[206:209], v[2:17]
	v_mfma_f32_32x32x16_bf16 v[50:65], v[210:213], v[214:217], v[50:65]
	v_mfma_f32_32x32x16_bf16 v[34:49], v[222:225], v[214:217], v[34:49]
	global_load_dwordx4 v[202:205], v[178:179], off offset:640
	global_load_dwordx4 v[206:209], v[180:181], off offset:640
	global_load_dwordx4 v[214:217], v[182:183], off offset:640
	global_load_dwordx4 v[218:221], v[184:185], off offset:640
	global_load_dwordx4 v[230:233], v[66:67], off offset:640
	global_load_dwordx4 v[234:237], v[70:71], off offset:640
	s_waitcnt lgkmcnt(0)
	v_mfma_f32_32x32x16_bf16 v[18:33], v[210:213], v[226:229], v[18:33]
	global_load_dwordx4 v[210:213], v[68:69], off offset:640
	global_load_dwordx4 v[238:241], v[72:73], off offset:640
	s_setprio 1
	s_waitcnt vmcnt(7)
	ds_write_b128 v196, v[202:205] offset:18432
	s_waitcnt vmcnt(6)
	ds_write_b128 v196, v[206:209] offset:23040
	s_waitcnt vmcnt(5)
	ds_write_b128 v196, v[214:217] offset:27648
	s_waitcnt vmcnt(4)
	ds_write_b128 v196, v[218:221] offset:32256
	s_waitcnt vmcnt(3)
	ds_write_b128 v196, v[230:233] offset:55296
	s_waitcnt vmcnt(2)
	ds_write_b128 v196, v[234:237] offset:59904
	s_waitcnt vmcnt(1)
	ds_write_b128 v196, v[210:213] offset:64512
	s_waitcnt vmcnt(0)
	ds_write_b128 v197, v[238:241] offset:32256
	v_mfma_f32_32x32x16_bf16 v[2:17], v[222:225], v[226:229], v[2:17]
	s_waitcnt lgkmcnt(0)
	s_barrier
	s_setprio 0
	ds_read_b128 v[202:205], v193 offset:18432
	ds_read_b128 v[206:209], v195 offset:55296
	ds_read_b128 v[210:213], v193 offset:18464
	ds_read_b128 v[214:217], v195 offset:55328
	ds_read_b128 v[218:221], v193 offset:23040
	ds_read_b128 v[222:225], v193 offset:23072
	s_waitcnt lgkmcnt(4)
	v_mfma_f32_32x32x16_bf16 v[50:65], v[202:205], v[206:209], v[50:65]
	s_waitcnt lgkmcnt(1)
	v_mfma_f32_32x32x16_bf16 v[34:49], v[218:221], v[206:209], v[34:49]
	ds_read_b128 v[206:209], v195 offset:59904
	ds_read_b128 v[226:229], v195 offset:59936
	s_waitcnt lgkmcnt(1)
	v_mfma_f32_32x32x16_bf16 v[18:33], v[202:205], v[206:209], v[18:33]
	v_mfma_f32_32x32x16_bf16 v[2:17], v[218:221], v[206:209], v[2:17]
	v_mfma_f32_32x32x16_bf16 v[50:65], v[210:213], v[214:217], v[50:65]
	v_mfma_f32_32x32x16_bf16 v[34:49], v[222:225], v[214:217], v[34:49]
	s_waitcnt lgkmcnt(0)
	v_mfma_f32_32x32x16_bf16 v[18:33], v[210:213], v[226:229], v[18:33]
	ds_read_b128 v[202:205], v193 offset:18496
	ds_read_b128 v[206:209], v195 offset:55360
	ds_read_b128 v[210:213], v193 offset:18528
	ds_read_b128 v[214:217], v195 offset:55392
	v_mfma_f32_32x32x16_bf16 v[2:17], v[222:225], v[226:229], v[2:17]
	ds_read_b128 v[218:221], v193 offset:23104
	ds_read_b128 v[222:225], v193 offset:23136
	s_waitcnt lgkmcnt(4)
	v_mfma_f32_32x32x16_bf16 v[50:65], v[202:205], v[206:209], v[50:65]
	s_waitcnt lgkmcnt(1)
	v_mfma_f32_32x32x16_bf16 v[34:49], v[218:221], v[206:209], v[34:49]
	ds_read_b128 v[206:209], v195 offset:59968
	ds_read_b128 v[226:229], v195 offset:60000
	s_waitcnt lgkmcnt(1)
	v_mfma_f32_32x32x16_bf16 v[18:33], v[202:205], v[206:209], v[18:33]
	v_mfma_f32_32x32x16_bf16 v[2:17], v[218:221], v[206:209], v[2:17]
	v_mfma_f32_32x32x16_bf16 v[50:65], v[210:213], v[214:217], v[50:65]
	v_mfma_f32_32x32x16_bf16 v[34:49], v[222:225], v[214:217], v[34:49]
	global_load_dwordx4 v[202:205], v[178:179], off offset:768
	global_load_dwordx4 v[206:209], v[180:181], off offset:768
	global_load_dwordx4 v[214:217], v[182:183], off offset:768
	global_load_dwordx4 v[218:221], v[184:185], off offset:768
	global_load_dwordx4 v[230:233], v[66:67], off offset:768
	global_load_dwordx4 v[234:237], v[70:71], off offset:768
	s_waitcnt lgkmcnt(0)
	v_mfma_f32_32x32x16_bf16 v[18:33], v[210:213], v[226:229], v[18:33]
	global_load_dwordx4 v[210:213], v[68:69], off offset:768
	global_load_dwordx4 v[238:241], v[72:73], off offset:768
	s_setprio 1
	s_waitcnt vmcnt(7)
	ds_write_b128 v196, v[202:205]
	s_waitcnt vmcnt(6)
	ds_write_b128 v196, v[206:209] offset:4608
	s_waitcnt vmcnt(5)
	ds_write_b128 v196, v[214:217] offset:9216
	s_waitcnt vmcnt(4)
	ds_write_b128 v196, v[218:221] offset:13824
	s_waitcnt vmcnt(3)
	ds_write_b128 v196, v[230:233] offset:36864
	s_waitcnt vmcnt(2)
	ds_write_b128 v196, v[234:237] offset:41472
	s_waitcnt vmcnt(1)
	ds_write_b128 v196, v[210:213] offset:46080
	s_waitcnt vmcnt(0)
	ds_write_b128 v196, v[238:241] offset:50688
	v_mfma_f32_32x32x16_bf16 v[2:17], v[222:225], v[226:229], v[2:17]
	s_waitcnt lgkmcnt(0)
	s_barrier
	s_setprio 0
	ds_read_b128 v[202:205], v193
	ds_read_b128 v[206:209], v195 offset:36864
	ds_read_b128 v[210:213], v193 offset:32
	ds_read_b128 v[214:217], v195 offset:36896
	ds_read_b128 v[218:221], v193 offset:4608
	ds_read_b128 v[222:225], v193 offset:4640
	s_waitcnt lgkmcnt(4)
	v_mfma_f32_32x32x16_bf16 v[50:65], v[202:205], v[206:209], v[50:65]
	s_waitcnt lgkmcnt(1)
	v_mfma_f32_32x32x16_bf16 v[34:49], v[218:221], v[206:209], v[34:49]
	ds_read_b128 v[206:209], v195 offset:41472
	ds_read_b128 v[226:229], v195 offset:41504
	s_waitcnt lgkmcnt(1)
	v_mfma_f32_32x32x16_bf16 v[18:33], v[202:205], v[206:209], v[18:33]
	v_mfma_f32_32x32x16_bf16 v[2:17], v[218:221], v[206:209], v[2:17]
	v_mfma_f32_32x32x16_bf16 v[50:65], v[210:213], v[214:217], v[50:65]
	v_mfma_f32_32x32x16_bf16 v[34:49], v[222:225], v[214:217], v[34:49]
	s_waitcnt lgkmcnt(0)
	v_mfma_f32_32x32x16_bf16 v[18:33], v[210:213], v[226:229], v[18:33]
	ds_read_b128 v[202:205], v193 offset:64
	ds_read_b128 v[206:209], v195 offset:36928
	ds_read_b128 v[210:213], v193 offset:96
	ds_read_b128 v[214:217], v195 offset:36960
	v_mfma_f32_32x32x16_bf16 v[2:17], v[222:225], v[226:229], v[2:17]
	ds_read_b128 v[218:221], v193 offset:4672
	ds_read_b128 v[222:225], v193 offset:4704
	s_waitcnt lgkmcnt(4)
	v_mfma_f32_32x32x16_bf16 v[50:65], v[202:205], v[206:209], v[50:65]
	s_waitcnt lgkmcnt(1)
	v_mfma_f32_32x32x16_bf16 v[34:49], v[218:221], v[206:209], v[34:49]
	ds_read_b128 v[206:209], v195 offset:41536
	ds_read_b128 v[226:229], v195 offset:41568
	s_waitcnt lgkmcnt(1)
	v_mfma_f32_32x32x16_bf16 v[18:33], v[202:205], v[206:209], v[18:33]
	v_mfma_f32_32x32x16_bf16 v[2:17], v[218:221], v[206:209], v[2:17]
	v_mfma_f32_32x32x16_bf16 v[50:65], v[210:213], v[214:217], v[50:65]
	v_mfma_f32_32x32x16_bf16 v[34:49], v[222:225], v[214:217], v[34:49]
	global_load_dwordx4 v[202:205], v[178:179], off offset:896
	s_nop 0
	global_load_dwordx4 v[178:181], v[180:181], off offset:896
	s_nop 0
	global_load_dwordx4 v[206:209], v[182:183], off offset:896
	s_nop 0
	global_load_dwordx4 v[182:185], v[184:185], off offset:896
	s_nop 0
	global_load_dwordx4 v[214:217], v[66:67], off offset:896
	global_load_dwordx4 v[218:221], v[70:71], off offset:896
	s_nop 0
	global_load_dwordx4 v[66:69], v[68:69], off offset:896
	s_nop 0
	global_load_dwordx4 v[70:73], v[72:73], off offset:896
	s_setprio 1
	s_waitcnt vmcnt(7)
	ds_write_b128 v196, v[202:205] offset:18432
	s_waitcnt vmcnt(6)
	ds_write_b128 v196, v[178:181] offset:23040
	s_waitcnt vmcnt(5)
	ds_write_b128 v196, v[206:209] offset:27648
	s_waitcnt vmcnt(4)
	ds_write_b128 v196, v[182:185] offset:32256
	s_waitcnt vmcnt(3)
	ds_write_b128 v196, v[214:217] offset:55296
	s_waitcnt vmcnt(2)
	ds_write_b128 v196, v[218:221] offset:59904
	s_waitcnt vmcnt(1)
	ds_write_b128 v196, v[66:69] offset:64512
	s_waitcnt vmcnt(0)
	ds_write_b128 v197, v[70:73] offset:32256
	s_waitcnt lgkmcnt(8)
	v_mfma_f32_32x32x16_bf16 v[18:33], v[210:213], v[226:229], v[18:33]
	s_waitcnt lgkmcnt(0)
	s_barrier
	s_setprio 0
	ds_read_b128 v[66:69], v193 offset:18432
	ds_read_b128 v[70:73], v195 offset:55296
	ds_read_b128 v[178:181], v193 offset:18464
	ds_read_b128 v[182:185], v195 offset:55328
	ds_read_b128 v[202:205], v193 offset:23040
	ds_read_b128 v[206:209], v193 offset:23072
	v_mfma_f32_32x32x16_bf16 v[2:17], v[222:225], v[226:229], v[2:17]
	s_waitcnt lgkmcnt(4)
	v_mfma_f32_32x32x16_bf16 v[50:65], v[66:69], v[70:73], v[50:65]
	s_waitcnt lgkmcnt(1)
	v_mfma_f32_32x32x16_bf16 v[34:49], v[202:205], v[70:73], v[34:49]
	ds_read_b128 v[70:73], v195 offset:59904
	ds_read_b128 v[210:213], v195 offset:59936
	s_waitcnt lgkmcnt(1)
	v_mfma_f32_32x32x16_bf16 v[18:33], v[66:69], v[70:73], v[18:33]
	v_mfma_f32_32x32x16_bf16 v[2:17], v[202:205], v[70:73], v[2:17]
	v_mfma_f32_32x32x16_bf16 v[50:65], v[178:181], v[182:185], v[50:65]
	v_mfma_f32_32x32x16_bf16 v[34:49], v[206:209], v[182:185], v[34:49]
	s_waitcnt lgkmcnt(0)
	v_mfma_f32_32x32x16_bf16 v[18:33], v[178:181], v[210:213], v[18:33]
	ds_read_b128 v[66:69], v193 offset:18496
	ds_read_b128 v[70:73], v195 offset:55360
	ds_read_b128 v[178:181], v193 offset:18528
	ds_read_b128 v[182:185], v195 offset:55392
	v_mfma_f32_32x32x16_bf16 v[2:17], v[206:209], v[210:213], v[2:17]
	ds_read_b128 v[202:205], v193 offset:23104
	ds_read_b128 v[206:209], v193 offset:23136
	s_waitcnt lgkmcnt(4)
	v_mfma_f32_32x32x16_bf16 v[50:65], v[66:69], v[70:73], v[50:65]
	s_waitcnt lgkmcnt(1)
	v_mfma_f32_32x32x16_bf16 v[34:49], v[202:205], v[70:73], v[34:49]
	ds_read_b128 v[70:73], v195 offset:59968
	ds_read_b128 v[210:213], v195 offset:60000
	s_waitcnt lgkmcnt(0)
	s_barrier
	v_mfma_f32_32x32x16_bf16 v[18:33], v[66:69], v[70:73], v[18:33]
	v_mfma_f32_32x32x16_bf16 v[2:17], v[202:205], v[70:73], v[2:17]
	v_mfma_f32_32x32x16_bf16 v[50:65], v[178:181], v[182:185], v[50:65]
	v_mfma_f32_32x32x16_bf16 v[34:49], v[206:209], v[182:185], v[34:49]
	v_mfma_f32_32x32x16_bf16 v[18:33], v[178:181], v[210:213], v[18:33]
	v_mfma_f32_32x32x16_bf16 v[2:17], v[206:209], v[210:213], v[2:17]
	s_cbranch_scc1 .LBB0_902
	s_cmp_lg_u32 s17, 1
	s_mov_b64 s[4:5], -1
	s_cbranch_scc0 .LBB0_906
	s_mov_b64 s[4:5], 0

.LBB0_979:
	s_lshr_b32 s0, s2, 2
	s_and_b32 s2, s2, 3
	s_or_b32 s2, s2, s8
	s_lshl_b32 s2, s2, 7
	v_or_b32_e32 v2, s2, v89
	v_lshlrev_b32_e32 v66, 11, v2
	s_add_i32 s0, s0, s9
	v_lshl_add_u64 v[72:73], v[68:69], 0, v[66:67]
	v_add_lshl_u32 v66, s2, v90, 11
	s_lshl_b32 s3, s0, 7
	v_lshl_add_u64 v[74:75], v[68:69], 0, v[66:67]
	v_add_lshl_u32 v66, s2, v91, 11
	v_lshl_add_u64 v[76:77], v[68:69], 0, v[66:67]
	v_add_lshl_u32 v66, s2, v92, 11
	v_or_b32_e32 v2, s3, v89
	v_lshl_add_u64 v[78:79], v[68:69], 0, v[66:67]
	v_lshlrev_b32_e32 v66, 11, v2
	v_lshl_add_u64 v[80:81], v[70:71], 0, v[66:67]
	v_add_lshl_u32 v66, s3, v90, 11
	v_lshl_add_u64 v[82:83], v[70:71], 0, v[66:67]
	v_add_lshl_u32 v66, s3, v91, 11
	v_lshl_add_u64 v[84:85], v[70:71], 0, v[66:67]
	v_add_lshl_u32 v66, s3, v92, 11
	v_lshl_add_u64 v[86:87], v[70:71], 0, v[66:67]
	global_load_dwordx4 v[2:5], v[72:73], off
	global_load_dwordx4 v[6:9], v[74:75], off
	global_load_dwordx4 v[10:13], v[76:77], off
	global_load_dwordx4 v[14:17], v[78:79], off
	global_load_dwordx4 v[18:21], v[80:81], off
	global_load_dwordx4 v[22:25], v[82:83], off
	global_load_dwordx4 v[26:29], v[84:85], off
	global_load_dwordx4 v[30:33], v[86:87], off
	global_load_dwordx4 v[98:101], v[72:73], off offset:128
	global_load_dwordx4 v[102:105], v[74:75], off offset:128
	global_load_dwordx4 v[106:109], v[76:77], off offset:128
	global_load_dwordx4 v[110:113], v[78:79], off offset:128
	global_load_dwordx4 v[114:117], v[80:81], off offset:128
	global_load_dwordx4 v[118:121], v[82:83], off offset:128
	global_load_dwordx4 v[122:125], v[84:85], off offset:128
	global_load_dwordx4 v[126:129], v[86:87], off offset:128
	s_setprio 1
	s_waitcnt vmcnt(15)
	ds_write_b128 v95, v[2:5]
	s_waitcnt vmcnt(14)
	ds_write_b128 v95, v[6:9] offset:4608
	s_waitcnt vmcnt(13)
	ds_write_b128 v95, v[10:13] offset:9216
	s_waitcnt vmcnt(12)
	ds_write_b128 v95, v[14:17] offset:13824
	s_waitcnt vmcnt(11)
	ds_write_b128 v95, v[18:21] offset:36864
	s_waitcnt vmcnt(10)
	ds_write_b128 v95, v[22:25] offset:41472
	s_waitcnt vmcnt(9)
	ds_write_b128 v95, v[26:29] offset:46080
	s_waitcnt vmcnt(8)
	ds_write_b128 v95, v[30:33] offset:50688
	s_waitcnt lgkmcnt(0)
	s_barrier
	s_setprio 0
	global_load_dwordx4 v[136:139], v[72:73], off offset:256
	global_load_dwordx4 v[140:143], v[74:75], off offset:256
	global_load_dwordx4 v[144:147], v[76:77], off offset:256
	global_load_dwordx4 v[148:151], v[78:79], off offset:256
	global_load_dwordx4 v[152:155], v[80:81], off offset:256
	global_load_dwordx4 v[156:159], v[82:83], off offset:256
	global_load_dwordx4 v[160:163], v[84:85], off offset:256
	global_load_dwordx4 v[164:167], v[86:87], off offset:256
	v_and_b32_e32 v246, 15, v1
	v_add_u32_e32 v246, 4, v246
	v_bfe_u32 v246, v246, 3, 1
	v_bfe_u32 v249, v1, 4, 2
	v_xor_b32_e32 v246, v246, v249
	v_bfe_u32 v249, v1, 5, 1
	v_sub_u32_e32 v246, v246, v249
	v_lshlrev_b32_e32 v246, 4, v246
	v_bfe_u32 v249, v1, 4, 1
	v_mul_u32_u24_e32 v249, 0x900, v249
	v_sub_u32_e32 v246, v246, v249
	v_add_u32_e32 v244, v246, v93
	v_add_u32_e32 v245, v246, v94
	ds_read_b128 v[212:215], v245 offset:36864
	ds_read_b128 v[196:199], v244
	ds_read_b128 v[216:219], v245 offset:39168
	ds_read_b128 v[220:223], v245 offset:41472
	ds_read_b128 v[224:227], v245 offset:43776
	ds_read_b128 v[200:203], v244 offset:2304
	ds_read_b128 v[204:207], v244 offset:4608
	ds_read_b128 v[208:211], v244 offset:6912
	s_waitcnt lgkmcnt(6)
	v_mfma_f32_16x16x32_bf16 v[34:37], v[196:199], v[212:215], 0
	ds_read_b128 v[228:231], v245 offset:36928
	s_waitcnt lgkmcnt(6)
	v_mfma_f32_16x16x32_bf16 v[38:41], v[196:199], v[216:219], 0
	ds_read_b128 v[232:235], v245 offset:39232
	s_waitcnt lgkmcnt(6)
	v_mfma_f32_16x16x32_bf16 v[2:5], v[196:199], v[220:223], 0
	ds_read_b128 v[236:239], v245 offset:41536
	s_waitcnt lgkmcnt(6)
	v_mfma_f32_16x16x32_bf16 v[6:9], v[196:199], v[224:227], 0
	ds_read_b128 v[240:243], v245 offset:43840
	ds_read_b128 v[196:199], v244 offset:64
	s_waitcnt lgkmcnt(7)
	v_mfma_f32_16x16x32_bf16 v[42:45], v[200:203], v[212:215], 0
	v_mfma_f32_16x16x32_bf16 v[46:49], v[200:203], v[216:219], 0
	v_mfma_f32_16x16x32_bf16 v[10:13], v[200:203], v[220:223], 0
	v_mfma_f32_16x16x32_bf16 v[14:17], v[200:203], v[224:227], 0
	ds_read_b128 v[200:203], v244 offset:2368
	s_waitcnt lgkmcnt(7)
	v_mfma_f32_16x16x32_bf16 v[50:53], v[204:207], v[212:215], 0
	v_mfma_f32_16x16x32_bf16 v[54:57], v[204:207], v[216:219], 0
	v_mfma_f32_16x16x32_bf16 v[18:21], v[204:207], v[220:223], 0
	v_mfma_f32_16x16x32_bf16 v[22:25], v[204:207], v[224:227], 0
	ds_read_b128 v[204:207], v244 offset:4672
	s_setprio 1
	s_waitcnt vmcnt(15)
	ds_write_b128 v95, v[98:101] offset:18432
	s_waitcnt vmcnt(14)
	ds_write_b128 v95, v[102:105] offset:23040
	s_waitcnt lgkmcnt(9)
	v_mfma_f32_16x16x32_bf16 v[58:61], v[208:211], v[212:215], 0
	v_mfma_f32_16x16x32_bf16 v[62:65], v[208:211], v[216:219], 0
	v_mfma_f32_16x16x32_bf16 v[26:29], v[208:211], v[220:223], 0
	v_mfma_f32_16x16x32_bf16 v[30:33], v[208:211], v[224:227], 0
	ds_read_b128 v[208:211], v244 offset:6976
	s_waitcnt vmcnt(13)
	ds_write_b128 v95, v[106:109] offset:27648
	s_waitcnt vmcnt(12)
	ds_write_b128 v95, v[110:113] offset:32256
	s_waitcnt lgkmcnt(7)
	v_mfma_f32_16x16x32_bf16 v[34:37], v[196:199], v[228:231], v[34:37]
	v_mfma_f32_16x16x32_bf16 v[38:41], v[196:199], v[232:235], v[38:41]
	v_mfma_f32_16x16x32_bf16 v[2:5], v[196:199], v[236:239], v[2:5]
	v_mfma_f32_16x16x32_bf16 v[6:9], v[196:199], v[240:243], v[6:9]
	s_waitcnt vmcnt(11)
	ds_write_b128 v95, v[114:117] offset:55296
	s_waitcnt vmcnt(10)
	ds_write_b128 v95, v[118:121] offset:59904
	s_waitcnt lgkmcnt(8)
	v_mfma_f32_16x16x32_bf16 v[42:45], v[200:203], v[228:231], v[42:45]
	v_mfma_f32_16x16x32_bf16 v[46:49], v[200:203], v[232:235], v[46:49]
	v_mfma_f32_16x16x32_bf16 v[10:13], v[200:203], v[236:239], v[10:13]
	v_mfma_f32_16x16x32_bf16 v[14:17], v[200:203], v[240:243], v[14:17]
	s_waitcnt vmcnt(9)
	ds_write_b128 v95, v[122:125] offset:64512
	s_waitcnt vmcnt(8)
	ds_write_b128 v96, v[126:129] offset:32256
	s_waitcnt lgkmcnt(0)
	s_barrier
	s_setprio 0
	ds_read_b128 v[212:215], v245 offset:55296
	ds_read_b128 v[196:199], v244 offset:18432
	ds_read_b128 v[216:219], v245 offset:57600
	ds_read_b128 v[220:223], v245 offset:59904
	ds_read_b128 v[224:227], v245 offset:62208
	ds_read_b128 v[200:203], v244 offset:20736
	v_mfma_f32_16x16x32_bf16 v[50:53], v[204:207], v[228:231], v[50:53]
	v_mfma_f32_16x16x32_bf16 v[54:57], v[204:207], v[232:235], v[54:57]
	v_mfma_f32_16x16x32_bf16 v[18:21], v[204:207], v[236:239], v[18:21]
	v_mfma_f32_16x16x32_bf16 v[22:25], v[204:207], v[240:243], v[22:25]
	ds_read_b128 v[204:207], v244 offset:23040
	v_mfma_f32_16x16x32_bf16 v[58:61], v[208:211], v[228:231], v[58:61]
	v_mfma_f32_16x16x32_bf16 v[62:65], v[208:211], v[232:235], v[62:65]
	v_mfma_f32_16x16x32_bf16 v[26:29], v[208:211], v[236:239], v[26:29]
	v_mfma_f32_16x16x32_bf16 v[30:33], v[208:211], v[240:243], v[30:33]
	ds_read_b128 v[208:211], v244 offset:25344
	global_load_dwordx4 v[98:101], v[72:73], off offset:384
	global_load_dwordx4 v[102:105], v[74:75], off offset:384
	global_load_dwordx4 v[106:109], v[76:77], off offset:384
	global_load_dwordx4 v[110:113], v[78:79], off offset:384
	global_load_dwordx4 v[114:117], v[80:81], off offset:384
	global_load_dwordx4 v[118:121], v[82:83], off offset:384
	global_load_dwordx4 v[122:125], v[84:85], off offset:384
	global_load_dwordx4 v[126:129], v[86:87], off offset:384
	s_waitcnt lgkmcnt(6)
	v_mfma_f32_16x16x32_bf16 v[34:37], v[196:199], v[212:215], v[34:37]
	ds_read_b128 v[228:231], v245 offset:55360
	s_waitcnt lgkmcnt(6)
	v_mfma_f32_16x16x32_bf16 v[38:41], v[196:199], v[216:219], v[38:41]
	ds_read_b128 v[232:235], v245 offset:57664
	s_waitcnt lgkmcnt(6)
	v_mfma_f32_16x16x32_bf16 v[2:5], v[196:199], v[220:223], v[2:5]
	ds_read_b128 v[236:239], v245 offset:59968
	s_waitcnt lgkmcnt(6)
	v_mfma_f32_16x16x32_bf16 v[6:9], v[196:199], v[224:227], v[6:9]
	ds_read_b128 v[240:243], v245 offset:62272
	ds_read_b128 v[196:199], v244 offset:18496
	s_waitcnt lgkmcnt(7)
	v_mfma_f32_16x16x32_bf16 v[42:45], v[200:203], v[212:215], v[42:45]
	v_mfma_f32_16x16x32_bf16 v[46:49], v[200:203], v[216:219], v[46:49]
	v_mfma_f32_16x16x32_bf16 v[10:13], v[200:203], v[220:223], v[10:13]
	v_mfma_f32_16x16x32_bf16 v[14:17], v[200:203], v[224:227], v[14:17]
	ds_read_b128 v[200:203], v244 offset:20800
	s_waitcnt lgkmcnt(7)
	v_mfma_f32_16x16x32_bf16 v[50:53], v[204:207], v[212:215], v[50:53]
	v_mfma_f32_16x16x32_bf16 v[54:57], v[204:207], v[216:219], v[54:57]
	v_mfma_f32_16x16x32_bf16 v[18:21], v[204:207], v[220:223], v[18:21]
	v_mfma_f32_16x16x32_bf16 v[22:25], v[204:207], v[224:227], v[22:25]
	ds_read_b128 v[204:207], v244 offset:23104
	s_setprio 1
	s_waitcnt vmcnt(15)
	ds_write_b128 v95, v[136:139]
	s_waitcnt vmcnt(14)
	ds_write_b128 v95, v[140:143] offset:4608
	s_waitcnt lgkmcnt(9)
	v_mfma_f32_16x16x32_bf16 v[58:61], v[208:211], v[212:215], v[58:61]
	v_mfma_f32_16x16x32_bf16 v[62:65], v[208:211], v[216:219], v[62:65]
	v_mfma_f32_16x16x32_bf16 v[26:29], v[208:211], v[220:223], v[26:29]
	v_mfma_f32_16x16x32_bf16 v[30:33], v[208:211], v[224:227], v[30:33]
	ds_read_b128 v[208:211], v244 offset:25408
	s_waitcnt vmcnt(13)
	ds_write_b128 v95, v[144:147] offset:9216
	s_waitcnt vmcnt(12)
	ds_write_b128 v95, v[148:151] offset:13824
	s_waitcnt lgkmcnt(7)
	v_mfma_f32_16x16x32_bf16 v[34:37], v[196:199], v[228:231], v[34:37]
	v_mfma_f32_16x16x32_bf16 v[38:41], v[196:199], v[232:235], v[38:41]
	v_mfma_f32_16x16x32_bf16 v[2:5], v[196:199], v[236:239], v[2:5]
	v_mfma_f32_16x16x32_bf16 v[6:9], v[196:199], v[240:243], v[6:9]
	s_waitcnt vmcnt(11)
	ds_write_b128 v95, v[152:155] offset:36864
	s_waitcnt vmcnt(10)
	ds_write_b128 v95, v[156:159] offset:41472
	s_waitcnt lgkmcnt(8)
	v_mfma_f32_16x16x32_bf16 v[42:45], v[200:203], v[228:231], v[42:45]
	v_mfma_f32_16x16x32_bf16 v[46:49], v[200:203], v[232:235], v[46:49]
	v_mfma_f32_16x16x32_bf16 v[10:13], v[200:203], v[236:239], v[10:13]
	v_mfma_f32_16x16x32_bf16 v[14:17], v[200:203], v[240:243], v[14:17]
	s_waitcnt vmcnt(9)
	ds_write_b128 v95, v[160:163] offset:46080
	s_waitcnt vmcnt(8)
	ds_write_b128 v95, v[164:167] offset:50688
	s_waitcnt lgkmcnt(0)
	s_barrier
	s_setprio 0
	ds_read_b128 v[212:215], v245 offset:36864
	ds_read_b128 v[196:199], v244
	ds_read_b128 v[216:219], v245 offset:39168
	ds_read_b128 v[220:223], v245 offset:41472
	ds_read_b128 v[224:227], v245 offset:43776
	ds_read_b128 v[200:203], v244 offset:2304
	v_mfma_f32_16x16x32_bf16 v[50:53], v[204:207], v[228:231], v[50:53]
	v_mfma_f32_16x16x32_bf16 v[54:57], v[204:207], v[232:235], v[54:57]
	v_mfma_f32_16x16x32_bf16 v[18:21], v[204:207], v[236:239], v[18:21]
	v_mfma_f32_16x16x32_bf16 v[22:25], v[204:207], v[240:243], v[22:25]
	ds_read_b128 v[204:207], v244 offset:4608
	v_mfma_f32_16x16x32_bf16 v[58:61], v[208:211], v[228:231], v[58:61]
	v_mfma_f32_16x16x32_bf16 v[62:65], v[208:211], v[232:235], v[62:65]
	v_mfma_f32_16x16x32_bf16 v[26:29], v[208:211], v[236:239], v[26:29]
	v_mfma_f32_16x16x32_bf16 v[30:33], v[208:211], v[240:243], v[30:33]
	ds_read_b128 v[208:211], v244 offset:6912
	global_load_dwordx4 v[136:139], v[72:73], off offset:512
	global_load_dwordx4 v[140:143], v[74:75], off offset:512
	global_load_dwordx4 v[144:147], v[76:77], off offset:512
	global_load_dwordx4 v[148:151], v[78:79], off offset:512
	global_load_dwordx4 v[152:155], v[80:81], off offset:512
	global_load_dwordx4 v[156:159], v[82:83], off offset:512
	global_load_dwordx4 v[160:163], v[84:85], off offset:512
	global_load_dwordx4 v[164:167], v[86:87], off offset:512
	s_waitcnt lgkmcnt(6)
	v_mfma_f32_16x16x32_bf16 v[34:37], v[196:199], v[212:215], v[34:37]
	ds_read_b128 v[228:231], v245 offset:36928
	s_waitcnt lgkmcnt(6)
	v_mfma_f32_16x16x32_bf16 v[38:41], v[196:199], v[216:219], v[38:41]
	ds_read_b128 v[232:235], v245 offset:39232
	s_waitcnt lgkmcnt(6)
	v_mfma_f32_16x16x32_bf16 v[2:5], v[196:199], v[220:223], v[2:5]
	ds_read_b128 v[236:239], v245 offset:41536
	s_waitcnt lgkmcnt(6)
	v_mfma_f32_16x16x32_bf16 v[6:9], v[196:199], v[224:227], v[6:9]
	ds_read_b128 v[240:243], v245 offset:43840
	ds_read_b128 v[196:199], v244 offset:64
	s_waitcnt lgkmcnt(7)
	v_mfma_f32_16x16x32_bf16 v[42:45], v[200:203], v[212:215], v[42:45]
	v_mfma_f32_16x16x32_bf16 v[46:49], v[200:203], v[216:219], v[46:49]
	v_mfma_f32_16x16x32_bf16 v[10:13], v[200:203], v[220:223], v[10:13]
	v_mfma_f32_16x16x32_bf16 v[14:17], v[200:203], v[224:227], v[14:17]
	ds_read_b128 v[200:203], v244 offset:2368
	s_waitcnt lgkmcnt(7)
	v_mfma_f32_16x16x32_bf16 v[50:53], v[204:207], v[212:215], v[50:53]
	v_mfma_f32_16x16x32_bf16 v[54:57], v[204:207], v[216:219], v[54:57]
	v_mfma_f32_16x16x32_bf16 v[18:21], v[204:207], v[220:223], v[18:21]
	v_mfma_f32_16x16x32_bf16 v[22:25], v[204:207], v[224:227], v[22:25]
	ds_read_b128 v[204:207], v244 offset:4672
	s_setprio 1
	s_waitcnt vmcnt(15)
	ds_write_b128 v95, v[98:101] offset:18432
	s_waitcnt vmcnt(14)
	ds_write_b128 v95, v[102:105] offset:23040
	s_waitcnt lgkmcnt(9)
	v_mfma_f32_16x16x32_bf16 v[58:61], v[208:211], v[212:215], v[58:61]
	v_mfma_f32_16x16x32_bf16 v[62:65], v[208:211], v[216:219], v[62:65]
	v_mfma_f32_16x16x32_bf16 v[26:29], v[208:211], v[220:223], v[26:29]
	v_mfma_f32_16x16x32_bf16 v[30:33], v[208:211], v[224:227], v[30:33]
	ds_read_b128 v[208:211], v244 offset:6976
	s_waitcnt vmcnt(13)
	ds_write_b128 v95, v[106:109] offset:27648
	s_waitcnt vmcnt(12)
	ds_write_b128 v95, v[110:113] offset:32256
	s_waitcnt lgkmcnt(7)
	v_mfma_f32_16x16x32_bf16 v[34:37], v[196:199], v[228:231], v[34:37]
	v_mfma_f32_16x16x32_bf16 v[38:41], v[196:199], v[232:235], v[38:41]
	v_mfma_f32_16x16x32_bf16 v[2:5], v[196:199], v[236:239], v[2:5]
	v_mfma_f32_16x16x32_bf16 v[6:9], v[196:199], v[240:243], v[6:9]
	s_waitcnt vmcnt(11)
	ds_write_b128 v95, v[114:117] offset:55296
	s_waitcnt vmcnt(10)
	ds_write_b128 v95, v[118:121] offset:59904
	s_waitcnt lgkmcnt(8)
	v_mfma_f32_16x16x32_bf16 v[42:45], v[200:203], v[228:231], v[42:45]
	v_mfma_f32_16x16x32_bf16 v[46:49], v[200:203], v[232:235], v[46:49]
	v_mfma_f32_16x16x32_bf16 v[10:13], v[200:203], v[236:239], v[10:13]
	v_mfma_f32_16x16x32_bf16 v[14:17], v[200:203], v[240:243], v[14:17]
	s_waitcnt vmcnt(9)
	ds_write_b128 v95, v[122:125] offset:64512
	s_waitcnt vmcnt(8)
	ds_write_b128 v96, v[126:129] offset:32256
	s_waitcnt lgkmcnt(0)
	s_barrier
	s_setprio 0
	ds_read_b128 v[212:215], v245 offset:55296
	ds_read_b128 v[196:199], v244 offset:18432
	ds_read_b128 v[216:219], v245 offset:57600
	ds_read_b128 v[220:223], v245 offset:59904
	ds_read_b128 v[224:227], v245 offset:62208
	ds_read_b128 v[200:203], v244 offset:20736
	v_mfma_f32_16x16x32_bf16 v[50:53], v[204:207], v[228:231], v[50:53]
	v_mfma_f32_16x16x32_bf16 v[54:57], v[204:207], v[232:235], v[54:57]
	v_mfma_f32_16x16x32_bf16 v[18:21], v[204:207], v[236:239], v[18:21]
	v_mfma_f32_16x16x32_bf16 v[22:25], v[204:207], v[240:243], v[22:25]
	ds_read_b128 v[204:207], v244 offset:23040
	v_mfma_f32_16x16x32_bf16 v[58:61], v[208:211], v[228:231], v[58:61]
	v_mfma_f32_16x16x32_bf16 v[62:65], v[208:211], v[232:235], v[62:65]
	v_mfma_f32_16x16x32_bf16 v[26:29], v[208:211], v[236:239], v[26:29]
	v_mfma_f32_16x16x32_bf16 v[30:33], v[208:211], v[240:243], v[30:33]
	ds_read_b128 v[208:211], v244 offset:25344
	global_load_dwordx4 v[98:101], v[72:73], off offset:640
	global_load_dwordx4 v[102:105], v[74:75], off offset:640
	global_load_dwordx4 v[106:109], v[76:77], off offset:640
	global_load_dwordx4 v[110:113], v[78:79], off offset:640
	global_load_dwordx4 v[114:117], v[80:81], off offset:640
	global_load_dwordx4 v[118:121], v[82:83], off offset:640
	global_load_dwordx4 v[122:125], v[84:85], off offset:640
	global_load_dwordx4 v[126:129], v[86:87], off offset:640
	s_waitcnt lgkmcnt(6)
	v_mfma_f32_16x16x32_bf16 v[34:37], v[196:199], v[212:215], v[34:37]
	ds_read_b128 v[228:231], v245 offset:55360
	s_waitcnt lgkmcnt(6)
	v_mfma_f32_16x16x32_bf16 v[38:41], v[196:199], v[216:219], v[38:41]
	ds_read_b128 v[232:235], v245 offset:57664
	s_waitcnt lgkmcnt(6)
	v_mfma_f32_16x16x32_bf16 v[2:5], v[196:199], v[220:223], v[2:5]
	ds_read_b128 v[236:239], v245 offset:59968
	s_waitcnt lgkmcnt(6)
	v_mfma_f32_16x16x32_bf16 v[6:9], v[196:199], v[224:227], v[6:9]
	ds_read_b128 v[240:243], v245 offset:62272
	ds_read_b128 v[196:199], v244 offset:18496
	s_waitcnt lgkmcnt(7)
	v_mfma_f32_16x16x32_bf16 v[42:45], v[200:203], v[212:215], v[42:45]
	v_mfma_f32_16x16x32_bf16 v[46:49], v[200:203], v[216:219], v[46:49]
	v_mfma_f32_16x16x32_bf16 v[10:13], v[200:203], v[220:223], v[10:13]
	v_mfma_f32_16x16x32_bf16 v[14:17], v[200:203], v[224:227], v[14:17]
	ds_read_b128 v[200:203], v244 offset:20800
	s_waitcnt lgkmcnt(7)
	v_mfma_f32_16x16x32_bf16 v[50:53], v[204:207], v[212:215], v[50:53]
	v_mfma_f32_16x16x32_bf16 v[54:57], v[204:207], v[216:219], v[54:57]
	v_mfma_f32_16x16x32_bf16 v[18:21], v[204:207], v[220:223], v[18:21]
	v_mfma_f32_16x16x32_bf16 v[22:25], v[204:207], v[224:227], v[22:25]
	ds_read_b128 v[204:207], v244 offset:23104
	s_setprio 1
	s_waitcnt vmcnt(15)
	ds_write_b128 v95, v[136:139]
	s_waitcnt vmcnt(14)
	ds_write_b128 v95, v[140:143] offset:4608
	s_waitcnt lgkmcnt(9)
	v_mfma_f32_16x16x32_bf16 v[58:61], v[208:211], v[212:215], v[58:61]
	v_mfma_f32_16x16x32_bf16 v[62:65], v[208:211], v[216:219], v[62:65]
	v_mfma_f32_16x16x32_bf16 v[26:29], v[208:211], v[220:223], v[26:29]
	v_mfma_f32_16x16x32_bf16 v[30:33], v[208:211], v[224:227], v[30:33]
	ds_read_b128 v[208:211], v244 offset:25408
	s_waitcnt vmcnt(13)
	ds_write_b128 v95, v[144:147] offset:9216
	s_waitcnt vmcnt(12)
	ds_write_b128 v95, v[148:151] offset:13824
	s_waitcnt lgkmcnt(7)
	v_mfma_f32_16x16x32_bf16 v[34:37], v[196:199], v[228:231], v[34:37]
	v_mfma_f32_16x16x32_bf16 v[38:41], v[196:199], v[232:235], v[38:41]
	v_mfma_f32_16x16x32_bf16 v[2:5], v[196:199], v[236:239], v[2:5]
	v_mfma_f32_16x16x32_bf16 v[6:9], v[196:199], v[240:243], v[6:9]
	s_waitcnt vmcnt(11)
	ds_write_b128 v95, v[152:155] offset:36864
	s_waitcnt vmcnt(10)
	ds_write_b128 v95, v[156:159] offset:41472
	s_waitcnt lgkmcnt(8)
	v_mfma_f32_16x16x32_bf16 v[42:45], v[200:203], v[228:231], v[42:45]
	v_mfma_f32_16x16x32_bf16 v[46:49], v[200:203], v[232:235], v[46:49]
	v_mfma_f32_16x16x32_bf16 v[10:13], v[200:203], v[236:239], v[10:13]
	v_mfma_f32_16x16x32_bf16 v[14:17], v[200:203], v[240:243], v[14:17]
	s_waitcnt vmcnt(9)
	ds_write_b128 v95, v[160:163] offset:46080
	s_waitcnt vmcnt(8)
	ds_write_b128 v95, v[164:167] offset:50688
	s_waitcnt lgkmcnt(0)
	s_barrier
	s_setprio 0
	ds_read_b128 v[212:215], v245 offset:36864
	ds_read_b128 v[196:199], v244
	ds_read_b128 v[216:219], v245 offset:39168
	ds_read_b128 v[220:223], v245 offset:41472
	ds_read_b128 v[224:227], v245 offset:43776
	ds_read_b128 v[200:203], v244 offset:2304
	v_mfma_f32_16x16x32_bf16 v[50:53], v[204:207], v[228:231], v[50:53]
	v_mfma_f32_16x16x32_bf16 v[54:57], v[204:207], v[232:235], v[54:57]
	v_mfma_f32_16x16x32_bf16 v[18:21], v[204:207], v[236:239], v[18:21]
	v_mfma_f32_16x16x32_bf16 v[22:25], v[204:207], v[240:243], v[22:25]
	ds_read_b128 v[204:207], v244 offset:4608
	v_mfma_f32_16x16x32_bf16 v[58:61], v[208:211], v[228:231], v[58:61]
	v_mfma_f32_16x16x32_bf16 v[62:65], v[208:211], v[232:235], v[62:65]
	v_mfma_f32_16x16x32_bf16 v[26:29], v[208:211], v[236:239], v[26:29]
	v_mfma_f32_16x16x32_bf16 v[30:33], v[208:211], v[240:243], v[30:33]
	ds_read_b128 v[208:211], v244 offset:6912
	global_load_dwordx4 v[136:139], v[72:73], off offset:768
	global_load_dwordx4 v[140:143], v[74:75], off offset:768
	global_load_dwordx4 v[144:147], v[76:77], off offset:768
	global_load_dwordx4 v[148:151], v[78:79], off offset:768
	global_load_dwordx4 v[152:155], v[80:81], off offset:768
	global_load_dwordx4 v[156:159], v[82:83], off offset:768
	global_load_dwordx4 v[160:163], v[84:85], off offset:768
	global_load_dwordx4 v[164:167], v[86:87], off offset:768
	s_waitcnt lgkmcnt(6)
	v_mfma_f32_16x16x32_bf16 v[34:37], v[196:199], v[212:215], v[34:37]
	ds_read_b128 v[228:231], v245 offset:36928
	s_waitcnt lgkmcnt(6)
	v_mfma_f32_16x16x32_bf16 v[38:41], v[196:199], v[216:219], v[38:41]
	ds_read_b128 v[232:235], v245 offset:39232
	s_waitcnt lgkmcnt(6)
	v_mfma_f32_16x16x32_bf16 v[2:5], v[196:199], v[220:223], v[2:5]
	ds_read_b128 v[236:239], v245 offset:41536
	s_waitcnt lgkmcnt(6)
	v_mfma_f32_16x16x32_bf16 v[6:9], v[196:199], v[224:227], v[6:9]
	ds_read_b128 v[240:243], v245 offset:43840
	ds_read_b128 v[196:199], v244 offset:64
	s_waitcnt lgkmcnt(7)
	v_mfma_f32_16x16x32_bf16 v[42:45], v[200:203], v[212:215], v[42:45]
	v_mfma_f32_16x16x32_bf16 v[46:49], v[200:203], v[216:219], v[46:49]
	v_mfma_f32_16x16x32_bf16 v[10:13], v[200:203], v[220:223], v[10:13]
	v_mfma_f32_16x16x32_bf16 v[14:17], v[200:203], v[224:227], v[14:17]
	ds_read_b128 v[200:203], v244 offset:2368
	s_waitcnt lgkmcnt(7)
	v_mfma_f32_16x16x32_bf16 v[50:53], v[204:207], v[212:215], v[50:53]
	v_mfma_f32_16x16x32_bf16 v[54:57], v[204:207], v[216:219], v[54:57]
	v_mfma_f32_16x16x32_bf16 v[18:21], v[204:207], v[220:223], v[18:21]
	v_mfma_f32_16x16x32_bf16 v[22:25], v[204:207], v[224:227], v[22:25]
	ds_read_b128 v[204:207], v244 offset:4672
	s_setprio 1
	s_waitcnt vmcnt(15)
	ds_write_b128 v95, v[98:101] offset:18432
	s_waitcnt vmcnt(14)
	ds_write_b128 v95, v[102:105] offset:23040
	s_waitcnt lgkmcnt(9)
	v_mfma_f32_16x16x32_bf16 v[58:61], v[208:211], v[212:215], v[58:61]
	v_mfma_f32_16x16x32_bf16 v[62:65], v[208:211], v[216:219], v[62:65]
	v_mfma_f32_16x16x32_bf16 v[26:29], v[208:211], v[220:223], v[26:29]
	v_mfma_f32_16x16x32_bf16 v[30:33], v[208:211], v[224:227], v[30:33]
	ds_read_b128 v[208:211], v244 offset:6976
	s_waitcnt vmcnt(13)
	ds_write_b128 v95, v[106:109] offset:27648
	s_waitcnt vmcnt(12)
	ds_write_b128 v95, v[110:113] offset:32256
	s_waitcnt lgkmcnt(7)
	v_mfma_f32_16x16x32_bf16 v[34:37], v[196:199], v[228:231], v[34:37]
	v_mfma_f32_16x16x32_bf16 v[38:41], v[196:199], v[232:235], v[38:41]
	v_mfma_f32_16x16x32_bf16 v[2:5], v[196:199], v[236:239], v[2:5]
	v_mfma_f32_16x16x32_bf16 v[6:9], v[196:199], v[240:243], v[6:9]
	s_waitcnt vmcnt(11)
	ds_write_b128 v95, v[114:117] offset:55296
	s_waitcnt vmcnt(10)
	ds_write_b128 v95, v[118:121] offset:59904
	s_waitcnt lgkmcnt(8)
	v_mfma_f32_16x16x32_bf16 v[42:45], v[200:203], v[228:231], v[42:45]
	v_mfma_f32_16x16x32_bf16 v[46:49], v[200:203], v[232:235], v[46:49]
	v_mfma_f32_16x16x32_bf16 v[10:13], v[200:203], v[236:239], v[10:13]
	v_mfma_f32_16x16x32_bf16 v[14:17], v[200:203], v[240:243], v[14:17]
	s_waitcnt vmcnt(9)
	ds_write_b128 v95, v[122:125] offset:64512
	s_waitcnt vmcnt(8)
	ds_write_b128 v96, v[126:129] offset:32256
	s_waitcnt lgkmcnt(0)
	s_barrier
	s_setprio 0
	ds_read_b128 v[212:215], v245 offset:55296
	ds_read_b128 v[196:199], v244 offset:18432
	ds_read_b128 v[216:219], v245 offset:57600
	ds_read_b128 v[220:223], v245 offset:59904
	ds_read_b128 v[224:227], v245 offset:62208
	ds_read_b128 v[200:203], v244 offset:20736
	v_mfma_f32_16x16x32_bf16 v[50:53], v[204:207], v[228:231], v[50:53]
	v_mfma_f32_16x16x32_bf16 v[54:57], v[204:207], v[232:235], v[54:57]
	v_mfma_f32_16x16x32_bf16 v[18:21], v[204:207], v[236:239], v[18:21]
	v_mfma_f32_16x16x32_bf16 v[22:25], v[204:207], v[240:243], v[22:25]
	ds_read_b128 v[204:207], v244 offset:23040
	v_mfma_f32_16x16x32_bf16 v[58:61], v[208:211], v[228:231], v[58:61]
	v_mfma_f32_16x16x32_bf16 v[62:65], v[208:211], v[232:235], v[62:65]
	v_mfma_f32_16x16x32_bf16 v[26:29], v[208:211], v[236:239], v[26:29]
	v_mfma_f32_16x16x32_bf16 v[30:33], v[208:211], v[240:243], v[30:33]
	ds_read_b128 v[208:211], v244 offset:25344
	global_load_dwordx4 v[98:101], v[72:73], off offset:896
	global_load_dwordx4 v[102:105], v[74:75], off offset:896
	global_load_dwordx4 v[106:109], v[76:77], off offset:896
	global_load_dwordx4 v[110:113], v[78:79], off offset:896
	global_load_dwordx4 v[114:117], v[80:81], off offset:896
	global_load_dwordx4 v[118:121], v[82:83], off offset:896
	global_load_dwordx4 v[122:125], v[84:85], off offset:896
	global_load_dwordx4 v[126:129], v[86:87], off offset:896
	s_waitcnt lgkmcnt(6)
	v_mfma_f32_16x16x32_bf16 v[34:37], v[196:199], v[212:215], v[34:37]
	ds_read_b128 v[228:231], v245 offset:55360
	s_waitcnt lgkmcnt(6)
	v_mfma_f32_16x16x32_bf16 v[38:41], v[196:199], v[216:219], v[38:41]
	ds_read_b128 v[232:235], v245 offset:57664
	s_waitcnt lgkmcnt(6)
	v_mfma_f32_16x16x32_bf16 v[2:5], v[196:199], v[220:223], v[2:5]
	ds_read_b128 v[236:239], v245 offset:59968
	s_waitcnt lgkmcnt(6)
	v_mfma_f32_16x16x32_bf16 v[6:9], v[196:199], v[224:227], v[6:9]
	ds_read_b128 v[240:243], v245 offset:62272
	ds_read_b128 v[196:199], v244 offset:18496
	s_waitcnt lgkmcnt(7)
	v_mfma_f32_16x16x32_bf16 v[42:45], v[200:203], v[212:215], v[42:45]
	v_mfma_f32_16x16x32_bf16 v[46:49], v[200:203], v[216:219], v[46:49]
	v_mfma_f32_16x16x32_bf16 v[10:13], v[200:203], v[220:223], v[10:13]
	v_mfma_f32_16x16x32_bf16 v[14:17], v[200:203], v[224:227], v[14:17]
	ds_read_b128 v[200:203], v244 offset:20800
	s_waitcnt lgkmcnt(7)
	v_mfma_f32_16x16x32_bf16 v[50:53], v[204:207], v[212:215], v[50:53]
	v_mfma_f32_16x16x32_bf16 v[54:57], v[204:207], v[216:219], v[54:57]
	v_mfma_f32_16x16x32_bf16 v[18:21], v[204:207], v[220:223], v[18:21]
	v_mfma_f32_16x16x32_bf16 v[22:25], v[204:207], v[224:227], v[22:25]
	ds_read_b128 v[204:207], v244 offset:23104
	s_setprio 1
	s_waitcnt vmcnt(15)
	ds_write_b128 v95, v[136:139]
	s_waitcnt vmcnt(14)
	ds_write_b128 v95, v[140:143] offset:4608
	s_waitcnt lgkmcnt(9)
	v_mfma_f32_16x16x32_bf16 v[58:61], v[208:211], v[212:215], v[58:61]
	v_mfma_f32_16x16x32_bf16 v[62:65], v[208:211], v[216:219], v[62:65]
	v_mfma_f32_16x16x32_bf16 v[26:29], v[208:211], v[220:223], v[26:29]
	v_mfma_f32_16x16x32_bf16 v[30:33], v[208:211], v[224:227], v[30:33]
	ds_read_b128 v[208:211], v244 offset:25408
	s_waitcnt vmcnt(13)
	ds_write_b128 v95, v[144:147] offset:9216
	s_waitcnt vmcnt(12)
	ds_write_b128 v95, v[148:151] offset:13824
	s_waitcnt lgkmcnt(7)
	v_mfma_f32_16x16x32_bf16 v[34:37], v[196:199], v[228:231], v[34:37]
	v_mfma_f32_16x16x32_bf16 v[38:41], v[196:199], v[232:235], v[38:41]
	v_mfma_f32_16x16x32_bf16 v[2:5], v[196:199], v[236:239], v[2:5]
	v_mfma_f32_16x16x32_bf16 v[6:9], v[196:199], v[240:243], v[6:9]
	s_waitcnt vmcnt(11)
	ds_write_b128 v95, v[152:155] offset:36864
	s_waitcnt vmcnt(10)
	ds_write_b128 v95, v[156:159] offset:41472
	s_waitcnt lgkmcnt(8)
	v_mfma_f32_16x16x32_bf16 v[42:45], v[200:203], v[228:231], v[42:45]
	v_mfma_f32_16x16x32_bf16 v[46:49], v[200:203], v[232:235], v[46:49]
	v_mfma_f32_16x16x32_bf16 v[10:13], v[200:203], v[236:239], v[10:13]
	v_mfma_f32_16x16x32_bf16 v[14:17], v[200:203], v[240:243], v[14:17]
	s_waitcnt vmcnt(9)
	ds_write_b128 v95, v[160:163] offset:46080
	s_waitcnt vmcnt(8)
	ds_write_b128 v95, v[164:167] offset:50688
	s_waitcnt lgkmcnt(0)
	s_barrier
	s_setprio 0
	ds_read_b128 v[212:215], v245 offset:36864
	ds_read_b128 v[196:199], v244
	ds_read_b128 v[216:219], v245 offset:39168
	ds_read_b128 v[220:223], v245 offset:41472
	ds_read_b128 v[224:227], v245 offset:43776
	ds_read_b128 v[200:203], v244 offset:2304
	v_mfma_f32_16x16x32_bf16 v[50:53], v[204:207], v[228:231], v[50:53]
	v_mfma_f32_16x16x32_bf16 v[54:57], v[204:207], v[232:235], v[54:57]
	v_mfma_f32_16x16x32_bf16 v[18:21], v[204:207], v[236:239], v[18:21]
	v_mfma_f32_16x16x32_bf16 v[22:25], v[204:207], v[240:243], v[22:25]
	ds_read_b128 v[204:207], v244 offset:4608
	v_mfma_f32_16x16x32_bf16 v[58:61], v[208:211], v[228:231], v[58:61]
	v_mfma_f32_16x16x32_bf16 v[62:65], v[208:211], v[232:235], v[62:65]
	v_mfma_f32_16x16x32_bf16 v[26:29], v[208:211], v[236:239], v[26:29]
	v_mfma_f32_16x16x32_bf16 v[30:33], v[208:211], v[240:243], v[30:33]
	ds_read_b128 v[208:211], v244 offset:6912
	global_load_dwordx4 v[136:139], v[72:73], off offset:1024
	global_load_dwordx4 v[140:143], v[74:75], off offset:1024
	global_load_dwordx4 v[144:147], v[76:77], off offset:1024
	global_load_dwordx4 v[148:151], v[78:79], off offset:1024
	global_load_dwordx4 v[152:155], v[80:81], off offset:1024
	global_load_dwordx4 v[156:159], v[82:83], off offset:1024
	global_load_dwordx4 v[160:163], v[84:85], off offset:1024
	global_load_dwordx4 v[164:167], v[86:87], off offset:1024
	s_waitcnt lgkmcnt(6)
	v_mfma_f32_16x16x32_bf16 v[34:37], v[196:199], v[212:215], v[34:37]
	ds_read_b128 v[228:231], v245 offset:36928
	s_waitcnt lgkmcnt(6)
	v_mfma_f32_16x16x32_bf16 v[38:41], v[196:199], v[216:219], v[38:41]
	ds_read_b128 v[232:235], v245 offset:39232
	s_waitcnt lgkmcnt(6)
	v_mfma_f32_16x16x32_bf16 v[2:5], v[196:199], v[220:223], v[2:5]
	ds_read_b128 v[236:239], v245 offset:41536
	s_waitcnt lgkmcnt(6)
	v_mfma_f32_16x16x32_bf16 v[6:9], v[196:199], v[224:227], v[6:9]
	ds_read_b128 v[240:243], v245 offset:43840
	ds_read_b128 v[196:199], v244 offset:64
	s_waitcnt lgkmcnt(7)
	v_mfma_f32_16x16x32_bf16 v[42:45], v[200:203], v[212:215], v[42:45]
	v_mfma_f32_16x16x32_bf16 v[46:49], v[200:203], v[216:219], v[46:49]
	v_mfma_f32_16x16x32_bf16 v[10:13], v[200:203], v[220:223], v[10:13]
	v_mfma_f32_16x16x32_bf16 v[14:17], v[200:203], v[224:227], v[14:17]
	ds_read_b128 v[200:203], v244 offset:2368
	s_waitcnt lgkmcnt(7)
	v_mfma_f32_16x16x32_bf16 v[50:53], v[204:207], v[212:215], v[50:53]
	v_mfma_f32_16x16x32_bf16 v[54:57], v[204:207], v[216:219], v[54:57]
	v_mfma_f32_16x16x32_bf16 v[18:21], v[204:207], v[220:223], v[18:21]
	v_mfma_f32_16x16x32_bf16 v[22:25], v[204:207], v[224:227], v[22:25]
	ds_read_b128 v[204:207], v244 offset:4672
	s_setprio 1
	s_waitcnt vmcnt(15)
	ds_write_b128 v95, v[98:101] offset:18432
	s_waitcnt vmcnt(14)
	ds_write_b128 v95, v[102:105] offset:23040
	s_waitcnt lgkmcnt(9)
	v_mfma_f32_16x16x32_bf16 v[58:61], v[208:211], v[212:215], v[58:61]
	v_mfma_f32_16x16x32_bf16 v[62:65], v[208:211], v[216:219], v[62:65]
	v_mfma_f32_16x16x32_bf16 v[26:29], v[208:211], v[220:223], v[26:29]
	v_mfma_f32_16x16x32_bf16 v[30:33], v[208:211], v[224:227], v[30:33]
	ds_read_b128 v[208:211], v244 offset:6976
	s_waitcnt vmcnt(13)
	ds_write_b128 v95, v[106:109] offset:27648
	s_waitcnt vmcnt(12)
	ds_write_b128 v95, v[110:113] offset:32256
	s_waitcnt lgkmcnt(7)
	v_mfma_f32_16x16x32_bf16 v[34:37], v[196:199], v[228:231], v[34:37]
	v_mfma_f32_16x16x32_bf16 v[38:41], v[196:199], v[232:235], v[38:41]
	v_mfma_f32_16x16x32_bf16 v[2:5], v[196:199], v[236:239], v[2:5]
	v_mfma_f32_16x16x32_bf16 v[6:9], v[196:199], v[240:243], v[6:9]
	s_waitcnt vmcnt(11)
	ds_write_b128 v95, v[114:117] offset:55296
	s_waitcnt vmcnt(10)
	ds_write_b128 v95, v[118:121] offset:59904
	s_waitcnt lgkmcnt(8)
	v_mfma_f32_16x16x32_bf16 v[42:45], v[200:203], v[228:231], v[42:45]
	v_mfma_f32_16x16x32_bf16 v[46:49], v[200:203], v[232:235], v[46:49]
	v_mfma_f32_16x16x32_bf16 v[10:13], v[200:203], v[236:239], v[10:13]
	v_mfma_f32_16x16x32_bf16 v[14:17], v[200:203], v[240:243], v[14:17]
	s_waitcnt vmcnt(9)
	ds_write_b128 v95, v[122:125] offset:64512
	s_waitcnt vmcnt(8)
	ds_write_b128 v96, v[126:129] offset:32256
	s_waitcnt lgkmcnt(0)
	s_barrier
	s_setprio 0
	ds_read_b128 v[212:215], v245 offset:55296
	ds_read_b128 v[196:199], v244 offset:18432
	ds_read_b128 v[216:219], v245 offset:57600
	ds_read_b128 v[220:223], v245 offset:59904
	ds_read_b128 v[224:227], v245 offset:62208
	ds_read_b128 v[200:203], v244 offset:20736
	v_mfma_f32_16x16x32_bf16 v[50:53], v[204:207], v[228:231], v[50:53]
	v_mfma_f32_16x16x32_bf16 v[54:57], v[204:207], v[232:235], v[54:57]
	v_mfma_f32_16x16x32_bf16 v[18:21], v[204:207], v[236:239], v[18:21]
	v_mfma_f32_16x16x32_bf16 v[22:25], v[204:207], v[240:243], v[22:25]
	ds_read_b128 v[204:207], v244 offset:23040
	v_mfma_f32_16x16x32_bf16 v[58:61], v[208:211], v[228:231], v[58:61]
	v_mfma_f32_16x16x32_bf16 v[62:65], v[208:211], v[232:235], v[62:65]
	v_mfma_f32_16x16x32_bf16 v[26:29], v[208:211], v[236:239], v[26:29]
	v_mfma_f32_16x16x32_bf16 v[30:33], v[208:211], v[240:243], v[30:33]
	ds_read_b128 v[208:211], v244 offset:25344
	global_load_dwordx4 v[98:101], v[72:73], off offset:1152
	global_load_dwordx4 v[102:105], v[74:75], off offset:1152
	global_load_dwordx4 v[106:109], v[76:77], off offset:1152
	global_load_dwordx4 v[110:113], v[78:79], off offset:1152
	global_load_dwordx4 v[114:117], v[80:81], off offset:1152
	global_load_dwordx4 v[118:121], v[82:83], off offset:1152
	global_load_dwordx4 v[122:125], v[84:85], off offset:1152
	global_load_dwordx4 v[126:129], v[86:87], off offset:1152
	s_waitcnt lgkmcnt(6)
	v_mfma_f32_16x16x32_bf16 v[34:37], v[196:199], v[212:215], v[34:37]
	ds_read_b128 v[228:231], v245 offset:55360
	s_waitcnt lgkmcnt(6)
	v_mfma_f32_16x16x32_bf16 v[38:41], v[196:199], v[216:219], v[38:41]
	ds_read_b128 v[232:235], v245 offset:57664
	s_waitcnt lgkmcnt(6)
	v_mfma_f32_16x16x32_bf16 v[2:5], v[196:199], v[220:223], v[2:5]
	ds_read_b128 v[236:239], v245 offset:59968
	s_waitcnt lgkmcnt(6)
	v_mfma_f32_16x16x32_bf16 v[6:9], v[196:199], v[224:227], v[6:9]
	ds_read_b128 v[240:243], v245 offset:62272
	ds_read_b128 v[196:199], v244 offset:18496
	s_waitcnt lgkmcnt(7)
	v_mfma_f32_16x16x32_bf16 v[42:45], v[200:203], v[212:215], v[42:45]
	v_mfma_f32_16x16x32_bf16 v[46:49], v[200:203], v[216:219], v[46:49]
	v_mfma_f32_16x16x32_bf16 v[10:13], v[200:203], v[220:223], v[10:13]
	v_mfma_f32_16x16x32_bf16 v[14:17], v[200:203], v[224:227], v[14:17]
	ds_read_b128 v[200:203], v244 offset:20800
	s_waitcnt lgkmcnt(7)
	v_mfma_f32_16x16x32_bf16 v[50:53], v[204:207], v[212:215], v[50:53]
	v_mfma_f32_16x16x32_bf16 v[54:57], v[204:207], v[216:219], v[54:57]
	v_mfma_f32_16x16x32_bf16 v[18:21], v[204:207], v[220:223], v[18:21]
	v_mfma_f32_16x16x32_bf16 v[22:25], v[204:207], v[224:227], v[22:25]
	ds_read_b128 v[204:207], v244 offset:23104
	s_setprio 1
	s_waitcnt vmcnt(15)
	ds_write_b128 v95, v[136:139]
	s_waitcnt vmcnt(14)
	ds_write_b128 v95, v[140:143] offset:4608
	s_waitcnt lgkmcnt(9)
	v_mfma_f32_16x16x32_bf16 v[58:61], v[208:211], v[212:215], v[58:61]
	v_mfma_f32_16x16x32_bf16 v[62:65], v[208:211], v[216:219], v[62:65]
	v_mfma_f32_16x16x32_bf16 v[26:29], v[208:211], v[220:223], v[26:29]
	v_mfma_f32_16x16x32_bf16 v[30:33], v[208:211], v[224:227], v[30:33]
	ds_read_b128 v[208:211], v244 offset:25408
	s_waitcnt vmcnt(13)
	ds_write_b128 v95, v[144:147] offset:9216
	s_waitcnt vmcnt(12)
	ds_write_b128 v95, v[148:151] offset:13824
	s_waitcnt lgkmcnt(7)
	v_mfma_f32_16x16x32_bf16 v[34:37], v[196:199], v[228:231], v[34:37]
	v_mfma_f32_16x16x32_bf16 v[38:41], v[196:199], v[232:235], v[38:41]
	v_mfma_f32_16x16x32_bf16 v[2:5], v[196:199], v[236:239], v[2:5]
	v_mfma_f32_16x16x32_bf16 v[6:9], v[196:199], v[240:243], v[6:9]
	s_waitcnt vmcnt(11)
	ds_write_b128 v95, v[152:155] offset:36864
	s_waitcnt vmcnt(10)
	ds_write_b128 v95, v[156:159] offset:41472
	s_waitcnt lgkmcnt(8)
	v_mfma_f32_16x16x32_bf16 v[42:45], v[200:203], v[228:231], v[42:45]
	v_mfma_f32_16x16x32_bf16 v[46:49], v[200:203], v[232:235], v[46:49]
	v_mfma_f32_16x16x32_bf16 v[10:13], v[200:203], v[236:239], v[10:13]
	v_mfma_f32_16x16x32_bf16 v[14:17], v[200:203], v[240:243], v[14:17]
	s_waitcnt vmcnt(9)
	ds_write_b128 v95, v[160:163] offset:46080
	s_waitcnt vmcnt(8)
	ds_write_b128 v95, v[164:167] offset:50688
	s_waitcnt lgkmcnt(0)
	s_barrier
	s_setprio 0
	ds_read_b128 v[212:215], v245 offset:36864
	ds_read_b128 v[196:199], v244
	ds_read_b128 v[216:219], v245 offset:39168
	ds_read_b128 v[220:223], v245 offset:41472
	ds_read_b128 v[224:227], v245 offset:43776
	ds_read_b128 v[200:203], v244 offset:2304
	v_mfma_f32_16x16x32_bf16 v[50:53], v[204:207], v[228:231], v[50:53]
	v_mfma_f32_16x16x32_bf16 v[54:57], v[204:207], v[232:235], v[54:57]
	v_mfma_f32_16x16x32_bf16 v[18:21], v[204:207], v[236:239], v[18:21]
	v_mfma_f32_16x16x32_bf16 v[22:25], v[204:207], v[240:243], v[22:25]
	ds_read_b128 v[204:207], v244 offset:4608
	v_mfma_f32_16x16x32_bf16 v[58:61], v[208:211], v[228:231], v[58:61]
	v_mfma_f32_16x16x32_bf16 v[62:65], v[208:211], v[232:235], v[62:65]
	v_mfma_f32_16x16x32_bf16 v[26:29], v[208:211], v[236:239], v[26:29]
	v_mfma_f32_16x16x32_bf16 v[30:33], v[208:211], v[240:243], v[30:33]
	ds_read_b128 v[208:211], v244 offset:6912
	global_load_dwordx4 v[136:139], v[72:73], off offset:1280
	global_load_dwordx4 v[140:143], v[74:75], off offset:1280
	global_load_dwordx4 v[144:147], v[76:77], off offset:1280
	global_load_dwordx4 v[148:151], v[78:79], off offset:1280
	global_load_dwordx4 v[152:155], v[80:81], off offset:1280
	global_load_dwordx4 v[156:159], v[82:83], off offset:1280
	global_load_dwordx4 v[160:163], v[84:85], off offset:1280
	global_load_dwordx4 v[164:167], v[86:87], off offset:1280
	s_waitcnt lgkmcnt(6)
	v_mfma_f32_16x16x32_bf16 v[34:37], v[196:199], v[212:215], v[34:37]
	ds_read_b128 v[228:231], v245 offset:36928
	s_waitcnt lgkmcnt(6)
	v_mfma_f32_16x16x32_bf16 v[38:41], v[196:199], v[216:219], v[38:41]
	ds_read_b128 v[232:235], v245 offset:39232
	s_waitcnt lgkmcnt(6)
	v_mfma_f32_16x16x32_bf16 v[2:5], v[196:199], v[220:223], v[2:5]
	ds_read_b128 v[236:239], v245 offset:41536
	s_waitcnt lgkmcnt(6)
	v_mfma_f32_16x16x32_bf16 v[6:9], v[196:199], v[224:227], v[6:9]
	ds_read_b128 v[240:243], v245 offset:43840
	ds_read_b128 v[196:199], v244 offset:64
	s_waitcnt lgkmcnt(7)
	v_mfma_f32_16x16x32_bf16 v[42:45], v[200:203], v[212:215], v[42:45]
	v_mfma_f32_16x16x32_bf16 v[46:49], v[200:203], v[216:219], v[46:49]
	v_mfma_f32_16x16x32_bf16 v[10:13], v[200:203], v[220:223], v[10:13]
	v_mfma_f32_16x16x32_bf16 v[14:17], v[200:203], v[224:227], v[14:17]
	ds_read_b128 v[200:203], v244 offset:2368
	s_waitcnt lgkmcnt(7)
	v_mfma_f32_16x16x32_bf16 v[50:53], v[204:207], v[212:215], v[50:53]
	v_mfma_f32_16x16x32_bf16 v[54:57], v[204:207], v[216:219], v[54:57]
	v_mfma_f32_16x16x32_bf16 v[18:21], v[204:207], v[220:223], v[18:21]
	v_mfma_f32_16x16x32_bf16 v[22:25], v[204:207], v[224:227], v[22:25]
	ds_read_b128 v[204:207], v244 offset:4672
	s_setprio 1
	s_waitcnt vmcnt(15)
	ds_write_b128 v95, v[98:101] offset:18432
	s_waitcnt vmcnt(14)
	ds_write_b128 v95, v[102:105] offset:23040
	s_waitcnt lgkmcnt(9)
	v_mfma_f32_16x16x32_bf16 v[58:61], v[208:211], v[212:215], v[58:61]
	v_mfma_f32_16x16x32_bf16 v[62:65], v[208:211], v[216:219], v[62:65]
	v_mfma_f32_16x16x32_bf16 v[26:29], v[208:211], v[220:223], v[26:29]
	v_mfma_f32_16x16x32_bf16 v[30:33], v[208:211], v[224:227], v[30:33]
	ds_read_b128 v[208:211], v244 offset:6976
	s_waitcnt vmcnt(13)
	ds_write_b128 v95, v[106:109] offset:27648
	s_waitcnt vmcnt(12)
	ds_write_b128 v95, v[110:113] offset:32256
	s_waitcnt lgkmcnt(7)
	v_mfma_f32_16x16x32_bf16 v[34:37], v[196:199], v[228:231], v[34:37]
	v_mfma_f32_16x16x32_bf16 v[38:41], v[196:199], v[232:235], v[38:41]
	v_mfma_f32_16x16x32_bf16 v[2:5], v[196:199], v[236:239], v[2:5]
	v_mfma_f32_16x16x32_bf16 v[6:9], v[196:199], v[240:243], v[6:9]
	s_waitcnt vmcnt(11)
	ds_write_b128 v95, v[114:117] offset:55296
	s_waitcnt vmcnt(10)
	ds_write_b128 v95, v[118:121] offset:59904
	s_waitcnt lgkmcnt(8)
	v_mfma_f32_16x16x32_bf16 v[42:45], v[200:203], v[228:231], v[42:45]
	v_mfma_f32_16x16x32_bf16 v[46:49], v[200:203], v[232:235], v[46:49]
	v_mfma_f32_16x16x32_bf16 v[10:13], v[200:203], v[236:239], v[10:13]
	v_mfma_f32_16x16x32_bf16 v[14:17], v[200:203], v[240:243], v[14:17]
	s_waitcnt vmcnt(9)
	ds_write_b128 v95, v[122:125] offset:64512
	s_waitcnt vmcnt(8)
	ds_write_b128 v96, v[126:129] offset:32256
	s_waitcnt lgkmcnt(0)
	s_barrier
	s_setprio 0
	ds_read_b128 v[212:215], v245 offset:55296
	ds_read_b128 v[196:199], v244 offset:18432
	ds_read_b128 v[216:219], v245 offset:57600
	ds_read_b128 v[220:223], v245 offset:59904
	ds_read_b128 v[224:227], v245 offset:62208
	ds_read_b128 v[200:203], v244 offset:20736
	v_mfma_f32_16x16x32_bf16 v[50:53], v[204:207], v[228:231], v[50:53]
	v_mfma_f32_16x16x32_bf16 v[54:57], v[204:207], v[232:235], v[54:57]
	v_mfma_f32_16x16x32_bf16 v[18:21], v[204:207], v[236:239], v[18:21]
	v_mfma_f32_16x16x32_bf16 v[22:25], v[204:207], v[240:243], v[22:25]
	ds_read_b128 v[204:207], v244 offset:23040
	v_mfma_f32_16x16x32_bf16 v[58:61], v[208:211], v[228:231], v[58:61]
	v_mfma_f32_16x16x32_bf16 v[62:65], v[208:211], v[232:235], v[62:65]
	v_mfma_f32_16x16x32_bf16 v[26:29], v[208:211], v[236:239], v[26:29]
	v_mfma_f32_16x16x32_bf16 v[30:33], v[208:211], v[240:243], v[30:33]
	ds_read_b128 v[208:211], v244 offset:25344
	global_load_dwordx4 v[98:101], v[72:73], off offset:1408
	global_load_dwordx4 v[102:105], v[74:75], off offset:1408
	global_load_dwordx4 v[106:109], v[76:77], off offset:1408
	global_load_dwordx4 v[110:113], v[78:79], off offset:1408
	global_load_dwordx4 v[114:117], v[80:81], off offset:1408
	global_load_dwordx4 v[118:121], v[82:83], off offset:1408
	global_load_dwordx4 v[122:125], v[84:85], off offset:1408
	global_load_dwordx4 v[126:129], v[86:87], off offset:1408
	s_waitcnt lgkmcnt(6)
	v_mfma_f32_16x16x32_bf16 v[34:37], v[196:199], v[212:215], v[34:37]
	ds_read_b128 v[228:231], v245 offset:55360
	s_waitcnt lgkmcnt(6)
	v_mfma_f32_16x16x32_bf16 v[38:41], v[196:199], v[216:219], v[38:41]
	ds_read_b128 v[232:235], v245 offset:57664
	s_waitcnt lgkmcnt(6)
	v_mfma_f32_16x16x32_bf16 v[2:5], v[196:199], v[220:223], v[2:5]
	ds_read_b128 v[236:239], v245 offset:59968
	s_waitcnt lgkmcnt(6)
	v_mfma_f32_16x16x32_bf16 v[6:9], v[196:199], v[224:227], v[6:9]
	ds_read_b128 v[240:243], v245 offset:62272
	ds_read_b128 v[196:199], v244 offset:18496
	s_waitcnt lgkmcnt(7)
	v_mfma_f32_16x16x32_bf16 v[42:45], v[200:203], v[212:215], v[42:45]
	v_mfma_f32_16x16x32_bf16 v[46:49], v[200:203], v[216:219], v[46:49]
	v_mfma_f32_16x16x32_bf16 v[10:13], v[200:203], v[220:223], v[10:13]
	v_mfma_f32_16x16x32_bf16 v[14:17], v[200:203], v[224:227], v[14:17]
	ds_read_b128 v[200:203], v244 offset:20800
	s_waitcnt lgkmcnt(7)
	v_mfma_f32_16x16x32_bf16 v[50:53], v[204:207], v[212:215], v[50:53]
	v_mfma_f32_16x16x32_bf16 v[54:57], v[204:207], v[216:219], v[54:57]
	v_mfma_f32_16x16x32_bf16 v[18:21], v[204:207], v[220:223], v[18:21]
	v_mfma_f32_16x16x32_bf16 v[22:25], v[204:207], v[224:227], v[22:25]
	ds_read_b128 v[204:207], v244 offset:23104
	s_setprio 1
	s_waitcnt vmcnt(15)
	ds_write_b128 v95, v[136:139]
	s_waitcnt vmcnt(14)
	ds_write_b128 v95, v[140:143] offset:4608
	s_waitcnt lgkmcnt(9)
	v_mfma_f32_16x16x32_bf16 v[58:61], v[208:211], v[212:215], v[58:61]
	v_mfma_f32_16x16x32_bf16 v[62:65], v[208:211], v[216:219], v[62:65]
	v_mfma_f32_16x16x32_bf16 v[26:29], v[208:211], v[220:223], v[26:29]
	v_mfma_f32_16x16x32_bf16 v[30:33], v[208:211], v[224:227], v[30:33]
	ds_read_b128 v[208:211], v244 offset:25408
	s_waitcnt vmcnt(13)
	ds_write_b128 v95, v[144:147] offset:9216
	s_waitcnt vmcnt(12)
	ds_write_b128 v95, v[148:151] offset:13824
	s_waitcnt lgkmcnt(7)
	v_mfma_f32_16x16x32_bf16 v[34:37], v[196:199], v[228:231], v[34:37]
	v_mfma_f32_16x16x32_bf16 v[38:41], v[196:199], v[232:235], v[38:41]
	v_mfma_f32_16x16x32_bf16 v[2:5], v[196:199], v[236:239], v[2:5]
	v_mfma_f32_16x16x32_bf16 v[6:9], v[196:199], v[240:243], v[6:9]
	s_waitcnt vmcnt(11)
	ds_write_b128 v95, v[152:155] offset:36864
	s_waitcnt vmcnt(10)
	ds_write_b128 v95, v[156:159] offset:41472
	s_waitcnt lgkmcnt(8)
	v_mfma_f32_16x16x32_bf16 v[42:45], v[200:203], v[228:231], v[42:45]
	v_mfma_f32_16x16x32_bf16 v[46:49], v[200:203], v[232:235], v[46:49]
	v_mfma_f32_16x16x32_bf16 v[10:13], v[200:203], v[236:239], v[10:13]
	v_mfma_f32_16x16x32_bf16 v[14:17], v[200:203], v[240:243], v[14:17]
	s_waitcnt vmcnt(9)
	ds_write_b128 v95, v[160:163] offset:46080
	s_waitcnt vmcnt(8)
	ds_write_b128 v95, v[164:167] offset:50688
	s_waitcnt lgkmcnt(0)
	s_barrier
	s_setprio 0
	ds_read_b128 v[212:215], v245 offset:36864
	ds_read_b128 v[196:199], v244
	ds_read_b128 v[216:219], v245 offset:39168
	ds_read_b128 v[220:223], v245 offset:41472
	ds_read_b128 v[224:227], v245 offset:43776
	ds_read_b128 v[200:203], v244 offset:2304
	v_mfma_f32_16x16x32_bf16 v[50:53], v[204:207], v[228:231], v[50:53]
	v_mfma_f32_16x16x32_bf16 v[54:57], v[204:207], v[232:235], v[54:57]
	v_mfma_f32_16x16x32_bf16 v[18:21], v[204:207], v[236:239], v[18:21]
	v_mfma_f32_16x16x32_bf16 v[22:25], v[204:207], v[240:243], v[22:25]
	ds_read_b128 v[204:207], v244 offset:4608
	v_mfma_f32_16x16x32_bf16 v[58:61], v[208:211], v[228:231], v[58:61]
	v_mfma_f32_16x16x32_bf16 v[62:65], v[208:211], v[232:235], v[62:65]
	v_mfma_f32_16x16x32_bf16 v[26:29], v[208:211], v[236:239], v[26:29]
	v_mfma_f32_16x16x32_bf16 v[30:33], v[208:211], v[240:243], v[30:33]
	ds_read_b128 v[208:211], v244 offset:6912
	global_load_dwordx4 v[136:139], v[72:73], off offset:1536
	global_load_dwordx4 v[140:143], v[74:75], off offset:1536
	global_load_dwordx4 v[144:147], v[76:77], off offset:1536
	global_load_dwordx4 v[148:151], v[78:79], off offset:1536
	global_load_dwordx4 v[152:155], v[80:81], off offset:1536
	global_load_dwordx4 v[156:159], v[82:83], off offset:1536
	global_load_dwordx4 v[160:163], v[84:85], off offset:1536
	global_load_dwordx4 v[164:167], v[86:87], off offset:1536
	s_waitcnt lgkmcnt(6)
	v_mfma_f32_16x16x32_bf16 v[34:37], v[196:199], v[212:215], v[34:37]
	ds_read_b128 v[228:231], v245 offset:36928
	s_waitcnt lgkmcnt(6)
	v_mfma_f32_16x16x32_bf16 v[38:41], v[196:199], v[216:219], v[38:41]
	ds_read_b128 v[232:235], v245 offset:39232
	s_waitcnt lgkmcnt(6)
	v_mfma_f32_16x16x32_bf16 v[2:5], v[196:199], v[220:223], v[2:5]
	ds_read_b128 v[236:239], v245 offset:41536
	s_waitcnt lgkmcnt(6)
	v_mfma_f32_16x16x32_bf16 v[6:9], v[196:199], v[224:227], v[6:9]
	ds_read_b128 v[240:243], v245 offset:43840
	ds_read_b128 v[196:199], v244 offset:64
	s_waitcnt lgkmcnt(7)
	v_mfma_f32_16x16x32_bf16 v[42:45], v[200:203], v[212:215], v[42:45]
	v_mfma_f32_16x16x32_bf16 v[46:49], v[200:203], v[216:219], v[46:49]
	v_mfma_f32_16x16x32_bf16 v[10:13], v[200:203], v[220:223], v[10:13]
	v_mfma_f32_16x16x32_bf16 v[14:17], v[200:203], v[224:227], v[14:17]
	ds_read_b128 v[200:203], v244 offset:2368
	s_waitcnt lgkmcnt(7)
	v_mfma_f32_16x16x32_bf16 v[50:53], v[204:207], v[212:215], v[50:53]
	v_mfma_f32_16x16x32_bf16 v[54:57], v[204:207], v[216:219], v[54:57]
	v_mfma_f32_16x16x32_bf16 v[18:21], v[204:207], v[220:223], v[18:21]
	v_mfma_f32_16x16x32_bf16 v[22:25], v[204:207], v[224:227], v[22:25]
	ds_read_b128 v[204:207], v244 offset:4672
	s_setprio 1
	s_waitcnt vmcnt(15)
	ds_write_b128 v95, v[98:101] offset:18432
	s_waitcnt vmcnt(14)
	ds_write_b128 v95, v[102:105] offset:23040
	s_waitcnt lgkmcnt(9)
	v_mfma_f32_16x16x32_bf16 v[58:61], v[208:211], v[212:215], v[58:61]
	v_mfma_f32_16x16x32_bf16 v[62:65], v[208:211], v[216:219], v[62:65]
	v_mfma_f32_16x16x32_bf16 v[26:29], v[208:211], v[220:223], v[26:29]
	v_mfma_f32_16x16x32_bf16 v[30:33], v[208:211], v[224:227], v[30:33]
	ds_read_b128 v[208:211], v244 offset:6976
	s_waitcnt vmcnt(13)
	ds_write_b128 v95, v[106:109] offset:27648
	s_waitcnt vmcnt(12)
	ds_write_b128 v95, v[110:113] offset:32256
	s_waitcnt lgkmcnt(7)
	v_mfma_f32_16x16x32_bf16 v[34:37], v[196:199], v[228:231], v[34:37]
	v_mfma_f32_16x16x32_bf16 v[38:41], v[196:199], v[232:235], v[38:41]
	v_mfma_f32_16x16x32_bf16 v[2:5], v[196:199], v[236:239], v[2:5]
	v_mfma_f32_16x16x32_bf16 v[6:9], v[196:199], v[240:243], v[6:9]
	s_waitcnt vmcnt(11)
	ds_write_b128 v95, v[114:117] offset:55296
	s_waitcnt vmcnt(10)
	ds_write_b128 v95, v[118:121] offset:59904
	s_waitcnt lgkmcnt(8)
	v_mfma_f32_16x16x32_bf16 v[42:45], v[200:203], v[228:231], v[42:45]
	v_mfma_f32_16x16x32_bf16 v[46:49], v[200:203], v[232:235], v[46:49]
	v_mfma_f32_16x16x32_bf16 v[10:13], v[200:203], v[236:239], v[10:13]
	v_mfma_f32_16x16x32_bf16 v[14:17], v[200:203], v[240:243], v[14:17]
	s_waitcnt vmcnt(9)
	ds_write_b128 v95, v[122:125] offset:64512
	s_waitcnt vmcnt(8)
	ds_write_b128 v96, v[126:129] offset:32256
	s_waitcnt lgkmcnt(0)
	s_barrier
	s_setprio 0
	ds_read_b128 v[212:215], v245 offset:55296
	ds_read_b128 v[196:199], v244 offset:18432
	ds_read_b128 v[216:219], v245 offset:57600
	ds_read_b128 v[220:223], v245 offset:59904
	ds_read_b128 v[224:227], v245 offset:62208
	ds_read_b128 v[200:203], v244 offset:20736
	v_mfma_f32_16x16x32_bf16 v[50:53], v[204:207], v[228:231], v[50:53]
	v_mfma_f32_16x16x32_bf16 v[54:57], v[204:207], v[232:235], v[54:57]
	v_mfma_f32_16x16x32_bf16 v[18:21], v[204:207], v[236:239], v[18:21]
	v_mfma_f32_16x16x32_bf16 v[22:25], v[204:207], v[240:243], v[22:25]
	ds_read_b128 v[204:207], v244 offset:23040
	v_mfma_f32_16x16x32_bf16 v[58:61], v[208:211], v[228:231], v[58:61]
	v_mfma_f32_16x16x32_bf16 v[62:65], v[208:211], v[232:235], v[62:65]
	v_mfma_f32_16x16x32_bf16 v[26:29], v[208:211], v[236:239], v[26:29]
	v_mfma_f32_16x16x32_bf16 v[30:33], v[208:211], v[240:243], v[30:33]
	ds_read_b128 v[208:211], v244 offset:25344
	global_load_dwordx4 v[98:101], v[72:73], off offset:1664
	global_load_dwordx4 v[102:105], v[74:75], off offset:1664
	global_load_dwordx4 v[106:109], v[76:77], off offset:1664
	global_load_dwordx4 v[110:113], v[78:79], off offset:1664
	global_load_dwordx4 v[114:117], v[80:81], off offset:1664
	global_load_dwordx4 v[118:121], v[82:83], off offset:1664
	global_load_dwordx4 v[122:125], v[84:85], off offset:1664
	global_load_dwordx4 v[126:129], v[86:87], off offset:1664
	s_waitcnt lgkmcnt(6)
	v_mfma_f32_16x16x32_bf16 v[34:37], v[196:199], v[212:215], v[34:37]
	ds_read_b128 v[228:231], v245 offset:55360
	s_waitcnt lgkmcnt(6)
	v_mfma_f32_16x16x32_bf16 v[38:41], v[196:199], v[216:219], v[38:41]
	ds_read_b128 v[232:235], v245 offset:57664
	s_waitcnt lgkmcnt(6)
	v_mfma_f32_16x16x32_bf16 v[2:5], v[196:199], v[220:223], v[2:5]
	ds_read_b128 v[236:239], v245 offset:59968
	s_waitcnt lgkmcnt(6)
	v_mfma_f32_16x16x32_bf16 v[6:9], v[196:199], v[224:227], v[6:9]
	ds_read_b128 v[240:243], v245 offset:62272
	ds_read_b128 v[196:199], v244 offset:18496
	s_waitcnt lgkmcnt(7)
	v_mfma_f32_16x16x32_bf16 v[42:45], v[200:203], v[212:215], v[42:45]
	v_mfma_f32_16x16x32_bf16 v[46:49], v[200:203], v[216:219], v[46:49]
	v_mfma_f32_16x16x32_bf16 v[10:13], v[200:203], v[220:223], v[10:13]
	v_mfma_f32_16x16x32_bf16 v[14:17], v[200:203], v[224:227], v[14:17]
	ds_read_b128 v[200:203], v244 offset:20800
	s_waitcnt lgkmcnt(7)
	v_mfma_f32_16x16x32_bf16 v[50:53], v[204:207], v[212:215], v[50:53]
	v_mfma_f32_16x16x32_bf16 v[54:57], v[204:207], v[216:219], v[54:57]
	v_mfma_f32_16x16x32_bf16 v[18:21], v[204:207], v[220:223], v[18:21]
	v_mfma_f32_16x16x32_bf16 v[22:25], v[204:207], v[224:227], v[22:25]
	ds_read_b128 v[204:207], v244 offset:23104
	s_setprio 1
	s_waitcnt vmcnt(15)
	ds_write_b128 v95, v[136:139]
	s_waitcnt vmcnt(14)
	ds_write_b128 v95, v[140:143] offset:4608
	s_waitcnt lgkmcnt(9)
	v_mfma_f32_16x16x32_bf16 v[58:61], v[208:211], v[212:215], v[58:61]
	v_mfma_f32_16x16x32_bf16 v[62:65], v[208:211], v[216:219], v[62:65]
	v_mfma_f32_16x16x32_bf16 v[26:29], v[208:211], v[220:223], v[26:29]
	v_mfma_f32_16x16x32_bf16 v[30:33], v[208:211], v[224:227], v[30:33]
	ds_read_b128 v[208:211], v244 offset:25408
	s_waitcnt vmcnt(13)
	ds_write_b128 v95, v[144:147] offset:9216
	s_waitcnt vmcnt(12)
	ds_write_b128 v95, v[148:151] offset:13824
	s_waitcnt lgkmcnt(7)
	v_mfma_f32_16x16x32_bf16 v[34:37], v[196:199], v[228:231], v[34:37]
	v_mfma_f32_16x16x32_bf16 v[38:41], v[196:199], v[232:235], v[38:41]
	v_mfma_f32_16x16x32_bf16 v[2:5], v[196:199], v[236:239], v[2:5]
	v_mfma_f32_16x16x32_bf16 v[6:9], v[196:199], v[240:243], v[6:9]
	s_waitcnt vmcnt(11)
	ds_write_b128 v95, v[152:155] offset:36864
	s_waitcnt vmcnt(10)
	ds_write_b128 v95, v[156:159] offset:41472
	s_waitcnt lgkmcnt(8)
	v_mfma_f32_16x16x32_bf16 v[42:45], v[200:203], v[228:231], v[42:45]
	v_mfma_f32_16x16x32_bf16 v[46:49], v[200:203], v[232:235], v[46:49]
	v_mfma_f32_16x16x32_bf16 v[10:13], v[200:203], v[236:239], v[10:13]
	v_mfma_f32_16x16x32_bf16 v[14:17], v[200:203], v[240:243], v[14:17]
	s_waitcnt vmcnt(9)
	ds_write_b128 v95, v[160:163] offset:46080
	s_waitcnt vmcnt(8)
	ds_write_b128 v95, v[164:167] offset:50688
	s_waitcnt lgkmcnt(0)
	s_barrier
	s_setprio 0
	ds_read_b128 v[212:215], v245 offset:36864
	ds_read_b128 v[196:199], v244
	ds_read_b128 v[216:219], v245 offset:39168
	ds_read_b128 v[220:223], v245 offset:41472
	ds_read_b128 v[224:227], v245 offset:43776
	ds_read_b128 v[200:203], v244 offset:2304
	v_mfma_f32_16x16x32_bf16 v[50:53], v[204:207], v[228:231], v[50:53]
	v_mfma_f32_16x16x32_bf16 v[54:57], v[204:207], v[232:235], v[54:57]
	v_mfma_f32_16x16x32_bf16 v[18:21], v[204:207], v[236:239], v[18:21]
	v_mfma_f32_16x16x32_bf16 v[22:25], v[204:207], v[240:243], v[22:25]
	ds_read_b128 v[204:207], v244 offset:4608
	v_mfma_f32_16x16x32_bf16 v[58:61], v[208:211], v[228:231], v[58:61]
	v_mfma_f32_16x16x32_bf16 v[62:65], v[208:211], v[232:235], v[62:65]
	v_mfma_f32_16x16x32_bf16 v[26:29], v[208:211], v[236:239], v[26:29]
	v_mfma_f32_16x16x32_bf16 v[30:33], v[208:211], v[240:243], v[30:33]
	ds_read_b128 v[208:211], v244 offset:6912
	global_load_dwordx4 v[136:139], v[72:73], off offset:1792
	global_load_dwordx4 v[140:143], v[74:75], off offset:1792
	global_load_dwordx4 v[144:147], v[76:77], off offset:1792
	global_load_dwordx4 v[148:151], v[78:79], off offset:1792
	global_load_dwordx4 v[152:155], v[80:81], off offset:1792
	global_load_dwordx4 v[156:159], v[82:83], off offset:1792
	global_load_dwordx4 v[160:163], v[84:85], off offset:1792
	global_load_dwordx4 v[164:167], v[86:87], off offset:1792
	s_waitcnt lgkmcnt(6)
	v_mfma_f32_16x16x32_bf16 v[34:37], v[196:199], v[212:215], v[34:37]
	ds_read_b128 v[228:231], v245 offset:36928
	s_waitcnt lgkmcnt(6)
	v_mfma_f32_16x16x32_bf16 v[38:41], v[196:199], v[216:219], v[38:41]
	ds_read_b128 v[232:235], v245 offset:39232
	s_waitcnt lgkmcnt(6)
	v_mfma_f32_16x16x32_bf16 v[2:5], v[196:199], v[220:223], v[2:5]
	ds_read_b128 v[236:239], v245 offset:41536
	s_waitcnt lgkmcnt(6)
	v_mfma_f32_16x16x32_bf16 v[6:9], v[196:199], v[224:227], v[6:9]
	ds_read_b128 v[240:243], v245 offset:43840
	ds_read_b128 v[196:199], v244 offset:64
	s_waitcnt lgkmcnt(7)
	v_mfma_f32_16x16x32_bf16 v[42:45], v[200:203], v[212:215], v[42:45]
	v_mfma_f32_16x16x32_bf16 v[46:49], v[200:203], v[216:219], v[46:49]
	v_mfma_f32_16x16x32_bf16 v[10:13], v[200:203], v[220:223], v[10:13]
	v_mfma_f32_16x16x32_bf16 v[14:17], v[200:203], v[224:227], v[14:17]
	ds_read_b128 v[200:203], v244 offset:2368
	s_waitcnt lgkmcnt(7)
	v_mfma_f32_16x16x32_bf16 v[50:53], v[204:207], v[212:215], v[50:53]
	v_mfma_f32_16x16x32_bf16 v[54:57], v[204:207], v[216:219], v[54:57]
	v_mfma_f32_16x16x32_bf16 v[18:21], v[204:207], v[220:223], v[18:21]
	v_mfma_f32_16x16x32_bf16 v[22:25], v[204:207], v[224:227], v[22:25]
	ds_read_b128 v[204:207], v244 offset:4672
	s_setprio 1
	s_waitcnt vmcnt(15)
	ds_write_b128 v95, v[98:101] offset:18432
	s_waitcnt vmcnt(14)
	ds_write_b128 v95, v[102:105] offset:23040
	s_waitcnt lgkmcnt(9)
	v_mfma_f32_16x16x32_bf16 v[58:61], v[208:211], v[212:215], v[58:61]
	v_mfma_f32_16x16x32_bf16 v[62:65], v[208:211], v[216:219], v[62:65]
	v_mfma_f32_16x16x32_bf16 v[26:29], v[208:211], v[220:223], v[26:29]
	v_mfma_f32_16x16x32_bf16 v[30:33], v[208:211], v[224:227], v[30:33]
	ds_read_b128 v[208:211], v244 offset:6976
	s_waitcnt vmcnt(13)
	ds_write_b128 v95, v[106:109] offset:27648
	s_waitcnt vmcnt(12)
	ds_write_b128 v95, v[110:113] offset:32256
	s_waitcnt lgkmcnt(7)
	v_mfma_f32_16x16x32_bf16 v[34:37], v[196:199], v[228:231], v[34:37]
	v_mfma_f32_16x16x32_bf16 v[38:41], v[196:199], v[232:235], v[38:41]
	v_mfma_f32_16x16x32_bf16 v[2:5], v[196:199], v[236:239], v[2:5]
	v_mfma_f32_16x16x32_bf16 v[6:9], v[196:199], v[240:243], v[6:9]
	s_waitcnt vmcnt(11)
	ds_write_b128 v95, v[114:117] offset:55296
	s_waitcnt vmcnt(10)
	ds_write_b128 v95, v[118:121] offset:59904
	s_waitcnt lgkmcnt(8)
	v_mfma_f32_16x16x32_bf16 v[42:45], v[200:203], v[228:231], v[42:45]
	v_mfma_f32_16x16x32_bf16 v[46:49], v[200:203], v[232:235], v[46:49]
	v_mfma_f32_16x16x32_bf16 v[10:13], v[200:203], v[236:239], v[10:13]
	v_mfma_f32_16x16x32_bf16 v[14:17], v[200:203], v[240:243], v[14:17]
	s_waitcnt vmcnt(9)
	ds_write_b128 v95, v[122:125] offset:64512
	s_waitcnt vmcnt(8)
	ds_write_b128 v96, v[126:129] offset:32256
	s_waitcnt lgkmcnt(0)
	s_barrier
	s_setprio 0
	ds_read_b128 v[212:215], v245 offset:55296
	ds_read_b128 v[196:199], v244 offset:18432
	ds_read_b128 v[216:219], v245 offset:57600
	ds_read_b128 v[220:223], v245 offset:59904
	ds_read_b128 v[224:227], v245 offset:62208
	ds_read_b128 v[200:203], v244 offset:20736
	v_mfma_f32_16x16x32_bf16 v[50:53], v[204:207], v[228:231], v[50:53]
	v_mfma_f32_16x16x32_bf16 v[54:57], v[204:207], v[232:235], v[54:57]
	v_mfma_f32_16x16x32_bf16 v[18:21], v[204:207], v[236:239], v[18:21]
	v_mfma_f32_16x16x32_bf16 v[22:25], v[204:207], v[240:243], v[22:25]
	ds_read_b128 v[204:207], v244 offset:23040
	v_mfma_f32_16x16x32_bf16 v[58:61], v[208:211], v[228:231], v[58:61]
	v_mfma_f32_16x16x32_bf16 v[62:65], v[208:211], v[232:235], v[62:65]
	v_mfma_f32_16x16x32_bf16 v[26:29], v[208:211], v[236:239], v[26:29]
	v_mfma_f32_16x16x32_bf16 v[30:33], v[208:211], v[240:243], v[30:33]
	ds_read_b128 v[208:211], v244 offset:25344
	global_load_dwordx4 v[98:101], v[72:73], off offset:1920
	s_nop 0
	global_load_dwordx4 v[72:75], v[74:75], off offset:1920
	s_nop 0
	global_load_dwordx4 v[102:105], v[76:77], off offset:1920
	s_nop 0
	global_load_dwordx4 v[76:79], v[78:79], off offset:1920
	s_nop 0
	global_load_dwordx4 v[106:109], v[80:81], off offset:1920
	s_nop 0
	global_load_dwordx4 v[80:83], v[82:83], off offset:1920
	s_nop 0
	global_load_dwordx4 v[110:113], v[84:85], off offset:1920
	s_nop 0
	global_load_dwordx4 v[84:87], v[86:87], off offset:1920
	s_waitcnt lgkmcnt(6)
	v_mfma_f32_16x16x32_bf16 v[34:37], v[196:199], v[212:215], v[34:37]
	ds_read_b128 v[228:231], v245 offset:55360
	s_waitcnt lgkmcnt(6)
	v_mfma_f32_16x16x32_bf16 v[38:41], v[196:199], v[216:219], v[38:41]
	ds_read_b128 v[232:235], v245 offset:57664
	s_waitcnt lgkmcnt(6)
	v_mfma_f32_16x16x32_bf16 v[2:5], v[196:199], v[220:223], v[2:5]
	ds_read_b128 v[236:239], v245 offset:59968
	s_waitcnt lgkmcnt(6)
	v_mfma_f32_16x16x32_bf16 v[6:9], v[196:199], v[224:227], v[6:9]
	ds_read_b128 v[240:243], v245 offset:62272
	ds_read_b128 v[196:199], v244 offset:18496
	s_waitcnt lgkmcnt(7)
	v_mfma_f32_16x16x32_bf16 v[42:45], v[200:203], v[212:215], v[42:45]
	v_mfma_f32_16x16x32_bf16 v[46:49], v[200:203], v[216:219], v[46:49]
	v_mfma_f32_16x16x32_bf16 v[10:13], v[200:203], v[220:223], v[10:13]
	v_mfma_f32_16x16x32_bf16 v[14:17], v[200:203], v[224:227], v[14:17]
	ds_read_b128 v[200:203], v244 offset:20800
	s_waitcnt lgkmcnt(7)
	v_mfma_f32_16x16x32_bf16 v[50:53], v[204:207], v[212:215], v[50:53]
	v_mfma_f32_16x16x32_bf16 v[54:57], v[204:207], v[216:219], v[54:57]
	v_mfma_f32_16x16x32_bf16 v[18:21], v[204:207], v[220:223], v[18:21]
	v_mfma_f32_16x16x32_bf16 v[22:25], v[204:207], v[224:227], v[22:25]
	ds_read_b128 v[204:207], v244 offset:23104
	s_setprio 1
	s_waitcnt vmcnt(15)
	ds_write_b128 v95, v[136:139]
	s_waitcnt vmcnt(14)
	ds_write_b128 v95, v[140:143] offset:4608
	s_waitcnt lgkmcnt(9)
	v_mfma_f32_16x16x32_bf16 v[58:61], v[208:211], v[212:215], v[58:61]
	v_mfma_f32_16x16x32_bf16 v[62:65], v[208:211], v[216:219], v[62:65]
	v_mfma_f32_16x16x32_bf16 v[26:29], v[208:211], v[220:223], v[26:29]
	v_mfma_f32_16x16x32_bf16 v[30:33], v[208:211], v[224:227], v[30:33]
	ds_read_b128 v[208:211], v244 offset:25408
	s_waitcnt vmcnt(13)
	ds_write_b128 v95, v[144:147] offset:9216
	s_waitcnt vmcnt(12)
	ds_write_b128 v95, v[148:151] offset:13824
	s_waitcnt lgkmcnt(7)
	v_mfma_f32_16x16x32_bf16 v[34:37], v[196:199], v[228:231], v[34:37]
	v_mfma_f32_16x16x32_bf16 v[38:41], v[196:199], v[232:235], v[38:41]
	v_mfma_f32_16x16x32_bf16 v[2:5], v[196:199], v[236:239], v[2:5]
	v_mfma_f32_16x16x32_bf16 v[6:9], v[196:199], v[240:243], v[6:9]
	s_waitcnt vmcnt(11)
	ds_write_b128 v95, v[152:155] offset:36864
	s_waitcnt vmcnt(10)
	ds_write_b128 v95, v[156:159] offset:41472
	s_waitcnt lgkmcnt(8)
	v_mfma_f32_16x16x32_bf16 v[42:45], v[200:203], v[228:231], v[42:45]
	v_mfma_f32_16x16x32_bf16 v[46:49], v[200:203], v[232:235], v[46:49]
	v_mfma_f32_16x16x32_bf16 v[10:13], v[200:203], v[236:239], v[10:13]
	v_mfma_f32_16x16x32_bf16 v[14:17], v[200:203], v[240:243], v[14:17]
	s_waitcnt vmcnt(9)
	ds_write_b128 v95, v[160:163] offset:46080
	s_waitcnt vmcnt(8)
	ds_write_b128 v95, v[164:167] offset:50688
	s_waitcnt lgkmcnt(0)
	s_barrier
	s_setprio 0
	ds_read_b128 v[212:215], v245 offset:36864
	ds_read_b128 v[196:199], v244
	ds_read_b128 v[216:219], v245 offset:39168
	ds_read_b128 v[220:223], v245 offset:41472
	ds_read_b128 v[224:227], v245 offset:43776
	ds_read_b128 v[200:203], v244 offset:2304
	v_mfma_f32_16x16x32_bf16 v[50:53], v[204:207], v[228:231], v[50:53]
	v_mfma_f32_16x16x32_bf16 v[54:57], v[204:207], v[232:235], v[54:57]
	v_mfma_f32_16x16x32_bf16 v[18:21], v[204:207], v[236:239], v[18:21]
	v_mfma_f32_16x16x32_bf16 v[22:25], v[204:207], v[240:243], v[22:25]
	ds_read_b128 v[204:207], v244 offset:4608
	v_mfma_f32_16x16x32_bf16 v[58:61], v[208:211], v[228:231], v[58:61]
	v_mfma_f32_16x16x32_bf16 v[62:65], v[208:211], v[232:235], v[62:65]
	v_mfma_f32_16x16x32_bf16 v[26:29], v[208:211], v[236:239], v[26:29]
	v_mfma_f32_16x16x32_bf16 v[30:33], v[208:211], v[240:243], v[30:33]
	ds_read_b128 v[208:211], v244 offset:6912
	s_waitcnt lgkmcnt(6)
	v_mfma_f32_16x16x32_bf16 v[34:37], v[196:199], v[212:215], v[34:37]
	ds_read_b128 v[228:231], v245 offset:36928
	s_waitcnt lgkmcnt(6)
	v_mfma_f32_16x16x32_bf16 v[38:41], v[196:199], v[216:219], v[38:41]
	ds_read_b128 v[232:235], v245 offset:39232
	s_waitcnt lgkmcnt(6)
	v_mfma_f32_16x16x32_bf16 v[2:5], v[196:199], v[220:223], v[2:5]
	ds_read_b128 v[236:239], v245 offset:41536
	s_waitcnt lgkmcnt(6)
	v_mfma_f32_16x16x32_bf16 v[6:9], v[196:199], v[224:227], v[6:9]
	ds_read_b128 v[240:243], v245 offset:43840
	ds_read_b128 v[196:199], v244 offset:64
	s_waitcnt lgkmcnt(7)
	v_mfma_f32_16x16x32_bf16 v[42:45], v[200:203], v[212:215], v[42:45]
	v_mfma_f32_16x16x32_bf16 v[46:49], v[200:203], v[216:219], v[46:49]
	v_mfma_f32_16x16x32_bf16 v[10:13], v[200:203], v[220:223], v[10:13]
	v_mfma_f32_16x16x32_bf16 v[14:17], v[200:203], v[224:227], v[14:17]
	ds_read_b128 v[200:203], v244 offset:2368
	s_waitcnt lgkmcnt(7)
	v_mfma_f32_16x16x32_bf16 v[50:53], v[204:207], v[212:215], v[50:53]
	v_mfma_f32_16x16x32_bf16 v[54:57], v[204:207], v[216:219], v[54:57]
	v_mfma_f32_16x16x32_bf16 v[18:21], v[204:207], v[220:223], v[18:21]
	v_mfma_f32_16x16x32_bf16 v[22:25], v[204:207], v[224:227], v[22:25]
	ds_read_b128 v[204:207], v244 offset:4672
	s_setprio 1
	s_waitcnt vmcnt(7)
	ds_write_b128 v95, v[98:101] offset:18432
	s_waitcnt vmcnt(6)
	ds_write_b128 v95, v[72:75] offset:23040
	s_waitcnt lgkmcnt(9)
	v_mfma_f32_16x16x32_bf16 v[58:61], v[208:211], v[212:215], v[58:61]
	v_mfma_f32_16x16x32_bf16 v[62:65], v[208:211], v[216:219], v[62:65]
	v_mfma_f32_16x16x32_bf16 v[26:29], v[208:211], v[220:223], v[26:29]
	v_mfma_f32_16x16x32_bf16 v[30:33], v[208:211], v[224:227], v[30:33]
	ds_read_b128 v[208:211], v244 offset:6976
	s_waitcnt vmcnt(5)
	ds_write_b128 v95, v[102:105] offset:27648
	s_waitcnt vmcnt(4)
	ds_write_b128 v95, v[76:79] offset:32256
	s_waitcnt lgkmcnt(7)
	v_mfma_f32_16x16x32_bf16 v[34:37], v[196:199], v[228:231], v[34:37]
	v_mfma_f32_16x16x32_bf16 v[38:41], v[196:199], v[232:235], v[38:41]
	v_mfma_f32_16x16x32_bf16 v[2:5], v[196:199], v[236:239], v[2:5]
	v_mfma_f32_16x16x32_bf16 v[6:9], v[196:199], v[240:243], v[6:9]
	s_waitcnt vmcnt(3)
	ds_write_b128 v95, v[106:109] offset:55296
	s_waitcnt vmcnt(2)
	ds_write_b128 v95, v[80:83] offset:59904
	s_waitcnt lgkmcnt(8)
	v_mfma_f32_16x16x32_bf16 v[42:45], v[200:203], v[228:231], v[42:45]
	v_mfma_f32_16x16x32_bf16 v[46:49], v[200:203], v[232:235], v[46:49]
	v_mfma_f32_16x16x32_bf16 v[10:13], v[200:203], v[236:239], v[10:13]
	v_mfma_f32_16x16x32_bf16 v[14:17], v[200:203], v[240:243], v[14:17]
	s_waitcnt vmcnt(1)
	ds_write_b128 v95, v[110:113] offset:64512
	s_waitcnt vmcnt(0)
	ds_write_b128 v96, v[84:87] offset:32256
	s_waitcnt lgkmcnt(0)
	s_barrier
	s_setprio 0
	ds_read_b128 v[212:215], v245 offset:55296
	ds_read_b128 v[196:199], v244 offset:18432
	ds_read_b128 v[216:219], v245 offset:57600
	ds_read_b128 v[220:223], v245 offset:59904
	ds_read_b128 v[224:227], v245 offset:62208
	ds_read_b128 v[200:203], v244 offset:20736
	v_mfma_f32_16x16x32_bf16 v[50:53], v[204:207], v[228:231], v[50:53]
	v_mfma_f32_16x16x32_bf16 v[54:57], v[204:207], v[232:235], v[54:57]
	v_mfma_f32_16x16x32_bf16 v[18:21], v[204:207], v[236:239], v[18:21]
	v_mfma_f32_16x16x32_bf16 v[22:25], v[204:207], v[240:243], v[22:25]
	ds_read_b128 v[204:207], v244 offset:23040
	v_mfma_f32_16x16x32_bf16 v[58:61], v[208:211], v[228:231], v[58:61]
	v_mfma_f32_16x16x32_bf16 v[62:65], v[208:211], v[232:235], v[62:65]
	v_mfma_f32_16x16x32_bf16 v[26:29], v[208:211], v[236:239], v[26:29]
	v_mfma_f32_16x16x32_bf16 v[30:33], v[208:211], v[240:243], v[30:33]
	ds_read_b128 v[208:211], v244 offset:25344
	s_waitcnt lgkmcnt(6)
	v_mfma_f32_16x16x32_bf16 v[34:37], v[196:199], v[212:215], v[34:37]
	ds_read_b128 v[228:231], v245 offset:55360
	s_waitcnt lgkmcnt(6)
	v_mfma_f32_16x16x32_bf16 v[38:41], v[196:199], v[216:219], v[38:41]
	ds_read_b128 v[232:235], v245 offset:57664
	s_waitcnt lgkmcnt(6)
	v_mfma_f32_16x16x32_bf16 v[2:5], v[196:199], v[220:223], v[2:5]
	ds_read_b128 v[236:239], v245 offset:59968
	s_waitcnt lgkmcnt(6)
	v_mfma_f32_16x16x32_bf16 v[6:9], v[196:199], v[224:227], v[6:9]
	ds_read_b128 v[240:243], v245 offset:62272
	ds_read_b128 v[196:199], v244 offset:18496
	s_waitcnt lgkmcnt(7)
	v_mfma_f32_16x16x32_bf16 v[42:45], v[200:203], v[212:215], v[42:45]
	v_mfma_f32_16x16x32_bf16 v[46:49], v[200:203], v[216:219], v[46:49]
	v_mfma_f32_16x16x32_bf16 v[10:13], v[200:203], v[220:223], v[10:13]
	v_mfma_f32_16x16x32_bf16 v[14:17], v[200:203], v[224:227], v[14:17]
	ds_read_b128 v[200:203], v244 offset:20800
	s_waitcnt lgkmcnt(7)
	v_mfma_f32_16x16x32_bf16 v[50:53], v[204:207], v[212:215], v[50:53]
	v_mfma_f32_16x16x32_bf16 v[54:57], v[204:207], v[216:219], v[54:57]
	v_mfma_f32_16x16x32_bf16 v[18:21], v[204:207], v[220:223], v[18:21]
	v_mfma_f32_16x16x32_bf16 v[22:25], v[204:207], v[224:227], v[22:25]
	ds_read_b128 v[204:207], v244 offset:23104
	s_waitcnt lgkmcnt(7)
	v_mfma_f32_16x16x32_bf16 v[58:61], v[208:211], v[212:215], v[58:61]
	v_mfma_f32_16x16x32_bf16 v[62:65], v[208:211], v[216:219], v[62:65]
	v_mfma_f32_16x16x32_bf16 v[26:29], v[208:211], v[220:223], v[26:29]
	v_mfma_f32_16x16x32_bf16 v[30:33], v[208:211], v[224:227], v[30:33]
	ds_read_b128 v[208:211], v244 offset:25408
	s_waitcnt lgkmcnt(3)
	v_mfma_f32_16x16x32_bf16 v[34:37], v[196:199], v[228:231], v[34:37]
	v_mfma_f32_16x16x32_bf16 v[38:41], v[196:199], v[232:235], v[38:41]
	v_mfma_f32_16x16x32_bf16 v[2:5], v[196:199], v[236:239], v[2:5]
	v_mfma_f32_16x16x32_bf16 v[6:9], v[196:199], v[240:243], v[6:9]
	s_waitcnt lgkmcnt(2)
	v_mfma_f32_16x16x32_bf16 v[42:45], v[200:203], v[228:231], v[42:45]
	v_mfma_f32_16x16x32_bf16 v[46:49], v[200:203], v[232:235], v[46:49]
	v_mfma_f32_16x16x32_bf16 v[10:13], v[200:203], v[236:239], v[10:13]
	v_mfma_f32_16x16x32_bf16 v[14:17], v[200:203], v[240:243], v[14:17]
	v_or_b32_e32 v66, s3, v88
	s_addk_i32 s3, 0xf000
	s_lshr_b32 s3, s3, 12
	s_cmp_lt_u32 s0, 32
	s_cselect_b64 vcc, -1, 0
	s_and_b64 s[4:5], vcc, exec
	s_mul_i32 s0, s3, 0xc00
	s_cselect_b32 s5, s17, s19
	s_cselect_b32 s4, s16, s18
	s_addk_i32 s0, 0xc00
	s_and_b64 s[12:13], vcc, exec
	s_cselect_b32 s0, 0, s0
	v_add_u32_e32 v72, 0xfffff000, v66
	v_cndmask_b32_e32 v72, v72, v66, vcc
	v_mov_b32_e32 v73, v67
	v_lshlrev_b64 v[72:73], 12, v[72:73]
	v_lshl_add_u64 v[78:79], s[4:5], 0, v[72:73]
	v_add_lshl_u32 v72, s2, v97, 2
	s_lshl_b64 s[2:3], s[0:1], 2
	s_add_u32 s0, s82, s2
	s_addc_u32 s3, s83, s3
	v_mov_b32_e32 v73, v67
	s_add_u32 s2, s0, 0xe958000
	v_lshl_add_u64 v[148:149], v[78:79], 0, v[72:73]
	s_addc_u32 s3, s3, 0
	v_or_b32_e32 v156, 0xe0, v72
	v_or_b32_e32 v157, 32, v72
	v_or_b32_e32 v158, 64, v72
	v_or_b32_e32 v159, 0x60, v72
	v_or_b32_e32 v160, 0x80, v72
	v_or_b32_e32 v161, 0xa0, v72
	v_or_b32_e32 v162, 0xc0, v72
	s_waitcnt lgkmcnt(0)
	s_barrier
	v_mfma_f32_16x16x32_bf16 v[50:53], v[204:207], v[228:231], v[50:53]
	v_mfma_f32_16x16x32_bf16 v[54:57], v[204:207], v[232:235], v[54:57]
	v_mfma_f32_16x16x32_bf16 v[18:21], v[204:207], v[236:239], v[18:21]
	v_mfma_f32_16x16x32_bf16 v[22:25], v[204:207], v[240:243], v[22:25]
	v_mfma_f32_16x16x32_bf16 v[58:61], v[208:211], v[228:231], v[58:61]
	v_mfma_f32_16x16x32_bf16 v[62:65], v[208:211], v[232:235], v[62:65]
	v_mfma_f32_16x16x32_bf16 v[26:29], v[208:211], v[236:239], v[26:29]
	v_mfma_f32_16x16x32_bf16 v[30:33], v[208:211], v[240:243], v[30:33]
	s_nop 7
	v_permlane16_swap_b32_e32 v34, v38
	v_permlane16_swap_b32_e32 v35, v39
	v_permlane16_swap_b32_e32 v36, v40
	v_permlane16_swap_b32_e32 v37, v41
	v_permlane16_swap_b32_e32 v42, v46
	v_permlane16_swap_b32_e32 v43, v47
	v_permlane16_swap_b32_e32 v44, v48
	v_permlane16_swap_b32_e32 v45, v49
	v_permlane16_swap_b32_e32 v2, v6
	v_permlane16_swap_b32_e32 v3, v7
	v_permlane16_swap_b32_e32 v4, v8
	v_permlane16_swap_b32_e32 v5, v9
	v_permlane16_swap_b32_e32 v10, v14
	v_permlane16_swap_b32_e32 v11, v15
	v_permlane16_swap_b32_e32 v12, v16
	v_permlane16_swap_b32_e32 v13, v17
	v_permlane16_swap_b32_e32 v50, v54
	v_permlane16_swap_b32_e32 v51, v55
	v_permlane16_swap_b32_e32 v52, v56
	v_permlane16_swap_b32_e32 v53, v57
	v_permlane16_swap_b32_e32 v58, v62
	v_permlane16_swap_b32_e32 v59, v63
	v_permlane16_swap_b32_e32 v60, v64
	v_permlane16_swap_b32_e32 v61, v65
	v_permlane16_swap_b32_e32 v18, v22
	v_permlane16_swap_b32_e32 v19, v23
	v_permlane16_swap_b32_e32 v20, v24
	v_permlane16_swap_b32_e32 v21, v25
	v_permlane16_swap_b32_e32 v26, v30
	v_permlane16_swap_b32_e32 v27, v31
	v_permlane16_swap_b32_e32 v28, v32
	v_permlane16_swap_b32_e32 v29, v33
	v_permlane32_swap_b32_e32 v34, v38
	v_permlane32_swap_b32_e32 v35, v39
	v_permlane32_swap_b32_e32 v36, v40
	v_permlane32_swap_b32_e32 v37, v41
	v_permlane32_swap_b32_e32 v42, v46
	v_permlane32_swap_b32_e32 v43, v47
	v_permlane32_swap_b32_e32 v44, v48
	v_permlane32_swap_b32_e32 v45, v49
	v_permlane32_swap_b32_e32 v2, v6
	v_permlane32_swap_b32_e32 v3, v7
	v_permlane32_swap_b32_e32 v4, v8
	v_permlane32_swap_b32_e32 v5, v9
	v_permlane32_swap_b32_e32 v10, v14
	v_permlane32_swap_b32_e32 v11, v15
	v_permlane32_swap_b32_e32 v12, v16
	v_permlane32_swap_b32_e32 v13, v17
	v_permlane32_swap_b32_e32 v50, v54
	v_permlane32_swap_b32_e32 v51, v55
	v_permlane32_swap_b32_e32 v52, v56
	v_permlane32_swap_b32_e32 v53, v57
	v_permlane32_swap_b32_e32 v58, v62
	v_permlane32_swap_b32_e32 v59, v63
	v_permlane32_swap_b32_e32 v60, v64
	v_permlane32_swap_b32_e32 v61, v65
	v_permlane32_swap_b32_e32 v18, v22
	v_permlane32_swap_b32_e32 v19, v23
	v_permlane32_swap_b32_e32 v20, v24
	v_permlane32_swap_b32_e32 v21, v25
	v_permlane32_swap_b32_e32 v26, v30
	v_permlane32_swap_b32_e32 v27, v31
	v_permlane32_swap_b32_e32 v28, v32
	v_permlane32_swap_b32_e32 v29, v33
	global_load_dwordx4 v[102:105], v[148:149], off offset:224
	s_add_i32 s11, s11, 1
	s_mul_i32 s0, s11, s7
	s_add_i32 s10, s10, s7
	global_load_dwordx4 v[84:87], v156, s[2:3]
	global_load_dwordx4 v[78:81], v[148:149], off offset:192
	v_lshlrev_b64 v[82:83], 12, v[66:67]
	v_lshl_add_u64 v[82:83], s[80:81], 0, v[82:83]
	v_lshl_add_u64 v[82:83], v[82:83], 0, v[72:73]
	s_waitcnt vmcnt(1)
	v_pk_fma_f32 v[64:65], v[64:65], v[86:87], v[104:105]
	global_load_dwordx4 v[74:77], v162, s[2:3]
	global_load_dwordx4 v[98:101], v[148:149], off offset:160
	global_load_dwordx4 v[106:109], v161, s[2:3]
	global_load_dwordx4 v[110:113], v[148:149], off offset:128
	global_load_dwordx4 v[114:117], v160, s[2:3]
	global_load_dwordx4 v[118:121], v[148:149], off offset:96
	global_load_dwordx4 v[122:125], v159, s[2:3]
	global_load_dwordx4 v[126:129], v[148:149], off offset:64
	global_load_dwordx4 v[136:139], v158, s[2:3]
	global_load_dwordx4 v[140:143], v[148:149], off offset:32
	global_load_dwordx4 v[144:147], v157, s[2:3]
	v_or_b32_e32 v86, 32, v66
	global_load_dwordx4 v[148:151], v[148:149], off
	v_pk_fma_f32 v[62:63], v[62:63], v[84:85], v[102:103]
	global_load_dwordx4 v[152:155], v72, s[2:3]
	v_mov_b32_e32 v87, v67
	global_store_dwordx4 v[82:83], v[62:65], off offset:224
	s_waitcnt vmcnt(13)
	v_pk_fma_f32 v[58:59], v[58:59], v[74:75], v[78:79]
	v_pk_fma_f32 v[60:61], v[60:61], v[76:77], v[80:81]
	s_waitcnt vmcnt(11)
	v_pk_fma_f32 v[54:55], v[54:55], v[106:107], v[98:99]
	v_pk_fma_f32 v[56:57], v[56:57], v[108:109], v[100:101]
	s_waitcnt vmcnt(9)
	v_pk_fma_f32 v[50:51], v[50:51], v[114:115], v[110:111]
	v_pk_fma_f32 v[52:53], v[52:53], v[116:117], v[112:113]
	s_waitcnt vmcnt(7)
	v_pk_fma_f32 v[46:47], v[46:47], v[122:123], v[118:119]
	v_pk_fma_f32 v[48:49], v[48:49], v[124:125], v[120:121]
	s_waitcnt vmcnt(5)
	v_pk_fma_f32 v[42:43], v[42:43], v[136:137], v[126:127]
	v_pk_fma_f32 v[44:45], v[44:45], v[138:139], v[128:129]
	s_waitcnt vmcnt(3)
	v_pk_fma_f32 v[38:39], v[38:39], v[144:145], v[140:141]
	v_pk_fma_f32 v[40:41], v[40:41], v[146:147], v[142:143]
	global_store_dwordx4 v[82:83], v[38:41], off offset:32
	global_store_dwordx4 v[82:83], v[42:45], off offset:64
	s_waitcnt vmcnt(3)
	v_pk_fma_f32 v[34:35], v[34:35], v[152:153], v[148:149]
	v_pk_fma_f32 v[36:37], v[36:37], v[154:155], v[150:151]
	global_store_dwordx4 v[82:83], v[34:37], off
	global_store_dwordx4 v[82:83], v[46:49], off offset:96
	global_store_dwordx4 v[82:83], v[50:53], off offset:128
	v_add_u32_e32 v34, 0xfffff020, v66
	v_cndmask_b32_e32 v66, v34, v86, vcc
	v_lshlrev_b64 v[34:35], 12, v[66:67]
	v_lshl_add_u64 v[34:35], s[4:5], 0, v[34:35]
	global_store_dwordx4 v[82:83], v[54:57], off offset:160
	global_store_dwordx4 v[82:83], v[58:61], off offset:192
	v_lshl_add_u64 v[118:119], v[34:35], 0, v[72:73]
	global_load_dwordx4 v[34:37], v[118:119], off offset:224
	global_load_dwordx4 v[38:41], v156, s[2:3]
	global_load_dwordx4 v[42:45], v[118:119], off offset:192
	global_load_dwordx4 v[46:49], v162, s[2:3]
	global_load_dwordx4 v[50:53], v[118:119], off offset:160
	global_load_dwordx4 v[54:57], v161, s[2:3]
	global_load_dwordx4 v[58:61], v[118:119], off offset:128
	global_load_dwordx4 v[62:65], v160, s[2:3]
	global_load_dwordx4 v[74:77], v[118:119], off offset:96
	global_load_dwordx4 v[78:81], v159, s[2:3]
	global_load_dwordx4 v[82:85], v[118:119], off offset:64
	global_load_dwordx4 v[98:101], v158, s[2:3]
	global_load_dwordx4 v[102:105], v[118:119], off offset:32
	global_load_dwordx4 v[106:109], v157, s[2:3]
	global_load_dwordx4 v[110:113], v[118:119], off
	global_load_dwordx4 v[114:117], v72, s[2:3]
	v_lshlrev_b64 v[86:87], 12, v[86:87]
	v_lshl_add_u64 v[86:87], s[80:81], 0, v[86:87]
	s_add_i32 s2, s0, s6
	v_lshl_add_u64 v[72:73], v[86:87], 0, v[72:73]
	s_cmpk_lt_u32 s10, 0x60
	s_waitcnt vmcnt(14)
	v_pk_fma_f32 v[30:31], v[30:31], v[38:39], v[34:35]
	v_pk_fma_f32 v[32:33], v[32:33], v[40:41], v[36:37]
	s_waitcnt vmcnt(12)
	v_pk_fma_f32 v[26:27], v[26:27], v[46:47], v[42:43]
	v_pk_fma_f32 v[28:29], v[28:29], v[48:49], v[44:45]
	s_waitcnt vmcnt(10)
	v_pk_fma_f32 v[22:23], v[22:23], v[54:55], v[50:51]
	v_pk_fma_f32 v[24:25], v[24:25], v[56:57], v[52:53]
	s_waitcnt vmcnt(8)
	v_pk_fma_f32 v[18:19], v[18:19], v[62:63], v[58:59]
	v_pk_fma_f32 v[20:21], v[20:21], v[64:65], v[60:61]
	s_waitcnt vmcnt(6)
	v_pk_fma_f32 v[14:15], v[14:15], v[78:79], v[74:75]
	v_pk_fma_f32 v[16:17], v[16:17], v[80:81], v[76:77]
	s_waitcnt vmcnt(4)
	v_pk_fma_f32 v[10:11], v[10:11], v[98:99], v[82:83]
	v_pk_fma_f32 v[12:13], v[12:13], v[100:101], v[84:85]
	s_waitcnt vmcnt(2)
	v_pk_fma_f32 v[6:7], v[6:7], v[106:107], v[102:103]
	v_pk_fma_f32 v[8:9], v[8:9], v[108:109], v[104:105]
	s_waitcnt vmcnt(0)
	v_pk_fma_f32 v[2:3], v[2:3], v[114:115], v[110:111]
	v_pk_fma_f32 v[4:5], v[4:5], v[116:117], v[112:113]
	global_store_dwordx4 v[72:73], v[2:5], off
	global_store_dwordx4 v[72:73], v[6:9], off offset:32
	global_store_dwordx4 v[72:73], v[10:13], off offset:64
	global_store_dwordx4 v[72:73], v[14:17], off offset:96
	global_store_dwordx4 v[72:73], v[18:21], off offset:128
	global_store_dwordx4 v[72:73], v[22:25], off offset:160
	global_store_dwordx4 v[72:73], v[26:29], off offset:192
	global_store_dwordx4 v[72:73], v[30:33], off offset:224
	s_cbranch_scc1 .LBB0_979

.LBB0_1149:
	v_ashrrev_i32_e32 v3, 31, v2
	v_lshlrev_b64 v[2:3], 11, v[2:3]
	v_lshl_add_u64 v[70:71], v[86:87], 0, v[2:3]
	v_or_b32_e32 v2, s56, v154
	v_ashrrev_i32_e32 v3, 31, v2
	v_lshlrev_b64 v[2:3], 11, v[2:3]
	v_lshl_add_u64 v[72:73], v[84:85], 0, v[2:3]
	v_add_u32_e32 v2, s56, v155
	v_ashrrev_i32_e32 v3, 31, v2
	v_lshlrev_b64 v[2:3], 11, v[2:3]
	v_lshl_add_u64 v[74:75], v[84:85], 0, v[2:3]
	v_add_u32_e32 v2, s56, v156
	v_ashrrev_i32_e32 v3, 31, v2
	v_lshlrev_b64 v[2:3], 11, v[2:3]
	v_lshl_add_u64 v[76:77], v[84:85], 0, v[2:3]
	v_add_u32_e32 v2, s56, v157
	v_ashrrev_i32_e32 v3, 31, v2
	v_ashrrev_i32_e32 v9, 31, v8
	v_ashrrev_i32_e32 v5, 31, v4
	v_lshlrev_b64 v[2:3], 11, v[2:3]
	v_ashrrev_i32_e32 v7, 31, v6
	v_lshlrev_b64 v[8:9], 11, v[8:9]
	v_lshlrev_b64 v[4:5], 11, v[4:5]
	v_lshl_add_u64 v[78:79], v[84:85], 0, v[2:3]
	v_lshlrev_b64 v[2:3], 11, v[6:7]
	v_lshl_add_u64 v[66:67], v[86:87], 0, v[8:9]
	v_lshl_add_u64 v[68:69], v[86:87], 0, v[4:5]
	v_lshl_add_u64 v[80:81], v[86:87], 0, v[2:3]
	global_load_dwordx4 v[2:5], v[70:71], off
	global_load_dwordx4 v[6:9], v[68:69], off
	global_load_dwordx4 v[10:13], v[66:67], off
	global_load_dwordx4 v[14:17], v[80:81], off
	global_load_dwordx4 v[18:21], v[72:73], off
	global_load_dwordx4 v[22:25], v[74:75], off
	global_load_dwordx4 v[26:29], v[76:77], off
	global_load_dwordx4 v[30:33], v[78:79], off
	global_load_dwordx4 v[122:125], v[70:71], off offset:128
	global_load_dwordx4 v[126:129], v[68:69], off offset:128
	global_load_dwordx4 v[136:139], v[66:67], off offset:128
	global_load_dwordx4 v[140:143], v[80:81], off offset:128
	global_load_dwordx4 v[144:147], v[72:73], off offset:128
	global_load_dwordx4 v[148:151], v[74:75], off offset:128
	global_load_dwordx4 v[172:175], v[76:77], off offset:128
	global_load_dwordx4 v[176:179], v[78:79], off offset:128
	s_setprio 1
	s_waitcnt vmcnt(15)
	ds_write_b128 v164, v[2:5] offset:36864
	s_waitcnt vmcnt(14)
	ds_write_b128 v164, v[6:9] offset:41472
	s_waitcnt vmcnt(13)
	ds_write_b128 v164, v[10:13] offset:46080
	s_waitcnt vmcnt(12)
	ds_write_b128 v164, v[14:17] offset:50688
	s_waitcnt vmcnt(11)
	ds_write_b128 v164, v[18:21]
	s_waitcnt vmcnt(10)
	ds_write_b128 v164, v[22:25] offset:4608
	s_waitcnt vmcnt(9)
	ds_write_b128 v164, v[26:29] offset:9216
	s_waitcnt vmcnt(8)
	ds_write_b128 v164, v[30:33] offset:13824
	s_waitcnt lgkmcnt(0)
	s_barrier
	s_setprio 0
	global_load_dwordx4 v[180:183], v[74:75], off offset:256
	global_load_dwordx4 v[188:191], v[76:77], off offset:256
	global_load_dwordx4 v[192:195], v[72:73], off offset:256
	global_load_dwordx4 v[196:199], v[70:71], off offset:256
	global_load_dwordx4 v[200:203], v[68:69], off offset:256
	global_load_dwordx4 v[204:207], v[66:67], off offset:256
	global_load_dwordx4 v[208:211], v[78:79], off offset:256
	global_load_dwordx4 v[212:215], v[80:81], off offset:256
	v_and_b32_e32 v246, 15, v1
	v_add_u32_e32 v246, 4, v246
	v_bfe_u32 v246, v246, 3, 1
	v_bfe_u32 v249, v1, 4, 2
	v_xor_b32_e32 v246, v246, v249
	v_bfe_u32 v249, v1, 5, 1
	v_sub_u32_e32 v246, v246, v249
	v_lshlrev_b32_e32 v246, 4, v246
	v_bfe_u32 v249, v1, 4, 1
	v_mul_u32_u24_e32 v249, 0x900, v249
	v_sub_u32_e32 v246, v246, v249
	v_add_u32_e32 v244, v246, v161
	v_add_u32_e32 v245, v246, v163
	ds_read_b128 v[232:235], v245 offset:36864
	ds_read_b128 v[216:219], v244
	ds_read_b128 v[236:239], v245 offset:39168
	ds_read_b128 v[240:243], v245 offset:41472
	ds_read_b128 v[252:255], v245 offset:43776
	ds_read_b128 v[220:223], v244 offset:2304
	ds_read_b128 v[224:227], v244 offset:4608
	ds_read_b128 v[228:231], v244 offset:6912
	s_waitcnt lgkmcnt(6)
	v_mfma_f32_16x16x32_bf16 v[50:53], v[216:219], v[232:235], 0
	s_waitcnt lgkmcnt(5)
	v_mfma_f32_16x16x32_bf16 v[54:57], v[216:219], v[236:239], 0
	s_waitcnt lgkmcnt(4)
	v_mfma_f32_16x16x32_bf16 v[34:37], v[216:219], v[240:243], 0
	s_waitcnt lgkmcnt(3)
	v_mfma_f32_16x16x32_bf16 v[38:41], v[216:219], v[252:255], 0
	ds_read_b128 v[216:219], v244 offset:64
	s_waitcnt lgkmcnt(3)
	v_mfma_f32_16x16x32_bf16 v[58:61], v[220:223], v[232:235], 0
	v_mfma_f32_16x16x32_bf16 v[62:65], v[220:223], v[236:239], 0
	v_mfma_f32_16x16x32_bf16 v[42:45], v[220:223], v[240:243], 0
	v_mfma_f32_16x16x32_bf16 v[46:49], v[220:223], v[252:255], 0
	ds_read_b128 v[220:223], v244 offset:2368
	s_setprio 1
	s_waitcnt vmcnt(11)
	ds_write_b128 v164, v[144:147] offset:18432
	s_waitcnt vmcnt(10)
	ds_write_b128 v164, v[148:151] offset:23040
	s_waitcnt lgkmcnt(5)
	v_mfma_f32_16x16x32_bf16 v[18:21], v[224:227], v[232:235], 0
	v_mfma_f32_16x16x32_bf16 v[22:25], v[224:227], v[236:239], 0
	v_mfma_f32_16x16x32_bf16 v[2:5], v[224:227], v[240:243], 0
	v_mfma_f32_16x16x32_bf16 v[6:9], v[224:227], v[252:255], 0
	ds_read_b128 v[224:227], v244 offset:4672
	s_waitcnt vmcnt(9)
	ds_write_b128 v164, v[172:175] offset:27648
	s_waitcnt vmcnt(8)
	ds_write_b128 v164, v[176:179] offset:32256
	s_waitcnt lgkmcnt(7)
	v_mfma_f32_16x16x32_bf16 v[26:29], v[228:231], v[232:235], 0
	ds_read_b128 v[232:235], v245 offset:36928
	v_mfma_f32_16x16x32_bf16 v[30:33], v[228:231], v[236:239], 0
	ds_read_b128 v[236:239], v245 offset:39232
	v_mfma_f32_16x16x32_bf16 v[10:13], v[228:231], v[240:243], 0
	ds_read_b128 v[240:243], v245 offset:41536
	v_mfma_f32_16x16x32_bf16 v[14:17], v[228:231], v[252:255], 0
	ds_read_b128 v[252:255], v245 offset:43840
	ds_read_b128 v[228:231], v244 offset:6976
	s_waitcnt lgkmcnt(4)
	v_mfma_f32_16x16x32_bf16 v[50:53], v[216:219], v[232:235], v[50:53]
	s_waitcnt lgkmcnt(3)
	v_mfma_f32_16x16x32_bf16 v[54:57], v[216:219], v[236:239], v[54:57]
	s_waitcnt lgkmcnt(2)
	v_mfma_f32_16x16x32_bf16 v[34:37], v[216:219], v[240:243], v[34:37]
	s_waitcnt lgkmcnt(1)
	v_mfma_f32_16x16x32_bf16 v[38:41], v[216:219], v[252:255], v[38:41]
	ds_write_b128 v164, v[122:125] offset:55296
	ds_write_b128 v164, v[126:129] offset:59904
	v_mfma_f32_16x16x32_bf16 v[58:61], v[220:223], v[232:235], v[58:61]
	v_mfma_f32_16x16x32_bf16 v[62:65], v[220:223], v[236:239], v[62:65]
	v_mfma_f32_16x16x32_bf16 v[42:45], v[220:223], v[240:243], v[42:45]
	v_mfma_f32_16x16x32_bf16 v[46:49], v[220:223], v[252:255], v[46:49]
	ds_write_b128 v164, v[136:139] offset:64512
	ds_write_b128 v165, v[140:143] offset:32256
	v_mfma_f32_16x16x32_bf16 v[18:21], v[224:227], v[232:235], v[18:21]
	v_mfma_f32_16x16x32_bf16 v[22:25], v[224:227], v[236:239], v[22:25]
	v_mfma_f32_16x16x32_bf16 v[2:5], v[224:227], v[240:243], v[2:5]
	v_mfma_f32_16x16x32_bf16 v[6:9], v[224:227], v[252:255], v[6:9]
	s_waitcnt lgkmcnt(4)
	v_mfma_f32_16x16x32_bf16 v[26:29], v[228:231], v[232:235], v[26:29]
	v_mfma_f32_16x16x32_bf16 v[30:33], v[228:231], v[236:239], v[30:33]
	v_mfma_f32_16x16x32_bf16 v[10:13], v[228:231], v[240:243], v[10:13]
	v_mfma_f32_16x16x32_bf16 v[14:17], v[228:231], v[252:255], v[14:17]
	s_waitcnt lgkmcnt(0)
	s_barrier
	s_setprio 0
	global_load_dwordx4 v[122:125], v[72:73], off offset:384
	global_load_dwordx4 v[126:129], v[74:75], off offset:384
	global_load_dwordx4 v[136:139], v[76:77], off offset:384
	global_load_dwordx4 v[140:143], v[78:79], off offset:384
	global_load_dwordx4 v[144:147], v[70:71], off offset:384
	global_load_dwordx4 v[148:151], v[68:69], off offset:384
	global_load_dwordx4 v[172:175], v[66:67], off offset:384
	global_load_dwordx4 v[176:179], v[80:81], off offset:384
	ds_read_b128 v[232:235], v245 offset:55296
	ds_read_b128 v[216:219], v244 offset:18432
	ds_read_b128 v[236:239], v245 offset:57600
	ds_read_b128 v[240:243], v245 offset:59904
	ds_read_b128 v[252:255], v245 offset:62208
	ds_read_b128 v[220:223], v244 offset:20736
	ds_read_b128 v[224:227], v244 offset:23040
	ds_read_b128 v[228:231], v244 offset:25344
	s_waitcnt lgkmcnt(6)
	v_mfma_f32_16x16x32_bf16 v[50:53], v[216:219], v[232:235], v[50:53]
	s_waitcnt lgkmcnt(5)
	v_mfma_f32_16x16x32_bf16 v[54:57], v[216:219], v[236:239], v[54:57]
	s_waitcnt lgkmcnt(4)
	v_mfma_f32_16x16x32_bf16 v[34:37], v[216:219], v[240:243], v[34:37]
	s_waitcnt lgkmcnt(3)
	v_mfma_f32_16x16x32_bf16 v[38:41], v[216:219], v[252:255], v[38:41]
	ds_read_b128 v[216:219], v244 offset:18496
	s_waitcnt lgkmcnt(3)
	v_mfma_f32_16x16x32_bf16 v[58:61], v[220:223], v[232:235], v[58:61]
	v_mfma_f32_16x16x32_bf16 v[62:65], v[220:223], v[236:239], v[62:65]
	v_mfma_f32_16x16x32_bf16 v[42:45], v[220:223], v[240:243], v[42:45]
	v_mfma_f32_16x16x32_bf16 v[46:49], v[220:223], v[252:255], v[46:49]
	ds_read_b128 v[220:223], v244 offset:20800
	s_setprio 1
	s_waitcnt vmcnt(13)
	ds_write_b128 v164, v[192:195]
	ds_write_b128 v164, v[180:183] offset:4608
	s_waitcnt lgkmcnt(5)
	v_mfma_f32_16x16x32_bf16 v[18:21], v[224:227], v[232:235], v[18:21]
	v_mfma_f32_16x16x32_bf16 v[22:25], v[224:227], v[236:239], v[22:25]
	v_mfma_f32_16x16x32_bf16 v[2:5], v[224:227], v[240:243], v[2:5]
	v_mfma_f32_16x16x32_bf16 v[6:9], v[224:227], v[252:255], v[6:9]
	ds_read_b128 v[224:227], v244 offset:23104
	ds_write_b128 v164, v[188:191] offset:9216
	s_waitcnt vmcnt(9)
	ds_write_b128 v164, v[208:211] offset:13824
	s_waitcnt lgkmcnt(7)
	v_mfma_f32_16x16x32_bf16 v[26:29], v[228:231], v[232:235], v[26:29]
	ds_read_b128 v[232:235], v245 offset:55360
	v_mfma_f32_16x16x32_bf16 v[30:33], v[228:231], v[236:239], v[30:33]
	ds_read_b128 v[236:239], v245 offset:57664
	v_mfma_f32_16x16x32_bf16 v[10:13], v[228:231], v[240:243], v[10:13]
	ds_read_b128 v[240:243], v245 offset:59968
	v_mfma_f32_16x16x32_bf16 v[14:17], v[228:231], v[252:255], v[14:17]
	ds_read_b128 v[252:255], v245 offset:62272
	ds_read_b128 v[228:231], v244 offset:25408
	s_waitcnt lgkmcnt(4)
	v_mfma_f32_16x16x32_bf16 v[50:53], v[216:219], v[232:235], v[50:53]
	s_waitcnt lgkmcnt(3)
	v_mfma_f32_16x16x32_bf16 v[54:57], v[216:219], v[236:239], v[54:57]
	s_waitcnt lgkmcnt(2)
	v_mfma_f32_16x16x32_bf16 v[34:37], v[216:219], v[240:243], v[34:37]
	s_waitcnt lgkmcnt(1)
	v_mfma_f32_16x16x32_bf16 v[38:41], v[216:219], v[252:255], v[38:41]
	ds_write_b128 v164, v[196:199] offset:36864
	ds_write_b128 v164, v[200:203] offset:41472
	v_mfma_f32_16x16x32_bf16 v[58:61], v[220:223], v[232:235], v[58:61]
	v_mfma_f32_16x16x32_bf16 v[62:65], v[220:223], v[236:239], v[62:65]
	v_mfma_f32_16x16x32_bf16 v[42:45], v[220:223], v[240:243], v[42:45]
	v_mfma_f32_16x16x32_bf16 v[46:49], v[220:223], v[252:255], v[46:49]
	ds_write_b128 v164, v[204:207] offset:46080
	s_waitcnt vmcnt(8)
	ds_write_b128 v164, v[212:215] offset:50688
	v_mfma_f32_16x16x32_bf16 v[18:21], v[224:227], v[232:235], v[18:21]
	v_mfma_f32_16x16x32_bf16 v[22:25], v[224:227], v[236:239], v[22:25]
	v_mfma_f32_16x16x32_bf16 v[2:5], v[224:227], v[240:243], v[2:5]
	v_mfma_f32_16x16x32_bf16 v[6:9], v[224:227], v[252:255], v[6:9]
	s_waitcnt lgkmcnt(4)
	v_mfma_f32_16x16x32_bf16 v[26:29], v[228:231], v[232:235], v[26:29]
	v_mfma_f32_16x16x32_bf16 v[30:33], v[228:231], v[236:239], v[30:33]
	v_mfma_f32_16x16x32_bf16 v[10:13], v[228:231], v[240:243], v[10:13]
	v_mfma_f32_16x16x32_bf16 v[14:17], v[228:231], v[252:255], v[14:17]
	s_waitcnt lgkmcnt(0)
	s_barrier
	s_setprio 0
	global_load_dwordx4 v[180:183], v[72:73], off offset:512
	global_load_dwordx4 v[188:191], v[74:75], off offset:512
	global_load_dwordx4 v[192:195], v[76:77], off offset:512
	global_load_dwordx4 v[196:199], v[78:79], off offset:512
	global_load_dwordx4 v[200:203], v[70:71], off offset:512
	global_load_dwordx4 v[204:207], v[68:69], off offset:512
	global_load_dwordx4 v[208:211], v[66:67], off offset:512
	global_load_dwordx4 v[212:215], v[80:81], off offset:512
	ds_read_b128 v[232:235], v245 offset:36864
	ds_read_b128 v[216:219], v244
	ds_read_b128 v[236:239], v245 offset:39168
	ds_read_b128 v[240:243], v245 offset:41472
	ds_read_b128 v[252:255], v245 offset:43776
	ds_read_b128 v[220:223], v244 offset:2304
	ds_read_b128 v[224:227], v244 offset:4608
	ds_read_b128 v[228:231], v244 offset:6912
	s_waitcnt lgkmcnt(6)
	v_mfma_f32_16x16x32_bf16 v[50:53], v[216:219], v[232:235], v[50:53]
	s_waitcnt lgkmcnt(5)
	v_mfma_f32_16x16x32_bf16 v[54:57], v[216:219], v[236:239], v[54:57]
	s_waitcnt lgkmcnt(4)
	v_mfma_f32_16x16x32_bf16 v[34:37], v[216:219], v[240:243], v[34:37]
	s_waitcnt lgkmcnt(3)
	v_mfma_f32_16x16x32_bf16 v[38:41], v[216:219], v[252:255], v[38:41]
	ds_read_b128 v[216:219], v244 offset:64
	s_waitcnt lgkmcnt(3)
	v_mfma_f32_16x16x32_bf16 v[58:61], v[220:223], v[232:235], v[58:61]
	v_mfma_f32_16x16x32_bf16 v[62:65], v[220:223], v[236:239], v[62:65]
	v_mfma_f32_16x16x32_bf16 v[42:45], v[220:223], v[240:243], v[42:45]
	v_mfma_f32_16x16x32_bf16 v[46:49], v[220:223], v[252:255], v[46:49]
	ds_read_b128 v[220:223], v244 offset:2368
	s_setprio 1
	s_waitcnt vmcnt(15)
	ds_write_b128 v164, v[122:125] offset:18432
	s_waitcnt vmcnt(14)
	ds_write_b128 v164, v[126:129] offset:23040
	s_waitcnt lgkmcnt(5)
	v_mfma_f32_16x16x32_bf16 v[18:21], v[224:227], v[232:235], v[18:21]
	v_mfma_f32_16x16x32_bf16 v[22:25], v[224:227], v[236:239], v[22:25]
	v_mfma_f32_16x16x32_bf16 v[2:5], v[224:227], v[240:243], v[2:5]
	v_mfma_f32_16x16x32_bf16 v[6:9], v[224:227], v[252:255], v[6:9]
	ds_read_b128 v[224:227], v244 offset:4672
	s_waitcnt vmcnt(13)
	ds_write_b128 v164, v[136:139] offset:27648
	s_waitcnt vmcnt(12)
	ds_write_b128 v164, v[140:143] offset:32256
	s_waitcnt lgkmcnt(7)
	v_mfma_f32_16x16x32_bf16 v[26:29], v[228:231], v[232:235], v[26:29]
	ds_read_b128 v[232:235], v245 offset:36928
	v_mfma_f32_16x16x32_bf16 v[30:33], v[228:231], v[236:239], v[30:33]
	ds_read_b128 v[236:239], v245 offset:39232
	v_mfma_f32_16x16x32_bf16 v[10:13], v[228:231], v[240:243], v[10:13]
	ds_read_b128 v[240:243], v245 offset:41536
	v_mfma_f32_16x16x32_bf16 v[14:17], v[228:231], v[252:255], v[14:17]
	ds_read_b128 v[252:255], v245 offset:43840
	ds_read_b128 v[228:231], v244 offset:6976
	s_waitcnt lgkmcnt(4)
	v_mfma_f32_16x16x32_bf16 v[50:53], v[216:219], v[232:235], v[50:53]
	s_waitcnt lgkmcnt(3)
	v_mfma_f32_16x16x32_bf16 v[54:57], v[216:219], v[236:239], v[54:57]
	s_waitcnt lgkmcnt(2)
	v_mfma_f32_16x16x32_bf16 v[34:37], v[216:219], v[240:243], v[34:37]
	s_waitcnt lgkmcnt(1)
	v_mfma_f32_16x16x32_bf16 v[38:41], v[216:219], v[252:255], v[38:41]
	s_waitcnt vmcnt(11)
	ds_write_b128 v164, v[144:147] offset:55296
	s_waitcnt vmcnt(10)
	ds_write_b128 v164, v[148:151] offset:59904
	v_mfma_f32_16x16x32_bf16 v[58:61], v[220:223], v[232:235], v[58:61]
	v_mfma_f32_16x16x32_bf16 v[62:65], v[220:223], v[236:239], v[62:65]
	v_mfma_f32_16x16x32_bf16 v[42:45], v[220:223], v[240:243], v[42:45]
	v_mfma_f32_16x16x32_bf16 v[46:49], v[220:223], v[252:255], v[46:49]
	s_waitcnt vmcnt(9)
	ds_write_b128 v164, v[172:175] offset:64512
	s_waitcnt vmcnt(8)
	ds_write_b128 v165, v[176:179] offset:32256
	v_mfma_f32_16x16x32_bf16 v[18:21], v[224:227], v[232:235], v[18:21]
	v_mfma_f32_16x16x32_bf16 v[22:25], v[224:227], v[236:239], v[22:25]
	v_mfma_f32_16x16x32_bf16 v[2:5], v[224:227], v[240:243], v[2:5]
	v_mfma_f32_16x16x32_bf16 v[6:9], v[224:227], v[252:255], v[6:9]
	s_waitcnt lgkmcnt(4)
	v_mfma_f32_16x16x32_bf16 v[26:29], v[228:231], v[232:235], v[26:29]
	v_mfma_f32_16x16x32_bf16 v[30:33], v[228:231], v[236:239], v[30:33]
	v_mfma_f32_16x16x32_bf16 v[10:13], v[228:231], v[240:243], v[10:13]
	v_mfma_f32_16x16x32_bf16 v[14:17], v[228:231], v[252:255], v[14:17]
	s_waitcnt lgkmcnt(0)
	s_barrier
	s_setprio 0
	global_load_dwordx4 v[122:125], v[72:73], off offset:640
	global_load_dwordx4 v[126:129], v[74:75], off offset:640
	global_load_dwordx4 v[136:139], v[76:77], off offset:640
	global_load_dwordx4 v[140:143], v[78:79], off offset:640
	global_load_dwordx4 v[144:147], v[70:71], off offset:640
	global_load_dwordx4 v[148:151], v[68:69], off offset:640
	global_load_dwordx4 v[172:175], v[66:67], off offset:640
	global_load_dwordx4 v[176:179], v[80:81], off offset:640
	ds_read_b128 v[232:235], v245 offset:55296
	ds_read_b128 v[216:219], v244 offset:18432
	ds_read_b128 v[236:239], v245 offset:57600
	ds_read_b128 v[240:243], v245 offset:59904
	ds_read_b128 v[252:255], v245 offset:62208
	ds_read_b128 v[220:223], v244 offset:20736
	ds_read_b128 v[224:227], v244 offset:23040
	ds_read_b128 v[228:231], v244 offset:25344
	s_waitcnt lgkmcnt(6)
	v_mfma_f32_16x16x32_bf16 v[50:53], v[216:219], v[232:235], v[50:53]
	s_waitcnt lgkmcnt(5)
	v_mfma_f32_16x16x32_bf16 v[54:57], v[216:219], v[236:239], v[54:57]
	s_waitcnt lgkmcnt(4)
	v_mfma_f32_16x16x32_bf16 v[34:37], v[216:219], v[240:243], v[34:37]
	s_waitcnt lgkmcnt(3)
	v_mfma_f32_16x16x32_bf16 v[38:41], v[216:219], v[252:255], v[38:41]
	ds_read_b128 v[216:219], v244 offset:18496
	s_waitcnt lgkmcnt(3)
	v_mfma_f32_16x16x32_bf16 v[58:61], v[220:223], v[232:235], v[58:61]
	v_mfma_f32_16x16x32_bf16 v[62:65], v[220:223], v[236:239], v[62:65]
	v_mfma_f32_16x16x32_bf16 v[42:45], v[220:223], v[240:243], v[42:45]
	v_mfma_f32_16x16x32_bf16 v[46:49], v[220:223], v[252:255], v[46:49]
	ds_read_b128 v[220:223], v244 offset:20800
	s_setprio 1
	s_waitcnt vmcnt(15)
	ds_write_b128 v164, v[180:183]
	s_waitcnt vmcnt(14)
	ds_write_b128 v164, v[188:191] offset:4608
	s_waitcnt lgkmcnt(5)
	v_mfma_f32_16x16x32_bf16 v[18:21], v[224:227], v[232:235], v[18:21]
	v_mfma_f32_16x16x32_bf16 v[22:25], v[224:227], v[236:239], v[22:25]
	v_mfma_f32_16x16x32_bf16 v[2:5], v[224:227], v[240:243], v[2:5]
	v_mfma_f32_16x16x32_bf16 v[6:9], v[224:227], v[252:255], v[6:9]
	ds_read_b128 v[224:227], v244 offset:23104
	s_waitcnt vmcnt(13)
	ds_write_b128 v164, v[192:195] offset:9216
	s_waitcnt vmcnt(12)
	ds_write_b128 v164, v[196:199] offset:13824
	s_waitcnt lgkmcnt(7)
	v_mfma_f32_16x16x32_bf16 v[26:29], v[228:231], v[232:235], v[26:29]
	ds_read_b128 v[232:235], v245 offset:55360
	v_mfma_f32_16x16x32_bf16 v[30:33], v[228:231], v[236:239], v[30:33]
	ds_read_b128 v[236:239], v245 offset:57664
	v_mfma_f32_16x16x32_bf16 v[10:13], v[228:231], v[240:243], v[10:13]
	ds_read_b128 v[240:243], v245 offset:59968
	v_mfma_f32_16x16x32_bf16 v[14:17], v[228:231], v[252:255], v[14:17]
	ds_read_b128 v[252:255], v245 offset:62272
	ds_read_b128 v[228:231], v244 offset:25408
	s_waitcnt lgkmcnt(4)
	v_mfma_f32_16x16x32_bf16 v[50:53], v[216:219], v[232:235], v[50:53]
	s_waitcnt lgkmcnt(3)
	v_mfma_f32_16x16x32_bf16 v[54:57], v[216:219], v[236:239], v[54:57]
	s_waitcnt lgkmcnt(2)
	v_mfma_f32_16x16x32_bf16 v[34:37], v[216:219], v[240:243], v[34:37]
	s_waitcnt lgkmcnt(1)
	v_mfma_f32_16x16x32_bf16 v[38:41], v[216:219], v[252:255], v[38:41]
	s_waitcnt vmcnt(11)
	ds_write_b128 v164, v[200:203] offset:36864
	s_waitcnt vmcnt(10)
	ds_write_b128 v164, v[204:207] offset:41472
	v_mfma_f32_16x16x32_bf16 v[58:61], v[220:223], v[232:235], v[58:61]
	v_mfma_f32_16x16x32_bf16 v[62:65], v[220:223], v[236:239], v[62:65]
	v_mfma_f32_16x16x32_bf16 v[42:45], v[220:223], v[240:243], v[42:45]
	v_mfma_f32_16x16x32_bf16 v[46:49], v[220:223], v[252:255], v[46:49]
	s_waitcnt vmcnt(9)
	ds_write_b128 v164, v[208:211] offset:46080
	s_waitcnt vmcnt(8)
	ds_write_b128 v164, v[212:215] offset:50688
	v_mfma_f32_16x16x32_bf16 v[18:21], v[224:227], v[232:235], v[18:21]
	v_mfma_f32_16x16x32_bf16 v[22:25], v[224:227], v[236:239], v[22:25]
	v_mfma_f32_16x16x32_bf16 v[2:5], v[224:227], v[240:243], v[2:5]
	v_mfma_f32_16x16x32_bf16 v[6:9], v[224:227], v[252:255], v[6:9]
	s_waitcnt lgkmcnt(4)
	v_mfma_f32_16x16x32_bf16 v[26:29], v[228:231], v[232:235], v[26:29]
	v_mfma_f32_16x16x32_bf16 v[30:33], v[228:231], v[236:239], v[30:33]
	v_mfma_f32_16x16x32_bf16 v[10:13], v[228:231], v[240:243], v[10:13]
	v_mfma_f32_16x16x32_bf16 v[14:17], v[228:231], v[252:255], v[14:17]
	s_waitcnt lgkmcnt(0)
	s_barrier
	s_setprio 0
	global_load_dwordx4 v[180:183], v[72:73], off offset:768
	global_load_dwordx4 v[188:191], v[74:75], off offset:768
	global_load_dwordx4 v[192:195], v[76:77], off offset:768
	global_load_dwordx4 v[196:199], v[78:79], off offset:768
	global_load_dwordx4 v[200:203], v[70:71], off offset:768
	global_load_dwordx4 v[204:207], v[68:69], off offset:768
	global_load_dwordx4 v[208:211], v[66:67], off offset:768
	global_load_dwordx4 v[212:215], v[80:81], off offset:768
	ds_read_b128 v[232:235], v245 offset:36864
	ds_read_b128 v[216:219], v244
	ds_read_b128 v[236:239], v245 offset:39168
	ds_read_b128 v[240:243], v245 offset:41472
	ds_read_b128 v[252:255], v245 offset:43776
	ds_read_b128 v[220:223], v244 offset:2304
	ds_read_b128 v[224:227], v244 offset:4608
	ds_read_b128 v[228:231], v244 offset:6912
	s_waitcnt lgkmcnt(6)
	v_mfma_f32_16x16x32_bf16 v[50:53], v[216:219], v[232:235], v[50:53]
	s_waitcnt lgkmcnt(5)
	v_mfma_f32_16x16x32_bf16 v[54:57], v[216:219], v[236:239], v[54:57]
	s_waitcnt lgkmcnt(4)
	v_mfma_f32_16x16x32_bf16 v[34:37], v[216:219], v[240:243], v[34:37]
	s_waitcnt lgkmcnt(3)
	v_mfma_f32_16x16x32_bf16 v[38:41], v[216:219], v[252:255], v[38:41]
	ds_read_b128 v[216:219], v244 offset:64
	s_waitcnt lgkmcnt(3)
	v_mfma_f32_16x16x32_bf16 v[58:61], v[220:223], v[232:235], v[58:61]
	v_mfma_f32_16x16x32_bf16 v[62:65], v[220:223], v[236:239], v[62:65]
	v_mfma_f32_16x16x32_bf16 v[42:45], v[220:223], v[240:243], v[42:45]
	v_mfma_f32_16x16x32_bf16 v[46:49], v[220:223], v[252:255], v[46:49]
	ds_read_b128 v[220:223], v244 offset:2368
	s_setprio 1
	s_waitcnt vmcnt(15)
	ds_write_b128 v164, v[122:125] offset:18432
	s_waitcnt vmcnt(14)
	ds_write_b128 v164, v[126:129] offset:23040
	s_waitcnt lgkmcnt(5)
	v_mfma_f32_16x16x32_bf16 v[18:21], v[224:227], v[232:235], v[18:21]
	v_mfma_f32_16x16x32_bf16 v[22:25], v[224:227], v[236:239], v[22:25]
	v_mfma_f32_16x16x32_bf16 v[2:5], v[224:227], v[240:243], v[2:5]
	v_mfma_f32_16x16x32_bf16 v[6:9], v[224:227], v[252:255], v[6:9]
	ds_read_b128 v[224:227], v244 offset:4672
	s_waitcnt vmcnt(13)
	ds_write_b128 v164, v[136:139] offset:27648
	s_waitcnt vmcnt(12)
	ds_write_b128 v164, v[140:143] offset:32256
	s_waitcnt lgkmcnt(7)
	v_mfma_f32_16x16x32_bf16 v[26:29], v[228:231], v[232:235], v[26:29]
	ds_read_b128 v[232:235], v245 offset:36928
	v_mfma_f32_16x16x32_bf16 v[30:33], v[228:231], v[236:239], v[30:33]
	ds_read_b128 v[236:239], v245 offset:39232
	v_mfma_f32_16x16x32_bf16 v[10:13], v[228:231], v[240:243], v[10:13]
	ds_read_b128 v[240:243], v245 offset:41536
	v_mfma_f32_16x16x32_bf16 v[14:17], v[228:231], v[252:255], v[14:17]
	ds_read_b128 v[252:255], v245 offset:43840
	ds_read_b128 v[228:231], v244 offset:6976
	s_waitcnt lgkmcnt(4)
	v_mfma_f32_16x16x32_bf16 v[50:53], v[216:219], v[232:235], v[50:53]
	s_waitcnt lgkmcnt(3)
	v_mfma_f32_16x16x32_bf16 v[54:57], v[216:219], v[236:239], v[54:57]
	s_waitcnt lgkmcnt(2)
	v_mfma_f32_16x16x32_bf16 v[34:37], v[216:219], v[240:243], v[34:37]
	s_waitcnt lgkmcnt(1)
	v_mfma_f32_16x16x32_bf16 v[38:41], v[216:219], v[252:255], v[38:41]
	s_waitcnt vmcnt(11)
	ds_write_b128 v164, v[144:147] offset:55296
	s_waitcnt vmcnt(10)
	ds_write_b128 v164, v[148:151] offset:59904
	v_mfma_f32_16x16x32_bf16 v[58:61], v[220:223], v[232:235], v[58:61]
	v_mfma_f32_16x16x32_bf16 v[62:65], v[220:223], v[236:239], v[62:65]
	v_mfma_f32_16x16x32_bf16 v[42:45], v[220:223], v[240:243], v[42:45]
	v_mfma_f32_16x16x32_bf16 v[46:49], v[220:223], v[252:255], v[46:49]
	s_waitcnt vmcnt(9)
	ds_write_b128 v164, v[172:175] offset:64512
	s_waitcnt vmcnt(8)
	ds_write_b128 v165, v[176:179] offset:32256
	v_mfma_f32_16x16x32_bf16 v[18:21], v[224:227], v[232:235], v[18:21]
	v_mfma_f32_16x16x32_bf16 v[22:25], v[224:227], v[236:239], v[22:25]
	v_mfma_f32_16x16x32_bf16 v[2:5], v[224:227], v[240:243], v[2:5]
	v_mfma_f32_16x16x32_bf16 v[6:9], v[224:227], v[252:255], v[6:9]
	s_waitcnt lgkmcnt(4)
	v_mfma_f32_16x16x32_bf16 v[26:29], v[228:231], v[232:235], v[26:29]
	v_mfma_f32_16x16x32_bf16 v[30:33], v[228:231], v[236:239], v[30:33]
	v_mfma_f32_16x16x32_bf16 v[10:13], v[228:231], v[240:243], v[10:13]
	v_mfma_f32_16x16x32_bf16 v[14:17], v[228:231], v[252:255], v[14:17]
	s_waitcnt lgkmcnt(0)
	s_barrier
	s_setprio 0
	global_load_dwordx4 v[122:125], v[72:73], off offset:896
	global_load_dwordx4 v[126:129], v[74:75], off offset:896
	global_load_dwordx4 v[136:139], v[76:77], off offset:896
	global_load_dwordx4 v[140:143], v[78:79], off offset:896
	global_load_dwordx4 v[144:147], v[70:71], off offset:896
	global_load_dwordx4 v[148:151], v[68:69], off offset:896
	global_load_dwordx4 v[172:175], v[66:67], off offset:896
	global_load_dwordx4 v[176:179], v[80:81], off offset:896
	ds_read_b128 v[232:235], v245 offset:55296
	ds_read_b128 v[216:219], v244 offset:18432
	ds_read_b128 v[236:239], v245 offset:57600
	ds_read_b128 v[240:243], v245 offset:59904
	ds_read_b128 v[252:255], v245 offset:62208
	ds_read_b128 v[220:223], v244 offset:20736
	ds_read_b128 v[224:227], v244 offset:23040
	ds_read_b128 v[228:231], v244 offset:25344
	s_waitcnt lgkmcnt(6)
	v_mfma_f32_16x16x32_bf16 v[50:53], v[216:219], v[232:235], v[50:53]
	s_waitcnt lgkmcnt(5)
	v_mfma_f32_16x16x32_bf16 v[54:57], v[216:219], v[236:239], v[54:57]
	s_waitcnt lgkmcnt(4)
	v_mfma_f32_16x16x32_bf16 v[34:37], v[216:219], v[240:243], v[34:37]
	s_waitcnt lgkmcnt(3)
	v_mfma_f32_16x16x32_bf16 v[38:41], v[216:219], v[252:255], v[38:41]
	ds_read_b128 v[216:219], v244 offset:18496
	s_waitcnt lgkmcnt(3)
	v_mfma_f32_16x16x32_bf16 v[58:61], v[220:223], v[232:235], v[58:61]
	v_mfma_f32_16x16x32_bf16 v[62:65], v[220:223], v[236:239], v[62:65]
	v_mfma_f32_16x16x32_bf16 v[42:45], v[220:223], v[240:243], v[42:45]
	v_mfma_f32_16x16x32_bf16 v[46:49], v[220:223], v[252:255], v[46:49]
	ds_read_b128 v[220:223], v244 offset:20800
	s_setprio 1
	s_waitcnt vmcnt(15)
	ds_write_b128 v164, v[180:183]
	s_waitcnt vmcnt(14)
	ds_write_b128 v164, v[188:191] offset:4608
	s_waitcnt lgkmcnt(5)
	v_mfma_f32_16x16x32_bf16 v[18:21], v[224:227], v[232:235], v[18:21]
	v_mfma_f32_16x16x32_bf16 v[22:25], v[224:227], v[236:239], v[22:25]
	v_mfma_f32_16x16x32_bf16 v[2:5], v[224:227], v[240:243], v[2:5]
	v_mfma_f32_16x16x32_bf16 v[6:9], v[224:227], v[252:255], v[6:9]
	ds_read_b128 v[224:227], v244 offset:23104
	s_waitcnt vmcnt(13)
	ds_write_b128 v164, v[192:195] offset:9216
	s_waitcnt vmcnt(12)
	ds_write_b128 v164, v[196:199] offset:13824
	s_waitcnt lgkmcnt(7)
	v_mfma_f32_16x16x32_bf16 v[26:29], v[228:231], v[232:235], v[26:29]
	ds_read_b128 v[232:235], v245 offset:55360
	v_mfma_f32_16x16x32_bf16 v[30:33], v[228:231], v[236:239], v[30:33]
	ds_read_b128 v[236:239], v245 offset:57664
	v_mfma_f32_16x16x32_bf16 v[10:13], v[228:231], v[240:243], v[10:13]
	ds_read_b128 v[240:243], v245 offset:59968
	v_mfma_f32_16x16x32_bf16 v[14:17], v[228:231], v[252:255], v[14:17]
	ds_read_b128 v[252:255], v245 offset:62272
	ds_read_b128 v[228:231], v244 offset:25408
	s_waitcnt lgkmcnt(4)
	v_mfma_f32_16x16x32_bf16 v[50:53], v[216:219], v[232:235], v[50:53]
	s_waitcnt lgkmcnt(3)
	v_mfma_f32_16x16x32_bf16 v[54:57], v[216:219], v[236:239], v[54:57]
	s_waitcnt lgkmcnt(2)
	v_mfma_f32_16x16x32_bf16 v[34:37], v[216:219], v[240:243], v[34:37]
	s_waitcnt lgkmcnt(1)
	v_mfma_f32_16x16x32_bf16 v[38:41], v[216:219], v[252:255], v[38:41]
	s_waitcnt vmcnt(11)
	ds_write_b128 v164, v[200:203] offset:36864
	s_waitcnt vmcnt(10)
	ds_write_b128 v164, v[204:207] offset:41472
	v_mfma_f32_16x16x32_bf16 v[58:61], v[220:223], v[232:235], v[58:61]
	v_mfma_f32_16x16x32_bf16 v[62:65], v[220:223], v[236:239], v[62:65]
	v_mfma_f32_16x16x32_bf16 v[42:45], v[220:223], v[240:243], v[42:45]
	v_mfma_f32_16x16x32_bf16 v[46:49], v[220:223], v[252:255], v[46:49]
	s_waitcnt vmcnt(9)
	ds_write_b128 v164, v[208:211] offset:46080
	s_waitcnt vmcnt(8)
	ds_write_b128 v164, v[212:215] offset:50688
	v_mfma_f32_16x16x32_bf16 v[18:21], v[224:227], v[232:235], v[18:21]
	v_mfma_f32_16x16x32_bf16 v[22:25], v[224:227], v[236:239], v[22:25]
	v_mfma_f32_16x16x32_bf16 v[2:5], v[224:227], v[240:243], v[2:5]
	v_mfma_f32_16x16x32_bf16 v[6:9], v[224:227], v[252:255], v[6:9]
	s_waitcnt lgkmcnt(4)
	v_mfma_f32_16x16x32_bf16 v[26:29], v[228:231], v[232:235], v[26:29]
	v_mfma_f32_16x16x32_bf16 v[30:33], v[228:231], v[236:239], v[30:33]
	v_mfma_f32_16x16x32_bf16 v[10:13], v[228:231], v[240:243], v[10:13]
	v_mfma_f32_16x16x32_bf16 v[14:17], v[228:231], v[252:255], v[14:17]
	s_waitcnt lgkmcnt(0)
	s_barrier
	s_setprio 0
	global_load_dwordx4 v[180:183], v[72:73], off offset:1024
	global_load_dwordx4 v[188:191], v[74:75], off offset:1024
	global_load_dwordx4 v[192:195], v[76:77], off offset:1024
	global_load_dwordx4 v[196:199], v[78:79], off offset:1024
	global_load_dwordx4 v[200:203], v[70:71], off offset:1024
	global_load_dwordx4 v[204:207], v[68:69], off offset:1024
	global_load_dwordx4 v[208:211], v[66:67], off offset:1024
	global_load_dwordx4 v[212:215], v[80:81], off offset:1024
	ds_read_b128 v[232:235], v245 offset:36864
	ds_read_b128 v[216:219], v244
	ds_read_b128 v[236:239], v245 offset:39168
	ds_read_b128 v[240:243], v245 offset:41472
	ds_read_b128 v[252:255], v245 offset:43776
	ds_read_b128 v[220:223], v244 offset:2304
	ds_read_b128 v[224:227], v244 offset:4608
	ds_read_b128 v[228:231], v244 offset:6912
	s_waitcnt lgkmcnt(6)
	v_mfma_f32_16x16x32_bf16 v[50:53], v[216:219], v[232:235], v[50:53]
	s_waitcnt lgkmcnt(5)
	v_mfma_f32_16x16x32_bf16 v[54:57], v[216:219], v[236:239], v[54:57]
	s_waitcnt lgkmcnt(4)
	v_mfma_f32_16x16x32_bf16 v[34:37], v[216:219], v[240:243], v[34:37]
	s_waitcnt lgkmcnt(3)
	v_mfma_f32_16x16x32_bf16 v[38:41], v[216:219], v[252:255], v[38:41]
	ds_read_b128 v[216:219], v244 offset:64
	s_waitcnt lgkmcnt(3)
	v_mfma_f32_16x16x32_bf16 v[58:61], v[220:223], v[232:235], v[58:61]
	v_mfma_f32_16x16x32_bf16 v[62:65], v[220:223], v[236:239], v[62:65]
	v_mfma_f32_16x16x32_bf16 v[42:45], v[220:223], v[240:243], v[42:45]
	v_mfma_f32_16x16x32_bf16 v[46:49], v[220:223], v[252:255], v[46:49]
	ds_read_b128 v[220:223], v244 offset:2368
	s_setprio 1
	s_waitcnt vmcnt(15)
	ds_write_b128 v164, v[122:125] offset:18432
	s_waitcnt vmcnt(14)
	ds_write_b128 v164, v[126:129] offset:23040
	s_waitcnt lgkmcnt(5)
	v_mfma_f32_16x16x32_bf16 v[18:21], v[224:227], v[232:235], v[18:21]
	v_mfma_f32_16x16x32_bf16 v[22:25], v[224:227], v[236:239], v[22:25]
	v_mfma_f32_16x16x32_bf16 v[2:5], v[224:227], v[240:243], v[2:5]
	v_mfma_f32_16x16x32_bf16 v[6:9], v[224:227], v[252:255], v[6:9]
	ds_read_b128 v[224:227], v244 offset:4672
	s_waitcnt vmcnt(13)
	ds_write_b128 v164, v[136:139] offset:27648
	s_waitcnt vmcnt(12)
	ds_write_b128 v164, v[140:143] offset:32256
	s_waitcnt lgkmcnt(7)
	v_mfma_f32_16x16x32_bf16 v[26:29], v[228:231], v[232:235], v[26:29]
	ds_read_b128 v[232:235], v245 offset:36928
	v_mfma_f32_16x16x32_bf16 v[30:33], v[228:231], v[236:239], v[30:33]
	ds_read_b128 v[236:239], v245 offset:39232
	v_mfma_f32_16x16x32_bf16 v[10:13], v[228:231], v[240:243], v[10:13]
	ds_read_b128 v[240:243], v245 offset:41536
	v_mfma_f32_16x16x32_bf16 v[14:17], v[228:231], v[252:255], v[14:17]
	ds_read_b128 v[252:255], v245 offset:43840
	ds_read_b128 v[228:231], v244 offset:6976
	s_waitcnt lgkmcnt(4)
	v_mfma_f32_16x16x32_bf16 v[50:53], v[216:219], v[232:235], v[50:53]
	s_waitcnt lgkmcnt(3)
	v_mfma_f32_16x16x32_bf16 v[54:57], v[216:219], v[236:239], v[54:57]
	s_waitcnt lgkmcnt(2)
	v_mfma_f32_16x16x32_bf16 v[34:37], v[216:219], v[240:243], v[34:37]
	s_waitcnt lgkmcnt(1)
	v_mfma_f32_16x16x32_bf16 v[38:41], v[216:219], v[252:255], v[38:41]
	s_waitcnt vmcnt(11)
	ds_write_b128 v164, v[144:147] offset:55296
	s_waitcnt vmcnt(10)
	ds_write_b128 v164, v[148:151] offset:59904
	v_mfma_f32_16x16x32_bf16 v[58:61], v[220:223], v[232:235], v[58:61]
	v_mfma_f32_16x16x32_bf16 v[62:65], v[220:223], v[236:239], v[62:65]
	v_mfma_f32_16x16x32_bf16 v[42:45], v[220:223], v[240:243], v[42:45]
	v_mfma_f32_16x16x32_bf16 v[46:49], v[220:223], v[252:255], v[46:49]
	s_waitcnt vmcnt(9)
	ds_write_b128 v164, v[172:175] offset:64512
	s_waitcnt vmcnt(8)
	ds_write_b128 v165, v[176:179] offset:32256
	v_mfma_f32_16x16x32_bf16 v[18:21], v[224:227], v[232:235], v[18:21]
	v_mfma_f32_16x16x32_bf16 v[22:25], v[224:227], v[236:239], v[22:25]
	v_mfma_f32_16x16x32_bf16 v[2:5], v[224:227], v[240:243], v[2:5]
	v_mfma_f32_16x16x32_bf16 v[6:9], v[224:227], v[252:255], v[6:9]
	s_waitcnt lgkmcnt(4)
	v_mfma_f32_16x16x32_bf16 v[26:29], v[228:231], v[232:235], v[26:29]
	v_mfma_f32_16x16x32_bf16 v[30:33], v[228:231], v[236:239], v[30:33]
	v_mfma_f32_16x16x32_bf16 v[10:13], v[228:231], v[240:243], v[10:13]
	v_mfma_f32_16x16x32_bf16 v[14:17], v[228:231], v[252:255], v[14:17]
	s_waitcnt lgkmcnt(0)
	s_barrier
	s_setprio 0
	global_load_dwordx4 v[122:125], v[72:73], off offset:1152
	global_load_dwordx4 v[126:129], v[74:75], off offset:1152
	global_load_dwordx4 v[136:139], v[76:77], off offset:1152
	global_load_dwordx4 v[140:143], v[78:79], off offset:1152
	global_load_dwordx4 v[144:147], v[70:71], off offset:1152
	global_load_dwordx4 v[148:151], v[68:69], off offset:1152
	global_load_dwordx4 v[172:175], v[66:67], off offset:1152
	global_load_dwordx4 v[176:179], v[80:81], off offset:1152
	ds_read_b128 v[232:235], v245 offset:55296
	ds_read_b128 v[216:219], v244 offset:18432
	ds_read_b128 v[236:239], v245 offset:57600
	ds_read_b128 v[240:243], v245 offset:59904
	ds_read_b128 v[252:255], v245 offset:62208
	ds_read_b128 v[220:223], v244 offset:20736
	ds_read_b128 v[224:227], v244 offset:23040
	ds_read_b128 v[228:231], v244 offset:25344
	s_waitcnt lgkmcnt(6)
	v_mfma_f32_16x16x32_bf16 v[50:53], v[216:219], v[232:235], v[50:53]
	s_waitcnt lgkmcnt(5)
	v_mfma_f32_16x16x32_bf16 v[54:57], v[216:219], v[236:239], v[54:57]
	s_waitcnt lgkmcnt(4)
	v_mfma_f32_16x16x32_bf16 v[34:37], v[216:219], v[240:243], v[34:37]
	s_waitcnt lgkmcnt(3)
	v_mfma_f32_16x16x32_bf16 v[38:41], v[216:219], v[252:255], v[38:41]
	ds_read_b128 v[216:219], v244 offset:18496
	s_waitcnt lgkmcnt(3)
	v_mfma_f32_16x16x32_bf16 v[58:61], v[220:223], v[232:235], v[58:61]
	v_mfma_f32_16x16x32_bf16 v[62:65], v[220:223], v[236:239], v[62:65]
	v_mfma_f32_16x16x32_bf16 v[42:45], v[220:223], v[240:243], v[42:45]
	v_mfma_f32_16x16x32_bf16 v[46:49], v[220:223], v[252:255], v[46:49]
	ds_read_b128 v[220:223], v244 offset:20800
	s_setprio 1
	s_waitcnt vmcnt(15)
	ds_write_b128 v164, v[180:183]
	s_waitcnt vmcnt(14)
	ds_write_b128 v164, v[188:191] offset:4608
	s_waitcnt lgkmcnt(5)
	v_mfma_f32_16x16x32_bf16 v[18:21], v[224:227], v[232:235], v[18:21]
	v_mfma_f32_16x16x32_bf16 v[22:25], v[224:227], v[236:239], v[22:25]
	v_mfma_f32_16x16x32_bf16 v[2:5], v[224:227], v[240:243], v[2:5]
	v_mfma_f32_16x16x32_bf16 v[6:9], v[224:227], v[252:255], v[6:9]
	ds_read_b128 v[224:227], v244 offset:23104
	s_waitcnt vmcnt(13)
	ds_write_b128 v164, v[192:195] offset:9216
	s_waitcnt vmcnt(12)
	ds_write_b128 v164, v[196:199] offset:13824
	s_waitcnt lgkmcnt(7)
	v_mfma_f32_16x16x32_bf16 v[26:29], v[228:231], v[232:235], v[26:29]
	ds_read_b128 v[232:235], v245 offset:55360
	v_mfma_f32_16x16x32_bf16 v[30:33], v[228:231], v[236:239], v[30:33]
	ds_read_b128 v[236:239], v245 offset:57664
	v_mfma_f32_16x16x32_bf16 v[10:13], v[228:231], v[240:243], v[10:13]
	ds_read_b128 v[240:243], v245 offset:59968
	v_mfma_f32_16x16x32_bf16 v[14:17], v[228:231], v[252:255], v[14:17]
	ds_read_b128 v[252:255], v245 offset:62272
	ds_read_b128 v[228:231], v244 offset:25408
	s_waitcnt lgkmcnt(4)
	v_mfma_f32_16x16x32_bf16 v[50:53], v[216:219], v[232:235], v[50:53]
	s_waitcnt lgkmcnt(3)
	v_mfma_f32_16x16x32_bf16 v[54:57], v[216:219], v[236:239], v[54:57]
	s_waitcnt lgkmcnt(2)
	v_mfma_f32_16x16x32_bf16 v[34:37], v[216:219], v[240:243], v[34:37]
	s_waitcnt lgkmcnt(1)
	v_mfma_f32_16x16x32_bf16 v[38:41], v[216:219], v[252:255], v[38:41]
	s_waitcnt vmcnt(11)
	ds_write_b128 v164, v[200:203] offset:36864
	s_waitcnt vmcnt(10)
	ds_write_b128 v164, v[204:207] offset:41472
	v_mfma_f32_16x16x32_bf16 v[58:61], v[220:223], v[232:235], v[58:61]
	v_mfma_f32_16x16x32_bf16 v[62:65], v[220:223], v[236:239], v[62:65]
	v_mfma_f32_16x16x32_bf16 v[42:45], v[220:223], v[240:243], v[42:45]
	v_mfma_f32_16x16x32_bf16 v[46:49], v[220:223], v[252:255], v[46:49]
	s_waitcnt vmcnt(9)
	ds_write_b128 v164, v[208:211] offset:46080
	s_waitcnt vmcnt(8)
	ds_write_b128 v164, v[212:215] offset:50688
	v_mfma_f32_16x16x32_bf16 v[18:21], v[224:227], v[232:235], v[18:21]
	v_mfma_f32_16x16x32_bf16 v[22:25], v[224:227], v[236:239], v[22:25]
	v_mfma_f32_16x16x32_bf16 v[2:5], v[224:227], v[240:243], v[2:5]
	v_mfma_f32_16x16x32_bf16 v[6:9], v[224:227], v[252:255], v[6:9]
	s_waitcnt lgkmcnt(4)
	v_mfma_f32_16x16x32_bf16 v[26:29], v[228:231], v[232:235], v[26:29]
	v_mfma_f32_16x16x32_bf16 v[30:33], v[228:231], v[236:239], v[30:33]
	v_mfma_f32_16x16x32_bf16 v[10:13], v[228:231], v[240:243], v[10:13]
	v_mfma_f32_16x16x32_bf16 v[14:17], v[228:231], v[252:255], v[14:17]
	s_waitcnt lgkmcnt(0)
	s_barrier
	s_setprio 0
	global_load_dwordx4 v[180:183], v[72:73], off offset:1280
	global_load_dwordx4 v[188:191], v[74:75], off offset:1280
	global_load_dwordx4 v[192:195], v[76:77], off offset:1280
	global_load_dwordx4 v[196:199], v[78:79], off offset:1280
	global_load_dwordx4 v[200:203], v[70:71], off offset:1280
	global_load_dwordx4 v[204:207], v[68:69], off offset:1280
	global_load_dwordx4 v[208:211], v[66:67], off offset:1280
	global_load_dwordx4 v[212:215], v[80:81], off offset:1280
	ds_read_b128 v[232:235], v245 offset:36864
	ds_read_b128 v[216:219], v244
	ds_read_b128 v[236:239], v245 offset:39168
	ds_read_b128 v[240:243], v245 offset:41472
	ds_read_b128 v[252:255], v245 offset:43776
	ds_read_b128 v[220:223], v244 offset:2304
	ds_read_b128 v[224:227], v244 offset:4608
	ds_read_b128 v[228:231], v244 offset:6912
	s_waitcnt lgkmcnt(6)
	v_mfma_f32_16x16x32_bf16 v[50:53], v[216:219], v[232:235], v[50:53]
	s_waitcnt lgkmcnt(5)
	v_mfma_f32_16x16x32_bf16 v[54:57], v[216:219], v[236:239], v[54:57]
	s_waitcnt lgkmcnt(4)
	v_mfma_f32_16x16x32_bf16 v[34:37], v[216:219], v[240:243], v[34:37]
	s_waitcnt lgkmcnt(3)
	v_mfma_f32_16x16x32_bf16 v[38:41], v[216:219], v[252:255], v[38:41]
	ds_read_b128 v[216:219], v244 offset:64
	s_waitcnt lgkmcnt(3)
	v_mfma_f32_16x16x32_bf16 v[58:61], v[220:223], v[232:235], v[58:61]
	v_mfma_f32_16x16x32_bf16 v[62:65], v[220:223], v[236:239], v[62:65]
	v_mfma_f32_16x16x32_bf16 v[42:45], v[220:223], v[240:243], v[42:45]
	v_mfma_f32_16x16x32_bf16 v[46:49], v[220:223], v[252:255], v[46:49]
	ds_read_b128 v[220:223], v244 offset:2368
	s_setprio 1
	s_waitcnt vmcnt(15)
	ds_write_b128 v164, v[122:125] offset:18432
	s_waitcnt vmcnt(14)
	ds_write_b128 v164, v[126:129] offset:23040
	s_waitcnt lgkmcnt(5)
	v_mfma_f32_16x16x32_bf16 v[18:21], v[224:227], v[232:235], v[18:21]
	v_mfma_f32_16x16x32_bf16 v[22:25], v[224:227], v[236:239], v[22:25]
	v_mfma_f32_16x16x32_bf16 v[2:5], v[224:227], v[240:243], v[2:5]
	v_mfma_f32_16x16x32_bf16 v[6:9], v[224:227], v[252:255], v[6:9]
	ds_read_b128 v[224:227], v244 offset:4672
	s_waitcnt vmcnt(13)
	ds_write_b128 v164, v[136:139] offset:27648
	s_waitcnt vmcnt(12)
	ds_write_b128 v164, v[140:143] offset:32256
	s_waitcnt lgkmcnt(7)
	v_mfma_f32_16x16x32_bf16 v[26:29], v[228:231], v[232:235], v[26:29]
	ds_read_b128 v[232:235], v245 offset:36928
	v_mfma_f32_16x16x32_bf16 v[30:33], v[228:231], v[236:239], v[30:33]
	ds_read_b128 v[236:239], v245 offset:39232
	v_mfma_f32_16x16x32_bf16 v[10:13], v[228:231], v[240:243], v[10:13]
	ds_read_b128 v[240:243], v245 offset:41536
	v_mfma_f32_16x16x32_bf16 v[14:17], v[228:231], v[252:255], v[14:17]
	ds_read_b128 v[252:255], v245 offset:43840
	ds_read_b128 v[228:231], v244 offset:6976
	s_waitcnt lgkmcnt(4)
	v_mfma_f32_16x16x32_bf16 v[50:53], v[216:219], v[232:235], v[50:53]
	s_waitcnt lgkmcnt(3)
	v_mfma_f32_16x16x32_bf16 v[54:57], v[216:219], v[236:239], v[54:57]
	s_waitcnt lgkmcnt(2)
	v_mfma_f32_16x16x32_bf16 v[34:37], v[216:219], v[240:243], v[34:37]
	s_waitcnt lgkmcnt(1)
	v_mfma_f32_16x16x32_bf16 v[38:41], v[216:219], v[252:255], v[38:41]
	s_waitcnt vmcnt(11)
	ds_write_b128 v164, v[144:147] offset:55296
	s_waitcnt vmcnt(10)
	ds_write_b128 v164, v[148:151] offset:59904
	v_mfma_f32_16x16x32_bf16 v[58:61], v[220:223], v[232:235], v[58:61]
	v_mfma_f32_16x16x32_bf16 v[62:65], v[220:223], v[236:239], v[62:65]
	v_mfma_f32_16x16x32_bf16 v[42:45], v[220:223], v[240:243], v[42:45]
	v_mfma_f32_16x16x32_bf16 v[46:49], v[220:223], v[252:255], v[46:49]
	s_waitcnt vmcnt(9)
	ds_write_b128 v164, v[172:175] offset:64512
	s_waitcnt vmcnt(8)
	ds_write_b128 v165, v[176:179] offset:32256
	v_mfma_f32_16x16x32_bf16 v[18:21], v[224:227], v[232:235], v[18:21]
	v_mfma_f32_16x16x32_bf16 v[22:25], v[224:227], v[236:239], v[22:25]
	v_mfma_f32_16x16x32_bf16 v[2:5], v[224:227], v[240:243], v[2:5]
	v_mfma_f32_16x16x32_bf16 v[6:9], v[224:227], v[252:255], v[6:9]
	s_waitcnt lgkmcnt(4)
	v_mfma_f32_16x16x32_bf16 v[26:29], v[228:231], v[232:235], v[26:29]
	v_mfma_f32_16x16x32_bf16 v[30:33], v[228:231], v[236:239], v[30:33]
	v_mfma_f32_16x16x32_bf16 v[10:13], v[228:231], v[240:243], v[10:13]
	v_mfma_f32_16x16x32_bf16 v[14:17], v[228:231], v[252:255], v[14:17]
	s_waitcnt lgkmcnt(0)
	s_barrier
	s_setprio 0
	global_load_dwordx4 v[122:125], v[72:73], off offset:1408
	global_load_dwordx4 v[126:129], v[74:75], off offset:1408
	global_load_dwordx4 v[136:139], v[76:77], off offset:1408
	global_load_dwordx4 v[140:143], v[78:79], off offset:1408
	global_load_dwordx4 v[144:147], v[70:71], off offset:1408
	global_load_dwordx4 v[148:151], v[68:69], off offset:1408
	global_load_dwordx4 v[172:175], v[66:67], off offset:1408
	global_load_dwordx4 v[176:179], v[80:81], off offset:1408
	ds_read_b128 v[232:235], v245 offset:55296
	ds_read_b128 v[216:219], v244 offset:18432
	ds_read_b128 v[236:239], v245 offset:57600
	ds_read_b128 v[240:243], v245 offset:59904
	ds_read_b128 v[252:255], v245 offset:62208
	ds_read_b128 v[220:223], v244 offset:20736
	ds_read_b128 v[224:227], v244 offset:23040
	ds_read_b128 v[228:231], v244 offset:25344
	s_waitcnt lgkmcnt(6)
	v_mfma_f32_16x16x32_bf16 v[50:53], v[216:219], v[232:235], v[50:53]
	s_waitcnt lgkmcnt(5)
	v_mfma_f32_16x16x32_bf16 v[54:57], v[216:219], v[236:239], v[54:57]
	s_waitcnt lgkmcnt(4)
	v_mfma_f32_16x16x32_bf16 v[34:37], v[216:219], v[240:243], v[34:37]
	s_waitcnt lgkmcnt(3)
	v_mfma_f32_16x16x32_bf16 v[38:41], v[216:219], v[252:255], v[38:41]
	ds_read_b128 v[216:219], v244 offset:18496
	s_waitcnt lgkmcnt(3)
	v_mfma_f32_16x16x32_bf16 v[58:61], v[220:223], v[232:235], v[58:61]
	v_mfma_f32_16x16x32_bf16 v[62:65], v[220:223], v[236:239], v[62:65]
	v_mfma_f32_16x16x32_bf16 v[42:45], v[220:223], v[240:243], v[42:45]
	v_mfma_f32_16x16x32_bf16 v[46:49], v[220:223], v[252:255], v[46:49]
	ds_read_b128 v[220:223], v244 offset:20800
	s_setprio 1
	s_waitcnt vmcnt(15)
	ds_write_b128 v164, v[180:183]
	s_waitcnt vmcnt(14)
	ds_write_b128 v164, v[188:191] offset:4608
	s_waitcnt lgkmcnt(5)
	v_mfma_f32_16x16x32_bf16 v[18:21], v[224:227], v[232:235], v[18:21]
	v_mfma_f32_16x16x32_bf16 v[22:25], v[224:227], v[236:239], v[22:25]
	v_mfma_f32_16x16x32_bf16 v[2:5], v[224:227], v[240:243], v[2:5]
	v_mfma_f32_16x16x32_bf16 v[6:9], v[224:227], v[252:255], v[6:9]
	ds_read_b128 v[224:227], v244 offset:23104
	s_waitcnt vmcnt(13)
	ds_write_b128 v164, v[192:195] offset:9216
	s_waitcnt vmcnt(12)
	ds_write_b128 v164, v[196:199] offset:13824
	s_waitcnt lgkmcnt(7)
	v_mfma_f32_16x16x32_bf16 v[26:29], v[228:231], v[232:235], v[26:29]
	ds_read_b128 v[232:235], v245 offset:55360
	v_mfma_f32_16x16x32_bf16 v[30:33], v[228:231], v[236:239], v[30:33]
	ds_read_b128 v[236:239], v245 offset:57664
	v_mfma_f32_16x16x32_bf16 v[10:13], v[228:231], v[240:243], v[10:13]
	ds_read_b128 v[240:243], v245 offset:59968
	v_mfma_f32_16x16x32_bf16 v[14:17], v[228:231], v[252:255], v[14:17]
	ds_read_b128 v[252:255], v245 offset:62272
	ds_read_b128 v[228:231], v244 offset:25408
	s_waitcnt lgkmcnt(4)
	v_mfma_f32_16x16x32_bf16 v[50:53], v[216:219], v[232:235], v[50:53]
	s_waitcnt lgkmcnt(3)
	v_mfma_f32_16x16x32_bf16 v[54:57], v[216:219], v[236:239], v[54:57]
	s_waitcnt lgkmcnt(2)
	v_mfma_f32_16x16x32_bf16 v[34:37], v[216:219], v[240:243], v[34:37]
	s_waitcnt lgkmcnt(1)
	v_mfma_f32_16x16x32_bf16 v[38:41], v[216:219], v[252:255], v[38:41]
	s_waitcnt vmcnt(11)
	ds_write_b128 v164, v[200:203] offset:36864
	s_waitcnt vmcnt(10)
	ds_write_b128 v164, v[204:207] offset:41472
	v_mfma_f32_16x16x32_bf16 v[58:61], v[220:223], v[232:235], v[58:61]
	v_mfma_f32_16x16x32_bf16 v[62:65], v[220:223], v[236:239], v[62:65]
	v_mfma_f32_16x16x32_bf16 v[42:45], v[220:223], v[240:243], v[42:45]
	v_mfma_f32_16x16x32_bf16 v[46:49], v[220:223], v[252:255], v[46:49]
	s_waitcnt vmcnt(9)
	ds_write_b128 v164, v[208:211] offset:46080
	s_waitcnt vmcnt(8)
	ds_write_b128 v164, v[212:215] offset:50688
	v_mfma_f32_16x16x32_bf16 v[18:21], v[224:227], v[232:235], v[18:21]
	v_mfma_f32_16x16x32_bf16 v[22:25], v[224:227], v[236:239], v[22:25]
	v_mfma_f32_16x16x32_bf16 v[2:5], v[224:227], v[240:243], v[2:5]
	v_mfma_f32_16x16x32_bf16 v[6:9], v[224:227], v[252:255], v[6:9]
	s_waitcnt lgkmcnt(4)
	v_mfma_f32_16x16x32_bf16 v[26:29], v[228:231], v[232:235], v[26:29]
	v_mfma_f32_16x16x32_bf16 v[30:33], v[228:231], v[236:239], v[30:33]
	v_mfma_f32_16x16x32_bf16 v[10:13], v[228:231], v[240:243], v[10:13]
	v_mfma_f32_16x16x32_bf16 v[14:17], v[228:231], v[252:255], v[14:17]
	s_waitcnt lgkmcnt(0)
	s_barrier
	s_setprio 0
	global_load_dwordx4 v[180:183], v[72:73], off offset:1536
	global_load_dwordx4 v[188:191], v[74:75], off offset:1536
	global_load_dwordx4 v[192:195], v[76:77], off offset:1536
	global_load_dwordx4 v[196:199], v[78:79], off offset:1536
	global_load_dwordx4 v[200:203], v[70:71], off offset:1536
	global_load_dwordx4 v[204:207], v[68:69], off offset:1536
	global_load_dwordx4 v[208:211], v[66:67], off offset:1536
	global_load_dwordx4 v[212:215], v[80:81], off offset:1536
	ds_read_b128 v[232:235], v245 offset:36864
	ds_read_b128 v[216:219], v244
	ds_read_b128 v[236:239], v245 offset:39168
	ds_read_b128 v[240:243], v245 offset:41472
	ds_read_b128 v[252:255], v245 offset:43776
	ds_read_b128 v[220:223], v244 offset:2304
	ds_read_b128 v[224:227], v244 offset:4608
	ds_read_b128 v[228:231], v244 offset:6912
	s_waitcnt lgkmcnt(6)
	v_mfma_f32_16x16x32_bf16 v[50:53], v[216:219], v[232:235], v[50:53]
	s_waitcnt lgkmcnt(5)
	v_mfma_f32_16x16x32_bf16 v[54:57], v[216:219], v[236:239], v[54:57]
	s_waitcnt lgkmcnt(4)
	v_mfma_f32_16x16x32_bf16 v[34:37], v[216:219], v[240:243], v[34:37]
	s_waitcnt lgkmcnt(3)
	v_mfma_f32_16x16x32_bf16 v[38:41], v[216:219], v[252:255], v[38:41]
	ds_read_b128 v[216:219], v244 offset:64
	s_waitcnt lgkmcnt(3)
	v_mfma_f32_16x16x32_bf16 v[58:61], v[220:223], v[232:235], v[58:61]
	v_mfma_f32_16x16x32_bf16 v[62:65], v[220:223], v[236:239], v[62:65]
	v_mfma_f32_16x16x32_bf16 v[42:45], v[220:223], v[240:243], v[42:45]
	v_mfma_f32_16x16x32_bf16 v[46:49], v[220:223], v[252:255], v[46:49]
	ds_read_b128 v[220:223], v244 offset:2368
	s_setprio 1
	s_waitcnt vmcnt(15)
	ds_write_b128 v164, v[122:125] offset:18432
	s_waitcnt vmcnt(14)
	ds_write_b128 v164, v[126:129] offset:23040
	s_waitcnt lgkmcnt(5)
	v_mfma_f32_16x16x32_bf16 v[18:21], v[224:227], v[232:235], v[18:21]
	v_mfma_f32_16x16x32_bf16 v[22:25], v[224:227], v[236:239], v[22:25]
	v_mfma_f32_16x16x32_bf16 v[2:5], v[224:227], v[240:243], v[2:5]
	v_mfma_f32_16x16x32_bf16 v[6:9], v[224:227], v[252:255], v[6:9]
	ds_read_b128 v[224:227], v244 offset:4672
	s_waitcnt vmcnt(13)
	ds_write_b128 v164, v[136:139] offset:27648
	s_waitcnt vmcnt(12)
	ds_write_b128 v164, v[140:143] offset:32256
	s_waitcnt lgkmcnt(7)
	v_mfma_f32_16x16x32_bf16 v[26:29], v[228:231], v[232:235], v[26:29]
	ds_read_b128 v[232:235], v245 offset:36928
	v_mfma_f32_16x16x32_bf16 v[30:33], v[228:231], v[236:239], v[30:33]
	ds_read_b128 v[236:239], v245 offset:39232
	v_mfma_f32_16x16x32_bf16 v[10:13], v[228:231], v[240:243], v[10:13]
	ds_read_b128 v[240:243], v245 offset:41536
	v_mfma_f32_16x16x32_bf16 v[14:17], v[228:231], v[252:255], v[14:17]
	ds_read_b128 v[252:255], v245 offset:43840
	ds_read_b128 v[228:231], v244 offset:6976
	s_waitcnt lgkmcnt(4)
	v_mfma_f32_16x16x32_bf16 v[50:53], v[216:219], v[232:235], v[50:53]
	s_waitcnt lgkmcnt(3)
	v_mfma_f32_16x16x32_bf16 v[54:57], v[216:219], v[236:239], v[54:57]
	s_waitcnt lgkmcnt(2)
	v_mfma_f32_16x16x32_bf16 v[34:37], v[216:219], v[240:243], v[34:37]
	s_waitcnt lgkmcnt(1)
	v_mfma_f32_16x16x32_bf16 v[38:41], v[216:219], v[252:255], v[38:41]
	s_waitcnt vmcnt(11)
	ds_write_b128 v164, v[144:147] offset:55296
	s_waitcnt vmcnt(10)
	ds_write_b128 v164, v[148:151] offset:59904
	v_mfma_f32_16x16x32_bf16 v[58:61], v[220:223], v[232:235], v[58:61]
	v_mfma_f32_16x16x32_bf16 v[62:65], v[220:223], v[236:239], v[62:65]
	v_mfma_f32_16x16x32_bf16 v[42:45], v[220:223], v[240:243], v[42:45]
	v_mfma_f32_16x16x32_bf16 v[46:49], v[220:223], v[252:255], v[46:49]
	s_waitcnt vmcnt(9)
	ds_write_b128 v164, v[172:175] offset:64512
	s_waitcnt vmcnt(8)
	ds_write_b128 v165, v[176:179] offset:32256
	v_mfma_f32_16x16x32_bf16 v[18:21], v[224:227], v[232:235], v[18:21]
	v_mfma_f32_16x16x32_bf16 v[22:25], v[224:227], v[236:239], v[22:25]
	v_mfma_f32_16x16x32_bf16 v[2:5], v[224:227], v[240:243], v[2:5]
	v_mfma_f32_16x16x32_bf16 v[6:9], v[224:227], v[252:255], v[6:9]
	s_waitcnt lgkmcnt(4)
	v_mfma_f32_16x16x32_bf16 v[26:29], v[228:231], v[232:235], v[26:29]
	v_mfma_f32_16x16x32_bf16 v[30:33], v[228:231], v[236:239], v[30:33]
	v_mfma_f32_16x16x32_bf16 v[10:13], v[228:231], v[240:243], v[10:13]
	v_mfma_f32_16x16x32_bf16 v[14:17], v[228:231], v[252:255], v[14:17]
	s_waitcnt lgkmcnt(0)
	s_barrier
	s_setprio 0
	global_load_dwordx4 v[122:125], v[72:73], off offset:1664
	global_load_dwordx4 v[126:129], v[74:75], off offset:1664
	global_load_dwordx4 v[136:139], v[76:77], off offset:1664
	global_load_dwordx4 v[140:143], v[78:79], off offset:1664
	global_load_dwordx4 v[144:147], v[70:71], off offset:1664
	global_load_dwordx4 v[148:151], v[68:69], off offset:1664
	global_load_dwordx4 v[172:175], v[66:67], off offset:1664
	global_load_dwordx4 v[176:179], v[80:81], off offset:1664
	ds_read_b128 v[232:235], v245 offset:55296
	ds_read_b128 v[216:219], v244 offset:18432
	ds_read_b128 v[236:239], v245 offset:57600
	ds_read_b128 v[240:243], v245 offset:59904
	ds_read_b128 v[252:255], v245 offset:62208
	ds_read_b128 v[220:223], v244 offset:20736
	ds_read_b128 v[224:227], v244 offset:23040
	ds_read_b128 v[228:231], v244 offset:25344
	s_waitcnt lgkmcnt(6)
	v_mfma_f32_16x16x32_bf16 v[50:53], v[216:219], v[232:235], v[50:53]
	s_waitcnt lgkmcnt(5)
	v_mfma_f32_16x16x32_bf16 v[54:57], v[216:219], v[236:239], v[54:57]
	s_waitcnt lgkmcnt(4)
	v_mfma_f32_16x16x32_bf16 v[34:37], v[216:219], v[240:243], v[34:37]
	s_waitcnt lgkmcnt(3)
	v_mfma_f32_16x16x32_bf16 v[38:41], v[216:219], v[252:255], v[38:41]
	ds_read_b128 v[216:219], v244 offset:18496
	s_waitcnt lgkmcnt(3)
	v_mfma_f32_16x16x32_bf16 v[58:61], v[220:223], v[232:235], v[58:61]
	v_mfma_f32_16x16x32_bf16 v[62:65], v[220:223], v[236:239], v[62:65]
	v_mfma_f32_16x16x32_bf16 v[42:45], v[220:223], v[240:243], v[42:45]
	v_mfma_f32_16x16x32_bf16 v[46:49], v[220:223], v[252:255], v[46:49]
	ds_read_b128 v[220:223], v244 offset:20800
	s_setprio 1
	s_waitcnt vmcnt(15)
	ds_write_b128 v164, v[180:183]
	s_waitcnt vmcnt(14)
	ds_write_b128 v164, v[188:191] offset:4608
	s_waitcnt lgkmcnt(5)
	v_mfma_f32_16x16x32_bf16 v[18:21], v[224:227], v[232:235], v[18:21]
	v_mfma_f32_16x16x32_bf16 v[22:25], v[224:227], v[236:239], v[22:25]
	v_mfma_f32_16x16x32_bf16 v[2:5], v[224:227], v[240:243], v[2:5]
	v_mfma_f32_16x16x32_bf16 v[6:9], v[224:227], v[252:255], v[6:9]
	ds_read_b128 v[224:227], v244 offset:23104
	s_waitcnt vmcnt(13)
	ds_write_b128 v164, v[192:195] offset:9216
	s_waitcnt vmcnt(12)
	ds_write_b128 v164, v[196:199] offset:13824
	s_waitcnt lgkmcnt(7)
	v_mfma_f32_16x16x32_bf16 v[26:29], v[228:231], v[232:235], v[26:29]
	ds_read_b128 v[232:235], v245 offset:55360
	v_mfma_f32_16x16x32_bf16 v[30:33], v[228:231], v[236:239], v[30:33]
	ds_read_b128 v[236:239], v245 offset:57664
	v_mfma_f32_16x16x32_bf16 v[10:13], v[228:231], v[240:243], v[10:13]
	ds_read_b128 v[240:243], v245 offset:59968
	v_mfma_f32_16x16x32_bf16 v[14:17], v[228:231], v[252:255], v[14:17]
	ds_read_b128 v[252:255], v245 offset:62272
	ds_read_b128 v[228:231], v244 offset:25408
	s_waitcnt lgkmcnt(4)
	v_mfma_f32_16x16x32_bf16 v[50:53], v[216:219], v[232:235], v[50:53]
	s_waitcnt lgkmcnt(3)
	v_mfma_f32_16x16x32_bf16 v[54:57], v[216:219], v[236:239], v[54:57]
	s_waitcnt lgkmcnt(2)
	v_mfma_f32_16x16x32_bf16 v[34:37], v[216:219], v[240:243], v[34:37]
	s_waitcnt lgkmcnt(1)
	v_mfma_f32_16x16x32_bf16 v[38:41], v[216:219], v[252:255], v[38:41]
	s_waitcnt vmcnt(11)
	ds_write_b128 v164, v[200:203] offset:36864
	s_waitcnt vmcnt(10)
	ds_write_b128 v164, v[204:207] offset:41472
	v_mfma_f32_16x16x32_bf16 v[58:61], v[220:223], v[232:235], v[58:61]
	v_mfma_f32_16x16x32_bf16 v[62:65], v[220:223], v[236:239], v[62:65]
	v_mfma_f32_16x16x32_bf16 v[42:45], v[220:223], v[240:243], v[42:45]
	v_mfma_f32_16x16x32_bf16 v[46:49], v[220:223], v[252:255], v[46:49]
	s_waitcnt vmcnt(9)
	ds_write_b128 v164, v[208:211] offset:46080
	s_waitcnt vmcnt(8)
	ds_write_b128 v164, v[212:215] offset:50688
	v_mfma_f32_16x16x32_bf16 v[18:21], v[224:227], v[232:235], v[18:21]
	v_mfma_f32_16x16x32_bf16 v[22:25], v[224:227], v[236:239], v[22:25]
	v_mfma_f32_16x16x32_bf16 v[2:5], v[224:227], v[240:243], v[2:5]
	v_mfma_f32_16x16x32_bf16 v[6:9], v[224:227], v[252:255], v[6:9]
	s_waitcnt lgkmcnt(4)
	v_mfma_f32_16x16x32_bf16 v[26:29], v[228:231], v[232:235], v[26:29]
	v_mfma_f32_16x16x32_bf16 v[30:33], v[228:231], v[236:239], v[30:33]
	v_mfma_f32_16x16x32_bf16 v[10:13], v[228:231], v[240:243], v[10:13]
	v_mfma_f32_16x16x32_bf16 v[14:17], v[228:231], v[252:255], v[14:17]
	s_waitcnt lgkmcnt(0)
	s_barrier
	s_setprio 0
	global_load_dwordx4 v[180:183], v[72:73], off offset:1792
	global_load_dwordx4 v[188:191], v[74:75], off offset:1792
	global_load_dwordx4 v[192:195], v[76:77], off offset:1792
	global_load_dwordx4 v[196:199], v[78:79], off offset:1792
	global_load_dwordx4 v[200:203], v[70:71], off offset:1792
	global_load_dwordx4 v[204:207], v[68:69], off offset:1792
	global_load_dwordx4 v[208:211], v[66:67], off offset:1792
	global_load_dwordx4 v[212:215], v[80:81], off offset:1792
	ds_read_b128 v[232:235], v245 offset:36864
	ds_read_b128 v[216:219], v244
	ds_read_b128 v[236:239], v245 offset:39168
	ds_read_b128 v[240:243], v245 offset:41472
	ds_read_b128 v[252:255], v245 offset:43776
	ds_read_b128 v[220:223], v244 offset:2304
	ds_read_b128 v[224:227], v244 offset:4608
	ds_read_b128 v[228:231], v244 offset:6912
	s_waitcnt lgkmcnt(6)
	v_mfma_f32_16x16x32_bf16 v[50:53], v[216:219], v[232:235], v[50:53]
	s_waitcnt lgkmcnt(5)
	v_mfma_f32_16x16x32_bf16 v[54:57], v[216:219], v[236:239], v[54:57]
	s_waitcnt lgkmcnt(4)
	v_mfma_f32_16x16x32_bf16 v[34:37], v[216:219], v[240:243], v[34:37]
	s_waitcnt lgkmcnt(3)
	v_mfma_f32_16x16x32_bf16 v[38:41], v[216:219], v[252:255], v[38:41]
	ds_read_b128 v[216:219], v244 offset:64
	s_waitcnt lgkmcnt(3)
	v_mfma_f32_16x16x32_bf16 v[58:61], v[220:223], v[232:235], v[58:61]
	v_mfma_f32_16x16x32_bf16 v[62:65], v[220:223], v[236:239], v[62:65]
	v_mfma_f32_16x16x32_bf16 v[42:45], v[220:223], v[240:243], v[42:45]
	v_mfma_f32_16x16x32_bf16 v[46:49], v[220:223], v[252:255], v[46:49]
	ds_read_b128 v[220:223], v244 offset:2368
	s_setprio 1
	s_waitcnt vmcnt(15)
	ds_write_b128 v164, v[122:125] offset:18432
	s_waitcnt vmcnt(14)
	ds_write_b128 v164, v[126:129] offset:23040
	s_waitcnt lgkmcnt(5)
	v_mfma_f32_16x16x32_bf16 v[18:21], v[224:227], v[232:235], v[18:21]
	v_mfma_f32_16x16x32_bf16 v[22:25], v[224:227], v[236:239], v[22:25]
	v_mfma_f32_16x16x32_bf16 v[2:5], v[224:227], v[240:243], v[2:5]
	v_mfma_f32_16x16x32_bf16 v[6:9], v[224:227], v[252:255], v[6:9]
	ds_read_b128 v[224:227], v244 offset:4672
	s_waitcnt vmcnt(13)
	ds_write_b128 v164, v[136:139] offset:27648
	s_waitcnt vmcnt(12)
	ds_write_b128 v164, v[140:143] offset:32256
	s_waitcnt lgkmcnt(7)
	v_mfma_f32_16x16x32_bf16 v[26:29], v[228:231], v[232:235], v[26:29]
	ds_read_b128 v[232:235], v245 offset:36928
	v_mfma_f32_16x16x32_bf16 v[30:33], v[228:231], v[236:239], v[30:33]
	ds_read_b128 v[236:239], v245 offset:39232
	v_mfma_f32_16x16x32_bf16 v[10:13], v[228:231], v[240:243], v[10:13]
	ds_read_b128 v[240:243], v245 offset:41536
	v_mfma_f32_16x16x32_bf16 v[14:17], v[228:231], v[252:255], v[14:17]
	ds_read_b128 v[252:255], v245 offset:43840
	ds_read_b128 v[228:231], v244 offset:6976
	s_waitcnt lgkmcnt(4)
	v_mfma_f32_16x16x32_bf16 v[50:53], v[216:219], v[232:235], v[50:53]
	s_waitcnt lgkmcnt(3)
	v_mfma_f32_16x16x32_bf16 v[54:57], v[216:219], v[236:239], v[54:57]
	s_waitcnt lgkmcnt(2)
	v_mfma_f32_16x16x32_bf16 v[34:37], v[216:219], v[240:243], v[34:37]
	s_waitcnt lgkmcnt(1)
	v_mfma_f32_16x16x32_bf16 v[38:41], v[216:219], v[252:255], v[38:41]
	s_waitcnt vmcnt(11)
	ds_write_b128 v164, v[144:147] offset:55296
	s_waitcnt vmcnt(10)
	ds_write_b128 v164, v[148:151] offset:59904
	v_mfma_f32_16x16x32_bf16 v[58:61], v[220:223], v[232:235], v[58:61]
	v_mfma_f32_16x16x32_bf16 v[62:65], v[220:223], v[236:239], v[62:65]
	v_mfma_f32_16x16x32_bf16 v[42:45], v[220:223], v[240:243], v[42:45]
	v_mfma_f32_16x16x32_bf16 v[46:49], v[220:223], v[252:255], v[46:49]
	s_waitcnt vmcnt(9)
	ds_write_b128 v164, v[172:175] offset:64512
	s_waitcnt vmcnt(8)
	ds_write_b128 v165, v[176:179] offset:32256
	v_mfma_f32_16x16x32_bf16 v[18:21], v[224:227], v[232:235], v[18:21]
	v_mfma_f32_16x16x32_bf16 v[22:25], v[224:227], v[236:239], v[22:25]
	v_mfma_f32_16x16x32_bf16 v[2:5], v[224:227], v[240:243], v[2:5]
	v_mfma_f32_16x16x32_bf16 v[6:9], v[224:227], v[252:255], v[6:9]
	s_waitcnt lgkmcnt(4)
	v_mfma_f32_16x16x32_bf16 v[26:29], v[228:231], v[232:235], v[26:29]
	v_mfma_f32_16x16x32_bf16 v[30:33], v[228:231], v[236:239], v[30:33]
	v_mfma_f32_16x16x32_bf16 v[10:13], v[228:231], v[240:243], v[10:13]
	v_mfma_f32_16x16x32_bf16 v[14:17], v[228:231], v[252:255], v[14:17]
	s_waitcnt lgkmcnt(0)
	s_barrier
	s_setprio 0
	global_load_dwordx4 v[122:125], v[72:73], off offset:1920
	s_nop 0
	global_load_dwordx4 v[72:75], v[74:75], off offset:1920
	s_nop 0
	global_load_dwordx4 v[126:129], v[76:77], off offset:1920
	s_nop 0
	global_load_dwordx4 v[76:79], v[78:79], off offset:1920
	s_nop 0
	global_load_dwordx4 v[136:139], v[70:71], off offset:1920
	s_nop 0
	global_load_dwordx4 v[68:71], v[68:69], off offset:1920
	s_nop 0
	global_load_dwordx4 v[140:143], v[66:67], off offset:1920
	global_load_dwordx4 v[144:147], v[80:81], off offset:1920
	ds_read_b128 v[232:235], v245 offset:55296
	ds_read_b128 v[216:219], v244 offset:18432
	ds_read_b128 v[236:239], v245 offset:57600
	ds_read_b128 v[240:243], v245 offset:59904
	ds_read_b128 v[252:255], v245 offset:62208
	ds_read_b128 v[220:223], v244 offset:20736
	ds_read_b128 v[224:227], v244 offset:23040
	ds_read_b128 v[228:231], v244 offset:25344
	s_waitcnt lgkmcnt(6)
	v_mfma_f32_16x16x32_bf16 v[50:53], v[216:219], v[232:235], v[50:53]
	s_waitcnt lgkmcnt(5)
	v_mfma_f32_16x16x32_bf16 v[54:57], v[216:219], v[236:239], v[54:57]
	s_waitcnt lgkmcnt(4)
	v_mfma_f32_16x16x32_bf16 v[34:37], v[216:219], v[240:243], v[34:37]
	s_waitcnt lgkmcnt(3)
	v_mfma_f32_16x16x32_bf16 v[38:41], v[216:219], v[252:255], v[38:41]
	ds_read_b128 v[216:219], v244 offset:18496
	s_waitcnt lgkmcnt(3)
	v_mfma_f32_16x16x32_bf16 v[58:61], v[220:223], v[232:235], v[58:61]
	v_mfma_f32_16x16x32_bf16 v[62:65], v[220:223], v[236:239], v[62:65]
	v_mfma_f32_16x16x32_bf16 v[42:45], v[220:223], v[240:243], v[42:45]
	v_mfma_f32_16x16x32_bf16 v[46:49], v[220:223], v[252:255], v[46:49]
	ds_read_b128 v[220:223], v244 offset:20800
	s_setprio 1
	s_waitcnt vmcnt(15)
	ds_write_b128 v164, v[180:183]
	s_waitcnt vmcnt(14)
	ds_write_b128 v164, v[188:191] offset:4608
	s_waitcnt lgkmcnt(5)
	v_mfma_f32_16x16x32_bf16 v[18:21], v[224:227], v[232:235], v[18:21]
	v_mfma_f32_16x16x32_bf16 v[22:25], v[224:227], v[236:239], v[22:25]
	v_mfma_f32_16x16x32_bf16 v[2:5], v[224:227], v[240:243], v[2:5]
	v_mfma_f32_16x16x32_bf16 v[6:9], v[224:227], v[252:255], v[6:9]
	ds_read_b128 v[224:227], v244 offset:23104
	s_waitcnt vmcnt(13)
	ds_write_b128 v164, v[192:195] offset:9216
	s_waitcnt vmcnt(12)
	ds_write_b128 v164, v[196:199] offset:13824
	s_waitcnt lgkmcnt(7)
	v_mfma_f32_16x16x32_bf16 v[26:29], v[228:231], v[232:235], v[26:29]
	ds_read_b128 v[232:235], v245 offset:55360
	v_mfma_f32_16x16x32_bf16 v[30:33], v[228:231], v[236:239], v[30:33]
	ds_read_b128 v[236:239], v245 offset:57664
	v_mfma_f32_16x16x32_bf16 v[10:13], v[228:231], v[240:243], v[10:13]
	ds_read_b128 v[240:243], v245 offset:59968
	v_mfma_f32_16x16x32_bf16 v[14:17], v[228:231], v[252:255], v[14:17]
	ds_read_b128 v[252:255], v245 offset:62272
	ds_read_b128 v[228:231], v244 offset:25408
	s_waitcnt lgkmcnt(4)
	v_mfma_f32_16x16x32_bf16 v[50:53], v[216:219], v[232:235], v[50:53]
	s_waitcnt lgkmcnt(3)
	v_mfma_f32_16x16x32_bf16 v[54:57], v[216:219], v[236:239], v[54:57]
	s_waitcnt lgkmcnt(2)
	v_mfma_f32_16x16x32_bf16 v[34:37], v[216:219], v[240:243], v[34:37]
	s_waitcnt lgkmcnt(1)
	v_mfma_f32_16x16x32_bf16 v[38:41], v[216:219], v[252:255], v[38:41]
	s_waitcnt vmcnt(11)
	ds_write_b128 v164, v[200:203] offset:36864
	s_waitcnt vmcnt(10)
	ds_write_b128 v164, v[204:207] offset:41472
	v_mfma_f32_16x16x32_bf16 v[58:61], v[220:223], v[232:235], v[58:61]
	v_mfma_f32_16x16x32_bf16 v[62:65], v[220:223], v[236:239], v[62:65]
	v_mfma_f32_16x16x32_bf16 v[42:45], v[220:223], v[240:243], v[42:45]
	v_mfma_f32_16x16x32_bf16 v[46:49], v[220:223], v[252:255], v[46:49]
	s_waitcnt vmcnt(9)
	ds_write_b128 v164, v[208:211] offset:46080
	s_waitcnt vmcnt(8)
	ds_write_b128 v164, v[212:215] offset:50688
	v_mfma_f32_16x16x32_bf16 v[18:21], v[224:227], v[232:235], v[18:21]
	v_mfma_f32_16x16x32_bf16 v[22:25], v[224:227], v[236:239], v[22:25]
	v_mfma_f32_16x16x32_bf16 v[2:5], v[224:227], v[240:243], v[2:5]
	v_mfma_f32_16x16x32_bf16 v[6:9], v[224:227], v[252:255], v[6:9]
	s_waitcnt lgkmcnt(4)
	v_mfma_f32_16x16x32_bf16 v[26:29], v[228:231], v[232:235], v[26:29]
	v_mfma_f32_16x16x32_bf16 v[30:33], v[228:231], v[236:239], v[30:33]
	v_mfma_f32_16x16x32_bf16 v[10:13], v[228:231], v[240:243], v[10:13]
	v_mfma_f32_16x16x32_bf16 v[14:17], v[228:231], v[252:255], v[14:17]
	s_waitcnt lgkmcnt(0)
	s_barrier
	s_setprio 0
	ds_read_b128 v[232:235], v245 offset:36864
	ds_read_b128 v[216:219], v244
	ds_read_b128 v[236:239], v245 offset:39168
	ds_read_b128 v[240:243], v245 offset:41472
	ds_read_b128 v[252:255], v245 offset:43776
	ds_read_b128 v[220:223], v244 offset:2304
	ds_read_b128 v[224:227], v244 offset:4608
	ds_read_b128 v[228:231], v244 offset:6912
	s_waitcnt lgkmcnt(6)
	v_mfma_f32_16x16x32_bf16 v[50:53], v[216:219], v[232:235], v[50:53]
	s_waitcnt lgkmcnt(5)
	v_mfma_f32_16x16x32_bf16 v[54:57], v[216:219], v[236:239], v[54:57]
	s_waitcnt lgkmcnt(4)
	v_mfma_f32_16x16x32_bf16 v[34:37], v[216:219], v[240:243], v[34:37]
	s_waitcnt lgkmcnt(3)
	v_mfma_f32_16x16x32_bf16 v[38:41], v[216:219], v[252:255], v[38:41]
	ds_read_b128 v[216:219], v244 offset:64
	s_waitcnt lgkmcnt(3)
	v_mfma_f32_16x16x32_bf16 v[58:61], v[220:223], v[232:235], v[58:61]
	v_mfma_f32_16x16x32_bf16 v[62:65], v[220:223], v[236:239], v[62:65]
	v_mfma_f32_16x16x32_bf16 v[42:45], v[220:223], v[240:243], v[42:45]
	v_mfma_f32_16x16x32_bf16 v[46:49], v[220:223], v[252:255], v[46:49]
	ds_read_b128 v[220:223], v244 offset:2368
	s_setprio 1
	s_waitcnt vmcnt(7)
	ds_write_b128 v164, v[122:125] offset:18432
	s_waitcnt vmcnt(6)
	ds_write_b128 v164, v[72:75] offset:23040
	s_waitcnt lgkmcnt(5)
	v_mfma_f32_16x16x32_bf16 v[18:21], v[224:227], v[232:235], v[18:21]
	v_mfma_f32_16x16x32_bf16 v[22:25], v[224:227], v[236:239], v[22:25]
	v_mfma_f32_16x16x32_bf16 v[2:5], v[224:227], v[240:243], v[2:5]
	v_mfma_f32_16x16x32_bf16 v[6:9], v[224:227], v[252:255], v[6:9]
	ds_read_b128 v[224:227], v244 offset:4672
	s_waitcnt vmcnt(5)
	ds_write_b128 v164, v[126:129] offset:27648
	s_waitcnt vmcnt(4)
	ds_write_b128 v164, v[76:79] offset:32256
	s_waitcnt lgkmcnt(7)
	v_mfma_f32_16x16x32_bf16 v[26:29], v[228:231], v[232:235], v[26:29]
	ds_read_b128 v[232:235], v245 offset:36928
	v_mfma_f32_16x16x32_bf16 v[30:33], v[228:231], v[236:239], v[30:33]
	ds_read_b128 v[236:239], v245 offset:39232
	v_mfma_f32_16x16x32_bf16 v[10:13], v[228:231], v[240:243], v[10:13]
	ds_read_b128 v[240:243], v245 offset:41536
	v_mfma_f32_16x16x32_bf16 v[14:17], v[228:231], v[252:255], v[14:17]
	ds_read_b128 v[252:255], v245 offset:43840
	ds_read_b128 v[228:231], v244 offset:6976
	s_waitcnt lgkmcnt(4)
	v_mfma_f32_16x16x32_bf16 v[50:53], v[216:219], v[232:235], v[50:53]
	s_waitcnt lgkmcnt(3)
	v_mfma_f32_16x16x32_bf16 v[54:57], v[216:219], v[236:239], v[54:57]
	s_waitcnt lgkmcnt(2)
	v_mfma_f32_16x16x32_bf16 v[34:37], v[216:219], v[240:243], v[34:37]
	s_waitcnt lgkmcnt(1)
	v_mfma_f32_16x16x32_bf16 v[38:41], v[216:219], v[252:255], v[38:41]
	s_waitcnt vmcnt(3)
	ds_write_b128 v164, v[136:139] offset:55296
	s_waitcnt vmcnt(2)
	ds_write_b128 v164, v[68:71] offset:59904
	v_mfma_f32_16x16x32_bf16 v[58:61], v[220:223], v[232:235], v[58:61]
	v_mfma_f32_16x16x32_bf16 v[62:65], v[220:223], v[236:239], v[62:65]
	v_mfma_f32_16x16x32_bf16 v[42:45], v[220:223], v[240:243], v[42:45]
	v_mfma_f32_16x16x32_bf16 v[46:49], v[220:223], v[252:255], v[46:49]
	s_waitcnt vmcnt(1)
	ds_write_b128 v164, v[140:143] offset:64512
	s_waitcnt vmcnt(0)
	ds_write_b128 v165, v[144:147] offset:32256
	v_mfma_f32_16x16x32_bf16 v[18:21], v[224:227], v[232:235], v[18:21]
	v_mfma_f32_16x16x32_bf16 v[22:25], v[224:227], v[236:239], v[22:25]
	v_mfma_f32_16x16x32_bf16 v[2:5], v[224:227], v[240:243], v[2:5]
	v_mfma_f32_16x16x32_bf16 v[6:9], v[224:227], v[252:255], v[6:9]
	s_waitcnt lgkmcnt(4)
	v_mfma_f32_16x16x32_bf16 v[26:29], v[228:231], v[232:235], v[26:29]
	v_mfma_f32_16x16x32_bf16 v[30:33], v[228:231], v[236:239], v[30:33]
	v_mfma_f32_16x16x32_bf16 v[10:13], v[228:231], v[240:243], v[10:13]
	v_mfma_f32_16x16x32_bf16 v[14:17], v[228:231], v[252:255], v[14:17]
	s_waitcnt lgkmcnt(0)
	s_barrier
	s_setprio 0
	ds_read_b128 v[232:235], v245 offset:55296
	ds_read_b128 v[216:219], v244 offset:18432
	ds_read_b128 v[236:239], v245 offset:57600
	ds_read_b128 v[240:243], v245 offset:59904
	ds_read_b128 v[252:255], v245 offset:62208
	ds_read_b128 v[220:223], v244 offset:20736
	ds_read_b128 v[224:227], v244 offset:23040
	ds_read_b128 v[228:231], v244 offset:25344
	s_waitcnt lgkmcnt(6)
	v_mfma_f32_16x16x32_bf16 v[50:53], v[216:219], v[232:235], v[50:53]
	s_waitcnt lgkmcnt(5)
	v_mfma_f32_16x16x32_bf16 v[54:57], v[216:219], v[236:239], v[54:57]
	s_waitcnt lgkmcnt(4)
	v_mfma_f32_16x16x32_bf16 v[34:37], v[216:219], v[240:243], v[34:37]
	s_waitcnt lgkmcnt(3)
	v_mfma_f32_16x16x32_bf16 v[38:41], v[216:219], v[252:255], v[38:41]
	ds_read_b128 v[216:219], v244 offset:18496
	s_waitcnt lgkmcnt(3)
	v_mfma_f32_16x16x32_bf16 v[58:61], v[220:223], v[232:235], v[58:61]
	v_mfma_f32_16x16x32_bf16 v[62:65], v[220:223], v[236:239], v[62:65]
	v_mfma_f32_16x16x32_bf16 v[42:45], v[220:223], v[240:243], v[42:45]
	v_mfma_f32_16x16x32_bf16 v[46:49], v[220:223], v[252:255], v[46:49]
	ds_read_b128 v[220:223], v244 offset:20800
	s_waitcnt lgkmcnt(3)
	v_mfma_f32_16x16x32_bf16 v[18:21], v[224:227], v[232:235], v[18:21]
	v_mfma_f32_16x16x32_bf16 v[22:25], v[224:227], v[236:239], v[22:25]
	v_mfma_f32_16x16x32_bf16 v[2:5], v[224:227], v[240:243], v[2:5]
	v_mfma_f32_16x16x32_bf16 v[6:9], v[224:227], v[252:255], v[6:9]
	ds_read_b128 v[224:227], v244 offset:23104
	s_waitcnt lgkmcnt(3)
	v_mfma_f32_16x16x32_bf16 v[26:29], v[228:231], v[232:235], v[26:29]
	ds_read_b128 v[232:235], v245 offset:55360
	v_mfma_f32_16x16x32_bf16 v[30:33], v[228:231], v[236:239], v[30:33]
	ds_read_b128 v[236:239], v245 offset:57664
	v_mfma_f32_16x16x32_bf16 v[10:13], v[228:231], v[240:243], v[10:13]
	ds_read_b128 v[240:243], v245 offset:59968
	v_mfma_f32_16x16x32_bf16 v[14:17], v[228:231], v[252:255], v[14:17]
	ds_read_b128 v[252:255], v245 offset:62272
	ds_read_b128 v[228:231], v244 offset:25408
	s_waitcnt lgkmcnt(4)
	v_mfma_f32_16x16x32_bf16 v[50:53], v[216:219], v[232:235], v[50:53]
	s_waitcnt lgkmcnt(3)
	v_mfma_f32_16x16x32_bf16 v[54:57], v[216:219], v[236:239], v[54:57]
	s_waitcnt lgkmcnt(2)
	v_mfma_f32_16x16x32_bf16 v[34:37], v[216:219], v[240:243], v[34:37]
	s_waitcnt lgkmcnt(1)
	v_mfma_f32_16x16x32_bf16 v[38:41], v[216:219], v[252:255], v[38:41]
	v_mfma_f32_16x16x32_bf16 v[58:61], v[220:223], v[232:235], v[58:61]
	v_mfma_f32_16x16x32_bf16 v[62:65], v[220:223], v[236:239], v[62:65]
	v_mfma_f32_16x16x32_bf16 v[42:45], v[220:223], v[240:243], v[42:45]
	v_mfma_f32_16x16x32_bf16 v[46:49], v[220:223], v[252:255], v[46:49]
	v_mfma_f32_16x16x32_bf16 v[18:21], v[224:227], v[232:235], v[18:21]
	v_mfma_f32_16x16x32_bf16 v[22:25], v[224:227], v[236:239], v[22:25]
	v_mfma_f32_16x16x32_bf16 v[2:5], v[224:227], v[240:243], v[2:5]
	v_mfma_f32_16x16x32_bf16 v[6:9], v[224:227], v[252:255], v[6:9]
	s_waitcnt lgkmcnt(0)
	v_mfma_f32_16x16x32_bf16 v[26:29], v[228:231], v[232:235], v[26:29]
	v_mfma_f32_16x16x32_bf16 v[30:33], v[228:231], v[236:239], v[30:33]
	v_mfma_f32_16x16x32_bf16 v[10:13], v[228:231], v[240:243], v[10:13]
	v_mfma_f32_16x16x32_bf16 v[14:17], v[228:231], v[252:255], v[14:17]
	s_mov_b64 s[2:3], 0
	s_waitcnt lgkmcnt(0)
	s_barrier
	s_nop 7
	v_permlane16_swap_b32_e32 v50, v54
	v_permlane16_swap_b32_e32 v51, v55
	v_permlane16_swap_b32_e32 v52, v56
	v_permlane16_swap_b32_e32 v53, v57
	v_permlane16_swap_b32_e32 v58, v62
	v_permlane16_swap_b32_e32 v59, v63
	v_permlane16_swap_b32_e32 v60, v64
	v_permlane16_swap_b32_e32 v61, v65
	v_permlane16_swap_b32_e32 v34, v38
	v_permlane16_swap_b32_e32 v35, v39
	v_permlane16_swap_b32_e32 v36, v40
	v_permlane16_swap_b32_e32 v37, v41
	v_permlane16_swap_b32_e32 v42, v46
	v_permlane16_swap_b32_e32 v43, v47
	v_permlane16_swap_b32_e32 v44, v48
	v_permlane16_swap_b32_e32 v45, v49
	v_permlane16_swap_b32_e32 v18, v22
	v_permlane16_swap_b32_e32 v19, v23
	v_permlane16_swap_b32_e32 v20, v24
	v_permlane16_swap_b32_e32 v21, v25
	v_permlane16_swap_b32_e32 v26, v30
	v_permlane16_swap_b32_e32 v27, v31
	v_permlane16_swap_b32_e32 v28, v32
	v_permlane16_swap_b32_e32 v29, v33
	v_permlane16_swap_b32_e32 v2, v6
	v_permlane16_swap_b32_e32 v3, v7
	v_permlane16_swap_b32_e32 v4, v8
	v_permlane16_swap_b32_e32 v5, v9
	v_permlane16_swap_b32_e32 v10, v14
	v_permlane16_swap_b32_e32 v11, v15
	v_permlane16_swap_b32_e32 v12, v16
	v_permlane16_swap_b32_e32 v13, v17
	v_permlane32_swap_b32_e32 v50, v54
	v_permlane32_swap_b32_e32 v51, v55
	v_permlane32_swap_b32_e32 v52, v56
	v_permlane32_swap_b32_e32 v53, v57
	v_permlane32_swap_b32_e32 v58, v62
	v_permlane32_swap_b32_e32 v59, v63
	v_permlane32_swap_b32_e32 v60, v64
	v_permlane32_swap_b32_e32 v61, v65
	v_permlane32_swap_b32_e32 v34, v38
	v_permlane32_swap_b32_e32 v35, v39
	v_permlane32_swap_b32_e32 v36, v40
	v_permlane32_swap_b32_e32 v37, v41
	v_permlane32_swap_b32_e32 v42, v46
	v_permlane32_swap_b32_e32 v43, v47
	v_permlane32_swap_b32_e32 v44, v48
	v_permlane32_swap_b32_e32 v45, v49
	v_permlane32_swap_b32_e32 v18, v22
	v_permlane32_swap_b32_e32 v19, v23
	v_permlane32_swap_b32_e32 v20, v24
	v_permlane32_swap_b32_e32 v21, v25
	v_permlane32_swap_b32_e32 v26, v30
	v_permlane32_swap_b32_e32 v27, v31
	v_permlane32_swap_b32_e32 v28, v32
	v_permlane32_swap_b32_e32 v29, v33
	v_permlane32_swap_b32_e32 v2, v6
	v_permlane32_swap_b32_e32 v3, v7
	v_permlane32_swap_b32_e32 v4, v8
	v_permlane32_swap_b32_e32 v5, v9
	v_permlane32_swap_b32_e32 v10, v14
	v_permlane32_swap_b32_e32 v11, v15
	v_permlane32_swap_b32_e32 v12, v16
	v_permlane32_swap_b32_e32 v13, v17

.LBB0_1167:
	v_ashrrev_i32_e32 v3, 31, v2
	v_lshlrev_b64 v[2:3], 11, v[2:3]
	v_ashrrev_i32_e32 v9, 31, v8
	v_lshl_add_u64 v[70:71], v[86:87], 0, v[2:3]
	v_lshlrev_b64 v[2:3], 11, v[8:9]
	v_lshl_add_u64 v[72:73], v[86:87], 0, v[2:3]
	v_or_b32_e32 v2, s56, v154
	v_ashrrev_i32_e32 v3, 31, v2
	v_lshlrev_b64 v[2:3], 11, v[2:3]
	v_lshl_add_u64 v[74:75], v[84:85], 0, v[2:3]
	v_add_u32_e32 v2, s56, v155
	v_ashrrev_i32_e32 v3, 31, v2
	v_lshlrev_b64 v[2:3], 11, v[2:3]
	v_lshl_add_u64 v[76:77], v[84:85], 0, v[2:3]
	v_add_u32_e32 v2, s56, v156
	v_ashrrev_i32_e32 v3, 31, v2
	v_lshlrev_b64 v[2:3], 11, v[2:3]
	v_lshl_add_u64 v[78:79], v[84:85], 0, v[2:3]
	v_add_u32_e32 v2, s56, v157
	v_ashrrev_i32_e32 v7, 31, v6
	v_ashrrev_i32_e32 v5, 31, v4
	v_ashrrev_i32_e32 v3, 31, v2
	v_lshlrev_b64 v[6:7], 11, v[6:7]
	v_lshlrev_b64 v[4:5], 11, v[4:5]
	v_lshlrev_b64 v[2:3], 11, v[2:3]
	v_lshl_add_u64 v[66:67], v[86:87], 0, v[6:7]
	v_lshl_add_u64 v[68:69], v[86:87], 0, v[4:5]
	v_lshl_add_u64 v[80:81], v[84:85], 0, v[2:3]
	global_load_dwordx4 v[2:5], v[70:71], off
	global_load_dwordx4 v[6:9], v[68:69], off
	global_load_dwordx4 v[10:13], v[66:67], off
	global_load_dwordx4 v[14:17], v[72:73], off
	global_load_dwordx4 v[18:21], v[74:75], off
	global_load_dwordx4 v[22:25], v[76:77], off
	global_load_dwordx4 v[26:29], v[78:79], off
	global_load_dwordx4 v[30:33], v[80:81], off
	global_load_dwordx4 v[122:125], v[70:71], off offset:128
	global_load_dwordx4 v[126:129], v[68:69], off offset:128
	global_load_dwordx4 v[136:139], v[66:67], off offset:128
	global_load_dwordx4 v[140:143], v[72:73], off offset:128
	global_load_dwordx4 v[144:147], v[74:75], off offset:128
	global_load_dwordx4 v[148:151], v[76:77], off offset:128
	global_load_dwordx4 v[172:175], v[78:79], off offset:128
	global_load_dwordx4 v[176:179], v[80:81], off offset:128
	s_setprio 1
	s_waitcnt vmcnt(15)
	ds_write_b128 v164, v[2:5]
	s_waitcnt vmcnt(14)
	ds_write_b128 v164, v[6:9] offset:4608
	s_waitcnt vmcnt(13)
	ds_write_b128 v164, v[10:13] offset:9216
	s_waitcnt vmcnt(12)
	ds_write_b128 v164, v[14:17] offset:13824
	s_waitcnt vmcnt(11)
	ds_write_b128 v164, v[18:21] offset:36864
	s_waitcnt vmcnt(10)
	ds_write_b128 v164, v[22:25] offset:41472
	s_waitcnt vmcnt(9)
	ds_write_b128 v164, v[26:29] offset:46080
	s_waitcnt vmcnt(8)
	ds_write_b128 v164, v[30:33] offset:50688
	s_waitcnt lgkmcnt(0)
	s_barrier
	s_setprio 0
	global_load_dwordx4 v[180:183], v[68:69], off offset:256
	global_load_dwordx4 v[188:191], v[66:67], off offset:256
	global_load_dwordx4 v[192:195], v[70:71], off offset:256
	global_load_dwordx4 v[196:199], v[72:73], off offset:256
	global_load_dwordx4 v[200:203], v[74:75], off offset:256
	global_load_dwordx4 v[204:207], v[76:77], off offset:256
	global_load_dwordx4 v[208:211], v[78:79], off offset:256
	global_load_dwordx4 v[212:215], v[80:81], off offset:256
	v_and_b32_e32 v246, 15, v1
	v_add_u32_e32 v246, 4, v246
	v_bfe_u32 v246, v246, 3, 1
	v_bfe_u32 v249, v1, 4, 2
	v_xor_b32_e32 v246, v246, v249
	v_bfe_u32 v249, v1, 5, 1
	v_sub_u32_e32 v246, v246, v249
	v_lshlrev_b32_e32 v246, 4, v246
	v_bfe_u32 v249, v1, 4, 1
	v_mul_u32_u24_e32 v249, 0x900, v249
	v_sub_u32_e32 v246, v246, v249
	v_add_u32_e32 v244, v246, v161
	v_add_u32_e32 v245, v246, v163
	ds_read_b128 v[232:235], v245 offset:36864
	ds_read_b128 v[216:219], v244
	ds_read_b128 v[236:239], v245 offset:39168
	ds_read_b128 v[240:243], v245 offset:41472
	ds_read_b128 v[252:255], v245 offset:43776
	ds_read_b128 v[220:223], v244 offset:2304
	ds_read_b128 v[224:227], v244 offset:4608
	ds_read_b128 v[228:231], v244 offset:6912
	s_waitcnt lgkmcnt(6)
	v_mfma_f32_16x16x32_bf16 v[50:53], v[216:219], v[232:235], 0
	s_waitcnt lgkmcnt(5)
	v_mfma_f32_16x16x32_bf16 v[54:57], v[216:219], v[236:239], 0
	s_waitcnt lgkmcnt(4)
	v_mfma_f32_16x16x32_bf16 v[34:37], v[216:219], v[240:243], 0
	s_waitcnt lgkmcnt(3)
	v_mfma_f32_16x16x32_bf16 v[38:41], v[216:219], v[252:255], 0
	ds_read_b128 v[216:219], v244 offset:64
	s_waitcnt lgkmcnt(3)
	v_mfma_f32_16x16x32_bf16 v[58:61], v[220:223], v[232:235], 0
	v_mfma_f32_16x16x32_bf16 v[62:65], v[220:223], v[236:239], 0
	v_mfma_f32_16x16x32_bf16 v[42:45], v[220:223], v[240:243], 0
	v_mfma_f32_16x16x32_bf16 v[46:49], v[220:223], v[252:255], 0
	ds_read_b128 v[220:223], v244 offset:2368
	s_setprio 1
	s_waitcnt vmcnt(15)
	ds_write_b128 v164, v[122:125] offset:18432
	s_waitcnt vmcnt(14)
	ds_write_b128 v164, v[126:129] offset:23040
	s_waitcnt lgkmcnt(5)
	v_mfma_f32_16x16x32_bf16 v[18:21], v[224:227], v[232:235], 0
	v_mfma_f32_16x16x32_bf16 v[22:25], v[224:227], v[236:239], 0
	v_mfma_f32_16x16x32_bf16 v[2:5], v[224:227], v[240:243], 0
	v_mfma_f32_16x16x32_bf16 v[6:9], v[224:227], v[252:255], 0
	ds_read_b128 v[224:227], v244 offset:4672
	s_waitcnt vmcnt(13)
	ds_write_b128 v164, v[136:139] offset:27648
	s_waitcnt vmcnt(12)
	ds_write_b128 v164, v[140:143] offset:32256
	s_waitcnt lgkmcnt(7)
	v_mfma_f32_16x16x32_bf16 v[26:29], v[228:231], v[232:235], 0
	ds_read_b128 v[232:235], v245 offset:36928
	v_mfma_f32_16x16x32_bf16 v[30:33], v[228:231], v[236:239], 0
	ds_read_b128 v[236:239], v245 offset:39232
	v_mfma_f32_16x16x32_bf16 v[10:13], v[228:231], v[240:243], 0
	ds_read_b128 v[240:243], v245 offset:41536
	v_mfma_f32_16x16x32_bf16 v[14:17], v[228:231], v[252:255], 0
	ds_read_b128 v[252:255], v245 offset:43840
	ds_read_b128 v[228:231], v244 offset:6976
	s_waitcnt lgkmcnt(4)
	v_mfma_f32_16x16x32_bf16 v[50:53], v[216:219], v[232:235], v[50:53]
	s_waitcnt lgkmcnt(3)
	v_mfma_f32_16x16x32_bf16 v[54:57], v[216:219], v[236:239], v[54:57]
	s_waitcnt lgkmcnt(2)
	v_mfma_f32_16x16x32_bf16 v[34:37], v[216:219], v[240:243], v[34:37]
	s_waitcnt lgkmcnt(1)
	v_mfma_f32_16x16x32_bf16 v[38:41], v[216:219], v[252:255], v[38:41]
	s_waitcnt vmcnt(11)
	ds_write_b128 v164, v[144:147] offset:55296
	s_waitcnt vmcnt(10)
	ds_write_b128 v164, v[148:151] offset:59904
	v_mfma_f32_16x16x32_bf16 v[58:61], v[220:223], v[232:235], v[58:61]
	v_mfma_f32_16x16x32_bf16 v[62:65], v[220:223], v[236:239], v[62:65]
	v_mfma_f32_16x16x32_bf16 v[42:45], v[220:223], v[240:243], v[42:45]
	v_mfma_f32_16x16x32_bf16 v[46:49], v[220:223], v[252:255], v[46:49]
	s_waitcnt vmcnt(9)
	ds_write_b128 v164, v[172:175] offset:64512
	s_waitcnt vmcnt(8)
	ds_write_b128 v165, v[176:179] offset:32256
	v_mfma_f32_16x16x32_bf16 v[18:21], v[224:227], v[232:235], v[18:21]
	v_mfma_f32_16x16x32_bf16 v[22:25], v[224:227], v[236:239], v[22:25]
	v_mfma_f32_16x16x32_bf16 v[2:5], v[224:227], v[240:243], v[2:5]
	v_mfma_f32_16x16x32_bf16 v[6:9], v[224:227], v[252:255], v[6:9]
	s_waitcnt lgkmcnt(4)
	v_mfma_f32_16x16x32_bf16 v[26:29], v[228:231], v[232:235], v[26:29]
	v_mfma_f32_16x16x32_bf16 v[30:33], v[228:231], v[236:239], v[30:33]
	v_mfma_f32_16x16x32_bf16 v[10:13], v[228:231], v[240:243], v[10:13]
	v_mfma_f32_16x16x32_bf16 v[14:17], v[228:231], v[252:255], v[14:17]
	s_waitcnt lgkmcnt(0)
	s_barrier
	s_setprio 0
	global_load_dwordx4 v[122:125], v[70:71], off offset:384
	global_load_dwordx4 v[126:129], v[68:69], off offset:384
	global_load_dwordx4 v[136:139], v[66:67], off offset:384
	global_load_dwordx4 v[140:143], v[72:73], off offset:384
	global_load_dwordx4 v[144:147], v[74:75], off offset:384
	global_load_dwordx4 v[148:151], v[76:77], off offset:384
	global_load_dwordx4 v[172:175], v[78:79], off offset:384
	global_load_dwordx4 v[176:179], v[80:81], off offset:384
	ds_read_b128 v[232:235], v245 offset:55296
	ds_read_b128 v[216:219], v244 offset:18432
	ds_read_b128 v[236:239], v245 offset:57600
	ds_read_b128 v[240:243], v245 offset:59904
	ds_read_b128 v[252:255], v245 offset:62208
	ds_read_b128 v[220:223], v244 offset:20736
	ds_read_b128 v[224:227], v244 offset:23040
	ds_read_b128 v[228:231], v244 offset:25344
	s_waitcnt lgkmcnt(6)
	v_mfma_f32_16x16x32_bf16 v[50:53], v[216:219], v[232:235], v[50:53]
	s_waitcnt lgkmcnt(5)
	v_mfma_f32_16x16x32_bf16 v[54:57], v[216:219], v[236:239], v[54:57]
	s_waitcnt lgkmcnt(4)
	v_mfma_f32_16x16x32_bf16 v[34:37], v[216:219], v[240:243], v[34:37]
	s_waitcnt lgkmcnt(3)
	v_mfma_f32_16x16x32_bf16 v[38:41], v[216:219], v[252:255], v[38:41]
	ds_read_b128 v[216:219], v244 offset:18496
	s_waitcnt lgkmcnt(3)
	v_mfma_f32_16x16x32_bf16 v[58:61], v[220:223], v[232:235], v[58:61]
	v_mfma_f32_16x16x32_bf16 v[62:65], v[220:223], v[236:239], v[62:65]
	v_mfma_f32_16x16x32_bf16 v[42:45], v[220:223], v[240:243], v[42:45]
	v_mfma_f32_16x16x32_bf16 v[46:49], v[220:223], v[252:255], v[46:49]
	ds_read_b128 v[220:223], v244 offset:20800
	s_setprio 1
	s_waitcnt vmcnt(13)
	ds_write_b128 v164, v[192:195]
	ds_write_b128 v164, v[180:183] offset:4608
	s_waitcnt lgkmcnt(5)
	v_mfma_f32_16x16x32_bf16 v[18:21], v[224:227], v[232:235], v[18:21]
	v_mfma_f32_16x16x32_bf16 v[22:25], v[224:227], v[236:239], v[22:25]
	v_mfma_f32_16x16x32_bf16 v[2:5], v[224:227], v[240:243], v[2:5]
	v_mfma_f32_16x16x32_bf16 v[6:9], v[224:227], v[252:255], v[6:9]
	ds_read_b128 v[224:227], v244 offset:23104
	ds_write_b128 v164, v[188:191] offset:9216
	s_waitcnt vmcnt(12)
	ds_write_b128 v164, v[196:199] offset:13824
	s_waitcnt lgkmcnt(7)
	v_mfma_f32_16x16x32_bf16 v[26:29], v[228:231], v[232:235], v[26:29]
	ds_read_b128 v[232:235], v245 offset:55360
	v_mfma_f32_16x16x32_bf16 v[30:33], v[228:231], v[236:239], v[30:33]
	ds_read_b128 v[236:239], v245 offset:57664
	v_mfma_f32_16x16x32_bf16 v[10:13], v[228:231], v[240:243], v[10:13]
	ds_read_b128 v[240:243], v245 offset:59968
	v_mfma_f32_16x16x32_bf16 v[14:17], v[228:231], v[252:255], v[14:17]
	ds_read_b128 v[252:255], v245 offset:62272
	ds_read_b128 v[228:231], v244 offset:25408
	s_waitcnt lgkmcnt(4)
	v_mfma_f32_16x16x32_bf16 v[50:53], v[216:219], v[232:235], v[50:53]
	s_waitcnt lgkmcnt(3)
	v_mfma_f32_16x16x32_bf16 v[54:57], v[216:219], v[236:239], v[54:57]
	s_waitcnt lgkmcnt(2)
	v_mfma_f32_16x16x32_bf16 v[34:37], v[216:219], v[240:243], v[34:37]
	s_waitcnt lgkmcnt(1)
	v_mfma_f32_16x16x32_bf16 v[38:41], v[216:219], v[252:255], v[38:41]
	s_waitcnt vmcnt(11)
	ds_write_b128 v164, v[200:203] offset:36864
	s_waitcnt vmcnt(10)
	ds_write_b128 v164, v[204:207] offset:41472
	v_mfma_f32_16x16x32_bf16 v[58:61], v[220:223], v[232:235], v[58:61]
	v_mfma_f32_16x16x32_bf16 v[62:65], v[220:223], v[236:239], v[62:65]
	v_mfma_f32_16x16x32_bf16 v[42:45], v[220:223], v[240:243], v[42:45]
	v_mfma_f32_16x16x32_bf16 v[46:49], v[220:223], v[252:255], v[46:49]
	s_waitcnt vmcnt(9)
	ds_write_b128 v164, v[208:211] offset:46080
	s_waitcnt vmcnt(8)
	ds_write_b128 v164, v[212:215] offset:50688
	v_mfma_f32_16x16x32_bf16 v[18:21], v[224:227], v[232:235], v[18:21]
	v_mfma_f32_16x16x32_bf16 v[22:25], v[224:227], v[236:239], v[22:25]
	v_mfma_f32_16x16x32_bf16 v[2:5], v[224:227], v[240:243], v[2:5]
	v_mfma_f32_16x16x32_bf16 v[6:9], v[224:227], v[252:255], v[6:9]
	s_waitcnt lgkmcnt(4)
	v_mfma_f32_16x16x32_bf16 v[26:29], v[228:231], v[232:235], v[26:29]
	v_mfma_f32_16x16x32_bf16 v[30:33], v[228:231], v[236:239], v[30:33]
	v_mfma_f32_16x16x32_bf16 v[10:13], v[228:231], v[240:243], v[10:13]
	v_mfma_f32_16x16x32_bf16 v[14:17], v[228:231], v[252:255], v[14:17]
	s_waitcnt lgkmcnt(0)
	s_barrier
	s_setprio 0
	global_load_dwordx4 v[180:183], v[70:71], off offset:512
	global_load_dwordx4 v[188:191], v[68:69], off offset:512
	global_load_dwordx4 v[192:195], v[66:67], off offset:512
	global_load_dwordx4 v[196:199], v[72:73], off offset:512
	global_load_dwordx4 v[200:203], v[74:75], off offset:512
	global_load_dwordx4 v[204:207], v[76:77], off offset:512
	global_load_dwordx4 v[208:211], v[78:79], off offset:512
	global_load_dwordx4 v[212:215], v[80:81], off offset:512
	ds_read_b128 v[232:235], v245 offset:36864
	ds_read_b128 v[216:219], v244
	ds_read_b128 v[236:239], v245 offset:39168
	ds_read_b128 v[240:243], v245 offset:41472
	ds_read_b128 v[252:255], v245 offset:43776
	ds_read_b128 v[220:223], v244 offset:2304
	ds_read_b128 v[224:227], v244 offset:4608
	ds_read_b128 v[228:231], v244 offset:6912
	s_waitcnt lgkmcnt(6)
	v_mfma_f32_16x16x32_bf16 v[50:53], v[216:219], v[232:235], v[50:53]
	s_waitcnt lgkmcnt(5)
	v_mfma_f32_16x16x32_bf16 v[54:57], v[216:219], v[236:239], v[54:57]
	s_waitcnt lgkmcnt(4)
	v_mfma_f32_16x16x32_bf16 v[34:37], v[216:219], v[240:243], v[34:37]
	s_waitcnt lgkmcnt(3)
	v_mfma_f32_16x16x32_bf16 v[38:41], v[216:219], v[252:255], v[38:41]
	ds_read_b128 v[216:219], v244 offset:64
	s_waitcnt lgkmcnt(3)
	v_mfma_f32_16x16x32_bf16 v[58:61], v[220:223], v[232:235], v[58:61]
	v_mfma_f32_16x16x32_bf16 v[62:65], v[220:223], v[236:239], v[62:65]
	v_mfma_f32_16x16x32_bf16 v[42:45], v[220:223], v[240:243], v[42:45]
	v_mfma_f32_16x16x32_bf16 v[46:49], v[220:223], v[252:255], v[46:49]
	ds_read_b128 v[220:223], v244 offset:2368
	s_setprio 1
	s_waitcnt vmcnt(15)
	ds_write_b128 v164, v[122:125] offset:18432
	s_waitcnt vmcnt(14)
	ds_write_b128 v164, v[126:129] offset:23040
	s_waitcnt lgkmcnt(5)
	v_mfma_f32_16x16x32_bf16 v[18:21], v[224:227], v[232:235], v[18:21]
	v_mfma_f32_16x16x32_bf16 v[22:25], v[224:227], v[236:239], v[22:25]
	v_mfma_f32_16x16x32_bf16 v[2:5], v[224:227], v[240:243], v[2:5]
	v_mfma_f32_16x16x32_bf16 v[6:9], v[224:227], v[252:255], v[6:9]
	ds_read_b128 v[224:227], v244 offset:4672
	s_waitcnt vmcnt(13)
	ds_write_b128 v164, v[136:139] offset:27648
	s_waitcnt vmcnt(12)
	ds_write_b128 v164, v[140:143] offset:32256
	s_waitcnt lgkmcnt(7)
	v_mfma_f32_16x16x32_bf16 v[26:29], v[228:231], v[232:235], v[26:29]
	ds_read_b128 v[232:235], v245 offset:36928
	v_mfma_f32_16x16x32_bf16 v[30:33], v[228:231], v[236:239], v[30:33]
	ds_read_b128 v[236:239], v245 offset:39232
	v_mfma_f32_16x16x32_bf16 v[10:13], v[228:231], v[240:243], v[10:13]
	ds_read_b128 v[240:243], v245 offset:41536
	v_mfma_f32_16x16x32_bf16 v[14:17], v[228:231], v[252:255], v[14:17]
	ds_read_b128 v[252:255], v245 offset:43840
	ds_read_b128 v[228:231], v244 offset:6976
	s_waitcnt lgkmcnt(4)
	v_mfma_f32_16x16x32_bf16 v[50:53], v[216:219], v[232:235], v[50:53]
	s_waitcnt lgkmcnt(3)
	v_mfma_f32_16x16x32_bf16 v[54:57], v[216:219], v[236:239], v[54:57]
	s_waitcnt lgkmcnt(2)
	v_mfma_f32_16x16x32_bf16 v[34:37], v[216:219], v[240:243], v[34:37]
	s_waitcnt lgkmcnt(1)
	v_mfma_f32_16x16x32_bf16 v[38:41], v[216:219], v[252:255], v[38:41]
	s_waitcnt vmcnt(11)
	ds_write_b128 v164, v[144:147] offset:55296
	s_waitcnt vmcnt(10)
	ds_write_b128 v164, v[148:151] offset:59904
	v_mfma_f32_16x16x32_bf16 v[58:61], v[220:223], v[232:235], v[58:61]
	v_mfma_f32_16x16x32_bf16 v[62:65], v[220:223], v[236:239], v[62:65]
	v_mfma_f32_16x16x32_bf16 v[42:45], v[220:223], v[240:243], v[42:45]
	v_mfma_f32_16x16x32_bf16 v[46:49], v[220:223], v[252:255], v[46:49]
	s_waitcnt vmcnt(9)
	ds_write_b128 v164, v[172:175] offset:64512
	s_waitcnt vmcnt(8)
	ds_write_b128 v165, v[176:179] offset:32256
	v_mfma_f32_16x16x32_bf16 v[18:21], v[224:227], v[232:235], v[18:21]
	v_mfma_f32_16x16x32_bf16 v[22:25], v[224:227], v[236:239], v[22:25]
	v_mfma_f32_16x16x32_bf16 v[2:5], v[224:227], v[240:243], v[2:5]
	v_mfma_f32_16x16x32_bf16 v[6:9], v[224:227], v[252:255], v[6:9]
	s_waitcnt lgkmcnt(4)
	v_mfma_f32_16x16x32_bf16 v[26:29], v[228:231], v[232:235], v[26:29]
	v_mfma_f32_16x16x32_bf16 v[30:33], v[228:231], v[236:239], v[30:33]
	v_mfma_f32_16x16x32_bf16 v[10:13], v[228:231], v[240:243], v[10:13]
	v_mfma_f32_16x16x32_bf16 v[14:17], v[228:231], v[252:255], v[14:17]
	s_waitcnt lgkmcnt(0)
	s_barrier
	s_setprio 0
	global_load_dwordx4 v[122:125], v[70:71], off offset:640
	global_load_dwordx4 v[126:129], v[68:69], off offset:640
	global_load_dwordx4 v[136:139], v[66:67], off offset:640
	global_load_dwordx4 v[140:143], v[72:73], off offset:640
	global_load_dwordx4 v[144:147], v[74:75], off offset:640
	global_load_dwordx4 v[148:151], v[76:77], off offset:640
	global_load_dwordx4 v[172:175], v[78:79], off offset:640
	global_load_dwordx4 v[176:179], v[80:81], off offset:640
	ds_read_b128 v[232:235], v245 offset:55296
	ds_read_b128 v[216:219], v244 offset:18432
	ds_read_b128 v[236:239], v245 offset:57600
	ds_read_b128 v[240:243], v245 offset:59904
	ds_read_b128 v[252:255], v245 offset:62208
	ds_read_b128 v[220:223], v244 offset:20736
	ds_read_b128 v[224:227], v244 offset:23040
	ds_read_b128 v[228:231], v244 offset:25344
	s_waitcnt lgkmcnt(6)
	v_mfma_f32_16x16x32_bf16 v[50:53], v[216:219], v[232:235], v[50:53]
	s_waitcnt lgkmcnt(5)
	v_mfma_f32_16x16x32_bf16 v[54:57], v[216:219], v[236:239], v[54:57]
	s_waitcnt lgkmcnt(4)
	v_mfma_f32_16x16x32_bf16 v[34:37], v[216:219], v[240:243], v[34:37]
	s_waitcnt lgkmcnt(3)
	v_mfma_f32_16x16x32_bf16 v[38:41], v[216:219], v[252:255], v[38:41]
	ds_read_b128 v[216:219], v244 offset:18496
	s_waitcnt lgkmcnt(3)
	v_mfma_f32_16x16x32_bf16 v[58:61], v[220:223], v[232:235], v[58:61]
	v_mfma_f32_16x16x32_bf16 v[62:65], v[220:223], v[236:239], v[62:65]
	v_mfma_f32_16x16x32_bf16 v[42:45], v[220:223], v[240:243], v[42:45]
	v_mfma_f32_16x16x32_bf16 v[46:49], v[220:223], v[252:255], v[46:49]
	ds_read_b128 v[220:223], v244 offset:20800
	s_setprio 1
	s_waitcnt vmcnt(15)
	ds_write_b128 v164, v[180:183]
	s_waitcnt vmcnt(14)
	ds_write_b128 v164, v[188:191] offset:4608
	s_waitcnt lgkmcnt(5)
	v_mfma_f32_16x16x32_bf16 v[18:21], v[224:227], v[232:235], v[18:21]
	v_mfma_f32_16x16x32_bf16 v[22:25], v[224:227], v[236:239], v[22:25]
	v_mfma_f32_16x16x32_bf16 v[2:5], v[224:227], v[240:243], v[2:5]
	v_mfma_f32_16x16x32_bf16 v[6:9], v[224:227], v[252:255], v[6:9]
	ds_read_b128 v[224:227], v244 offset:23104
	s_waitcnt vmcnt(13)
	ds_write_b128 v164, v[192:195] offset:9216
	s_waitcnt vmcnt(12)
	ds_write_b128 v164, v[196:199] offset:13824
	s_waitcnt lgkmcnt(7)
	v_mfma_f32_16x16x32_bf16 v[26:29], v[228:231], v[232:235], v[26:29]
	ds_read_b128 v[232:235], v245 offset:55360
	v_mfma_f32_16x16x32_bf16 v[30:33], v[228:231], v[236:239], v[30:33]
	ds_read_b128 v[236:239], v245 offset:57664
	v_mfma_f32_16x16x32_bf16 v[10:13], v[228:231], v[240:243], v[10:13]
	ds_read_b128 v[240:243], v245 offset:59968
	v_mfma_f32_16x16x32_bf16 v[14:17], v[228:231], v[252:255], v[14:17]
	ds_read_b128 v[252:255], v245 offset:62272
	ds_read_b128 v[228:231], v244 offset:25408
	s_waitcnt lgkmcnt(4)
	v_mfma_f32_16x16x32_bf16 v[50:53], v[216:219], v[232:235], v[50:53]
	s_waitcnt lgkmcnt(3)
	v_mfma_f32_16x16x32_bf16 v[54:57], v[216:219], v[236:239], v[54:57]
	s_waitcnt lgkmcnt(2)
	v_mfma_f32_16x16x32_bf16 v[34:37], v[216:219], v[240:243], v[34:37]
	s_waitcnt lgkmcnt(1)
	v_mfma_f32_16x16x32_bf16 v[38:41], v[216:219], v[252:255], v[38:41]
	s_waitcnt vmcnt(11)
	ds_write_b128 v164, v[200:203] offset:36864
	s_waitcnt vmcnt(10)
	ds_write_b128 v164, v[204:207] offset:41472
	v_mfma_f32_16x16x32_bf16 v[58:61], v[220:223], v[232:235], v[58:61]
	v_mfma_f32_16x16x32_bf16 v[62:65], v[220:223], v[236:239], v[62:65]
	v_mfma_f32_16x16x32_bf16 v[42:45], v[220:223], v[240:243], v[42:45]
	v_mfma_f32_16x16x32_bf16 v[46:49], v[220:223], v[252:255], v[46:49]
	s_waitcnt vmcnt(9)
	ds_write_b128 v164, v[208:211] offset:46080
	s_waitcnt vmcnt(8)
	ds_write_b128 v164, v[212:215] offset:50688
	v_mfma_f32_16x16x32_bf16 v[18:21], v[224:227], v[232:235], v[18:21]
	v_mfma_f32_16x16x32_bf16 v[22:25], v[224:227], v[236:239], v[22:25]
	v_mfma_f32_16x16x32_bf16 v[2:5], v[224:227], v[240:243], v[2:5]
	v_mfma_f32_16x16x32_bf16 v[6:9], v[224:227], v[252:255], v[6:9]
	s_waitcnt lgkmcnt(4)
	v_mfma_f32_16x16x32_bf16 v[26:29], v[228:231], v[232:235], v[26:29]
	v_mfma_f32_16x16x32_bf16 v[30:33], v[228:231], v[236:239], v[30:33]
	v_mfma_f32_16x16x32_bf16 v[10:13], v[228:231], v[240:243], v[10:13]
	v_mfma_f32_16x16x32_bf16 v[14:17], v[228:231], v[252:255], v[14:17]
	s_waitcnt lgkmcnt(0)
	s_barrier
	s_setprio 0
	global_load_dwordx4 v[180:183], v[70:71], off offset:768
	global_load_dwordx4 v[188:191], v[68:69], off offset:768
	global_load_dwordx4 v[192:195], v[66:67], off offset:768
	global_load_dwordx4 v[196:199], v[72:73], off offset:768
	global_load_dwordx4 v[200:203], v[74:75], off offset:768
	global_load_dwordx4 v[204:207], v[76:77], off offset:768
	global_load_dwordx4 v[208:211], v[78:79], off offset:768
	global_load_dwordx4 v[212:215], v[80:81], off offset:768
	ds_read_b128 v[232:235], v245 offset:36864
	ds_read_b128 v[216:219], v244
	ds_read_b128 v[236:239], v245 offset:39168
	ds_read_b128 v[240:243], v245 offset:41472
	ds_read_b128 v[252:255], v245 offset:43776
	ds_read_b128 v[220:223], v244 offset:2304
	ds_read_b128 v[224:227], v244 offset:4608
	ds_read_b128 v[228:231], v244 offset:6912
	s_waitcnt lgkmcnt(6)
	v_mfma_f32_16x16x32_bf16 v[50:53], v[216:219], v[232:235], v[50:53]
	s_waitcnt lgkmcnt(5)
	v_mfma_f32_16x16x32_bf16 v[54:57], v[216:219], v[236:239], v[54:57]
	s_waitcnt lgkmcnt(4)
	v_mfma_f32_16x16x32_bf16 v[34:37], v[216:219], v[240:243], v[34:37]
	s_waitcnt lgkmcnt(3)
	v_mfma_f32_16x16x32_bf16 v[38:41], v[216:219], v[252:255], v[38:41]
	ds_read_b128 v[216:219], v244 offset:64
	s_waitcnt lgkmcnt(3)
	v_mfma_f32_16x16x32_bf16 v[58:61], v[220:223], v[232:235], v[58:61]
	v_mfma_f32_16x16x32_bf16 v[62:65], v[220:223], v[236:239], v[62:65]
	v_mfma_f32_16x16x32_bf16 v[42:45], v[220:223], v[240:243], v[42:45]
	v_mfma_f32_16x16x32_bf16 v[46:49], v[220:223], v[252:255], v[46:49]
	ds_read_b128 v[220:223], v244 offset:2368
	s_setprio 1
	s_waitcnt vmcnt(15)
	ds_write_b128 v164, v[122:125] offset:18432
	s_waitcnt vmcnt(14)
	ds_write_b128 v164, v[126:129] offset:23040
	s_waitcnt lgkmcnt(5)
	v_mfma_f32_16x16x32_bf16 v[18:21], v[224:227], v[232:235], v[18:21]
	v_mfma_f32_16x16x32_bf16 v[22:25], v[224:227], v[236:239], v[22:25]
	v_mfma_f32_16x16x32_bf16 v[2:5], v[224:227], v[240:243], v[2:5]
	v_mfma_f32_16x16x32_bf16 v[6:9], v[224:227], v[252:255], v[6:9]
	ds_read_b128 v[224:227], v244 offset:4672
	s_waitcnt vmcnt(13)
	ds_write_b128 v164, v[136:139] offset:27648
	s_waitcnt vmcnt(12)
	ds_write_b128 v164, v[140:143] offset:32256
	s_waitcnt lgkmcnt(7)
	v_mfma_f32_16x16x32_bf16 v[26:29], v[228:231], v[232:235], v[26:29]
	ds_read_b128 v[232:235], v245 offset:36928
	v_mfma_f32_16x16x32_bf16 v[30:33], v[228:231], v[236:239], v[30:33]
	ds_read_b128 v[236:239], v245 offset:39232
	v_mfma_f32_16x16x32_bf16 v[10:13], v[228:231], v[240:243], v[10:13]
	ds_read_b128 v[240:243], v245 offset:41536
	v_mfma_f32_16x16x32_bf16 v[14:17], v[228:231], v[252:255], v[14:17]
	ds_read_b128 v[252:255], v245 offset:43840
	ds_read_b128 v[228:231], v244 offset:6976
	s_waitcnt lgkmcnt(4)
	v_mfma_f32_16x16x32_bf16 v[50:53], v[216:219], v[232:235], v[50:53]
	s_waitcnt lgkmcnt(3)
	v_mfma_f32_16x16x32_bf16 v[54:57], v[216:219], v[236:239], v[54:57]
	s_waitcnt lgkmcnt(2)
	v_mfma_f32_16x16x32_bf16 v[34:37], v[216:219], v[240:243], v[34:37]
	s_waitcnt lgkmcnt(1)
	v_mfma_f32_16x16x32_bf16 v[38:41], v[216:219], v[252:255], v[38:41]
	s_waitcnt vmcnt(11)
	ds_write_b128 v164, v[144:147] offset:55296
	s_waitcnt vmcnt(10)
	ds_write_b128 v164, v[148:151] offset:59904
	v_mfma_f32_16x16x32_bf16 v[58:61], v[220:223], v[232:235], v[58:61]
	v_mfma_f32_16x16x32_bf16 v[62:65], v[220:223], v[236:239], v[62:65]
	v_mfma_f32_16x16x32_bf16 v[42:45], v[220:223], v[240:243], v[42:45]
	v_mfma_f32_16x16x32_bf16 v[46:49], v[220:223], v[252:255], v[46:49]
	s_waitcnt vmcnt(9)
	ds_write_b128 v164, v[172:175] offset:64512
	s_waitcnt vmcnt(8)
	ds_write_b128 v165, v[176:179] offset:32256
	v_mfma_f32_16x16x32_bf16 v[18:21], v[224:227], v[232:235], v[18:21]
	v_mfma_f32_16x16x32_bf16 v[22:25], v[224:227], v[236:239], v[22:25]
	v_mfma_f32_16x16x32_bf16 v[2:5], v[224:227], v[240:243], v[2:5]
	v_mfma_f32_16x16x32_bf16 v[6:9], v[224:227], v[252:255], v[6:9]
	s_waitcnt lgkmcnt(4)
	v_mfma_f32_16x16x32_bf16 v[26:29], v[228:231], v[232:235], v[26:29]
	v_mfma_f32_16x16x32_bf16 v[30:33], v[228:231], v[236:239], v[30:33]
	v_mfma_f32_16x16x32_bf16 v[10:13], v[228:231], v[240:243], v[10:13]
	v_mfma_f32_16x16x32_bf16 v[14:17], v[228:231], v[252:255], v[14:17]
	s_waitcnt lgkmcnt(0)
	s_barrier
	s_setprio 0
	global_load_dwordx4 v[122:125], v[70:71], off offset:896
	global_load_dwordx4 v[126:129], v[68:69], off offset:896
	global_load_dwordx4 v[136:139], v[66:67], off offset:896
	global_load_dwordx4 v[140:143], v[72:73], off offset:896
	global_load_dwordx4 v[144:147], v[74:75], off offset:896
	global_load_dwordx4 v[148:151], v[76:77], off offset:896
	global_load_dwordx4 v[172:175], v[78:79], off offset:896
	global_load_dwordx4 v[176:179], v[80:81], off offset:896
	ds_read_b128 v[232:235], v245 offset:55296
	ds_read_b128 v[216:219], v244 offset:18432
	ds_read_b128 v[236:239], v245 offset:57600
	ds_read_b128 v[240:243], v245 offset:59904
	ds_read_b128 v[252:255], v245 offset:62208
	ds_read_b128 v[220:223], v244 offset:20736
	ds_read_b128 v[224:227], v244 offset:23040
	ds_read_b128 v[228:231], v244 offset:25344
	s_waitcnt lgkmcnt(6)
	v_mfma_f32_16x16x32_bf16 v[50:53], v[216:219], v[232:235], v[50:53]
	s_waitcnt lgkmcnt(5)
	v_mfma_f32_16x16x32_bf16 v[54:57], v[216:219], v[236:239], v[54:57]
	s_waitcnt lgkmcnt(4)
	v_mfma_f32_16x16x32_bf16 v[34:37], v[216:219], v[240:243], v[34:37]
	s_waitcnt lgkmcnt(3)
	v_mfma_f32_16x16x32_bf16 v[38:41], v[216:219], v[252:255], v[38:41]
	ds_read_b128 v[216:219], v244 offset:18496
	s_waitcnt lgkmcnt(3)
	v_mfma_f32_16x16x32_bf16 v[58:61], v[220:223], v[232:235], v[58:61]
	v_mfma_f32_16x16x32_bf16 v[62:65], v[220:223], v[236:239], v[62:65]
	v_mfma_f32_16x16x32_bf16 v[42:45], v[220:223], v[240:243], v[42:45]
	v_mfma_f32_16x16x32_bf16 v[46:49], v[220:223], v[252:255], v[46:49]
	ds_read_b128 v[220:223], v244 offset:20800
	s_setprio 1
	s_waitcnt vmcnt(15)
	ds_write_b128 v164, v[180:183]
	s_waitcnt vmcnt(14)
	ds_write_b128 v164, v[188:191] offset:4608
	s_waitcnt lgkmcnt(5)
	v_mfma_f32_16x16x32_bf16 v[18:21], v[224:227], v[232:235], v[18:21]
	v_mfma_f32_16x16x32_bf16 v[22:25], v[224:227], v[236:239], v[22:25]
	v_mfma_f32_16x16x32_bf16 v[2:5], v[224:227], v[240:243], v[2:5]
	v_mfma_f32_16x16x32_bf16 v[6:9], v[224:227], v[252:255], v[6:9]
	ds_read_b128 v[224:227], v244 offset:23104
	s_waitcnt vmcnt(13)
	ds_write_b128 v164, v[192:195] offset:9216
	s_waitcnt vmcnt(12)
	ds_write_b128 v164, v[196:199] offset:13824
	s_waitcnt lgkmcnt(7)
	v_mfma_f32_16x16x32_bf16 v[26:29], v[228:231], v[232:235], v[26:29]
	ds_read_b128 v[232:235], v245 offset:55360
	v_mfma_f32_16x16x32_bf16 v[30:33], v[228:231], v[236:239], v[30:33]
	ds_read_b128 v[236:239], v245 offset:57664
	v_mfma_f32_16x16x32_bf16 v[10:13], v[228:231], v[240:243], v[10:13]
	ds_read_b128 v[240:243], v245 offset:59968
	v_mfma_f32_16x16x32_bf16 v[14:17], v[228:231], v[252:255], v[14:17]
	ds_read_b128 v[252:255], v245 offset:62272
	ds_read_b128 v[228:231], v244 offset:25408
	s_waitcnt lgkmcnt(4)
	v_mfma_f32_16x16x32_bf16 v[50:53], v[216:219], v[232:235], v[50:53]
	s_waitcnt lgkmcnt(3)
	v_mfma_f32_16x16x32_bf16 v[54:57], v[216:219], v[236:239], v[54:57]
	s_waitcnt lgkmcnt(2)
	v_mfma_f32_16x16x32_bf16 v[34:37], v[216:219], v[240:243], v[34:37]
	s_waitcnt lgkmcnt(1)
	v_mfma_f32_16x16x32_bf16 v[38:41], v[216:219], v[252:255], v[38:41]
	s_waitcnt vmcnt(11)
	ds_write_b128 v164, v[200:203] offset:36864
	s_waitcnt vmcnt(10)
	ds_write_b128 v164, v[204:207] offset:41472
	v_mfma_f32_16x16x32_bf16 v[58:61], v[220:223], v[232:235], v[58:61]
	v_mfma_f32_16x16x32_bf16 v[62:65], v[220:223], v[236:239], v[62:65]
	v_mfma_f32_16x16x32_bf16 v[42:45], v[220:223], v[240:243], v[42:45]
	v_mfma_f32_16x16x32_bf16 v[46:49], v[220:223], v[252:255], v[46:49]
	s_waitcnt vmcnt(9)
	ds_write_b128 v164, v[208:211] offset:46080
	s_waitcnt vmcnt(8)
	ds_write_b128 v164, v[212:215] offset:50688
	v_mfma_f32_16x16x32_bf16 v[18:21], v[224:227], v[232:235], v[18:21]
	v_mfma_f32_16x16x32_bf16 v[22:25], v[224:227], v[236:239], v[22:25]
	v_mfma_f32_16x16x32_bf16 v[2:5], v[224:227], v[240:243], v[2:5]
	v_mfma_f32_16x16x32_bf16 v[6:9], v[224:227], v[252:255], v[6:9]
	s_waitcnt lgkmcnt(4)
	v_mfma_f32_16x16x32_bf16 v[26:29], v[228:231], v[232:235], v[26:29]
	v_mfma_f32_16x16x32_bf16 v[30:33], v[228:231], v[236:239], v[30:33]
	v_mfma_f32_16x16x32_bf16 v[10:13], v[228:231], v[240:243], v[10:13]
	v_mfma_f32_16x16x32_bf16 v[14:17], v[228:231], v[252:255], v[14:17]
	s_waitcnt lgkmcnt(0)
	s_barrier
	s_setprio 0
	global_load_dwordx4 v[180:183], v[70:71], off offset:1024
	global_load_dwordx4 v[188:191], v[68:69], off offset:1024
	global_load_dwordx4 v[192:195], v[66:67], off offset:1024
	global_load_dwordx4 v[196:199], v[72:73], off offset:1024
	global_load_dwordx4 v[200:203], v[74:75], off offset:1024
	global_load_dwordx4 v[204:207], v[76:77], off offset:1024
	global_load_dwordx4 v[208:211], v[78:79], off offset:1024
	global_load_dwordx4 v[212:215], v[80:81], off offset:1024
	ds_read_b128 v[232:235], v245 offset:36864
	ds_read_b128 v[216:219], v244
	ds_read_b128 v[236:239], v245 offset:39168
	ds_read_b128 v[240:243], v245 offset:41472
	ds_read_b128 v[252:255], v245 offset:43776
	ds_read_b128 v[220:223], v244 offset:2304
	ds_read_b128 v[224:227], v244 offset:4608
	ds_read_b128 v[228:231], v244 offset:6912
	s_waitcnt lgkmcnt(6)
	v_mfma_f32_16x16x32_bf16 v[50:53], v[216:219], v[232:235], v[50:53]
	s_waitcnt lgkmcnt(5)
	v_mfma_f32_16x16x32_bf16 v[54:57], v[216:219], v[236:239], v[54:57]
	s_waitcnt lgkmcnt(4)
	v_mfma_f32_16x16x32_bf16 v[34:37], v[216:219], v[240:243], v[34:37]
	s_waitcnt lgkmcnt(3)
	v_mfma_f32_16x16x32_bf16 v[38:41], v[216:219], v[252:255], v[38:41]
	ds_read_b128 v[216:219], v244 offset:64
	s_waitcnt lgkmcnt(3)
	v_mfma_f32_16x16x32_bf16 v[58:61], v[220:223], v[232:235], v[58:61]
	v_mfma_f32_16x16x32_bf16 v[62:65], v[220:223], v[236:239], v[62:65]
	v_mfma_f32_16x16x32_bf16 v[42:45], v[220:223], v[240:243], v[42:45]
	v_mfma_f32_16x16x32_bf16 v[46:49], v[220:223], v[252:255], v[46:49]
	ds_read_b128 v[220:223], v244 offset:2368
	s_setprio 1
	s_waitcnt vmcnt(15)
	ds_write_b128 v164, v[122:125] offset:18432
	s_waitcnt vmcnt(14)
	ds_write_b128 v164, v[126:129] offset:23040
	s_waitcnt lgkmcnt(5)
	v_mfma_f32_16x16x32_bf16 v[18:21], v[224:227], v[232:235], v[18:21]
	v_mfma_f32_16x16x32_bf16 v[22:25], v[224:227], v[236:239], v[22:25]
	v_mfma_f32_16x16x32_bf16 v[2:5], v[224:227], v[240:243], v[2:5]
	v_mfma_f32_16x16x32_bf16 v[6:9], v[224:227], v[252:255], v[6:9]
	ds_read_b128 v[224:227], v244 offset:4672
	s_waitcnt vmcnt(13)
	ds_write_b128 v164, v[136:139] offset:27648
	s_waitcnt vmcnt(12)
	ds_write_b128 v164, v[140:143] offset:32256
	s_waitcnt lgkmcnt(7)
	v_mfma_f32_16x16x32_bf16 v[26:29], v[228:231], v[232:235], v[26:29]
	ds_read_b128 v[232:235], v245 offset:36928
	v_mfma_f32_16x16x32_bf16 v[30:33], v[228:231], v[236:239], v[30:33]
	ds_read_b128 v[236:239], v245 offset:39232
	v_mfma_f32_16x16x32_bf16 v[10:13], v[228:231], v[240:243], v[10:13]
	ds_read_b128 v[240:243], v245 offset:41536
	v_mfma_f32_16x16x32_bf16 v[14:17], v[228:231], v[252:255], v[14:17]
	ds_read_b128 v[252:255], v245 offset:43840
	ds_read_b128 v[228:231], v244 offset:6976
	s_waitcnt lgkmcnt(4)
	v_mfma_f32_16x16x32_bf16 v[50:53], v[216:219], v[232:235], v[50:53]
	s_waitcnt lgkmcnt(3)
	v_mfma_f32_16x16x32_bf16 v[54:57], v[216:219], v[236:239], v[54:57]
	s_waitcnt lgkmcnt(2)
	v_mfma_f32_16x16x32_bf16 v[34:37], v[216:219], v[240:243], v[34:37]
	s_waitcnt lgkmcnt(1)
	v_mfma_f32_16x16x32_bf16 v[38:41], v[216:219], v[252:255], v[38:41]
	s_waitcnt vmcnt(11)
	ds_write_b128 v164, v[144:147] offset:55296
	s_waitcnt vmcnt(10)
	ds_write_b128 v164, v[148:151] offset:59904
	v_mfma_f32_16x16x32_bf16 v[58:61], v[220:223], v[232:235], v[58:61]
	v_mfma_f32_16x16x32_bf16 v[62:65], v[220:223], v[236:239], v[62:65]
	v_mfma_f32_16x16x32_bf16 v[42:45], v[220:223], v[240:243], v[42:45]
	v_mfma_f32_16x16x32_bf16 v[46:49], v[220:223], v[252:255], v[46:49]
	s_waitcnt vmcnt(9)
	ds_write_b128 v164, v[172:175] offset:64512
	s_waitcnt vmcnt(8)
	ds_write_b128 v165, v[176:179] offset:32256
	v_mfma_f32_16x16x32_bf16 v[18:21], v[224:227], v[232:235], v[18:21]
	v_mfma_f32_16x16x32_bf16 v[22:25], v[224:227], v[236:239], v[22:25]
	v_mfma_f32_16x16x32_bf16 v[2:5], v[224:227], v[240:243], v[2:5]
	v_mfma_f32_16x16x32_bf16 v[6:9], v[224:227], v[252:255], v[6:9]
	s_waitcnt lgkmcnt(4)
	v_mfma_f32_16x16x32_bf16 v[26:29], v[228:231], v[232:235], v[26:29]
	v_mfma_f32_16x16x32_bf16 v[30:33], v[228:231], v[236:239], v[30:33]
	v_mfma_f32_16x16x32_bf16 v[10:13], v[228:231], v[240:243], v[10:13]
	v_mfma_f32_16x16x32_bf16 v[14:17], v[228:231], v[252:255], v[14:17]
	s_waitcnt lgkmcnt(0)
	s_barrier
	s_setprio 0
	global_load_dwordx4 v[122:125], v[70:71], off offset:1152
	global_load_dwordx4 v[126:129], v[68:69], off offset:1152
	global_load_dwordx4 v[136:139], v[66:67], off offset:1152
	global_load_dwordx4 v[140:143], v[72:73], off offset:1152
	global_load_dwordx4 v[144:147], v[74:75], off offset:1152
	global_load_dwordx4 v[148:151], v[76:77], off offset:1152
	global_load_dwordx4 v[172:175], v[78:79], off offset:1152
	global_load_dwordx4 v[176:179], v[80:81], off offset:1152
	ds_read_b128 v[232:235], v245 offset:55296
	ds_read_b128 v[216:219], v244 offset:18432
	ds_read_b128 v[236:239], v245 offset:57600
	ds_read_b128 v[240:243], v245 offset:59904
	ds_read_b128 v[252:255], v245 offset:62208
	ds_read_b128 v[220:223], v244 offset:20736
	ds_read_b128 v[224:227], v244 offset:23040
	ds_read_b128 v[228:231], v244 offset:25344
	s_waitcnt lgkmcnt(6)
	v_mfma_f32_16x16x32_bf16 v[50:53], v[216:219], v[232:235], v[50:53]
	s_waitcnt lgkmcnt(5)
	v_mfma_f32_16x16x32_bf16 v[54:57], v[216:219], v[236:239], v[54:57]
	s_waitcnt lgkmcnt(4)
	v_mfma_f32_16x16x32_bf16 v[34:37], v[216:219], v[240:243], v[34:37]
	s_waitcnt lgkmcnt(3)
	v_mfma_f32_16x16x32_bf16 v[38:41], v[216:219], v[252:255], v[38:41]
	ds_read_b128 v[216:219], v244 offset:18496
	s_waitcnt lgkmcnt(3)
	v_mfma_f32_16x16x32_bf16 v[58:61], v[220:223], v[232:235], v[58:61]
	v_mfma_f32_16x16x32_bf16 v[62:65], v[220:223], v[236:239], v[62:65]
	v_mfma_f32_16x16x32_bf16 v[42:45], v[220:223], v[240:243], v[42:45]
	v_mfma_f32_16x16x32_bf16 v[46:49], v[220:223], v[252:255], v[46:49]
	ds_read_b128 v[220:223], v244 offset:20800
	s_setprio 1
	s_waitcnt vmcnt(15)
	ds_write_b128 v164, v[180:183]
	s_waitcnt vmcnt(14)
	ds_write_b128 v164, v[188:191] offset:4608
	s_waitcnt lgkmcnt(5)
	v_mfma_f32_16x16x32_bf16 v[18:21], v[224:227], v[232:235], v[18:21]
	v_mfma_f32_16x16x32_bf16 v[22:25], v[224:227], v[236:239], v[22:25]
	v_mfma_f32_16x16x32_bf16 v[2:5], v[224:227], v[240:243], v[2:5]
	v_mfma_f32_16x16x32_bf16 v[6:9], v[224:227], v[252:255], v[6:9]
	ds_read_b128 v[224:227], v244 offset:23104
	s_waitcnt vmcnt(13)
	ds_write_b128 v164, v[192:195] offset:9216
	s_waitcnt vmcnt(12)
	ds_write_b128 v164, v[196:199] offset:13824
	s_waitcnt lgkmcnt(7)
	v_mfma_f32_16x16x32_bf16 v[26:29], v[228:231], v[232:235], v[26:29]
	ds_read_b128 v[232:235], v245 offset:55360
	v_mfma_f32_16x16x32_bf16 v[30:33], v[228:231], v[236:239], v[30:33]
	ds_read_b128 v[236:239], v245 offset:57664
	v_mfma_f32_16x16x32_bf16 v[10:13], v[228:231], v[240:243], v[10:13]
	ds_read_b128 v[240:243], v245 offset:59968
	v_mfma_f32_16x16x32_bf16 v[14:17], v[228:231], v[252:255], v[14:17]
	ds_read_b128 v[252:255], v245 offset:62272
	ds_read_b128 v[228:231], v244 offset:25408
	s_waitcnt lgkmcnt(4)
	v_mfma_f32_16x16x32_bf16 v[50:53], v[216:219], v[232:235], v[50:53]
	s_waitcnt lgkmcnt(3)
	v_mfma_f32_16x16x32_bf16 v[54:57], v[216:219], v[236:239], v[54:57]
	s_waitcnt lgkmcnt(2)
	v_mfma_f32_16x16x32_bf16 v[34:37], v[216:219], v[240:243], v[34:37]
	s_waitcnt lgkmcnt(1)
	v_mfma_f32_16x16x32_bf16 v[38:41], v[216:219], v[252:255], v[38:41]
	s_waitcnt vmcnt(11)
	ds_write_b128 v164, v[200:203] offset:36864
	s_waitcnt vmcnt(10)
	ds_write_b128 v164, v[204:207] offset:41472
	v_mfma_f32_16x16x32_bf16 v[58:61], v[220:223], v[232:235], v[58:61]
	v_mfma_f32_16x16x32_bf16 v[62:65], v[220:223], v[236:239], v[62:65]
	v_mfma_f32_16x16x32_bf16 v[42:45], v[220:223], v[240:243], v[42:45]
	v_mfma_f32_16x16x32_bf16 v[46:49], v[220:223], v[252:255], v[46:49]
	s_waitcnt vmcnt(9)
	ds_write_b128 v164, v[208:211] offset:46080
	s_waitcnt vmcnt(8)
	ds_write_b128 v164, v[212:215] offset:50688
	v_mfma_f32_16x16x32_bf16 v[18:21], v[224:227], v[232:235], v[18:21]
	v_mfma_f32_16x16x32_bf16 v[22:25], v[224:227], v[236:239], v[22:25]
	v_mfma_f32_16x16x32_bf16 v[2:5], v[224:227], v[240:243], v[2:5]
	v_mfma_f32_16x16x32_bf16 v[6:9], v[224:227], v[252:255], v[6:9]
	s_waitcnt lgkmcnt(4)
	v_mfma_f32_16x16x32_bf16 v[26:29], v[228:231], v[232:235], v[26:29]
	v_mfma_f32_16x16x32_bf16 v[30:33], v[228:231], v[236:239], v[30:33]
	v_mfma_f32_16x16x32_bf16 v[10:13], v[228:231], v[240:243], v[10:13]
	v_mfma_f32_16x16x32_bf16 v[14:17], v[228:231], v[252:255], v[14:17]
	s_waitcnt lgkmcnt(0)
	s_barrier
	s_setprio 0
	global_load_dwordx4 v[180:183], v[70:71], off offset:1280
	global_load_dwordx4 v[188:191], v[68:69], off offset:1280
	global_load_dwordx4 v[192:195], v[66:67], off offset:1280
	global_load_dwordx4 v[196:199], v[72:73], off offset:1280
	global_load_dwordx4 v[200:203], v[74:75], off offset:1280
	global_load_dwordx4 v[204:207], v[76:77], off offset:1280
	global_load_dwordx4 v[208:211], v[78:79], off offset:1280
	global_load_dwordx4 v[212:215], v[80:81], off offset:1280
	ds_read_b128 v[232:235], v245 offset:36864
	ds_read_b128 v[216:219], v244
	ds_read_b128 v[236:239], v245 offset:39168
	ds_read_b128 v[240:243], v245 offset:41472
	ds_read_b128 v[252:255], v245 offset:43776
	ds_read_b128 v[220:223], v244 offset:2304
	ds_read_b128 v[224:227], v244 offset:4608
	ds_read_b128 v[228:231], v244 offset:6912
	s_waitcnt lgkmcnt(6)
	v_mfma_f32_16x16x32_bf16 v[50:53], v[216:219], v[232:235], v[50:53]
	s_waitcnt lgkmcnt(5)
	v_mfma_f32_16x16x32_bf16 v[54:57], v[216:219], v[236:239], v[54:57]
	s_waitcnt lgkmcnt(4)
	v_mfma_f32_16x16x32_bf16 v[34:37], v[216:219], v[240:243], v[34:37]
	s_waitcnt lgkmcnt(3)
	v_mfma_f32_16x16x32_bf16 v[38:41], v[216:219], v[252:255], v[38:41]
	ds_read_b128 v[216:219], v244 offset:64
	s_waitcnt lgkmcnt(3)
	v_mfma_f32_16x16x32_bf16 v[58:61], v[220:223], v[232:235], v[58:61]
	v_mfma_f32_16x16x32_bf16 v[62:65], v[220:223], v[236:239], v[62:65]
	v_mfma_f32_16x16x32_bf16 v[42:45], v[220:223], v[240:243], v[42:45]
	v_mfma_f32_16x16x32_bf16 v[46:49], v[220:223], v[252:255], v[46:49]
	ds_read_b128 v[220:223], v244 offset:2368
	s_setprio 1
	s_waitcnt vmcnt(15)
	ds_write_b128 v164, v[122:125] offset:18432
	s_waitcnt vmcnt(14)
	ds_write_b128 v164, v[126:129] offset:23040
	s_waitcnt lgkmcnt(5)
	v_mfma_f32_16x16x32_bf16 v[18:21], v[224:227], v[232:235], v[18:21]
	v_mfma_f32_16x16x32_bf16 v[22:25], v[224:227], v[236:239], v[22:25]
	v_mfma_f32_16x16x32_bf16 v[2:5], v[224:227], v[240:243], v[2:5]
	v_mfma_f32_16x16x32_bf16 v[6:9], v[224:227], v[252:255], v[6:9]
	ds_read_b128 v[224:227], v244 offset:4672
	s_waitcnt vmcnt(13)
	ds_write_b128 v164, v[136:139] offset:27648
	s_waitcnt vmcnt(12)
	ds_write_b128 v164, v[140:143] offset:32256
	s_waitcnt lgkmcnt(7)
	v_mfma_f32_16x16x32_bf16 v[26:29], v[228:231], v[232:235], v[26:29]
	ds_read_b128 v[232:235], v245 offset:36928
	v_mfma_f32_16x16x32_bf16 v[30:33], v[228:231], v[236:239], v[30:33]
	ds_read_b128 v[236:239], v245 offset:39232
	v_mfma_f32_16x16x32_bf16 v[10:13], v[228:231], v[240:243], v[10:13]
	ds_read_b128 v[240:243], v245 offset:41536
	v_mfma_f32_16x16x32_bf16 v[14:17], v[228:231], v[252:255], v[14:17]
	ds_read_b128 v[252:255], v245 offset:43840
	ds_read_b128 v[228:231], v244 offset:6976
	s_waitcnt lgkmcnt(4)
	v_mfma_f32_16x16x32_bf16 v[50:53], v[216:219], v[232:235], v[50:53]
	s_waitcnt lgkmcnt(3)
	v_mfma_f32_16x16x32_bf16 v[54:57], v[216:219], v[236:239], v[54:57]
	s_waitcnt lgkmcnt(2)
	v_mfma_f32_16x16x32_bf16 v[34:37], v[216:219], v[240:243], v[34:37]
	s_waitcnt lgkmcnt(1)
	v_mfma_f32_16x16x32_bf16 v[38:41], v[216:219], v[252:255], v[38:41]
	s_waitcnt vmcnt(11)
	ds_write_b128 v164, v[144:147] offset:55296
	s_waitcnt vmcnt(10)
	ds_write_b128 v164, v[148:151] offset:59904
	v_mfma_f32_16x16x32_bf16 v[58:61], v[220:223], v[232:235], v[58:61]
	v_mfma_f32_16x16x32_bf16 v[62:65], v[220:223], v[236:239], v[62:65]
	v_mfma_f32_16x16x32_bf16 v[42:45], v[220:223], v[240:243], v[42:45]
	v_mfma_f32_16x16x32_bf16 v[46:49], v[220:223], v[252:255], v[46:49]
	s_waitcnt vmcnt(9)
	ds_write_b128 v164, v[172:175] offset:64512
	s_waitcnt vmcnt(8)
	ds_write_b128 v165, v[176:179] offset:32256
	v_mfma_f32_16x16x32_bf16 v[18:21], v[224:227], v[232:235], v[18:21]
	v_mfma_f32_16x16x32_bf16 v[22:25], v[224:227], v[236:239], v[22:25]
	v_mfma_f32_16x16x32_bf16 v[2:5], v[224:227], v[240:243], v[2:5]
	v_mfma_f32_16x16x32_bf16 v[6:9], v[224:227], v[252:255], v[6:9]
	s_waitcnt lgkmcnt(4)
	v_mfma_f32_16x16x32_bf16 v[26:29], v[228:231], v[232:235], v[26:29]
	v_mfma_f32_16x16x32_bf16 v[30:33], v[228:231], v[236:239], v[30:33]
	v_mfma_f32_16x16x32_bf16 v[10:13], v[228:231], v[240:243], v[10:13]
	v_mfma_f32_16x16x32_bf16 v[14:17], v[228:231], v[252:255], v[14:17]
	s_waitcnt lgkmcnt(0)
	s_barrier
	s_setprio 0
	global_load_dwordx4 v[122:125], v[70:71], off offset:1408
	global_load_dwordx4 v[126:129], v[68:69], off offset:1408
	global_load_dwordx4 v[136:139], v[66:67], off offset:1408
	global_load_dwordx4 v[140:143], v[72:73], off offset:1408
	global_load_dwordx4 v[144:147], v[74:75], off offset:1408
	global_load_dwordx4 v[148:151], v[76:77], off offset:1408
	global_load_dwordx4 v[172:175], v[78:79], off offset:1408
	global_load_dwordx4 v[176:179], v[80:81], off offset:1408
	ds_read_b128 v[232:235], v245 offset:55296
	ds_read_b128 v[216:219], v244 offset:18432
	ds_read_b128 v[236:239], v245 offset:57600
	ds_read_b128 v[240:243], v245 offset:59904
	ds_read_b128 v[252:255], v245 offset:62208
	ds_read_b128 v[220:223], v244 offset:20736
	ds_read_b128 v[224:227], v244 offset:23040
	ds_read_b128 v[228:231], v244 offset:25344
	s_waitcnt lgkmcnt(6)
	v_mfma_f32_16x16x32_bf16 v[50:53], v[216:219], v[232:235], v[50:53]
	s_waitcnt lgkmcnt(5)
	v_mfma_f32_16x16x32_bf16 v[54:57], v[216:219], v[236:239], v[54:57]
	s_waitcnt lgkmcnt(4)
	v_mfma_f32_16x16x32_bf16 v[34:37], v[216:219], v[240:243], v[34:37]
	s_waitcnt lgkmcnt(3)
	v_mfma_f32_16x16x32_bf16 v[38:41], v[216:219], v[252:255], v[38:41]
	ds_read_b128 v[216:219], v244 offset:18496
	s_waitcnt lgkmcnt(3)
	v_mfma_f32_16x16x32_bf16 v[58:61], v[220:223], v[232:235], v[58:61]
	v_mfma_f32_16x16x32_bf16 v[62:65], v[220:223], v[236:239], v[62:65]
	v_mfma_f32_16x16x32_bf16 v[42:45], v[220:223], v[240:243], v[42:45]
	v_mfma_f32_16x16x32_bf16 v[46:49], v[220:223], v[252:255], v[46:49]
	ds_read_b128 v[220:223], v244 offset:20800
	s_setprio 1
	s_waitcnt vmcnt(15)
	ds_write_b128 v164, v[180:183]
	s_waitcnt vmcnt(14)
	ds_write_b128 v164, v[188:191] offset:4608
	s_waitcnt lgkmcnt(5)
	v_mfma_f32_16x16x32_bf16 v[18:21], v[224:227], v[232:235], v[18:21]
	v_mfma_f32_16x16x32_bf16 v[22:25], v[224:227], v[236:239], v[22:25]
	v_mfma_f32_16x16x32_bf16 v[2:5], v[224:227], v[240:243], v[2:5]
	v_mfma_f32_16x16x32_bf16 v[6:9], v[224:227], v[252:255], v[6:9]
	ds_read_b128 v[224:227], v244 offset:23104
	s_waitcnt vmcnt(13)
	ds_write_b128 v164, v[192:195] offset:9216
	s_waitcnt vmcnt(12)
	ds_write_b128 v164, v[196:199] offset:13824
	s_waitcnt lgkmcnt(7)
	v_mfma_f32_16x16x32_bf16 v[26:29], v[228:231], v[232:235], v[26:29]
	ds_read_b128 v[232:235], v245 offset:55360
	v_mfma_f32_16x16x32_bf16 v[30:33], v[228:231], v[236:239], v[30:33]
	ds_read_b128 v[236:239], v245 offset:57664
	v_mfma_f32_16x16x32_bf16 v[10:13], v[228:231], v[240:243], v[10:13]
	ds_read_b128 v[240:243], v245 offset:59968
	v_mfma_f32_16x16x32_bf16 v[14:17], v[228:231], v[252:255], v[14:17]
	ds_read_b128 v[252:255], v245 offset:62272
	ds_read_b128 v[228:231], v244 offset:25408
	s_waitcnt lgkmcnt(4)
	v_mfma_f32_16x16x32_bf16 v[50:53], v[216:219], v[232:235], v[50:53]
	s_waitcnt lgkmcnt(3)
	v_mfma_f32_16x16x32_bf16 v[54:57], v[216:219], v[236:239], v[54:57]
	s_waitcnt lgkmcnt(2)
	v_mfma_f32_16x16x32_bf16 v[34:37], v[216:219], v[240:243], v[34:37]
	s_waitcnt lgkmcnt(1)
	v_mfma_f32_16x16x32_bf16 v[38:41], v[216:219], v[252:255], v[38:41]
	s_waitcnt vmcnt(11)
	ds_write_b128 v164, v[200:203] offset:36864
	s_waitcnt vmcnt(10)
	ds_write_b128 v164, v[204:207] offset:41472
	v_mfma_f32_16x16x32_bf16 v[58:61], v[220:223], v[232:235], v[58:61]
	v_mfma_f32_16x16x32_bf16 v[62:65], v[220:223], v[236:239], v[62:65]
	v_mfma_f32_16x16x32_bf16 v[42:45], v[220:223], v[240:243], v[42:45]
	v_mfma_f32_16x16x32_bf16 v[46:49], v[220:223], v[252:255], v[46:49]
	s_waitcnt vmcnt(9)
	ds_write_b128 v164, v[208:211] offset:46080
	s_waitcnt vmcnt(8)
	ds_write_b128 v164, v[212:215] offset:50688
	v_mfma_f32_16x16x32_bf16 v[18:21], v[224:227], v[232:235], v[18:21]
	v_mfma_f32_16x16x32_bf16 v[22:25], v[224:227], v[236:239], v[22:25]
	v_mfma_f32_16x16x32_bf16 v[2:5], v[224:227], v[240:243], v[2:5]
	v_mfma_f32_16x16x32_bf16 v[6:9], v[224:227], v[252:255], v[6:9]
	s_waitcnt lgkmcnt(4)
	v_mfma_f32_16x16x32_bf16 v[26:29], v[228:231], v[232:235], v[26:29]
	v_mfma_f32_16x16x32_bf16 v[30:33], v[228:231], v[236:239], v[30:33]
	v_mfma_f32_16x16x32_bf16 v[10:13], v[228:231], v[240:243], v[10:13]
	v_mfma_f32_16x16x32_bf16 v[14:17], v[228:231], v[252:255], v[14:17]
	s_waitcnt lgkmcnt(0)
	s_barrier
	s_setprio 0
	global_load_dwordx4 v[180:183], v[70:71], off offset:1536
	global_load_dwordx4 v[188:191], v[68:69], off offset:1536
	global_load_dwordx4 v[192:195], v[66:67], off offset:1536
	global_load_dwordx4 v[196:199], v[72:73], off offset:1536
	global_load_dwordx4 v[200:203], v[74:75], off offset:1536
	global_load_dwordx4 v[204:207], v[76:77], off offset:1536
	global_load_dwordx4 v[208:211], v[78:79], off offset:1536
	global_load_dwordx4 v[212:215], v[80:81], off offset:1536
	ds_read_b128 v[232:235], v245 offset:36864
	ds_read_b128 v[216:219], v244
	ds_read_b128 v[236:239], v245 offset:39168
	ds_read_b128 v[240:243], v245 offset:41472
	ds_read_b128 v[252:255], v245 offset:43776
	ds_read_b128 v[220:223], v244 offset:2304
	ds_read_b128 v[224:227], v244 offset:4608
	ds_read_b128 v[228:231], v244 offset:6912
	s_waitcnt lgkmcnt(6)
	v_mfma_f32_16x16x32_bf16 v[50:53], v[216:219], v[232:235], v[50:53]
	s_waitcnt lgkmcnt(5)
	v_mfma_f32_16x16x32_bf16 v[54:57], v[216:219], v[236:239], v[54:57]
	s_waitcnt lgkmcnt(4)
	v_mfma_f32_16x16x32_bf16 v[34:37], v[216:219], v[240:243], v[34:37]
	s_waitcnt lgkmcnt(3)
	v_mfma_f32_16x16x32_bf16 v[38:41], v[216:219], v[252:255], v[38:41]
	ds_read_b128 v[216:219], v244 offset:64
	s_waitcnt lgkmcnt(3)
	v_mfma_f32_16x16x32_bf16 v[58:61], v[220:223], v[232:235], v[58:61]
	v_mfma_f32_16x16x32_bf16 v[62:65], v[220:223], v[236:239], v[62:65]
	v_mfma_f32_16x16x32_bf16 v[42:45], v[220:223], v[240:243], v[42:45]
	v_mfma_f32_16x16x32_bf16 v[46:49], v[220:223], v[252:255], v[46:49]
	ds_read_b128 v[220:223], v244 offset:2368
	s_setprio 1
	s_waitcnt vmcnt(15)
	ds_write_b128 v164, v[122:125] offset:18432
	s_waitcnt vmcnt(14)
	ds_write_b128 v164, v[126:129] offset:23040
	s_waitcnt lgkmcnt(5)
	v_mfma_f32_16x16x32_bf16 v[18:21], v[224:227], v[232:235], v[18:21]
	v_mfma_f32_16x16x32_bf16 v[22:25], v[224:227], v[236:239], v[22:25]
	v_mfma_f32_16x16x32_bf16 v[2:5], v[224:227], v[240:243], v[2:5]
	v_mfma_f32_16x16x32_bf16 v[6:9], v[224:227], v[252:255], v[6:9]
	ds_read_b128 v[224:227], v244 offset:4672
	s_waitcnt vmcnt(13)
	ds_write_b128 v164, v[136:139] offset:27648
	s_waitcnt vmcnt(12)
	ds_write_b128 v164, v[140:143] offset:32256
	s_waitcnt lgkmcnt(7)
	v_mfma_f32_16x16x32_bf16 v[26:29], v[228:231], v[232:235], v[26:29]
	ds_read_b128 v[232:235], v245 offset:36928
	v_mfma_f32_16x16x32_bf16 v[30:33], v[228:231], v[236:239], v[30:33]
	ds_read_b128 v[236:239], v245 offset:39232
	v_mfma_f32_16x16x32_bf16 v[10:13], v[228:231], v[240:243], v[10:13]
	ds_read_b128 v[240:243], v245 offset:41536
	v_mfma_f32_16x16x32_bf16 v[14:17], v[228:231], v[252:255], v[14:17]
	ds_read_b128 v[252:255], v245 offset:43840
	ds_read_b128 v[228:231], v244 offset:6976
	s_waitcnt lgkmcnt(4)
	v_mfma_f32_16x16x32_bf16 v[50:53], v[216:219], v[232:235], v[50:53]
	s_waitcnt lgkmcnt(3)
	v_mfma_f32_16x16x32_bf16 v[54:57], v[216:219], v[236:239], v[54:57]
	s_waitcnt lgkmcnt(2)
	v_mfma_f32_16x16x32_bf16 v[34:37], v[216:219], v[240:243], v[34:37]
	s_waitcnt lgkmcnt(1)
	v_mfma_f32_16x16x32_bf16 v[38:41], v[216:219], v[252:255], v[38:41]
	s_waitcnt vmcnt(11)
	ds_write_b128 v164, v[144:147] offset:55296
	s_waitcnt vmcnt(10)
	ds_write_b128 v164, v[148:151] offset:59904
	v_mfma_f32_16x16x32_bf16 v[58:61], v[220:223], v[232:235], v[58:61]
	v_mfma_f32_16x16x32_bf16 v[62:65], v[220:223], v[236:239], v[62:65]
	v_mfma_f32_16x16x32_bf16 v[42:45], v[220:223], v[240:243], v[42:45]
	v_mfma_f32_16x16x32_bf16 v[46:49], v[220:223], v[252:255], v[46:49]
	s_waitcnt vmcnt(9)
	ds_write_b128 v164, v[172:175] offset:64512
	s_waitcnt vmcnt(8)
	ds_write_b128 v165, v[176:179] offset:32256
	v_mfma_f32_16x16x32_bf16 v[18:21], v[224:227], v[232:235], v[18:21]
	v_mfma_f32_16x16x32_bf16 v[22:25], v[224:227], v[236:239], v[22:25]
	v_mfma_f32_16x16x32_bf16 v[2:5], v[224:227], v[240:243], v[2:5]
	v_mfma_f32_16x16x32_bf16 v[6:9], v[224:227], v[252:255], v[6:9]
	s_waitcnt lgkmcnt(4)
	v_mfma_f32_16x16x32_bf16 v[26:29], v[228:231], v[232:235], v[26:29]
	v_mfma_f32_16x16x32_bf16 v[30:33], v[228:231], v[236:239], v[30:33]
	v_mfma_f32_16x16x32_bf16 v[10:13], v[228:231], v[240:243], v[10:13]
	v_mfma_f32_16x16x32_bf16 v[14:17], v[228:231], v[252:255], v[14:17]
	s_waitcnt lgkmcnt(0)
	s_barrier
	s_setprio 0
	global_load_dwordx4 v[122:125], v[70:71], off offset:1664
	global_load_dwordx4 v[126:129], v[68:69], off offset:1664
	global_load_dwordx4 v[136:139], v[66:67], off offset:1664
	global_load_dwordx4 v[140:143], v[72:73], off offset:1664
	global_load_dwordx4 v[144:147], v[74:75], off offset:1664
	global_load_dwordx4 v[148:151], v[76:77], off offset:1664
	global_load_dwordx4 v[172:175], v[78:79], off offset:1664
	global_load_dwordx4 v[176:179], v[80:81], off offset:1664
	ds_read_b128 v[232:235], v245 offset:55296
	ds_read_b128 v[216:219], v244 offset:18432
	ds_read_b128 v[236:239], v245 offset:57600
	ds_read_b128 v[240:243], v245 offset:59904
	ds_read_b128 v[252:255], v245 offset:62208
	ds_read_b128 v[220:223], v244 offset:20736
	ds_read_b128 v[224:227], v244 offset:23040
	ds_read_b128 v[228:231], v244 offset:25344
	s_waitcnt lgkmcnt(6)
	v_mfma_f32_16x16x32_bf16 v[50:53], v[216:219], v[232:235], v[50:53]
	s_waitcnt lgkmcnt(5)
	v_mfma_f32_16x16x32_bf16 v[54:57], v[216:219], v[236:239], v[54:57]
	s_waitcnt lgkmcnt(4)
	v_mfma_f32_16x16x32_bf16 v[34:37], v[216:219], v[240:243], v[34:37]
	s_waitcnt lgkmcnt(3)
	v_mfma_f32_16x16x32_bf16 v[38:41], v[216:219], v[252:255], v[38:41]
	ds_read_b128 v[216:219], v244 offset:18496
	s_waitcnt lgkmcnt(3)
	v_mfma_f32_16x16x32_bf16 v[58:61], v[220:223], v[232:235], v[58:61]
	v_mfma_f32_16x16x32_bf16 v[62:65], v[220:223], v[236:239], v[62:65]
	v_mfma_f32_16x16x32_bf16 v[42:45], v[220:223], v[240:243], v[42:45]
	v_mfma_f32_16x16x32_bf16 v[46:49], v[220:223], v[252:255], v[46:49]
	ds_read_b128 v[220:223], v244 offset:20800
	s_setprio 1
	s_waitcnt vmcnt(15)
	ds_write_b128 v164, v[180:183]
	s_waitcnt vmcnt(14)
	ds_write_b128 v164, v[188:191] offset:4608
	s_waitcnt lgkmcnt(5)
	v_mfma_f32_16x16x32_bf16 v[18:21], v[224:227], v[232:235], v[18:21]
	v_mfma_f32_16x16x32_bf16 v[22:25], v[224:227], v[236:239], v[22:25]
	v_mfma_f32_16x16x32_bf16 v[2:5], v[224:227], v[240:243], v[2:5]
	v_mfma_f32_16x16x32_bf16 v[6:9], v[224:227], v[252:255], v[6:9]
	ds_read_b128 v[224:227], v244 offset:23104
	s_waitcnt vmcnt(13)
	ds_write_b128 v164, v[192:195] offset:9216
	s_waitcnt vmcnt(12)
	ds_write_b128 v164, v[196:199] offset:13824
	s_waitcnt lgkmcnt(7)
	v_mfma_f32_16x16x32_bf16 v[26:29], v[228:231], v[232:235], v[26:29]
	ds_read_b128 v[232:235], v245 offset:55360
	v_mfma_f32_16x16x32_bf16 v[30:33], v[228:231], v[236:239], v[30:33]
	ds_read_b128 v[236:239], v245 offset:57664
	v_mfma_f32_16x16x32_bf16 v[10:13], v[228:231], v[240:243], v[10:13]
	ds_read_b128 v[240:243], v245 offset:59968
	v_mfma_f32_16x16x32_bf16 v[14:17], v[228:231], v[252:255], v[14:17]
	ds_read_b128 v[252:255], v245 offset:62272
	ds_read_b128 v[228:231], v244 offset:25408
	s_waitcnt lgkmcnt(4)
	v_mfma_f32_16x16x32_bf16 v[50:53], v[216:219], v[232:235], v[50:53]
	s_waitcnt lgkmcnt(3)
	v_mfma_f32_16x16x32_bf16 v[54:57], v[216:219], v[236:239], v[54:57]
	s_waitcnt lgkmcnt(2)
	v_mfma_f32_16x16x32_bf16 v[34:37], v[216:219], v[240:243], v[34:37]
	s_waitcnt lgkmcnt(1)
	v_mfma_f32_16x16x32_bf16 v[38:41], v[216:219], v[252:255], v[38:41]
	s_waitcnt vmcnt(11)
	ds_write_b128 v164, v[200:203] offset:36864
	s_waitcnt vmcnt(10)
	ds_write_b128 v164, v[204:207] offset:41472
	v_mfma_f32_16x16x32_bf16 v[58:61], v[220:223], v[232:235], v[58:61]
	v_mfma_f32_16x16x32_bf16 v[62:65], v[220:223], v[236:239], v[62:65]
	v_mfma_f32_16x16x32_bf16 v[42:45], v[220:223], v[240:243], v[42:45]
	v_mfma_f32_16x16x32_bf16 v[46:49], v[220:223], v[252:255], v[46:49]
	s_waitcnt vmcnt(9)
	ds_write_b128 v164, v[208:211] offset:46080
	s_waitcnt vmcnt(8)
	ds_write_b128 v164, v[212:215] offset:50688
	v_mfma_f32_16x16x32_bf16 v[18:21], v[224:227], v[232:235], v[18:21]
	v_mfma_f32_16x16x32_bf16 v[22:25], v[224:227], v[236:239], v[22:25]
	v_mfma_f32_16x16x32_bf16 v[2:5], v[224:227], v[240:243], v[2:5]
	v_mfma_f32_16x16x32_bf16 v[6:9], v[224:227], v[252:255], v[6:9]
	s_waitcnt lgkmcnt(4)
	v_mfma_f32_16x16x32_bf16 v[26:29], v[228:231], v[232:235], v[26:29]
	v_mfma_f32_16x16x32_bf16 v[30:33], v[228:231], v[236:239], v[30:33]
	v_mfma_f32_16x16x32_bf16 v[10:13], v[228:231], v[240:243], v[10:13]
	v_mfma_f32_16x16x32_bf16 v[14:17], v[228:231], v[252:255], v[14:17]
	s_waitcnt lgkmcnt(0)
	s_barrier
	s_setprio 0
	global_load_dwordx4 v[180:183], v[70:71], off offset:1792
	global_load_dwordx4 v[188:191], v[68:69], off offset:1792
	global_load_dwordx4 v[192:195], v[66:67], off offset:1792
	global_load_dwordx4 v[196:199], v[72:73], off offset:1792
	global_load_dwordx4 v[200:203], v[74:75], off offset:1792
	global_load_dwordx4 v[204:207], v[76:77], off offset:1792
	global_load_dwordx4 v[208:211], v[78:79], off offset:1792
	global_load_dwordx4 v[212:215], v[80:81], off offset:1792
	ds_read_b128 v[232:235], v245 offset:36864
	ds_read_b128 v[216:219], v244
	ds_read_b128 v[236:239], v245 offset:39168
	ds_read_b128 v[240:243], v245 offset:41472
	ds_read_b128 v[252:255], v245 offset:43776
	ds_read_b128 v[220:223], v244 offset:2304
	ds_read_b128 v[224:227], v244 offset:4608
	ds_read_b128 v[228:231], v244 offset:6912
	s_waitcnt lgkmcnt(6)
	v_mfma_f32_16x16x32_bf16 v[50:53], v[216:219], v[232:235], v[50:53]
	s_waitcnt lgkmcnt(5)
	v_mfma_f32_16x16x32_bf16 v[54:57], v[216:219], v[236:239], v[54:57]
	s_waitcnt lgkmcnt(4)
	v_mfma_f32_16x16x32_bf16 v[34:37], v[216:219], v[240:243], v[34:37]
	s_waitcnt lgkmcnt(3)
	v_mfma_f32_16x16x32_bf16 v[38:41], v[216:219], v[252:255], v[38:41]
	ds_read_b128 v[216:219], v244 offset:64
	s_waitcnt lgkmcnt(3)
	v_mfma_f32_16x16x32_bf16 v[58:61], v[220:223], v[232:235], v[58:61]
	v_mfma_f32_16x16x32_bf16 v[62:65], v[220:223], v[236:239], v[62:65]
	v_mfma_f32_16x16x32_bf16 v[42:45], v[220:223], v[240:243], v[42:45]
	v_mfma_f32_16x16x32_bf16 v[46:49], v[220:223], v[252:255], v[46:49]
	ds_read_b128 v[220:223], v244 offset:2368
	s_setprio 1
	s_waitcnt vmcnt(15)
	ds_write_b128 v164, v[122:125] offset:18432
	s_waitcnt vmcnt(14)
	ds_write_b128 v164, v[126:129] offset:23040
	s_waitcnt lgkmcnt(5)
	v_mfma_f32_16x16x32_bf16 v[18:21], v[224:227], v[232:235], v[18:21]
	v_mfma_f32_16x16x32_bf16 v[22:25], v[224:227], v[236:239], v[22:25]
	v_mfma_f32_16x16x32_bf16 v[2:5], v[224:227], v[240:243], v[2:5]
	v_mfma_f32_16x16x32_bf16 v[6:9], v[224:227], v[252:255], v[6:9]
	ds_read_b128 v[224:227], v244 offset:4672
	s_waitcnt vmcnt(13)
	ds_write_b128 v164, v[136:139] offset:27648
	s_waitcnt vmcnt(12)
	ds_write_b128 v164, v[140:143] offset:32256
	s_waitcnt lgkmcnt(7)
	v_mfma_f32_16x16x32_bf16 v[26:29], v[228:231], v[232:235], v[26:29]
	ds_read_b128 v[232:235], v245 offset:36928
	v_mfma_f32_16x16x32_bf16 v[30:33], v[228:231], v[236:239], v[30:33]
	ds_read_b128 v[236:239], v245 offset:39232
	v_mfma_f32_16x16x32_bf16 v[10:13], v[228:231], v[240:243], v[10:13]
	ds_read_b128 v[240:243], v245 offset:41536
	v_mfma_f32_16x16x32_bf16 v[14:17], v[228:231], v[252:255], v[14:17]
	ds_read_b128 v[252:255], v245 offset:43840
	ds_read_b128 v[228:231], v244 offset:6976
	s_waitcnt lgkmcnt(4)
	v_mfma_f32_16x16x32_bf16 v[50:53], v[216:219], v[232:235], v[50:53]
	s_waitcnt lgkmcnt(3)
	v_mfma_f32_16x16x32_bf16 v[54:57], v[216:219], v[236:239], v[54:57]
	s_waitcnt lgkmcnt(2)
	v_mfma_f32_16x16x32_bf16 v[34:37], v[216:219], v[240:243], v[34:37]
	s_waitcnt lgkmcnt(1)
	v_mfma_f32_16x16x32_bf16 v[38:41], v[216:219], v[252:255], v[38:41]
	s_waitcnt vmcnt(11)
	ds_write_b128 v164, v[144:147] offset:55296
	s_waitcnt vmcnt(10)
	ds_write_b128 v164, v[148:151] offset:59904
	v_mfma_f32_16x16x32_bf16 v[58:61], v[220:223], v[232:235], v[58:61]
	v_mfma_f32_16x16x32_bf16 v[62:65], v[220:223], v[236:239], v[62:65]
	v_mfma_f32_16x16x32_bf16 v[42:45], v[220:223], v[240:243], v[42:45]
	v_mfma_f32_16x16x32_bf16 v[46:49], v[220:223], v[252:255], v[46:49]
	s_waitcnt vmcnt(9)
	ds_write_b128 v164, v[172:175] offset:64512
	s_waitcnt vmcnt(8)
	ds_write_b128 v165, v[176:179] offset:32256
	v_mfma_f32_16x16x32_bf16 v[18:21], v[224:227], v[232:235], v[18:21]
	v_mfma_f32_16x16x32_bf16 v[22:25], v[224:227], v[236:239], v[22:25]
	v_mfma_f32_16x16x32_bf16 v[2:5], v[224:227], v[240:243], v[2:5]
	v_mfma_f32_16x16x32_bf16 v[6:9], v[224:227], v[252:255], v[6:9]
	s_waitcnt lgkmcnt(4)
	v_mfma_f32_16x16x32_bf16 v[26:29], v[228:231], v[232:235], v[26:29]
	v_mfma_f32_16x16x32_bf16 v[30:33], v[228:231], v[236:239], v[30:33]
	v_mfma_f32_16x16x32_bf16 v[10:13], v[228:231], v[240:243], v[10:13]
	v_mfma_f32_16x16x32_bf16 v[14:17], v[228:231], v[252:255], v[14:17]
	s_waitcnt lgkmcnt(0)
	s_barrier
	s_setprio 0
	global_load_dwordx4 v[122:125], v[70:71], off offset:1920
	s_nop 0
	global_load_dwordx4 v[68:71], v[68:69], off offset:1920
	s_nop 0
	global_load_dwordx4 v[126:129], v[66:67], off offset:1920
	global_load_dwordx4 v[136:139], v[72:73], off offset:1920
	s_nop 0
	global_load_dwordx4 v[72:75], v[74:75], off offset:1920
	s_nop 0
	global_load_dwordx4 v[140:143], v[76:77], off offset:1920
	s_nop 0
	global_load_dwordx4 v[76:79], v[78:79], off offset:1920
	s_nop 0
	global_load_dwordx4 v[144:147], v[80:81], off offset:1920
	ds_read_b128 v[232:235], v245 offset:55296
	ds_read_b128 v[216:219], v244 offset:18432
	ds_read_b128 v[236:239], v245 offset:57600
	ds_read_b128 v[240:243], v245 offset:59904
	ds_read_b128 v[252:255], v245 offset:62208
	ds_read_b128 v[220:223], v244 offset:20736
	ds_read_b128 v[224:227], v244 offset:23040
	ds_read_b128 v[228:231], v244 offset:25344
	s_waitcnt lgkmcnt(6)
	v_mfma_f32_16x16x32_bf16 v[50:53], v[216:219], v[232:235], v[50:53]
	s_waitcnt lgkmcnt(5)
	v_mfma_f32_16x16x32_bf16 v[54:57], v[216:219], v[236:239], v[54:57]
	s_waitcnt lgkmcnt(4)
	v_mfma_f32_16x16x32_bf16 v[34:37], v[216:219], v[240:243], v[34:37]
	s_waitcnt lgkmcnt(3)
	v_mfma_f32_16x16x32_bf16 v[38:41], v[216:219], v[252:255], v[38:41]
	ds_read_b128 v[216:219], v244 offset:18496
	s_waitcnt lgkmcnt(3)
	v_mfma_f32_16x16x32_bf16 v[58:61], v[220:223], v[232:235], v[58:61]
	v_mfma_f32_16x16x32_bf16 v[62:65], v[220:223], v[236:239], v[62:65]
	v_mfma_f32_16x16x32_bf16 v[42:45], v[220:223], v[240:243], v[42:45]
	v_mfma_f32_16x16x32_bf16 v[46:49], v[220:223], v[252:255], v[46:49]
	ds_read_b128 v[220:223], v244 offset:20800
	s_setprio 1
	s_waitcnt vmcnt(15)
	ds_write_b128 v164, v[180:183]
	s_waitcnt vmcnt(14)
	ds_write_b128 v164, v[188:191] offset:4608
	s_waitcnt lgkmcnt(5)
	v_mfma_f32_16x16x32_bf16 v[18:21], v[224:227], v[232:235], v[18:21]
	v_mfma_f32_16x16x32_bf16 v[22:25], v[224:227], v[236:239], v[22:25]
	v_mfma_f32_16x16x32_bf16 v[2:5], v[224:227], v[240:243], v[2:5]
	v_mfma_f32_16x16x32_bf16 v[6:9], v[224:227], v[252:255], v[6:9]
	ds_read_b128 v[224:227], v244 offset:23104
	s_waitcnt vmcnt(13)
	ds_write_b128 v164, v[192:195] offset:9216
	s_waitcnt vmcnt(12)
	ds_write_b128 v164, v[196:199] offset:13824
	s_waitcnt lgkmcnt(7)
	v_mfma_f32_16x16x32_bf16 v[26:29], v[228:231], v[232:235], v[26:29]
	ds_read_b128 v[232:235], v245 offset:55360
	v_mfma_f32_16x16x32_bf16 v[30:33], v[228:231], v[236:239], v[30:33]
	ds_read_b128 v[236:239], v245 offset:57664
	v_mfma_f32_16x16x32_bf16 v[10:13], v[228:231], v[240:243], v[10:13]
	ds_read_b128 v[240:243], v245 offset:59968
	v_mfma_f32_16x16x32_bf16 v[14:17], v[228:231], v[252:255], v[14:17]
	ds_read_b128 v[252:255], v245 offset:62272
	ds_read_b128 v[228:231], v244 offset:25408
	s_waitcnt lgkmcnt(4)
	v_mfma_f32_16x16x32_bf16 v[50:53], v[216:219], v[232:235], v[50:53]
	s_waitcnt lgkmcnt(3)
	v_mfma_f32_16x16x32_bf16 v[54:57], v[216:219], v[236:239], v[54:57]
	s_waitcnt lgkmcnt(2)
	v_mfma_f32_16x16x32_bf16 v[34:37], v[216:219], v[240:243], v[34:37]
	s_waitcnt lgkmcnt(1)
	v_mfma_f32_16x16x32_bf16 v[38:41], v[216:219], v[252:255], v[38:41]
	s_waitcnt vmcnt(11)
	ds_write_b128 v164, v[200:203] offset:36864
	s_waitcnt vmcnt(10)
	ds_write_b128 v164, v[204:207] offset:41472
	v_mfma_f32_16x16x32_bf16 v[58:61], v[220:223], v[232:235], v[58:61]
	v_mfma_f32_16x16x32_bf16 v[62:65], v[220:223], v[236:239], v[62:65]
	v_mfma_f32_16x16x32_bf16 v[42:45], v[220:223], v[240:243], v[42:45]
	v_mfma_f32_16x16x32_bf16 v[46:49], v[220:223], v[252:255], v[46:49]
	s_waitcnt vmcnt(9)
	ds_write_b128 v164, v[208:211] offset:46080
	s_waitcnt vmcnt(8)
	ds_write_b128 v164, v[212:215] offset:50688
	v_mfma_f32_16x16x32_bf16 v[18:21], v[224:227], v[232:235], v[18:21]
	v_mfma_f32_16x16x32_bf16 v[22:25], v[224:227], v[236:239], v[22:25]
	v_mfma_f32_16x16x32_bf16 v[2:5], v[224:227], v[240:243], v[2:5]
	v_mfma_f32_16x16x32_bf16 v[6:9], v[224:227], v[252:255], v[6:9]
	s_waitcnt lgkmcnt(4)
	v_mfma_f32_16x16x32_bf16 v[26:29], v[228:231], v[232:235], v[26:29]
	v_mfma_f32_16x16x32_bf16 v[30:33], v[228:231], v[236:239], v[30:33]
	v_mfma_f32_16x16x32_bf16 v[10:13], v[228:231], v[240:243], v[10:13]
	v_mfma_f32_16x16x32_bf16 v[14:17], v[228:231], v[252:255], v[14:17]
	s_waitcnt lgkmcnt(0)
	s_barrier
	s_setprio 0
	ds_read_b128 v[232:235], v245 offset:36864
	ds_read_b128 v[216:219], v244
	ds_read_b128 v[236:239], v245 offset:39168
	ds_read_b128 v[240:243], v245 offset:41472
	ds_read_b128 v[252:255], v245 offset:43776
	ds_read_b128 v[220:223], v244 offset:2304
	ds_read_b128 v[224:227], v244 offset:4608
	ds_read_b128 v[228:231], v244 offset:6912
	s_waitcnt lgkmcnt(6)
	v_mfma_f32_16x16x32_bf16 v[50:53], v[216:219], v[232:235], v[50:53]
	s_waitcnt lgkmcnt(5)
	v_mfma_f32_16x16x32_bf16 v[54:57], v[216:219], v[236:239], v[54:57]
	s_waitcnt lgkmcnt(4)
	v_mfma_f32_16x16x32_bf16 v[34:37], v[216:219], v[240:243], v[34:37]
	s_waitcnt lgkmcnt(3)
	v_mfma_f32_16x16x32_bf16 v[38:41], v[216:219], v[252:255], v[38:41]
	ds_read_b128 v[216:219], v244 offset:64
	s_waitcnt lgkmcnt(3)
	v_mfma_f32_16x16x32_bf16 v[58:61], v[220:223], v[232:235], v[58:61]
	v_mfma_f32_16x16x32_bf16 v[62:65], v[220:223], v[236:239], v[62:65]
	v_mfma_f32_16x16x32_bf16 v[42:45], v[220:223], v[240:243], v[42:45]
	v_mfma_f32_16x16x32_bf16 v[46:49], v[220:223], v[252:255], v[46:49]
	ds_read_b128 v[220:223], v244 offset:2368
	s_setprio 1
	s_waitcnt vmcnt(7)
	ds_write_b128 v164, v[122:125] offset:18432
	s_waitcnt vmcnt(6)
	ds_write_b128 v164, v[68:71] offset:23040
	s_waitcnt lgkmcnt(5)
	v_mfma_f32_16x16x32_bf16 v[18:21], v[224:227], v[232:235], v[18:21]
	v_mfma_f32_16x16x32_bf16 v[22:25], v[224:227], v[236:239], v[22:25]
	v_mfma_f32_16x16x32_bf16 v[2:5], v[224:227], v[240:243], v[2:5]
	v_mfma_f32_16x16x32_bf16 v[6:9], v[224:227], v[252:255], v[6:9]
	ds_read_b128 v[224:227], v244 offset:4672
	s_waitcnt vmcnt(5)
	ds_write_b128 v164, v[126:129] offset:27648
	s_waitcnt vmcnt(4)
	ds_write_b128 v164, v[136:139] offset:32256
	s_waitcnt lgkmcnt(7)
	v_mfma_f32_16x16x32_bf16 v[26:29], v[228:231], v[232:235], v[26:29]
	ds_read_b128 v[232:235], v245 offset:36928
	v_mfma_f32_16x16x32_bf16 v[30:33], v[228:231], v[236:239], v[30:33]
	ds_read_b128 v[236:239], v245 offset:39232
	v_mfma_f32_16x16x32_bf16 v[10:13], v[228:231], v[240:243], v[10:13]
	ds_read_b128 v[240:243], v245 offset:41536
	v_mfma_f32_16x16x32_bf16 v[14:17], v[228:231], v[252:255], v[14:17]
	ds_read_b128 v[252:255], v245 offset:43840
	ds_read_b128 v[228:231], v244 offset:6976
	s_waitcnt lgkmcnt(4)
	v_mfma_f32_16x16x32_bf16 v[50:53], v[216:219], v[232:235], v[50:53]
	s_waitcnt lgkmcnt(3)
	v_mfma_f32_16x16x32_bf16 v[54:57], v[216:219], v[236:239], v[54:57]
	s_waitcnt lgkmcnt(2)
	v_mfma_f32_16x16x32_bf16 v[34:37], v[216:219], v[240:243], v[34:37]
	s_waitcnt lgkmcnt(1)
	v_mfma_f32_16x16x32_bf16 v[38:41], v[216:219], v[252:255], v[38:41]
	s_waitcnt vmcnt(3)
	ds_write_b128 v164, v[72:75] offset:55296
	s_waitcnt vmcnt(2)
	ds_write_b128 v164, v[140:143] offset:59904
	v_mfma_f32_16x16x32_bf16 v[58:61], v[220:223], v[232:235], v[58:61]
	v_mfma_f32_16x16x32_bf16 v[62:65], v[220:223], v[236:239], v[62:65]
	v_mfma_f32_16x16x32_bf16 v[42:45], v[220:223], v[240:243], v[42:45]
	v_mfma_f32_16x16x32_bf16 v[46:49], v[220:223], v[252:255], v[46:49]
	s_waitcnt vmcnt(1)
	ds_write_b128 v164, v[76:79] offset:64512
	s_waitcnt vmcnt(0)
	ds_write_b128 v165, v[144:147] offset:32256
	v_mfma_f32_16x16x32_bf16 v[18:21], v[224:227], v[232:235], v[18:21]
	v_mfma_f32_16x16x32_bf16 v[22:25], v[224:227], v[236:239], v[22:25]
	v_mfma_f32_16x16x32_bf16 v[2:5], v[224:227], v[240:243], v[2:5]
	v_mfma_f32_16x16x32_bf16 v[6:9], v[224:227], v[252:255], v[6:9]
	s_waitcnt lgkmcnt(4)
	v_mfma_f32_16x16x32_bf16 v[26:29], v[228:231], v[232:235], v[26:29]
	v_mfma_f32_16x16x32_bf16 v[30:33], v[228:231], v[236:239], v[30:33]
	v_mfma_f32_16x16x32_bf16 v[10:13], v[228:231], v[240:243], v[10:13]
	v_mfma_f32_16x16x32_bf16 v[14:17], v[228:231], v[252:255], v[14:17]
	s_waitcnt lgkmcnt(0)
	s_barrier
	s_setprio 0
	ds_read_b128 v[232:235], v245 offset:55296
	ds_read_b128 v[216:219], v244 offset:18432
	ds_read_b128 v[236:239], v245 offset:57600
	ds_read_b128 v[240:243], v245 offset:59904
	ds_read_b128 v[252:255], v245 offset:62208
	ds_read_b128 v[220:223], v244 offset:20736
	ds_read_b128 v[224:227], v244 offset:23040
	ds_read_b128 v[228:231], v244 offset:25344
	s_waitcnt lgkmcnt(6)
	v_mfma_f32_16x16x32_bf16 v[50:53], v[216:219], v[232:235], v[50:53]
	s_waitcnt lgkmcnt(5)
	v_mfma_f32_16x16x32_bf16 v[54:57], v[216:219], v[236:239], v[54:57]
	s_waitcnt lgkmcnt(4)
	v_mfma_f32_16x16x32_bf16 v[34:37], v[216:219], v[240:243], v[34:37]
	s_waitcnt lgkmcnt(3)
	v_mfma_f32_16x16x32_bf16 v[38:41], v[216:219], v[252:255], v[38:41]
	ds_read_b128 v[216:219], v244 offset:18496
	s_waitcnt lgkmcnt(3)
	v_mfma_f32_16x16x32_bf16 v[58:61], v[220:223], v[232:235], v[58:61]
	v_mfma_f32_16x16x32_bf16 v[62:65], v[220:223], v[236:239], v[62:65]
	v_mfma_f32_16x16x32_bf16 v[42:45], v[220:223], v[240:243], v[42:45]
	v_mfma_f32_16x16x32_bf16 v[46:49], v[220:223], v[252:255], v[46:49]
	ds_read_b128 v[220:223], v244 offset:20800
	s_waitcnt lgkmcnt(3)
	v_mfma_f32_16x16x32_bf16 v[18:21], v[224:227], v[232:235], v[18:21]
	v_mfma_f32_16x16x32_bf16 v[22:25], v[224:227], v[236:239], v[22:25]
	v_mfma_f32_16x16x32_bf16 v[2:5], v[224:227], v[240:243], v[2:5]
	v_mfma_f32_16x16x32_bf16 v[6:9], v[224:227], v[252:255], v[6:9]
	ds_read_b128 v[224:227], v244 offset:23104
	s_waitcnt lgkmcnt(3)
	v_mfma_f32_16x16x32_bf16 v[26:29], v[228:231], v[232:235], v[26:29]
	ds_read_b128 v[232:235], v245 offset:55360
	v_mfma_f32_16x16x32_bf16 v[30:33], v[228:231], v[236:239], v[30:33]
	ds_read_b128 v[236:239], v245 offset:57664
	v_mfma_f32_16x16x32_bf16 v[10:13], v[228:231], v[240:243], v[10:13]
	ds_read_b128 v[240:243], v245 offset:59968
	v_mfma_f32_16x16x32_bf16 v[14:17], v[228:231], v[252:255], v[14:17]
	ds_read_b128 v[252:255], v245 offset:62272
	ds_read_b128 v[228:231], v244 offset:25408
	s_waitcnt lgkmcnt(4)
	v_mfma_f32_16x16x32_bf16 v[50:53], v[216:219], v[232:235], v[50:53]
	s_waitcnt lgkmcnt(3)
	v_mfma_f32_16x16x32_bf16 v[54:57], v[216:219], v[236:239], v[54:57]
	s_waitcnt lgkmcnt(2)
	v_mfma_f32_16x16x32_bf16 v[34:37], v[216:219], v[240:243], v[34:37]
	s_waitcnt lgkmcnt(1)
	v_mfma_f32_16x16x32_bf16 v[38:41], v[216:219], v[252:255], v[38:41]
	v_mfma_f32_16x16x32_bf16 v[58:61], v[220:223], v[232:235], v[58:61]
	v_mfma_f32_16x16x32_bf16 v[62:65], v[220:223], v[236:239], v[62:65]
	v_mfma_f32_16x16x32_bf16 v[42:45], v[220:223], v[240:243], v[42:45]
	v_mfma_f32_16x16x32_bf16 v[46:49], v[220:223], v[252:255], v[46:49]
	v_mfma_f32_16x16x32_bf16 v[18:21], v[224:227], v[232:235], v[18:21]
	v_mfma_f32_16x16x32_bf16 v[22:25], v[224:227], v[236:239], v[22:25]
	v_mfma_f32_16x16x32_bf16 v[2:5], v[224:227], v[240:243], v[2:5]
	v_mfma_f32_16x16x32_bf16 v[6:9], v[224:227], v[252:255], v[6:9]
	s_waitcnt lgkmcnt(0)
	v_mfma_f32_16x16x32_bf16 v[26:29], v[228:231], v[232:235], v[26:29]
	v_mfma_f32_16x16x32_bf16 v[30:33], v[228:231], v[236:239], v[30:33]
	v_mfma_f32_16x16x32_bf16 v[10:13], v[228:231], v[240:243], v[10:13]
	v_mfma_f32_16x16x32_bf16 v[14:17], v[228:231], v[252:255], v[14:17]
	s_waitcnt lgkmcnt(0)
	s_barrier
	s_nop 7
	v_permlane16_swap_b32_e32 v50, v54
	v_permlane16_swap_b32_e32 v51, v55
	v_permlane16_swap_b32_e32 v52, v56
	v_permlane16_swap_b32_e32 v53, v57
	v_permlane16_swap_b32_e32 v58, v62
	v_permlane16_swap_b32_e32 v59, v63
	v_permlane16_swap_b32_e32 v60, v64
	v_permlane16_swap_b32_e32 v61, v65
	v_permlane16_swap_b32_e32 v34, v38
	v_permlane16_swap_b32_e32 v35, v39
	v_permlane16_swap_b32_e32 v36, v40
	v_permlane16_swap_b32_e32 v37, v41
	v_permlane16_swap_b32_e32 v42, v46
	v_permlane16_swap_b32_e32 v43, v47
	v_permlane16_swap_b32_e32 v44, v48
	v_permlane16_swap_b32_e32 v45, v49
	v_permlane16_swap_b32_e32 v18, v22
	v_permlane16_swap_b32_e32 v19, v23
	v_permlane16_swap_b32_e32 v20, v24
	v_permlane16_swap_b32_e32 v21, v25
	v_permlane16_swap_b32_e32 v26, v30
	v_permlane16_swap_b32_e32 v27, v31
	v_permlane16_swap_b32_e32 v28, v32
	v_permlane16_swap_b32_e32 v29, v33
	v_permlane16_swap_b32_e32 v2, v6
	v_permlane16_swap_b32_e32 v3, v7
	v_permlane16_swap_b32_e32 v4, v8
	v_permlane16_swap_b32_e32 v5, v9
	v_permlane16_swap_b32_e32 v10, v14
	v_permlane16_swap_b32_e32 v11, v15
	v_permlane16_swap_b32_e32 v12, v16
	v_permlane16_swap_b32_e32 v13, v17
	v_permlane32_swap_b32_e32 v50, v54
	v_permlane32_swap_b32_e32 v51, v55
	v_permlane32_swap_b32_e32 v52, v56
	v_permlane32_swap_b32_e32 v53, v57
	v_permlane32_swap_b32_e32 v58, v62
	v_permlane32_swap_b32_e32 v59, v63
	v_permlane32_swap_b32_e32 v60, v64
	v_permlane32_swap_b32_e32 v61, v65
	v_permlane32_swap_b32_e32 v34, v38
	v_permlane32_swap_b32_e32 v35, v39
	v_permlane32_swap_b32_e32 v36, v40
	v_permlane32_swap_b32_e32 v37, v41
	v_permlane32_swap_b32_e32 v42, v46
	v_permlane32_swap_b32_e32 v43, v47
	v_permlane32_swap_b32_e32 v44, v48
	v_permlane32_swap_b32_e32 v45, v49
	v_permlane32_swap_b32_e32 v18, v22
	v_permlane32_swap_b32_e32 v19, v23
	v_permlane32_swap_b32_e32 v20, v24
	v_permlane32_swap_b32_e32 v21, v25
	v_permlane32_swap_b32_e32 v26, v30
	v_permlane32_swap_b32_e32 v27, v31
	v_permlane32_swap_b32_e32 v28, v32
	v_permlane32_swap_b32_e32 v29, v33
	v_permlane32_swap_b32_e32 v2, v6
	v_permlane32_swap_b32_e32 v3, v7
	v_permlane32_swap_b32_e32 v4, v8
	v_permlane32_swap_b32_e32 v5, v9
	v_permlane32_swap_b32_e32 v10, v14
	v_permlane32_swap_b32_e32 v11, v15
	v_permlane32_swap_b32_e32 v12, v16
	v_permlane32_swap_b32_e32 v13, v17

.LBB0_1446:
	s_add_i32 s0, s37, 0xfffffe00
	s_cmpk_lt_i32 s37, 0x200
	s_cselect_b64 s[12:13], -1, 0
	s_and_b64 s[12:13], s[12:13], exec
	s_cselect_b32 s14, s37, s0
	s_cselect_b32 s38, 0x43, 3
	s_lshr_b32 s15, s14, 2
	s_cmpk_lt_i32 s37, 0x200
	s_cselect_b64 s[12:13], -1, 0
	s_and_b64 s[12:13], s[12:13], exec
	s_cselect_b32 s15, s37, s15
	s_bfe_u32 s14, s14, 0x10002
	s_ashr_i32 s18, s0, 4
	s_cmpk_lt_i32 s37, 0x200
	s_cselect_b64 s[12:13], -1, 0
	s_and_b64 s[12:13], s[12:13], exec
	s_cselect_b32 s19, s14, s18
	s_and_b32 s21, s15, 3
	s_lshl_b32 s33, s21, 7
	s_lshl_b32 s0, s19, 9
	s_or_b32 s12, s33, s0
	s_ashr_i32 s13, s12, 31
	s_lshl_b64 s[14:15], s[12:13], 12
	s_add_u32 s0, s14, 0x200000
	s_addc_u32 s16, s15, 0
	s_lshl_b64 s[12:13], s[12:13], 8
	s_cmpk_lt_i32 s37, 0x200
	s_cselect_b64 s[14:15], -1, 0
	s_and_b64 s[14:15], s[14:15], exec
	s_cselect_b32 s20, -4, 0
	s_cselect_b32 s15, s16, s13
	s_cselect_b32 s14, s0, s12
	s_lshl_b32 s0, s19, 3
	s_or_b32 s0, s0, s21
	s_or_b32 s25, s0, 4
	s_lshl_b32 s12, s25, 7
	s_ashr_i32 s13, s12, 31
	s_lshl_b64 s[12:13], s[12:13], 9
	s_add_u32 s12, s28, s12
	s_addc_u32 s13, s29, s13
	s_lshl_b64 s[14:15], s[14:15], 1
	s_add_u32 s14, s34, s14
	s_addc_u32 s15, s35, s15
	s_lshl_b32 s0, s20, 6
	s_lshl_b64 s[16:17], s[0:1], 1
	s_add_u32 s0, s14, s16
	s_addc_u32 s23, s15, s17
	s_cmpk_lt_i32 s37, 0x200
	s_cselect_b64 s[16:17], -1, 0
	s_and_b64 s[16:17], s[16:17], exec
	s_cselect_b32 s22, s12, s0
	s_cselect_b32 s23, s13, s23
	s_lshl_b32 s0, s19, 12
	s_addk_i32 s0, 0x1000
	s_lshl_b32 s18, s18, 8
	s_cmpk_lt_i32 s37, 0x200
	s_cselect_b64 s[16:17], -1, 0
	s_and_b64 s[16:17], s[16:17], exec
	s_cselect_b32 s24, s0, s18
	s_lshl_b32 s16, s25, 8
	s_ashr_i32 s17, s16, 31
	s_lshl_b32 s0, s21, 8
	s_lshl_b64 s[16:17], s[16:17], 8
	s_add_u32 s16, s26, s16
	s_addc_u32 s17, s27, s17
	s_ashr_i32 s25, s24, 31
	s_lshl_b64 s[18:19], s[24:25], 10
	s_add_u32 s18, s30, s18
	s_addc_u32 s19, s31, s19
	s_mov_b32 s21, s1
	s_add_u32 s18, s18, s0
	s_addc_u32 s19, s19, 0
	s_lshl_b64 s[20:21], s[20:21], 16
	s_add_u32 s25, s18, s20
	s_addc_u32 s40, s19, s21
	s_cmpk_lt_i32 s37, 0x200
	s_cselect_b64 s[20:21], -1, 0
	s_and_b64 s[20:21], s[20:21], exec
	s_cselect_b32 s39, 4, 0
	s_cselect_b32 s41, 12, 8
	s_cselect_b32 s21, s17, s40
	s_cselect_b32 s20, s16, s25
	s_lshr_b32 s25, s37, 3
	s_and_b32 s40, s37, 3
	s_cmpk_lt_i32 s37, 0x200
	s_cselect_b64 vcc, -1, 0
	v_cndmask_b32_e32 v82, v139, v135, vcc
	v_cndmask_b32_e32 v158, v164, v167, vcc
	v_cndmask_b32_e32 v160, v145, v166, vcc
	v_cndmask_b32_e32 v162, v143, v165, vcc
	v_lshlrev_b32_e32 v2, 1, v82
	v_lshlrev_b32_e32 v4, 1, v162
	v_lshlrev_b32_e32 v5, 1, v160
	v_lshlrev_b32_e32 v6, 1, v158
	global_load_dwordx4 v[14:17], v2, s[20:21]
	global_load_dwordx4 v[18:21], v197, s[22:23]
	global_load_dwordx4 v[22:25], v4, s[20:21]
	global_load_dwordx4 v[26:29], v198, s[22:23]
	global_load_dwordx4 v[30:33], v5, s[20:21]
	global_load_dwordx4 v[34:37], v199, s[22:23]
	global_load_dwordx4 v[38:41], v6, s[20:21]
	global_load_dwordx4 v[42:45], v200, s[22:23]
	s_and_b64 s[20:21], vcc, exec
	s_cselect_b32 s20, s25, s40
	s_lshl_b32 s20, s20, 6
	s_add_i32 s20, s24, s20
	v_or_b32_e32 v46, s20, v137
	v_ashrrev_i32_e32 v47, 31, v46
	v_lshlrev_b64 v[4:5], 10, v[46:47]
	v_lshl_add_u64 v[4:5], s[6:7], 0, v[4:5]
	v_lshl_add_u64 v[154:155], v[4:5], 0, s[0:1]
	v_lshl_add_u64 v[4:5], v[154:155], 0, v[148:149]
	v_lshl_add_u64 v[4:5], v[4:5], 0, v[152:153]
	global_load_dwordx4 v[126:129], v[4:5], off
	global_load_dwordx4 v[122:125], v[4:5], off offset:32
	global_load_dwordx4 v[118:121], v[4:5], off offset:64
	global_load_dwordx4 v[114:117], v[4:5], off offset:96
	v_mov_b32_e32 v2, v3
	v_mov_b32_e32 v4, v3
	v_mov_b32_e32 v5, v3
	v_mov_b32_e32 v6, v3
	v_mov_b32_e32 v7, v3
	v_mov_b32_e32 v8, v3
	v_mov_b32_e32 v9, v3
	v_mov_b32_e32 v10, v3
	v_mov_b32_e32 v11, v3
	v_mov_b32_e32 v12, v3
	v_mov_b32_e32 v13, v3
	v_lshlrev_b64 v[156:157], 9, v[46:47]
	v_lshl_or_b32 v203, v169, s41, v141
	v_lshl_or_b32 v204, v185, s41, v141
	v_lshl_or_b32 v205, v192, s41, v141
	v_lshl_or_b32 v206, v172, s41, v141
	s_sub_i32 s40, 1, s39
	v_mov_b32_e32 v151, 0xff800000
	s_mov_b32 s42, s1
	s_setprio 1
	s_waitcnt vmcnt(11)
	ds_write_b128 v180, v[14:17]
	s_waitcnt vmcnt(10)
	ds_write_b128 v182, v[18:21]
	s_waitcnt vmcnt(9)
	ds_write_b128 v184, v[22:25]
	s_waitcnt vmcnt(8)
	ds_write_b128 v189, v[26:29]
	s_waitcnt vmcnt(7)
	ds_write_b128 v191, v[30:33]
	s_waitcnt vmcnt(6)
	ds_write_b128 v194, v[34:37]
	s_waitcnt vmcnt(5)
	ds_write_b128 v195, v[38:41]
	s_waitcnt vmcnt(4)
	ds_write_b128 v196, v[42:45]
	v_mov_b32_e32 v16, v3
	v_mov_b32_e32 v17, v3
	v_mov_b32_e32 v14, v3
	v_mov_b32_e32 v15, v3
	v_mov_b64_e32 v[32:33], v[16:17]
	v_mov_b64_e32 v[48:49], v[16:17]
	v_mov_b64_e32 v[64:65], v[16:17]
	v_mov_b64_e32 v[80:81], v[16:17]
	v_mov_b64_e32 v[30:31], v[14:15]
	v_mov_b64_e32 v[28:29], v[12:13]
	v_mov_b64_e32 v[26:27], v[10:11]
	v_mov_b64_e32 v[24:25], v[8:9]
	v_mov_b64_e32 v[22:23], v[6:7]
	v_mov_b64_e32 v[20:21], v[4:5]
	v_mov_b64_e32 v[18:19], v[2:3]
	v_mov_b64_e32 v[46:47], v[14:15]
	v_mov_b64_e32 v[44:45], v[12:13]
	v_mov_b64_e32 v[42:43], v[10:11]
	v_mov_b64_e32 v[40:41], v[8:9]
	v_mov_b64_e32 v[38:39], v[6:7]
	v_mov_b64_e32 v[36:37], v[4:5]
	v_mov_b64_e32 v[34:35], v[2:3]
	v_mov_b64_e32 v[62:63], v[14:15]
	v_mov_b64_e32 v[60:61], v[12:13]
	v_mov_b64_e32 v[58:59], v[10:11]
	v_mov_b64_e32 v[56:57], v[8:9]
	v_mov_b64_e32 v[54:55], v[6:7]
	v_mov_b64_e32 v[52:53], v[4:5]
	v_mov_b64_e32 v[50:51], v[2:3]
	v_mov_b64_e32 v[78:79], v[14:15]
	v_mov_b64_e32 v[76:77], v[12:13]
	v_mov_b64_e32 v[74:75], v[10:11]
	v_mov_b64_e32 v[72:73], v[8:9]
	v_mov_b64_e32 v[70:71], v[6:7]
	v_mov_b64_e32 v[68:69], v[4:5]
	v_mov_b64_e32 v[66:67], v[2:3]
	v_mov_b32_e32 v10, v138
	v_mov_b32_e32 v8, v140
	v_mov_b32_e32 v6, v142
	v_mov_b32_e32 v4, v144
	v_mov_b32_e32 v2, v82
	s_waitcnt lgkmcnt(0)
	s_barrier
	s_setprio 0

.LBB0_1476:
	v_lshlrev_b64 v[154:155], 9, v[2:3]
	v_mul_u32_u24_e32 v2, s48, v157
	v_lshlrev_b32_e32 v138, 1, v2
	v_lshl_add_u64 v[2:3], s[44:45], 0, v[138:139]
	v_lshl_add_u64 v[2:3], v[2:3], 0, v[150:151]
	v_lshl_add_u64 v[4:5], s[46:47], 0, v[140:141]
	global_load_dwordx4 v[114:117], v[2:3], off
	v_mul_u32_u24_e32 v2, s48, v158
	v_lshl_add_u64 v[4:5], v[4:5], 0, v[150:151]
	v_lshlrev_b32_e32 v138, 1, v2
	global_load_dwordx4 v[122:125], v[4:5], off
	v_lshl_add_u64 v[4:5], s[46:47], 0, v[142:143]
	v_lshl_add_u64 v[2:3], s[44:45], 0, v[138:139]
	v_lshl_add_u64 v[4:5], v[4:5], 0, v[150:151]
	v_lshl_add_u64 v[2:3], v[2:3], 0, v[150:151]
	global_load_dwordx4 v[126:129], v[4:5], off
	global_load_dwordx4 v[118:121], v[2:3], off
	v_sub_u32_e64 v2, s9, 4 clamp
	v_sub_u32_e64 v3, s9, 3 clamp
	v_readfirstlane_b32 s6, v2
	v_readfirstlane_b32 s7, v3
	s_min_u32 s40, s6, 56
	s_min_u32 s6, s7, 56
	s_sub_i32 s6, s6, s40
	s_add_i32 s9, s6, 12
	s_and_b64 s[6:7], s[4:5], exec
	s_cselect_b32 s43, s9, 4
	s_cmp_lt_i32 s43, 1
	s_setprio 1
	s_waitcnt vmcnt(2)
	ds_write_b128 v160, v[122:125] offset:18432
	ds_write_b128 v160, v[114:117]
	s_waitcnt vmcnt(1)
	ds_write_b128 v162, v[126:129] offset:18432
	s_waitcnt vmcnt(0)
	ds_write_b128 v162, v[118:121]
	s_waitcnt lgkmcnt(0)
	s_barrier
	s_setprio 0
	s_cbranch_scc1 .LBB0_1558
	s_and_b64 s[6:7], s[4:5], exec
	s_cselect_b32 s2, s8, s2
	s_lshl_b32 s6, s2, 12
	s_ashr_i32 s7, s6, 31
	s_lshl_b64 s[6:7], s[6:7], 10
	v_readlane_b32 s2, v247, 1
	v_cndmask_b32_e64 v2, 0, v6, s[4:5]
	s_add_u32 s2, s2, s6
	v_sub_u32_e64 v3, v2, 4 clamp
	s_addc_u32 s6, s3, s7
	s_lshl_b32 s7, s42, 1
	v_min_u32_e32 v147, 56, v3
	s_add_u32 s2, s2, s7
	v_cndmask_b32_e64 v3, 0, v135, s[4:5]
	s_addc_u32 s6, s6, 0
	v_or_b32_e32 v4, v3, v132
	s_add_u32 s56, s2, 0x400000
	v_sub_u32_e64 v4, v4, 8 clamp
	s_addc_u32 s57, s6, 0
	s_lshl_b64 s[0:1], s[0:1], 13
	v_readlane_b32 s2, v247, 7
	v_min_u32_e32 v4, 48, v4
	s_add_u32 s58, s2, s0
	v_readlane_b32 s0, v247, 4
	v_add_u32_e32 v5, 16, v4
	s_addc_u32 s59, s0, s1
	v_cmp_ge_u32_e64 s[0:1], v165, v4
	v_cmp_lt_u32_e64 s[6:7], v165, v5
	s_and_b64 s[60:61], s[0:1], s[6:7]
	v_cmp_ge_u32_e64 s[0:1], v167, v4
	v_cmp_lt_u32_e64 s[8:9], v167, v5
	s_and_b64 s[62:63], s[0:1], s[8:9]
	v_cmp_ge_u32_e64 s[0:1], v169, v4
	v_cmp_lt_u32_e64 s[10:11], v169, v5
	s_and_b64 s[64:65], s[0:1], s[10:11]
	v_cmp_ge_u32_e64 s[0:1], v171, v4
	v_cmp_lt_u32_e64 s[12:13], v171, v5
	s_and_b64 s[66:67], s[0:1], s[12:13]
	v_cmp_ge_u32_e64 s[0:1], v173, v4
	v_cmp_lt_u32_e64 s[14:15], v173, v5
	s_and_b64 s[68:69], s[0:1], s[14:15]
	v_cmp_ge_u32_e64 s[0:1], v175, v4
	v_cmp_lt_u32_e64 s[16:17], v175, v5
	s_and_b64 s[70:71], s[0:1], s[16:17]
	v_cmp_ge_u32_e64 s[0:1], v177, v4
	v_cmp_lt_u32_e64 s[18:19], v177, v5
	s_and_b64 s[72:73], s[0:1], s[18:19]
	v_cmp_ge_u32_e64 s[0:1], v179, v4
	v_cmp_lt_u32_e64 s[20:21], v179, v5
	v_cmp_lt_u32_e32 vcc, v164, v4
	s_and_b64 s[74:75], s[0:1], s[20:21]
	v_cmp_ge_u32_e64 s[0:1], v180, v4
	s_and_b64 s[76:77], s[0:1], vcc
	v_cmp_ge_u32_e32 vcc, v182, v4
	v_cmp_lt_u32_e64 s[0:1], v182, v5
	s_and_b64 s[78:79], vcc, s[0:1]
	v_cmp_ge_u32_e32 vcc, v184, v4
	v_cmp_lt_u32_e64 s[0:1], v184, v5
	s_and_b64 s[38:39], vcc, s[0:1]
	v_cmp_ge_u32_e32 vcc, v188, v4
	v_cmp_lt_u32_e64 s[0:1], v188, v5
	s_and_b64 s[80:81], vcc, s[0:1]
	v_cmp_ge_u32_e32 vcc, v190, v4
	v_cmp_lt_u32_e64 s[0:1], v190, v5
	s_and_b64 s[82:83], vcc, s[0:1]
	v_cmp_ge_u32_e32 vcc, v192, v4
	v_cmp_lt_u32_e64 s[0:1], v192, v5
	s_and_b64 s[84:85], vcc, s[0:1]
	v_cmp_ge_u32_e32 vcc, v194, v4
	v_cmp_lt_u32_e64 s[0:1], v194, v5
	s_and_b64 s[86:87], vcc, s[0:1]
	v_cmp_ge_u32_e32 vcc, v196, v4
	v_cmp_lt_u32_e64 s[0:1], v196, v5
	s_and_b64 s[88:89], vcc, s[0:1]
	v_add_u32_e32 v3, v132, v3
	s_mul_i32 s0, s40, 0x7c
	v_mul_u32_u24_e32 v2, 0x7c, v2
	v_sub_u32_e32 v213, s0, v2
	v_sub_u32_e32 v2, v165, v3
	v_max_i32_e32 v2, -15, v2
	v_add_u32_e32 v2, 15, v2
	v_min_u32_e32 v2, 30, v2
	v_lshlrev_b32_e32 v214, 2, v2
	v_sub_u32_e32 v2, v166, v3
	v_max_i32_e32 v2, -15, v2
	v_lshlrev_b32_e32 v215, 2, v2
	v_sub_u32_e32 v2, v167, v3
	v_max_i32_e32 v2, -15, v2
	v_add_u32_e32 v2, 15, v2
	v_min_u32_e32 v2, 30, v2
	v_lshlrev_b32_e32 v216, 2, v2
	v_sub_u32_e32 v2, v168, v3
	v_max_i32_e32 v2, -15, v2
	v_lshlrev_b32_e32 v217, 2, v2
	v_sub_u32_e32 v2, v169, v3
	v_max_i32_e32 v2, -15, v2
	v_add_u32_e32 v2, 15, v2
	v_min_u32_e32 v2, 30, v2
	v_lshlrev_b32_e32 v218, 2, v2
	v_sub_u32_e32 v2, v170, v3
	v_max_i32_e32 v2, -15, v2
	v_lshlrev_b32_e32 v219, 2, v2
	v_sub_u32_e32 v2, v171, v3
	v_max_i32_e32 v2, -15, v2
	v_add_u32_e32 v2, 15, v2
	v_min_u32_e32 v2, 30, v2
	v_lshlrev_b32_e32 v220, 2, v2
	v_sub_u32_e32 v2, v172, v3
	v_max_i32_e32 v2, -15, v2
	v_lshlrev_b32_e32 v221, 2, v2
	v_sub_u32_e32 v2, v173, v3
	v_max_i32_e32 v2, -15, v2
	v_add_u32_e32 v2, 15, v2
	v_min_u32_e32 v2, 30, v2
	v_lshlrev_b32_e32 v222, 2, v2
	v_sub_u32_e32 v2, v174, v3
	v_max_i32_e32 v2, -15, v2
	v_lshlrev_b32_e32 v223, 2, v2
	v_sub_u32_e32 v2, v175, v3
	v_max_i32_e32 v2, -15, v2
	v_add_u32_e32 v2, 15, v2
	v_min_u32_e32 v2, 30, v2
	v_lshlrev_b32_e32 v224, 2, v2
	v_sub_u32_e32 v2, v176, v3
	v_max_i32_e32 v2, -15, v2
	v_lshlrev_b32_e32 v225, 2, v2
	v_sub_u32_e32 v2, v177, v3
	v_max_i32_e32 v2, -15, v2
	v_add_u32_e32 v2, 15, v2
	v_min_u32_e32 v2, 30, v2
	v_lshlrev_b32_e32 v226, 2, v2
	v_sub_u32_e32 v2, v178, v3
	v_max_i32_e32 v2, -15, v2
	v_lshlrev_b32_e32 v227, 2, v2
	v_sub_u32_e32 v2, v179, v3
	v_max_i32_e32 v2, -15, v2
	v_add_u32_e32 v2, 15, v2
	v_min_u32_e32 v2, 30, v2
	v_lshlrev_b32_e32 v228, 2, v2
	v_sub_u32_e32 v2, v180, v3
	v_max_i32_e32 v2, -15, v2
	v_add_u32_e32 v2, 15, v2
	v_min_u32_e32 v2, 30, v2
	v_lshlrev_b32_e32 v229, 2, v2
	v_sub_u32_e32 v2, v201, v3
	v_min_u32_e32 v2, 30, v2
	v_lshlrev_b32_e32 v230, 2, v2
	v_sub_u32_e32 v2, v182, v3
	v_max_i32_e32 v2, -15, v2
	v_add_u32_e32 v2, 15, v2
	v_min_u32_e32 v2, 30, v2
	v_lshlrev_b32_e32 v231, 2, v2
	v_sub_u32_e32 v2, v202, v3
	v_min_u32_e32 v2, 30, v2
	v_lshlrev_b32_e32 v232, 2, v2
	v_sub_u32_e32 v2, v184, v3
	v_max_i32_e32 v2, -15, v2
	v_add_u32_e32 v2, 15, v2
	v_min_u32_e32 v2, 30, v2
	v_lshlrev_b32_e32 v233, 2, v2
	v_sub_u32_e32 v2, v203, v3
	v_min_u32_e32 v2, 30, v2
	v_lshlrev_b32_e32 v234, 2, v2
	v_sub_u32_e32 v2, v188, v3
	v_max_i32_e32 v2, -15, v2
	v_add_u32_e32 v2, 15, v2
	v_min_u32_e32 v2, 30, v2
	v_lshlrev_b32_e32 v235, 2, v2
	v_sub_u32_e32 v2, v204, v3
	v_min_u32_e32 v2, 30, v2
	v_lshlrev_b32_e32 v236, 2, v2
	v_sub_u32_e32 v2, v190, v3
	v_max_i32_e32 v2, -15, v2
	v_add_u32_e32 v2, 15, v2
	v_min_u32_e32 v2, 30, v2
	v_lshlrev_b32_e32 v237, 2, v2
	v_sub_u32_e32 v2, v205, v3
	v_min_u32_e32 v2, 30, v2
	v_lshlrev_b32_e32 v238, 2, v2
	v_sub_u32_e32 v2, v192, v3
	v_max_i32_e32 v2, -15, v2
	v_add_u32_e32 v2, 15, v2
	v_min_u32_e32 v2, 30, v2
	v_lshlrev_b32_e32 v239, 2, v2
	v_sub_u32_e32 v2, v206, v3
	v_min_u32_e32 v2, 30, v2
	v_lshlrev_b32_e32 v240, 2, v2
	v_sub_u32_e32 v2, v194, v3
	v_max_i32_e32 v2, -15, v2
	v_add_u32_e32 v2, 15, v2
	v_min_u32_e32 v2, 30, v2
	v_lshlrev_b32_e32 v241, 2, v2
	v_sub_u32_e32 v2, v207, v3
	v_min_u32_e32 v2, 30, v2
	v_lshlrev_b32_e32 v242, 2, v2
	v_sub_u32_e32 v2, v196, v3
	v_max_i32_e32 v2, -15, v2
	v_add_u32_e32 v2, 15, v2
	v_min_u32_e32 v2, 30, v2
	v_cmp_ge_u32_e64 s[4:5], v164, v4
	v_cmp_ge_u32_e64 s[6:7], v166, v4
	v_cmp_ge_u32_e64 s[8:9], v168, v4
	v_cmp_ge_u32_e64 s[10:11], v170, v4
	v_cmp_ge_u32_e64 s[12:13], v172, v4
	v_cmp_ge_u32_e64 s[14:15], v174, v4
	v_cmp_ge_u32_e64 s[16:17], v176, v4
	v_cmp_ge_u32_e64 s[18:19], v178, v4
	v_sub_u32_e32 v4, v164, v3
	v_lshlrev_b32_e32 v243, 2, v2
	v_sub_u32_e32 v2, v208, v3
	v_max_i32_e32 v4, -15, v4
	v_min_u32_e32 v2, 30, v2
	v_mov_b32_e32 v211, 0
	s_mov_b32 s52, 0
	v_add_u32_e32 v210, 8, v147
	v_cmp_lt_u32_e64 s[20:21], v181, v5
	v_cmp_lt_u32_e64 s[22:23], v183, v5
	v_cmp_lt_u32_e64 s[24:25], v185, v5
	v_cmp_lt_u32_e64 s[26:27], v189, v5
	v_cmp_lt_u32_e64 s[28:29], v191, v5
	v_cmp_lt_u32_e64 s[30:31], v193, v5
	v_cmp_lt_u32_e64 s[34:35], v195, v5
	v_cmp_lt_u32_e64 s[36:37], v197, v5
	s_add_i32 s2, s40, -4
	v_lshlrev_b32_e32 v212, 2, v4
	v_lshlrev_b32_e32 v244, 2, v2
	v_mov_b32_e32 v245, 0xff800000
	s_mov_b32 s50, 64
	v_mov_b32_e32 v18, 0
	v_mov_b32_e32 v19, v211
	v_mov_b32_e32 v20, v211
	v_mov_b32_e32 v21, v211
	v_mov_b32_e32 v22, v211
	v_mov_b32_e32 v23, v211
	v_mov_b32_e32 v24, v211
	v_mov_b32_e32 v25, v211
	v_mov_b32_e32 v26, v211
	v_mov_b32_e32 v27, v211
	v_mov_b32_e32 v28, v211
	v_mov_b32_e32 v29, v211
	v_mov_b32_e32 v30, v211
	v_mov_b32_e32 v31, v211
	v_mov_b32_e32 v32, v211
	v_mov_b32_e32 v33, v211
	v_mov_b32_e32 v2, v211
	v_mov_b32_e32 v3, v211
	v_mov_b32_e32 v4, v211
	v_mov_b32_e32 v5, v211
	v_mov_b32_e32 v6, v211
	v_mov_b32_e32 v7, v211
	v_mov_b32_e32 v8, v211
	v_mov_b32_e32 v9, v211
	v_mov_b32_e32 v10, v211
	v_mov_b32_e32 v11, v211
	v_mov_b32_e32 v12, v211
	v_mov_b32_e32 v13, v211
	v_mov_b32_e32 v14, v211
	v_mov_b32_e32 v15, v211
	v_mov_b32_e32 v16, v211
	v_mov_b32_e32 v17, v211

.LBB0_1641:
	s_and_b32 s3, s2, 0xffff
	s_mul_i32 s3, s3, 0xaaab
	s_lshr_b32 s3, s3, 18
	s_mul_i32 s10, s3, 6
	s_sub_i32 s2, s2, s10
	s_and_b32 s2, s2, 0xffff
	s_add_i32 s2, s6, s2
	s_lshl_b32 s10, s2, 7
	v_or_b32_e32 v2, s10, v91
	v_lshlrev_b32_e32 v66, 11, v2
	v_lshl_add_u64 v[74:75], v[68:69], 0, v[66:67]
	v_add_lshl_u32 v66, s10, v92, 11
	s_add_i32 s3, s8, s3
	v_lshl_add_u64 v[76:77], v[68:69], 0, v[66:67]
	v_add_lshl_u32 v66, s10, v93, 11
	s_lshl_b32 s11, s3, 7
	v_lshl_add_u64 v[78:79], v[68:69], 0, v[66:67]
	v_add_lshl_u32 v66, s10, v94, 11
	v_lshl_add_u64 v[80:81], v[68:69], 0, v[66:67]
	v_or_b32_e32 v66, s11, v91
	v_lshlrev_b64 v[2:3], 11, v[66:67]
	v_add_u32_e32 v66, s11, v92
	v_lshl_add_u64 v[82:83], v[70:71], 0, v[2:3]
	v_lshlrev_b64 v[2:3], 11, v[66:67]
	v_add_u32_e32 v66, s11, v93
	v_lshl_add_u64 v[84:85], v[70:71], 0, v[2:3]
	v_lshlrev_b64 v[2:3], 11, v[66:67]
	v_add_u32_e32 v66, s11, v94
	v_lshl_add_u64 v[86:87], v[70:71], 0, v[2:3]
	v_lshlrev_b64 v[2:3], 11, v[66:67]
	v_lshl_add_u64 v[88:89], v[70:71], 0, v[2:3]
	global_load_dwordx4 v[2:5], v[74:75], off
	global_load_dwordx4 v[6:9], v[76:77], off
	global_load_dwordx4 v[10:13], v[78:79], off
	global_load_dwordx4 v[14:17], v[80:81], off
	global_load_dwordx4 v[18:21], v[82:83], off
	global_load_dwordx4 v[22:25], v[84:85], off
	global_load_dwordx4 v[26:29], v[86:87], off
	global_load_dwordx4 v[30:33], v[88:89], off
	global_load_dwordx4 v[102:105], v[74:75], off offset:128
	global_load_dwordx4 v[106:109], v[76:77], off offset:128
	global_load_dwordx4 v[110:113], v[78:79], off offset:128
	global_load_dwordx4 v[114:117], v[80:81], off offset:128
	global_load_dwordx4 v[118:121], v[82:83], off offset:128
	global_load_dwordx4 v[122:125], v[84:85], off offset:128
	global_load_dwordx4 v[126:129], v[86:87], off offset:128
	global_load_dwordx4 v[132:135], v[88:89], off offset:128
	s_setprio 1
	s_waitcnt vmcnt(15)
	ds_write_b128 v98, v[2:5]
	s_waitcnt vmcnt(14)
	ds_write_b128 v98, v[6:9] offset:4608
	s_waitcnt vmcnt(13)
	ds_write_b128 v98, v[10:13] offset:9216
	s_waitcnt vmcnt(12)
	ds_write_b128 v98, v[14:17] offset:13824
	s_waitcnt vmcnt(11)
	ds_write_b128 v98, v[18:21] offset:36864
	s_waitcnt vmcnt(10)
	ds_write_b128 v98, v[22:25] offset:41472
	s_waitcnt vmcnt(9)
	ds_write_b128 v98, v[26:29] offset:46080
	s_waitcnt vmcnt(8)
	ds_write_b128 v98, v[30:33] offset:50688
	s_waitcnt lgkmcnt(0)
	s_barrier
	s_setprio 0
	global_load_dwordx4 v[136:139], v[74:75], off offset:256
	global_load_dwordx4 v[140:143], v[76:77], off offset:256
	global_load_dwordx4 v[144:147], v[78:79], off offset:256
	global_load_dwordx4 v[148:151], v[80:81], off offset:256
	global_load_dwordx4 v[152:155], v[82:83], off offset:256
	global_load_dwordx4 v[156:159], v[84:85], off offset:256
	global_load_dwordx4 v[160:163], v[86:87], off offset:256
	global_load_dwordx4 v[164:167], v[88:89], off offset:256
	v_and_b32_e32 v246, 15, v1
	v_add_u32_e32 v246, 4, v246
	v_bfe_u32 v246, v246, 3, 1
	v_bfe_u32 v249, v1, 4, 2
	v_xor_b32_e32 v246, v246, v249
	v_bfe_u32 v249, v1, 5, 1
	v_sub_u32_e32 v246, v246, v249
	v_lshlrev_b32_e32 v246, 4, v246
	v_bfe_u32 v249, v1, 4, 1
	v_mul_u32_u24_e32 v249, 0x900, v249
	v_sub_u32_e32 v246, v246, v249
	v_add_u32_e32 v244, v246, v96
	v_add_u32_e32 v245, v246, v97
	ds_read_b128 v[212:215], v245 offset:36864
	ds_read_b128 v[196:199], v244
	ds_read_b128 v[216:219], v245 offset:39168
	ds_read_b128 v[220:223], v245 offset:41472
	ds_read_b128 v[224:227], v245 offset:43776
	ds_read_b128 v[200:203], v244 offset:2304
	ds_read_b128 v[204:207], v244 offset:4608
	ds_read_b128 v[208:211], v244 offset:6912
	s_waitcnt lgkmcnt(6)
	v_mfma_f32_16x16x32_bf16 v[50:53], v[196:199], v[212:215], 0
	ds_read_b128 v[228:231], v245 offset:36928
	s_waitcnt lgkmcnt(6)
	v_mfma_f32_16x16x32_bf16 v[54:57], v[196:199], v[216:219], 0
	ds_read_b128 v[232:235], v245 offset:39232
	s_waitcnt lgkmcnt(6)
	v_mfma_f32_16x16x32_bf16 v[18:21], v[196:199], v[220:223], 0
	ds_read_b128 v[236:239], v245 offset:41536
	s_waitcnt lgkmcnt(6)
	v_mfma_f32_16x16x32_bf16 v[22:25], v[196:199], v[224:227], 0
	ds_read_b128 v[240:243], v245 offset:43840
	ds_read_b128 v[196:199], v244 offset:64
	s_waitcnt lgkmcnt(7)
	v_mfma_f32_16x16x32_bf16 v[58:61], v[200:203], v[212:215], 0
	v_mfma_f32_16x16x32_bf16 v[62:65], v[200:203], v[216:219], 0
	v_mfma_f32_16x16x32_bf16 v[26:29], v[200:203], v[220:223], 0
	v_mfma_f32_16x16x32_bf16 v[30:33], v[200:203], v[224:227], 0
	ds_read_b128 v[200:203], v244 offset:2368
	s_waitcnt lgkmcnt(7)
	v_mfma_f32_16x16x32_bf16 v[34:37], v[204:207], v[212:215], 0
	v_mfma_f32_16x16x32_bf16 v[38:41], v[204:207], v[216:219], 0
	v_mfma_f32_16x16x32_bf16 v[2:5], v[204:207], v[220:223], 0
	v_mfma_f32_16x16x32_bf16 v[6:9], v[204:207], v[224:227], 0
	ds_read_b128 v[204:207], v244 offset:4672
	s_setprio 1
	s_waitcnt vmcnt(15)
	ds_write_b128 v98, v[102:105] offset:18432
	s_waitcnt vmcnt(14)
	ds_write_b128 v98, v[106:109] offset:23040
	s_waitcnt lgkmcnt(9)
	v_mfma_f32_16x16x32_bf16 v[42:45], v[208:211], v[212:215], 0
	v_mfma_f32_16x16x32_bf16 v[46:49], v[208:211], v[216:219], 0
	v_mfma_f32_16x16x32_bf16 v[10:13], v[208:211], v[220:223], 0
	v_mfma_f32_16x16x32_bf16 v[14:17], v[208:211], v[224:227], 0
	ds_read_b128 v[208:211], v244 offset:6976
	s_waitcnt vmcnt(13)
	ds_write_b128 v98, v[110:113] offset:27648
	s_waitcnt vmcnt(12)
	ds_write_b128 v98, v[114:117] offset:32256
	s_waitcnt lgkmcnt(7)
	v_mfma_f32_16x16x32_bf16 v[50:53], v[196:199], v[228:231], v[50:53]
	v_mfma_f32_16x16x32_bf16 v[54:57], v[196:199], v[232:235], v[54:57]
	v_mfma_f32_16x16x32_bf16 v[18:21], v[196:199], v[236:239], v[18:21]
	v_mfma_f32_16x16x32_bf16 v[22:25], v[196:199], v[240:243], v[22:25]
	s_waitcnt vmcnt(11)
	ds_write_b128 v98, v[118:121] offset:55296
	s_waitcnt vmcnt(10)
	ds_write_b128 v98, v[122:125] offset:59904
	s_waitcnt lgkmcnt(8)
	v_mfma_f32_16x16x32_bf16 v[58:61], v[200:203], v[228:231], v[58:61]
	v_mfma_f32_16x16x32_bf16 v[62:65], v[200:203], v[232:235], v[62:65]
	v_mfma_f32_16x16x32_bf16 v[26:29], v[200:203], v[236:239], v[26:29]
	v_mfma_f32_16x16x32_bf16 v[30:33], v[200:203], v[240:243], v[30:33]
	s_waitcnt vmcnt(9)
	ds_write_b128 v98, v[126:129] offset:64512
	s_waitcnt vmcnt(8)
	ds_write_b128 v99, v[132:135] offset:32256
	s_waitcnt lgkmcnt(0)
	s_barrier
	s_setprio 0
	ds_read_b128 v[212:215], v245 offset:55296
	ds_read_b128 v[196:199], v244 offset:18432
	ds_read_b128 v[216:219], v245 offset:57600
	ds_read_b128 v[220:223], v245 offset:59904
	ds_read_b128 v[224:227], v245 offset:62208
	ds_read_b128 v[200:203], v244 offset:20736
	v_mfma_f32_16x16x32_bf16 v[34:37], v[204:207], v[228:231], v[34:37]
	v_mfma_f32_16x16x32_bf16 v[38:41], v[204:207], v[232:235], v[38:41]
	v_mfma_f32_16x16x32_bf16 v[2:5], v[204:207], v[236:239], v[2:5]
	v_mfma_f32_16x16x32_bf16 v[6:9], v[204:207], v[240:243], v[6:9]
	ds_read_b128 v[204:207], v244 offset:23040
	v_mfma_f32_16x16x32_bf16 v[42:45], v[208:211], v[228:231], v[42:45]
	v_mfma_f32_16x16x32_bf16 v[46:49], v[208:211], v[232:235], v[46:49]
	v_mfma_f32_16x16x32_bf16 v[10:13], v[208:211], v[236:239], v[10:13]
	v_mfma_f32_16x16x32_bf16 v[14:17], v[208:211], v[240:243], v[14:17]
	ds_read_b128 v[208:211], v244 offset:25344
	global_load_dwordx4 v[102:105], v[74:75], off offset:384
	global_load_dwordx4 v[106:109], v[76:77], off offset:384
	global_load_dwordx4 v[110:113], v[78:79], off offset:384
	global_load_dwordx4 v[114:117], v[80:81], off offset:384
	global_load_dwordx4 v[118:121], v[82:83], off offset:384
	global_load_dwordx4 v[122:125], v[84:85], off offset:384
	global_load_dwordx4 v[126:129], v[86:87], off offset:384
	global_load_dwordx4 v[132:135], v[88:89], off offset:384
	s_waitcnt lgkmcnt(6)
	v_mfma_f32_16x16x32_bf16 v[50:53], v[196:199], v[212:215], v[50:53]
	ds_read_b128 v[228:231], v245 offset:55360
	s_waitcnt lgkmcnt(6)
	v_mfma_f32_16x16x32_bf16 v[54:57], v[196:199], v[216:219], v[54:57]
	ds_read_b128 v[232:235], v245 offset:57664
	s_waitcnt lgkmcnt(6)
	v_mfma_f32_16x16x32_bf16 v[18:21], v[196:199], v[220:223], v[18:21]
	ds_read_b128 v[236:239], v245 offset:59968
	s_waitcnt lgkmcnt(6)
	v_mfma_f32_16x16x32_bf16 v[22:25], v[196:199], v[224:227], v[22:25]
	ds_read_b128 v[240:243], v245 offset:62272
	ds_read_b128 v[196:199], v244 offset:18496
	s_waitcnt lgkmcnt(7)
	v_mfma_f32_16x16x32_bf16 v[58:61], v[200:203], v[212:215], v[58:61]
	v_mfma_f32_16x16x32_bf16 v[62:65], v[200:203], v[216:219], v[62:65]
	v_mfma_f32_16x16x32_bf16 v[26:29], v[200:203], v[220:223], v[26:29]
	v_mfma_f32_16x16x32_bf16 v[30:33], v[200:203], v[224:227], v[30:33]
	ds_read_b128 v[200:203], v244 offset:20800
	s_waitcnt lgkmcnt(7)
	v_mfma_f32_16x16x32_bf16 v[34:37], v[204:207], v[212:215], v[34:37]
	v_mfma_f32_16x16x32_bf16 v[38:41], v[204:207], v[216:219], v[38:41]
	v_mfma_f32_16x16x32_bf16 v[2:5], v[204:207], v[220:223], v[2:5]
	v_mfma_f32_16x16x32_bf16 v[6:9], v[204:207], v[224:227], v[6:9]
	ds_read_b128 v[204:207], v244 offset:23104
	s_setprio 1
	s_waitcnt vmcnt(15)
	ds_write_b128 v98, v[136:139]
	s_waitcnt vmcnt(14)
	ds_write_b128 v98, v[140:143] offset:4608
	s_waitcnt lgkmcnt(9)
	v_mfma_f32_16x16x32_bf16 v[42:45], v[208:211], v[212:215], v[42:45]
	v_mfma_f32_16x16x32_bf16 v[46:49], v[208:211], v[216:219], v[46:49]
	v_mfma_f32_16x16x32_bf16 v[10:13], v[208:211], v[220:223], v[10:13]
	v_mfma_f32_16x16x32_bf16 v[14:17], v[208:211], v[224:227], v[14:17]
	ds_read_b128 v[208:211], v244 offset:25408
	s_waitcnt vmcnt(13)
	ds_write_b128 v98, v[144:147] offset:9216
	s_waitcnt vmcnt(12)
	ds_write_b128 v98, v[148:151] offset:13824
	s_waitcnt lgkmcnt(7)
	v_mfma_f32_16x16x32_bf16 v[50:53], v[196:199], v[228:231], v[50:53]
	v_mfma_f32_16x16x32_bf16 v[54:57], v[196:199], v[232:235], v[54:57]
	v_mfma_f32_16x16x32_bf16 v[18:21], v[196:199], v[236:239], v[18:21]
	v_mfma_f32_16x16x32_bf16 v[22:25], v[196:199], v[240:243], v[22:25]
	s_waitcnt vmcnt(11)
	ds_write_b128 v98, v[152:155] offset:36864
	s_waitcnt vmcnt(10)
	ds_write_b128 v98, v[156:159] offset:41472
	s_waitcnt lgkmcnt(8)
	v_mfma_f32_16x16x32_bf16 v[58:61], v[200:203], v[228:231], v[58:61]
	v_mfma_f32_16x16x32_bf16 v[62:65], v[200:203], v[232:235], v[62:65]
	v_mfma_f32_16x16x32_bf16 v[26:29], v[200:203], v[236:239], v[26:29]
	v_mfma_f32_16x16x32_bf16 v[30:33], v[200:203], v[240:243], v[30:33]
	s_waitcnt vmcnt(9)
	ds_write_b128 v98, v[160:163] offset:46080
	s_waitcnt vmcnt(8)
	ds_write_b128 v98, v[164:167] offset:50688
	s_waitcnt lgkmcnt(0)
	s_barrier
	s_setprio 0
	ds_read_b128 v[212:215], v245 offset:36864
	ds_read_b128 v[196:199], v244
	ds_read_b128 v[216:219], v245 offset:39168
	ds_read_b128 v[220:223], v245 offset:41472
	ds_read_b128 v[224:227], v245 offset:43776
	ds_read_b128 v[200:203], v244 offset:2304
	v_mfma_f32_16x16x32_bf16 v[34:37], v[204:207], v[228:231], v[34:37]
	v_mfma_f32_16x16x32_bf16 v[38:41], v[204:207], v[232:235], v[38:41]
	v_mfma_f32_16x16x32_bf16 v[2:5], v[204:207], v[236:239], v[2:5]
	v_mfma_f32_16x16x32_bf16 v[6:9], v[204:207], v[240:243], v[6:9]
	ds_read_b128 v[204:207], v244 offset:4608
	v_mfma_f32_16x16x32_bf16 v[42:45], v[208:211], v[228:231], v[42:45]
	v_mfma_f32_16x16x32_bf16 v[46:49], v[208:211], v[232:235], v[46:49]
	v_mfma_f32_16x16x32_bf16 v[10:13], v[208:211], v[236:239], v[10:13]
	v_mfma_f32_16x16x32_bf16 v[14:17], v[208:211], v[240:243], v[14:17]
	ds_read_b128 v[208:211], v244 offset:6912
	global_load_dwordx4 v[136:139], v[74:75], off offset:512
	global_load_dwordx4 v[140:143], v[76:77], off offset:512
	global_load_dwordx4 v[144:147], v[78:79], off offset:512
	global_load_dwordx4 v[148:151], v[80:81], off offset:512
	global_load_dwordx4 v[152:155], v[82:83], off offset:512
	global_load_dwordx4 v[156:159], v[84:85], off offset:512
	global_load_dwordx4 v[160:163], v[86:87], off offset:512
	global_load_dwordx4 v[164:167], v[88:89], off offset:512
	s_waitcnt lgkmcnt(6)
	v_mfma_f32_16x16x32_bf16 v[50:53], v[196:199], v[212:215], v[50:53]
	ds_read_b128 v[228:231], v245 offset:36928
	s_waitcnt lgkmcnt(6)
	v_mfma_f32_16x16x32_bf16 v[54:57], v[196:199], v[216:219], v[54:57]
	ds_read_b128 v[232:235], v245 offset:39232
	s_waitcnt lgkmcnt(6)
	v_mfma_f32_16x16x32_bf16 v[18:21], v[196:199], v[220:223], v[18:21]
	ds_read_b128 v[236:239], v245 offset:41536
	s_waitcnt lgkmcnt(6)
	v_mfma_f32_16x16x32_bf16 v[22:25], v[196:199], v[224:227], v[22:25]
	ds_read_b128 v[240:243], v245 offset:43840
	ds_read_b128 v[196:199], v244 offset:64
	s_waitcnt lgkmcnt(7)
	v_mfma_f32_16x16x32_bf16 v[58:61], v[200:203], v[212:215], v[58:61]
	v_mfma_f32_16x16x32_bf16 v[62:65], v[200:203], v[216:219], v[62:65]
	v_mfma_f32_16x16x32_bf16 v[26:29], v[200:203], v[220:223], v[26:29]
	v_mfma_f32_16x16x32_bf16 v[30:33], v[200:203], v[224:227], v[30:33]
	ds_read_b128 v[200:203], v244 offset:2368
	s_waitcnt lgkmcnt(7)
	v_mfma_f32_16x16x32_bf16 v[34:37], v[204:207], v[212:215], v[34:37]
	v_mfma_f32_16x16x32_bf16 v[38:41], v[204:207], v[216:219], v[38:41]
	v_mfma_f32_16x16x32_bf16 v[2:5], v[204:207], v[220:223], v[2:5]
	v_mfma_f32_16x16x32_bf16 v[6:9], v[204:207], v[224:227], v[6:9]
	ds_read_b128 v[204:207], v244 offset:4672
	s_setprio 1
	s_waitcnt vmcnt(15)
	ds_write_b128 v98, v[102:105] offset:18432
	s_waitcnt vmcnt(14)
	ds_write_b128 v98, v[106:109] offset:23040
	s_waitcnt lgkmcnt(9)
	v_mfma_f32_16x16x32_bf16 v[42:45], v[208:211], v[212:215], v[42:45]
	v_mfma_f32_16x16x32_bf16 v[46:49], v[208:211], v[216:219], v[46:49]
	v_mfma_f32_16x16x32_bf16 v[10:13], v[208:211], v[220:223], v[10:13]
	v_mfma_f32_16x16x32_bf16 v[14:17], v[208:211], v[224:227], v[14:17]
	ds_read_b128 v[208:211], v244 offset:6976
	s_waitcnt vmcnt(13)
	ds_write_b128 v98, v[110:113] offset:27648
	s_waitcnt vmcnt(12)
	ds_write_b128 v98, v[114:117] offset:32256
	s_waitcnt lgkmcnt(7)
	v_mfma_f32_16x16x32_bf16 v[50:53], v[196:199], v[228:231], v[50:53]
	v_mfma_f32_16x16x32_bf16 v[54:57], v[196:199], v[232:235], v[54:57]
	v_mfma_f32_16x16x32_bf16 v[18:21], v[196:199], v[236:239], v[18:21]
	v_mfma_f32_16x16x32_bf16 v[22:25], v[196:199], v[240:243], v[22:25]
	s_waitcnt vmcnt(11)
	ds_write_b128 v98, v[118:121] offset:55296
	s_waitcnt vmcnt(10)
	ds_write_b128 v98, v[122:125] offset:59904
	s_waitcnt lgkmcnt(8)
	v_mfma_f32_16x16x32_bf16 v[58:61], v[200:203], v[228:231], v[58:61]
	v_mfma_f32_16x16x32_bf16 v[62:65], v[200:203], v[232:235], v[62:65]
	v_mfma_f32_16x16x32_bf16 v[26:29], v[200:203], v[236:239], v[26:29]
	v_mfma_f32_16x16x32_bf16 v[30:33], v[200:203], v[240:243], v[30:33]
	s_waitcnt vmcnt(9)
	ds_write_b128 v98, v[126:129] offset:64512
	s_waitcnt vmcnt(8)
	ds_write_b128 v99, v[132:135] offset:32256
	s_waitcnt lgkmcnt(0)
	s_barrier
	s_setprio 0
	ds_read_b128 v[212:215], v245 offset:55296
	ds_read_b128 v[196:199], v244 offset:18432
	ds_read_b128 v[216:219], v245 offset:57600
	ds_read_b128 v[220:223], v245 offset:59904
	ds_read_b128 v[224:227], v245 offset:62208
	ds_read_b128 v[200:203], v244 offset:20736
	v_mfma_f32_16x16x32_bf16 v[34:37], v[204:207], v[228:231], v[34:37]
	v_mfma_f32_16x16x32_bf16 v[38:41], v[204:207], v[232:235], v[38:41]
	v_mfma_f32_16x16x32_bf16 v[2:5], v[204:207], v[236:239], v[2:5]
	v_mfma_f32_16x16x32_bf16 v[6:9], v[204:207], v[240:243], v[6:9]
	ds_read_b128 v[204:207], v244 offset:23040
	v_mfma_f32_16x16x32_bf16 v[42:45], v[208:211], v[228:231], v[42:45]
	v_mfma_f32_16x16x32_bf16 v[46:49], v[208:211], v[232:235], v[46:49]
	v_mfma_f32_16x16x32_bf16 v[10:13], v[208:211], v[236:239], v[10:13]
	v_mfma_f32_16x16x32_bf16 v[14:17], v[208:211], v[240:243], v[14:17]
	ds_read_b128 v[208:211], v244 offset:25344
	global_load_dwordx4 v[102:105], v[74:75], off offset:640
	global_load_dwordx4 v[106:109], v[76:77], off offset:640
	global_load_dwordx4 v[110:113], v[78:79], off offset:640
	global_load_dwordx4 v[114:117], v[80:81], off offset:640
	global_load_dwordx4 v[118:121], v[82:83], off offset:640
	global_load_dwordx4 v[122:125], v[84:85], off offset:640
	global_load_dwordx4 v[126:129], v[86:87], off offset:640
	global_load_dwordx4 v[132:135], v[88:89], off offset:640
	s_waitcnt lgkmcnt(6)
	v_mfma_f32_16x16x32_bf16 v[50:53], v[196:199], v[212:215], v[50:53]
	ds_read_b128 v[228:231], v245 offset:55360
	s_waitcnt lgkmcnt(6)
	v_mfma_f32_16x16x32_bf16 v[54:57], v[196:199], v[216:219], v[54:57]
	ds_read_b128 v[232:235], v245 offset:57664
	s_waitcnt lgkmcnt(6)
	v_mfma_f32_16x16x32_bf16 v[18:21], v[196:199], v[220:223], v[18:21]
	ds_read_b128 v[236:239], v245 offset:59968
	s_waitcnt lgkmcnt(6)
	v_mfma_f32_16x16x32_bf16 v[22:25], v[196:199], v[224:227], v[22:25]
	ds_read_b128 v[240:243], v245 offset:62272
	ds_read_b128 v[196:199], v244 offset:18496
	s_waitcnt lgkmcnt(7)
	v_mfma_f32_16x16x32_bf16 v[58:61], v[200:203], v[212:215], v[58:61]
	v_mfma_f32_16x16x32_bf16 v[62:65], v[200:203], v[216:219], v[62:65]
	v_mfma_f32_16x16x32_bf16 v[26:29], v[200:203], v[220:223], v[26:29]
	v_mfma_f32_16x16x32_bf16 v[30:33], v[200:203], v[224:227], v[30:33]
	ds_read_b128 v[200:203], v244 offset:20800
	s_waitcnt lgkmcnt(7)
	v_mfma_f32_16x16x32_bf16 v[34:37], v[204:207], v[212:215], v[34:37]
	v_mfma_f32_16x16x32_bf16 v[38:41], v[204:207], v[216:219], v[38:41]
	v_mfma_f32_16x16x32_bf16 v[2:5], v[204:207], v[220:223], v[2:5]
	v_mfma_f32_16x16x32_bf16 v[6:9], v[204:207], v[224:227], v[6:9]
	ds_read_b128 v[204:207], v244 offset:23104
	s_setprio 1
	s_waitcnt vmcnt(15)
	ds_write_b128 v98, v[136:139]
	s_waitcnt vmcnt(14)
	ds_write_b128 v98, v[140:143] offset:4608
	s_waitcnt lgkmcnt(9)
	v_mfma_f32_16x16x32_bf16 v[42:45], v[208:211], v[212:215], v[42:45]
	v_mfma_f32_16x16x32_bf16 v[46:49], v[208:211], v[216:219], v[46:49]
	v_mfma_f32_16x16x32_bf16 v[10:13], v[208:211], v[220:223], v[10:13]
	v_mfma_f32_16x16x32_bf16 v[14:17], v[208:211], v[224:227], v[14:17]
	ds_read_b128 v[208:211], v244 offset:25408
	s_waitcnt vmcnt(13)
	ds_write_b128 v98, v[144:147] offset:9216
	s_waitcnt vmcnt(12)
	ds_write_b128 v98, v[148:151] offset:13824
	s_waitcnt lgkmcnt(7)
	v_mfma_f32_16x16x32_bf16 v[50:53], v[196:199], v[228:231], v[50:53]
	v_mfma_f32_16x16x32_bf16 v[54:57], v[196:199], v[232:235], v[54:57]
	v_mfma_f32_16x16x32_bf16 v[18:21], v[196:199], v[236:239], v[18:21]
	v_mfma_f32_16x16x32_bf16 v[22:25], v[196:199], v[240:243], v[22:25]
	s_waitcnt vmcnt(11)
	ds_write_b128 v98, v[152:155] offset:36864
	s_waitcnt vmcnt(10)
	ds_write_b128 v98, v[156:159] offset:41472
	s_waitcnt lgkmcnt(8)
	v_mfma_f32_16x16x32_bf16 v[58:61], v[200:203], v[228:231], v[58:61]
	v_mfma_f32_16x16x32_bf16 v[62:65], v[200:203], v[232:235], v[62:65]
	v_mfma_f32_16x16x32_bf16 v[26:29], v[200:203], v[236:239], v[26:29]
	v_mfma_f32_16x16x32_bf16 v[30:33], v[200:203], v[240:243], v[30:33]
	s_waitcnt vmcnt(9)
	ds_write_b128 v98, v[160:163] offset:46080
	s_waitcnt vmcnt(8)
	ds_write_b128 v98, v[164:167] offset:50688
	s_waitcnt lgkmcnt(0)
	s_barrier
	s_setprio 0
	ds_read_b128 v[212:215], v245 offset:36864
	ds_read_b128 v[196:199], v244
	ds_read_b128 v[216:219], v245 offset:39168
	ds_read_b128 v[220:223], v245 offset:41472
	ds_read_b128 v[224:227], v245 offset:43776
	ds_read_b128 v[200:203], v244 offset:2304
	v_mfma_f32_16x16x32_bf16 v[34:37], v[204:207], v[228:231], v[34:37]
	v_mfma_f32_16x16x32_bf16 v[38:41], v[204:207], v[232:235], v[38:41]
	v_mfma_f32_16x16x32_bf16 v[2:5], v[204:207], v[236:239], v[2:5]
	v_mfma_f32_16x16x32_bf16 v[6:9], v[204:207], v[240:243], v[6:9]
	ds_read_b128 v[204:207], v244 offset:4608
	v_mfma_f32_16x16x32_bf16 v[42:45], v[208:211], v[228:231], v[42:45]
	v_mfma_f32_16x16x32_bf16 v[46:49], v[208:211], v[232:235], v[46:49]
	v_mfma_f32_16x16x32_bf16 v[10:13], v[208:211], v[236:239], v[10:13]
	v_mfma_f32_16x16x32_bf16 v[14:17], v[208:211], v[240:243], v[14:17]
	ds_read_b128 v[208:211], v244 offset:6912
	global_load_dwordx4 v[136:139], v[74:75], off offset:768
	global_load_dwordx4 v[140:143], v[76:77], off offset:768
	global_load_dwordx4 v[144:147], v[78:79], off offset:768
	global_load_dwordx4 v[148:151], v[80:81], off offset:768
	global_load_dwordx4 v[152:155], v[82:83], off offset:768
	global_load_dwordx4 v[156:159], v[84:85], off offset:768
	global_load_dwordx4 v[160:163], v[86:87], off offset:768
	global_load_dwordx4 v[164:167], v[88:89], off offset:768
	s_waitcnt lgkmcnt(6)
	v_mfma_f32_16x16x32_bf16 v[50:53], v[196:199], v[212:215], v[50:53]
	ds_read_b128 v[228:231], v245 offset:36928
	s_waitcnt lgkmcnt(6)
	v_mfma_f32_16x16x32_bf16 v[54:57], v[196:199], v[216:219], v[54:57]
	ds_read_b128 v[232:235], v245 offset:39232
	s_waitcnt lgkmcnt(6)
	v_mfma_f32_16x16x32_bf16 v[18:21], v[196:199], v[220:223], v[18:21]
	ds_read_b128 v[236:239], v245 offset:41536
	s_waitcnt lgkmcnt(6)
	v_mfma_f32_16x16x32_bf16 v[22:25], v[196:199], v[224:227], v[22:25]
	ds_read_b128 v[240:243], v245 offset:43840
	ds_read_b128 v[196:199], v244 offset:64
	s_waitcnt lgkmcnt(7)
	v_mfma_f32_16x16x32_bf16 v[58:61], v[200:203], v[212:215], v[58:61]
	v_mfma_f32_16x16x32_bf16 v[62:65], v[200:203], v[216:219], v[62:65]
	v_mfma_f32_16x16x32_bf16 v[26:29], v[200:203], v[220:223], v[26:29]
	v_mfma_f32_16x16x32_bf16 v[30:33], v[200:203], v[224:227], v[30:33]
	ds_read_b128 v[200:203], v244 offset:2368
	s_waitcnt lgkmcnt(7)
	v_mfma_f32_16x16x32_bf16 v[34:37], v[204:207], v[212:215], v[34:37]
	v_mfma_f32_16x16x32_bf16 v[38:41], v[204:207], v[216:219], v[38:41]
	v_mfma_f32_16x16x32_bf16 v[2:5], v[204:207], v[220:223], v[2:5]
	v_mfma_f32_16x16x32_bf16 v[6:9], v[204:207], v[224:227], v[6:9]
	ds_read_b128 v[204:207], v244 offset:4672
	s_setprio 1
	s_waitcnt vmcnt(15)
	ds_write_b128 v98, v[102:105] offset:18432
	s_waitcnt vmcnt(14)
	ds_write_b128 v98, v[106:109] offset:23040
	s_waitcnt lgkmcnt(9)
	v_mfma_f32_16x16x32_bf16 v[42:45], v[208:211], v[212:215], v[42:45]
	v_mfma_f32_16x16x32_bf16 v[46:49], v[208:211], v[216:219], v[46:49]
	v_mfma_f32_16x16x32_bf16 v[10:13], v[208:211], v[220:223], v[10:13]
	v_mfma_f32_16x16x32_bf16 v[14:17], v[208:211], v[224:227], v[14:17]
	ds_read_b128 v[208:211], v244 offset:6976
	s_waitcnt vmcnt(13)
	ds_write_b128 v98, v[110:113] offset:27648
	s_waitcnt vmcnt(12)
	ds_write_b128 v98, v[114:117] offset:32256
	s_waitcnt lgkmcnt(7)
	v_mfma_f32_16x16x32_bf16 v[50:53], v[196:199], v[228:231], v[50:53]
	v_mfma_f32_16x16x32_bf16 v[54:57], v[196:199], v[232:235], v[54:57]
	v_mfma_f32_16x16x32_bf16 v[18:21], v[196:199], v[236:239], v[18:21]
	v_mfma_f32_16x16x32_bf16 v[22:25], v[196:199], v[240:243], v[22:25]
	s_waitcnt vmcnt(11)
	ds_write_b128 v98, v[118:121] offset:55296
	s_waitcnt vmcnt(10)
	ds_write_b128 v98, v[122:125] offset:59904
	s_waitcnt lgkmcnt(8)
	v_mfma_f32_16x16x32_bf16 v[58:61], v[200:203], v[228:231], v[58:61]
	v_mfma_f32_16x16x32_bf16 v[62:65], v[200:203], v[232:235], v[62:65]
	v_mfma_f32_16x16x32_bf16 v[26:29], v[200:203], v[236:239], v[26:29]
	v_mfma_f32_16x16x32_bf16 v[30:33], v[200:203], v[240:243], v[30:33]
	s_waitcnt vmcnt(9)
	ds_write_b128 v98, v[126:129] offset:64512
	s_waitcnt vmcnt(8)
	ds_write_b128 v99, v[132:135] offset:32256
	s_waitcnt lgkmcnt(0)
	s_barrier
	s_setprio 0
	ds_read_b128 v[212:215], v245 offset:55296
	ds_read_b128 v[196:199], v244 offset:18432
	ds_read_b128 v[216:219], v245 offset:57600
	ds_read_b128 v[220:223], v245 offset:59904
	ds_read_b128 v[224:227], v245 offset:62208
	ds_read_b128 v[200:203], v244 offset:20736
	v_mfma_f32_16x16x32_bf16 v[34:37], v[204:207], v[228:231], v[34:37]
	v_mfma_f32_16x16x32_bf16 v[38:41], v[204:207], v[232:235], v[38:41]
	v_mfma_f32_16x16x32_bf16 v[2:5], v[204:207], v[236:239], v[2:5]
	v_mfma_f32_16x16x32_bf16 v[6:9], v[204:207], v[240:243], v[6:9]
	ds_read_b128 v[204:207], v244 offset:23040
	v_mfma_f32_16x16x32_bf16 v[42:45], v[208:211], v[228:231], v[42:45]
	v_mfma_f32_16x16x32_bf16 v[46:49], v[208:211], v[232:235], v[46:49]
	v_mfma_f32_16x16x32_bf16 v[10:13], v[208:211], v[236:239], v[10:13]
	v_mfma_f32_16x16x32_bf16 v[14:17], v[208:211], v[240:243], v[14:17]
	ds_read_b128 v[208:211], v244 offset:25344
	global_load_dwordx4 v[102:105], v[74:75], off offset:896
	global_load_dwordx4 v[106:109], v[76:77], off offset:896
	global_load_dwordx4 v[110:113], v[78:79], off offset:896
	global_load_dwordx4 v[114:117], v[80:81], off offset:896
	global_load_dwordx4 v[118:121], v[82:83], off offset:896
	global_load_dwordx4 v[122:125], v[84:85], off offset:896
	global_load_dwordx4 v[126:129], v[86:87], off offset:896
	global_load_dwordx4 v[132:135], v[88:89], off offset:896
	s_waitcnt lgkmcnt(6)
	v_mfma_f32_16x16x32_bf16 v[50:53], v[196:199], v[212:215], v[50:53]
	ds_read_b128 v[228:231], v245 offset:55360
	s_waitcnt lgkmcnt(6)
	v_mfma_f32_16x16x32_bf16 v[54:57], v[196:199], v[216:219], v[54:57]
	ds_read_b128 v[232:235], v245 offset:57664
	s_waitcnt lgkmcnt(6)
	v_mfma_f32_16x16x32_bf16 v[18:21], v[196:199], v[220:223], v[18:21]
	ds_read_b128 v[236:239], v245 offset:59968
	s_waitcnt lgkmcnt(6)
	v_mfma_f32_16x16x32_bf16 v[22:25], v[196:199], v[224:227], v[22:25]
	ds_read_b128 v[240:243], v245 offset:62272
	ds_read_b128 v[196:199], v244 offset:18496
	s_waitcnt lgkmcnt(7)
	v_mfma_f32_16x16x32_bf16 v[58:61], v[200:203], v[212:215], v[58:61]
	v_mfma_f32_16x16x32_bf16 v[62:65], v[200:203], v[216:219], v[62:65]
	v_mfma_f32_16x16x32_bf16 v[26:29], v[200:203], v[220:223], v[26:29]
	v_mfma_f32_16x16x32_bf16 v[30:33], v[200:203], v[224:227], v[30:33]
	ds_read_b128 v[200:203], v244 offset:20800
	s_waitcnt lgkmcnt(7)
	v_mfma_f32_16x16x32_bf16 v[34:37], v[204:207], v[212:215], v[34:37]
	v_mfma_f32_16x16x32_bf16 v[38:41], v[204:207], v[216:219], v[38:41]
	v_mfma_f32_16x16x32_bf16 v[2:5], v[204:207], v[220:223], v[2:5]
	v_mfma_f32_16x16x32_bf16 v[6:9], v[204:207], v[224:227], v[6:9]
	ds_read_b128 v[204:207], v244 offset:23104
	s_setprio 1
	s_waitcnt vmcnt(15)
	ds_write_b128 v98, v[136:139]
	s_waitcnt vmcnt(14)
	ds_write_b128 v98, v[140:143] offset:4608
	s_waitcnt lgkmcnt(9)
	v_mfma_f32_16x16x32_bf16 v[42:45], v[208:211], v[212:215], v[42:45]
	v_mfma_f32_16x16x32_bf16 v[46:49], v[208:211], v[216:219], v[46:49]
	v_mfma_f32_16x16x32_bf16 v[10:13], v[208:211], v[220:223], v[10:13]
	v_mfma_f32_16x16x32_bf16 v[14:17], v[208:211], v[224:227], v[14:17]
	ds_read_b128 v[208:211], v244 offset:25408
	s_waitcnt vmcnt(13)
	ds_write_b128 v98, v[144:147] offset:9216
	s_waitcnt vmcnt(12)
	ds_write_b128 v98, v[148:151] offset:13824
	s_waitcnt lgkmcnt(7)
	v_mfma_f32_16x16x32_bf16 v[50:53], v[196:199], v[228:231], v[50:53]
	v_mfma_f32_16x16x32_bf16 v[54:57], v[196:199], v[232:235], v[54:57]
	v_mfma_f32_16x16x32_bf16 v[18:21], v[196:199], v[236:239], v[18:21]
	v_mfma_f32_16x16x32_bf16 v[22:25], v[196:199], v[240:243], v[22:25]
	s_waitcnt vmcnt(11)
	ds_write_b128 v98, v[152:155] offset:36864
	s_waitcnt vmcnt(10)
	ds_write_b128 v98, v[156:159] offset:41472
	s_waitcnt lgkmcnt(8)
	v_mfma_f32_16x16x32_bf16 v[58:61], v[200:203], v[228:231], v[58:61]
	v_mfma_f32_16x16x32_bf16 v[62:65], v[200:203], v[232:235], v[62:65]
	v_mfma_f32_16x16x32_bf16 v[26:29], v[200:203], v[236:239], v[26:29]
	v_mfma_f32_16x16x32_bf16 v[30:33], v[200:203], v[240:243], v[30:33]
	s_waitcnt vmcnt(9)
	ds_write_b128 v98, v[160:163] offset:46080
	s_waitcnt vmcnt(8)
	ds_write_b128 v98, v[164:167] offset:50688
	s_waitcnt lgkmcnt(0)
	s_barrier
	s_setprio 0
	ds_read_b128 v[212:215], v245 offset:36864
	ds_read_b128 v[196:199], v244
	ds_read_b128 v[216:219], v245 offset:39168
	ds_read_b128 v[220:223], v245 offset:41472
	ds_read_b128 v[224:227], v245 offset:43776
	ds_read_b128 v[200:203], v244 offset:2304
	v_mfma_f32_16x16x32_bf16 v[34:37], v[204:207], v[228:231], v[34:37]
	v_mfma_f32_16x16x32_bf16 v[38:41], v[204:207], v[232:235], v[38:41]
	v_mfma_f32_16x16x32_bf16 v[2:5], v[204:207], v[236:239], v[2:5]
	v_mfma_f32_16x16x32_bf16 v[6:9], v[204:207], v[240:243], v[6:9]
	ds_read_b128 v[204:207], v244 offset:4608
	v_mfma_f32_16x16x32_bf16 v[42:45], v[208:211], v[228:231], v[42:45]
	v_mfma_f32_16x16x32_bf16 v[46:49], v[208:211], v[232:235], v[46:49]
	v_mfma_f32_16x16x32_bf16 v[10:13], v[208:211], v[236:239], v[10:13]
	v_mfma_f32_16x16x32_bf16 v[14:17], v[208:211], v[240:243], v[14:17]
	ds_read_b128 v[208:211], v244 offset:6912
	global_load_dwordx4 v[136:139], v[74:75], off offset:1024
	global_load_dwordx4 v[140:143], v[76:77], off offset:1024
	global_load_dwordx4 v[144:147], v[78:79], off offset:1024
	global_load_dwordx4 v[148:151], v[80:81], off offset:1024
	global_load_dwordx4 v[152:155], v[82:83], off offset:1024
	global_load_dwordx4 v[156:159], v[84:85], off offset:1024
	global_load_dwordx4 v[160:163], v[86:87], off offset:1024
	global_load_dwordx4 v[164:167], v[88:89], off offset:1024
	s_waitcnt lgkmcnt(6)
	v_mfma_f32_16x16x32_bf16 v[50:53], v[196:199], v[212:215], v[50:53]
	ds_read_b128 v[228:231], v245 offset:36928
	s_waitcnt lgkmcnt(6)
	v_mfma_f32_16x16x32_bf16 v[54:57], v[196:199], v[216:219], v[54:57]
	ds_read_b128 v[232:235], v245 offset:39232
	s_waitcnt lgkmcnt(6)
	v_mfma_f32_16x16x32_bf16 v[18:21], v[196:199], v[220:223], v[18:21]
	ds_read_b128 v[236:239], v245 offset:41536
	s_waitcnt lgkmcnt(6)
	v_mfma_f32_16x16x32_bf16 v[22:25], v[196:199], v[224:227], v[22:25]
	ds_read_b128 v[240:243], v245 offset:43840
	ds_read_b128 v[196:199], v244 offset:64
	s_waitcnt lgkmcnt(7)
	v_mfma_f32_16x16x32_bf16 v[58:61], v[200:203], v[212:215], v[58:61]
	v_mfma_f32_16x16x32_bf16 v[62:65], v[200:203], v[216:219], v[62:65]
	v_mfma_f32_16x16x32_bf16 v[26:29], v[200:203], v[220:223], v[26:29]
	v_mfma_f32_16x16x32_bf16 v[30:33], v[200:203], v[224:227], v[30:33]
	ds_read_b128 v[200:203], v244 offset:2368
	s_waitcnt lgkmcnt(7)
	v_mfma_f32_16x16x32_bf16 v[34:37], v[204:207], v[212:215], v[34:37]
	v_mfma_f32_16x16x32_bf16 v[38:41], v[204:207], v[216:219], v[38:41]
	v_mfma_f32_16x16x32_bf16 v[2:5], v[204:207], v[220:223], v[2:5]
	v_mfma_f32_16x16x32_bf16 v[6:9], v[204:207], v[224:227], v[6:9]
	ds_read_b128 v[204:207], v244 offset:4672
	s_setprio 1
	s_waitcnt vmcnt(15)
	ds_write_b128 v98, v[102:105] offset:18432
	s_waitcnt vmcnt(14)
	ds_write_b128 v98, v[106:109] offset:23040
	s_waitcnt lgkmcnt(9)
	v_mfma_f32_16x16x32_bf16 v[42:45], v[208:211], v[212:215], v[42:45]
	v_mfma_f32_16x16x32_bf16 v[46:49], v[208:211], v[216:219], v[46:49]
	v_mfma_f32_16x16x32_bf16 v[10:13], v[208:211], v[220:223], v[10:13]
	v_mfma_f32_16x16x32_bf16 v[14:17], v[208:211], v[224:227], v[14:17]
	ds_read_b128 v[208:211], v244 offset:6976
	s_waitcnt vmcnt(13)
	ds_write_b128 v98, v[110:113] offset:27648
	s_waitcnt vmcnt(12)
	ds_write_b128 v98, v[114:117] offset:32256
	s_waitcnt lgkmcnt(7)
	v_mfma_f32_16x16x32_bf16 v[50:53], v[196:199], v[228:231], v[50:53]
	v_mfma_f32_16x16x32_bf16 v[54:57], v[196:199], v[232:235], v[54:57]
	v_mfma_f32_16x16x32_bf16 v[18:21], v[196:199], v[236:239], v[18:21]
	v_mfma_f32_16x16x32_bf16 v[22:25], v[196:199], v[240:243], v[22:25]
	s_waitcnt vmcnt(11)
	ds_write_b128 v98, v[118:121] offset:55296
	s_waitcnt vmcnt(10)
	ds_write_b128 v98, v[122:125] offset:59904
	s_waitcnt lgkmcnt(8)
	v_mfma_f32_16x16x32_bf16 v[58:61], v[200:203], v[228:231], v[58:61]
	v_mfma_f32_16x16x32_bf16 v[62:65], v[200:203], v[232:235], v[62:65]
	v_mfma_f32_16x16x32_bf16 v[26:29], v[200:203], v[236:239], v[26:29]
	v_mfma_f32_16x16x32_bf16 v[30:33], v[200:203], v[240:243], v[30:33]
	s_waitcnt vmcnt(9)
	ds_write_b128 v98, v[126:129] offset:64512
	s_waitcnt vmcnt(8)
	ds_write_b128 v99, v[132:135] offset:32256
	s_waitcnt lgkmcnt(0)
	s_barrier
	s_setprio 0
	ds_read_b128 v[212:215], v245 offset:55296
	ds_read_b128 v[196:199], v244 offset:18432
	ds_read_b128 v[216:219], v245 offset:57600
	ds_read_b128 v[220:223], v245 offset:59904
	ds_read_b128 v[224:227], v245 offset:62208
	ds_read_b128 v[200:203], v244 offset:20736
	v_mfma_f32_16x16x32_bf16 v[34:37], v[204:207], v[228:231], v[34:37]
	v_mfma_f32_16x16x32_bf16 v[38:41], v[204:207], v[232:235], v[38:41]
	v_mfma_f32_16x16x32_bf16 v[2:5], v[204:207], v[236:239], v[2:5]
	v_mfma_f32_16x16x32_bf16 v[6:9], v[204:207], v[240:243], v[6:9]
	ds_read_b128 v[204:207], v244 offset:23040
	v_mfma_f32_16x16x32_bf16 v[42:45], v[208:211], v[228:231], v[42:45]
	v_mfma_f32_16x16x32_bf16 v[46:49], v[208:211], v[232:235], v[46:49]
	v_mfma_f32_16x16x32_bf16 v[10:13], v[208:211], v[236:239], v[10:13]
	v_mfma_f32_16x16x32_bf16 v[14:17], v[208:211], v[240:243], v[14:17]
	ds_read_b128 v[208:211], v244 offset:25344
	global_load_dwordx4 v[102:105], v[74:75], off offset:1152
	global_load_dwordx4 v[106:109], v[76:77], off offset:1152
	global_load_dwordx4 v[110:113], v[78:79], off offset:1152
	global_load_dwordx4 v[114:117], v[80:81], off offset:1152
	global_load_dwordx4 v[118:121], v[82:83], off offset:1152
	global_load_dwordx4 v[122:125], v[84:85], off offset:1152
	global_load_dwordx4 v[126:129], v[86:87], off offset:1152
	global_load_dwordx4 v[132:135], v[88:89], off offset:1152
	s_waitcnt lgkmcnt(6)
	v_mfma_f32_16x16x32_bf16 v[50:53], v[196:199], v[212:215], v[50:53]
	ds_read_b128 v[228:231], v245 offset:55360
	s_waitcnt lgkmcnt(6)
	v_mfma_f32_16x16x32_bf16 v[54:57], v[196:199], v[216:219], v[54:57]
	ds_read_b128 v[232:235], v245 offset:57664
	s_waitcnt lgkmcnt(6)
	v_mfma_f32_16x16x32_bf16 v[18:21], v[196:199], v[220:223], v[18:21]
	ds_read_b128 v[236:239], v245 offset:59968
	s_waitcnt lgkmcnt(6)
	v_mfma_f32_16x16x32_bf16 v[22:25], v[196:199], v[224:227], v[22:25]
	ds_read_b128 v[240:243], v245 offset:62272
	ds_read_b128 v[196:199], v244 offset:18496
	s_waitcnt lgkmcnt(7)
	v_mfma_f32_16x16x32_bf16 v[58:61], v[200:203], v[212:215], v[58:61]
	v_mfma_f32_16x16x32_bf16 v[62:65], v[200:203], v[216:219], v[62:65]
	v_mfma_f32_16x16x32_bf16 v[26:29], v[200:203], v[220:223], v[26:29]
	v_mfma_f32_16x16x32_bf16 v[30:33], v[200:203], v[224:227], v[30:33]
	ds_read_b128 v[200:203], v244 offset:20800
	s_waitcnt lgkmcnt(7)
	v_mfma_f32_16x16x32_bf16 v[34:37], v[204:207], v[212:215], v[34:37]
	v_mfma_f32_16x16x32_bf16 v[38:41], v[204:207], v[216:219], v[38:41]
	v_mfma_f32_16x16x32_bf16 v[2:5], v[204:207], v[220:223], v[2:5]
	v_mfma_f32_16x16x32_bf16 v[6:9], v[204:207], v[224:227], v[6:9]
	ds_read_b128 v[204:207], v244 offset:23104
	s_setprio 1
	s_waitcnt vmcnt(15)
	ds_write_b128 v98, v[136:139]
	s_waitcnt vmcnt(14)
	ds_write_b128 v98, v[140:143] offset:4608
	s_waitcnt lgkmcnt(9)
	v_mfma_f32_16x16x32_bf16 v[42:45], v[208:211], v[212:215], v[42:45]
	v_mfma_f32_16x16x32_bf16 v[46:49], v[208:211], v[216:219], v[46:49]
	v_mfma_f32_16x16x32_bf16 v[10:13], v[208:211], v[220:223], v[10:13]
	v_mfma_f32_16x16x32_bf16 v[14:17], v[208:211], v[224:227], v[14:17]
	ds_read_b128 v[208:211], v244 offset:25408
	s_waitcnt vmcnt(13)
	ds_write_b128 v98, v[144:147] offset:9216
	s_waitcnt vmcnt(12)
	ds_write_b128 v98, v[148:151] offset:13824
	s_waitcnt lgkmcnt(7)
	v_mfma_f32_16x16x32_bf16 v[50:53], v[196:199], v[228:231], v[50:53]
	v_mfma_f32_16x16x32_bf16 v[54:57], v[196:199], v[232:235], v[54:57]
	v_mfma_f32_16x16x32_bf16 v[18:21], v[196:199], v[236:239], v[18:21]
	v_mfma_f32_16x16x32_bf16 v[22:25], v[196:199], v[240:243], v[22:25]
	s_waitcnt vmcnt(11)
	ds_write_b128 v98, v[152:155] offset:36864
	s_waitcnt vmcnt(10)
	ds_write_b128 v98, v[156:159] offset:41472
	s_waitcnt lgkmcnt(8)
	v_mfma_f32_16x16x32_bf16 v[58:61], v[200:203], v[228:231], v[58:61]
	v_mfma_f32_16x16x32_bf16 v[62:65], v[200:203], v[232:235], v[62:65]
	v_mfma_f32_16x16x32_bf16 v[26:29], v[200:203], v[236:239], v[26:29]
	v_mfma_f32_16x16x32_bf16 v[30:33], v[200:203], v[240:243], v[30:33]
	s_waitcnt vmcnt(9)
	ds_write_b128 v98, v[160:163] offset:46080
	s_waitcnt vmcnt(8)
	ds_write_b128 v98, v[164:167] offset:50688
	s_waitcnt lgkmcnt(0)
	s_barrier
	s_setprio 0
	ds_read_b128 v[212:215], v245 offset:36864
	ds_read_b128 v[196:199], v244
	ds_read_b128 v[216:219], v245 offset:39168
	ds_read_b128 v[220:223], v245 offset:41472
	ds_read_b128 v[224:227], v245 offset:43776
	ds_read_b128 v[200:203], v244 offset:2304
	v_mfma_f32_16x16x32_bf16 v[34:37], v[204:207], v[228:231], v[34:37]
	v_mfma_f32_16x16x32_bf16 v[38:41], v[204:207], v[232:235], v[38:41]
	v_mfma_f32_16x16x32_bf16 v[2:5], v[204:207], v[236:239], v[2:5]
	v_mfma_f32_16x16x32_bf16 v[6:9], v[204:207], v[240:243], v[6:9]
	ds_read_b128 v[204:207], v244 offset:4608
	v_mfma_f32_16x16x32_bf16 v[42:45], v[208:211], v[228:231], v[42:45]
	v_mfma_f32_16x16x32_bf16 v[46:49], v[208:211], v[232:235], v[46:49]
	v_mfma_f32_16x16x32_bf16 v[10:13], v[208:211], v[236:239], v[10:13]
	v_mfma_f32_16x16x32_bf16 v[14:17], v[208:211], v[240:243], v[14:17]
	ds_read_b128 v[208:211], v244 offset:6912
	global_load_dwordx4 v[136:139], v[74:75], off offset:1280
	global_load_dwordx4 v[140:143], v[76:77], off offset:1280
	global_load_dwordx4 v[144:147], v[78:79], off offset:1280
	global_load_dwordx4 v[148:151], v[80:81], off offset:1280
	global_load_dwordx4 v[152:155], v[82:83], off offset:1280
	global_load_dwordx4 v[156:159], v[84:85], off offset:1280
	global_load_dwordx4 v[160:163], v[86:87], off offset:1280
	global_load_dwordx4 v[164:167], v[88:89], off offset:1280
	s_waitcnt lgkmcnt(6)
	v_mfma_f32_16x16x32_bf16 v[50:53], v[196:199], v[212:215], v[50:53]
	ds_read_b128 v[228:231], v245 offset:36928
	s_waitcnt lgkmcnt(6)
	v_mfma_f32_16x16x32_bf16 v[54:57], v[196:199], v[216:219], v[54:57]
	ds_read_b128 v[232:235], v245 offset:39232
	s_waitcnt lgkmcnt(6)
	v_mfma_f32_16x16x32_bf16 v[18:21], v[196:199], v[220:223], v[18:21]
	ds_read_b128 v[236:239], v245 offset:41536
	s_waitcnt lgkmcnt(6)
	v_mfma_f32_16x16x32_bf16 v[22:25], v[196:199], v[224:227], v[22:25]
	ds_read_b128 v[240:243], v245 offset:43840
	ds_read_b128 v[196:199], v244 offset:64
	s_waitcnt lgkmcnt(7)
	v_mfma_f32_16x16x32_bf16 v[58:61], v[200:203], v[212:215], v[58:61]
	v_mfma_f32_16x16x32_bf16 v[62:65], v[200:203], v[216:219], v[62:65]
	v_mfma_f32_16x16x32_bf16 v[26:29], v[200:203], v[220:223], v[26:29]
	v_mfma_f32_16x16x32_bf16 v[30:33], v[200:203], v[224:227], v[30:33]
	ds_read_b128 v[200:203], v244 offset:2368
	s_waitcnt lgkmcnt(7)
	v_mfma_f32_16x16x32_bf16 v[34:37], v[204:207], v[212:215], v[34:37]
	v_mfma_f32_16x16x32_bf16 v[38:41], v[204:207], v[216:219], v[38:41]
	v_mfma_f32_16x16x32_bf16 v[2:5], v[204:207], v[220:223], v[2:5]
	v_mfma_f32_16x16x32_bf16 v[6:9], v[204:207], v[224:227], v[6:9]
	ds_read_b128 v[204:207], v244 offset:4672
	s_setprio 1
	s_waitcnt vmcnt(15)
	ds_write_b128 v98, v[102:105] offset:18432
	s_waitcnt vmcnt(14)
	ds_write_b128 v98, v[106:109] offset:23040
	s_waitcnt lgkmcnt(9)
	v_mfma_f32_16x16x32_bf16 v[42:45], v[208:211], v[212:215], v[42:45]
	v_mfma_f32_16x16x32_bf16 v[46:49], v[208:211], v[216:219], v[46:49]
	v_mfma_f32_16x16x32_bf16 v[10:13], v[208:211], v[220:223], v[10:13]
	v_mfma_f32_16x16x32_bf16 v[14:17], v[208:211], v[224:227], v[14:17]
	ds_read_b128 v[208:211], v244 offset:6976
	s_waitcnt vmcnt(13)
	ds_write_b128 v98, v[110:113] offset:27648
	s_waitcnt vmcnt(12)
	ds_write_b128 v98, v[114:117] offset:32256
	s_waitcnt lgkmcnt(7)
	v_mfma_f32_16x16x32_bf16 v[50:53], v[196:199], v[228:231], v[50:53]
	v_mfma_f32_16x16x32_bf16 v[54:57], v[196:199], v[232:235], v[54:57]
	v_mfma_f32_16x16x32_bf16 v[18:21], v[196:199], v[236:239], v[18:21]
	v_mfma_f32_16x16x32_bf16 v[22:25], v[196:199], v[240:243], v[22:25]
	s_waitcnt vmcnt(11)
	ds_write_b128 v98, v[118:121] offset:55296
	s_waitcnt vmcnt(10)
	ds_write_b128 v98, v[122:125] offset:59904
	s_waitcnt lgkmcnt(8)
	v_mfma_f32_16x16x32_bf16 v[58:61], v[200:203], v[228:231], v[58:61]
	v_mfma_f32_16x16x32_bf16 v[62:65], v[200:203], v[232:235], v[62:65]
	v_mfma_f32_16x16x32_bf16 v[26:29], v[200:203], v[236:239], v[26:29]
	v_mfma_f32_16x16x32_bf16 v[30:33], v[200:203], v[240:243], v[30:33]
	s_waitcnt vmcnt(9)
	ds_write_b128 v98, v[126:129] offset:64512
	s_waitcnt vmcnt(8)
	ds_write_b128 v99, v[132:135] offset:32256
	s_waitcnt lgkmcnt(0)
	s_barrier
	s_setprio 0
	ds_read_b128 v[212:215], v245 offset:55296
	ds_read_b128 v[196:199], v244 offset:18432
	ds_read_b128 v[216:219], v245 offset:57600
	ds_read_b128 v[220:223], v245 offset:59904
	ds_read_b128 v[224:227], v245 offset:62208
	ds_read_b128 v[200:203], v244 offset:20736
	v_mfma_f32_16x16x32_bf16 v[34:37], v[204:207], v[228:231], v[34:37]
	v_mfma_f32_16x16x32_bf16 v[38:41], v[204:207], v[232:235], v[38:41]
	v_mfma_f32_16x16x32_bf16 v[2:5], v[204:207], v[236:239], v[2:5]
	v_mfma_f32_16x16x32_bf16 v[6:9], v[204:207], v[240:243], v[6:9]
	ds_read_b128 v[204:207], v244 offset:23040
	v_mfma_f32_16x16x32_bf16 v[42:45], v[208:211], v[228:231], v[42:45]
	v_mfma_f32_16x16x32_bf16 v[46:49], v[208:211], v[232:235], v[46:49]
	v_mfma_f32_16x16x32_bf16 v[10:13], v[208:211], v[236:239], v[10:13]
	v_mfma_f32_16x16x32_bf16 v[14:17], v[208:211], v[240:243], v[14:17]
	ds_read_b128 v[208:211], v244 offset:25344
	global_load_dwordx4 v[102:105], v[74:75], off offset:1408
	global_load_dwordx4 v[106:109], v[76:77], off offset:1408
	global_load_dwordx4 v[110:113], v[78:79], off offset:1408
	global_load_dwordx4 v[114:117], v[80:81], off offset:1408
	global_load_dwordx4 v[118:121], v[82:83], off offset:1408
	global_load_dwordx4 v[122:125], v[84:85], off offset:1408
	global_load_dwordx4 v[126:129], v[86:87], off offset:1408
	global_load_dwordx4 v[132:135], v[88:89], off offset:1408
	s_waitcnt lgkmcnt(6)
	v_mfma_f32_16x16x32_bf16 v[50:53], v[196:199], v[212:215], v[50:53]
	ds_read_b128 v[228:231], v245 offset:55360
	s_waitcnt lgkmcnt(6)
	v_mfma_f32_16x16x32_bf16 v[54:57], v[196:199], v[216:219], v[54:57]
	ds_read_b128 v[232:235], v245 offset:57664
	s_waitcnt lgkmcnt(6)
	v_mfma_f32_16x16x32_bf16 v[18:21], v[196:199], v[220:223], v[18:21]
	ds_read_b128 v[236:239], v245 offset:59968
	s_waitcnt lgkmcnt(6)
	v_mfma_f32_16x16x32_bf16 v[22:25], v[196:199], v[224:227], v[22:25]
	ds_read_b128 v[240:243], v245 offset:62272
	ds_read_b128 v[196:199], v244 offset:18496
	s_waitcnt lgkmcnt(7)
	v_mfma_f32_16x16x32_bf16 v[58:61], v[200:203], v[212:215], v[58:61]
	v_mfma_f32_16x16x32_bf16 v[62:65], v[200:203], v[216:219], v[62:65]
	v_mfma_f32_16x16x32_bf16 v[26:29], v[200:203], v[220:223], v[26:29]
	v_mfma_f32_16x16x32_bf16 v[30:33], v[200:203], v[224:227], v[30:33]
	ds_read_b128 v[200:203], v244 offset:20800
	s_waitcnt lgkmcnt(7)
	v_mfma_f32_16x16x32_bf16 v[34:37], v[204:207], v[212:215], v[34:37]
	v_mfma_f32_16x16x32_bf16 v[38:41], v[204:207], v[216:219], v[38:41]
	v_mfma_f32_16x16x32_bf16 v[2:5], v[204:207], v[220:223], v[2:5]
	v_mfma_f32_16x16x32_bf16 v[6:9], v[204:207], v[224:227], v[6:9]
	ds_read_b128 v[204:207], v244 offset:23104
	s_setprio 1
	s_waitcnt vmcnt(15)
	ds_write_b128 v98, v[136:139]
	s_waitcnt vmcnt(14)
	ds_write_b128 v98, v[140:143] offset:4608
	s_waitcnt lgkmcnt(9)
	v_mfma_f32_16x16x32_bf16 v[42:45], v[208:211], v[212:215], v[42:45]
	v_mfma_f32_16x16x32_bf16 v[46:49], v[208:211], v[216:219], v[46:49]
	v_mfma_f32_16x16x32_bf16 v[10:13], v[208:211], v[220:223], v[10:13]
	v_mfma_f32_16x16x32_bf16 v[14:17], v[208:211], v[224:227], v[14:17]
	ds_read_b128 v[208:211], v244 offset:25408
	s_waitcnt vmcnt(13)
	ds_write_b128 v98, v[144:147] offset:9216
	s_waitcnt vmcnt(12)
	ds_write_b128 v98, v[148:151] offset:13824
	s_waitcnt lgkmcnt(7)
	v_mfma_f32_16x16x32_bf16 v[50:53], v[196:199], v[228:231], v[50:53]
	v_mfma_f32_16x16x32_bf16 v[54:57], v[196:199], v[232:235], v[54:57]
	v_mfma_f32_16x16x32_bf16 v[18:21], v[196:199], v[236:239], v[18:21]
	v_mfma_f32_16x16x32_bf16 v[22:25], v[196:199], v[240:243], v[22:25]
	s_waitcnt vmcnt(11)
	ds_write_b128 v98, v[152:155] offset:36864
	s_waitcnt vmcnt(10)
	ds_write_b128 v98, v[156:159] offset:41472
	s_waitcnt lgkmcnt(8)
	v_mfma_f32_16x16x32_bf16 v[58:61], v[200:203], v[228:231], v[58:61]
	v_mfma_f32_16x16x32_bf16 v[62:65], v[200:203], v[232:235], v[62:65]
	v_mfma_f32_16x16x32_bf16 v[26:29], v[200:203], v[236:239], v[26:29]
	v_mfma_f32_16x16x32_bf16 v[30:33], v[200:203], v[240:243], v[30:33]
	s_waitcnt vmcnt(9)
	ds_write_b128 v98, v[160:163] offset:46080
	s_waitcnt vmcnt(8)
	ds_write_b128 v98, v[164:167] offset:50688
	s_waitcnt lgkmcnt(0)
	s_barrier
	s_setprio 0
	ds_read_b128 v[212:215], v245 offset:36864
	ds_read_b128 v[196:199], v244
	ds_read_b128 v[216:219], v245 offset:39168
	ds_read_b128 v[220:223], v245 offset:41472
	ds_read_b128 v[224:227], v245 offset:43776
	ds_read_b128 v[200:203], v244 offset:2304
	v_mfma_f32_16x16x32_bf16 v[34:37], v[204:207], v[228:231], v[34:37]
	v_mfma_f32_16x16x32_bf16 v[38:41], v[204:207], v[232:235], v[38:41]
	v_mfma_f32_16x16x32_bf16 v[2:5], v[204:207], v[236:239], v[2:5]
	v_mfma_f32_16x16x32_bf16 v[6:9], v[204:207], v[240:243], v[6:9]
	ds_read_b128 v[204:207], v244 offset:4608
	v_mfma_f32_16x16x32_bf16 v[42:45], v[208:211], v[228:231], v[42:45]
	v_mfma_f32_16x16x32_bf16 v[46:49], v[208:211], v[232:235], v[46:49]
	v_mfma_f32_16x16x32_bf16 v[10:13], v[208:211], v[236:239], v[10:13]
	v_mfma_f32_16x16x32_bf16 v[14:17], v[208:211], v[240:243], v[14:17]
	ds_read_b128 v[208:211], v244 offset:6912
	global_load_dwordx4 v[136:139], v[74:75], off offset:1536
	global_load_dwordx4 v[140:143], v[76:77], off offset:1536
	global_load_dwordx4 v[144:147], v[78:79], off offset:1536
	global_load_dwordx4 v[148:151], v[80:81], off offset:1536
	global_load_dwordx4 v[152:155], v[82:83], off offset:1536
	global_load_dwordx4 v[156:159], v[84:85], off offset:1536
	global_load_dwordx4 v[160:163], v[86:87], off offset:1536
	global_load_dwordx4 v[164:167], v[88:89], off offset:1536
	s_waitcnt lgkmcnt(6)
	v_mfma_f32_16x16x32_bf16 v[50:53], v[196:199], v[212:215], v[50:53]
	ds_read_b128 v[228:231], v245 offset:36928
	s_waitcnt lgkmcnt(6)
	v_mfma_f32_16x16x32_bf16 v[54:57], v[196:199], v[216:219], v[54:57]
	ds_read_b128 v[232:235], v245 offset:39232
	s_waitcnt lgkmcnt(6)
	v_mfma_f32_16x16x32_bf16 v[18:21], v[196:199], v[220:223], v[18:21]
	ds_read_b128 v[236:239], v245 offset:41536
	s_waitcnt lgkmcnt(6)
	v_mfma_f32_16x16x32_bf16 v[22:25], v[196:199], v[224:227], v[22:25]
	ds_read_b128 v[240:243], v245 offset:43840
	ds_read_b128 v[196:199], v244 offset:64
	s_waitcnt lgkmcnt(7)
	v_mfma_f32_16x16x32_bf16 v[58:61], v[200:203], v[212:215], v[58:61]
	v_mfma_f32_16x16x32_bf16 v[62:65], v[200:203], v[216:219], v[62:65]
	v_mfma_f32_16x16x32_bf16 v[26:29], v[200:203], v[220:223], v[26:29]
	v_mfma_f32_16x16x32_bf16 v[30:33], v[200:203], v[224:227], v[30:33]
	ds_read_b128 v[200:203], v244 offset:2368
	s_waitcnt lgkmcnt(7)
	v_mfma_f32_16x16x32_bf16 v[34:37], v[204:207], v[212:215], v[34:37]
	v_mfma_f32_16x16x32_bf16 v[38:41], v[204:207], v[216:219], v[38:41]
	v_mfma_f32_16x16x32_bf16 v[2:5], v[204:207], v[220:223], v[2:5]
	v_mfma_f32_16x16x32_bf16 v[6:9], v[204:207], v[224:227], v[6:9]
	ds_read_b128 v[204:207], v244 offset:4672
	s_setprio 1
	s_waitcnt vmcnt(15)
	ds_write_b128 v98, v[102:105] offset:18432
	s_waitcnt vmcnt(14)
	ds_write_b128 v98, v[106:109] offset:23040
	s_waitcnt lgkmcnt(9)
	v_mfma_f32_16x16x32_bf16 v[42:45], v[208:211], v[212:215], v[42:45]
	v_mfma_f32_16x16x32_bf16 v[46:49], v[208:211], v[216:219], v[46:49]
	v_mfma_f32_16x16x32_bf16 v[10:13], v[208:211], v[220:223], v[10:13]
	v_mfma_f32_16x16x32_bf16 v[14:17], v[208:211], v[224:227], v[14:17]
	ds_read_b128 v[208:211], v244 offset:6976
	s_waitcnt vmcnt(13)
	ds_write_b128 v98, v[110:113] offset:27648
	s_waitcnt vmcnt(12)
	ds_write_b128 v98, v[114:117] offset:32256
	s_waitcnt lgkmcnt(7)
	v_mfma_f32_16x16x32_bf16 v[50:53], v[196:199], v[228:231], v[50:53]
	v_mfma_f32_16x16x32_bf16 v[54:57], v[196:199], v[232:235], v[54:57]
	v_mfma_f32_16x16x32_bf16 v[18:21], v[196:199], v[236:239], v[18:21]
	v_mfma_f32_16x16x32_bf16 v[22:25], v[196:199], v[240:243], v[22:25]
	s_waitcnt vmcnt(11)
	ds_write_b128 v98, v[118:121] offset:55296
	s_waitcnt vmcnt(10)
	ds_write_b128 v98, v[122:125] offset:59904
	s_waitcnt lgkmcnt(8)
	v_mfma_f32_16x16x32_bf16 v[58:61], v[200:203], v[228:231], v[58:61]
	v_mfma_f32_16x16x32_bf16 v[62:65], v[200:203], v[232:235], v[62:65]
	v_mfma_f32_16x16x32_bf16 v[26:29], v[200:203], v[236:239], v[26:29]
	v_mfma_f32_16x16x32_bf16 v[30:33], v[200:203], v[240:243], v[30:33]
	s_waitcnt vmcnt(9)
	ds_write_b128 v98, v[126:129] offset:64512
	s_waitcnt vmcnt(8)
	ds_write_b128 v99, v[132:135] offset:32256
	s_waitcnt lgkmcnt(0)
	s_barrier
	s_setprio 0
	ds_read_b128 v[212:215], v245 offset:55296
	ds_read_b128 v[196:199], v244 offset:18432
	ds_read_b128 v[216:219], v245 offset:57600
	ds_read_b128 v[220:223], v245 offset:59904
	ds_read_b128 v[224:227], v245 offset:62208
	ds_read_b128 v[200:203], v244 offset:20736
	v_mfma_f32_16x16x32_bf16 v[34:37], v[204:207], v[228:231], v[34:37]
	v_mfma_f32_16x16x32_bf16 v[38:41], v[204:207], v[232:235], v[38:41]
	v_mfma_f32_16x16x32_bf16 v[2:5], v[204:207], v[236:239], v[2:5]
	v_mfma_f32_16x16x32_bf16 v[6:9], v[204:207], v[240:243], v[6:9]
	ds_read_b128 v[204:207], v244 offset:23040
	v_mfma_f32_16x16x32_bf16 v[42:45], v[208:211], v[228:231], v[42:45]
	v_mfma_f32_16x16x32_bf16 v[46:49], v[208:211], v[232:235], v[46:49]
	v_mfma_f32_16x16x32_bf16 v[10:13], v[208:211], v[236:239], v[10:13]
	v_mfma_f32_16x16x32_bf16 v[14:17], v[208:211], v[240:243], v[14:17]
	ds_read_b128 v[208:211], v244 offset:25344
	global_load_dwordx4 v[102:105], v[74:75], off offset:1664
	global_load_dwordx4 v[106:109], v[76:77], off offset:1664
	global_load_dwordx4 v[110:113], v[78:79], off offset:1664
	global_load_dwordx4 v[114:117], v[80:81], off offset:1664
	global_load_dwordx4 v[118:121], v[82:83], off offset:1664
	global_load_dwordx4 v[122:125], v[84:85], off offset:1664
	global_load_dwordx4 v[126:129], v[86:87], off offset:1664
	global_load_dwordx4 v[132:135], v[88:89], off offset:1664
	s_waitcnt lgkmcnt(6)
	v_mfma_f32_16x16x32_bf16 v[50:53], v[196:199], v[212:215], v[50:53]
	ds_read_b128 v[228:231], v245 offset:55360
	s_waitcnt lgkmcnt(6)
	v_mfma_f32_16x16x32_bf16 v[54:57], v[196:199], v[216:219], v[54:57]
	ds_read_b128 v[232:235], v245 offset:57664
	s_waitcnt lgkmcnt(6)
	v_mfma_f32_16x16x32_bf16 v[18:21], v[196:199], v[220:223], v[18:21]
	ds_read_b128 v[236:239], v245 offset:59968
	s_waitcnt lgkmcnt(6)
	v_mfma_f32_16x16x32_bf16 v[22:25], v[196:199], v[224:227], v[22:25]
	ds_read_b128 v[240:243], v245 offset:62272
	ds_read_b128 v[196:199], v244 offset:18496
	s_waitcnt lgkmcnt(7)
	v_mfma_f32_16x16x32_bf16 v[58:61], v[200:203], v[212:215], v[58:61]
	v_mfma_f32_16x16x32_bf16 v[62:65], v[200:203], v[216:219], v[62:65]
	v_mfma_f32_16x16x32_bf16 v[26:29], v[200:203], v[220:223], v[26:29]
	v_mfma_f32_16x16x32_bf16 v[30:33], v[200:203], v[224:227], v[30:33]
	ds_read_b128 v[200:203], v244 offset:20800
	s_waitcnt lgkmcnt(7)
	v_mfma_f32_16x16x32_bf16 v[34:37], v[204:207], v[212:215], v[34:37]
	v_mfma_f32_16x16x32_bf16 v[38:41], v[204:207], v[216:219], v[38:41]
	v_mfma_f32_16x16x32_bf16 v[2:5], v[204:207], v[220:223], v[2:5]
	v_mfma_f32_16x16x32_bf16 v[6:9], v[204:207], v[224:227], v[6:9]
	ds_read_b128 v[204:207], v244 offset:23104
	s_setprio 1
	s_waitcnt vmcnt(15)
	ds_write_b128 v98, v[136:139]
	s_waitcnt vmcnt(14)
	ds_write_b128 v98, v[140:143] offset:4608
	s_waitcnt lgkmcnt(9)
	v_mfma_f32_16x16x32_bf16 v[42:45], v[208:211], v[212:215], v[42:45]
	v_mfma_f32_16x16x32_bf16 v[46:49], v[208:211], v[216:219], v[46:49]
	v_mfma_f32_16x16x32_bf16 v[10:13], v[208:211], v[220:223], v[10:13]
	v_mfma_f32_16x16x32_bf16 v[14:17], v[208:211], v[224:227], v[14:17]
	ds_read_b128 v[208:211], v244 offset:25408
	s_waitcnt vmcnt(13)
	ds_write_b128 v98, v[144:147] offset:9216
	s_waitcnt vmcnt(12)
	ds_write_b128 v98, v[148:151] offset:13824
	s_waitcnt lgkmcnt(7)
	v_mfma_f32_16x16x32_bf16 v[50:53], v[196:199], v[228:231], v[50:53]
	v_mfma_f32_16x16x32_bf16 v[54:57], v[196:199], v[232:235], v[54:57]
	v_mfma_f32_16x16x32_bf16 v[18:21], v[196:199], v[236:239], v[18:21]
	v_mfma_f32_16x16x32_bf16 v[22:25], v[196:199], v[240:243], v[22:25]
	s_waitcnt vmcnt(11)
	ds_write_b128 v98, v[152:155] offset:36864
	s_waitcnt vmcnt(10)
	ds_write_b128 v98, v[156:159] offset:41472
	s_waitcnt lgkmcnt(8)
	v_mfma_f32_16x16x32_bf16 v[58:61], v[200:203], v[228:231], v[58:61]
	v_mfma_f32_16x16x32_bf16 v[62:65], v[200:203], v[232:235], v[62:65]
	v_mfma_f32_16x16x32_bf16 v[26:29], v[200:203], v[236:239], v[26:29]
	v_mfma_f32_16x16x32_bf16 v[30:33], v[200:203], v[240:243], v[30:33]
	s_waitcnt vmcnt(9)
	ds_write_b128 v98, v[160:163] offset:46080
	s_waitcnt vmcnt(8)
	ds_write_b128 v98, v[164:167] offset:50688
	s_waitcnt lgkmcnt(0)
	s_barrier
	s_setprio 0
	ds_read_b128 v[212:215], v245 offset:36864
	ds_read_b128 v[196:199], v244
	ds_read_b128 v[216:219], v245 offset:39168
	ds_read_b128 v[220:223], v245 offset:41472
	ds_read_b128 v[224:227], v245 offset:43776
	ds_read_b128 v[200:203], v244 offset:2304
	v_mfma_f32_16x16x32_bf16 v[34:37], v[204:207], v[228:231], v[34:37]
	v_mfma_f32_16x16x32_bf16 v[38:41], v[204:207], v[232:235], v[38:41]
	v_mfma_f32_16x16x32_bf16 v[2:5], v[204:207], v[236:239], v[2:5]
	v_mfma_f32_16x16x32_bf16 v[6:9], v[204:207], v[240:243], v[6:9]
	ds_read_b128 v[204:207], v244 offset:4608
	v_mfma_f32_16x16x32_bf16 v[42:45], v[208:211], v[228:231], v[42:45]
	v_mfma_f32_16x16x32_bf16 v[46:49], v[208:211], v[232:235], v[46:49]
	v_mfma_f32_16x16x32_bf16 v[10:13], v[208:211], v[236:239], v[10:13]
	v_mfma_f32_16x16x32_bf16 v[14:17], v[208:211], v[240:243], v[14:17]
	ds_read_b128 v[208:211], v244 offset:6912
	global_load_dwordx4 v[136:139], v[74:75], off offset:1792
	global_load_dwordx4 v[140:143], v[76:77], off offset:1792
	global_load_dwordx4 v[144:147], v[78:79], off offset:1792
	global_load_dwordx4 v[148:151], v[80:81], off offset:1792
	global_load_dwordx4 v[152:155], v[82:83], off offset:1792
	global_load_dwordx4 v[156:159], v[84:85], off offset:1792
	global_load_dwordx4 v[160:163], v[86:87], off offset:1792
	global_load_dwordx4 v[164:167], v[88:89], off offset:1792
	s_waitcnt lgkmcnt(6)
	v_mfma_f32_16x16x32_bf16 v[50:53], v[196:199], v[212:215], v[50:53]
	ds_read_b128 v[228:231], v245 offset:36928
	s_waitcnt lgkmcnt(6)
	v_mfma_f32_16x16x32_bf16 v[54:57], v[196:199], v[216:219], v[54:57]
	ds_read_b128 v[232:235], v245 offset:39232
	s_waitcnt lgkmcnt(6)
	v_mfma_f32_16x16x32_bf16 v[18:21], v[196:199], v[220:223], v[18:21]
	ds_read_b128 v[236:239], v245 offset:41536
	s_waitcnt lgkmcnt(6)
	v_mfma_f32_16x16x32_bf16 v[22:25], v[196:199], v[224:227], v[22:25]
	ds_read_b128 v[240:243], v245 offset:43840
	ds_read_b128 v[196:199], v244 offset:64
	s_waitcnt lgkmcnt(7)
	v_mfma_f32_16x16x32_bf16 v[58:61], v[200:203], v[212:215], v[58:61]
	v_mfma_f32_16x16x32_bf16 v[62:65], v[200:203], v[216:219], v[62:65]
	v_mfma_f32_16x16x32_bf16 v[26:29], v[200:203], v[220:223], v[26:29]
	v_mfma_f32_16x16x32_bf16 v[30:33], v[200:203], v[224:227], v[30:33]
	ds_read_b128 v[200:203], v244 offset:2368
	s_waitcnt lgkmcnt(7)
	v_mfma_f32_16x16x32_bf16 v[34:37], v[204:207], v[212:215], v[34:37]
	v_mfma_f32_16x16x32_bf16 v[38:41], v[204:207], v[216:219], v[38:41]
	v_mfma_f32_16x16x32_bf16 v[2:5], v[204:207], v[220:223], v[2:5]
	v_mfma_f32_16x16x32_bf16 v[6:9], v[204:207], v[224:227], v[6:9]
	ds_read_b128 v[204:207], v244 offset:4672
	s_setprio 1
	s_waitcnt vmcnt(15)
	ds_write_b128 v98, v[102:105] offset:18432
	s_waitcnt vmcnt(14)
	ds_write_b128 v98, v[106:109] offset:23040
	s_waitcnt lgkmcnt(9)
	v_mfma_f32_16x16x32_bf16 v[42:45], v[208:211], v[212:215], v[42:45]
	v_mfma_f32_16x16x32_bf16 v[46:49], v[208:211], v[216:219], v[46:49]
	v_mfma_f32_16x16x32_bf16 v[10:13], v[208:211], v[220:223], v[10:13]
	v_mfma_f32_16x16x32_bf16 v[14:17], v[208:211], v[224:227], v[14:17]
	ds_read_b128 v[208:211], v244 offset:6976
	s_waitcnt vmcnt(13)
	ds_write_b128 v98, v[110:113] offset:27648
	s_waitcnt vmcnt(12)
	ds_write_b128 v98, v[114:117] offset:32256
	s_waitcnt lgkmcnt(7)
	v_mfma_f32_16x16x32_bf16 v[50:53], v[196:199], v[228:231], v[50:53]
	v_mfma_f32_16x16x32_bf16 v[54:57], v[196:199], v[232:235], v[54:57]
	v_mfma_f32_16x16x32_bf16 v[18:21], v[196:199], v[236:239], v[18:21]
	v_mfma_f32_16x16x32_bf16 v[22:25], v[196:199], v[240:243], v[22:25]
	s_waitcnt vmcnt(11)
	ds_write_b128 v98, v[118:121] offset:55296
	s_waitcnt vmcnt(10)
	ds_write_b128 v98, v[122:125] offset:59904
	s_waitcnt lgkmcnt(8)
	v_mfma_f32_16x16x32_bf16 v[58:61], v[200:203], v[228:231], v[58:61]
	v_mfma_f32_16x16x32_bf16 v[62:65], v[200:203], v[232:235], v[62:65]
	v_mfma_f32_16x16x32_bf16 v[26:29], v[200:203], v[236:239], v[26:29]
	v_mfma_f32_16x16x32_bf16 v[30:33], v[200:203], v[240:243], v[30:33]
	s_waitcnt vmcnt(9)
	ds_write_b128 v98, v[126:129] offset:64512
	s_waitcnt vmcnt(8)
	ds_write_b128 v99, v[132:135] offset:32256
	s_waitcnt lgkmcnt(0)
	s_barrier
	s_setprio 0
	ds_read_b128 v[212:215], v245 offset:55296
	ds_read_b128 v[196:199], v244 offset:18432
	ds_read_b128 v[216:219], v245 offset:57600
	ds_read_b128 v[220:223], v245 offset:59904
	ds_read_b128 v[224:227], v245 offset:62208
	ds_read_b128 v[200:203], v244 offset:20736
	v_mfma_f32_16x16x32_bf16 v[34:37], v[204:207], v[228:231], v[34:37]
	v_mfma_f32_16x16x32_bf16 v[38:41], v[204:207], v[232:235], v[38:41]
	v_mfma_f32_16x16x32_bf16 v[2:5], v[204:207], v[236:239], v[2:5]
	v_mfma_f32_16x16x32_bf16 v[6:9], v[204:207], v[240:243], v[6:9]
	ds_read_b128 v[204:207], v244 offset:23040
	v_mfma_f32_16x16x32_bf16 v[42:45], v[208:211], v[228:231], v[42:45]
	v_mfma_f32_16x16x32_bf16 v[46:49], v[208:211], v[232:235], v[46:49]
	v_mfma_f32_16x16x32_bf16 v[10:13], v[208:211], v[236:239], v[10:13]
	v_mfma_f32_16x16x32_bf16 v[14:17], v[208:211], v[240:243], v[14:17]
	ds_read_b128 v[208:211], v244 offset:25344
	global_load_dwordx4 v[102:105], v[74:75], off offset:1920
	s_nop 0
	global_load_dwordx4 v[74:77], v[76:77], off offset:1920
	s_nop 0
	global_load_dwordx4 v[106:109], v[78:79], off offset:1920
	s_nop 0
	global_load_dwordx4 v[78:81], v[80:81], off offset:1920
	s_nop 0
	global_load_dwordx4 v[110:113], v[82:83], off offset:1920
	s_nop 0
	global_load_dwordx4 v[82:85], v[84:85], off offset:1920
	s_nop 0
	global_load_dwordx4 v[114:117], v[86:87], off offset:1920
	s_nop 0
	global_load_dwordx4 v[86:89], v[88:89], off offset:1920
	s_waitcnt lgkmcnt(6)
	v_mfma_f32_16x16x32_bf16 v[50:53], v[196:199], v[212:215], v[50:53]
	ds_read_b128 v[228:231], v245 offset:55360
	s_waitcnt lgkmcnt(6)
	v_mfma_f32_16x16x32_bf16 v[54:57], v[196:199], v[216:219], v[54:57]
	ds_read_b128 v[232:235], v245 offset:57664
	s_waitcnt lgkmcnt(6)
	v_mfma_f32_16x16x32_bf16 v[18:21], v[196:199], v[220:223], v[18:21]
	ds_read_b128 v[236:239], v245 offset:59968
	s_waitcnt lgkmcnt(6)
	v_mfma_f32_16x16x32_bf16 v[22:25], v[196:199], v[224:227], v[22:25]
	ds_read_b128 v[240:243], v245 offset:62272
	ds_read_b128 v[196:199], v244 offset:18496
	s_waitcnt lgkmcnt(7)
	v_mfma_f32_16x16x32_bf16 v[58:61], v[200:203], v[212:215], v[58:61]
	v_mfma_f32_16x16x32_bf16 v[62:65], v[200:203], v[216:219], v[62:65]
	v_mfma_f32_16x16x32_bf16 v[26:29], v[200:203], v[220:223], v[26:29]
	v_mfma_f32_16x16x32_bf16 v[30:33], v[200:203], v[224:227], v[30:33]
	ds_read_b128 v[200:203], v244 offset:20800
	s_waitcnt lgkmcnt(7)
	v_mfma_f32_16x16x32_bf16 v[34:37], v[204:207], v[212:215], v[34:37]
	v_mfma_f32_16x16x32_bf16 v[38:41], v[204:207], v[216:219], v[38:41]
	v_mfma_f32_16x16x32_bf16 v[2:5], v[204:207], v[220:223], v[2:5]
	v_mfma_f32_16x16x32_bf16 v[6:9], v[204:207], v[224:227], v[6:9]
	ds_read_b128 v[204:207], v244 offset:23104
	s_setprio 1
	s_waitcnt vmcnt(15)
	ds_write_b128 v98, v[136:139]
	s_waitcnt vmcnt(14)
	ds_write_b128 v98, v[140:143] offset:4608
	s_waitcnt lgkmcnt(9)
	v_mfma_f32_16x16x32_bf16 v[42:45], v[208:211], v[212:215], v[42:45]
	v_mfma_f32_16x16x32_bf16 v[46:49], v[208:211], v[216:219], v[46:49]
	v_mfma_f32_16x16x32_bf16 v[10:13], v[208:211], v[220:223], v[10:13]
	v_mfma_f32_16x16x32_bf16 v[14:17], v[208:211], v[224:227], v[14:17]
	ds_read_b128 v[208:211], v244 offset:25408
	s_waitcnt vmcnt(13)
	ds_write_b128 v98, v[144:147] offset:9216
	s_waitcnt vmcnt(12)
	ds_write_b128 v98, v[148:151] offset:13824
	s_waitcnt lgkmcnt(7)
	v_mfma_f32_16x16x32_bf16 v[50:53], v[196:199], v[228:231], v[50:53]
	v_mfma_f32_16x16x32_bf16 v[54:57], v[196:199], v[232:235], v[54:57]
	v_mfma_f32_16x16x32_bf16 v[18:21], v[196:199], v[236:239], v[18:21]
	v_mfma_f32_16x16x32_bf16 v[22:25], v[196:199], v[240:243], v[22:25]
	s_waitcnt vmcnt(11)
	ds_write_b128 v98, v[152:155] offset:36864
	s_waitcnt vmcnt(10)
	ds_write_b128 v98, v[156:159] offset:41472
	s_waitcnt lgkmcnt(8)
	v_mfma_f32_16x16x32_bf16 v[58:61], v[200:203], v[228:231], v[58:61]
	v_mfma_f32_16x16x32_bf16 v[62:65], v[200:203], v[232:235], v[62:65]
	v_mfma_f32_16x16x32_bf16 v[26:29], v[200:203], v[236:239], v[26:29]
	v_mfma_f32_16x16x32_bf16 v[30:33], v[200:203], v[240:243], v[30:33]
	s_waitcnt vmcnt(9)
	ds_write_b128 v98, v[160:163] offset:46080
	s_waitcnt vmcnt(8)
	ds_write_b128 v98, v[164:167] offset:50688
	s_waitcnt lgkmcnt(0)
	s_barrier
	s_setprio 0
	ds_read_b128 v[212:215], v245 offset:36864
	ds_read_b128 v[196:199], v244
	ds_read_b128 v[216:219], v245 offset:39168
	ds_read_b128 v[220:223], v245 offset:41472
	ds_read_b128 v[224:227], v245 offset:43776
	ds_read_b128 v[200:203], v244 offset:2304
	v_mfma_f32_16x16x32_bf16 v[34:37], v[204:207], v[228:231], v[34:37]
	v_mfma_f32_16x16x32_bf16 v[38:41], v[204:207], v[232:235], v[38:41]
	v_mfma_f32_16x16x32_bf16 v[2:5], v[204:207], v[236:239], v[2:5]
	v_mfma_f32_16x16x32_bf16 v[6:9], v[204:207], v[240:243], v[6:9]
	ds_read_b128 v[204:207], v244 offset:4608
	v_mfma_f32_16x16x32_bf16 v[42:45], v[208:211], v[228:231], v[42:45]
	v_mfma_f32_16x16x32_bf16 v[46:49], v[208:211], v[232:235], v[46:49]
	v_mfma_f32_16x16x32_bf16 v[10:13], v[208:211], v[236:239], v[10:13]
	v_mfma_f32_16x16x32_bf16 v[14:17], v[208:211], v[240:243], v[14:17]
	ds_read_b128 v[208:211], v244 offset:6912
	s_waitcnt lgkmcnt(6)
	v_mfma_f32_16x16x32_bf16 v[50:53], v[196:199], v[212:215], v[50:53]
	ds_read_b128 v[228:231], v245 offset:36928
	s_waitcnt lgkmcnt(6)
	v_mfma_f32_16x16x32_bf16 v[54:57], v[196:199], v[216:219], v[54:57]
	ds_read_b128 v[232:235], v245 offset:39232
	s_waitcnt lgkmcnt(6)
	v_mfma_f32_16x16x32_bf16 v[18:21], v[196:199], v[220:223], v[18:21]
	ds_read_b128 v[236:239], v245 offset:41536
	s_waitcnt lgkmcnt(6)
	v_mfma_f32_16x16x32_bf16 v[22:25], v[196:199], v[224:227], v[22:25]
	ds_read_b128 v[240:243], v245 offset:43840
	ds_read_b128 v[196:199], v244 offset:64
	s_waitcnt lgkmcnt(7)
	v_mfma_f32_16x16x32_bf16 v[58:61], v[200:203], v[212:215], v[58:61]
	v_mfma_f32_16x16x32_bf16 v[62:65], v[200:203], v[216:219], v[62:65]
	v_mfma_f32_16x16x32_bf16 v[26:29], v[200:203], v[220:223], v[26:29]
	v_mfma_f32_16x16x32_bf16 v[30:33], v[200:203], v[224:227], v[30:33]
	ds_read_b128 v[200:203], v244 offset:2368
	s_waitcnt lgkmcnt(7)
	v_mfma_f32_16x16x32_bf16 v[34:37], v[204:207], v[212:215], v[34:37]
	v_mfma_f32_16x16x32_bf16 v[38:41], v[204:207], v[216:219], v[38:41]
	v_mfma_f32_16x16x32_bf16 v[2:5], v[204:207], v[220:223], v[2:5]
	v_mfma_f32_16x16x32_bf16 v[6:9], v[204:207], v[224:227], v[6:9]
	ds_read_b128 v[204:207], v244 offset:4672
	s_setprio 1
	s_waitcnt vmcnt(7)
	ds_write_b128 v98, v[102:105] offset:18432
	s_waitcnt vmcnt(6)
	ds_write_b128 v98, v[74:77] offset:23040
	s_waitcnt lgkmcnt(9)
	v_mfma_f32_16x16x32_bf16 v[42:45], v[208:211], v[212:215], v[42:45]
	v_mfma_f32_16x16x32_bf16 v[46:49], v[208:211], v[216:219], v[46:49]
	v_mfma_f32_16x16x32_bf16 v[10:13], v[208:211], v[220:223], v[10:13]
	v_mfma_f32_16x16x32_bf16 v[14:17], v[208:211], v[224:227], v[14:17]
	ds_read_b128 v[208:211], v244 offset:6976
	s_waitcnt vmcnt(5)
	ds_write_b128 v98, v[106:109] offset:27648
	s_waitcnt vmcnt(4)
	ds_write_b128 v98, v[78:81] offset:32256
	s_waitcnt lgkmcnt(7)
	v_mfma_f32_16x16x32_bf16 v[50:53], v[196:199], v[228:231], v[50:53]
	v_mfma_f32_16x16x32_bf16 v[54:57], v[196:199], v[232:235], v[54:57]
	v_mfma_f32_16x16x32_bf16 v[18:21], v[196:199], v[236:239], v[18:21]
	v_mfma_f32_16x16x32_bf16 v[22:25], v[196:199], v[240:243], v[22:25]
	s_waitcnt vmcnt(3)
	ds_write_b128 v98, v[110:113] offset:55296
	s_waitcnt vmcnt(2)
	ds_write_b128 v98, v[82:85] offset:59904
	s_waitcnt lgkmcnt(8)
	v_mfma_f32_16x16x32_bf16 v[58:61], v[200:203], v[228:231], v[58:61]
	v_mfma_f32_16x16x32_bf16 v[62:65], v[200:203], v[232:235], v[62:65]
	v_mfma_f32_16x16x32_bf16 v[26:29], v[200:203], v[236:239], v[26:29]
	v_mfma_f32_16x16x32_bf16 v[30:33], v[200:203], v[240:243], v[30:33]
	s_waitcnt vmcnt(1)
	ds_write_b128 v98, v[114:117] offset:64512
	s_waitcnt vmcnt(0)
	ds_write_b128 v99, v[86:89] offset:32256
	s_waitcnt lgkmcnt(0)
	s_barrier
	s_setprio 0
	ds_read_b128 v[212:215], v245 offset:55296
	ds_read_b128 v[196:199], v244 offset:18432
	ds_read_b128 v[216:219], v245 offset:57600
	ds_read_b128 v[220:223], v245 offset:59904
	ds_read_b128 v[224:227], v245 offset:62208
	ds_read_b128 v[200:203], v244 offset:20736
	v_mfma_f32_16x16x32_bf16 v[34:37], v[204:207], v[228:231], v[34:37]
	v_mfma_f32_16x16x32_bf16 v[38:41], v[204:207], v[232:235], v[38:41]
	v_mfma_f32_16x16x32_bf16 v[2:5], v[204:207], v[236:239], v[2:5]
	v_mfma_f32_16x16x32_bf16 v[6:9], v[204:207], v[240:243], v[6:9]
	ds_read_b128 v[204:207], v244 offset:23040
	v_mfma_f32_16x16x32_bf16 v[42:45], v[208:211], v[228:231], v[42:45]
	v_mfma_f32_16x16x32_bf16 v[46:49], v[208:211], v[232:235], v[46:49]
	v_mfma_f32_16x16x32_bf16 v[10:13], v[208:211], v[236:239], v[10:13]
	v_mfma_f32_16x16x32_bf16 v[14:17], v[208:211], v[240:243], v[14:17]
	ds_read_b128 v[208:211], v244 offset:25344
	s_waitcnt lgkmcnt(6)
	v_mfma_f32_16x16x32_bf16 v[50:53], v[196:199], v[212:215], v[50:53]
	ds_read_b128 v[228:231], v245 offset:55360
	s_waitcnt lgkmcnt(6)
	v_mfma_f32_16x16x32_bf16 v[54:57], v[196:199], v[216:219], v[54:57]
	ds_read_b128 v[232:235], v245 offset:57664
	s_waitcnt lgkmcnt(6)
	v_mfma_f32_16x16x32_bf16 v[18:21], v[196:199], v[220:223], v[18:21]
	ds_read_b128 v[236:239], v245 offset:59968
	s_waitcnt lgkmcnt(6)
	v_mfma_f32_16x16x32_bf16 v[22:25], v[196:199], v[224:227], v[22:25]
	ds_read_b128 v[240:243], v245 offset:62272
	ds_read_b128 v[196:199], v244 offset:18496
	s_waitcnt lgkmcnt(7)
	v_mfma_f32_16x16x32_bf16 v[58:61], v[200:203], v[212:215], v[58:61]
	v_mfma_f32_16x16x32_bf16 v[62:65], v[200:203], v[216:219], v[62:65]
	v_mfma_f32_16x16x32_bf16 v[26:29], v[200:203], v[220:223], v[26:29]
	v_mfma_f32_16x16x32_bf16 v[30:33], v[200:203], v[224:227], v[30:33]
	ds_read_b128 v[200:203], v244 offset:20800
	s_waitcnt lgkmcnt(7)
	v_mfma_f32_16x16x32_bf16 v[34:37], v[204:207], v[212:215], v[34:37]
	v_mfma_f32_16x16x32_bf16 v[38:41], v[204:207], v[216:219], v[38:41]
	v_mfma_f32_16x16x32_bf16 v[2:5], v[204:207], v[220:223], v[2:5]
	v_mfma_f32_16x16x32_bf16 v[6:9], v[204:207], v[224:227], v[6:9]
	ds_read_b128 v[204:207], v244 offset:23104
	s_waitcnt lgkmcnt(7)
	v_mfma_f32_16x16x32_bf16 v[42:45], v[208:211], v[212:215], v[42:45]
	v_mfma_f32_16x16x32_bf16 v[46:49], v[208:211], v[216:219], v[46:49]
	v_mfma_f32_16x16x32_bf16 v[10:13], v[208:211], v[220:223], v[10:13]
	v_mfma_f32_16x16x32_bf16 v[14:17], v[208:211], v[224:227], v[14:17]
	ds_read_b128 v[208:211], v244 offset:25408
	s_waitcnt lgkmcnt(3)
	v_mfma_f32_16x16x32_bf16 v[50:53], v[196:199], v[228:231], v[50:53]
	v_mfma_f32_16x16x32_bf16 v[54:57], v[196:199], v[232:235], v[54:57]
	v_mfma_f32_16x16x32_bf16 v[18:21], v[196:199], v[236:239], v[18:21]
	v_mfma_f32_16x16x32_bf16 v[22:25], v[196:199], v[240:243], v[22:25]
	s_waitcnt lgkmcnt(2)
	v_mfma_f32_16x16x32_bf16 v[58:61], v[200:203], v[228:231], v[58:61]
	v_mfma_f32_16x16x32_bf16 v[62:65], v[200:203], v[232:235], v[62:65]
	v_mfma_f32_16x16x32_bf16 v[26:29], v[200:203], v[236:239], v[26:29]
	v_mfma_f32_16x16x32_bf16 v[30:33], v[200:203], v[240:243], v[30:33]
	s_lshr_b32 s14, s2, 3
	s_bfe_u32 s13, s2, 0x10002
	s_cmp_lt_i32 s14, 1
	s_mov_b64 s[2:3], -1
	s_waitcnt lgkmcnt(0)
	s_barrier
	v_mfma_f32_16x16x32_bf16 v[34:37], v[204:207], v[228:231], v[34:37]
	v_mfma_f32_16x16x32_bf16 v[38:41], v[204:207], v[232:235], v[38:41]
	v_mfma_f32_16x16x32_bf16 v[2:5], v[204:207], v[236:239], v[2:5]
	v_mfma_f32_16x16x32_bf16 v[6:9], v[204:207], v[240:243], v[6:9]
	v_mfma_f32_16x16x32_bf16 v[42:45], v[208:211], v[228:231], v[42:45]
	v_mfma_f32_16x16x32_bf16 v[46:49], v[208:211], v[232:235], v[46:49]
	v_mfma_f32_16x16x32_bf16 v[10:13], v[208:211], v[236:239], v[10:13]
	v_mfma_f32_16x16x32_bf16 v[14:17], v[208:211], v[240:243], v[14:17]
	s_nop 7
	v_permlane16_swap_b32_e32 v50, v54
	v_permlane16_swap_b32_e32 v51, v55
	v_permlane16_swap_b32_e32 v52, v56
	v_permlane16_swap_b32_e32 v53, v57
	v_permlane16_swap_b32_e32 v58, v62
	v_permlane16_swap_b32_e32 v59, v63
	v_permlane16_swap_b32_e32 v60, v64
	v_permlane16_swap_b32_e32 v61, v65
	v_permlane16_swap_b32_e32 v18, v22
	v_permlane16_swap_b32_e32 v19, v23
	v_permlane16_swap_b32_e32 v20, v24
	v_permlane16_swap_b32_e32 v21, v25
	v_permlane16_swap_b32_e32 v26, v30
	v_permlane16_swap_b32_e32 v27, v31
	v_permlane16_swap_b32_e32 v28, v32
	v_permlane16_swap_b32_e32 v29, v33
	v_permlane16_swap_b32_e32 v34, v38
	v_permlane16_swap_b32_e32 v35, v39
	v_permlane16_swap_b32_e32 v36, v40
	v_permlane16_swap_b32_e32 v37, v41
	v_permlane16_swap_b32_e32 v42, v46
	v_permlane16_swap_b32_e32 v43, v47
	v_permlane16_swap_b32_e32 v44, v48
	v_permlane16_swap_b32_e32 v45, v49
	v_permlane16_swap_b32_e32 v2, v6
	v_permlane16_swap_b32_e32 v3, v7
	v_permlane16_swap_b32_e32 v4, v8
	v_permlane16_swap_b32_e32 v5, v9
	v_permlane16_swap_b32_e32 v10, v14
	v_permlane16_swap_b32_e32 v11, v15
	v_permlane16_swap_b32_e32 v12, v16
	v_permlane16_swap_b32_e32 v13, v17
	v_permlane32_swap_b32_e32 v50, v54
	v_permlane32_swap_b32_e32 v51, v55
	v_permlane32_swap_b32_e32 v52, v56
	v_permlane32_swap_b32_e32 v53, v57
	v_permlane32_swap_b32_e32 v58, v62
	v_permlane32_swap_b32_e32 v59, v63
	v_permlane32_swap_b32_e32 v60, v64
	v_permlane32_swap_b32_e32 v61, v65
	v_permlane32_swap_b32_e32 v18, v22
	v_permlane32_swap_b32_e32 v19, v23
	v_permlane32_swap_b32_e32 v20, v24
	v_permlane32_swap_b32_e32 v21, v25
	v_permlane32_swap_b32_e32 v26, v30
	v_permlane32_swap_b32_e32 v27, v31
	v_permlane32_swap_b32_e32 v28, v32
	v_permlane32_swap_b32_e32 v29, v33
	v_permlane32_swap_b32_e32 v34, v38
	v_permlane32_swap_b32_e32 v35, v39
	v_permlane32_swap_b32_e32 v36, v40
	v_permlane32_swap_b32_e32 v37, v41
	v_permlane32_swap_b32_e32 v42, v46
	v_permlane32_swap_b32_e32 v43, v47
	v_permlane32_swap_b32_e32 v44, v48
	v_permlane32_swap_b32_e32 v45, v49
	v_permlane32_swap_b32_e32 v2, v6
	v_permlane32_swap_b32_e32 v3, v7
	v_permlane32_swap_b32_e32 v4, v8
	v_permlane32_swap_b32_e32 v5, v9
	v_permlane32_swap_b32_e32 v10, v14
	v_permlane32_swap_b32_e32 v11, v15
	v_permlane32_swap_b32_e32 v12, v16
	v_permlane32_swap_b32_e32 v13, v17
	s_cbranch_scc1 .LBB0_1647
	s_and_b32 s2, 0xffff, s14
	s_cmp_lg_u32 s2, 1
	s_mov_b64 s[2:3], -1
	s_cbranch_scc0 .LBB0_1644
	s_cmp_eq_u32 s13, 0
	s_cselect_b32 s12, 3, 10
	s_mov_b64 s[2:3], 0

.LBB0_1720:
	s_lshr_b32 s8, s0, 2
	s_lshl_b32 s0, s0, 7
	s_and_b32 s7, s0, 0x180
	v_or_b32_e32 v2, s7, v93
	v_lshlrev_b32_e32 v74, 10, v2
	s_add_i32 s8, s8, s4
	v_lshl_add_u64 v[66:67], v[76:77], 0, v[74:75]
	v_add_lshl_u32 v74, s7, v94, 10
	s_lshl_b32 s0, s8, 7
	v_lshl_add_u64 v[68:69], v[76:77], 0, v[74:75]
	v_add_lshl_u32 v74, s7, v95, 10
	v_lshl_add_u64 v[70:71], v[76:77], 0, v[74:75]
	v_add_lshl_u32 v74, s7, v96, 10
	v_or_b32_e32 v2, s0, v93
	v_lshl_add_u64 v[72:73], v[76:77], 0, v[74:75]
	v_lshlrev_b32_e32 v74, 10, v2
	v_lshl_add_u64 v[84:85], v[78:79], 0, v[74:75]
	v_add_lshl_u32 v74, s0, v94, 10
	v_lshl_add_u64 v[86:87], v[78:79], 0, v[74:75]
	v_add_lshl_u32 v74, s0, v95, 10
	v_lshl_add_u64 v[88:89], v[78:79], 0, v[74:75]
	v_add_lshl_u32 v74, s0, v96, 10
	v_lshl_add_u64 v[90:91], v[78:79], 0, v[74:75]
	global_load_dwordx4 v[2:5], v[66:67], off
	global_load_dwordx4 v[6:9], v[68:69], off
	global_load_dwordx4 v[10:13], v[70:71], off
	global_load_dwordx4 v[14:17], v[72:73], off
	global_load_dwordx4 v[18:21], v[84:85], off
	global_load_dwordx4 v[22:25], v[86:87], off
	global_load_dwordx4 v[26:29], v[88:89], off
	global_load_dwordx4 v[30:33], v[90:91], off
	global_load_dwordx4 v[102:105], v[66:67], off offset:128
	global_load_dwordx4 v[106:109], v[68:69], off offset:128
	global_load_dwordx4 v[110:113], v[70:71], off offset:128
	global_load_dwordx4 v[114:117], v[72:73], off offset:128
	global_load_dwordx4 v[118:121], v[84:85], off offset:128
	global_load_dwordx4 v[122:125], v[86:87], off offset:128
	global_load_dwordx4 v[126:129], v[88:89], off offset:128
	global_load_dwordx4 v[132:135], v[90:91], off offset:128
	s_setprio 1
	s_waitcnt vmcnt(15)
	ds_write_b128 v100, v[2:5]
	s_waitcnt vmcnt(14)
	ds_write_b128 v100, v[6:9] offset:4608
	s_waitcnt vmcnt(13)
	ds_write_b128 v100, v[10:13] offset:9216
	s_waitcnt vmcnt(12)
	ds_write_b128 v100, v[14:17] offset:13824
	s_waitcnt vmcnt(11)
	ds_write_b128 v100, v[18:21] offset:36864
	s_waitcnt vmcnt(10)
	ds_write_b128 v100, v[22:25] offset:41472
	s_waitcnt vmcnt(9)
	ds_write_b128 v100, v[26:29] offset:46080
	s_waitcnt vmcnt(8)
	ds_write_b128 v100, v[30:33] offset:50688
	s_waitcnt lgkmcnt(0)
	s_barrier
	s_setprio 0
	global_load_dwordx4 v[136:139], v[66:67], off offset:256
	global_load_dwordx4 v[140:143], v[68:69], off offset:256
	global_load_dwordx4 v[144:147], v[70:71], off offset:256
	global_load_dwordx4 v[148:151], v[72:73], off offset:256
	global_load_dwordx4 v[152:155], v[84:85], off offset:256
	global_load_dwordx4 v[156:159], v[86:87], off offset:256
	global_load_dwordx4 v[160:163], v[88:89], off offset:256
	global_load_dwordx4 v[164:167], v[90:91], off offset:256
	v_and_b32_e32 v246, 15, v1
	v_add_u32_e32 v246, 4, v246
	v_bfe_u32 v246, v246, 3, 1
	v_bfe_u32 v249, v1, 4, 2
	v_xor_b32_e32 v246, v246, v249
	v_bfe_u32 v249, v1, 5, 1
	v_sub_u32_e32 v246, v246, v249
	v_lshlrev_b32_e32 v246, 4, v246
	v_bfe_u32 v249, v1, 4, 1
	v_mul_u32_u24_e32 v249, 0x900, v249
	v_sub_u32_e32 v246, v246, v249
	v_add_u32_e32 v244, v246, v98
	v_add_u32_e32 v245, v246, v99
	ds_read_b128 v[212:215], v245 offset:36864
	ds_read_b128 v[196:199], v244
	ds_read_b128 v[216:219], v245 offset:39168
	ds_read_b128 v[220:223], v245 offset:41472
	ds_read_b128 v[224:227], v245 offset:43776
	ds_read_b128 v[200:203], v244 offset:2304
	ds_read_b128 v[204:207], v244 offset:4608
	ds_read_b128 v[208:211], v244 offset:6912
	s_waitcnt lgkmcnt(6)
	v_mfma_f32_16x16x32_bf16 v[50:53], v[196:199], v[212:215], 0
	ds_read_b128 v[228:231], v245 offset:36928
	s_waitcnt lgkmcnt(6)
	v_mfma_f32_16x16x32_bf16 v[54:57], v[196:199], v[216:219], 0
	ds_read_b128 v[232:235], v245 offset:39232
	s_waitcnt lgkmcnt(6)
	v_mfma_f32_16x16x32_bf16 v[18:21], v[196:199], v[220:223], 0
	ds_read_b128 v[236:239], v245 offset:41536
	s_waitcnt lgkmcnt(6)
	v_mfma_f32_16x16x32_bf16 v[22:25], v[196:199], v[224:227], 0
	ds_read_b128 v[240:243], v245 offset:43840
	ds_read_b128 v[196:199], v244 offset:64
	s_waitcnt lgkmcnt(7)
	v_mfma_f32_16x16x32_bf16 v[58:61], v[200:203], v[212:215], 0
	v_mfma_f32_16x16x32_bf16 v[62:65], v[200:203], v[216:219], 0
	v_mfma_f32_16x16x32_bf16 v[26:29], v[200:203], v[220:223], 0
	v_mfma_f32_16x16x32_bf16 v[30:33], v[200:203], v[224:227], 0
	ds_read_b128 v[200:203], v244 offset:2368
	s_waitcnt lgkmcnt(7)
	v_mfma_f32_16x16x32_bf16 v[34:37], v[204:207], v[212:215], 0
	v_mfma_f32_16x16x32_bf16 v[38:41], v[204:207], v[216:219], 0
	v_mfma_f32_16x16x32_bf16 v[2:5], v[204:207], v[220:223], 0
	v_mfma_f32_16x16x32_bf16 v[6:9], v[204:207], v[224:227], 0
	ds_read_b128 v[204:207], v244 offset:4672
	s_setprio 1
	s_waitcnt vmcnt(15)
	ds_write_b128 v100, v[102:105] offset:18432
	s_waitcnt vmcnt(14)
	ds_write_b128 v100, v[106:109] offset:23040
	s_waitcnt lgkmcnt(9)
	v_mfma_f32_16x16x32_bf16 v[42:45], v[208:211], v[212:215], 0
	v_mfma_f32_16x16x32_bf16 v[46:49], v[208:211], v[216:219], 0
	v_mfma_f32_16x16x32_bf16 v[10:13], v[208:211], v[220:223], 0
	v_mfma_f32_16x16x32_bf16 v[14:17], v[208:211], v[224:227], 0
	ds_read_b128 v[208:211], v244 offset:6976
	s_waitcnt vmcnt(13)
	ds_write_b128 v100, v[110:113] offset:27648
	s_waitcnt vmcnt(12)
	ds_write_b128 v100, v[114:117] offset:32256
	s_waitcnt lgkmcnt(7)
	v_mfma_f32_16x16x32_bf16 v[50:53], v[196:199], v[228:231], v[50:53]
	v_mfma_f32_16x16x32_bf16 v[54:57], v[196:199], v[232:235], v[54:57]
	v_mfma_f32_16x16x32_bf16 v[18:21], v[196:199], v[236:239], v[18:21]
	v_mfma_f32_16x16x32_bf16 v[22:25], v[196:199], v[240:243], v[22:25]
	s_waitcnt vmcnt(11)
	ds_write_b128 v100, v[118:121] offset:55296
	s_waitcnt vmcnt(10)
	ds_write_b128 v100, v[122:125] offset:59904
	s_waitcnt lgkmcnt(8)
	v_mfma_f32_16x16x32_bf16 v[58:61], v[200:203], v[228:231], v[58:61]
	v_mfma_f32_16x16x32_bf16 v[62:65], v[200:203], v[232:235], v[62:65]
	v_mfma_f32_16x16x32_bf16 v[26:29], v[200:203], v[236:239], v[26:29]
	v_mfma_f32_16x16x32_bf16 v[30:33], v[200:203], v[240:243], v[30:33]
	s_waitcnt vmcnt(9)
	ds_write_b128 v100, v[126:129] offset:64512
	s_waitcnt vmcnt(8)
	ds_write_b128 v101, v[132:135] offset:32256
	s_waitcnt lgkmcnt(0)
	s_barrier
	s_setprio 0
	ds_read_b128 v[212:215], v245 offset:55296
	ds_read_b128 v[196:199], v244 offset:18432
	ds_read_b128 v[216:219], v245 offset:57600
	ds_read_b128 v[220:223], v245 offset:59904
	ds_read_b128 v[224:227], v245 offset:62208
	ds_read_b128 v[200:203], v244 offset:20736
	v_mfma_f32_16x16x32_bf16 v[34:37], v[204:207], v[228:231], v[34:37]
	v_mfma_f32_16x16x32_bf16 v[38:41], v[204:207], v[232:235], v[38:41]
	v_mfma_f32_16x16x32_bf16 v[2:5], v[204:207], v[236:239], v[2:5]
	v_mfma_f32_16x16x32_bf16 v[6:9], v[204:207], v[240:243], v[6:9]
	ds_read_b128 v[204:207], v244 offset:23040
	v_mfma_f32_16x16x32_bf16 v[42:45], v[208:211], v[228:231], v[42:45]
	v_mfma_f32_16x16x32_bf16 v[46:49], v[208:211], v[232:235], v[46:49]
	v_mfma_f32_16x16x32_bf16 v[10:13], v[208:211], v[236:239], v[10:13]
	v_mfma_f32_16x16x32_bf16 v[14:17], v[208:211], v[240:243], v[14:17]
	ds_read_b128 v[208:211], v244 offset:25344
	global_load_dwordx4 v[102:105], v[66:67], off offset:384
	global_load_dwordx4 v[106:109], v[68:69], off offset:384
	global_load_dwordx4 v[110:113], v[70:71], off offset:384
	global_load_dwordx4 v[114:117], v[72:73], off offset:384
	global_load_dwordx4 v[118:121], v[84:85], off offset:384
	global_load_dwordx4 v[122:125], v[86:87], off offset:384
	global_load_dwordx4 v[126:129], v[88:89], off offset:384
	global_load_dwordx4 v[132:135], v[90:91], off offset:384
	s_waitcnt lgkmcnt(6)
	v_mfma_f32_16x16x32_bf16 v[50:53], v[196:199], v[212:215], v[50:53]
	ds_read_b128 v[228:231], v245 offset:55360
	s_waitcnt lgkmcnt(6)
	v_mfma_f32_16x16x32_bf16 v[54:57], v[196:199], v[216:219], v[54:57]
	ds_read_b128 v[232:235], v245 offset:57664
	s_waitcnt lgkmcnt(6)
	v_mfma_f32_16x16x32_bf16 v[18:21], v[196:199], v[220:223], v[18:21]
	ds_read_b128 v[236:239], v245 offset:59968
	s_waitcnt lgkmcnt(6)
	v_mfma_f32_16x16x32_bf16 v[22:25], v[196:199], v[224:227], v[22:25]
	ds_read_b128 v[240:243], v245 offset:62272
	ds_read_b128 v[196:199], v244 offset:18496
	s_waitcnt lgkmcnt(7)
	v_mfma_f32_16x16x32_bf16 v[58:61], v[200:203], v[212:215], v[58:61]
	v_mfma_f32_16x16x32_bf16 v[62:65], v[200:203], v[216:219], v[62:65]
	v_mfma_f32_16x16x32_bf16 v[26:29], v[200:203], v[220:223], v[26:29]
	v_mfma_f32_16x16x32_bf16 v[30:33], v[200:203], v[224:227], v[30:33]
	ds_read_b128 v[200:203], v244 offset:20800
	s_waitcnt lgkmcnt(7)
	v_mfma_f32_16x16x32_bf16 v[34:37], v[204:207], v[212:215], v[34:37]
	v_mfma_f32_16x16x32_bf16 v[38:41], v[204:207], v[216:219], v[38:41]
	v_mfma_f32_16x16x32_bf16 v[2:5], v[204:207], v[220:223], v[2:5]
	v_mfma_f32_16x16x32_bf16 v[6:9], v[204:207], v[224:227], v[6:9]
	ds_read_b128 v[204:207], v244 offset:23104
	s_setprio 1
	s_waitcnt vmcnt(15)
	ds_write_b128 v100, v[136:139]
	s_waitcnt vmcnt(14)
	ds_write_b128 v100, v[140:143] offset:4608
	s_waitcnt lgkmcnt(9)
	v_mfma_f32_16x16x32_bf16 v[42:45], v[208:211], v[212:215], v[42:45]
	v_mfma_f32_16x16x32_bf16 v[46:49], v[208:211], v[216:219], v[46:49]
	v_mfma_f32_16x16x32_bf16 v[10:13], v[208:211], v[220:223], v[10:13]
	v_mfma_f32_16x16x32_bf16 v[14:17], v[208:211], v[224:227], v[14:17]
	ds_read_b128 v[208:211], v244 offset:25408
	s_waitcnt vmcnt(13)
	ds_write_b128 v100, v[144:147] offset:9216
	s_waitcnt vmcnt(12)
	ds_write_b128 v100, v[148:151] offset:13824
	s_waitcnt lgkmcnt(7)
	v_mfma_f32_16x16x32_bf16 v[50:53], v[196:199], v[228:231], v[50:53]
	v_mfma_f32_16x16x32_bf16 v[54:57], v[196:199], v[232:235], v[54:57]
	v_mfma_f32_16x16x32_bf16 v[18:21], v[196:199], v[236:239], v[18:21]
	v_mfma_f32_16x16x32_bf16 v[22:25], v[196:199], v[240:243], v[22:25]
	s_waitcnt vmcnt(11)
	ds_write_b128 v100, v[152:155] offset:36864
	s_waitcnt vmcnt(10)
	ds_write_b128 v100, v[156:159] offset:41472
	s_waitcnt lgkmcnt(8)
	v_mfma_f32_16x16x32_bf16 v[58:61], v[200:203], v[228:231], v[58:61]
	v_mfma_f32_16x16x32_bf16 v[62:65], v[200:203], v[232:235], v[62:65]
	v_mfma_f32_16x16x32_bf16 v[26:29], v[200:203], v[236:239], v[26:29]
	v_mfma_f32_16x16x32_bf16 v[30:33], v[200:203], v[240:243], v[30:33]
	s_waitcnt vmcnt(9)
	ds_write_b128 v100, v[160:163] offset:46080
	s_waitcnt vmcnt(8)
	ds_write_b128 v100, v[164:167] offset:50688
	s_waitcnt lgkmcnt(0)
	s_barrier
	s_setprio 0
	ds_read_b128 v[212:215], v245 offset:36864
	ds_read_b128 v[196:199], v244
	ds_read_b128 v[216:219], v245 offset:39168
	ds_read_b128 v[220:223], v245 offset:41472
	ds_read_b128 v[224:227], v245 offset:43776
	ds_read_b128 v[200:203], v244 offset:2304
	v_mfma_f32_16x16x32_bf16 v[34:37], v[204:207], v[228:231], v[34:37]
	v_mfma_f32_16x16x32_bf16 v[38:41], v[204:207], v[232:235], v[38:41]
	v_mfma_f32_16x16x32_bf16 v[2:5], v[204:207], v[236:239], v[2:5]
	v_mfma_f32_16x16x32_bf16 v[6:9], v[204:207], v[240:243], v[6:9]
	ds_read_b128 v[204:207], v244 offset:4608
	v_mfma_f32_16x16x32_bf16 v[42:45], v[208:211], v[228:231], v[42:45]
	v_mfma_f32_16x16x32_bf16 v[46:49], v[208:211], v[232:235], v[46:49]
	v_mfma_f32_16x16x32_bf16 v[10:13], v[208:211], v[236:239], v[10:13]
	v_mfma_f32_16x16x32_bf16 v[14:17], v[208:211], v[240:243], v[14:17]
	ds_read_b128 v[208:211], v244 offset:6912
	global_load_dwordx4 v[136:139], v[66:67], off offset:512
	global_load_dwordx4 v[140:143], v[68:69], off offset:512
	global_load_dwordx4 v[144:147], v[70:71], off offset:512
	global_load_dwordx4 v[148:151], v[72:73], off offset:512
	global_load_dwordx4 v[152:155], v[84:85], off offset:512
	global_load_dwordx4 v[156:159], v[86:87], off offset:512
	global_load_dwordx4 v[160:163], v[88:89], off offset:512
	global_load_dwordx4 v[164:167], v[90:91], off offset:512
	s_waitcnt lgkmcnt(6)
	v_mfma_f32_16x16x32_bf16 v[50:53], v[196:199], v[212:215], v[50:53]
	ds_read_b128 v[228:231], v245 offset:36928
	s_waitcnt lgkmcnt(6)
	v_mfma_f32_16x16x32_bf16 v[54:57], v[196:199], v[216:219], v[54:57]
	ds_read_b128 v[232:235], v245 offset:39232
	s_waitcnt lgkmcnt(6)
	v_mfma_f32_16x16x32_bf16 v[18:21], v[196:199], v[220:223], v[18:21]
	ds_read_b128 v[236:239], v245 offset:41536
	s_waitcnt lgkmcnt(6)
	v_mfma_f32_16x16x32_bf16 v[22:25], v[196:199], v[224:227], v[22:25]
	ds_read_b128 v[240:243], v245 offset:43840
	ds_read_b128 v[196:199], v244 offset:64
	s_waitcnt lgkmcnt(7)
	v_mfma_f32_16x16x32_bf16 v[58:61], v[200:203], v[212:215], v[58:61]
	v_mfma_f32_16x16x32_bf16 v[62:65], v[200:203], v[216:219], v[62:65]
	v_mfma_f32_16x16x32_bf16 v[26:29], v[200:203], v[220:223], v[26:29]
	v_mfma_f32_16x16x32_bf16 v[30:33], v[200:203], v[224:227], v[30:33]
	ds_read_b128 v[200:203], v244 offset:2368
	s_waitcnt lgkmcnt(7)
	v_mfma_f32_16x16x32_bf16 v[34:37], v[204:207], v[212:215], v[34:37]
	v_mfma_f32_16x16x32_bf16 v[38:41], v[204:207], v[216:219], v[38:41]
	v_mfma_f32_16x16x32_bf16 v[2:5], v[204:207], v[220:223], v[2:5]
	v_mfma_f32_16x16x32_bf16 v[6:9], v[204:207], v[224:227], v[6:9]
	ds_read_b128 v[204:207], v244 offset:4672
	s_setprio 1
	s_waitcnt vmcnt(15)
	ds_write_b128 v100, v[102:105] offset:18432
	s_waitcnt vmcnt(14)
	ds_write_b128 v100, v[106:109] offset:23040
	s_waitcnt lgkmcnt(9)
	v_mfma_f32_16x16x32_bf16 v[42:45], v[208:211], v[212:215], v[42:45]
	v_mfma_f32_16x16x32_bf16 v[46:49], v[208:211], v[216:219], v[46:49]
	v_mfma_f32_16x16x32_bf16 v[10:13], v[208:211], v[220:223], v[10:13]
	v_mfma_f32_16x16x32_bf16 v[14:17], v[208:211], v[224:227], v[14:17]
	ds_read_b128 v[208:211], v244 offset:6976
	s_waitcnt vmcnt(13)
	ds_write_b128 v100, v[110:113] offset:27648
	s_waitcnt vmcnt(12)
	ds_write_b128 v100, v[114:117] offset:32256
	s_waitcnt lgkmcnt(7)
	v_mfma_f32_16x16x32_bf16 v[50:53], v[196:199], v[228:231], v[50:53]
	v_mfma_f32_16x16x32_bf16 v[54:57], v[196:199], v[232:235], v[54:57]
	v_mfma_f32_16x16x32_bf16 v[18:21], v[196:199], v[236:239], v[18:21]
	v_mfma_f32_16x16x32_bf16 v[22:25], v[196:199], v[240:243], v[22:25]
	s_waitcnt vmcnt(11)
	ds_write_b128 v100, v[118:121] offset:55296
	s_waitcnt vmcnt(10)
	ds_write_b128 v100, v[122:125] offset:59904
	s_waitcnt lgkmcnt(8)
	v_mfma_f32_16x16x32_bf16 v[58:61], v[200:203], v[228:231], v[58:61]
	v_mfma_f32_16x16x32_bf16 v[62:65], v[200:203], v[232:235], v[62:65]
	v_mfma_f32_16x16x32_bf16 v[26:29], v[200:203], v[236:239], v[26:29]
	v_mfma_f32_16x16x32_bf16 v[30:33], v[200:203], v[240:243], v[30:33]
	s_waitcnt vmcnt(9)
	ds_write_b128 v100, v[126:129] offset:64512
	s_waitcnt vmcnt(8)
	ds_write_b128 v101, v[132:135] offset:32256
	s_waitcnt lgkmcnt(0)
	s_barrier
	s_setprio 0
	ds_read_b128 v[212:215], v245 offset:55296
	ds_read_b128 v[196:199], v244 offset:18432
	ds_read_b128 v[216:219], v245 offset:57600
	ds_read_b128 v[220:223], v245 offset:59904
	ds_read_b128 v[224:227], v245 offset:62208
	ds_read_b128 v[200:203], v244 offset:20736
	v_mfma_f32_16x16x32_bf16 v[34:37], v[204:207], v[228:231], v[34:37]
	v_mfma_f32_16x16x32_bf16 v[38:41], v[204:207], v[232:235], v[38:41]
	v_mfma_f32_16x16x32_bf16 v[2:5], v[204:207], v[236:239], v[2:5]
	v_mfma_f32_16x16x32_bf16 v[6:9], v[204:207], v[240:243], v[6:9]
	ds_read_b128 v[204:207], v244 offset:23040
	v_mfma_f32_16x16x32_bf16 v[42:45], v[208:211], v[228:231], v[42:45]
	v_mfma_f32_16x16x32_bf16 v[46:49], v[208:211], v[232:235], v[46:49]
	v_mfma_f32_16x16x32_bf16 v[10:13], v[208:211], v[236:239], v[10:13]
	v_mfma_f32_16x16x32_bf16 v[14:17], v[208:211], v[240:243], v[14:17]
	ds_read_b128 v[208:211], v244 offset:25344
	global_load_dwordx4 v[102:105], v[66:67], off offset:640
	global_load_dwordx4 v[106:109], v[68:69], off offset:640
	global_load_dwordx4 v[110:113], v[70:71], off offset:640
	global_load_dwordx4 v[114:117], v[72:73], off offset:640
	global_load_dwordx4 v[118:121], v[84:85], off offset:640
	global_load_dwordx4 v[122:125], v[86:87], off offset:640
	global_load_dwordx4 v[126:129], v[88:89], off offset:640
	global_load_dwordx4 v[132:135], v[90:91], off offset:640
	s_waitcnt lgkmcnt(6)
	v_mfma_f32_16x16x32_bf16 v[50:53], v[196:199], v[212:215], v[50:53]
	ds_read_b128 v[228:231], v245 offset:55360
	s_waitcnt lgkmcnt(6)
	v_mfma_f32_16x16x32_bf16 v[54:57], v[196:199], v[216:219], v[54:57]
	ds_read_b128 v[232:235], v245 offset:57664
	s_waitcnt lgkmcnt(6)
	v_mfma_f32_16x16x32_bf16 v[18:21], v[196:199], v[220:223], v[18:21]
	ds_read_b128 v[236:239], v245 offset:59968
	s_waitcnt lgkmcnt(6)
	v_mfma_f32_16x16x32_bf16 v[22:25], v[196:199], v[224:227], v[22:25]
	ds_read_b128 v[240:243], v245 offset:62272
	ds_read_b128 v[196:199], v244 offset:18496
	s_waitcnt lgkmcnt(7)
	v_mfma_f32_16x16x32_bf16 v[58:61], v[200:203], v[212:215], v[58:61]
	v_mfma_f32_16x16x32_bf16 v[62:65], v[200:203], v[216:219], v[62:65]
	v_mfma_f32_16x16x32_bf16 v[26:29], v[200:203], v[220:223], v[26:29]
	v_mfma_f32_16x16x32_bf16 v[30:33], v[200:203], v[224:227], v[30:33]
	ds_read_b128 v[200:203], v244 offset:20800
	s_waitcnt lgkmcnt(7)
	v_mfma_f32_16x16x32_bf16 v[34:37], v[204:207], v[212:215], v[34:37]
	v_mfma_f32_16x16x32_bf16 v[38:41], v[204:207], v[216:219], v[38:41]
	v_mfma_f32_16x16x32_bf16 v[2:5], v[204:207], v[220:223], v[2:5]
	v_mfma_f32_16x16x32_bf16 v[6:9], v[204:207], v[224:227], v[6:9]
	ds_read_b128 v[204:207], v244 offset:23104
	s_setprio 1
	s_waitcnt vmcnt(15)
	ds_write_b128 v100, v[136:139]
	s_waitcnt vmcnt(14)
	ds_write_b128 v100, v[140:143] offset:4608
	s_waitcnt lgkmcnt(9)
	v_mfma_f32_16x16x32_bf16 v[42:45], v[208:211], v[212:215], v[42:45]
	v_mfma_f32_16x16x32_bf16 v[46:49], v[208:211], v[216:219], v[46:49]
	v_mfma_f32_16x16x32_bf16 v[10:13], v[208:211], v[220:223], v[10:13]
	v_mfma_f32_16x16x32_bf16 v[14:17], v[208:211], v[224:227], v[14:17]
	ds_read_b128 v[208:211], v244 offset:25408
	s_waitcnt vmcnt(13)
	ds_write_b128 v100, v[144:147] offset:9216
	s_waitcnt vmcnt(12)
	ds_write_b128 v100, v[148:151] offset:13824
	s_waitcnt lgkmcnt(7)
	v_mfma_f32_16x16x32_bf16 v[50:53], v[196:199], v[228:231], v[50:53]
	v_mfma_f32_16x16x32_bf16 v[54:57], v[196:199], v[232:235], v[54:57]
	v_mfma_f32_16x16x32_bf16 v[18:21], v[196:199], v[236:239], v[18:21]
	v_mfma_f32_16x16x32_bf16 v[22:25], v[196:199], v[240:243], v[22:25]
	s_waitcnt vmcnt(11)
	ds_write_b128 v100, v[152:155] offset:36864
	s_waitcnt vmcnt(10)
	ds_write_b128 v100, v[156:159] offset:41472
	s_waitcnt lgkmcnt(8)
	v_mfma_f32_16x16x32_bf16 v[58:61], v[200:203], v[228:231], v[58:61]
	v_mfma_f32_16x16x32_bf16 v[62:65], v[200:203], v[232:235], v[62:65]
	v_mfma_f32_16x16x32_bf16 v[26:29], v[200:203], v[236:239], v[26:29]
	v_mfma_f32_16x16x32_bf16 v[30:33], v[200:203], v[240:243], v[30:33]
	s_waitcnt vmcnt(9)
	ds_write_b128 v100, v[160:163] offset:46080
	s_waitcnt vmcnt(8)
	ds_write_b128 v100, v[164:167] offset:50688
	s_waitcnt lgkmcnt(0)
	s_barrier
	s_setprio 0
	ds_read_b128 v[212:215], v245 offset:36864
	ds_read_b128 v[196:199], v244
	ds_read_b128 v[216:219], v245 offset:39168
	ds_read_b128 v[220:223], v245 offset:41472
	ds_read_b128 v[224:227], v245 offset:43776
	ds_read_b128 v[200:203], v244 offset:2304
	v_mfma_f32_16x16x32_bf16 v[34:37], v[204:207], v[228:231], v[34:37]
	v_mfma_f32_16x16x32_bf16 v[38:41], v[204:207], v[232:235], v[38:41]
	v_mfma_f32_16x16x32_bf16 v[2:5], v[204:207], v[236:239], v[2:5]
	v_mfma_f32_16x16x32_bf16 v[6:9], v[204:207], v[240:243], v[6:9]
	ds_read_b128 v[204:207], v244 offset:4608
	v_mfma_f32_16x16x32_bf16 v[42:45], v[208:211], v[228:231], v[42:45]
	v_mfma_f32_16x16x32_bf16 v[46:49], v[208:211], v[232:235], v[46:49]
	v_mfma_f32_16x16x32_bf16 v[10:13], v[208:211], v[236:239], v[10:13]
	v_mfma_f32_16x16x32_bf16 v[14:17], v[208:211], v[240:243], v[14:17]
	ds_read_b128 v[208:211], v244 offset:6912
	global_load_dwordx4 v[136:139], v[66:67], off offset:768
	global_load_dwordx4 v[140:143], v[68:69], off offset:768
	global_load_dwordx4 v[144:147], v[70:71], off offset:768
	global_load_dwordx4 v[148:151], v[72:73], off offset:768
	global_load_dwordx4 v[152:155], v[84:85], off offset:768
	global_load_dwordx4 v[156:159], v[86:87], off offset:768
	global_load_dwordx4 v[160:163], v[88:89], off offset:768
	global_load_dwordx4 v[164:167], v[90:91], off offset:768
	s_waitcnt lgkmcnt(6)
	v_mfma_f32_16x16x32_bf16 v[50:53], v[196:199], v[212:215], v[50:53]
	ds_read_b128 v[228:231], v245 offset:36928
	s_waitcnt lgkmcnt(6)
	v_mfma_f32_16x16x32_bf16 v[54:57], v[196:199], v[216:219], v[54:57]
	ds_read_b128 v[232:235], v245 offset:39232
	s_waitcnt lgkmcnt(6)
	v_mfma_f32_16x16x32_bf16 v[18:21], v[196:199], v[220:223], v[18:21]
	ds_read_b128 v[236:239], v245 offset:41536
	s_waitcnt lgkmcnt(6)
	v_mfma_f32_16x16x32_bf16 v[22:25], v[196:199], v[224:227], v[22:25]
	ds_read_b128 v[240:243], v245 offset:43840
	ds_read_b128 v[196:199], v244 offset:64
	s_waitcnt lgkmcnt(7)
	v_mfma_f32_16x16x32_bf16 v[58:61], v[200:203], v[212:215], v[58:61]
	v_mfma_f32_16x16x32_bf16 v[62:65], v[200:203], v[216:219], v[62:65]
	v_mfma_f32_16x16x32_bf16 v[26:29], v[200:203], v[220:223], v[26:29]
	v_mfma_f32_16x16x32_bf16 v[30:33], v[200:203], v[224:227], v[30:33]
	ds_read_b128 v[200:203], v244 offset:2368
	s_waitcnt lgkmcnt(7)
	v_mfma_f32_16x16x32_bf16 v[34:37], v[204:207], v[212:215], v[34:37]
	v_mfma_f32_16x16x32_bf16 v[38:41], v[204:207], v[216:219], v[38:41]
	v_mfma_f32_16x16x32_bf16 v[2:5], v[204:207], v[220:223], v[2:5]
	v_mfma_f32_16x16x32_bf16 v[6:9], v[204:207], v[224:227], v[6:9]
	ds_read_b128 v[204:207], v244 offset:4672
	s_setprio 1
	s_waitcnt vmcnt(15)
	ds_write_b128 v100, v[102:105] offset:18432
	s_waitcnt vmcnt(14)
	ds_write_b128 v100, v[106:109] offset:23040
	s_waitcnt lgkmcnt(9)
	v_mfma_f32_16x16x32_bf16 v[42:45], v[208:211], v[212:215], v[42:45]
	v_mfma_f32_16x16x32_bf16 v[46:49], v[208:211], v[216:219], v[46:49]
	v_mfma_f32_16x16x32_bf16 v[10:13], v[208:211], v[220:223], v[10:13]
	v_mfma_f32_16x16x32_bf16 v[14:17], v[208:211], v[224:227], v[14:17]
	ds_read_b128 v[208:211], v244 offset:6976
	s_waitcnt vmcnt(13)
	ds_write_b128 v100, v[110:113] offset:27648
	s_waitcnt vmcnt(12)
	ds_write_b128 v100, v[114:117] offset:32256
	s_waitcnt lgkmcnt(7)
	v_mfma_f32_16x16x32_bf16 v[50:53], v[196:199], v[228:231], v[50:53]
	v_mfma_f32_16x16x32_bf16 v[54:57], v[196:199], v[232:235], v[54:57]
	v_mfma_f32_16x16x32_bf16 v[18:21], v[196:199], v[236:239], v[18:21]
	v_mfma_f32_16x16x32_bf16 v[22:25], v[196:199], v[240:243], v[22:25]
	s_waitcnt vmcnt(11)
	ds_write_b128 v100, v[118:121] offset:55296
	s_waitcnt vmcnt(10)
	ds_write_b128 v100, v[122:125] offset:59904
	s_waitcnt lgkmcnt(8)
	v_mfma_f32_16x16x32_bf16 v[58:61], v[200:203], v[228:231], v[58:61]
	v_mfma_f32_16x16x32_bf16 v[62:65], v[200:203], v[232:235], v[62:65]
	v_mfma_f32_16x16x32_bf16 v[26:29], v[200:203], v[236:239], v[26:29]
	v_mfma_f32_16x16x32_bf16 v[30:33], v[200:203], v[240:243], v[30:33]
	s_waitcnt vmcnt(9)
	ds_write_b128 v100, v[126:129] offset:64512
	s_waitcnt vmcnt(8)
	ds_write_b128 v101, v[132:135] offset:32256
	s_waitcnt lgkmcnt(0)
	s_barrier
	s_setprio 0
	ds_read_b128 v[212:215], v245 offset:55296
	ds_read_b128 v[196:199], v244 offset:18432
	ds_read_b128 v[216:219], v245 offset:57600
	ds_read_b128 v[220:223], v245 offset:59904
	ds_read_b128 v[224:227], v245 offset:62208
	ds_read_b128 v[200:203], v244 offset:20736
	v_mfma_f32_16x16x32_bf16 v[34:37], v[204:207], v[228:231], v[34:37]
	v_mfma_f32_16x16x32_bf16 v[38:41], v[204:207], v[232:235], v[38:41]
	v_mfma_f32_16x16x32_bf16 v[2:5], v[204:207], v[236:239], v[2:5]
	v_mfma_f32_16x16x32_bf16 v[6:9], v[204:207], v[240:243], v[6:9]
	ds_read_b128 v[204:207], v244 offset:23040
	v_mfma_f32_16x16x32_bf16 v[42:45], v[208:211], v[228:231], v[42:45]
	v_mfma_f32_16x16x32_bf16 v[46:49], v[208:211], v[232:235], v[46:49]
	v_mfma_f32_16x16x32_bf16 v[10:13], v[208:211], v[236:239], v[10:13]
	v_mfma_f32_16x16x32_bf16 v[14:17], v[208:211], v[240:243], v[14:17]
	ds_read_b128 v[208:211], v244 offset:25344
	global_load_dwordx4 v[102:105], v[66:67], off offset:896
	s_nop 0
	global_load_dwordx4 v[66:69], v[68:69], off offset:896
	s_nop 0
	global_load_dwordx4 v[106:109], v[70:71], off offset:896
	s_nop 0
	global_load_dwordx4 v[70:73], v[72:73], off offset:896
	s_nop 0
	global_load_dwordx4 v[110:113], v[84:85], off offset:896
	s_nop 0
	global_load_dwordx4 v[84:87], v[86:87], off offset:896
	s_nop 0
	global_load_dwordx4 v[114:117], v[88:89], off offset:896
	s_nop 0
	global_load_dwordx4 v[88:91], v[90:91], off offset:896
	s_waitcnt lgkmcnt(6)
	v_mfma_f32_16x16x32_bf16 v[50:53], v[196:199], v[212:215], v[50:53]
	ds_read_b128 v[228:231], v245 offset:55360
	s_waitcnt lgkmcnt(6)
	v_mfma_f32_16x16x32_bf16 v[54:57], v[196:199], v[216:219], v[54:57]
	ds_read_b128 v[232:235], v245 offset:57664
	s_waitcnt lgkmcnt(6)
	v_mfma_f32_16x16x32_bf16 v[18:21], v[196:199], v[220:223], v[18:21]
	ds_read_b128 v[236:239], v245 offset:59968
	s_waitcnt lgkmcnt(6)
	v_mfma_f32_16x16x32_bf16 v[22:25], v[196:199], v[224:227], v[22:25]
	ds_read_b128 v[240:243], v245 offset:62272
	ds_read_b128 v[196:199], v244 offset:18496
	s_waitcnt lgkmcnt(7)
	v_mfma_f32_16x16x32_bf16 v[58:61], v[200:203], v[212:215], v[58:61]
	v_mfma_f32_16x16x32_bf16 v[62:65], v[200:203], v[216:219], v[62:65]
	v_mfma_f32_16x16x32_bf16 v[26:29], v[200:203], v[220:223], v[26:29]
	v_mfma_f32_16x16x32_bf16 v[30:33], v[200:203], v[224:227], v[30:33]
	ds_read_b128 v[200:203], v244 offset:20800
	s_waitcnt lgkmcnt(7)
	v_mfma_f32_16x16x32_bf16 v[34:37], v[204:207], v[212:215], v[34:37]
	v_mfma_f32_16x16x32_bf16 v[38:41], v[204:207], v[216:219], v[38:41]
	v_mfma_f32_16x16x32_bf16 v[2:5], v[204:207], v[220:223], v[2:5]
	v_mfma_f32_16x16x32_bf16 v[6:9], v[204:207], v[224:227], v[6:9]
	ds_read_b128 v[204:207], v244 offset:23104
	s_setprio 1
	s_waitcnt vmcnt(15)
	ds_write_b128 v100, v[136:139]
	s_waitcnt vmcnt(14)
	ds_write_b128 v100, v[140:143] offset:4608
	s_waitcnt lgkmcnt(9)
	v_mfma_f32_16x16x32_bf16 v[42:45], v[208:211], v[212:215], v[42:45]
	v_mfma_f32_16x16x32_bf16 v[46:49], v[208:211], v[216:219], v[46:49]
	v_mfma_f32_16x16x32_bf16 v[10:13], v[208:211], v[220:223], v[10:13]
	v_mfma_f32_16x16x32_bf16 v[14:17], v[208:211], v[224:227], v[14:17]
	ds_read_b128 v[208:211], v244 offset:25408
	s_waitcnt vmcnt(13)
	ds_write_b128 v100, v[144:147] offset:9216
	s_waitcnt vmcnt(12)
	ds_write_b128 v100, v[148:151] offset:13824
	s_waitcnt lgkmcnt(7)
	v_mfma_f32_16x16x32_bf16 v[50:53], v[196:199], v[228:231], v[50:53]
	v_mfma_f32_16x16x32_bf16 v[54:57], v[196:199], v[232:235], v[54:57]
	v_mfma_f32_16x16x32_bf16 v[18:21], v[196:199], v[236:239], v[18:21]
	v_mfma_f32_16x16x32_bf16 v[22:25], v[196:199], v[240:243], v[22:25]
	s_waitcnt vmcnt(11)
	ds_write_b128 v100, v[152:155] offset:36864
	s_waitcnt vmcnt(10)
	ds_write_b128 v100, v[156:159] offset:41472
	s_waitcnt lgkmcnt(8)
	v_mfma_f32_16x16x32_bf16 v[58:61], v[200:203], v[228:231], v[58:61]
	v_mfma_f32_16x16x32_bf16 v[62:65], v[200:203], v[232:235], v[62:65]
	v_mfma_f32_16x16x32_bf16 v[26:29], v[200:203], v[236:239], v[26:29]
	v_mfma_f32_16x16x32_bf16 v[30:33], v[200:203], v[240:243], v[30:33]
	s_waitcnt vmcnt(9)
	ds_write_b128 v100, v[160:163] offset:46080
	s_waitcnt vmcnt(8)
	ds_write_b128 v100, v[164:167] offset:50688
	s_waitcnt lgkmcnt(0)
	s_barrier
	s_setprio 0
	ds_read_b128 v[212:215], v245 offset:36864
	ds_read_b128 v[196:199], v244
	ds_read_b128 v[216:219], v245 offset:39168
	ds_read_b128 v[220:223], v245 offset:41472
	ds_read_b128 v[224:227], v245 offset:43776
	ds_read_b128 v[200:203], v244 offset:2304
	v_mfma_f32_16x16x32_bf16 v[34:37], v[204:207], v[228:231], v[34:37]
	v_mfma_f32_16x16x32_bf16 v[38:41], v[204:207], v[232:235], v[38:41]
	v_mfma_f32_16x16x32_bf16 v[2:5], v[204:207], v[236:239], v[2:5]
	v_mfma_f32_16x16x32_bf16 v[6:9], v[204:207], v[240:243], v[6:9]
	ds_read_b128 v[204:207], v244 offset:4608
	v_mfma_f32_16x16x32_bf16 v[42:45], v[208:211], v[228:231], v[42:45]
	v_mfma_f32_16x16x32_bf16 v[46:49], v[208:211], v[232:235], v[46:49]
	v_mfma_f32_16x16x32_bf16 v[10:13], v[208:211], v[236:239], v[10:13]
	v_mfma_f32_16x16x32_bf16 v[14:17], v[208:211], v[240:243], v[14:17]
	ds_read_b128 v[208:211], v244 offset:6912
	s_waitcnt lgkmcnt(6)
	v_mfma_f32_16x16x32_bf16 v[50:53], v[196:199], v[212:215], v[50:53]
	ds_read_b128 v[228:231], v245 offset:36928
	s_waitcnt lgkmcnt(6)
	v_mfma_f32_16x16x32_bf16 v[54:57], v[196:199], v[216:219], v[54:57]
	ds_read_b128 v[232:235], v245 offset:39232
	s_waitcnt lgkmcnt(6)
	v_mfma_f32_16x16x32_bf16 v[18:21], v[196:199], v[220:223], v[18:21]
	ds_read_b128 v[236:239], v245 offset:41536
	s_waitcnt lgkmcnt(6)
	v_mfma_f32_16x16x32_bf16 v[22:25], v[196:199], v[224:227], v[22:25]
	ds_read_b128 v[240:243], v245 offset:43840
	ds_read_b128 v[196:199], v244 offset:64
	s_waitcnt lgkmcnt(7)
	v_mfma_f32_16x16x32_bf16 v[58:61], v[200:203], v[212:215], v[58:61]
	v_mfma_f32_16x16x32_bf16 v[62:65], v[200:203], v[216:219], v[62:65]
	v_mfma_f32_16x16x32_bf16 v[26:29], v[200:203], v[220:223], v[26:29]
	v_mfma_f32_16x16x32_bf16 v[30:33], v[200:203], v[224:227], v[30:33]
	ds_read_b128 v[200:203], v244 offset:2368
	s_waitcnt lgkmcnt(7)
	v_mfma_f32_16x16x32_bf16 v[34:37], v[204:207], v[212:215], v[34:37]
	v_mfma_f32_16x16x32_bf16 v[38:41], v[204:207], v[216:219], v[38:41]
	v_mfma_f32_16x16x32_bf16 v[2:5], v[204:207], v[220:223], v[2:5]
	v_mfma_f32_16x16x32_bf16 v[6:9], v[204:207], v[224:227], v[6:9]
	ds_read_b128 v[204:207], v244 offset:4672
	s_setprio 1
	s_waitcnt vmcnt(7)
	ds_write_b128 v100, v[102:105] offset:18432
	s_waitcnt vmcnt(6)
	ds_write_b128 v100, v[66:69] offset:23040
	s_waitcnt lgkmcnt(9)
	v_mfma_f32_16x16x32_bf16 v[42:45], v[208:211], v[212:215], v[42:45]
	v_mfma_f32_16x16x32_bf16 v[46:49], v[208:211], v[216:219], v[46:49]
	v_mfma_f32_16x16x32_bf16 v[10:13], v[208:211], v[220:223], v[10:13]
	v_mfma_f32_16x16x32_bf16 v[14:17], v[208:211], v[224:227], v[14:17]
	ds_read_b128 v[208:211], v244 offset:6976
	s_waitcnt vmcnt(5)
	ds_write_b128 v100, v[106:109] offset:27648
	s_waitcnt vmcnt(4)
	ds_write_b128 v100, v[70:73] offset:32256
	s_waitcnt lgkmcnt(7)
	v_mfma_f32_16x16x32_bf16 v[50:53], v[196:199], v[228:231], v[50:53]
	v_mfma_f32_16x16x32_bf16 v[54:57], v[196:199], v[232:235], v[54:57]
	v_mfma_f32_16x16x32_bf16 v[18:21], v[196:199], v[236:239], v[18:21]
	v_mfma_f32_16x16x32_bf16 v[22:25], v[196:199], v[240:243], v[22:25]
	s_waitcnt vmcnt(3)
	ds_write_b128 v100, v[110:113] offset:55296
	s_waitcnt vmcnt(2)
	ds_write_b128 v100, v[84:87] offset:59904
	s_waitcnt lgkmcnt(8)
	v_mfma_f32_16x16x32_bf16 v[58:61], v[200:203], v[228:231], v[58:61]
	v_mfma_f32_16x16x32_bf16 v[62:65], v[200:203], v[232:235], v[62:65]
	v_mfma_f32_16x16x32_bf16 v[26:29], v[200:203], v[236:239], v[26:29]
	v_mfma_f32_16x16x32_bf16 v[30:33], v[200:203], v[240:243], v[30:33]
	s_waitcnt vmcnt(1)
	ds_write_b128 v100, v[114:117] offset:64512
	s_waitcnt vmcnt(0)
	ds_write_b128 v101, v[88:91] offset:32256
	s_waitcnt lgkmcnt(0)
	s_barrier
	s_setprio 0
	ds_read_b128 v[212:215], v245 offset:55296
	ds_read_b128 v[196:199], v244 offset:18432
	ds_read_b128 v[216:219], v245 offset:57600
	ds_read_b128 v[220:223], v245 offset:59904
	ds_read_b128 v[224:227], v245 offset:62208
	ds_read_b128 v[200:203], v244 offset:20736
	v_mfma_f32_16x16x32_bf16 v[34:37], v[204:207], v[228:231], v[34:37]
	v_mfma_f32_16x16x32_bf16 v[38:41], v[204:207], v[232:235], v[38:41]
	v_mfma_f32_16x16x32_bf16 v[2:5], v[204:207], v[236:239], v[2:5]
	v_mfma_f32_16x16x32_bf16 v[6:9], v[204:207], v[240:243], v[6:9]
	ds_read_b128 v[204:207], v244 offset:23040
	v_mfma_f32_16x16x32_bf16 v[42:45], v[208:211], v[228:231], v[42:45]
	v_mfma_f32_16x16x32_bf16 v[46:49], v[208:211], v[232:235], v[46:49]
	v_mfma_f32_16x16x32_bf16 v[10:13], v[208:211], v[236:239], v[10:13]
	v_mfma_f32_16x16x32_bf16 v[14:17], v[208:211], v[240:243], v[14:17]
	ds_read_b128 v[208:211], v244 offset:25344
	s_waitcnt lgkmcnt(6)
	v_mfma_f32_16x16x32_bf16 v[50:53], v[196:199], v[212:215], v[50:53]
	ds_read_b128 v[228:231], v245 offset:55360
	s_waitcnt lgkmcnt(6)
	v_mfma_f32_16x16x32_bf16 v[54:57], v[196:199], v[216:219], v[54:57]
	ds_read_b128 v[232:235], v245 offset:57664
	s_waitcnt lgkmcnt(6)
	v_mfma_f32_16x16x32_bf16 v[18:21], v[196:199], v[220:223], v[18:21]
	ds_read_b128 v[236:239], v245 offset:59968
	s_waitcnt lgkmcnt(6)
	v_mfma_f32_16x16x32_bf16 v[22:25], v[196:199], v[224:227], v[22:25]
	ds_read_b128 v[240:243], v245 offset:62272
	ds_read_b128 v[196:199], v244 offset:18496
	s_waitcnt lgkmcnt(7)
	v_mfma_f32_16x16x32_bf16 v[58:61], v[200:203], v[212:215], v[58:61]
	v_mfma_f32_16x16x32_bf16 v[62:65], v[200:203], v[216:219], v[62:65]
	v_mfma_f32_16x16x32_bf16 v[26:29], v[200:203], v[220:223], v[26:29]
	v_mfma_f32_16x16x32_bf16 v[30:33], v[200:203], v[224:227], v[30:33]
	ds_read_b128 v[200:203], v244 offset:20800
	s_waitcnt lgkmcnt(7)
	v_mfma_f32_16x16x32_bf16 v[34:37], v[204:207], v[212:215], v[34:37]
	v_mfma_f32_16x16x32_bf16 v[38:41], v[204:207], v[216:219], v[38:41]
	v_mfma_f32_16x16x32_bf16 v[2:5], v[204:207], v[220:223], v[2:5]
	v_mfma_f32_16x16x32_bf16 v[6:9], v[204:207], v[224:227], v[6:9]
	ds_read_b128 v[204:207], v244 offset:23104
	s_waitcnt lgkmcnt(7)
	v_mfma_f32_16x16x32_bf16 v[42:45], v[208:211], v[212:215], v[42:45]
	v_mfma_f32_16x16x32_bf16 v[46:49], v[208:211], v[216:219], v[46:49]
	v_mfma_f32_16x16x32_bf16 v[10:13], v[208:211], v[220:223], v[10:13]
	v_mfma_f32_16x16x32_bf16 v[14:17], v[208:211], v[224:227], v[14:17]
	ds_read_b128 v[208:211], v244 offset:25408
	s_waitcnt lgkmcnt(3)
	v_mfma_f32_16x16x32_bf16 v[50:53], v[196:199], v[228:231], v[50:53]
	v_mfma_f32_16x16x32_bf16 v[54:57], v[196:199], v[232:235], v[54:57]
	v_mfma_f32_16x16x32_bf16 v[18:21], v[196:199], v[236:239], v[18:21]
	v_mfma_f32_16x16x32_bf16 v[22:25], v[196:199], v[240:243], v[22:25]
	s_waitcnt lgkmcnt(2)
	v_mfma_f32_16x16x32_bf16 v[58:61], v[200:203], v[228:231], v[58:61]
	v_mfma_f32_16x16x32_bf16 v[62:65], v[200:203], v[232:235], v[62:65]
	v_mfma_f32_16x16x32_bf16 v[26:29], v[200:203], v[236:239], v[26:29]
	v_mfma_f32_16x16x32_bf16 v[30:33], v[200:203], v[240:243], v[30:33]
	s_add_i32 s6, s6, 1
	s_add_i32 s5, s5, s3
	v_or_b32_e32 v70, s0, v92
	s_lshl_b32 s0, s7, 1
	v_lshl_add_u64 v[110:111], v[80:81], 0, s[0:1]
	v_lshlrev_b32_e32 v74, 10, v70
	v_lshl_add_u64 v[112:113], v[110:111], 0, v[74:75]
	s_waitcnt lgkmcnt(0)
	s_barrier
	v_mfma_f32_16x16x32_bf16 v[34:37], v[204:207], v[228:231], v[34:37]
	v_mfma_f32_16x16x32_bf16 v[38:41], v[204:207], v[232:235], v[38:41]
	v_mfma_f32_16x16x32_bf16 v[2:5], v[204:207], v[236:239], v[2:5]
	v_mfma_f32_16x16x32_bf16 v[6:9], v[204:207], v[240:243], v[6:9]
	v_mfma_f32_16x16x32_bf16 v[42:45], v[208:211], v[228:231], v[42:45]
	v_mfma_f32_16x16x32_bf16 v[46:49], v[208:211], v[232:235], v[46:49]
	v_mfma_f32_16x16x32_bf16 v[10:13], v[208:211], v[236:239], v[10:13]
	v_mfma_f32_16x16x32_bf16 v[14:17], v[208:211], v[240:243], v[14:17]
	s_nop 7
	v_permlane16_swap_b32_e32 v50, v54
	v_permlane16_swap_b32_e32 v51, v55
	v_permlane16_swap_b32_e32 v52, v56
	v_permlane16_swap_b32_e32 v53, v57
	v_permlane16_swap_b32_e32 v58, v62
	v_permlane16_swap_b32_e32 v59, v63
	v_permlane16_swap_b32_e32 v60, v64
	v_permlane16_swap_b32_e32 v61, v65
	v_permlane16_swap_b32_e32 v18, v22
	v_permlane16_swap_b32_e32 v19, v23
	v_permlane16_swap_b32_e32 v20, v24
	v_permlane16_swap_b32_e32 v21, v25
	v_permlane16_swap_b32_e32 v26, v30
	v_permlane16_swap_b32_e32 v27, v31
	v_permlane16_swap_b32_e32 v28, v32
	v_permlane16_swap_b32_e32 v29, v33
	v_permlane16_swap_b32_e32 v34, v38
	v_permlane16_swap_b32_e32 v35, v39
	v_permlane16_swap_b32_e32 v36, v40
	v_permlane16_swap_b32_e32 v37, v41
	v_permlane16_swap_b32_e32 v42, v46
	v_permlane16_swap_b32_e32 v43, v47
	v_permlane16_swap_b32_e32 v44, v48
	v_permlane16_swap_b32_e32 v45, v49
	v_permlane16_swap_b32_e32 v2, v6
	v_permlane16_swap_b32_e32 v3, v7
	v_permlane16_swap_b32_e32 v4, v8
	v_permlane16_swap_b32_e32 v5, v9
	v_permlane16_swap_b32_e32 v10, v14
	v_permlane16_swap_b32_e32 v11, v15
	v_permlane16_swap_b32_e32 v12, v16
	v_permlane16_swap_b32_e32 v13, v17
	v_permlane32_swap_b32_e32 v50, v54
	v_permlane32_swap_b32_e32 v51, v55
	v_permlane32_swap_b32_e32 v52, v56
	v_permlane32_swap_b32_e32 v53, v57
	v_permlane32_swap_b32_e32 v58, v62
	v_permlane32_swap_b32_e32 v59, v63
	v_permlane32_swap_b32_e32 v60, v64
	v_permlane32_swap_b32_e32 v61, v65
	v_permlane32_swap_b32_e32 v18, v22
	v_permlane32_swap_b32_e32 v19, v23
	v_permlane32_swap_b32_e32 v20, v24
	v_permlane32_swap_b32_e32 v21, v25
	v_permlane32_swap_b32_e32 v26, v30
	v_permlane32_swap_b32_e32 v27, v31
	v_permlane32_swap_b32_e32 v28, v32
	v_permlane32_swap_b32_e32 v29, v33
	v_permlane32_swap_b32_e32 v34, v38
	v_permlane32_swap_b32_e32 v35, v39
	v_permlane32_swap_b32_e32 v36, v40
	v_permlane32_swap_b32_e32 v37, v41
	v_permlane32_swap_b32_e32 v42, v46
	v_permlane32_swap_b32_e32 v43, v47
	v_permlane32_swap_b32_e32 v44, v48
	v_permlane32_swap_b32_e32 v45, v49
	v_permlane32_swap_b32_e32 v2, v6
	v_permlane32_swap_b32_e32 v3, v7
	v_permlane32_swap_b32_e32 v4, v8
	v_permlane32_swap_b32_e32 v5, v9
	v_permlane32_swap_b32_e32 v10, v14
	v_permlane32_swap_b32_e32 v11, v15
	v_permlane32_swap_b32_e32 v12, v16
	v_permlane32_swap_b32_e32 v13, v17
	global_load_dwordx4 v[106:109], v[112:113], off
	s_mul_i32 s0, s6, s3
	s_add_i32 s0, s0, s2
	s_cmp_lt_u32 s5, 48
	global_load_dwordx4 v[88:91], v[112:113], off offset:32
	global_load_dwordx4 v[70:73], v[112:113], off offset:64
	s_waitcnt vmcnt(2)
	v_mov_b32_e32 v86, v108
	global_load_dwordx4 v[66:69], v[112:113], off offset:96
	v_permlane32_swap_b32_e32 v106, v86
	v_mov_b32_e32 v102, v109
	s_nop 1
	v_permlane32_swap_b32_e32 v107, v102
	s_waitcnt vmcnt(2)
	v_mov_b32_e32 v108, v90
	v_mov_b32_e32 v109, v91
	s_nop 0
	v_permlane32_swap_b32_e32 v88, v108
	v_permlane32_swap_b32_e32 v89, v109
	s_waitcnt vmcnt(1)
	v_mov_b32_e32 v112, v72
	v_mov_b32_e32 v113, v73
	v_lshlrev_b32_e32 v72, 16, v106
	v_and_b32_e32 v73, 0xffff0000, v106
	v_pk_mul_f32 v[72:73], v[50:51], v[72:73]
	v_lshlrev_b32_e32 v50, 16, v107
	v_and_b32_e32 v51, 0xffff0000, v107
	v_pk_mul_f32 v[84:85], v[52:53], v[50:51]
	v_lshlrev_b32_e32 v50, 16, v86
	v_and_b32_e32 v51, 0xffff0000, v86
	v_pk_mul_f32 v[86:87], v[54:55], v[50:51]
	v_lshlrev_b32_e32 v54, 16, v102
	v_and_b32_e32 v55, 0xffff0000, v102
	v_pk_mul_f32 v[102:103], v[56:57], v[54:55]
	v_cvt_pk_bf16_f32 v55, v84, v85
	v_cvt_pk_bf16_f32 v56, v86, v87
	v_cvt_pk_bf16_f32 v57, v102, v103
	v_cvt_pk_bf16_f32 v54, v72, v73
	v_add_lshl_u32 v72, s7, v97, 1
	v_mov_b32_e32 v73, v75
	v_permlane32_swap_b32_e32 v54, v56
	v_permlane32_swap_b32_e32 v55, v57
	v_lshlrev_b32_e32 v106, 16, v88
	v_and_b32_e32 v107, 0xffff0000, v88
	v_lshlrev_b32_e32 v88, 16, v89
	v_and_b32_e32 v89, 0xffff0000, v89
	v_pk_mul_f32 v[60:61], v[60:61], v[88:89]
	v_lshlrev_b32_e32 v88, 16, v108
	v_and_b32_e32 v89, 0xffff0000, v108
	v_pk_mul_f32 v[62:63], v[62:63], v[88:89]
	v_lshlrev_b32_e32 v88, 16, v109
	v_and_b32_e32 v89, 0xffff0000, v109
	v_pk_mul_f32 v[58:59], v[58:59], v[106:107]
	v_pk_mul_f32 v[64:65], v[64:65], v[88:89]
	v_cvt_pk_bf16_f32 v58, v58, v59
	v_cvt_pk_bf16_f32 v59, v60, v61
	v_cvt_pk_bf16_f32 v60, v62, v63
	v_cvt_pk_bf16_f32 v61, v64, v65
	v_permlane32_swap_b32_e32 v70, v112
	v_permlane32_swap_b32_e32 v58, v60
	v_permlane32_swap_b32_e32 v59, v61
	v_permlane32_swap_b32_e32 v71, v113
	s_waitcnt vmcnt(0)
	v_mov_b32_e32 v114, v68
	v_mov_b32_e32 v115, v69
	v_lshl_add_u64 v[68:69], v[82:83], 0, v[74:75]
	v_or_b32_e32 v74, 0x8000, v74
	v_lshl_add_u64 v[90:91], v[110:111], 0, v[74:75]
	global_load_dwordx4 v[50:53], v[90:91], off
	global_load_dwordx4 v[84:87], v[90:91], off offset:32
	global_load_dwordx4 v[102:105], v[90:91], off offset:64
	v_lshl_add_u64 v[68:69], v[68:69], 0, v[72:73]
	global_store_dwordx4 v[68:69], v[54:57], off
	global_load_dwordx4 v[54:57], v[90:91], off offset:96
	v_permlane32_swap_b32_e32 v66, v114
	global_store_dwordx4 v[68:69], v[58:61], off offset:32
	v_permlane32_swap_b32_e32 v67, v115
	s_nop 0
	v_lshlrev_b32_e32 v58, 16, v70
	v_and_b32_e32 v59, 0xffff0000, v70
	v_pk_mul_f32 v[34:35], v[34:35], v[58:59]
	v_lshlrev_b32_e32 v58, 16, v71
	v_and_b32_e32 v59, 0xffff0000, v71
	v_pk_mul_f32 v[36:37], v[36:37], v[58:59]
	v_lshlrev_b32_e32 v58, 16, v112
	v_and_b32_e32 v59, 0xffff0000, v112
	v_pk_mul_f32 v[38:39], v[38:39], v[58:59]
	v_lshlrev_b32_e32 v58, 16, v113
	v_and_b32_e32 v59, 0xffff0000, v113
	v_pk_mul_f32 v[40:41], v[40:41], v[58:59]
	v_cvt_pk_bf16_f32 v34, v34, v35
	v_cvt_pk_bf16_f32 v35, v36, v37
	v_cvt_pk_bf16_f32 v36, v38, v39
	v_cvt_pk_bf16_f32 v37, v40, v41
	s_nop 0
	v_permlane32_swap_b32_e32 v34, v36
	v_permlane32_swap_b32_e32 v35, v37
	global_store_dwordx4 v[68:69], v[34:37], off offset:64
	v_lshlrev_b32_e32 v38, 16, v114
	v_and_b32_e32 v39, 0xffff0000, v114
	v_lshlrev_b32_e32 v34, 16, v66
	v_and_b32_e32 v35, 0xffff0000, v66
	v_lshlrev_b32_e32 v36, 16, v67
	v_and_b32_e32 v37, 0xffff0000, v67
	v_lshlrev_b32_e32 v40, 16, v115
	v_and_b32_e32 v41, 0xffff0000, v115
	v_pk_mul_f32 v[34:35], v[42:43], v[34:35]
	v_pk_mul_f32 v[36:37], v[44:45], v[36:37]
	v_pk_mul_f32 v[38:39], v[46:47], v[38:39]
	v_pk_mul_f32 v[40:41], v[48:49], v[40:41]
	v_cvt_pk_bf16_f32 v34, v34, v35
	v_cvt_pk_bf16_f32 v35, v36, v37
	v_cvt_pk_bf16_f32 v36, v38, v39
	v_cvt_pk_bf16_f32 v37, v40, v41
	s_nop 0
	v_permlane32_swap_b32_e32 v34, v36
	v_permlane32_swap_b32_e32 v35, v37
	global_store_dwordx4 v[68:69], v[34:37], off offset:96
	s_waitcnt vmcnt(7)
	v_mov_b32_e32 v38, v52
	s_nop 1
	v_permlane32_swap_b32_e32 v50, v38
	v_mov_b32_e32 v39, v53
	s_nop 1
	v_permlane32_swap_b32_e32 v51, v39
	v_lshlrev_b32_e32 v36, 16, v50
	v_and_b32_e32 v37, 0xffff0000, v50
	v_pk_mul_f32 v[18:19], v[18:19], v[36:37]
	v_lshlrev_b32_e32 v36, 16, v51
	v_and_b32_e32 v37, 0xffff0000, v51
	v_pk_mul_f32 v[20:21], v[20:21], v[36:37]
	v_lshlrev_b32_e32 v36, 16, v38
	v_and_b32_e32 v37, 0xffff0000, v38
	v_pk_mul_f32 v[22:23], v[22:23], v[36:37]
	v_lshlrev_b32_e32 v36, 16, v39
	v_and_b32_e32 v37, 0xffff0000, v39
	v_pk_mul_f32 v[24:25], v[24:25], v[36:37]
	s_waitcnt vmcnt(6)
	v_mov_b32_e32 v40, v86
	v_lshl_add_u64 v[34:35], v[82:83], 0, v[74:75]
	v_cvt_pk_bf16_f32 v18, v18, v19
	v_cvt_pk_bf16_f32 v19, v20, v21
	v_cvt_pk_bf16_f32 v20, v22, v23
	v_cvt_pk_bf16_f32 v21, v24, v25
	v_permlane32_swap_b32_e32 v84, v40
	v_mov_b32_e32 v41, v87
	v_permlane32_swap_b32_e32 v18, v20
	v_permlane32_swap_b32_e32 v19, v21
	v_lshl_add_u64 v[22:23], v[34:35], 0, v[72:73]
	v_permlane32_swap_b32_e32 v85, v41
	global_store_dwordx4 v[22:23], v[18:21], off
	v_lshlrev_b32_e32 v24, 16, v40
	v_and_b32_e32 v25, 0xffff0000, v40
	v_lshlrev_b32_e32 v18, 16, v84
	v_and_b32_e32 v19, 0xffff0000, v84
	v_pk_mul_f32 v[18:19], v[26:27], v[18:19]
	v_lshlrev_b32_e32 v20, 16, v85
	v_and_b32_e32 v21, 0xffff0000, v85
	v_lshlrev_b32_e32 v26, 16, v41
	v_and_b32_e32 v27, 0xffff0000, v41
	v_pk_mul_f32 v[20:21], v[28:29], v[20:21]
	v_pk_mul_f32 v[24:25], v[30:31], v[24:25]
	v_pk_mul_f32 v[26:27], v[32:33], v[26:27]
	s_waitcnt vmcnt(6)
	v_mov_b32_e32 v42, v104
	v_cvt_pk_bf16_f32 v18, v18, v19
	v_cvt_pk_bf16_f32 v19, v20, v21
	v_cvt_pk_bf16_f32 v20, v24, v25
	v_cvt_pk_bf16_f32 v21, v26, v27
	v_permlane32_swap_b32_e32 v102, v42
	v_mov_b32_e32 v43, v105
	v_permlane32_swap_b32_e32 v18, v20
	v_permlane32_swap_b32_e32 v19, v21
	v_permlane32_swap_b32_e32 v103, v43
	global_store_dwordx4 v[22:23], v[18:21], off offset:32
	s_waitcnt vmcnt(5)
	v_mov_b32_e32 v44, v56
	v_mov_b32_e32 v45, v57
	v_lshlrev_b32_e32 v18, 16, v102
	v_and_b32_e32 v19, 0xffff0000, v102
	v_pk_mul_f32 v[2:3], v[2:3], v[18:19]
	v_lshlrev_b32_e32 v18, 16, v103
	v_and_b32_e32 v19, 0xffff0000, v103
	v_pk_mul_f32 v[4:5], v[4:5], v[18:19]
	v_lshlrev_b32_e32 v18, 16, v42
	v_and_b32_e32 v19, 0xffff0000, v42
	v_pk_mul_f32 v[6:7], v[6:7], v[18:19]
	v_lshlrev_b32_e32 v18, 16, v43
	v_and_b32_e32 v19, 0xffff0000, v43
	v_pk_mul_f32 v[8:9], v[8:9], v[18:19]
	v_cvt_pk_bf16_f32 v2, v2, v3
	v_cvt_pk_bf16_f32 v3, v4, v5
	v_cvt_pk_bf16_f32 v4, v6, v7
	v_cvt_pk_bf16_f32 v5, v8, v9
	v_permlane32_swap_b32_e32 v54, v44
	v_permlane32_swap_b32_e32 v55, v45
	v_permlane32_swap_b32_e32 v2, v4
	v_permlane32_swap_b32_e32 v3, v5
	global_store_dwordx4 v[22:23], v[2:5], off offset:64
	v_lshlrev_b32_e32 v6, 16, v44
	v_and_b32_e32 v7, 0xffff0000, v44
	v_lshlrev_b32_e32 v2, 16, v54
	v_and_b32_e32 v3, 0xffff0000, v54
	v_lshlrev_b32_e32 v4, 16, v55
	v_and_b32_e32 v5, 0xffff0000, v55
	v_lshlrev_b32_e32 v8, 16, v45
	v_and_b32_e32 v9, 0xffff0000, v45
	v_pk_mul_f32 v[2:3], v[10:11], v[2:3]
	v_pk_mul_f32 v[4:5], v[12:13], v[4:5]
	v_pk_mul_f32 v[6:7], v[14:15], v[6:7]
	v_pk_mul_f32 v[8:9], v[16:17], v[8:9]
	v_cvt_pk_bf16_f32 v2, v2, v3
	v_cvt_pk_bf16_f32 v3, v4, v5
	v_cvt_pk_bf16_f32 v4, v6, v7
	v_cvt_pk_bf16_f32 v5, v8, v9
	s_nop 0
	v_permlane32_swap_b32_e32 v2, v4
	v_permlane32_swap_b32_e32 v3, v5
	global_store_dwordx4 v[22:23], v[2:5], off offset:96
	s_cbranch_scc1 .LBB0_1720

.LBB0_1795:
	s_cmp_eq_u32 s2, 0x100000
	s_cselect_b32 s0, s13, 0x5400000
	s_cmp_lg_u32 s2, 0
	v_lshl_add_u64 v[2:3], v[148:149], 0, s[2:3]
	s_cselect_b32 s0, s0, 0
	v_add_co_u32_e32 v174, vcc, s14, v2
	s_add_u32 s4, s82, s0
	v_lshl_add_u64 v[4:5], v[152:153], 0, s[2:3]
	v_addc_co_u32_e32 v175, vcc, 0, v3, vcc
	s_addc_u32 s5, s83, 0
	v_add_co_u32_e32 v176, vcc, s14, v4
	v_lshl_add_u64 v[10:11], v[154:155], 0, s[2:3]
	v_lshl_add_u64 v[6:7], s[4:5], 0, v[104:105]
	v_addc_co_u32_e32 v177, vcc, 0, v5, vcc
	v_lshl_add_u64 v[66:67], v[6:7], 0, v[82:83]
	v_lshl_add_u64 v[6:7], s[4:5], 0, v[112:113]
	v_add_co_u32_e32 v178, vcc, s14, v10
	v_lshl_add_u64 v[12:13], v[156:157], 0, s[2:3]
	v_lshl_add_u64 v[70:71], v[6:7], 0, v[82:83]
	v_lshl_add_u64 v[6:7], s[4:5], 0, v[116:117]
	v_addc_co_u32_e32 v179, vcc, 0, v11, vcc
	v_lshl_add_u64 v[68:69], v[6:7], 0, v[82:83]
	v_lshl_add_u64 v[6:7], s[4:5], 0, v[120:121]
	v_add_co_u32_e32 v180, vcc, s14, v12
	v_lshl_add_u64 v[72:73], v[6:7], 0, v[82:83]
	global_load_dwordx4 v[2:5], v[174:175], off
	global_load_dwordx4 v[6:9], v[176:177], off
	v_addc_co_u32_e32 v181, vcc, 0, v13, vcc
	global_load_dwordx4 v[10:13], v[178:179], off
	global_load_dwordx4 v[14:17], v[180:181], off
	global_load_dwordx4 v[18:21], v[66:67], off
	global_load_dwordx4 v[22:25], v[70:71], off
	global_load_dwordx4 v[26:29], v[68:69], off
	global_load_dwordx4 v[30:33], v[72:73], off
	s_cmp_lt_i32 s17, 1
	s_mov_b32 s0, s11
	s_setprio 1
	s_waitcnt vmcnt(7)
	ds_write_b128 v189, v[2:5]
	s_waitcnt vmcnt(6)
	ds_write_b128 v189, v[6:9] offset:4608
	s_waitcnt vmcnt(5)
	ds_write_b128 v189, v[10:13] offset:9216
	s_waitcnt vmcnt(4)
	ds_write_b128 v189, v[14:17] offset:13824
	s_waitcnt vmcnt(3)
	ds_write_b128 v189, v[18:21] offset:36864
	s_waitcnt vmcnt(2)
	ds_write_b128 v189, v[22:25] offset:41472
	s_waitcnt vmcnt(1)
	ds_write_b128 v189, v[26:29] offset:46080
	s_waitcnt vmcnt(0)
	ds_write_b128 v189, v[30:33] offset:50688
	s_waitcnt lgkmcnt(0)
	s_barrier
	s_setprio 0
	ds_read_b128 v[2:5], v186
	ds_read_b128 v[6:9], v188 offset:36864
	ds_read_b128 v[196:199], v186 offset:32
	ds_read_b128 v[200:203], v188 offset:36896
	ds_read_b128 v[10:13], v186 offset:4608
	ds_read_b128 v[204:207], v186 offset:4640
	s_waitcnt lgkmcnt(4)
	v_mfma_f32_32x32x16_bf16 v[50:65], v[2:5], v[6:9], 0
	s_waitcnt lgkmcnt(1)
	v_mfma_f32_32x32x16_bf16 v[34:49], v[10:13], v[6:9], 0
	ds_read_b128 v[6:9], v188 offset:41472
	ds_read_b128 v[208:211], v188 offset:41504
	s_waitcnt lgkmcnt(1)
	v_mfma_f32_32x32x16_bf16 v[18:33], v[2:5], v[6:9], 0
	v_mfma_f32_32x32x16_bf16 v[2:17], v[10:13], v[6:9], 0
	v_mfma_f32_32x32x16_bf16 v[50:65], v[196:199], v[200:203], v[50:65]
	v_mfma_f32_32x32x16_bf16 v[34:49], v[204:207], v[200:203], v[34:49]
	s_waitcnt lgkmcnt(0)
	v_mfma_f32_32x32x16_bf16 v[18:33], v[196:199], v[208:211], v[18:33]
	v_mfma_f32_32x32x16_bf16 v[2:17], v[204:207], v[208:211], v[2:17]
	ds_read_b128 v[196:199], v186 offset:64
	ds_read_b128 v[200:203], v188 offset:36928
	ds_read_b128 v[204:207], v186 offset:96
	ds_read_b128 v[208:211], v188 offset:36960
	ds_read_b128 v[212:215], v186 offset:4672
	ds_read_b128 v[216:219], v186 offset:4704
	s_waitcnt lgkmcnt(4)
	v_mfma_f32_32x32x16_bf16 v[50:65], v[196:199], v[200:203], v[50:65]
	s_waitcnt lgkmcnt(1)
	v_mfma_f32_32x32x16_bf16 v[34:49], v[212:215], v[200:203], v[34:49]
	ds_read_b128 v[200:203], v188 offset:41536
	ds_read_b128 v[220:223], v188 offset:41568
	s_waitcnt lgkmcnt(1)
	v_mfma_f32_32x32x16_bf16 v[18:33], v[196:199], v[200:203], v[18:33]
	v_mfma_f32_32x32x16_bf16 v[2:17], v[212:215], v[200:203], v[2:17]
	v_mfma_f32_32x32x16_bf16 v[50:65], v[204:207], v[208:211], v[50:65]
	v_mfma_f32_32x32x16_bf16 v[34:49], v[216:219], v[208:211], v[34:49]
	global_load_dwordx4 v[196:199], v[174:175], off offset:128
	global_load_dwordx4 v[200:203], v[176:177], off offset:128
	global_load_dwordx4 v[208:211], v[178:179], off offset:128
	global_load_dwordx4 v[212:215], v[180:181], off offset:128
	global_load_dwordx4 v[224:227], v[66:67], off offset:128
	global_load_dwordx4 v[228:231], v[70:71], off offset:128
	s_waitcnt lgkmcnt(0)
	v_mfma_f32_32x32x16_bf16 v[18:33], v[204:207], v[220:223], v[18:33]
	global_load_dwordx4 v[204:207], v[68:69], off offset:128
	global_load_dwordx4 v[232:235], v[72:73], off offset:128
	s_setprio 1
	s_waitcnt vmcnt(7)
	ds_write_b128 v189, v[196:199] offset:18432
	s_waitcnt vmcnt(6)
	ds_write_b128 v189, v[200:203] offset:23040
	s_waitcnt vmcnt(5)
	ds_write_b128 v189, v[208:211] offset:27648
	s_waitcnt vmcnt(4)
	ds_write_b128 v189, v[212:215] offset:32256
	s_waitcnt vmcnt(3)
	ds_write_b128 v189, v[224:227] offset:55296
	s_waitcnt vmcnt(2)
	ds_write_b128 v189, v[228:231] offset:59904
	s_waitcnt vmcnt(1)
	ds_write_b128 v189, v[204:207] offset:64512
	s_waitcnt vmcnt(0)
	ds_write_b128 v190, v[232:235] offset:32256
	v_mfma_f32_32x32x16_bf16 v[2:17], v[216:219], v[220:223], v[2:17]
	s_waitcnt lgkmcnt(0)
	s_barrier
	s_setprio 0
	ds_read_b128 v[196:199], v186 offset:18432
	ds_read_b128 v[200:203], v188 offset:55296
	ds_read_b128 v[204:207], v186 offset:18464
	ds_read_b128 v[208:211], v188 offset:55328
	ds_read_b128 v[212:215], v186 offset:23040
	ds_read_b128 v[216:219], v186 offset:23072
	s_waitcnt lgkmcnt(4)
	v_mfma_f32_32x32x16_bf16 v[50:65], v[196:199], v[200:203], v[50:65]
	s_waitcnt lgkmcnt(1)
	v_mfma_f32_32x32x16_bf16 v[34:49], v[212:215], v[200:203], v[34:49]
	ds_read_b128 v[200:203], v188 offset:59904
	ds_read_b128 v[220:223], v188 offset:59936
	s_waitcnt lgkmcnt(1)
	v_mfma_f32_32x32x16_bf16 v[18:33], v[196:199], v[200:203], v[18:33]
	v_mfma_f32_32x32x16_bf16 v[2:17], v[212:215], v[200:203], v[2:17]
	v_mfma_f32_32x32x16_bf16 v[50:65], v[204:207], v[208:211], v[50:65]
	v_mfma_f32_32x32x16_bf16 v[34:49], v[216:219], v[208:211], v[34:49]
	s_waitcnt lgkmcnt(0)
	v_mfma_f32_32x32x16_bf16 v[18:33], v[204:207], v[220:223], v[18:33]
	ds_read_b128 v[196:199], v186 offset:18496
	ds_read_b128 v[200:203], v188 offset:55360
	ds_read_b128 v[204:207], v186 offset:18528
	ds_read_b128 v[208:211], v188 offset:55392
	v_mfma_f32_32x32x16_bf16 v[2:17], v[216:219], v[220:223], v[2:17]
	ds_read_b128 v[212:215], v186 offset:23104
	ds_read_b128 v[216:219], v186 offset:23136
	s_waitcnt lgkmcnt(4)
	v_mfma_f32_32x32x16_bf16 v[50:65], v[196:199], v[200:203], v[50:65]
	s_waitcnt lgkmcnt(1)
	v_mfma_f32_32x32x16_bf16 v[34:49], v[212:215], v[200:203], v[34:49]
	ds_read_b128 v[200:203], v188 offset:59968
	ds_read_b128 v[220:223], v188 offset:60000
	s_waitcnt lgkmcnt(1)
	v_mfma_f32_32x32x16_bf16 v[18:33], v[196:199], v[200:203], v[18:33]
	v_mfma_f32_32x32x16_bf16 v[2:17], v[212:215], v[200:203], v[2:17]
	v_mfma_f32_32x32x16_bf16 v[50:65], v[204:207], v[208:211], v[50:65]
	v_mfma_f32_32x32x16_bf16 v[34:49], v[216:219], v[208:211], v[34:49]
	global_load_dwordx4 v[196:199], v[174:175], off offset:256
	global_load_dwordx4 v[200:203], v[176:177], off offset:256
	global_load_dwordx4 v[208:211], v[178:179], off offset:256
	global_load_dwordx4 v[212:215], v[180:181], off offset:256
	global_load_dwordx4 v[224:227], v[66:67], off offset:256
	global_load_dwordx4 v[228:231], v[70:71], off offset:256
	s_waitcnt lgkmcnt(0)
	v_mfma_f32_32x32x16_bf16 v[18:33], v[204:207], v[220:223], v[18:33]
	global_load_dwordx4 v[204:207], v[68:69], off offset:256
	global_load_dwordx4 v[232:235], v[72:73], off offset:256
	s_setprio 1
	s_waitcnt vmcnt(7)
	ds_write_b128 v189, v[196:199]
	s_waitcnt vmcnt(6)
	ds_write_b128 v189, v[200:203] offset:4608
	s_waitcnt vmcnt(5)
	ds_write_b128 v189, v[208:211] offset:9216
	s_waitcnt vmcnt(4)
	ds_write_b128 v189, v[212:215] offset:13824
	s_waitcnt vmcnt(3)
	ds_write_b128 v189, v[224:227] offset:36864
	s_waitcnt vmcnt(2)
	ds_write_b128 v189, v[228:231] offset:41472
	s_waitcnt vmcnt(1)
	ds_write_b128 v189, v[204:207] offset:46080
	s_waitcnt vmcnt(0)
	ds_write_b128 v189, v[232:235] offset:50688
	v_mfma_f32_32x32x16_bf16 v[2:17], v[216:219], v[220:223], v[2:17]
	s_waitcnt lgkmcnt(0)
	s_barrier
	s_setprio 0
	ds_read_b128 v[196:199], v186
	ds_read_b128 v[200:203], v188 offset:36864
	ds_read_b128 v[204:207], v186 offset:32
	ds_read_b128 v[208:211], v188 offset:36896
	ds_read_b128 v[212:215], v186 offset:4608
	ds_read_b128 v[216:219], v186 offset:4640
	s_waitcnt lgkmcnt(4)
	v_mfma_f32_32x32x16_bf16 v[50:65], v[196:199], v[200:203], v[50:65]
	s_waitcnt lgkmcnt(1)
	v_mfma_f32_32x32x16_bf16 v[34:49], v[212:215], v[200:203], v[34:49]
	ds_read_b128 v[200:203], v188 offset:41472
	ds_read_b128 v[220:223], v188 offset:41504
	s_waitcnt lgkmcnt(1)
	v_mfma_f32_32x32x16_bf16 v[18:33], v[196:199], v[200:203], v[18:33]
	v_mfma_f32_32x32x16_bf16 v[2:17], v[212:215], v[200:203], v[2:17]
	v_mfma_f32_32x32x16_bf16 v[50:65], v[204:207], v[208:211], v[50:65]
	v_mfma_f32_32x32x16_bf16 v[34:49], v[216:219], v[208:211], v[34:49]
	s_waitcnt lgkmcnt(0)
	v_mfma_f32_32x32x16_bf16 v[18:33], v[204:207], v[220:223], v[18:33]
	ds_read_b128 v[196:199], v186 offset:64
	ds_read_b128 v[200:203], v188 offset:36928
	ds_read_b128 v[204:207], v186 offset:96
	ds_read_b128 v[208:211], v188 offset:36960
	v_mfma_f32_32x32x16_bf16 v[2:17], v[216:219], v[220:223], v[2:17]
	ds_read_b128 v[212:215], v186 offset:4672
	ds_read_b128 v[216:219], v186 offset:4704
	s_waitcnt lgkmcnt(4)
	v_mfma_f32_32x32x16_bf16 v[50:65], v[196:199], v[200:203], v[50:65]
	s_waitcnt lgkmcnt(1)
	v_mfma_f32_32x32x16_bf16 v[34:49], v[212:215], v[200:203], v[34:49]
	ds_read_b128 v[200:203], v188 offset:41536
	ds_read_b128 v[220:223], v188 offset:41568
	s_waitcnt lgkmcnt(1)
	v_mfma_f32_32x32x16_bf16 v[18:33], v[196:199], v[200:203], v[18:33]
	v_mfma_f32_32x32x16_bf16 v[2:17], v[212:215], v[200:203], v[2:17]
	v_mfma_f32_32x32x16_bf16 v[50:65], v[204:207], v[208:211], v[50:65]
	v_mfma_f32_32x32x16_bf16 v[34:49], v[216:219], v[208:211], v[34:49]
	global_load_dwordx4 v[196:199], v[174:175], off offset:384
	global_load_dwordx4 v[200:203], v[176:177], off offset:384
	global_load_dwordx4 v[208:211], v[178:179], off offset:384
	global_load_dwordx4 v[212:215], v[180:181], off offset:384
	global_load_dwordx4 v[224:227], v[66:67], off offset:384
	global_load_dwordx4 v[228:231], v[70:71], off offset:384
	s_waitcnt lgkmcnt(0)
	v_mfma_f32_32x32x16_bf16 v[18:33], v[204:207], v[220:223], v[18:33]
	global_load_dwordx4 v[204:207], v[68:69], off offset:384
	global_load_dwordx4 v[232:235], v[72:73], off offset:384
	s_setprio 1
	s_waitcnt vmcnt(7)
	ds_write_b128 v189, v[196:199] offset:18432
	s_waitcnt vmcnt(6)
	ds_write_b128 v189, v[200:203] offset:23040
	s_waitcnt vmcnt(5)
	ds_write_b128 v189, v[208:211] offset:27648
	s_waitcnt vmcnt(4)
	ds_write_b128 v189, v[212:215] offset:32256
	s_waitcnt vmcnt(3)
	ds_write_b128 v189, v[224:227] offset:55296
	s_waitcnt vmcnt(2)
	ds_write_b128 v189, v[228:231] offset:59904
	s_waitcnt vmcnt(1)
	ds_write_b128 v189, v[204:207] offset:64512
	s_waitcnt vmcnt(0)
	ds_write_b128 v190, v[232:235] offset:32256
	v_mfma_f32_32x32x16_bf16 v[2:17], v[216:219], v[220:223], v[2:17]
	s_waitcnt lgkmcnt(0)
	s_barrier
	s_setprio 0
	ds_read_b128 v[196:199], v186 offset:18432
	ds_read_b128 v[200:203], v188 offset:55296
	ds_read_b128 v[204:207], v186 offset:18464
	ds_read_b128 v[208:211], v188 offset:55328
	ds_read_b128 v[212:215], v186 offset:23040
	ds_read_b128 v[216:219], v186 offset:23072
	s_waitcnt lgkmcnt(4)
	v_mfma_f32_32x32x16_bf16 v[50:65], v[196:199], v[200:203], v[50:65]
	s_waitcnt lgkmcnt(1)
	v_mfma_f32_32x32x16_bf16 v[34:49], v[212:215], v[200:203], v[34:49]
	ds_read_b128 v[200:203], v188 offset:59904
	ds_read_b128 v[220:223], v188 offset:59936
	s_waitcnt lgkmcnt(1)
	v_mfma_f32_32x32x16_bf16 v[18:33], v[196:199], v[200:203], v[18:33]
	v_mfma_f32_32x32x16_bf16 v[2:17], v[212:215], v[200:203], v[2:17]
	v_mfma_f32_32x32x16_bf16 v[50:65], v[204:207], v[208:211], v[50:65]
	v_mfma_f32_32x32x16_bf16 v[34:49], v[216:219], v[208:211], v[34:49]
	s_waitcnt lgkmcnt(0)
	v_mfma_f32_32x32x16_bf16 v[18:33], v[204:207], v[220:223], v[18:33]
	ds_read_b128 v[196:199], v186 offset:18496
	ds_read_b128 v[200:203], v188 offset:55360
	ds_read_b128 v[204:207], v186 offset:18528
	ds_read_b128 v[208:211], v188 offset:55392
	v_mfma_f32_32x32x16_bf16 v[2:17], v[216:219], v[220:223], v[2:17]
	ds_read_b128 v[212:215], v186 offset:23104
	ds_read_b128 v[216:219], v186 offset:23136
	s_waitcnt lgkmcnt(4)
	v_mfma_f32_32x32x16_bf16 v[50:65], v[196:199], v[200:203], v[50:65]
	s_waitcnt lgkmcnt(1)
	v_mfma_f32_32x32x16_bf16 v[34:49], v[212:215], v[200:203], v[34:49]
	ds_read_b128 v[200:203], v188 offset:59968
	ds_read_b128 v[220:223], v188 offset:60000
	s_waitcnt lgkmcnt(1)
	v_mfma_f32_32x32x16_bf16 v[18:33], v[196:199], v[200:203], v[18:33]
	v_mfma_f32_32x32x16_bf16 v[2:17], v[212:215], v[200:203], v[2:17]
	v_mfma_f32_32x32x16_bf16 v[50:65], v[204:207], v[208:211], v[50:65]
	v_mfma_f32_32x32x16_bf16 v[34:49], v[216:219], v[208:211], v[34:49]
	global_load_dwordx4 v[196:199], v[174:175], off offset:512
	global_load_dwordx4 v[200:203], v[176:177], off offset:512
	global_load_dwordx4 v[208:211], v[178:179], off offset:512
	global_load_dwordx4 v[212:215], v[180:181], off offset:512
	global_load_dwordx4 v[224:227], v[66:67], off offset:512
	global_load_dwordx4 v[228:231], v[70:71], off offset:512
	s_waitcnt lgkmcnt(0)
	v_mfma_f32_32x32x16_bf16 v[18:33], v[204:207], v[220:223], v[18:33]
	global_load_dwordx4 v[204:207], v[68:69], off offset:512
	global_load_dwordx4 v[232:235], v[72:73], off offset:512
	s_setprio 1
	s_waitcnt vmcnt(7)
	ds_write_b128 v189, v[196:199]
	s_waitcnt vmcnt(6)
	ds_write_b128 v189, v[200:203] offset:4608
	s_waitcnt vmcnt(5)
	ds_write_b128 v189, v[208:211] offset:9216
	s_waitcnt vmcnt(4)
	ds_write_b128 v189, v[212:215] offset:13824
	s_waitcnt vmcnt(3)
	ds_write_b128 v189, v[224:227] offset:36864
	s_waitcnt vmcnt(2)
	ds_write_b128 v189, v[228:231] offset:41472
	s_waitcnt vmcnt(1)
	ds_write_b128 v189, v[204:207] offset:46080
	s_waitcnt vmcnt(0)
	ds_write_b128 v189, v[232:235] offset:50688
	v_mfma_f32_32x32x16_bf16 v[2:17], v[216:219], v[220:223], v[2:17]
	s_waitcnt lgkmcnt(0)
	s_barrier
	s_setprio 0
	ds_read_b128 v[196:199], v186
	ds_read_b128 v[200:203], v188 offset:36864
	ds_read_b128 v[204:207], v186 offset:32
	ds_read_b128 v[208:211], v188 offset:36896
	ds_read_b128 v[212:215], v186 offset:4608
	ds_read_b128 v[216:219], v186 offset:4640
	s_waitcnt lgkmcnt(4)
	v_mfma_f32_32x32x16_bf16 v[50:65], v[196:199], v[200:203], v[50:65]
	s_waitcnt lgkmcnt(1)
	v_mfma_f32_32x32x16_bf16 v[34:49], v[212:215], v[200:203], v[34:49]
	ds_read_b128 v[200:203], v188 offset:41472
	ds_read_b128 v[220:223], v188 offset:41504
	s_waitcnt lgkmcnt(1)
	v_mfma_f32_32x32x16_bf16 v[18:33], v[196:199], v[200:203], v[18:33]
	v_mfma_f32_32x32x16_bf16 v[2:17], v[212:215], v[200:203], v[2:17]
	v_mfma_f32_32x32x16_bf16 v[50:65], v[204:207], v[208:211], v[50:65]
	v_mfma_f32_32x32x16_bf16 v[34:49], v[216:219], v[208:211], v[34:49]
	s_waitcnt lgkmcnt(0)
	v_mfma_f32_32x32x16_bf16 v[18:33], v[204:207], v[220:223], v[18:33]
	ds_read_b128 v[196:199], v186 offset:64
	ds_read_b128 v[200:203], v188 offset:36928
	ds_read_b128 v[204:207], v186 offset:96
	ds_read_b128 v[208:211], v188 offset:36960
	v_mfma_f32_32x32x16_bf16 v[2:17], v[216:219], v[220:223], v[2:17]
	ds_read_b128 v[212:215], v186 offset:4672
	ds_read_b128 v[216:219], v186 offset:4704
	s_waitcnt lgkmcnt(4)
	v_mfma_f32_32x32x16_bf16 v[50:65], v[196:199], v[200:203], v[50:65]
	s_waitcnt lgkmcnt(1)
	v_mfma_f32_32x32x16_bf16 v[34:49], v[212:215], v[200:203], v[34:49]
	ds_read_b128 v[200:203], v188 offset:41536
	ds_read_b128 v[220:223], v188 offset:41568
	s_waitcnt lgkmcnt(1)
	v_mfma_f32_32x32x16_bf16 v[18:33], v[196:199], v[200:203], v[18:33]
	v_mfma_f32_32x32x16_bf16 v[2:17], v[212:215], v[200:203], v[2:17]
	v_mfma_f32_32x32x16_bf16 v[50:65], v[204:207], v[208:211], v[50:65]
	v_mfma_f32_32x32x16_bf16 v[34:49], v[216:219], v[208:211], v[34:49]
	global_load_dwordx4 v[196:199], v[174:175], off offset:640
	global_load_dwordx4 v[200:203], v[176:177], off offset:640
	global_load_dwordx4 v[208:211], v[178:179], off offset:640
	global_load_dwordx4 v[212:215], v[180:181], off offset:640
	global_load_dwordx4 v[224:227], v[66:67], off offset:640
	global_load_dwordx4 v[228:231], v[70:71], off offset:640
	s_waitcnt lgkmcnt(0)
	v_mfma_f32_32x32x16_bf16 v[18:33], v[204:207], v[220:223], v[18:33]
	global_load_dwordx4 v[204:207], v[68:69], off offset:640
	global_load_dwordx4 v[232:235], v[72:73], off offset:640
	s_setprio 1
	s_waitcnt vmcnt(7)
	ds_write_b128 v189, v[196:199] offset:18432
	s_waitcnt vmcnt(6)
	ds_write_b128 v189, v[200:203] offset:23040
	s_waitcnt vmcnt(5)
	ds_write_b128 v189, v[208:211] offset:27648
	s_waitcnt vmcnt(4)
	ds_write_b128 v189, v[212:215] offset:32256
	s_waitcnt vmcnt(3)
	ds_write_b128 v189, v[224:227] offset:55296
	s_waitcnt vmcnt(2)
	ds_write_b128 v189, v[228:231] offset:59904
	s_waitcnt vmcnt(1)
	ds_write_b128 v189, v[204:207] offset:64512
	s_waitcnt vmcnt(0)
	ds_write_b128 v190, v[232:235] offset:32256
	v_mfma_f32_32x32x16_bf16 v[2:17], v[216:219], v[220:223], v[2:17]
	s_waitcnt lgkmcnt(0)
	s_barrier
	s_setprio 0
	ds_read_b128 v[196:199], v186 offset:18432
	ds_read_b128 v[200:203], v188 offset:55296
	ds_read_b128 v[204:207], v186 offset:18464
	ds_read_b128 v[208:211], v188 offset:55328
	ds_read_b128 v[212:215], v186 offset:23040
	ds_read_b128 v[216:219], v186 offset:23072
	s_waitcnt lgkmcnt(4)
	v_mfma_f32_32x32x16_bf16 v[50:65], v[196:199], v[200:203], v[50:65]
	s_waitcnt lgkmcnt(1)
	v_mfma_f32_32x32x16_bf16 v[34:49], v[212:215], v[200:203], v[34:49]
	ds_read_b128 v[200:203], v188 offset:59904
	ds_read_b128 v[220:223], v188 offset:59936
	s_waitcnt lgkmcnt(1)
	v_mfma_f32_32x32x16_bf16 v[18:33], v[196:199], v[200:203], v[18:33]
	v_mfma_f32_32x32x16_bf16 v[2:17], v[212:215], v[200:203], v[2:17]
	v_mfma_f32_32x32x16_bf16 v[50:65], v[204:207], v[208:211], v[50:65]
	v_mfma_f32_32x32x16_bf16 v[34:49], v[216:219], v[208:211], v[34:49]
	s_waitcnt lgkmcnt(0)
	v_mfma_f32_32x32x16_bf16 v[18:33], v[204:207], v[220:223], v[18:33]
	ds_read_b128 v[196:199], v186 offset:18496
	ds_read_b128 v[200:203], v188 offset:55360
	ds_read_b128 v[204:207], v186 offset:18528
	ds_read_b128 v[208:211], v188 offset:55392
	v_mfma_f32_32x32x16_bf16 v[2:17], v[216:219], v[220:223], v[2:17]
	ds_read_b128 v[212:215], v186 offset:23104
	ds_read_b128 v[216:219], v186 offset:23136
	s_waitcnt lgkmcnt(4)
	v_mfma_f32_32x32x16_bf16 v[50:65], v[196:199], v[200:203], v[50:65]
	s_waitcnt lgkmcnt(1)
	v_mfma_f32_32x32x16_bf16 v[34:49], v[212:215], v[200:203], v[34:49]
	ds_read_b128 v[200:203], v188 offset:59968
	ds_read_b128 v[220:223], v188 offset:60000
	s_waitcnt lgkmcnt(1)
	v_mfma_f32_32x32x16_bf16 v[18:33], v[196:199], v[200:203], v[18:33]
	v_mfma_f32_32x32x16_bf16 v[2:17], v[212:215], v[200:203], v[2:17]
	v_mfma_f32_32x32x16_bf16 v[50:65], v[204:207], v[208:211], v[50:65]
	v_mfma_f32_32x32x16_bf16 v[34:49], v[216:219], v[208:211], v[34:49]
	global_load_dwordx4 v[196:199], v[174:175], off offset:768
	global_load_dwordx4 v[200:203], v[176:177], off offset:768
	global_load_dwordx4 v[208:211], v[178:179], off offset:768
	global_load_dwordx4 v[212:215], v[180:181], off offset:768
	global_load_dwordx4 v[224:227], v[66:67], off offset:768
	global_load_dwordx4 v[228:231], v[70:71], off offset:768
	s_waitcnt lgkmcnt(0)
	v_mfma_f32_32x32x16_bf16 v[18:33], v[204:207], v[220:223], v[18:33]
	global_load_dwordx4 v[204:207], v[68:69], off offset:768
	global_load_dwordx4 v[232:235], v[72:73], off offset:768
	s_setprio 1
	s_waitcnt vmcnt(7)
	ds_write_b128 v189, v[196:199]
	s_waitcnt vmcnt(6)
	ds_write_b128 v189, v[200:203] offset:4608
	s_waitcnt vmcnt(5)
	ds_write_b128 v189, v[208:211] offset:9216
	s_waitcnt vmcnt(4)
	ds_write_b128 v189, v[212:215] offset:13824
	s_waitcnt vmcnt(3)
	ds_write_b128 v189, v[224:227] offset:36864
	s_waitcnt vmcnt(2)
	ds_write_b128 v189, v[228:231] offset:41472
	s_waitcnt vmcnt(1)
	ds_write_b128 v189, v[204:207] offset:46080
	s_waitcnt vmcnt(0)
	ds_write_b128 v189, v[232:235] offset:50688
	v_mfma_f32_32x32x16_bf16 v[2:17], v[216:219], v[220:223], v[2:17]
	s_waitcnt lgkmcnt(0)
	s_barrier
	s_setprio 0
	ds_read_b128 v[196:199], v186
	ds_read_b128 v[200:203], v188 offset:36864
	ds_read_b128 v[204:207], v186 offset:32
	ds_read_b128 v[208:211], v188 offset:36896
	ds_read_b128 v[212:215], v186 offset:4608
	ds_read_b128 v[216:219], v186 offset:4640
	s_waitcnt lgkmcnt(4)
	v_mfma_f32_32x32x16_bf16 v[50:65], v[196:199], v[200:203], v[50:65]
	s_waitcnt lgkmcnt(1)
	v_mfma_f32_32x32x16_bf16 v[34:49], v[212:215], v[200:203], v[34:49]
	ds_read_b128 v[200:203], v188 offset:41472
	ds_read_b128 v[220:223], v188 offset:41504
	s_waitcnt lgkmcnt(1)
	v_mfma_f32_32x32x16_bf16 v[18:33], v[196:199], v[200:203], v[18:33]
	v_mfma_f32_32x32x16_bf16 v[2:17], v[212:215], v[200:203], v[2:17]
	v_mfma_f32_32x32x16_bf16 v[50:65], v[204:207], v[208:211], v[50:65]
	v_mfma_f32_32x32x16_bf16 v[34:49], v[216:219], v[208:211], v[34:49]
	s_waitcnt lgkmcnt(0)
	v_mfma_f32_32x32x16_bf16 v[18:33], v[204:207], v[220:223], v[18:33]
	ds_read_b128 v[196:199], v186 offset:64
	ds_read_b128 v[200:203], v188 offset:36928
	ds_read_b128 v[204:207], v186 offset:96
	ds_read_b128 v[208:211], v188 offset:36960
	v_mfma_f32_32x32x16_bf16 v[2:17], v[216:219], v[220:223], v[2:17]
	ds_read_b128 v[212:215], v186 offset:4672
	ds_read_b128 v[216:219], v186 offset:4704
	s_waitcnt lgkmcnt(4)
	v_mfma_f32_32x32x16_bf16 v[50:65], v[196:199], v[200:203], v[50:65]
	s_waitcnt lgkmcnt(1)
	v_mfma_f32_32x32x16_bf16 v[34:49], v[212:215], v[200:203], v[34:49]
	ds_read_b128 v[200:203], v188 offset:41536
	ds_read_b128 v[220:223], v188 offset:41568
	s_waitcnt lgkmcnt(1)
	v_mfma_f32_32x32x16_bf16 v[18:33], v[196:199], v[200:203], v[18:33]
	v_mfma_f32_32x32x16_bf16 v[2:17], v[212:215], v[200:203], v[2:17]
	v_mfma_f32_32x32x16_bf16 v[50:65], v[204:207], v[208:211], v[50:65]
	v_mfma_f32_32x32x16_bf16 v[34:49], v[216:219], v[208:211], v[34:49]
	global_load_dwordx4 v[196:199], v[174:175], off offset:896
	s_nop 0
	global_load_dwordx4 v[174:177], v[176:177], off offset:896
	s_nop 0
	global_load_dwordx4 v[200:203], v[178:179], off offset:896
	s_nop 0
	global_load_dwordx4 v[178:181], v[180:181], off offset:896
	s_nop 0
	global_load_dwordx4 v[208:211], v[66:67], off offset:896
	global_load_dwordx4 v[212:215], v[70:71], off offset:896
	s_nop 0
	global_load_dwordx4 v[66:69], v[68:69], off offset:896
	s_nop 0
	global_load_dwordx4 v[70:73], v[72:73], off offset:896
	s_setprio 1
	s_waitcnt vmcnt(7)
	ds_write_b128 v189, v[196:199] offset:18432
	s_waitcnt vmcnt(6)
	ds_write_b128 v189, v[174:177] offset:23040
	s_waitcnt vmcnt(5)
	ds_write_b128 v189, v[200:203] offset:27648
	s_waitcnt vmcnt(4)
	ds_write_b128 v189, v[178:181] offset:32256
	s_waitcnt vmcnt(3)
	ds_write_b128 v189, v[208:211] offset:55296
	s_waitcnt vmcnt(2)
	ds_write_b128 v189, v[212:215] offset:59904
	s_waitcnt vmcnt(1)
	ds_write_b128 v189, v[66:69] offset:64512
	s_waitcnt vmcnt(0)
	ds_write_b128 v190, v[70:73] offset:32256
	s_waitcnt lgkmcnt(8)
	v_mfma_f32_32x32x16_bf16 v[18:33], v[204:207], v[220:223], v[18:33]
	s_waitcnt lgkmcnt(0)
	s_barrier
	s_setprio 0
	ds_read_b128 v[66:69], v186 offset:18432
	ds_read_b128 v[70:73], v188 offset:55296
	ds_read_b128 v[174:177], v186 offset:18464
	ds_read_b128 v[178:181], v188 offset:55328
	ds_read_b128 v[196:199], v186 offset:23040
	ds_read_b128 v[200:203], v186 offset:23072
	v_mfma_f32_32x32x16_bf16 v[2:17], v[216:219], v[220:223], v[2:17]
	s_waitcnt lgkmcnt(4)
	v_mfma_f32_32x32x16_bf16 v[50:65], v[66:69], v[70:73], v[50:65]
	s_waitcnt lgkmcnt(1)
	v_mfma_f32_32x32x16_bf16 v[34:49], v[196:199], v[70:73], v[34:49]
	ds_read_b128 v[70:73], v188 offset:59904
	ds_read_b128 v[204:207], v188 offset:59936
	s_waitcnt lgkmcnt(1)
	v_mfma_f32_32x32x16_bf16 v[18:33], v[66:69], v[70:73], v[18:33]
	v_mfma_f32_32x32x16_bf16 v[2:17], v[196:199], v[70:73], v[2:17]
	v_mfma_f32_32x32x16_bf16 v[50:65], v[174:177], v[178:181], v[50:65]
	v_mfma_f32_32x32x16_bf16 v[34:49], v[200:203], v[178:181], v[34:49]
	s_waitcnt lgkmcnt(0)
	v_mfma_f32_32x32x16_bf16 v[18:33], v[174:177], v[204:207], v[18:33]
	ds_read_b128 v[66:69], v186 offset:18496
	ds_read_b128 v[70:73], v188 offset:55360
	ds_read_b128 v[174:177], v186 offset:18528
	ds_read_b128 v[178:181], v188 offset:55392
	v_mfma_f32_32x32x16_bf16 v[2:17], v[200:203], v[204:207], v[2:17]
	ds_read_b128 v[196:199], v186 offset:23104
	ds_read_b128 v[200:203], v186 offset:23136
	s_waitcnt lgkmcnt(4)
	v_mfma_f32_32x32x16_bf16 v[50:65], v[66:69], v[70:73], v[50:65]
	s_waitcnt lgkmcnt(1)
	v_mfma_f32_32x32x16_bf16 v[34:49], v[196:199], v[70:73], v[34:49]
	ds_read_b128 v[70:73], v188 offset:59968
	ds_read_b128 v[204:207], v188 offset:60000
	s_waitcnt lgkmcnt(0)
	s_barrier
	v_mfma_f32_32x32x16_bf16 v[18:33], v[66:69], v[70:73], v[18:33]
	v_mfma_f32_32x32x16_bf16 v[2:17], v[196:199], v[70:73], v[2:17]
	v_mfma_f32_32x32x16_bf16 v[50:65], v[174:177], v[178:181], v[50:65]
	v_mfma_f32_32x32x16_bf16 v[34:49], v[200:203], v[178:181], v[34:49]
	v_mfma_f32_32x32x16_bf16 v[18:33], v[174:177], v[204:207], v[18:33]
	v_mfma_f32_32x32x16_bf16 v[2:17], v[200:203], v[204:207], v[2:17]
	s_cbranch_scc1 .LBB0_1794
	s_cmp_lg_u32 s17, 1
	s_mov_b64 s[4:5], -1
	s_cbranch_scc0 .LBB0_1798
	s_mov_b64 s[4:5], 0

.LBB0_1871:
	s_lshr_b32 s0, s4, 2
	s_and_b32 s4, s4, 3
	s_or_b32 s4, s4, s8
	s_lshl_b32 s4, s4, 7
	v_or_b32_e32 v2, s4, v89
	v_lshlrev_b32_e32 v66, 11, v2
	s_add_i32 s0, s0, s9
	v_lshl_add_u64 v[72:73], v[68:69], 0, v[66:67]
	v_add_lshl_u32 v66, s4, v90, 11
	s_lshl_b32 s5, s0, 7
	v_lshl_add_u64 v[74:75], v[68:69], 0, v[66:67]
	v_add_lshl_u32 v66, s4, v91, 11
	v_lshl_add_u64 v[76:77], v[68:69], 0, v[66:67]
	v_add_lshl_u32 v66, s4, v92, 11
	v_or_b32_e32 v2, s5, v89
	v_lshl_add_u64 v[78:79], v[68:69], 0, v[66:67]
	v_lshlrev_b32_e32 v66, 11, v2
	v_lshl_add_u64 v[80:81], v[70:71], 0, v[66:67]
	v_add_lshl_u32 v66, s5, v90, 11
	v_lshl_add_u64 v[82:83], v[70:71], 0, v[66:67]
	v_add_lshl_u32 v66, s5, v91, 11
	v_lshl_add_u64 v[84:85], v[70:71], 0, v[66:67]
	v_add_lshl_u32 v66, s5, v92, 11
	v_lshl_add_u64 v[86:87], v[70:71], 0, v[66:67]
	global_load_dwordx4 v[2:5], v[72:73], off
	global_load_dwordx4 v[6:9], v[74:75], off
	global_load_dwordx4 v[10:13], v[76:77], off
	global_load_dwordx4 v[14:17], v[78:79], off
	global_load_dwordx4 v[18:21], v[80:81], off
	global_load_dwordx4 v[22:25], v[82:83], off
	global_load_dwordx4 v[26:29], v[84:85], off
	global_load_dwordx4 v[30:33], v[86:87], off
	global_load_dwordx4 v[98:101], v[72:73], off offset:128
	global_load_dwordx4 v[102:105], v[74:75], off offset:128
	global_load_dwordx4 v[106:109], v[76:77], off offset:128
	global_load_dwordx4 v[110:113], v[78:79], off offset:128
	global_load_dwordx4 v[114:117], v[80:81], off offset:128
	global_load_dwordx4 v[118:121], v[82:83], off offset:128
	global_load_dwordx4 v[122:125], v[84:85], off offset:128
	global_load_dwordx4 v[126:129], v[86:87], off offset:128
	s_setprio 1
	s_waitcnt vmcnt(15)
	ds_write_b128 v95, v[2:5]
	s_waitcnt vmcnt(14)
	ds_write_b128 v95, v[6:9] offset:4608
	s_waitcnt vmcnt(13)
	ds_write_b128 v95, v[10:13] offset:9216
	s_waitcnt vmcnt(12)
	ds_write_b128 v95, v[14:17] offset:13824
	s_waitcnt vmcnt(11)
	ds_write_b128 v95, v[18:21] offset:36864
	s_waitcnt vmcnt(10)
	ds_write_b128 v95, v[22:25] offset:41472
	s_waitcnt vmcnt(9)
	ds_write_b128 v95, v[26:29] offset:46080
	s_waitcnt vmcnt(8)
	ds_write_b128 v95, v[30:33] offset:50688
	s_waitcnt lgkmcnt(0)
	s_barrier
	s_setprio 0
	global_load_dwordx4 v[132:135], v[72:73], off offset:256
	global_load_dwordx4 v[136:139], v[74:75], off offset:256
	global_load_dwordx4 v[140:143], v[76:77], off offset:256
	global_load_dwordx4 v[144:147], v[78:79], off offset:256
	global_load_dwordx4 v[148:151], v[80:81], off offset:256
	global_load_dwordx4 v[152:155], v[82:83], off offset:256
	global_load_dwordx4 v[156:159], v[84:85], off offset:256
	global_load_dwordx4 v[160:163], v[86:87], off offset:256
	v_and_b32_e32 v246, 15, v1
	v_add_u32_e32 v246, 4, v246
	v_bfe_u32 v246, v246, 3, 1
	v_bfe_u32 v249, v1, 4, 2
	v_xor_b32_e32 v246, v246, v249
	v_bfe_u32 v249, v1, 5, 1
	v_sub_u32_e32 v246, v246, v249
	v_lshlrev_b32_e32 v246, 4, v246
	v_bfe_u32 v249, v1, 4, 1
	v_mul_u32_u24_e32 v249, 0x900, v249
	v_sub_u32_e32 v246, v246, v249
	v_add_u32_e32 v244, v246, v93
	v_add_u32_e32 v245, v246, v94
	ds_read_b128 v[212:215], v245 offset:36864
	ds_read_b128 v[196:199], v244
	ds_read_b128 v[216:219], v245 offset:39168
	ds_read_b128 v[220:223], v245 offset:41472
	ds_read_b128 v[224:227], v245 offset:43776
	ds_read_b128 v[200:203], v244 offset:2304
	ds_read_b128 v[204:207], v244 offset:4608
	ds_read_b128 v[208:211], v244 offset:6912
	s_waitcnt lgkmcnt(6)
	v_mfma_f32_16x16x32_bf16 v[34:37], v[196:199], v[212:215], 0
	ds_read_b128 v[228:231], v245 offset:36928
	s_waitcnt lgkmcnt(6)
	v_mfma_f32_16x16x32_bf16 v[38:41], v[196:199], v[216:219], 0
	ds_read_b128 v[232:235], v245 offset:39232
	s_waitcnt lgkmcnt(6)
	v_mfma_f32_16x16x32_bf16 v[2:5], v[196:199], v[220:223], 0
	ds_read_b128 v[236:239], v245 offset:41536
	s_waitcnt lgkmcnt(6)
	v_mfma_f32_16x16x32_bf16 v[6:9], v[196:199], v[224:227], 0
	ds_read_b128 v[240:243], v245 offset:43840
	ds_read_b128 v[196:199], v244 offset:64
	s_waitcnt lgkmcnt(7)
	v_mfma_f32_16x16x32_bf16 v[42:45], v[200:203], v[212:215], 0
	v_mfma_f32_16x16x32_bf16 v[46:49], v[200:203], v[216:219], 0
	v_mfma_f32_16x16x32_bf16 v[10:13], v[200:203], v[220:223], 0
	v_mfma_f32_16x16x32_bf16 v[14:17], v[200:203], v[224:227], 0
	ds_read_b128 v[200:203], v244 offset:2368
	s_waitcnt lgkmcnt(7)
	v_mfma_f32_16x16x32_bf16 v[50:53], v[204:207], v[212:215], 0
	v_mfma_f32_16x16x32_bf16 v[54:57], v[204:207], v[216:219], 0
	v_mfma_f32_16x16x32_bf16 v[18:21], v[204:207], v[220:223], 0
	v_mfma_f32_16x16x32_bf16 v[22:25], v[204:207], v[224:227], 0
	ds_read_b128 v[204:207], v244 offset:4672
	s_setprio 1
	s_waitcnt vmcnt(15)
	ds_write_b128 v95, v[98:101] offset:18432
	s_waitcnt vmcnt(14)
	ds_write_b128 v95, v[102:105] offset:23040
	s_waitcnt lgkmcnt(9)
	v_mfma_f32_16x16x32_bf16 v[58:61], v[208:211], v[212:215], 0
	v_mfma_f32_16x16x32_bf16 v[62:65], v[208:211], v[216:219], 0
	v_mfma_f32_16x16x32_bf16 v[26:29], v[208:211], v[220:223], 0
	v_mfma_f32_16x16x32_bf16 v[30:33], v[208:211], v[224:227], 0
	ds_read_b128 v[208:211], v244 offset:6976
	s_waitcnt vmcnt(13)
	ds_write_b128 v95, v[106:109] offset:27648
	s_waitcnt vmcnt(12)
	ds_write_b128 v95, v[110:113] offset:32256
	s_waitcnt lgkmcnt(7)
	v_mfma_f32_16x16x32_bf16 v[34:37], v[196:199], v[228:231], v[34:37]
	v_mfma_f32_16x16x32_bf16 v[38:41], v[196:199], v[232:235], v[38:41]
	v_mfma_f32_16x16x32_bf16 v[2:5], v[196:199], v[236:239], v[2:5]
	v_mfma_f32_16x16x32_bf16 v[6:9], v[196:199], v[240:243], v[6:9]
	s_waitcnt vmcnt(11)
	ds_write_b128 v95, v[114:117] offset:55296
	s_waitcnt vmcnt(10)
	ds_write_b128 v95, v[118:121] offset:59904
	s_waitcnt lgkmcnt(8)
	v_mfma_f32_16x16x32_bf16 v[42:45], v[200:203], v[228:231], v[42:45]
	v_mfma_f32_16x16x32_bf16 v[46:49], v[200:203], v[232:235], v[46:49]
	v_mfma_f32_16x16x32_bf16 v[10:13], v[200:203], v[236:239], v[10:13]
	v_mfma_f32_16x16x32_bf16 v[14:17], v[200:203], v[240:243], v[14:17]
	s_waitcnt vmcnt(9)
	ds_write_b128 v95, v[122:125] offset:64512
	s_waitcnt vmcnt(8)
	ds_write_b128 v96, v[126:129] offset:32256
	s_waitcnt lgkmcnt(0)
	s_barrier
	s_setprio 0
	ds_read_b128 v[212:215], v245 offset:55296
	ds_read_b128 v[196:199], v244 offset:18432
	ds_read_b128 v[216:219], v245 offset:57600
	ds_read_b128 v[220:223], v245 offset:59904
	ds_read_b128 v[224:227], v245 offset:62208
	ds_read_b128 v[200:203], v244 offset:20736
	v_mfma_f32_16x16x32_bf16 v[50:53], v[204:207], v[228:231], v[50:53]
	v_mfma_f32_16x16x32_bf16 v[54:57], v[204:207], v[232:235], v[54:57]
	v_mfma_f32_16x16x32_bf16 v[18:21], v[204:207], v[236:239], v[18:21]
	v_mfma_f32_16x16x32_bf16 v[22:25], v[204:207], v[240:243], v[22:25]
	ds_read_b128 v[204:207], v244 offset:23040
	v_mfma_f32_16x16x32_bf16 v[58:61], v[208:211], v[228:231], v[58:61]
	v_mfma_f32_16x16x32_bf16 v[62:65], v[208:211], v[232:235], v[62:65]
	v_mfma_f32_16x16x32_bf16 v[26:29], v[208:211], v[236:239], v[26:29]
	v_mfma_f32_16x16x32_bf16 v[30:33], v[208:211], v[240:243], v[30:33]
	ds_read_b128 v[208:211], v244 offset:25344
	global_load_dwordx4 v[98:101], v[72:73], off offset:384
	global_load_dwordx4 v[102:105], v[74:75], off offset:384
	global_load_dwordx4 v[106:109], v[76:77], off offset:384
	global_load_dwordx4 v[110:113], v[78:79], off offset:384
	global_load_dwordx4 v[114:117], v[80:81], off offset:384
	global_load_dwordx4 v[118:121], v[82:83], off offset:384
	global_load_dwordx4 v[122:125], v[84:85], off offset:384
	global_load_dwordx4 v[126:129], v[86:87], off offset:384
	s_waitcnt lgkmcnt(6)
	v_mfma_f32_16x16x32_bf16 v[34:37], v[196:199], v[212:215], v[34:37]
	ds_read_b128 v[228:231], v245 offset:55360
	s_waitcnt lgkmcnt(6)
	v_mfma_f32_16x16x32_bf16 v[38:41], v[196:199], v[216:219], v[38:41]
	ds_read_b128 v[232:235], v245 offset:57664
	s_waitcnt lgkmcnt(6)
	v_mfma_f32_16x16x32_bf16 v[2:5], v[196:199], v[220:223], v[2:5]
	ds_read_b128 v[236:239], v245 offset:59968
	s_waitcnt lgkmcnt(6)
	v_mfma_f32_16x16x32_bf16 v[6:9], v[196:199], v[224:227], v[6:9]
	ds_read_b128 v[240:243], v245 offset:62272
	ds_read_b128 v[196:199], v244 offset:18496
	s_waitcnt lgkmcnt(7)
	v_mfma_f32_16x16x32_bf16 v[42:45], v[200:203], v[212:215], v[42:45]
	v_mfma_f32_16x16x32_bf16 v[46:49], v[200:203], v[216:219], v[46:49]
	v_mfma_f32_16x16x32_bf16 v[10:13], v[200:203], v[220:223], v[10:13]
	v_mfma_f32_16x16x32_bf16 v[14:17], v[200:203], v[224:227], v[14:17]
	ds_read_b128 v[200:203], v244 offset:20800
	s_waitcnt lgkmcnt(7)
	v_mfma_f32_16x16x32_bf16 v[50:53], v[204:207], v[212:215], v[50:53]
	v_mfma_f32_16x16x32_bf16 v[54:57], v[204:207], v[216:219], v[54:57]
	v_mfma_f32_16x16x32_bf16 v[18:21], v[204:207], v[220:223], v[18:21]
	v_mfma_f32_16x16x32_bf16 v[22:25], v[204:207], v[224:227], v[22:25]
	ds_read_b128 v[204:207], v244 offset:23104
	s_setprio 1
	s_waitcnt vmcnt(15)
	ds_write_b128 v95, v[132:135]
	s_waitcnt vmcnt(14)
	ds_write_b128 v95, v[136:139] offset:4608
	s_waitcnt lgkmcnt(9)
	v_mfma_f32_16x16x32_bf16 v[58:61], v[208:211], v[212:215], v[58:61]
	v_mfma_f32_16x16x32_bf16 v[62:65], v[208:211], v[216:219], v[62:65]
	v_mfma_f32_16x16x32_bf16 v[26:29], v[208:211], v[220:223], v[26:29]
	v_mfma_f32_16x16x32_bf16 v[30:33], v[208:211], v[224:227], v[30:33]
	ds_read_b128 v[208:211], v244 offset:25408
	s_waitcnt vmcnt(13)
	ds_write_b128 v95, v[140:143] offset:9216
	s_waitcnt vmcnt(12)
	ds_write_b128 v95, v[144:147] offset:13824
	s_waitcnt lgkmcnt(7)
	v_mfma_f32_16x16x32_bf16 v[34:37], v[196:199], v[228:231], v[34:37]
	v_mfma_f32_16x16x32_bf16 v[38:41], v[196:199], v[232:235], v[38:41]
	v_mfma_f32_16x16x32_bf16 v[2:5], v[196:199], v[236:239], v[2:5]
	v_mfma_f32_16x16x32_bf16 v[6:9], v[196:199], v[240:243], v[6:9]
	s_waitcnt vmcnt(11)
	ds_write_b128 v95, v[148:151] offset:36864
	s_waitcnt vmcnt(10)
	ds_write_b128 v95, v[152:155] offset:41472
	s_waitcnt lgkmcnt(8)
	v_mfma_f32_16x16x32_bf16 v[42:45], v[200:203], v[228:231], v[42:45]
	v_mfma_f32_16x16x32_bf16 v[46:49], v[200:203], v[232:235], v[46:49]
	v_mfma_f32_16x16x32_bf16 v[10:13], v[200:203], v[236:239], v[10:13]
	v_mfma_f32_16x16x32_bf16 v[14:17], v[200:203], v[240:243], v[14:17]
	s_waitcnt vmcnt(9)
	ds_write_b128 v95, v[156:159] offset:46080
	s_waitcnt vmcnt(8)
	ds_write_b128 v95, v[160:163] offset:50688
	s_waitcnt lgkmcnt(0)
	s_barrier
	s_setprio 0
	ds_read_b128 v[212:215], v245 offset:36864
	ds_read_b128 v[196:199], v244
	ds_read_b128 v[216:219], v245 offset:39168
	ds_read_b128 v[220:223], v245 offset:41472
	ds_read_b128 v[224:227], v245 offset:43776
	ds_read_b128 v[200:203], v244 offset:2304
	v_mfma_f32_16x16x32_bf16 v[50:53], v[204:207], v[228:231], v[50:53]
	v_mfma_f32_16x16x32_bf16 v[54:57], v[204:207], v[232:235], v[54:57]
	v_mfma_f32_16x16x32_bf16 v[18:21], v[204:207], v[236:239], v[18:21]
	v_mfma_f32_16x16x32_bf16 v[22:25], v[204:207], v[240:243], v[22:25]
	ds_read_b128 v[204:207], v244 offset:4608
	v_mfma_f32_16x16x32_bf16 v[58:61], v[208:211], v[228:231], v[58:61]
	v_mfma_f32_16x16x32_bf16 v[62:65], v[208:211], v[232:235], v[62:65]
	v_mfma_f32_16x16x32_bf16 v[26:29], v[208:211], v[236:239], v[26:29]
	v_mfma_f32_16x16x32_bf16 v[30:33], v[208:211], v[240:243], v[30:33]
	ds_read_b128 v[208:211], v244 offset:6912
	global_load_dwordx4 v[132:135], v[72:73], off offset:512
	global_load_dwordx4 v[136:139], v[74:75], off offset:512
	global_load_dwordx4 v[140:143], v[76:77], off offset:512
	global_load_dwordx4 v[144:147], v[78:79], off offset:512
	global_load_dwordx4 v[148:151], v[80:81], off offset:512
	global_load_dwordx4 v[152:155], v[82:83], off offset:512
	global_load_dwordx4 v[156:159], v[84:85], off offset:512
	global_load_dwordx4 v[160:163], v[86:87], off offset:512
	s_waitcnt lgkmcnt(6)
	v_mfma_f32_16x16x32_bf16 v[34:37], v[196:199], v[212:215], v[34:37]
	ds_read_b128 v[228:231], v245 offset:36928
	s_waitcnt lgkmcnt(6)
	v_mfma_f32_16x16x32_bf16 v[38:41], v[196:199], v[216:219], v[38:41]
	ds_read_b128 v[232:235], v245 offset:39232
	s_waitcnt lgkmcnt(6)
	v_mfma_f32_16x16x32_bf16 v[2:5], v[196:199], v[220:223], v[2:5]
	ds_read_b128 v[236:239], v245 offset:41536
	s_waitcnt lgkmcnt(6)
	v_mfma_f32_16x16x32_bf16 v[6:9], v[196:199], v[224:227], v[6:9]
	ds_read_b128 v[240:243], v245 offset:43840
	ds_read_b128 v[196:199], v244 offset:64
	s_waitcnt lgkmcnt(7)
	v_mfma_f32_16x16x32_bf16 v[42:45], v[200:203], v[212:215], v[42:45]
	v_mfma_f32_16x16x32_bf16 v[46:49], v[200:203], v[216:219], v[46:49]
	v_mfma_f32_16x16x32_bf16 v[10:13], v[200:203], v[220:223], v[10:13]
	v_mfma_f32_16x16x32_bf16 v[14:17], v[200:203], v[224:227], v[14:17]
	ds_read_b128 v[200:203], v244 offset:2368
	s_waitcnt lgkmcnt(7)
	v_mfma_f32_16x16x32_bf16 v[50:53], v[204:207], v[212:215], v[50:53]
	v_mfma_f32_16x16x32_bf16 v[54:57], v[204:207], v[216:219], v[54:57]
	v_mfma_f32_16x16x32_bf16 v[18:21], v[204:207], v[220:223], v[18:21]
	v_mfma_f32_16x16x32_bf16 v[22:25], v[204:207], v[224:227], v[22:25]
	ds_read_b128 v[204:207], v244 offset:4672
	s_setprio 1
	s_waitcnt vmcnt(15)
	ds_write_b128 v95, v[98:101] offset:18432
	s_waitcnt vmcnt(14)
	ds_write_b128 v95, v[102:105] offset:23040
	s_waitcnt lgkmcnt(9)
	v_mfma_f32_16x16x32_bf16 v[58:61], v[208:211], v[212:215], v[58:61]
	v_mfma_f32_16x16x32_bf16 v[62:65], v[208:211], v[216:219], v[62:65]
	v_mfma_f32_16x16x32_bf16 v[26:29], v[208:211], v[220:223], v[26:29]
	v_mfma_f32_16x16x32_bf16 v[30:33], v[208:211], v[224:227], v[30:33]
	ds_read_b128 v[208:211], v244 offset:6976
	s_waitcnt vmcnt(13)
	ds_write_b128 v95, v[106:109] offset:27648
	s_waitcnt vmcnt(12)
	ds_write_b128 v95, v[110:113] offset:32256
	s_waitcnt lgkmcnt(7)
	v_mfma_f32_16x16x32_bf16 v[34:37], v[196:199], v[228:231], v[34:37]
	v_mfma_f32_16x16x32_bf16 v[38:41], v[196:199], v[232:235], v[38:41]
	v_mfma_f32_16x16x32_bf16 v[2:5], v[196:199], v[236:239], v[2:5]
	v_mfma_f32_16x16x32_bf16 v[6:9], v[196:199], v[240:243], v[6:9]
	s_waitcnt vmcnt(11)
	ds_write_b128 v95, v[114:117] offset:55296
	s_waitcnt vmcnt(10)
	ds_write_b128 v95, v[118:121] offset:59904
	s_waitcnt lgkmcnt(8)
	v_mfma_f32_16x16x32_bf16 v[42:45], v[200:203], v[228:231], v[42:45]
	v_mfma_f32_16x16x32_bf16 v[46:49], v[200:203], v[232:235], v[46:49]
	v_mfma_f32_16x16x32_bf16 v[10:13], v[200:203], v[236:239], v[10:13]
	v_mfma_f32_16x16x32_bf16 v[14:17], v[200:203], v[240:243], v[14:17]
	s_waitcnt vmcnt(9)
	ds_write_b128 v95, v[122:125] offset:64512
	s_waitcnt vmcnt(8)
	ds_write_b128 v96, v[126:129] offset:32256
	s_waitcnt lgkmcnt(0)
	s_barrier
	s_setprio 0
	ds_read_b128 v[212:215], v245 offset:55296
	ds_read_b128 v[196:199], v244 offset:18432
	ds_read_b128 v[216:219], v245 offset:57600
	ds_read_b128 v[220:223], v245 offset:59904
	ds_read_b128 v[224:227], v245 offset:62208
	ds_read_b128 v[200:203], v244 offset:20736
	v_mfma_f32_16x16x32_bf16 v[50:53], v[204:207], v[228:231], v[50:53]
	v_mfma_f32_16x16x32_bf16 v[54:57], v[204:207], v[232:235], v[54:57]
	v_mfma_f32_16x16x32_bf16 v[18:21], v[204:207], v[236:239], v[18:21]
	v_mfma_f32_16x16x32_bf16 v[22:25], v[204:207], v[240:243], v[22:25]
	ds_read_b128 v[204:207], v244 offset:23040
	v_mfma_f32_16x16x32_bf16 v[58:61], v[208:211], v[228:231], v[58:61]
	v_mfma_f32_16x16x32_bf16 v[62:65], v[208:211], v[232:235], v[62:65]
	v_mfma_f32_16x16x32_bf16 v[26:29], v[208:211], v[236:239], v[26:29]
	v_mfma_f32_16x16x32_bf16 v[30:33], v[208:211], v[240:243], v[30:33]
	ds_read_b128 v[208:211], v244 offset:25344
	global_load_dwordx4 v[98:101], v[72:73], off offset:640
	global_load_dwordx4 v[102:105], v[74:75], off offset:640
	global_load_dwordx4 v[106:109], v[76:77], off offset:640
	global_load_dwordx4 v[110:113], v[78:79], off offset:640
	global_load_dwordx4 v[114:117], v[80:81], off offset:640
	global_load_dwordx4 v[118:121], v[82:83], off offset:640
	global_load_dwordx4 v[122:125], v[84:85], off offset:640
	global_load_dwordx4 v[126:129], v[86:87], off offset:640
	s_waitcnt lgkmcnt(6)
	v_mfma_f32_16x16x32_bf16 v[34:37], v[196:199], v[212:215], v[34:37]
	ds_read_b128 v[228:231], v245 offset:55360
	s_waitcnt lgkmcnt(6)
	v_mfma_f32_16x16x32_bf16 v[38:41], v[196:199], v[216:219], v[38:41]
	ds_read_b128 v[232:235], v245 offset:57664
	s_waitcnt lgkmcnt(6)
	v_mfma_f32_16x16x32_bf16 v[2:5], v[196:199], v[220:223], v[2:5]
	ds_read_b128 v[236:239], v245 offset:59968
	s_waitcnt lgkmcnt(6)
	v_mfma_f32_16x16x32_bf16 v[6:9], v[196:199], v[224:227], v[6:9]
	ds_read_b128 v[240:243], v245 offset:62272
	ds_read_b128 v[196:199], v244 offset:18496
	s_waitcnt lgkmcnt(7)
	v_mfma_f32_16x16x32_bf16 v[42:45], v[200:203], v[212:215], v[42:45]
	v_mfma_f32_16x16x32_bf16 v[46:49], v[200:203], v[216:219], v[46:49]
	v_mfma_f32_16x16x32_bf16 v[10:13], v[200:203], v[220:223], v[10:13]
	v_mfma_f32_16x16x32_bf16 v[14:17], v[200:203], v[224:227], v[14:17]
	ds_read_b128 v[200:203], v244 offset:20800
	s_waitcnt lgkmcnt(7)
	v_mfma_f32_16x16x32_bf16 v[50:53], v[204:207], v[212:215], v[50:53]
	v_mfma_f32_16x16x32_bf16 v[54:57], v[204:207], v[216:219], v[54:57]
	v_mfma_f32_16x16x32_bf16 v[18:21], v[204:207], v[220:223], v[18:21]
	v_mfma_f32_16x16x32_bf16 v[22:25], v[204:207], v[224:227], v[22:25]
	ds_read_b128 v[204:207], v244 offset:23104
	s_setprio 1
	s_waitcnt vmcnt(15)
	ds_write_b128 v95, v[132:135]
	s_waitcnt vmcnt(14)
	ds_write_b128 v95, v[136:139] offset:4608
	s_waitcnt lgkmcnt(9)
	v_mfma_f32_16x16x32_bf16 v[58:61], v[208:211], v[212:215], v[58:61]
	v_mfma_f32_16x16x32_bf16 v[62:65], v[208:211], v[216:219], v[62:65]
	v_mfma_f32_16x16x32_bf16 v[26:29], v[208:211], v[220:223], v[26:29]
	v_mfma_f32_16x16x32_bf16 v[30:33], v[208:211], v[224:227], v[30:33]
	ds_read_b128 v[208:211], v244 offset:25408
	s_waitcnt vmcnt(13)
	ds_write_b128 v95, v[140:143] offset:9216
	s_waitcnt vmcnt(12)
	ds_write_b128 v95, v[144:147] offset:13824
	s_waitcnt lgkmcnt(7)
	v_mfma_f32_16x16x32_bf16 v[34:37], v[196:199], v[228:231], v[34:37]
	v_mfma_f32_16x16x32_bf16 v[38:41], v[196:199], v[232:235], v[38:41]
	v_mfma_f32_16x16x32_bf16 v[2:5], v[196:199], v[236:239], v[2:5]
	v_mfma_f32_16x16x32_bf16 v[6:9], v[196:199], v[240:243], v[6:9]
	s_waitcnt vmcnt(11)
	ds_write_b128 v95, v[148:151] offset:36864
	s_waitcnt vmcnt(10)
	ds_write_b128 v95, v[152:155] offset:41472
	s_waitcnt lgkmcnt(8)
	v_mfma_f32_16x16x32_bf16 v[42:45], v[200:203], v[228:231], v[42:45]
	v_mfma_f32_16x16x32_bf16 v[46:49], v[200:203], v[232:235], v[46:49]
	v_mfma_f32_16x16x32_bf16 v[10:13], v[200:203], v[236:239], v[10:13]
	v_mfma_f32_16x16x32_bf16 v[14:17], v[200:203], v[240:243], v[14:17]
	s_waitcnt vmcnt(9)
	ds_write_b128 v95, v[156:159] offset:46080
	s_waitcnt vmcnt(8)
	ds_write_b128 v95, v[160:163] offset:50688
	s_waitcnt lgkmcnt(0)
	s_barrier
	s_setprio 0
	ds_read_b128 v[212:215], v245 offset:36864
	ds_read_b128 v[196:199], v244
	ds_read_b128 v[216:219], v245 offset:39168
	ds_read_b128 v[220:223], v245 offset:41472
	ds_read_b128 v[224:227], v245 offset:43776
	ds_read_b128 v[200:203], v244 offset:2304
	v_mfma_f32_16x16x32_bf16 v[50:53], v[204:207], v[228:231], v[50:53]
	v_mfma_f32_16x16x32_bf16 v[54:57], v[204:207], v[232:235], v[54:57]
	v_mfma_f32_16x16x32_bf16 v[18:21], v[204:207], v[236:239], v[18:21]
	v_mfma_f32_16x16x32_bf16 v[22:25], v[204:207], v[240:243], v[22:25]
	ds_read_b128 v[204:207], v244 offset:4608
	v_mfma_f32_16x16x32_bf16 v[58:61], v[208:211], v[228:231], v[58:61]
	v_mfma_f32_16x16x32_bf16 v[62:65], v[208:211], v[232:235], v[62:65]
	v_mfma_f32_16x16x32_bf16 v[26:29], v[208:211], v[236:239], v[26:29]
	v_mfma_f32_16x16x32_bf16 v[30:33], v[208:211], v[240:243], v[30:33]
	ds_read_b128 v[208:211], v244 offset:6912
	global_load_dwordx4 v[132:135], v[72:73], off offset:768
	global_load_dwordx4 v[136:139], v[74:75], off offset:768
	global_load_dwordx4 v[140:143], v[76:77], off offset:768
	global_load_dwordx4 v[144:147], v[78:79], off offset:768
	global_load_dwordx4 v[148:151], v[80:81], off offset:768
	global_load_dwordx4 v[152:155], v[82:83], off offset:768
	global_load_dwordx4 v[156:159], v[84:85], off offset:768
	global_load_dwordx4 v[160:163], v[86:87], off offset:768
	s_waitcnt lgkmcnt(6)
	v_mfma_f32_16x16x32_bf16 v[34:37], v[196:199], v[212:215], v[34:37]
	ds_read_b128 v[228:231], v245 offset:36928
	s_waitcnt lgkmcnt(6)
	v_mfma_f32_16x16x32_bf16 v[38:41], v[196:199], v[216:219], v[38:41]
	ds_read_b128 v[232:235], v245 offset:39232
	s_waitcnt lgkmcnt(6)
	v_mfma_f32_16x16x32_bf16 v[2:5], v[196:199], v[220:223], v[2:5]
	ds_read_b128 v[236:239], v245 offset:41536
	s_waitcnt lgkmcnt(6)
	v_mfma_f32_16x16x32_bf16 v[6:9], v[196:199], v[224:227], v[6:9]
	ds_read_b128 v[240:243], v245 offset:43840
	ds_read_b128 v[196:199], v244 offset:64
	s_waitcnt lgkmcnt(7)
	v_mfma_f32_16x16x32_bf16 v[42:45], v[200:203], v[212:215], v[42:45]
	v_mfma_f32_16x16x32_bf16 v[46:49], v[200:203], v[216:219], v[46:49]
	v_mfma_f32_16x16x32_bf16 v[10:13], v[200:203], v[220:223], v[10:13]
	v_mfma_f32_16x16x32_bf16 v[14:17], v[200:203], v[224:227], v[14:17]
	ds_read_b128 v[200:203], v244 offset:2368
	s_waitcnt lgkmcnt(7)
	v_mfma_f32_16x16x32_bf16 v[50:53], v[204:207], v[212:215], v[50:53]
	v_mfma_f32_16x16x32_bf16 v[54:57], v[204:207], v[216:219], v[54:57]
	v_mfma_f32_16x16x32_bf16 v[18:21], v[204:207], v[220:223], v[18:21]
	v_mfma_f32_16x16x32_bf16 v[22:25], v[204:207], v[224:227], v[22:25]
	ds_read_b128 v[204:207], v244 offset:4672
	s_setprio 1
	s_waitcnt vmcnt(15)
	ds_write_b128 v95, v[98:101] offset:18432
	s_waitcnt vmcnt(14)
	ds_write_b128 v95, v[102:105] offset:23040
	s_waitcnt lgkmcnt(9)
	v_mfma_f32_16x16x32_bf16 v[58:61], v[208:211], v[212:215], v[58:61]
	v_mfma_f32_16x16x32_bf16 v[62:65], v[208:211], v[216:219], v[62:65]
	v_mfma_f32_16x16x32_bf16 v[26:29], v[208:211], v[220:223], v[26:29]
	v_mfma_f32_16x16x32_bf16 v[30:33], v[208:211], v[224:227], v[30:33]
	ds_read_b128 v[208:211], v244 offset:6976
	s_waitcnt vmcnt(13)
	ds_write_b128 v95, v[106:109] offset:27648
	s_waitcnt vmcnt(12)
	ds_write_b128 v95, v[110:113] offset:32256
	s_waitcnt lgkmcnt(7)
	v_mfma_f32_16x16x32_bf16 v[34:37], v[196:199], v[228:231], v[34:37]
	v_mfma_f32_16x16x32_bf16 v[38:41], v[196:199], v[232:235], v[38:41]
	v_mfma_f32_16x16x32_bf16 v[2:5], v[196:199], v[236:239], v[2:5]
	v_mfma_f32_16x16x32_bf16 v[6:9], v[196:199], v[240:243], v[6:9]
	s_waitcnt vmcnt(11)
	ds_write_b128 v95, v[114:117] offset:55296
	s_waitcnt vmcnt(10)
	ds_write_b128 v95, v[118:121] offset:59904
	s_waitcnt lgkmcnt(8)
	v_mfma_f32_16x16x32_bf16 v[42:45], v[200:203], v[228:231], v[42:45]
	v_mfma_f32_16x16x32_bf16 v[46:49], v[200:203], v[232:235], v[46:49]
	v_mfma_f32_16x16x32_bf16 v[10:13], v[200:203], v[236:239], v[10:13]
	v_mfma_f32_16x16x32_bf16 v[14:17], v[200:203], v[240:243], v[14:17]
	s_waitcnt vmcnt(9)
	ds_write_b128 v95, v[122:125] offset:64512
	s_waitcnt vmcnt(8)
	ds_write_b128 v96, v[126:129] offset:32256
	s_waitcnt lgkmcnt(0)
	s_barrier
	s_setprio 0
	ds_read_b128 v[212:215], v245 offset:55296
	ds_read_b128 v[196:199], v244 offset:18432
	ds_read_b128 v[216:219], v245 offset:57600
	ds_read_b128 v[220:223], v245 offset:59904
	ds_read_b128 v[224:227], v245 offset:62208
	ds_read_b128 v[200:203], v244 offset:20736
	v_mfma_f32_16x16x32_bf16 v[50:53], v[204:207], v[228:231], v[50:53]
	v_mfma_f32_16x16x32_bf16 v[54:57], v[204:207], v[232:235], v[54:57]
	v_mfma_f32_16x16x32_bf16 v[18:21], v[204:207], v[236:239], v[18:21]
	v_mfma_f32_16x16x32_bf16 v[22:25], v[204:207], v[240:243], v[22:25]
	ds_read_b128 v[204:207], v244 offset:23040
	v_mfma_f32_16x16x32_bf16 v[58:61], v[208:211], v[228:231], v[58:61]
	v_mfma_f32_16x16x32_bf16 v[62:65], v[208:211], v[232:235], v[62:65]
	v_mfma_f32_16x16x32_bf16 v[26:29], v[208:211], v[236:239], v[26:29]
	v_mfma_f32_16x16x32_bf16 v[30:33], v[208:211], v[240:243], v[30:33]
	ds_read_b128 v[208:211], v244 offset:25344
	global_load_dwordx4 v[98:101], v[72:73], off offset:896
	global_load_dwordx4 v[102:105], v[74:75], off offset:896
	global_load_dwordx4 v[106:109], v[76:77], off offset:896
	global_load_dwordx4 v[110:113], v[78:79], off offset:896
	global_load_dwordx4 v[114:117], v[80:81], off offset:896
	global_load_dwordx4 v[118:121], v[82:83], off offset:896
	global_load_dwordx4 v[122:125], v[84:85], off offset:896
	global_load_dwordx4 v[126:129], v[86:87], off offset:896
	s_waitcnt lgkmcnt(6)
	v_mfma_f32_16x16x32_bf16 v[34:37], v[196:199], v[212:215], v[34:37]
	ds_read_b128 v[228:231], v245 offset:55360
	s_waitcnt lgkmcnt(6)
	v_mfma_f32_16x16x32_bf16 v[38:41], v[196:199], v[216:219], v[38:41]
	ds_read_b128 v[232:235], v245 offset:57664
	s_waitcnt lgkmcnt(6)
	v_mfma_f32_16x16x32_bf16 v[2:5], v[196:199], v[220:223], v[2:5]
	ds_read_b128 v[236:239], v245 offset:59968
	s_waitcnt lgkmcnt(6)
	v_mfma_f32_16x16x32_bf16 v[6:9], v[196:199], v[224:227], v[6:9]
	ds_read_b128 v[240:243], v245 offset:62272
	ds_read_b128 v[196:199], v244 offset:18496
	s_waitcnt lgkmcnt(7)
	v_mfma_f32_16x16x32_bf16 v[42:45], v[200:203], v[212:215], v[42:45]
	v_mfma_f32_16x16x32_bf16 v[46:49], v[200:203], v[216:219], v[46:49]
	v_mfma_f32_16x16x32_bf16 v[10:13], v[200:203], v[220:223], v[10:13]
	v_mfma_f32_16x16x32_bf16 v[14:17], v[200:203], v[224:227], v[14:17]
	ds_read_b128 v[200:203], v244 offset:20800
	s_waitcnt lgkmcnt(7)
	v_mfma_f32_16x16x32_bf16 v[50:53], v[204:207], v[212:215], v[50:53]
	v_mfma_f32_16x16x32_bf16 v[54:57], v[204:207], v[216:219], v[54:57]
	v_mfma_f32_16x16x32_bf16 v[18:21], v[204:207], v[220:223], v[18:21]
	v_mfma_f32_16x16x32_bf16 v[22:25], v[204:207], v[224:227], v[22:25]
	ds_read_b128 v[204:207], v244 offset:23104
	s_setprio 1
	s_waitcnt vmcnt(15)
	ds_write_b128 v95, v[132:135]
	s_waitcnt vmcnt(14)
	ds_write_b128 v95, v[136:139] offset:4608
	s_waitcnt lgkmcnt(9)
	v_mfma_f32_16x16x32_bf16 v[58:61], v[208:211], v[212:215], v[58:61]
	v_mfma_f32_16x16x32_bf16 v[62:65], v[208:211], v[216:219], v[62:65]
	v_mfma_f32_16x16x32_bf16 v[26:29], v[208:211], v[220:223], v[26:29]
	v_mfma_f32_16x16x32_bf16 v[30:33], v[208:211], v[224:227], v[30:33]
	ds_read_b128 v[208:211], v244 offset:25408
	s_waitcnt vmcnt(13)
	ds_write_b128 v95, v[140:143] offset:9216
	s_waitcnt vmcnt(12)
	ds_write_b128 v95, v[144:147] offset:13824
	s_waitcnt lgkmcnt(7)
	v_mfma_f32_16x16x32_bf16 v[34:37], v[196:199], v[228:231], v[34:37]
	v_mfma_f32_16x16x32_bf16 v[38:41], v[196:199], v[232:235], v[38:41]
	v_mfma_f32_16x16x32_bf16 v[2:5], v[196:199], v[236:239], v[2:5]
	v_mfma_f32_16x16x32_bf16 v[6:9], v[196:199], v[240:243], v[6:9]
	s_waitcnt vmcnt(11)
	ds_write_b128 v95, v[148:151] offset:36864
	s_waitcnt vmcnt(10)
	ds_write_b128 v95, v[152:155] offset:41472
	s_waitcnt lgkmcnt(8)
	v_mfma_f32_16x16x32_bf16 v[42:45], v[200:203], v[228:231], v[42:45]
	v_mfma_f32_16x16x32_bf16 v[46:49], v[200:203], v[232:235], v[46:49]
	v_mfma_f32_16x16x32_bf16 v[10:13], v[200:203], v[236:239], v[10:13]
	v_mfma_f32_16x16x32_bf16 v[14:17], v[200:203], v[240:243], v[14:17]
	s_waitcnt vmcnt(9)
	ds_write_b128 v95, v[156:159] offset:46080
	s_waitcnt vmcnt(8)
	ds_write_b128 v95, v[160:163] offset:50688
	s_waitcnt lgkmcnt(0)
	s_barrier
	s_setprio 0
	ds_read_b128 v[212:215], v245 offset:36864
	ds_read_b128 v[196:199], v244
	ds_read_b128 v[216:219], v245 offset:39168
	ds_read_b128 v[220:223], v245 offset:41472
	ds_read_b128 v[224:227], v245 offset:43776
	ds_read_b128 v[200:203], v244 offset:2304
	v_mfma_f32_16x16x32_bf16 v[50:53], v[204:207], v[228:231], v[50:53]
	v_mfma_f32_16x16x32_bf16 v[54:57], v[204:207], v[232:235], v[54:57]
	v_mfma_f32_16x16x32_bf16 v[18:21], v[204:207], v[236:239], v[18:21]
	v_mfma_f32_16x16x32_bf16 v[22:25], v[204:207], v[240:243], v[22:25]
	ds_read_b128 v[204:207], v244 offset:4608
	v_mfma_f32_16x16x32_bf16 v[58:61], v[208:211], v[228:231], v[58:61]
	v_mfma_f32_16x16x32_bf16 v[62:65], v[208:211], v[232:235], v[62:65]
	v_mfma_f32_16x16x32_bf16 v[26:29], v[208:211], v[236:239], v[26:29]
	v_mfma_f32_16x16x32_bf16 v[30:33], v[208:211], v[240:243], v[30:33]
	ds_read_b128 v[208:211], v244 offset:6912
	global_load_dwordx4 v[132:135], v[72:73], off offset:1024
	global_load_dwordx4 v[136:139], v[74:75], off offset:1024
	global_load_dwordx4 v[140:143], v[76:77], off offset:1024
	global_load_dwordx4 v[144:147], v[78:79], off offset:1024
	global_load_dwordx4 v[148:151], v[80:81], off offset:1024
	global_load_dwordx4 v[152:155], v[82:83], off offset:1024
	global_load_dwordx4 v[156:159], v[84:85], off offset:1024
	global_load_dwordx4 v[160:163], v[86:87], off offset:1024
	s_waitcnt lgkmcnt(6)
	v_mfma_f32_16x16x32_bf16 v[34:37], v[196:199], v[212:215], v[34:37]
	ds_read_b128 v[228:231], v245 offset:36928
	s_waitcnt lgkmcnt(6)
	v_mfma_f32_16x16x32_bf16 v[38:41], v[196:199], v[216:219], v[38:41]
	ds_read_b128 v[232:235], v245 offset:39232
	s_waitcnt lgkmcnt(6)
	v_mfma_f32_16x16x32_bf16 v[2:5], v[196:199], v[220:223], v[2:5]
	ds_read_b128 v[236:239], v245 offset:41536
	s_waitcnt lgkmcnt(6)
	v_mfma_f32_16x16x32_bf16 v[6:9], v[196:199], v[224:227], v[6:9]
	ds_read_b128 v[240:243], v245 offset:43840
	ds_read_b128 v[196:199], v244 offset:64
	s_waitcnt lgkmcnt(7)
	v_mfma_f32_16x16x32_bf16 v[42:45], v[200:203], v[212:215], v[42:45]
	v_mfma_f32_16x16x32_bf16 v[46:49], v[200:203], v[216:219], v[46:49]
	v_mfma_f32_16x16x32_bf16 v[10:13], v[200:203], v[220:223], v[10:13]
	v_mfma_f32_16x16x32_bf16 v[14:17], v[200:203], v[224:227], v[14:17]
	ds_read_b128 v[200:203], v244 offset:2368
	s_waitcnt lgkmcnt(7)
	v_mfma_f32_16x16x32_bf16 v[50:53], v[204:207], v[212:215], v[50:53]
	v_mfma_f32_16x16x32_bf16 v[54:57], v[204:207], v[216:219], v[54:57]
	v_mfma_f32_16x16x32_bf16 v[18:21], v[204:207], v[220:223], v[18:21]
	v_mfma_f32_16x16x32_bf16 v[22:25], v[204:207], v[224:227], v[22:25]
	ds_read_b128 v[204:207], v244 offset:4672
	s_setprio 1
	s_waitcnt vmcnt(15)
	ds_write_b128 v95, v[98:101] offset:18432
	s_waitcnt vmcnt(14)
	ds_write_b128 v95, v[102:105] offset:23040
	s_waitcnt lgkmcnt(9)
	v_mfma_f32_16x16x32_bf16 v[58:61], v[208:211], v[212:215], v[58:61]
	v_mfma_f32_16x16x32_bf16 v[62:65], v[208:211], v[216:219], v[62:65]
	v_mfma_f32_16x16x32_bf16 v[26:29], v[208:211], v[220:223], v[26:29]
	v_mfma_f32_16x16x32_bf16 v[30:33], v[208:211], v[224:227], v[30:33]
	ds_read_b128 v[208:211], v244 offset:6976
	s_waitcnt vmcnt(13)
	ds_write_b128 v95, v[106:109] offset:27648
	s_waitcnt vmcnt(12)
	ds_write_b128 v95, v[110:113] offset:32256
	s_waitcnt lgkmcnt(7)
	v_mfma_f32_16x16x32_bf16 v[34:37], v[196:199], v[228:231], v[34:37]
	v_mfma_f32_16x16x32_bf16 v[38:41], v[196:199], v[232:235], v[38:41]
	v_mfma_f32_16x16x32_bf16 v[2:5], v[196:199], v[236:239], v[2:5]
	v_mfma_f32_16x16x32_bf16 v[6:9], v[196:199], v[240:243], v[6:9]
	s_waitcnt vmcnt(11)
	ds_write_b128 v95, v[114:117] offset:55296
	s_waitcnt vmcnt(10)
	ds_write_b128 v95, v[118:121] offset:59904
	s_waitcnt lgkmcnt(8)
	v_mfma_f32_16x16x32_bf16 v[42:45], v[200:203], v[228:231], v[42:45]
	v_mfma_f32_16x16x32_bf16 v[46:49], v[200:203], v[232:235], v[46:49]
	v_mfma_f32_16x16x32_bf16 v[10:13], v[200:203], v[236:239], v[10:13]
	v_mfma_f32_16x16x32_bf16 v[14:17], v[200:203], v[240:243], v[14:17]
	s_waitcnt vmcnt(9)
	ds_write_b128 v95, v[122:125] offset:64512
	s_waitcnt vmcnt(8)
	ds_write_b128 v96, v[126:129] offset:32256
	s_waitcnt lgkmcnt(0)
	s_barrier
	s_setprio 0
	ds_read_b128 v[212:215], v245 offset:55296
	ds_read_b128 v[196:199], v244 offset:18432
	ds_read_b128 v[216:219], v245 offset:57600
	ds_read_b128 v[220:223], v245 offset:59904
	ds_read_b128 v[224:227], v245 offset:62208
	ds_read_b128 v[200:203], v244 offset:20736
	v_mfma_f32_16x16x32_bf16 v[50:53], v[204:207], v[228:231], v[50:53]
	v_mfma_f32_16x16x32_bf16 v[54:57], v[204:207], v[232:235], v[54:57]
	v_mfma_f32_16x16x32_bf16 v[18:21], v[204:207], v[236:239], v[18:21]
	v_mfma_f32_16x16x32_bf16 v[22:25], v[204:207], v[240:243], v[22:25]
	ds_read_b128 v[204:207], v244 offset:23040
	v_mfma_f32_16x16x32_bf16 v[58:61], v[208:211], v[228:231], v[58:61]
	v_mfma_f32_16x16x32_bf16 v[62:65], v[208:211], v[232:235], v[62:65]
	v_mfma_f32_16x16x32_bf16 v[26:29], v[208:211], v[236:239], v[26:29]
	v_mfma_f32_16x16x32_bf16 v[30:33], v[208:211], v[240:243], v[30:33]
	ds_read_b128 v[208:211], v244 offset:25344
	global_load_dwordx4 v[98:101], v[72:73], off offset:1152
	global_load_dwordx4 v[102:105], v[74:75], off offset:1152
	global_load_dwordx4 v[106:109], v[76:77], off offset:1152
	global_load_dwordx4 v[110:113], v[78:79], off offset:1152
	global_load_dwordx4 v[114:117], v[80:81], off offset:1152
	global_load_dwordx4 v[118:121], v[82:83], off offset:1152
	global_load_dwordx4 v[122:125], v[84:85], off offset:1152
	global_load_dwordx4 v[126:129], v[86:87], off offset:1152
	s_waitcnt lgkmcnt(6)
	v_mfma_f32_16x16x32_bf16 v[34:37], v[196:199], v[212:215], v[34:37]
	ds_read_b128 v[228:231], v245 offset:55360
	s_waitcnt lgkmcnt(6)
	v_mfma_f32_16x16x32_bf16 v[38:41], v[196:199], v[216:219], v[38:41]
	ds_read_b128 v[232:235], v245 offset:57664
	s_waitcnt lgkmcnt(6)
	v_mfma_f32_16x16x32_bf16 v[2:5], v[196:199], v[220:223], v[2:5]
	ds_read_b128 v[236:239], v245 offset:59968
	s_waitcnt lgkmcnt(6)
	v_mfma_f32_16x16x32_bf16 v[6:9], v[196:199], v[224:227], v[6:9]
	ds_read_b128 v[240:243], v245 offset:62272
	ds_read_b128 v[196:199], v244 offset:18496
	s_waitcnt lgkmcnt(7)
	v_mfma_f32_16x16x32_bf16 v[42:45], v[200:203], v[212:215], v[42:45]
	v_mfma_f32_16x16x32_bf16 v[46:49], v[200:203], v[216:219], v[46:49]
	v_mfma_f32_16x16x32_bf16 v[10:13], v[200:203], v[220:223], v[10:13]
	v_mfma_f32_16x16x32_bf16 v[14:17], v[200:203], v[224:227], v[14:17]
	ds_read_b128 v[200:203], v244 offset:20800
	s_waitcnt lgkmcnt(7)
	v_mfma_f32_16x16x32_bf16 v[50:53], v[204:207], v[212:215], v[50:53]
	v_mfma_f32_16x16x32_bf16 v[54:57], v[204:207], v[216:219], v[54:57]
	v_mfma_f32_16x16x32_bf16 v[18:21], v[204:207], v[220:223], v[18:21]
	v_mfma_f32_16x16x32_bf16 v[22:25], v[204:207], v[224:227], v[22:25]
	ds_read_b128 v[204:207], v244 offset:23104
	s_setprio 1
	s_waitcnt vmcnt(15)
	ds_write_b128 v95, v[132:135]
	s_waitcnt vmcnt(14)
	ds_write_b128 v95, v[136:139] offset:4608
	s_waitcnt lgkmcnt(9)
	v_mfma_f32_16x16x32_bf16 v[58:61], v[208:211], v[212:215], v[58:61]
	v_mfma_f32_16x16x32_bf16 v[62:65], v[208:211], v[216:219], v[62:65]
	v_mfma_f32_16x16x32_bf16 v[26:29], v[208:211], v[220:223], v[26:29]
	v_mfma_f32_16x16x32_bf16 v[30:33], v[208:211], v[224:227], v[30:33]
	ds_read_b128 v[208:211], v244 offset:25408
	s_waitcnt vmcnt(13)
	ds_write_b128 v95, v[140:143] offset:9216
	s_waitcnt vmcnt(12)
	ds_write_b128 v95, v[144:147] offset:13824
	s_waitcnt lgkmcnt(7)
	v_mfma_f32_16x16x32_bf16 v[34:37], v[196:199], v[228:231], v[34:37]
	v_mfma_f32_16x16x32_bf16 v[38:41], v[196:199], v[232:235], v[38:41]
	v_mfma_f32_16x16x32_bf16 v[2:5], v[196:199], v[236:239], v[2:5]
	v_mfma_f32_16x16x32_bf16 v[6:9], v[196:199], v[240:243], v[6:9]
	s_waitcnt vmcnt(11)
	ds_write_b128 v95, v[148:151] offset:36864
	s_waitcnt vmcnt(10)
	ds_write_b128 v95, v[152:155] offset:41472
	s_waitcnt lgkmcnt(8)
	v_mfma_f32_16x16x32_bf16 v[42:45], v[200:203], v[228:231], v[42:45]
	v_mfma_f32_16x16x32_bf16 v[46:49], v[200:203], v[232:235], v[46:49]
	v_mfma_f32_16x16x32_bf16 v[10:13], v[200:203], v[236:239], v[10:13]
	v_mfma_f32_16x16x32_bf16 v[14:17], v[200:203], v[240:243], v[14:17]
	s_waitcnt vmcnt(9)
	ds_write_b128 v95, v[156:159] offset:46080
	s_waitcnt vmcnt(8)
	ds_write_b128 v95, v[160:163] offset:50688
	s_waitcnt lgkmcnt(0)
	s_barrier
	s_setprio 0
	ds_read_b128 v[212:215], v245 offset:36864
	ds_read_b128 v[196:199], v244
	ds_read_b128 v[216:219], v245 offset:39168
	ds_read_b128 v[220:223], v245 offset:41472
	ds_read_b128 v[224:227], v245 offset:43776
	ds_read_b128 v[200:203], v244 offset:2304
	v_mfma_f32_16x16x32_bf16 v[50:53], v[204:207], v[228:231], v[50:53]
	v_mfma_f32_16x16x32_bf16 v[54:57], v[204:207], v[232:235], v[54:57]
	v_mfma_f32_16x16x32_bf16 v[18:21], v[204:207], v[236:239], v[18:21]
	v_mfma_f32_16x16x32_bf16 v[22:25], v[204:207], v[240:243], v[22:25]
	ds_read_b128 v[204:207], v244 offset:4608
	v_mfma_f32_16x16x32_bf16 v[58:61], v[208:211], v[228:231], v[58:61]
	v_mfma_f32_16x16x32_bf16 v[62:65], v[208:211], v[232:235], v[62:65]
	v_mfma_f32_16x16x32_bf16 v[26:29], v[208:211], v[236:239], v[26:29]
	v_mfma_f32_16x16x32_bf16 v[30:33], v[208:211], v[240:243], v[30:33]
	ds_read_b128 v[208:211], v244 offset:6912
	global_load_dwordx4 v[132:135], v[72:73], off offset:1280
	global_load_dwordx4 v[136:139], v[74:75], off offset:1280
	global_load_dwordx4 v[140:143], v[76:77], off offset:1280
	global_load_dwordx4 v[144:147], v[78:79], off offset:1280
	global_load_dwordx4 v[148:151], v[80:81], off offset:1280
	global_load_dwordx4 v[152:155], v[82:83], off offset:1280
	global_load_dwordx4 v[156:159], v[84:85], off offset:1280
	global_load_dwordx4 v[160:163], v[86:87], off offset:1280
	s_waitcnt lgkmcnt(6)
	v_mfma_f32_16x16x32_bf16 v[34:37], v[196:199], v[212:215], v[34:37]
	ds_read_b128 v[228:231], v245 offset:36928
	s_waitcnt lgkmcnt(6)
	v_mfma_f32_16x16x32_bf16 v[38:41], v[196:199], v[216:219], v[38:41]
	ds_read_b128 v[232:235], v245 offset:39232
	s_waitcnt lgkmcnt(6)
	v_mfma_f32_16x16x32_bf16 v[2:5], v[196:199], v[220:223], v[2:5]
	ds_read_b128 v[236:239], v245 offset:41536
	s_waitcnt lgkmcnt(6)
	v_mfma_f32_16x16x32_bf16 v[6:9], v[196:199], v[224:227], v[6:9]
	ds_read_b128 v[240:243], v245 offset:43840
	ds_read_b128 v[196:199], v244 offset:64
	s_waitcnt lgkmcnt(7)
	v_mfma_f32_16x16x32_bf16 v[42:45], v[200:203], v[212:215], v[42:45]
	v_mfma_f32_16x16x32_bf16 v[46:49], v[200:203], v[216:219], v[46:49]
	v_mfma_f32_16x16x32_bf16 v[10:13], v[200:203], v[220:223], v[10:13]
	v_mfma_f32_16x16x32_bf16 v[14:17], v[200:203], v[224:227], v[14:17]
	ds_read_b128 v[200:203], v244 offset:2368
	s_waitcnt lgkmcnt(7)
	v_mfma_f32_16x16x32_bf16 v[50:53], v[204:207], v[212:215], v[50:53]
	v_mfma_f32_16x16x32_bf16 v[54:57], v[204:207], v[216:219], v[54:57]
	v_mfma_f32_16x16x32_bf16 v[18:21], v[204:207], v[220:223], v[18:21]
	v_mfma_f32_16x16x32_bf16 v[22:25], v[204:207], v[224:227], v[22:25]
	ds_read_b128 v[204:207], v244 offset:4672
	s_setprio 1
	s_waitcnt vmcnt(15)
	ds_write_b128 v95, v[98:101] offset:18432
	s_waitcnt vmcnt(14)
	ds_write_b128 v95, v[102:105] offset:23040
	s_waitcnt lgkmcnt(9)
	v_mfma_f32_16x16x32_bf16 v[58:61], v[208:211], v[212:215], v[58:61]
	v_mfma_f32_16x16x32_bf16 v[62:65], v[208:211], v[216:219], v[62:65]
	v_mfma_f32_16x16x32_bf16 v[26:29], v[208:211], v[220:223], v[26:29]
	v_mfma_f32_16x16x32_bf16 v[30:33], v[208:211], v[224:227], v[30:33]
	ds_read_b128 v[208:211], v244 offset:6976
	s_waitcnt vmcnt(13)
	ds_write_b128 v95, v[106:109] offset:27648
	s_waitcnt vmcnt(12)
	ds_write_b128 v95, v[110:113] offset:32256
	s_waitcnt lgkmcnt(7)
	v_mfma_f32_16x16x32_bf16 v[34:37], v[196:199], v[228:231], v[34:37]
	v_mfma_f32_16x16x32_bf16 v[38:41], v[196:199], v[232:235], v[38:41]
	v_mfma_f32_16x16x32_bf16 v[2:5], v[196:199], v[236:239], v[2:5]
	v_mfma_f32_16x16x32_bf16 v[6:9], v[196:199], v[240:243], v[6:9]
	s_waitcnt vmcnt(11)
	ds_write_b128 v95, v[114:117] offset:55296
	s_waitcnt vmcnt(10)
	ds_write_b128 v95, v[118:121] offset:59904
	s_waitcnt lgkmcnt(8)
	v_mfma_f32_16x16x32_bf16 v[42:45], v[200:203], v[228:231], v[42:45]
	v_mfma_f32_16x16x32_bf16 v[46:49], v[200:203], v[232:235], v[46:49]
	v_mfma_f32_16x16x32_bf16 v[10:13], v[200:203], v[236:239], v[10:13]
	v_mfma_f32_16x16x32_bf16 v[14:17], v[200:203], v[240:243], v[14:17]
	s_waitcnt vmcnt(9)
	ds_write_b128 v95, v[122:125] offset:64512
	s_waitcnt vmcnt(8)
	ds_write_b128 v96, v[126:129] offset:32256
	s_waitcnt lgkmcnt(0)
	s_barrier
	s_setprio 0
	ds_read_b128 v[212:215], v245 offset:55296
	ds_read_b128 v[196:199], v244 offset:18432
	ds_read_b128 v[216:219], v245 offset:57600
	ds_read_b128 v[220:223], v245 offset:59904
	ds_read_b128 v[224:227], v245 offset:62208
	ds_read_b128 v[200:203], v244 offset:20736
	v_mfma_f32_16x16x32_bf16 v[50:53], v[204:207], v[228:231], v[50:53]
	v_mfma_f32_16x16x32_bf16 v[54:57], v[204:207], v[232:235], v[54:57]
	v_mfma_f32_16x16x32_bf16 v[18:21], v[204:207], v[236:239], v[18:21]
	v_mfma_f32_16x16x32_bf16 v[22:25], v[204:207], v[240:243], v[22:25]
	ds_read_b128 v[204:207], v244 offset:23040
	v_mfma_f32_16x16x32_bf16 v[58:61], v[208:211], v[228:231], v[58:61]
	v_mfma_f32_16x16x32_bf16 v[62:65], v[208:211], v[232:235], v[62:65]
	v_mfma_f32_16x16x32_bf16 v[26:29], v[208:211], v[236:239], v[26:29]
	v_mfma_f32_16x16x32_bf16 v[30:33], v[208:211], v[240:243], v[30:33]
	ds_read_b128 v[208:211], v244 offset:25344
	global_load_dwordx4 v[98:101], v[72:73], off offset:1408
	global_load_dwordx4 v[102:105], v[74:75], off offset:1408
	global_load_dwordx4 v[106:109], v[76:77], off offset:1408
	global_load_dwordx4 v[110:113], v[78:79], off offset:1408
	global_load_dwordx4 v[114:117], v[80:81], off offset:1408
	global_load_dwordx4 v[118:121], v[82:83], off offset:1408
	global_load_dwordx4 v[122:125], v[84:85], off offset:1408
	global_load_dwordx4 v[126:129], v[86:87], off offset:1408
	s_waitcnt lgkmcnt(6)
	v_mfma_f32_16x16x32_bf16 v[34:37], v[196:199], v[212:215], v[34:37]
	ds_read_b128 v[228:231], v245 offset:55360
	s_waitcnt lgkmcnt(6)
	v_mfma_f32_16x16x32_bf16 v[38:41], v[196:199], v[216:219], v[38:41]
	ds_read_b128 v[232:235], v245 offset:57664
	s_waitcnt lgkmcnt(6)
	v_mfma_f32_16x16x32_bf16 v[2:5], v[196:199], v[220:223], v[2:5]
	ds_read_b128 v[236:239], v245 offset:59968
	s_waitcnt lgkmcnt(6)
	v_mfma_f32_16x16x32_bf16 v[6:9], v[196:199], v[224:227], v[6:9]
	ds_read_b128 v[240:243], v245 offset:62272
	ds_read_b128 v[196:199], v244 offset:18496
	s_waitcnt lgkmcnt(7)
	v_mfma_f32_16x16x32_bf16 v[42:45], v[200:203], v[212:215], v[42:45]
	v_mfma_f32_16x16x32_bf16 v[46:49], v[200:203], v[216:219], v[46:49]
	v_mfma_f32_16x16x32_bf16 v[10:13], v[200:203], v[220:223], v[10:13]
	v_mfma_f32_16x16x32_bf16 v[14:17], v[200:203], v[224:227], v[14:17]
	ds_read_b128 v[200:203], v244 offset:20800
	s_waitcnt lgkmcnt(7)
	v_mfma_f32_16x16x32_bf16 v[50:53], v[204:207], v[212:215], v[50:53]
	v_mfma_f32_16x16x32_bf16 v[54:57], v[204:207], v[216:219], v[54:57]
	v_mfma_f32_16x16x32_bf16 v[18:21], v[204:207], v[220:223], v[18:21]
	v_mfma_f32_16x16x32_bf16 v[22:25], v[204:207], v[224:227], v[22:25]
	ds_read_b128 v[204:207], v244 offset:23104
	s_setprio 1
	s_waitcnt vmcnt(15)
	ds_write_b128 v95, v[132:135]
	s_waitcnt vmcnt(14)
	ds_write_b128 v95, v[136:139] offset:4608
	s_waitcnt lgkmcnt(9)
	v_mfma_f32_16x16x32_bf16 v[58:61], v[208:211], v[212:215], v[58:61]
	v_mfma_f32_16x16x32_bf16 v[62:65], v[208:211], v[216:219], v[62:65]
	v_mfma_f32_16x16x32_bf16 v[26:29], v[208:211], v[220:223], v[26:29]
	v_mfma_f32_16x16x32_bf16 v[30:33], v[208:211], v[224:227], v[30:33]
	ds_read_b128 v[208:211], v244 offset:25408
	s_waitcnt vmcnt(13)
	ds_write_b128 v95, v[140:143] offset:9216
	s_waitcnt vmcnt(12)
	ds_write_b128 v95, v[144:147] offset:13824
	s_waitcnt lgkmcnt(7)
	v_mfma_f32_16x16x32_bf16 v[34:37], v[196:199], v[228:231], v[34:37]
	v_mfma_f32_16x16x32_bf16 v[38:41], v[196:199], v[232:235], v[38:41]
	v_mfma_f32_16x16x32_bf16 v[2:5], v[196:199], v[236:239], v[2:5]
	v_mfma_f32_16x16x32_bf16 v[6:9], v[196:199], v[240:243], v[6:9]
	s_waitcnt vmcnt(11)
	ds_write_b128 v95, v[148:151] offset:36864
	s_waitcnt vmcnt(10)
	ds_write_b128 v95, v[152:155] offset:41472
	s_waitcnt lgkmcnt(8)
	v_mfma_f32_16x16x32_bf16 v[42:45], v[200:203], v[228:231], v[42:45]
	v_mfma_f32_16x16x32_bf16 v[46:49], v[200:203], v[232:235], v[46:49]
	v_mfma_f32_16x16x32_bf16 v[10:13], v[200:203], v[236:239], v[10:13]
	v_mfma_f32_16x16x32_bf16 v[14:17], v[200:203], v[240:243], v[14:17]
	s_waitcnt vmcnt(9)
	ds_write_b128 v95, v[156:159] offset:46080
	s_waitcnt vmcnt(8)
	ds_write_b128 v95, v[160:163] offset:50688
	s_waitcnt lgkmcnt(0)
	s_barrier
	s_setprio 0
	ds_read_b128 v[212:215], v245 offset:36864
	ds_read_b128 v[196:199], v244
	ds_read_b128 v[216:219], v245 offset:39168
	ds_read_b128 v[220:223], v245 offset:41472
	ds_read_b128 v[224:227], v245 offset:43776
	ds_read_b128 v[200:203], v244 offset:2304
	v_mfma_f32_16x16x32_bf16 v[50:53], v[204:207], v[228:231], v[50:53]
	v_mfma_f32_16x16x32_bf16 v[54:57], v[204:207], v[232:235], v[54:57]
	v_mfma_f32_16x16x32_bf16 v[18:21], v[204:207], v[236:239], v[18:21]
	v_mfma_f32_16x16x32_bf16 v[22:25], v[204:207], v[240:243], v[22:25]
	ds_read_b128 v[204:207], v244 offset:4608
	v_mfma_f32_16x16x32_bf16 v[58:61], v[208:211], v[228:231], v[58:61]
	v_mfma_f32_16x16x32_bf16 v[62:65], v[208:211], v[232:235], v[62:65]
	v_mfma_f32_16x16x32_bf16 v[26:29], v[208:211], v[236:239], v[26:29]
	v_mfma_f32_16x16x32_bf16 v[30:33], v[208:211], v[240:243], v[30:33]
	ds_read_b128 v[208:211], v244 offset:6912
	global_load_dwordx4 v[132:135], v[72:73], off offset:1536
	global_load_dwordx4 v[136:139], v[74:75], off offset:1536
	global_load_dwordx4 v[140:143], v[76:77], off offset:1536
	global_load_dwordx4 v[144:147], v[78:79], off offset:1536
	global_load_dwordx4 v[148:151], v[80:81], off offset:1536
	global_load_dwordx4 v[152:155], v[82:83], off offset:1536
	global_load_dwordx4 v[156:159], v[84:85], off offset:1536
	global_load_dwordx4 v[160:163], v[86:87], off offset:1536
	s_waitcnt lgkmcnt(6)
	v_mfma_f32_16x16x32_bf16 v[34:37], v[196:199], v[212:215], v[34:37]
	ds_read_b128 v[228:231], v245 offset:36928
	s_waitcnt lgkmcnt(6)
	v_mfma_f32_16x16x32_bf16 v[38:41], v[196:199], v[216:219], v[38:41]
	ds_read_b128 v[232:235], v245 offset:39232
	s_waitcnt lgkmcnt(6)
	v_mfma_f32_16x16x32_bf16 v[2:5], v[196:199], v[220:223], v[2:5]
	ds_read_b128 v[236:239], v245 offset:41536
	s_waitcnt lgkmcnt(6)
	v_mfma_f32_16x16x32_bf16 v[6:9], v[196:199], v[224:227], v[6:9]
	ds_read_b128 v[240:243], v245 offset:43840
	ds_read_b128 v[196:199], v244 offset:64
	s_waitcnt lgkmcnt(7)
	v_mfma_f32_16x16x32_bf16 v[42:45], v[200:203], v[212:215], v[42:45]
	v_mfma_f32_16x16x32_bf16 v[46:49], v[200:203], v[216:219], v[46:49]
	v_mfma_f32_16x16x32_bf16 v[10:13], v[200:203], v[220:223], v[10:13]
	v_mfma_f32_16x16x32_bf16 v[14:17], v[200:203], v[224:227], v[14:17]
	ds_read_b128 v[200:203], v244 offset:2368
	s_waitcnt lgkmcnt(7)
	v_mfma_f32_16x16x32_bf16 v[50:53], v[204:207], v[212:215], v[50:53]
	v_mfma_f32_16x16x32_bf16 v[54:57], v[204:207], v[216:219], v[54:57]
	v_mfma_f32_16x16x32_bf16 v[18:21], v[204:207], v[220:223], v[18:21]
	v_mfma_f32_16x16x32_bf16 v[22:25], v[204:207], v[224:227], v[22:25]
	ds_read_b128 v[204:207], v244 offset:4672
	s_setprio 1
	s_waitcnt vmcnt(15)
	ds_write_b128 v95, v[98:101] offset:18432
	s_waitcnt vmcnt(14)
	ds_write_b128 v95, v[102:105] offset:23040
	s_waitcnt lgkmcnt(9)
	v_mfma_f32_16x16x32_bf16 v[58:61], v[208:211], v[212:215], v[58:61]
	v_mfma_f32_16x16x32_bf16 v[62:65], v[208:211], v[216:219], v[62:65]
	v_mfma_f32_16x16x32_bf16 v[26:29], v[208:211], v[220:223], v[26:29]
	v_mfma_f32_16x16x32_bf16 v[30:33], v[208:211], v[224:227], v[30:33]
	ds_read_b128 v[208:211], v244 offset:6976
	s_waitcnt vmcnt(13)
	ds_write_b128 v95, v[106:109] offset:27648
	s_waitcnt vmcnt(12)
	ds_write_b128 v95, v[110:113] offset:32256
	s_waitcnt lgkmcnt(7)
	v_mfma_f32_16x16x32_bf16 v[34:37], v[196:199], v[228:231], v[34:37]
	v_mfma_f32_16x16x32_bf16 v[38:41], v[196:199], v[232:235], v[38:41]
	v_mfma_f32_16x16x32_bf16 v[2:5], v[196:199], v[236:239], v[2:5]
	v_mfma_f32_16x16x32_bf16 v[6:9], v[196:199], v[240:243], v[6:9]
	s_waitcnt vmcnt(11)
	ds_write_b128 v95, v[114:117] offset:55296
	s_waitcnt vmcnt(10)
	ds_write_b128 v95, v[118:121] offset:59904
	s_waitcnt lgkmcnt(8)
	v_mfma_f32_16x16x32_bf16 v[42:45], v[200:203], v[228:231], v[42:45]
	v_mfma_f32_16x16x32_bf16 v[46:49], v[200:203], v[232:235], v[46:49]
	v_mfma_f32_16x16x32_bf16 v[10:13], v[200:203], v[236:239], v[10:13]
	v_mfma_f32_16x16x32_bf16 v[14:17], v[200:203], v[240:243], v[14:17]
	s_waitcnt vmcnt(9)
	ds_write_b128 v95, v[122:125] offset:64512
	s_waitcnt vmcnt(8)
	ds_write_b128 v96, v[126:129] offset:32256
	s_waitcnt lgkmcnt(0)
	s_barrier
	s_setprio 0
	ds_read_b128 v[212:215], v245 offset:55296
	ds_read_b128 v[196:199], v244 offset:18432
	ds_read_b128 v[216:219], v245 offset:57600
	ds_read_b128 v[220:223], v245 offset:59904
	ds_read_b128 v[224:227], v245 offset:62208
	ds_read_b128 v[200:203], v244 offset:20736
	v_mfma_f32_16x16x32_bf16 v[50:53], v[204:207], v[228:231], v[50:53]
	v_mfma_f32_16x16x32_bf16 v[54:57], v[204:207], v[232:235], v[54:57]
	v_mfma_f32_16x16x32_bf16 v[18:21], v[204:207], v[236:239], v[18:21]
	v_mfma_f32_16x16x32_bf16 v[22:25], v[204:207], v[240:243], v[22:25]
	ds_read_b128 v[204:207], v244 offset:23040
	v_mfma_f32_16x16x32_bf16 v[58:61], v[208:211], v[228:231], v[58:61]
	v_mfma_f32_16x16x32_bf16 v[62:65], v[208:211], v[232:235], v[62:65]
	v_mfma_f32_16x16x32_bf16 v[26:29], v[208:211], v[236:239], v[26:29]
	v_mfma_f32_16x16x32_bf16 v[30:33], v[208:211], v[240:243], v[30:33]
	ds_read_b128 v[208:211], v244 offset:25344
	global_load_dwordx4 v[98:101], v[72:73], off offset:1664
	global_load_dwordx4 v[102:105], v[74:75], off offset:1664
	global_load_dwordx4 v[106:109], v[76:77], off offset:1664
	global_load_dwordx4 v[110:113], v[78:79], off offset:1664
	global_load_dwordx4 v[114:117], v[80:81], off offset:1664
	global_load_dwordx4 v[118:121], v[82:83], off offset:1664
	global_load_dwordx4 v[122:125], v[84:85], off offset:1664
	global_load_dwordx4 v[126:129], v[86:87], off offset:1664
	s_waitcnt lgkmcnt(6)
	v_mfma_f32_16x16x32_bf16 v[34:37], v[196:199], v[212:215], v[34:37]
	ds_read_b128 v[228:231], v245 offset:55360
	s_waitcnt lgkmcnt(6)
	v_mfma_f32_16x16x32_bf16 v[38:41], v[196:199], v[216:219], v[38:41]
	ds_read_b128 v[232:235], v245 offset:57664
	s_waitcnt lgkmcnt(6)
	v_mfma_f32_16x16x32_bf16 v[2:5], v[196:199], v[220:223], v[2:5]
	ds_read_b128 v[236:239], v245 offset:59968
	s_waitcnt lgkmcnt(6)
	v_mfma_f32_16x16x32_bf16 v[6:9], v[196:199], v[224:227], v[6:9]
	ds_read_b128 v[240:243], v245 offset:62272
	ds_read_b128 v[196:199], v244 offset:18496
	s_waitcnt lgkmcnt(7)
	v_mfma_f32_16x16x32_bf16 v[42:45], v[200:203], v[212:215], v[42:45]
	v_mfma_f32_16x16x32_bf16 v[46:49], v[200:203], v[216:219], v[46:49]
	v_mfma_f32_16x16x32_bf16 v[10:13], v[200:203], v[220:223], v[10:13]
	v_mfma_f32_16x16x32_bf16 v[14:17], v[200:203], v[224:227], v[14:17]
	ds_read_b128 v[200:203], v244 offset:20800
	s_waitcnt lgkmcnt(7)
	v_mfma_f32_16x16x32_bf16 v[50:53], v[204:207], v[212:215], v[50:53]
	v_mfma_f32_16x16x32_bf16 v[54:57], v[204:207], v[216:219], v[54:57]
	v_mfma_f32_16x16x32_bf16 v[18:21], v[204:207], v[220:223], v[18:21]
	v_mfma_f32_16x16x32_bf16 v[22:25], v[204:207], v[224:227], v[22:25]
	ds_read_b128 v[204:207], v244 offset:23104
	s_setprio 1
	s_waitcnt vmcnt(15)
	ds_write_b128 v95, v[132:135]
	s_waitcnt vmcnt(14)
	ds_write_b128 v95, v[136:139] offset:4608
	s_waitcnt lgkmcnt(9)
	v_mfma_f32_16x16x32_bf16 v[58:61], v[208:211], v[212:215], v[58:61]
	v_mfma_f32_16x16x32_bf16 v[62:65], v[208:211], v[216:219], v[62:65]
	v_mfma_f32_16x16x32_bf16 v[26:29], v[208:211], v[220:223], v[26:29]
	v_mfma_f32_16x16x32_bf16 v[30:33], v[208:211], v[224:227], v[30:33]
	ds_read_b128 v[208:211], v244 offset:25408
	s_waitcnt vmcnt(13)
	ds_write_b128 v95, v[140:143] offset:9216
	s_waitcnt vmcnt(12)
	ds_write_b128 v95, v[144:147] offset:13824
	s_waitcnt lgkmcnt(7)
	v_mfma_f32_16x16x32_bf16 v[34:37], v[196:199], v[228:231], v[34:37]
	v_mfma_f32_16x16x32_bf16 v[38:41], v[196:199], v[232:235], v[38:41]
	v_mfma_f32_16x16x32_bf16 v[2:5], v[196:199], v[236:239], v[2:5]
	v_mfma_f32_16x16x32_bf16 v[6:9], v[196:199], v[240:243], v[6:9]
	s_waitcnt vmcnt(11)
	ds_write_b128 v95, v[148:151] offset:36864
	s_waitcnt vmcnt(10)
	ds_write_b128 v95, v[152:155] offset:41472
	s_waitcnt lgkmcnt(8)
	v_mfma_f32_16x16x32_bf16 v[42:45], v[200:203], v[228:231], v[42:45]
	v_mfma_f32_16x16x32_bf16 v[46:49], v[200:203], v[232:235], v[46:49]
	v_mfma_f32_16x16x32_bf16 v[10:13], v[200:203], v[236:239], v[10:13]
	v_mfma_f32_16x16x32_bf16 v[14:17], v[200:203], v[240:243], v[14:17]
	s_waitcnt vmcnt(9)
	ds_write_b128 v95, v[156:159] offset:46080
	s_waitcnt vmcnt(8)
	ds_write_b128 v95, v[160:163] offset:50688
	s_waitcnt lgkmcnt(0)
	s_barrier
	s_setprio 0
	ds_read_b128 v[212:215], v245 offset:36864
	ds_read_b128 v[196:199], v244
	ds_read_b128 v[216:219], v245 offset:39168
	ds_read_b128 v[220:223], v245 offset:41472
	ds_read_b128 v[224:227], v245 offset:43776
	ds_read_b128 v[200:203], v244 offset:2304
	v_mfma_f32_16x16x32_bf16 v[50:53], v[204:207], v[228:231], v[50:53]
	v_mfma_f32_16x16x32_bf16 v[54:57], v[204:207], v[232:235], v[54:57]
	v_mfma_f32_16x16x32_bf16 v[18:21], v[204:207], v[236:239], v[18:21]
	v_mfma_f32_16x16x32_bf16 v[22:25], v[204:207], v[240:243], v[22:25]
	ds_read_b128 v[204:207], v244 offset:4608
	v_mfma_f32_16x16x32_bf16 v[58:61], v[208:211], v[228:231], v[58:61]
	v_mfma_f32_16x16x32_bf16 v[62:65], v[208:211], v[232:235], v[62:65]
	v_mfma_f32_16x16x32_bf16 v[26:29], v[208:211], v[236:239], v[26:29]
	v_mfma_f32_16x16x32_bf16 v[30:33], v[208:211], v[240:243], v[30:33]
	ds_read_b128 v[208:211], v244 offset:6912
	global_load_dwordx4 v[132:135], v[72:73], off offset:1792
	global_load_dwordx4 v[136:139], v[74:75], off offset:1792
	global_load_dwordx4 v[140:143], v[76:77], off offset:1792
	global_load_dwordx4 v[144:147], v[78:79], off offset:1792
	global_load_dwordx4 v[148:151], v[80:81], off offset:1792
	global_load_dwordx4 v[152:155], v[82:83], off offset:1792
	global_load_dwordx4 v[156:159], v[84:85], off offset:1792
	global_load_dwordx4 v[160:163], v[86:87], off offset:1792
	s_waitcnt lgkmcnt(6)
	v_mfma_f32_16x16x32_bf16 v[34:37], v[196:199], v[212:215], v[34:37]
	ds_read_b128 v[228:231], v245 offset:36928
	s_waitcnt lgkmcnt(6)
	v_mfma_f32_16x16x32_bf16 v[38:41], v[196:199], v[216:219], v[38:41]
	ds_read_b128 v[232:235], v245 offset:39232
	s_waitcnt lgkmcnt(6)
	v_mfma_f32_16x16x32_bf16 v[2:5], v[196:199], v[220:223], v[2:5]
	ds_read_b128 v[236:239], v245 offset:41536
	s_waitcnt lgkmcnt(6)
	v_mfma_f32_16x16x32_bf16 v[6:9], v[196:199], v[224:227], v[6:9]
	ds_read_b128 v[240:243], v245 offset:43840
	ds_read_b128 v[196:199], v244 offset:64
	s_waitcnt lgkmcnt(7)
	v_mfma_f32_16x16x32_bf16 v[42:45], v[200:203], v[212:215], v[42:45]
	v_mfma_f32_16x16x32_bf16 v[46:49], v[200:203], v[216:219], v[46:49]
	v_mfma_f32_16x16x32_bf16 v[10:13], v[200:203], v[220:223], v[10:13]
	v_mfma_f32_16x16x32_bf16 v[14:17], v[200:203], v[224:227], v[14:17]
	ds_read_b128 v[200:203], v244 offset:2368
	s_waitcnt lgkmcnt(7)
	v_mfma_f32_16x16x32_bf16 v[50:53], v[204:207], v[212:215], v[50:53]
	v_mfma_f32_16x16x32_bf16 v[54:57], v[204:207], v[216:219], v[54:57]
	v_mfma_f32_16x16x32_bf16 v[18:21], v[204:207], v[220:223], v[18:21]
	v_mfma_f32_16x16x32_bf16 v[22:25], v[204:207], v[224:227], v[22:25]
	ds_read_b128 v[204:207], v244 offset:4672
	s_setprio 1
	s_waitcnt vmcnt(15)
	ds_write_b128 v95, v[98:101] offset:18432
	s_waitcnt vmcnt(14)
	ds_write_b128 v95, v[102:105] offset:23040
	s_waitcnt lgkmcnt(9)
	v_mfma_f32_16x16x32_bf16 v[58:61], v[208:211], v[212:215], v[58:61]
	v_mfma_f32_16x16x32_bf16 v[62:65], v[208:211], v[216:219], v[62:65]
	v_mfma_f32_16x16x32_bf16 v[26:29], v[208:211], v[220:223], v[26:29]
	v_mfma_f32_16x16x32_bf16 v[30:33], v[208:211], v[224:227], v[30:33]
	ds_read_b128 v[208:211], v244 offset:6976
	s_waitcnt vmcnt(13)
	ds_write_b128 v95, v[106:109] offset:27648
	s_waitcnt vmcnt(12)
	ds_write_b128 v95, v[110:113] offset:32256
	s_waitcnt lgkmcnt(7)
	v_mfma_f32_16x16x32_bf16 v[34:37], v[196:199], v[228:231], v[34:37]
	v_mfma_f32_16x16x32_bf16 v[38:41], v[196:199], v[232:235], v[38:41]
	v_mfma_f32_16x16x32_bf16 v[2:5], v[196:199], v[236:239], v[2:5]
	v_mfma_f32_16x16x32_bf16 v[6:9], v[196:199], v[240:243], v[6:9]
	s_waitcnt vmcnt(11)
	ds_write_b128 v95, v[114:117] offset:55296
	s_waitcnt vmcnt(10)
	ds_write_b128 v95, v[118:121] offset:59904
	s_waitcnt lgkmcnt(8)
	v_mfma_f32_16x16x32_bf16 v[42:45], v[200:203], v[228:231], v[42:45]
	v_mfma_f32_16x16x32_bf16 v[46:49], v[200:203], v[232:235], v[46:49]
	v_mfma_f32_16x16x32_bf16 v[10:13], v[200:203], v[236:239], v[10:13]
	v_mfma_f32_16x16x32_bf16 v[14:17], v[200:203], v[240:243], v[14:17]
	s_waitcnt vmcnt(9)
	ds_write_b128 v95, v[122:125] offset:64512
	s_waitcnt vmcnt(8)
	ds_write_b128 v96, v[126:129] offset:32256
	s_waitcnt lgkmcnt(0)
	s_barrier
	s_setprio 0
	ds_read_b128 v[212:215], v245 offset:55296
	ds_read_b128 v[196:199], v244 offset:18432
	ds_read_b128 v[216:219], v245 offset:57600
	ds_read_b128 v[220:223], v245 offset:59904
	ds_read_b128 v[224:227], v245 offset:62208
	ds_read_b128 v[200:203], v244 offset:20736
	v_mfma_f32_16x16x32_bf16 v[50:53], v[204:207], v[228:231], v[50:53]
	v_mfma_f32_16x16x32_bf16 v[54:57], v[204:207], v[232:235], v[54:57]
	v_mfma_f32_16x16x32_bf16 v[18:21], v[204:207], v[236:239], v[18:21]
	v_mfma_f32_16x16x32_bf16 v[22:25], v[204:207], v[240:243], v[22:25]
	ds_read_b128 v[204:207], v244 offset:23040
	v_mfma_f32_16x16x32_bf16 v[58:61], v[208:211], v[228:231], v[58:61]
	v_mfma_f32_16x16x32_bf16 v[62:65], v[208:211], v[232:235], v[62:65]
	v_mfma_f32_16x16x32_bf16 v[26:29], v[208:211], v[236:239], v[26:29]
	v_mfma_f32_16x16x32_bf16 v[30:33], v[208:211], v[240:243], v[30:33]
	ds_read_b128 v[208:211], v244 offset:25344
	global_load_dwordx4 v[98:101], v[72:73], off offset:1920
	s_nop 0
	global_load_dwordx4 v[72:75], v[74:75], off offset:1920
	s_nop 0
	global_load_dwordx4 v[102:105], v[76:77], off offset:1920
	s_nop 0
	global_load_dwordx4 v[76:79], v[78:79], off offset:1920
	s_nop 0
	global_load_dwordx4 v[106:109], v[80:81], off offset:1920
	s_nop 0
	global_load_dwordx4 v[80:83], v[82:83], off offset:1920
	s_nop 0
	global_load_dwordx4 v[110:113], v[84:85], off offset:1920
	s_nop 0
	global_load_dwordx4 v[84:87], v[86:87], off offset:1920
	s_waitcnt lgkmcnt(6)
	v_mfma_f32_16x16x32_bf16 v[34:37], v[196:199], v[212:215], v[34:37]
	ds_read_b128 v[228:231], v245 offset:55360
	s_waitcnt lgkmcnt(6)
	v_mfma_f32_16x16x32_bf16 v[38:41], v[196:199], v[216:219], v[38:41]
	ds_read_b128 v[232:235], v245 offset:57664
	s_waitcnt lgkmcnt(6)
	v_mfma_f32_16x16x32_bf16 v[2:5], v[196:199], v[220:223], v[2:5]
	ds_read_b128 v[236:239], v245 offset:59968
	s_waitcnt lgkmcnt(6)
	v_mfma_f32_16x16x32_bf16 v[6:9], v[196:199], v[224:227], v[6:9]
	ds_read_b128 v[240:243], v245 offset:62272
	ds_read_b128 v[196:199], v244 offset:18496
	s_waitcnt lgkmcnt(7)
	v_mfma_f32_16x16x32_bf16 v[42:45], v[200:203], v[212:215], v[42:45]
	v_mfma_f32_16x16x32_bf16 v[46:49], v[200:203], v[216:219], v[46:49]
	v_mfma_f32_16x16x32_bf16 v[10:13], v[200:203], v[220:223], v[10:13]
	v_mfma_f32_16x16x32_bf16 v[14:17], v[200:203], v[224:227], v[14:17]
	ds_read_b128 v[200:203], v244 offset:20800
	s_waitcnt lgkmcnt(7)
	v_mfma_f32_16x16x32_bf16 v[50:53], v[204:207], v[212:215], v[50:53]
	v_mfma_f32_16x16x32_bf16 v[54:57], v[204:207], v[216:219], v[54:57]
	v_mfma_f32_16x16x32_bf16 v[18:21], v[204:207], v[220:223], v[18:21]
	v_mfma_f32_16x16x32_bf16 v[22:25], v[204:207], v[224:227], v[22:25]
	ds_read_b128 v[204:207], v244 offset:23104
	s_setprio 1
	s_waitcnt vmcnt(15)
	ds_write_b128 v95, v[132:135]
	s_waitcnt vmcnt(14)
	ds_write_b128 v95, v[136:139] offset:4608
	s_waitcnt lgkmcnt(9)
	v_mfma_f32_16x16x32_bf16 v[58:61], v[208:211], v[212:215], v[58:61]
	v_mfma_f32_16x16x32_bf16 v[62:65], v[208:211], v[216:219], v[62:65]
	v_mfma_f32_16x16x32_bf16 v[26:29], v[208:211], v[220:223], v[26:29]
	v_mfma_f32_16x16x32_bf16 v[30:33], v[208:211], v[224:227], v[30:33]
	ds_read_b128 v[208:211], v244 offset:25408
	s_waitcnt vmcnt(13)
	ds_write_b128 v95, v[140:143] offset:9216
	s_waitcnt vmcnt(12)
	ds_write_b128 v95, v[144:147] offset:13824
	s_waitcnt lgkmcnt(7)
	v_mfma_f32_16x16x32_bf16 v[34:37], v[196:199], v[228:231], v[34:37]
	v_mfma_f32_16x16x32_bf16 v[38:41], v[196:199], v[232:235], v[38:41]
	v_mfma_f32_16x16x32_bf16 v[2:5], v[196:199], v[236:239], v[2:5]
	v_mfma_f32_16x16x32_bf16 v[6:9], v[196:199], v[240:243], v[6:9]
	s_waitcnt vmcnt(11)
	ds_write_b128 v95, v[148:151] offset:36864
	s_waitcnt vmcnt(10)
	ds_write_b128 v95, v[152:155] offset:41472
	s_waitcnt lgkmcnt(8)
	v_mfma_f32_16x16x32_bf16 v[42:45], v[200:203], v[228:231], v[42:45]
	v_mfma_f32_16x16x32_bf16 v[46:49], v[200:203], v[232:235], v[46:49]
	v_mfma_f32_16x16x32_bf16 v[10:13], v[200:203], v[236:239], v[10:13]
	v_mfma_f32_16x16x32_bf16 v[14:17], v[200:203], v[240:243], v[14:17]
	s_waitcnt vmcnt(9)
	ds_write_b128 v95, v[156:159] offset:46080
	s_waitcnt vmcnt(8)
	ds_write_b128 v95, v[160:163] offset:50688
	s_waitcnt lgkmcnt(0)
	s_barrier
	s_setprio 0
	ds_read_b128 v[212:215], v245 offset:36864
	ds_read_b128 v[196:199], v244
	ds_read_b128 v[216:219], v245 offset:39168
	ds_read_b128 v[220:223], v245 offset:41472
	ds_read_b128 v[224:227], v245 offset:43776
	ds_read_b128 v[200:203], v244 offset:2304
	v_mfma_f32_16x16x32_bf16 v[50:53], v[204:207], v[228:231], v[50:53]
	v_mfma_f32_16x16x32_bf16 v[54:57], v[204:207], v[232:235], v[54:57]
	v_mfma_f32_16x16x32_bf16 v[18:21], v[204:207], v[236:239], v[18:21]
	v_mfma_f32_16x16x32_bf16 v[22:25], v[204:207], v[240:243], v[22:25]
	ds_read_b128 v[204:207], v244 offset:4608
	v_mfma_f32_16x16x32_bf16 v[58:61], v[208:211], v[228:231], v[58:61]
	v_mfma_f32_16x16x32_bf16 v[62:65], v[208:211], v[232:235], v[62:65]
	v_mfma_f32_16x16x32_bf16 v[26:29], v[208:211], v[236:239], v[26:29]
	v_mfma_f32_16x16x32_bf16 v[30:33], v[208:211], v[240:243], v[30:33]
	ds_read_b128 v[208:211], v244 offset:6912
	s_waitcnt lgkmcnt(6)
	v_mfma_f32_16x16x32_bf16 v[34:37], v[196:199], v[212:215], v[34:37]
	ds_read_b128 v[228:231], v245 offset:36928
	s_waitcnt lgkmcnt(6)
	v_mfma_f32_16x16x32_bf16 v[38:41], v[196:199], v[216:219], v[38:41]
	ds_read_b128 v[232:235], v245 offset:39232
	s_waitcnt lgkmcnt(6)
	v_mfma_f32_16x16x32_bf16 v[2:5], v[196:199], v[220:223], v[2:5]
	ds_read_b128 v[236:239], v245 offset:41536
	s_waitcnt lgkmcnt(6)
	v_mfma_f32_16x16x32_bf16 v[6:9], v[196:199], v[224:227], v[6:9]
	ds_read_b128 v[240:243], v245 offset:43840
	ds_read_b128 v[196:199], v244 offset:64
	s_waitcnt lgkmcnt(7)
	v_mfma_f32_16x16x32_bf16 v[42:45], v[200:203], v[212:215], v[42:45]
	v_mfma_f32_16x16x32_bf16 v[46:49], v[200:203], v[216:219], v[46:49]
	v_mfma_f32_16x16x32_bf16 v[10:13], v[200:203], v[220:223], v[10:13]
	v_mfma_f32_16x16x32_bf16 v[14:17], v[200:203], v[224:227], v[14:17]
	ds_read_b128 v[200:203], v244 offset:2368
	s_waitcnt lgkmcnt(7)
	v_mfma_f32_16x16x32_bf16 v[50:53], v[204:207], v[212:215], v[50:53]
	v_mfma_f32_16x16x32_bf16 v[54:57], v[204:207], v[216:219], v[54:57]
	v_mfma_f32_16x16x32_bf16 v[18:21], v[204:207], v[220:223], v[18:21]
	v_mfma_f32_16x16x32_bf16 v[22:25], v[204:207], v[224:227], v[22:25]
	ds_read_b128 v[204:207], v244 offset:4672
	s_setprio 1
	s_waitcnt vmcnt(7)
	ds_write_b128 v95, v[98:101] offset:18432
	s_waitcnt vmcnt(6)
	ds_write_b128 v95, v[72:75] offset:23040
	s_waitcnt lgkmcnt(9)
	v_mfma_f32_16x16x32_bf16 v[58:61], v[208:211], v[212:215], v[58:61]
	v_mfma_f32_16x16x32_bf16 v[62:65], v[208:211], v[216:219], v[62:65]
	v_mfma_f32_16x16x32_bf16 v[26:29], v[208:211], v[220:223], v[26:29]
	v_mfma_f32_16x16x32_bf16 v[30:33], v[208:211], v[224:227], v[30:33]
	ds_read_b128 v[208:211], v244 offset:6976
	s_waitcnt vmcnt(5)
	ds_write_b128 v95, v[102:105] offset:27648
	s_waitcnt vmcnt(4)
	ds_write_b128 v95, v[76:79] offset:32256
	s_waitcnt lgkmcnt(7)
	v_mfma_f32_16x16x32_bf16 v[34:37], v[196:199], v[228:231], v[34:37]
	v_mfma_f32_16x16x32_bf16 v[38:41], v[196:199], v[232:235], v[38:41]
	v_mfma_f32_16x16x32_bf16 v[2:5], v[196:199], v[236:239], v[2:5]
	v_mfma_f32_16x16x32_bf16 v[6:9], v[196:199], v[240:243], v[6:9]
	s_waitcnt vmcnt(3)
	ds_write_b128 v95, v[106:109] offset:55296
	s_waitcnt vmcnt(2)
	ds_write_b128 v95, v[80:83] offset:59904
	s_waitcnt lgkmcnt(8)
	v_mfma_f32_16x16x32_bf16 v[42:45], v[200:203], v[228:231], v[42:45]
	v_mfma_f32_16x16x32_bf16 v[46:49], v[200:203], v[232:235], v[46:49]
	v_mfma_f32_16x16x32_bf16 v[10:13], v[200:203], v[236:239], v[10:13]
	v_mfma_f32_16x16x32_bf16 v[14:17], v[200:203], v[240:243], v[14:17]
	s_waitcnt vmcnt(1)
	ds_write_b128 v95, v[110:113] offset:64512
	s_waitcnt vmcnt(0)
	ds_write_b128 v96, v[84:87] offset:32256
	s_waitcnt lgkmcnt(0)
	s_barrier
	s_setprio 0
	ds_read_b128 v[212:215], v245 offset:55296
	ds_read_b128 v[196:199], v244 offset:18432
	ds_read_b128 v[216:219], v245 offset:57600
	ds_read_b128 v[220:223], v245 offset:59904
	ds_read_b128 v[224:227], v245 offset:62208
	ds_read_b128 v[200:203], v244 offset:20736
	v_mfma_f32_16x16x32_bf16 v[50:53], v[204:207], v[228:231], v[50:53]
	v_mfma_f32_16x16x32_bf16 v[54:57], v[204:207], v[232:235], v[54:57]
	v_mfma_f32_16x16x32_bf16 v[18:21], v[204:207], v[236:239], v[18:21]
	v_mfma_f32_16x16x32_bf16 v[22:25], v[204:207], v[240:243], v[22:25]
	ds_read_b128 v[204:207], v244 offset:23040
	v_mfma_f32_16x16x32_bf16 v[58:61], v[208:211], v[228:231], v[58:61]
	v_mfma_f32_16x16x32_bf16 v[62:65], v[208:211], v[232:235], v[62:65]
	v_mfma_f32_16x16x32_bf16 v[26:29], v[208:211], v[236:239], v[26:29]
	v_mfma_f32_16x16x32_bf16 v[30:33], v[208:211], v[240:243], v[30:33]
	ds_read_b128 v[208:211], v244 offset:25344
	s_waitcnt lgkmcnt(6)
	v_mfma_f32_16x16x32_bf16 v[34:37], v[196:199], v[212:215], v[34:37]
	ds_read_b128 v[228:231], v245 offset:55360
	s_waitcnt lgkmcnt(6)
	v_mfma_f32_16x16x32_bf16 v[38:41], v[196:199], v[216:219], v[38:41]
	ds_read_b128 v[232:235], v245 offset:57664
	s_waitcnt lgkmcnt(6)
	v_mfma_f32_16x16x32_bf16 v[2:5], v[196:199], v[220:223], v[2:5]
	ds_read_b128 v[236:239], v245 offset:59968
	s_waitcnt lgkmcnt(6)
	v_mfma_f32_16x16x32_bf16 v[6:9], v[196:199], v[224:227], v[6:9]
	ds_read_b128 v[240:243], v245 offset:62272
	ds_read_b128 v[196:199], v244 offset:18496
	s_waitcnt lgkmcnt(7)
	v_mfma_f32_16x16x32_bf16 v[42:45], v[200:203], v[212:215], v[42:45]
	v_mfma_f32_16x16x32_bf16 v[46:49], v[200:203], v[216:219], v[46:49]
	v_mfma_f32_16x16x32_bf16 v[10:13], v[200:203], v[220:223], v[10:13]
	v_mfma_f32_16x16x32_bf16 v[14:17], v[200:203], v[224:227], v[14:17]
	ds_read_b128 v[200:203], v244 offset:20800
	s_waitcnt lgkmcnt(7)
	v_mfma_f32_16x16x32_bf16 v[50:53], v[204:207], v[212:215], v[50:53]
	v_mfma_f32_16x16x32_bf16 v[54:57], v[204:207], v[216:219], v[54:57]
	v_mfma_f32_16x16x32_bf16 v[18:21], v[204:207], v[220:223], v[18:21]
	v_mfma_f32_16x16x32_bf16 v[22:25], v[204:207], v[224:227], v[22:25]
	ds_read_b128 v[204:207], v244 offset:23104
	s_waitcnt lgkmcnt(7)
	v_mfma_f32_16x16x32_bf16 v[58:61], v[208:211], v[212:215], v[58:61]
	v_mfma_f32_16x16x32_bf16 v[62:65], v[208:211], v[216:219], v[62:65]
	v_mfma_f32_16x16x32_bf16 v[26:29], v[208:211], v[220:223], v[26:29]
	v_mfma_f32_16x16x32_bf16 v[30:33], v[208:211], v[224:227], v[30:33]
	ds_read_b128 v[208:211], v244 offset:25408
	s_waitcnt lgkmcnt(3)
	v_mfma_f32_16x16x32_bf16 v[34:37], v[196:199], v[228:231], v[34:37]
	v_mfma_f32_16x16x32_bf16 v[38:41], v[196:199], v[232:235], v[38:41]
	v_mfma_f32_16x16x32_bf16 v[2:5], v[196:199], v[236:239], v[2:5]
	v_mfma_f32_16x16x32_bf16 v[6:9], v[196:199], v[240:243], v[6:9]
	s_waitcnt lgkmcnt(2)
	v_mfma_f32_16x16x32_bf16 v[42:45], v[200:203], v[228:231], v[42:45]
	v_mfma_f32_16x16x32_bf16 v[46:49], v[200:203], v[232:235], v[46:49]
	v_mfma_f32_16x16x32_bf16 v[10:13], v[200:203], v[236:239], v[10:13]
	v_mfma_f32_16x16x32_bf16 v[14:17], v[200:203], v[240:243], v[14:17]
	v_or_b32_e32 v66, s5, v88
	s_addk_i32 s5, 0xf000
	s_lshr_b32 s5, s5, 12
	s_mulk_i32 s5, 0xc00
	s_addk_i32 s5, 0x3000
	s_cmp_gt_u32 s0, 31
	v_lshlrev_b32_e32 v66, 12, v66
	s_cselect_b32 s0, s5, 0x2400
	v_lshl_add_u64 v[148:149], s[80:81], 0, v[66:67]
	v_add_lshl_u32 v66, s4, v97, 2
	s_lshl_b64 s[4:5], s[0:1], 2
	s_add_u32 s0, s82, s4
	s_addc_u32 s5, s83, s5
	s_add_u32 s4, s0, 0xe958000
	v_lshl_add_u64 v[150:151], v[148:149], 0, v[66:67]
	s_addc_u32 s5, s5, 0
	v_or_b32_e32 v152, 0xe0, v66
	v_or_b32_e32 v154, 32, v66
	v_or_b32_e32 v156, 64, v66
	v_or_b32_e32 v158, 0x60, v66
	v_or_b32_e32 v160, 0x80, v66
	v_or_b32_e32 v162, 0xa0, v66
	v_or_b32_e32 v164, 0xc0, v66
	v_mov_b32_e32 v155, v67
	v_mov_b32_e32 v157, v67
	v_mov_b32_e32 v159, v67
	v_mov_b32_e32 v161, v67
	v_mov_b32_e32 v163, v67
	v_mov_b32_e32 v165, v67
	v_mov_b32_e32 v153, v67
	s_add_i32 s11, s11, 1
	s_mul_i32 s0, s11, s7
	s_add_i32 s10, s10, s7
	s_waitcnt lgkmcnt(0)
	s_barrier
	v_mfma_f32_16x16x32_bf16 v[50:53], v[204:207], v[228:231], v[50:53]
	v_mfma_f32_16x16x32_bf16 v[54:57], v[204:207], v[232:235], v[54:57]
	v_mfma_f32_16x16x32_bf16 v[18:21], v[204:207], v[236:239], v[18:21]
	v_mfma_f32_16x16x32_bf16 v[22:25], v[204:207], v[240:243], v[22:25]
	v_mfma_f32_16x16x32_bf16 v[58:61], v[208:211], v[228:231], v[58:61]
	v_mfma_f32_16x16x32_bf16 v[62:65], v[208:211], v[232:235], v[62:65]
	v_mfma_f32_16x16x32_bf16 v[26:29], v[208:211], v[236:239], v[26:29]
	v_mfma_f32_16x16x32_bf16 v[30:33], v[208:211], v[240:243], v[30:33]
	s_nop 7
	v_permlane16_swap_b32_e32 v34, v38
	v_permlane16_swap_b32_e32 v35, v39
	v_permlane16_swap_b32_e32 v36, v40
	v_permlane16_swap_b32_e32 v37, v41
	v_permlane16_swap_b32_e32 v42, v46
	v_permlane16_swap_b32_e32 v43, v47
	v_permlane16_swap_b32_e32 v44, v48
	v_permlane16_swap_b32_e32 v45, v49
	v_permlane16_swap_b32_e32 v2, v6
	v_permlane16_swap_b32_e32 v3, v7
	v_permlane16_swap_b32_e32 v4, v8
	v_permlane16_swap_b32_e32 v5, v9
	v_permlane16_swap_b32_e32 v10, v14
	v_permlane16_swap_b32_e32 v11, v15
	v_permlane16_swap_b32_e32 v12, v16
	v_permlane16_swap_b32_e32 v13, v17
	v_permlane16_swap_b32_e32 v50, v54
	v_permlane16_swap_b32_e32 v51, v55
	v_permlane16_swap_b32_e32 v52, v56
	v_permlane16_swap_b32_e32 v53, v57
	v_permlane16_swap_b32_e32 v58, v62
	v_permlane16_swap_b32_e32 v59, v63
	v_permlane16_swap_b32_e32 v60, v64
	v_permlane16_swap_b32_e32 v61, v65
	v_permlane16_swap_b32_e32 v18, v22
	v_permlane16_swap_b32_e32 v19, v23
	v_permlane16_swap_b32_e32 v20, v24
	v_permlane16_swap_b32_e32 v21, v25
	v_permlane16_swap_b32_e32 v26, v30
	v_permlane16_swap_b32_e32 v27, v31
	v_permlane16_swap_b32_e32 v28, v32
	v_permlane16_swap_b32_e32 v29, v33
	v_permlane32_swap_b32_e32 v34, v38
	v_permlane32_swap_b32_e32 v35, v39
	v_permlane32_swap_b32_e32 v36, v40
	v_permlane32_swap_b32_e32 v37, v41
	v_permlane32_swap_b32_e32 v42, v46
	v_permlane32_swap_b32_e32 v43, v47
	v_permlane32_swap_b32_e32 v44, v48
	v_permlane32_swap_b32_e32 v45, v49
	v_permlane32_swap_b32_e32 v2, v6
	v_permlane32_swap_b32_e32 v3, v7
	v_permlane32_swap_b32_e32 v4, v8
	v_permlane32_swap_b32_e32 v5, v9
	v_permlane32_swap_b32_e32 v10, v14
	v_permlane32_swap_b32_e32 v11, v15
	v_permlane32_swap_b32_e32 v12, v16
	v_permlane32_swap_b32_e32 v13, v17
	v_permlane32_swap_b32_e32 v50, v54
	v_permlane32_swap_b32_e32 v51, v55
	v_permlane32_swap_b32_e32 v52, v56
	v_permlane32_swap_b32_e32 v53, v57
	v_permlane32_swap_b32_e32 v58, v62
	v_permlane32_swap_b32_e32 v59, v63
	v_permlane32_swap_b32_e32 v60, v64
	v_permlane32_swap_b32_e32 v61, v65
	v_permlane32_swap_b32_e32 v18, v22
	v_permlane32_swap_b32_e32 v19, v23
	v_permlane32_swap_b32_e32 v20, v24
	v_permlane32_swap_b32_e32 v21, v25
	v_permlane32_swap_b32_e32 v26, v30
	v_permlane32_swap_b32_e32 v27, v31
	v_permlane32_swap_b32_e32 v28, v32
	v_permlane32_swap_b32_e32 v29, v33
	global_load_dwordx4 v[76:79], v[150:151], off offset:224
	global_load_dwordx4 v[84:87], v152, s[4:5]
	global_load_dwordx4 v[80:83], v[150:151], off offset:192
	s_waitcnt vmcnt(1)
	v_fma_f32 v62, v62, v84, v76
	v_fma_f32 v63, v63, v85, v77
	global_load_dwordx4 v[72:75], v164, s[4:5]
	global_load_dwordx4 v[98:101], v[150:151], off offset:160
	global_load_dwordx4 v[102:105], v162, s[4:5]
	global_load_dwordx4 v[106:109], v[150:151], off offset:128
	global_load_dwordx4 v[110:113], v160, s[4:5]
	global_load_dwordx4 v[114:117], v[150:151], off offset:96
	global_load_dwordx4 v[118:121], v158, s[4:5]
	global_load_dwordx4 v[122:125], v[150:151], off offset:64
	global_load_dwordx4 v[126:129], v156, s[4:5]
	global_load_dwordx4 v[132:135], v[150:151], off offset:32
	global_load_dwordx4 v[136:139], v154, s[4:5]
	global_load_dwordx4 v[140:143], v[150:151], off
	global_load_dwordx4 v[144:147], v66, s[4:5]
	v_pk_fma_f32 v[64:65], v[64:65], v[86:87], v[78:79]
	global_store_dwordx4 v[150:151], v[62:65], off offset:224
	s_waitcnt vmcnt(13)
	v_pk_fma_f32 v[58:59], v[58:59], v[72:73], v[80:81]
	v_pk_fma_f32 v[60:61], v[60:61], v[74:75], v[82:83]
	s_waitcnt vmcnt(11)
	v_pk_fma_f32 v[54:55], v[54:55], v[102:103], v[98:99]
	v_pk_fma_f32 v[56:57], v[56:57], v[104:105], v[100:101]
	s_waitcnt vmcnt(9)
	v_pk_fma_f32 v[50:51], v[50:51], v[110:111], v[106:107]
	v_pk_fma_f32 v[52:53], v[52:53], v[112:113], v[108:109]
	s_waitcnt vmcnt(7)
	v_pk_fma_f32 v[46:47], v[46:47], v[118:119], v[114:115]
	v_pk_fma_f32 v[48:49], v[48:49], v[120:121], v[116:117]
	s_waitcnt vmcnt(5)
	v_pk_fma_f32 v[42:43], v[42:43], v[126:127], v[122:123]
	v_pk_fma_f32 v[44:45], v[44:45], v[128:129], v[124:125]
	s_waitcnt vmcnt(3)
	v_pk_fma_f32 v[38:39], v[38:39], v[136:137], v[132:133]
	v_pk_fma_f32 v[40:41], v[40:41], v[138:139], v[134:135]
	s_waitcnt vmcnt(1)
	v_pk_fma_f32 v[34:35], v[34:35], v[144:145], v[140:141]
	v_pk_fma_f32 v[36:37], v[36:37], v[146:147], v[142:143]
	global_store_dwordx4 v[150:151], v[34:37], off
	global_store_dwordx4 v[150:151], v[38:41], off offset:32
	global_store_dwordx4 v[150:151], v[42:45], off offset:64
	v_lshl_add_u64 v[34:35], v[148:149], 0, s[2:3]
	global_store_dwordx4 v[150:151], v[46:49], off offset:96
	global_store_dwordx4 v[150:151], v[50:53], off offset:128
	global_store_dwordx4 v[150:151], v[54:57], off offset:160
	global_store_dwordx4 v[150:151], v[58:61], off offset:192
	v_lshl_add_u64 v[114:115], v[34:35], 0, v[66:67]
	v_lshl_add_u64 v[116:117], v[34:35], 0, v[154:155]
	v_lshl_add_u64 v[118:119], v[34:35], 0, v[156:157]
	v_lshl_add_u64 v[120:121], v[34:35], 0, v[158:159]
	v_lshl_add_u64 v[122:123], v[34:35], 0, v[160:161]
	v_lshl_add_u64 v[124:125], v[34:35], 0, v[162:163]
	v_lshl_add_u64 v[126:127], v[34:35], 0, v[164:165]
	v_lshl_add_u64 v[128:129], v[34:35], 0, v[152:153]
	global_load_dwordx4 v[34:37], v[128:129], off
	global_load_dwordx4 v[38:41], v152, s[4:5]
	global_load_dwordx4 v[42:45], v[126:127], off
	global_load_dwordx4 v[46:49], v164, s[4:5]
	global_load_dwordx4 v[50:53], v[124:125], off
	global_load_dwordx4 v[54:57], v162, s[4:5]
	global_load_dwordx4 v[58:61], v[122:123], off
	global_load_dwordx4 v[62:65], v160, s[4:5]
	global_load_dwordx4 v[72:75], v[120:121], off
	global_load_dwordx4 v[76:79], v158, s[4:5]
	global_load_dwordx4 v[80:83], v[118:119], off
	global_load_dwordx4 v[84:87], v156, s[4:5]
	global_load_dwordx4 v[98:101], v[116:117], off
	global_load_dwordx4 v[102:105], v154, s[4:5]
	global_load_dwordx4 v[106:109], v[114:115], off
	global_load_dwordx4 v[110:113], v66, s[4:5]
	s_add_i32 s4, s0, s6
	s_cmpk_lt_u32 s10, 0x60
	s_waitcnt vmcnt(14)
	v_pk_fma_f32 v[30:31], v[30:31], v[38:39], v[34:35]
	v_pk_fma_f32 v[32:33], v[32:33], v[40:41], v[36:37]
	s_waitcnt vmcnt(12)
	v_pk_fma_f32 v[26:27], v[26:27], v[46:47], v[42:43]
	v_pk_fma_f32 v[28:29], v[28:29], v[48:49], v[44:45]
	s_waitcnt vmcnt(10)
	v_pk_fma_f32 v[22:23], v[22:23], v[54:55], v[50:51]
	v_pk_fma_f32 v[24:25], v[24:25], v[56:57], v[52:53]
	s_waitcnt vmcnt(8)
	v_pk_fma_f32 v[18:19], v[18:19], v[62:63], v[58:59]
	v_pk_fma_f32 v[20:21], v[20:21], v[64:65], v[60:61]
	s_waitcnt vmcnt(6)
	v_pk_fma_f32 v[14:15], v[14:15], v[76:77], v[72:73]
	v_pk_fma_f32 v[16:17], v[16:17], v[78:79], v[74:75]
	s_waitcnt vmcnt(4)
	v_pk_fma_f32 v[10:11], v[10:11], v[84:85], v[80:81]
	v_pk_fma_f32 v[12:13], v[12:13], v[86:87], v[82:83]
	s_waitcnt vmcnt(2)
	v_pk_fma_f32 v[6:7], v[6:7], v[102:103], v[98:99]
	v_pk_fma_f32 v[8:9], v[8:9], v[104:105], v[100:101]
	s_waitcnt vmcnt(0)
	v_pk_fma_f32 v[2:3], v[2:3], v[110:111], v[106:107]
	v_pk_fma_f32 v[4:5], v[4:5], v[112:113], v[108:109]
	global_store_dwordx4 v[114:115], v[2:5], off
	global_store_dwordx4 v[116:117], v[6:9], off
	global_store_dwordx4 v[118:119], v[10:13], off
	global_store_dwordx4 v[120:121], v[14:17], off
	global_store_dwordx4 v[122:123], v[18:21], off
	global_store_dwordx4 v[124:125], v[22:25], off
	global_store_dwordx4 v[126:127], v[26:29], off
	global_store_dwordx4 v[128:129], v[30:33], off
	s_cbranch_scc1 .LBB0_1871
